# K-loop register-double-buffered pipeline (barrier at 75%), NA/scan global loads + counted waits, batched f32 RMW epilogues for out-proj and FFN-down
# speedup vs baseline: 1.0505x; 1.0505x over previous
.LBB0_149:
	s_or_b64 exec, exec, s[4:5]
	s_and_b64 s[4:5], exec, s[28:29]
	s_cselect_b32 s4, 0x8000, 0
	s_add_i32 s4, s66, s4
	v_mov_b32_e32 v10, v132
	s_ashr_i32 s5, s4, 31
	s_lshl_b64 s[4:5], s[4:5], 11
	v_lshlrev_b32_e32 v1, 4, v10
	v_and_b32_e32 v0, 32, v10
	v_lshrrev_b32_e32 v2, 1, v10
	v_bitop3_b32 v0, v1, v0, 48 bitop3:0x6c
	s_add_u32 s42, s6, s4
	v_bfe_u32 v11, v10, 2, 4
	v_and_b32_e32 v12, 32, v2
	v_lshrrev_b32_e32 v13, 1, v0
	v_ashrrev_i32_e32 v14, 3, v10
	s_addc_u32 s43, s36, s5
	v_or_b32_e32 v4, v13, v12
	v_and_or_b32 v0, v14, s48, v11
	s_add_u32 s38, s42, 0x2400000
	v_and_b32_e32 v3, 0xfffffc00, v1
	v_lshl_or_b32 v134, v0, 10, v4
	v_add_u32_e32 v0, 0x2000, v1
	v_add_u32_e32 v2, 0x4000, v1
	v_add_u32_e32 v1, 0x6000, v1
	s_addc_u32 s39, s43, 0
	s_ashr_i32 s27, s26, 31
	v_ashrrev_i32_e32 v15, 7, v0
	v_ashrrev_i32_e32 v16, 7, v2
	v_ashrrev_i32_e32 v17, 7, v1
	s_lshl_b64 s[4:5], s[26:27], 19
	v_and_or_b32 v0, v15, s48, v11
	v_and_or_b32 v2, v16, s48, v11
	v_and_or_b32 v1, v17, s48, v11
	v_add_u32_e32 v148, 0, v3
	s_add_u32 s4, s6, s4
	v_lshl_or_b32 v0, v0, 10, v4
	v_lshl_or_b32 v2, v2, 10, v4
	v_lshl_or_b32 v4, v1, 10, v4
	v_add_u32_e32 v1, 0x8000, v148
	v_lshlrev_b64 v[6:7], 1, v[134:135]
	v_readfirstlane_b32 s27, v148
	s_addc_u32 s5, s36, s5
	v_lshl_add_u64 v[8:9], s[38:39], 0, v[6:7]
	s_mov_b32 m0, s27
	v_readfirstlane_b32 s27, v1
	v_mov_b32_e32 v1, v135
	v_add_u32_e32 v3, 0x2000, v148
	global_load_lds_dwordx4 v[8:9], off
	v_lshl_add_u64 v[6:7], s[4:5], 0, v[6:7]
	s_mov_b32 m0, s27
	v_lshlrev_b64 v[0:1], 1, v[0:1]
	v_readfirstlane_b32 s27, v3
	v_add_u32_e32 v3, 0xa000, v148
	global_load_lds_dwordx4 v[6:7], off
	v_lshl_add_u64 v[6:7], s[38:39], 0, v[0:1]
	s_mov_b32 m0, s27
	v_readfirstlane_b32 s27, v3
	global_load_lds_dwordx4 v[6:7], off
	v_lshl_add_u64 v[0:1], s[4:5], 0, v[0:1]
	s_mov_b32 m0, s27
	v_mov_b32_e32 v3, v135
	v_add_u32_e32 v5, 0x4000, v148
	global_load_lds_dwordx4 v[0:1], off
	v_lshlrev_b64 v[0:1], 1, v[2:3]
	v_readfirstlane_b32 s27, v5
	v_lshl_add_u64 v[2:3], s[38:39], 0, v[0:1]
	s_mov_b32 m0, s27
	v_lshl_add_u64 v[0:1], s[4:5], 0, v[0:1]
	global_load_lds_dwordx4 v[2:3], off
	v_add_u32_e32 v2, 0xc000, v148
	v_mov_b32_e32 v5, v135
	v_readfirstlane_b32 s27, v2
	s_mov_b32 m0, s27
	v_lshlrev_b32_e32 v6, 10, v11
	global_load_lds_dwordx4 v[0:1], off
	v_lshlrev_b64 v[0:1], 1, v[4:5]
	v_add_u32_e32 v4, 0x6000, v148
	v_lshl_add_u64 v[2:3], s[38:39], 0, v[0:1]
	v_readfirstlane_b32 s27, v4
	s_mov_b32 m0, s27
	v_lshl_add_u64 v[0:1], s[4:5], 0, v[0:1]
	global_load_lds_dwordx4 v[2:3], off
	v_add_u32_e32 v2, 0xe000, v148
	v_lshlrev_b32_e32 v4, 10, v15
	v_readfirstlane_b32 s27, v2
	s_mov_b32 m0, s27
	v_lshlrev_b32_e32 v2, 2, v10
	global_load_lds_dwordx4 v[0:1], off
	v_and_b32_e32 v0, 15, v10
	v_and_b32_e32 v1, 48, v10
	v_lshlrev_b32_e32 v0, 6, v0
	v_and_b32_e32 v2, 32, v2
	v_bitop3_b32 v149, v0, v2, v1 bitop3:0x36
	v_lshlrev_b32_e32 v0, 7, v10
	v_and_b32_e32 v150, 0x6000, v0
	v_lshlrev_b32_e32 v0, 6, v10
	v_and_b32_e32 v151, 0xffffc000, v0
	v_and_b32_e32 v0, 0x3c0, v0
	v_bitop3_b32 v153, v0, v2, v1 bitop3:0x36
	v_lshlrev_b32_e32 v0, 10, v17
	v_and_or_b32 v0, v0, s49, v13
	v_lshlrev_b32_e32 v2, 10, v16
	v_or3_b32 v134, v0, v6, v12
	v_and_or_b32 v2, v2, s49, v13
	v_lshlrev_b64 v[0:1], 1, v[134:135]
	v_or3_b32 v134, v2, v6, v12
	v_and_or_b32 v4, v4, s49, v13
	v_lshlrev_b32_e32 v7, 10, v14
	v_lshlrev_b64 v[2:3], 1, v[134:135]
	v_or3_b32 v134, v4, v6, v12
	v_and_or_b32 v7, v7, s49, v13
	s_add_u32 s4, s4, 0x80
	v_lshlrev_b64 v[4:5], 1, v[134:135]
	v_or3_b32 v134, v7, v6, v12
	s_addc_u32 s5, s5, 0
	v_lshlrev_b64 v[6:7], 1, v[134:135]
	s_waitcnt vmcnt(0)
	v_lshl_add_u64 v[128:129], s[4:5], 0, v[0:1]
	v_lshl_add_u64 v[130:131], s[4:5], 0, v[2:3]
	v_lshl_add_u64 v[136:137], s[4:5], 0, v[4:5]
	v_lshl_add_u64 v[138:139], s[4:5], 0, v[6:7]
	s_add_u32 s4, s42, 0x2400080
	s_addc_u32 s5, s43, 0
	v_mov_b32_e32 v8, 0
	s_mov_b32 s37, 0
	v_or_b32_e32 v152, 0x800, v151
	v_or_b32_e32 v154, 0x1000, v151
	v_or_b32_e32 v155, 0x1800, v151
	v_or_b32_e32 v156, 0x2000, v151
	v_or_b32_e32 v157, 0x2800, v151
	v_or_b32_e32 v158, 0x3000, v151
	v_or_b32_e32 v159, 0x3800, v151
	v_lshl_add_u64 v[140:141], s[4:5], 0, v[0:1]
	v_lshl_add_u64 v[142:143], s[4:5], 0, v[2:3]
	v_lshl_add_u64 v[144:145], s[4:5], 0, v[4:5]
	v_lshl_add_u64 v[146:147], s[4:5], 0, v[6:7]
	s_mov_b64 s[4:5], 0
	v_mov_b32_e32 v9, v8
	v_mov_b32_e32 v10, v8
	v_mov_b32_e32 v11, v8
	v_mov_b32_e32 v20, v8
	v_mov_b32_e32 v21, v8
	v_mov_b32_e32 v22, v8
	v_mov_b32_e32 v23, v8
	v_mov_b32_e32 v28, v8
	v_mov_b32_e32 v29, v8
	v_mov_b32_e32 v30, v8
	v_mov_b32_e32 v31, v8
	v_mov_b32_e32 v36, v8
	v_mov_b32_e32 v37, v8
	v_mov_b32_e32 v38, v8
	v_mov_b32_e32 v39, v8
	v_mov_b32_e32 v0, v8
	v_mov_b32_e32 v1, v8
	v_mov_b32_e32 v2, v8
	v_mov_b32_e32 v3, v8
	v_mov_b32_e32 v4, v8
	v_mov_b32_e32 v5, v8
	v_mov_b32_e32 v6, v8
	v_mov_b32_e32 v7, v8
	v_mov_b32_e32 v12, v8
	v_mov_b32_e32 v13, v8
	v_mov_b32_e32 v14, v8
	v_mov_b32_e32 v15, v8
	v_mov_b32_e32 v16, v8
	v_mov_b32_e32 v17, v8
	v_mov_b32_e32 v18, v8
	v_mov_b32_e32 v19, v8
	v_mov_b32_e32 v24, v8
	v_mov_b32_e32 v25, v8
	v_mov_b32_e32 v26, v8
	v_mov_b32_e32 v27, v8
	v_mov_b32_e32 v32, v8
	v_mov_b32_e32 v33, v8
	v_mov_b32_e32 v34, v8
	v_mov_b32_e32 v35, v8
	v_mov_b32_e32 v40, v8
	v_mov_b32_e32 v41, v8
	v_mov_b32_e32 v42, v8
	v_mov_b32_e32 v43, v8
	v_mov_b32_e32 v44, v8
	v_mov_b32_e32 v45, v8
	v_mov_b32_e32 v46, v8
	v_mov_b32_e32 v47, v8
	v_mov_b32_e32 v48, v8
	v_mov_b32_e32 v49, v8
	v_mov_b32_e32 v50, v8
	v_mov_b32_e32 v51, v8
	v_mov_b32_e32 v52, v8
	v_mov_b32_e32 v53, v8
	v_mov_b32_e32 v54, v8
	v_mov_b32_e32 v55, v8
	v_mov_b32_e32 v56, v8
	v_mov_b32_e32 v57, v8
	v_mov_b32_e32 v58, v8
	v_mov_b32_e32 v59, v8
	v_mov_b32_e32 v60, v8
	v_mov_b32_e32 v61, v8
	v_mov_b32_e32 v62, v8
	v_mov_b32_e32 v63, v8
	v_mov_b32_e32 v64, v8
	v_mov_b32_e32 v65, v8
	v_mov_b32_e32 v66, v8
	v_mov_b32_e32 v67, v8
	v_mov_b32_e32 v68, v8
	v_mov_b32_e32 v69, v8
	v_mov_b32_e32 v70, v8
	v_mov_b32_e32 v71, v8
	v_mov_b32_e32 v72, v8
	v_mov_b32_e32 v73, v8
	v_mov_b32_e32 v74, v8
	v_mov_b32_e32 v75, v8
	v_mov_b32_e32 v76, v8
	v_mov_b32_e32 v77, v8
	v_mov_b32_e32 v78, v8
	v_mov_b32_e32 v79, v8
	v_mov_b32_e32 v80, v8
	v_mov_b32_e32 v81, v8
	v_mov_b32_e32 v82, v8
	v_mov_b32_e32 v83, v8
	v_mov_b32_e32 v84, v8
	v_mov_b32_e32 v85, v8
	v_mov_b32_e32 v86, v8
	v_mov_b32_e32 v87, v8
	v_mov_b32_e32 v88, v8
	v_mov_b32_e32 v89, v8
	v_mov_b32_e32 v90, v8
	v_mov_b32_e32 v91, v8
	v_mov_b32_e32 v92, v8
	v_mov_b32_e32 v93, v8
	v_mov_b32_e32 v94, v8
	v_mov_b32_e32 v95, v8
	v_mov_b32_e32 v96, v8
	v_mov_b32_e32 v97, v8
	v_mov_b32_e32 v98, v8
	v_mov_b32_e32 v99, v8
	v_mov_b32_e32 v100, v8
	v_mov_b32_e32 v101, v8
	v_mov_b32_e32 v102, v8
	v_mov_b32_e32 v103, v8
	v_mov_b32_e32 v104, v8
	v_mov_b32_e32 v105, v8
	v_mov_b32_e32 v106, v8
	v_mov_b32_e32 v107, v8
	v_mov_b32_e32 v108, v8
	v_mov_b32_e32 v109, v8
	v_mov_b32_e32 v110, v8
	v_mov_b32_e32 v111, v8
	v_mov_b32_e32 v112, v8
	v_mov_b32_e32 v113, v8
	v_mov_b32_e32 v114, v8
	v_mov_b32_e32 v115, v8
	v_mov_b32_e32 v116, v8
	v_mov_b32_e32 v117, v8
	v_mov_b32_e32 v118, v8
	v_mov_b32_e32 v119, v8
	v_mov_b32_e32 v120, v8
	v_mov_b32_e32 v121, v8
	v_mov_b32_e32 v122, v8
	v_mov_b32_e32 v123, v8
	v_mov_b32_e32 v124, v8
	v_mov_b32_e32 v125, v8
	v_mov_b32_e32 v126, v8
	v_mov_b32_e32 v127, v8
	s_waitcnt vmcnt(0) lgkmcnt(0)
	s_barrier
	v_readfirstlane_b32 s100, v148
	s_mov_b64 s[98:99], 0x80
	s_and_b32 s27, s37, 0x10000
	s_xor_b32 s38, s27, 0x10000
	s_add_i32 s27, s27, 0
	v_add3_u32 v134, s27, v149, v150
	v_add3_u32 v196, s27, v149, v151
	v_add3_u32 v197, s27, v153, v152
	v_add3_u32 v198, s27, v153, v154
	v_add3_u32 v199, s27, v153, v155
	v_add3_u32 v200, s27, v153, v156
	v_add3_u32 v201, s27, v153, v157
	v_add3_u32 v202, s27, v153, v158
	v_add3_u32 v203, s27, v153, v159
	ds_read_b128 v[180:183], v134 offset:32768
	ds_read_b128 v[160:163], v196
	ds_read_b128 v[168:171], v197
	ds_read_b128 v[172:175], v198
	ds_read_b128 v[176:179], v199
	ds_read_b128 v[184:187], v134 offset:34816
	ds_read_b128 v[188:191], v134 offset:36864
	ds_read_b128 v[192:195], v134 offset:38912
	s_add_i32 s101, s100, s38
	s_mov_b32 m0, s101
	s_nop 0
	global_load_lds_dwordx4 v[146:147], off
	s_add_i32 m0, s101, 0x8000
	s_nop 0
	global_load_lds_dwordx4 v[138:139], off
	s_add_i32 m0, s101, 0x2000
	s_nop 0
	global_load_lds_dwordx4 v[144:145], off
	s_add_i32 m0, s101, 0xa000
	s_nop 0
	global_load_lds_dwordx4 v[136:137], off
	s_add_i32 m0, s101, 0x4000
	s_nop 0
	global_load_lds_dwordx4 v[142:143], off
	s_add_i32 m0, s101, 0xc000
	s_nop 0
	global_load_lds_dwordx4 v[130:131], off
	s_add_i32 m0, s101, 0x6000
	s_nop 0
	global_load_lds_dwordx4 v[140:141], off
	s_add_i32 m0, s101, 0xe000
	s_nop 0
	global_load_lds_dwordx4 v[128:129], off
.LBB0_150:
	s_and_b32 s27, s37, 0x10000
	s_xor_b32 s38, s27, 0x10000
	s_add_i32 s27, s27, 0
	s_waitcnt lgkmcnt(3)
	v_mfma_f32_16x16x32_bf16 v[124:127], v[160:163], v[180:183], v[124:127]
	v_mfma_f32_16x16x32_bf16 v[108:111], v[168:171], v[180:183], v[108:111]
	v_mfma_f32_16x16x32_bf16 v[92:95], v[172:175], v[180:183], v[92:95]
	v_mfma_f32_16x16x32_bf16 v[76:79], v[176:179], v[180:183], v[76:79]
	ds_read_b128 v[240:243], v200
	ds_read_b128 v[244:247], v201
	s_waitcnt lgkmcnt(4)
	v_mfma_f32_16x16x32_bf16 v[120:123], v[160:163], v[184:187], v[120:123]
	v_mfma_f32_16x16x32_bf16 v[104:107], v[168:171], v[184:187], v[104:107]
	v_mfma_f32_16x16x32_bf16 v[88:91], v[172:175], v[184:187], v[88:91]
	v_mfma_f32_16x16x32_bf16 v[72:75], v[176:179], v[184:187], v[72:75]
	ds_read_b128 v[248:251], v202
	ds_read_b128 v[252:255], v203
	s_waitcnt lgkmcnt(5)
	v_mfma_f32_16x16x32_bf16 v[116:119], v[160:163], v[188:191], v[116:119]
	v_mfma_f32_16x16x32_bf16 v[100:103], v[168:171], v[188:191], v[100:103]
	v_mfma_f32_16x16x32_bf16 v[84:87], v[172:175], v[188:191], v[84:87]
	v_mfma_f32_16x16x32_bf16 v[68:71], v[176:179], v[188:191], v[68:71]
	s_waitcnt lgkmcnt(4)
	v_mfma_f32_16x16x32_bf16 v[112:115], v[160:163], v[192:195], v[112:115]
	v_mfma_f32_16x16x32_bf16 v[96:99], v[168:171], v[192:195], v[96:99]
	v_mfma_f32_16x16x32_bf16 v[80:83], v[172:175], v[192:195], v[80:83]
	v_mfma_f32_16x16x32_bf16 v[64:67], v[176:179], v[192:195], v[64:67]
	ds_read_b128 v[160:163], v196 offset:1024
	ds_read_b128 v[168:171], v197 offset:1024
	ds_read_b128 v[172:175], v198 offset:1024
	ds_read_b128 v[176:179], v199 offset:1024
	s_waitcnt lgkmcnt(4)
	v_mfma_f32_16x16x32_bf16 v[60:63], v[240:243], v[180:183], v[60:63]
	v_mfma_f32_16x16x32_bf16 v[44:47], v[244:247], v[180:183], v[44:47]
	v_mfma_f32_16x16x32_bf16 v[16:19], v[248:251], v[180:183], v[16:19]
	v_mfma_f32_16x16x32_bf16 v[36:39], v[252:255], v[180:183], v[36:39]
	ds_read_b128 v[180:183], v134 offset:33792
	v_mfma_f32_16x16x32_bf16 v[56:59], v[240:243], v[184:187], v[56:59]
	v_mfma_f32_16x16x32_bf16 v[40:43], v[244:247], v[184:187], v[40:43]
	v_mfma_f32_16x16x32_bf16 v[12:15], v[248:251], v[184:187], v[12:15]
	v_mfma_f32_16x16x32_bf16 v[28:31], v[252:255], v[184:187], v[28:31]
	ds_read_b128 v[184:187], v134 offset:35840
	v_mfma_f32_16x16x32_bf16 v[52:55], v[240:243], v[188:191], v[52:55]
	v_mfma_f32_16x16x32_bf16 v[32:35], v[244:247], v[188:191], v[32:35]
	v_mfma_f32_16x16x32_bf16 v[4:7], v[248:251], v[188:191], v[4:7]
	v_mfma_f32_16x16x32_bf16 v[20:23], v[252:255], v[188:191], v[20:23]
	ds_read_b128 v[188:191], v134 offset:37888
	v_mfma_f32_16x16x32_bf16 v[48:51], v[240:243], v[192:195], v[48:51]
	v_mfma_f32_16x16x32_bf16 v[24:27], v[244:247], v[192:195], v[24:27]
	v_mfma_f32_16x16x32_bf16 v[0:3], v[248:251], v[192:195], v[0:3]
	v_mfma_f32_16x16x32_bf16 v[8:11], v[252:255], v[192:195], v[8:11]
	ds_read_b128 v[192:195], v134 offset:39936
	s_waitcnt lgkmcnt(3)
	v_mfma_f32_16x16x32_bf16 v[124:127], v[160:163], v[180:183], v[124:127]
	v_mfma_f32_16x16x32_bf16 v[108:111], v[168:171], v[180:183], v[108:111]
	v_mfma_f32_16x16x32_bf16 v[92:95], v[172:175], v[180:183], v[92:95]
	v_mfma_f32_16x16x32_bf16 v[76:79], v[176:179], v[180:183], v[76:79]
	ds_read_b128 v[240:243], v200 offset:1024
	ds_read_b128 v[244:247], v201 offset:1024
	s_waitcnt lgkmcnt(4)
	v_mfma_f32_16x16x32_bf16 v[120:123], v[160:163], v[184:187], v[120:123]
	v_mfma_f32_16x16x32_bf16 v[104:107], v[168:171], v[184:187], v[104:107]
	v_mfma_f32_16x16x32_bf16 v[88:91], v[172:175], v[184:187], v[88:91]
	v_mfma_f32_16x16x32_bf16 v[72:75], v[176:179], v[184:187], v[72:75]
	ds_read_b128 v[248:251], v202 offset:1024
	ds_read_b128 v[252:255], v203 offset:1024
	s_waitcnt lgkmcnt(5)
	v_mfma_f32_16x16x32_bf16 v[116:119], v[160:163], v[188:191], v[116:119]
	v_mfma_f32_16x16x32_bf16 v[100:103], v[168:171], v[188:191], v[100:103]
	v_mfma_f32_16x16x32_bf16 v[84:87], v[172:175], v[188:191], v[84:87]
	v_mfma_f32_16x16x32_bf16 v[68:71], v[176:179], v[188:191], v[68:71]
	s_waitcnt lgkmcnt(4)
	v_mfma_f32_16x16x32_bf16 v[112:115], v[160:163], v[192:195], v[112:115]
	v_mfma_f32_16x16x32_bf16 v[96:99], v[168:171], v[192:195], v[96:99]
	v_mfma_f32_16x16x32_bf16 v[80:83], v[172:175], v[192:195], v[80:83]
	v_mfma_f32_16x16x32_bf16 v[64:67], v[176:179], v[192:195], v[64:67]
	s_waitcnt vmcnt(0) lgkmcnt(0)
	s_barrier
	s_add_i32 s101, s100, s27
	v_mfma_f32_16x16x32_bf16 v[60:63], v[240:243], v[180:183], v[60:63]
	v_mfma_f32_16x16x32_bf16 v[44:47], v[244:247], v[180:183], v[44:47]
	v_mfma_f32_16x16x32_bf16 v[16:19], v[248:251], v[180:183], v[16:19]
	v_mfma_f32_16x16x32_bf16 v[36:39], v[252:255], v[180:183], v[36:39]
	v_add3_u32 v134, s38, v149, v150
	ds_read_b128 v[180:183], v134 offset:32768
	v_add3_u32 v196, s38, v149, v151
	v_add3_u32 v197, s38, v153, v152
	v_add3_u32 v198, s38, v153, v154
	v_add3_u32 v199, s38, v153, v155
	ds_read_b128 v[160:163], v196
	ds_read_b128 v[168:171], v197
	ds_read_b128 v[172:175], v198
	ds_read_b128 v[176:179], v199
	s_cmpk_eq_i32 s4, 0x700
	s_cbranch_scc1 .Lpk_150_0
	s_mov_b32 m0, s101
	v_lshl_add_u64 v[146:147], v[146:147], 0, s[98:99]
	global_load_lds_dwordx4 v[146:147], off
.Lpk_150_0:
	s_cmpk_eq_i32 s4, 0x700
	s_cbranch_scc1 .Lpk_150_1
	s_add_i32 m0, s101, 0x8000
	v_lshl_add_u64 v[138:139], v[138:139], 0, s[98:99]
	global_load_lds_dwordx4 v[138:139], off
.Lpk_150_1:
	v_mfma_f32_16x16x32_bf16 v[56:59], v[240:243], v[184:187], v[56:59]
	v_mfma_f32_16x16x32_bf16 v[40:43], v[244:247], v[184:187], v[40:43]
	v_mfma_f32_16x16x32_bf16 v[12:15], v[248:251], v[184:187], v[12:15]
	v_mfma_f32_16x16x32_bf16 v[28:31], v[252:255], v[184:187], v[28:31]
	ds_read_b128 v[184:187], v134 offset:34816
	v_add3_u32 v200, s38, v153, v156
	v_add3_u32 v201, s38, v153, v157
	v_add3_u32 v202, s38, v153, v158
	v_add3_u32 v203, s38, v153, v159
	s_cmpk_eq_i32 s4, 0x700
	s_cbranch_scc1 .Lpk_150_2
	s_add_i32 m0, s101, 0x2000
	v_lshl_add_u64 v[144:145], v[144:145], 0, s[98:99]
	global_load_lds_dwordx4 v[144:145], off
.Lpk_150_2:
	s_cmpk_eq_i32 s4, 0x700
	s_cbranch_scc1 .Lpk_150_3
	s_add_i32 m0, s101, 0xa000
	v_lshl_add_u64 v[136:137], v[136:137], 0, s[98:99]
	global_load_lds_dwordx4 v[136:137], off
.Lpk_150_3:
	v_mfma_f32_16x16x32_bf16 v[52:55], v[240:243], v[188:191], v[52:55]
	v_mfma_f32_16x16x32_bf16 v[32:35], v[244:247], v[188:191], v[32:35]
	v_mfma_f32_16x16x32_bf16 v[4:7], v[248:251], v[188:191], v[4:7]
	v_mfma_f32_16x16x32_bf16 v[20:23], v[252:255], v[188:191], v[20:23]
	ds_read_b128 v[188:191], v134 offset:36864
	s_cmpk_eq_i32 s4, 0x700
	s_cbranch_scc1 .Lpk_150_4
	s_add_i32 m0, s101, 0x4000
	v_lshl_add_u64 v[142:143], v[142:143], 0, s[98:99]
	global_load_lds_dwordx4 v[142:143], off
.Lpk_150_4:
	s_cmpk_eq_i32 s4, 0x700
	s_cbranch_scc1 .Lpk_150_5
	s_add_i32 m0, s101, 0xc000
	v_lshl_add_u64 v[130:131], v[130:131], 0, s[98:99]
	global_load_lds_dwordx4 v[130:131], off
.Lpk_150_5:
	v_mfma_f32_16x16x32_bf16 v[48:51], v[240:243], v[192:195], v[48:51]
	v_mfma_f32_16x16x32_bf16 v[24:27], v[244:247], v[192:195], v[24:27]
	v_mfma_f32_16x16x32_bf16 v[0:3], v[248:251], v[192:195], v[0:3]
	v_mfma_f32_16x16x32_bf16 v[8:11], v[252:255], v[192:195], v[8:11]
	ds_read_b128 v[192:195], v134 offset:38912
	s_cmpk_eq_i32 s4, 0x700
	s_cbranch_scc1 .Lpk_150_6
	s_add_i32 m0, s101, 0x6000
	v_lshl_add_u64 v[140:141], v[140:141], 0, s[98:99]
	global_load_lds_dwordx4 v[140:141], off
.Lpk_150_6:
	s_cmpk_eq_i32 s4, 0x700
	s_cbranch_scc1 .Lpk_150_7
	s_add_i32 m0, s101, 0xe000
	v_lshl_add_u64 v[128:129], v[128:129], 0, s[98:99]
	global_load_lds_dwordx4 v[128:129], off
.Lpk_150_7:
	s_add_i32 s37, s37, 0x10000
	s_add_u32 s4, s4, 0x80
	s_addc_u32 s5, s5, 0
	s_cmpk_lg_i32 s4, 0x780
	s_cbranch_scc1 .LBB0_150
	s_waitcnt lgkmcnt(0)
	s_add_i32 s27, 0, 0x10000
	v_add3_u32 v134, s27, v153, v159
	ds_read_b128 v[128:131], v134
	v_add3_u32 v200, s27, v153, v158
	v_add3_u32 v201, s27, v153, v157
	v_add3_u32 v202, s27, v153, v156
	v_add3_u32 v203, s27, v153, v155
	v_add3_u32 v204, s27, v153, v154
	v_add3_u32 v205, s27, v153, v152
	v_add3_u32 v188, s27, v149, v151
	v_add3_u32 v196, s52, v149, v150
	ds_read_b128 v[136:139], v200
	ds_read_b128 v[140:143], v201
	ds_read_b128 v[144:147], v202
	ds_read_b128 v[156:159], v203
	ds_read_b128 v[160:163], v204
	ds_read_b128 v[152:155], v205
	ds_read_b128 v[168:171], v188
	ds_read_b128 v[148:151], v196
	s_waitcnt lgkmcnt(0)
	v_mfma_f32_16x16x32_bf16 v[172:175], v[128:131], v[148:151], v[36:39]
	s_nop 2
	ds_read_b128 v[36:39], v196 offset:2048
	s_waitcnt lgkmcnt(0)
	v_mfma_f32_16x16x32_bf16 v[176:179], v[128:131], v[36:39], v[28:31]
	s_nop 2
	ds_read_b128 v[28:31], v196 offset:4096
	s_waitcnt lgkmcnt(0)
	v_mfma_f32_16x16x32_bf16 v[4:7], v[136:139], v[28:31], v[4:7]
	v_mfma_f32_16x16x32_bf16 v[76:79], v[156:159], v[148:151], v[76:79]
	v_mfma_f32_16x16x32_bf16 v[104:107], v[152:155], v[36:39], v[104:107]
	v_mfma_f32_16x16x32_bf16 v[88:91], v[160:163], v[36:39], v[88:91]
	v_mfma_f32_16x16x32_bf16 v[72:75], v[156:159], v[36:39], v[72:75]
	v_mfma_f32_16x16x32_bf16 v[180:183], v[128:131], v[28:31], v[20:23]
	v_mfma_f32_16x16x32_bf16 v[184:187], v[160:163], v[28:31], v[84:87]
	v_mfma_f32_16x16x32_bf16 v[68:71], v[156:159], v[28:31], v[68:71]
	s_nop 0
	ds_read_b128 v[20:23], v196 offset:6144
	s_waitcnt lgkmcnt(0)
	v_mfma_f32_16x16x32_bf16 v[64:67], v[156:159], v[20:23], v[64:67]
	v_mfma_f32_16x16x32_bf16 v[84:87], v[168:171], v[36:39], v[120:123]
	v_mfma_f32_16x16x32_bf16 v[156:159], v[144:147], v[36:39], v[56:59]
	v_mfma_f32_16x16x32_bf16 v[40:43], v[140:143], v[36:39], v[40:43]
	v_mfma_f32_16x16x32_bf16 v[36:39], v[136:139], v[36:39], v[12:15]
	v_mfma_f32_16x16x32_bf16 v[108:111], v[152:155], v[148:151], v[108:111]
	v_mfma_f32_16x16x32_bf16 v[100:103], v[152:155], v[28:31], v[100:103]
	v_mfma_f32_16x16x32_bf16 v[128:131], v[128:131], v[20:23], v[8:11]
	v_mfma_f32_16x16x32_bf16 v[8:11], v[168:171], v[20:23], v[112:115]
	v_mfma_f32_16x16x32_bf16 v[96:99], v[152:155], v[20:23], v[96:99]
	v_mfma_f32_16x16x32_bf16 v[112:115], v[168:171], v[28:31], v[116:119]
	v_mfma_f32_16x16x32_bf16 v[116:119], v[168:171], v[148:151], v[124:127]
	v_mfma_f32_16x16x32_bf16 v[120:123], v[160:163], v[148:151], v[92:95]
	v_mfma_f32_16x16x32_bf16 v[152:155], v[144:147], v[148:151], v[60:63]
	v_mfma_f32_16x16x32_bf16 v[168:171], v[140:143], v[148:151], v[44:47]
	v_mfma_f32_16x16x32_bf16 v[148:151], v[136:139], v[148:151], v[16:19]
	v_mfma_f32_16x16x32_bf16 v[32:35], v[140:143], v[28:31], v[32:35]
	v_mfma_f32_16x16x32_bf16 v[140:143], v[140:143], v[20:23], v[24:27]
	v_mfma_f32_16x16x32_bf16 v[80:83], v[160:163], v[20:23], v[80:83]
	v_mfma_f32_16x16x32_bf16 v[0:3], v[136:139], v[20:23], v[0:3]
	v_mfma_f32_16x16x32_bf16 v[160:163], v[144:147], v[28:31], v[52:55]
	v_mfma_f32_16x16x32_bf16 v[144:147], v[144:147], v[20:23], v[48:51]
	ds_read_b128 v[12:15], v188 offset:1024
	ds_read_b128 v[16:19], v205 offset:1024
	ds_read_b128 v[24:27], v204 offset:1024
	ds_read_b128 v[44:47], v203 offset:1024
	ds_read_b128 v[136:139], v196 offset:1024
	ds_read_b128 v[188:191], v196 offset:3072
	ds_read_b128 v[192:195], v196 offset:5120
	ds_read_b128 v[196:199], v196 offset:7168
	s_waitcnt lgkmcnt(3)
	v_mfma_f32_16x16x32_bf16 v[116:119], v[12:15], v[136:139], v[116:119]
	s_waitcnt lgkmcnt(2)
	v_mfma_f32_16x16x32_bf16 v[84:87], v[12:15], v[188:191], v[84:87]
	s_waitcnt lgkmcnt(1)
	v_mfma_f32_16x16x32_bf16 v[52:55], v[12:15], v[192:195], v[112:115]
	s_waitcnt lgkmcnt(0)
	v_mfma_f32_16x16x32_bf16 v[20:23], v[12:15], v[196:199], v[8:11]
	s_nop 2
	ds_read_b128 v[8:11], v202 offset:1024
	v_mfma_f32_16x16x32_bf16 v[124:127], v[16:19], v[136:139], v[108:111]
	v_mfma_f32_16x16x32_bf16 v[92:95], v[16:19], v[188:191], v[104:107]
	v_mfma_f32_16x16x32_bf16 v[60:63], v[16:19], v[192:195], v[100:103]
	v_mfma_f32_16x16x32_bf16 v[28:31], v[16:19], v[196:199], v[96:99]
	s_nop 2
	ds_read_b128 v[96:99], v201 offset:1024
	v_mfma_f32_16x16x32_bf16 v[120:123], v[24:27], v[136:139], v[120:123]
	v_mfma_f32_16x16x32_bf16 v[88:91], v[24:27], v[188:191], v[88:91]
	v_mfma_f32_16x16x32_bf16 v[56:59], v[24:27], v[192:195], v[184:187]
	v_mfma_f32_16x16x32_bf16 v[24:27], v[24:27], v[196:199], v[80:83]
	s_nop 1
	ds_read_b128 v[184:187], v200 offset:1024
	v_mfma_f32_16x16x32_bf16 v[112:115], v[44:47], v[136:139], v[76:79]
	v_mfma_f32_16x16x32_bf16 v[80:83], v[44:47], v[188:191], v[72:75]
	v_mfma_f32_16x16x32_bf16 v[48:51], v[44:47], v[192:195], v[68:71]
	v_mfma_f32_16x16x32_bf16 v[16:19], v[44:47], v[196:199], v[64:67]
	ds_read_b128 v[200:203], v134 offset:1024
	s_waitcnt lgkmcnt(3)
	v_mfma_f32_16x16x32_bf16 v[108:111], v[8:11], v[136:139], v[152:155]
	v_mfma_f32_16x16x32_bf16 v[76:79], v[8:11], v[188:191], v[156:159]
	v_mfma_f32_16x16x32_bf16 v[44:47], v[8:11], v[192:195], v[160:163]
	v_mfma_f32_16x16x32_bf16 v[12:15], v[8:11], v[196:199], v[144:147]
	s_waitcnt lgkmcnt(2)
	v_mfma_f32_16x16x32_bf16 v[104:107], v[96:99], v[136:139], v[168:171]
	v_mfma_f32_16x16x32_bf16 v[72:75], v[96:99], v[188:191], v[40:43]
	v_mfma_f32_16x16x32_bf16 v[40:43], v[96:99], v[192:195], v[32:35]
	v_mfma_f32_16x16x32_bf16 v[8:11], v[96:99], v[196:199], v[140:143]
	s_waitcnt lgkmcnt(1)
	v_mfma_f32_16x16x32_bf16 v[100:103], v[184:187], v[136:139], v[148:151]
	v_mfma_f32_16x16x32_bf16 v[68:71], v[184:187], v[188:191], v[36:39]
	v_mfma_f32_16x16x32_bf16 v[36:39], v[184:187], v[192:195], v[4:7]
	v_mfma_f32_16x16x32_bf16 v[0:3], v[184:187], v[196:199], v[0:3]
	s_waitcnt lgkmcnt(0)
	v_mfma_f32_16x16x32_bf16 v[96:99], v[200:203], v[136:139], v[172:175]
	v_mfma_f32_16x16x32_bf16 v[64:67], v[200:203], v[188:191], v[176:179]
	v_mfma_f32_16x16x32_bf16 v[32:35], v[200:203], v[192:195], v[180:183]
	v_mfma_f32_16x16x32_bf16 v[4:7], v[200:203], v[196:199], v[128:131]
	v_mov_b32_e32 v172, v132
	s_waitcnt vmcnt(0)
	s_barrier
	s_and_b64 vcc, exec, s[34:35]
	v_ashrrev_i32_e32 v128, 1, v172
	v_and_b32_e32 v171, 0xffffff80, v128
	v_and_b32_e32 v170, 15, v172
	v_bfe_u32 v169, v172, 4, 2
	v_add_u32_e32 v168, s66, v171
	s_cbranch_vccz .LBB0_154
	v_lshlrev_b32_e32 v144, 2, v169
	v_and_b32_e32 v173, 64, v172
	v_or_b32_e32 v154, v168, v144
	v_lshrrev_b32_e32 v145, 6, v168
	v_cmp_eq_u32_e32 vcc, 0, v173
	v_or_b32_e32 v130, 1, v154
	s_add_u32 s4, s6, 0x22b6000
	v_cndmask_b32_e32 v128, v144, v145, vcc
	v_lshlrev_b32_e32 v128, 5, v128
	v_cndmask_b32_e32 v130, v130, v145, vcc
	v_and_or_b32 v128, v128, s53, v170
	v_lshlrev_b32_e32 v130, 5, v130
	s_addc_u32 s5, s36, 0
	v_lshlrev_b32_e32 v134, 3, v128
	v_and_or_b32 v130, v130, s54, v170
	v_lshl_add_u64 v[128:129], s[4:5], 0, v[134:135]
	v_lshlrev_b32_e32 v134, 3, v130
	v_lshl_add_u64 v[130:131], s[4:5], 0, v[134:135]
	flat_load_dwordx2 v[142:143], v[128:129]
	flat_load_dwordx2 v[146:147], v[130:131]
	s_nop 0
	flat_load_dwordx2 v[130:131], v[130:131] offset:128
	s_nop 0
	flat_load_dwordx2 v[136:137], v[128:129] offset:128
	v_or_b32_e32 v128, 2, v154
	v_cndmask_b32_e32 v128, v128, v145, vcc
	v_lshlrev_b32_e32 v128, 5, v128
	v_and_or_b32 v128, v128, s54, v170
	v_lshlrev_b32_e32 v134, 3, v128
	v_lshl_add_u64 v[128:129], s[4:5], 0, v[134:135]
	v_or_b32_e32 v134, 3, v154
	v_cndmask_b32_e32 v134, v134, v145, vcc
	v_lshlrev_b32_e32 v134, 5, v134
	v_and_or_b32 v134, v134, s54, v170
	v_lshlrev_b32_e32 v134, 3, v134
	flat_load_dwordx2 v[148:149], v[128:129]
	s_nop 0
	flat_load_dwordx2 v[128:129], v[128:129] offset:128
	v_lshl_add_u64 v[138:139], s[4:5], 0, v[134:135]
	flat_load_dwordx2 v[150:151], v[138:139]
	flat_load_dwordx2 v[152:153], v[138:139] offset:128
	v_or_b32_e32 v134, 16, v154
	v_or_b32_e32 v138, 17, v154
	v_cndmask_b32_e32 v134, v134, v145, vcc
	v_cndmask_b32_e32 v138, v138, v145, vcc
	v_lshlrev_b32_e32 v134, 5, v134
	v_lshlrev_b32_e32 v138, 5, v138
	v_and_or_b32 v134, v134, s54, v170
	v_and_or_b32 v138, v138, s54, v170
	v_lshlrev_b32_e32 v134, 3, v134
	v_lshl_add_u64 v[140:141], s[4:5], 0, v[134:135]
	v_lshlrev_b32_e32 v134, 3, v138
	v_lshl_add_u64 v[156:157], s[4:5], 0, v[134:135]
	flat_load_dwordx2 v[138:139], v[140:141]
	flat_load_dwordx2 v[158:159], v[156:157]
	v_or_b32_e32 v134, 18, v154
	v_or_b32_e32 v155, 19, v154
	v_cndmask_b32_e32 v134, v134, v145, vcc
	v_cndmask_b32_e32 v155, v155, v145, vcc
	v_lshlrev_b32_e32 v134, 5, v134
	v_lshlrev_b32_e32 v155, 5, v155
	v_and_or_b32 v134, v134, s54, v170
	flat_load_dwordx2 v[156:157], v[156:157] offset:128
	s_nop 0
	flat_load_dwordx2 v[140:141], v[140:141] offset:128
	v_and_or_b32 v155, v155, s54, v170
	v_lshlrev_b32_e32 v134, 3, v134
	v_lshl_add_u64 v[160:161], s[4:5], 0, v[134:135]
	v_lshlrev_b32_e32 v134, 3, v155
	v_lshl_add_u64 v[162:163], s[4:5], 0, v[134:135]
	flat_load_dwordx2 v[174:175], v[160:161]
	s_nop 0
	flat_load_dwordx2 v[160:161], v[160:161] offset:128
	s_nop 0
	flat_load_dwordx2 v[176:177], v[162:163]
	s_and_b32 s6, s66, 0xf00
	s_mov_b64 s[38:39], s[6:7]
	s_waitcnt vmcnt(0) lgkmcnt(0)
	v_mov_b32_e32 v178, v143
	v_mov_b32_e32 v179, v147
	v_mov_b32_e32 v143, v146
	v_mov_b32_e32 v146, v137
	v_mov_b32_e32 v147, v131
	v_mov_b32_e32 v137, v130
	v_pk_mul_f32 v[130:131], v[116:117], v[178:179]
	v_pk_mul_f32 v[178:179], v[52:53], v[178:179]
	v_pk_fma_f32 v[52:53], v[52:53], v[142:143], v[130:131]
	v_pk_fma_f32 v[116:117], v[116:117], v[142:143], v[178:179] neg_lo:[0,0,1] neg_hi:[0,0,1]
	v_pk_mul_f32 v[180:181], v[84:85], v[146:147]
	v_pk_mul_f32 v[146:147], v[20:21], v[146:147]
	v_pk_fma_f32 v[20:21], v[20:21], v[136:137], v[180:181]
	v_pk_fma_f32 v[84:85], v[84:85], v[136:137], v[146:147] neg_lo:[0,0,1] neg_hi:[0,0,1]
	v_mul_f32_e32 v182, v118, v148
	v_mul_f32_e32 v184, v54, v149
	v_mul_f32_e32 v186, v118, v149
	v_mul_f32_e32 v148, v54, v148
	v_mul_f32_e32 v188, v86, v128
	v_mul_f32_e32 v190, v22, v129
	v_mul_f32_e32 v192, v86, v129
	v_mul_f32_e32 v194, v22, v128
	v_mov_b32_e32 v54, v119
	v_mov_b32_e32 v118, v55
	v_mov_b32_e32 v22, v87
	v_mov_b32_e32 v86, v23
	v_pk_mul_f32 v[128:129], v[54:55], v[150:151]
	v_pk_mul_f32 v[54:55], v[118:119], v[150:151]
	v_pk_mul_f32 v[118:119], v[22:23], v[152:153]
	v_pk_mul_f32 v[22:23], v[86:87], v[152:153]
	v_mov_b32_e32 v189, v118
	v_mov_b32_e32 v195, v22
	v_or_b32_e32 v22, 32, v154
	v_cndmask_b32_e32 v22, v22, v145, vcc
	v_lshlrev_b32_e32 v22, 5, v22
	v_and_or_b32 v22, v22, s54, v170
	v_lshlrev_b32_e32 v134, 3, v22
	v_or_b32_e32 v22, 33, v154
	v_cndmask_b32_e32 v22, v22, v145, vcc
	v_lshlrev_b32_e32 v22, 5, v22
	v_and_or_b32 v22, v22, s54, v170
	v_mov_b32_e32 v191, v119
	v_lshl_add_u64 v[118:119], s[4:5], 0, v[134:135]
	v_lshlrev_b32_e32 v134, 3, v22
	v_lshl_add_u64 v[142:143], s[4:5], 0, v[134:135]
	v_or_b32_e32 v134, 34, v154
	v_cndmask_b32_e32 v134, v134, v145, vcc
	v_lshlrev_b32_e32 v134, 5, v134
	v_and_or_b32 v134, v134, s54, v170
	v_lshlrev_b32_e32 v134, 3, v134
	v_lshl_add_u64 v[136:137], s[4:5], 0, v[134:135]
	flat_load_dwordx2 v[86:87], v[162:163] offset:128
	flat_load_dwordx2 v[146:147], v[118:119]
	flat_load_dwordx2 v[150:151], v[142:143]
	s_nop 0
	flat_load_dwordx2 v[142:143], v[142:143] offset:128
	s_nop 0
	flat_load_dwordx2 v[152:153], v[118:119] offset:128
	v_mov_b32_e32 v118, v139
	v_mov_b32_e32 v119, v159
	v_mov_b32_e32 v139, v158
	flat_load_dwordx2 v[158:159], v[136:137]
	v_mov_b32_e32 v149, v54
	v_mov_b32_e32 v187, v55
	v_pk_add_f32 v[54:55], v[148:149], v[186:187]
	v_mov_b32_e32 v148, v141
	v_mov_b32_e32 v149, v157
	v_pk_mul_f32 v[178:179], v[92:93], v[148:149]
	v_mov_b32_e32 v141, v156
	flat_load_dwordx2 v[156:157], v[136:137] offset:128
	v_pk_mul_f32 v[180:181], v[28:29], v[148:149]
	v_mul_f32_e32 v136, v126, v174
	v_mul_f32_e32 v148, v62, v175
	v_mul_f32_e32 v174, v62, v174
	v_or_b32_e32 v62, 35, v154
	v_pk_add_f32 v[130:131], v[188:189], v[190:191] neg_lo:[0,1] neg_hi:[0,1]
	v_cndmask_b32_e32 v62, v62, v145, vcc
	v_mul_f32_e32 v188, v94, v160
	v_mul_f32_e32 v190, v30, v161
	v_mul_f32_e32 v160, v30, v160
	v_or_b32_e32 v30, 48, v154
	v_lshlrev_b32_e32 v62, 5, v62
	v_cndmask_b32_e32 v30, v30, v145, vcc
	v_and_or_b32 v62, v62, s54, v170
	v_lshlrev_b32_e32 v30, 5, v30
	v_mov_b32_e32 v183, v128
	v_mov_b32_e32 v185, v129
	v_lshlrev_b32_e32 v134, 3, v62
	v_and_or_b32 v30, v30, s54, v170
	v_pk_add_f32 v[128:129], v[182:183], v[184:185] neg_lo:[0,1] neg_hi:[0,1]
	v_lshl_add_u64 v[184:185], s[4:5], 0, v[134:135]
	v_lshlrev_b32_e32 v134, 3, v30
	v_or_b32_e32 v30, 49, v154
	v_cndmask_b32_e32 v30, v30, v145, vcc
	v_mov_b32_e32 v193, v23
	v_mov_b32_e32 v62, v127
	v_lshlrev_b32_e32 v30, 5, v30
	v_pk_add_f32 v[22:23], v[194:195], v[192:193]
	v_pk_mul_f32 v[194:195], v[62:63], v[176:177]
	v_and_or_b32 v30, v30, s54, v170
	v_mov_b32_e32 v137, v194
	v_mov_b32_e32 v149, v195
	v_lshl_add_u64 v[194:195], s[4:5], 0, v[134:135]
	v_lshlrev_b32_e32 v134, 3, v30
	v_pk_mul_f32 v[162:163], v[124:125], v[118:119]
	v_pk_mul_f32 v[118:119], v[60:61], v[118:119]
	v_lshl_add_u64 v[196:197], s[4:5], 0, v[134:135]
	flat_load_dwordx2 v[186:187], v[184:185]
	v_pk_fma_f32 v[124:125], v[124:125], v[138:139], v[118:119] neg_lo:[0,0,1] neg_hi:[0,0,1]
	flat_load_dwordx2 v[184:185], v[184:185] offset:128
	s_nop 0
	flat_load_dwordx2 v[118:119], v[194:195]
	flat_load_dwordx2 v[198:199], v[196:197]
	v_pk_add_f32 v[136:137], v[136:137], v[148:149] neg_lo:[0,1] neg_hi:[0,1]
	flat_load_dwordx2 v[196:197], v[196:197] offset:128
	s_nop 0
	flat_load_dwordx2 v[148:149], v[194:195] offset:128
	v_or_b32_e32 v134, 50, v154
	v_cndmask_b32_e32 v134, v134, v145, vcc
	v_lshlrev_b32_e32 v134, 5, v134
	v_mul_f32_e32 v182, v126, v175
	v_mov_b32_e32 v126, v63
	v_and_or_b32 v134, v134, s54, v170
	v_pk_mul_f32 v[62:63], v[126:127], v[176:177]
	v_lshlrev_b32_e32 v134, 3, v134
	v_mul_f32_e32 v192, v94, v161
	v_mov_b32_e32 v175, v62
	v_mov_b32_e32 v183, v63
	v_mov_b32_e32 v30, v95
	v_pk_fma_f32 v[92:93], v[92:93], v[140:141], v[180:181] neg_lo:[0,0,1] neg_hi:[0,0,1]
	v_mov_b32_e32 v94, v31
	v_pk_fma_f32 v[28:29], v[28:29], v[140:141], v[178:179]
	v_lshl_add_u64 v[140:141], s[4:5], 0, v[134:135]
	v_pk_fma_f32 v[60:61], v[60:61], v[138:139], v[162:163]
	v_pk_add_f32 v[62:63], v[174:175], v[182:183]
	flat_load_dwordx2 v[174:175], v[140:141] offset:128
	s_waitcnt vmcnt(0) lgkmcnt(0)
	v_pk_mul_f32 v[126:127], v[30:31], v[86:87]
	v_pk_mul_f32 v[30:31], v[94:95], v[86:87]
	v_mov_b32_e32 v86, v147
	v_mov_b32_e32 v87, v151
	v_mov_b32_e32 v147, v150
	flat_load_dwordx2 v[150:151], v[140:141]
	v_mul_f32_e32 v162, v122, v158
	v_mul_f32_e32 v140, v58, v159
	v_mul_f32_e32 v158, v58, v158
	v_or_b32_e32 v58, 51, v154
	v_cndmask_b32_e32 v58, v58, v145, vcc
	v_lshlrev_b32_e32 v58, 5, v58
	v_and_or_b32 v58, v58, s54, v170
	v_mov_b32_e32 v189, v126
	v_mov_b32_e32 v191, v127
	v_lshlrev_b32_e32 v134, 3, v58
	v_pk_add_f32 v[138:139], v[188:189], v[190:191] neg_lo:[0,1] neg_hi:[0,1]
	v_mov_b32_e32 v161, v30
	v_mov_b32_e32 v193, v31
	v_mov_b32_e32 v94, v153
	v_mov_b32_e32 v95, v143
	v_lshl_add_u64 v[188:189], s[4:5], 0, v[134:135]
	v_pk_add_f32 v[30:31], v[160:161], v[192:193]
	v_pk_mul_f32 v[160:161], v[88:89], v[94:95]
	v_mov_b32_e32 v153, v142
	v_pk_mul_f32 v[142:143], v[24:25], v[94:95]
	flat_load_dwordx2 v[94:95], v[188:189]
	v_pk_mul_f32 v[126:127], v[120:121], v[86:87]
	v_pk_mul_f32 v[86:87], v[56:57], v[86:87]
	v_mul_f32_e32 v178, v90, v156
	v_mul_f32_e32 v180, v26, v157
	v_mul_f32_e32 v182, v90, v157
	v_mul_f32_e32 v156, v26, v156
	v_mov_b32_e32 v26, v91
	v_mov_b32_e32 v90, v27
	v_pk_fma_f32 v[120:121], v[120:121], v[146:147], v[86:87] neg_lo:[0,0,1] neg_hi:[0,0,1]
	v_pk_fma_f32 v[56:57], v[56:57], v[146:147], v[126:127]
	v_mul_f32_e32 v176, v122, v159
	v_mov_b32_e32 v58, v123
	v_mov_b32_e32 v122, v59
	v_pk_fma_f32 v[88:89], v[88:89], v[152:153], v[142:143] neg_lo:[0,0,1] neg_hi:[0,0,1]
	v_pk_fma_f32 v[24:25], v[24:25], v[152:153], v[160:161]
	flat_load_dwordx2 v[152:153], v[188:189] offset:128
	v_pk_mul_f32 v[190:191], v[58:59], v[186:187]
	v_pk_mul_f32 v[58:59], v[122:123], v[186:187]
	v_pk_mul_f32 v[86:87], v[26:27], v[184:185]
	v_pk_mul_f32 v[26:27], v[90:91], v[184:185]
	v_mov_b32_e32 v91, v197
	v_mov_b32_e32 v90, v149
	v_pk_mul_f32 v[126:127], v[80:81], v[90:91]
	v_pk_mul_f32 v[146:147], v[16:17], v[90:91]
	v_or_b32_e32 v90, 1, v145
	v_cndmask_b32_e32 v90, v144, v90, vcc
	v_lshlrev_b32_e32 v90, 5, v90
	v_and_or_b32 v90, v90, s54, v170
	v_lshlrev_b32_e32 v134, 3, v90
	v_lshl_add_u64 v[90:91], s[4:5], 0, v[134:135]
	v_or_b32_e32 v134, 0x41, v154
	v_lshrrev_b32_e32 v144, 6, v134
	v_cndmask_b32_e32 v134, v134, v144, vcc
	v_lshlrev_b32_e32 v134, 5, v134
	v_and_or_b32 v134, v134, s54, v170
	v_mov_b32_e32 v163, v190
	v_mov_b32_e32 v141, v191
	v_mov_b32_e32 v159, v58
	v_mov_b32_e32 v177, v59
	v_mov_b32_e32 v157, v26
	v_mov_b32_e32 v183, v27
	v_lshlrev_b32_e32 v134, 3, v134
	v_pk_add_f32 v[140:141], v[162:163], v[140:141] neg_lo:[0,1] neg_hi:[0,1]
	v_pk_add_f32 v[58:59], v[158:159], v[176:177]
	v_pk_add_f32 v[26:27], v[156:157], v[182:183]
	v_lshl_add_u64 v[144:145], s[4:5], 0, v[134:135]
	flat_load_dwordx2 v[156:157], v[90:91]
	flat_load_dwordx2 v[158:159], v[144:145]
	flat_load_dwordx2 v[160:161], v[144:145] offset:128
	flat_load_dwordx2 v[162:163], v[90:91] offset:128
	v_or_b32_e32 v90, 0x42, v154
	v_lshrrev_b32_e32 v91, 6, v90
	v_cndmask_b32_e32 v90, v90, v91, vcc
	v_lshlrev_b32_e32 v90, 5, v90
	v_and_or_b32 v90, v90, s54, v170
	v_lshlrev_b32_e32 v134, 3, v90
	v_lshl_add_u64 v[90:91], s[4:5], 0, v[134:135]
	flat_load_dwordx2 v[182:183], v[90:91] offset:128
	flat_load_dwordx2 v[176:177], v[90:91]
	v_mov_b32_e32 v179, v86
	v_mov_b32_e32 v181, v87
	v_mul_f32_e32 v184, v82, v174
	v_mul_f32_e32 v186, v18, v175
	v_mul_f32_e32 v174, v18, v174
	v_or_b32_e32 v18, 0x43, v154
	v_pk_add_f32 v[142:143], v[178:179], v[180:181] neg_lo:[0,1] neg_hi:[0,1]
	s_waitcnt vmcnt(0) lgkmcnt(0)
	v_mul_f32_e32 v144, v114, v150
	v_mul_f32_e32 v178, v50, v151
	v_mul_f32_e32 v150, v50, v150
	v_lshrrev_b32_e32 v50, 6, v18
	v_cndmask_b32_e32 v18, v18, v50, vcc
	v_lshlrev_b32_e32 v18, 5, v18
	v_and_or_b32 v18, v18, s54, v170
	v_lshlrev_b32_e32 v134, 3, v18
	v_mov_b32_e32 v50, v115
	v_or_b32_e32 v18, 0x50, v154
	v_pk_mul_f32 v[192:193], v[50:51], v[94:95]
	v_lshrrev_b32_e32 v50, 6, v18
	v_cndmask_b32_e32 v18, v18, v50, vcc
	v_lshlrev_b32_e32 v18, 5, v18
	v_and_or_b32 v18, v18, s54, v170
	v_lshl_add_u64 v[90:91], s[4:5], 0, v[134:135]
	v_lshlrev_b32_e32 v134, 3, v18
	v_or_b32_e32 v18, 0x51, v154
	v_mul_f32_e32 v188, v82, v175
	v_lshrrev_b32_e32 v82, 6, v18
	v_cndmask_b32_e32 v18, v18, v82, vcc
	v_lshlrev_b32_e32 v18, 5, v18
	v_mov_b32_e32 v86, v119
	v_mov_b32_e32 v87, v199
	v_and_or_b32 v18, v18, s54, v170
	v_pk_mul_f32 v[122:123], v[112:113], v[86:87]
	v_mov_b32_e32 v119, v198
	v_pk_mul_f32 v[86:87], v[48:49], v[86:87]
	v_mul_f32_e32 v180, v114, v151
	v_mov_b32_e32 v114, v51
	v_lshl_add_u64 v[50:51], s[4:5], 0, v[134:135]
	v_lshlrev_b32_e32 v134, 3, v18
	v_mov_b32_e32 v145, v192
	v_mov_b32_e32 v179, v193
	v_pk_fma_f32 v[112:113], v[112:113], v[118:119], v[86:87] neg_lo:[0,0,1] neg_hi:[0,0,1]
	v_lshl_add_u64 v[86:87], s[4:5], 0, v[134:135]
	v_or_b32_e32 v18, 0x52, v154
	flat_load_dwordx2 v[190:191], v[90:91]
	v_pk_add_f32 v[144:145], v[144:145], v[178:179] neg_lo:[0,1] neg_hi:[0,1]
	flat_load_dwordx2 v[178:179], v[90:91] offset:128
	s_nop 0
	flat_load_dwordx2 v[90:91], v[50:51]
	flat_load_dwordx2 v[192:193], v[86:87]
	flat_load_dwordx2 v[194:195], v[86:87] offset:128
	s_nop 0
	flat_load_dwordx2 v[86:87], v[50:51] offset:128
	v_lshrrev_b32_e32 v50, 6, v18
	v_cndmask_b32_e32 v18, v18, v50, vcc
	v_lshlrev_b32_e32 v18, 5, v18
	v_and_or_b32 v18, v18, s54, v170
	v_lshlrev_b32_e32 v134, 3, v18
	v_lshl_add_u64 v[50:51], s[4:5], 0, v[134:135]
	v_pk_mul_f32 v[94:95], v[114:115], v[94:95]
	v_mov_b32_e32 v18, v83
	v_mov_b32_e32 v151, v94
	v_mov_b32_e32 v181, v95
	flat_load_dwordx2 v[94:95], v[50:51] offset:128
	v_mov_b32_e32 v82, v19
	v_pk_mul_f32 v[114:115], v[18:19], v[152:153]
	v_pk_mul_f32 v[18:19], v[82:83], v[152:153]
	v_mov_b32_e32 v149, v196
	v_mov_b32_e32 v175, v18
	v_mov_b32_e32 v189, v19
	flat_load_dwordx2 v[196:197], v[50:51]
	v_pk_add_f32 v[50:51], v[150:151], v[180:181]
	v_pk_add_f32 v[18:19], v[174:175], v[188:189]
	v_mov_b32_e32 v82, v157
	v_mov_b32_e32 v157, v158
	v_mov_b32_e32 v83, v159
	v_pk_fma_f32 v[48:49], v[48:49], v[118:119], v[122:123]
	v_mov_b32_e32 v185, v114
	v_mov_b32_e32 v187, v115
	v_pk_fma_f32 v[80:81], v[80:81], v[148:149], v[146:147] neg_lo:[0,0,1] neg_hi:[0,0,1]
	v_pk_fma_f32 v[16:17], v[16:17], v[148:149], v[126:127]
	v_pk_mul_f32 v[114:115], v[108:109], v[82:83]
	v_pk_mul_f32 v[118:119], v[44:45], v[82:83]
	v_mul_f32_e32 v174, v14, v183
	v_mul_f32_e32 v180, v14, v182
	v_or_b32_e32 v14, 0x53, v154
	v_mul_f32_e32 v150, v46, v177
	v_mul_f32_e32 v158, v46, v176
	v_lshrrev_b32_e32 v46, 6, v14
	v_cndmask_b32_e32 v14, v14, v46, vcc
	v_lshlrev_b32_e32 v14, 5, v14
	v_and_or_b32 v14, v14, s54, v170
	v_lshlrev_b32_e32 v134, 3, v14
	v_mov_b32_e32 v82, v163
	v_mov_b32_e32 v83, v161
	v_mov_b32_e32 v163, v160
	v_mul_f32_e32 v148, v110, v176
	v_mul_f32_e32 v160, v78, v182
	v_mul_f32_e32 v176, v78, v183
	v_lshl_add_u64 v[182:183], s[4:5], 0, v[134:135]
	v_pk_mul_f32 v[122:123], v[76:77], v[82:83]
	v_pk_mul_f32 v[126:127], v[12:13], v[82:83]
	flat_load_dwordx2 v[82:83], v[182:183]
	v_pk_fma_f32 v[12:13], v[12:13], v[162:163], v[122:123]
	flat_load_dwordx2 v[122:123], v[182:183] offset:128
	v_mul_f32_e32 v152, v110, v177
	v_mov_b32_e32 v46, v111
	v_mov_b32_e32 v110, v47
	v_mov_b32_e32 v14, v79
	v_pk_add_f32 v[146:147], v[184:185], v[186:187] neg_lo:[0,1] neg_hi:[0,1]
	v_pk_fma_f32 v[76:77], v[76:77], v[162:163], v[126:127] neg_lo:[0,0,1] neg_hi:[0,0,1]
	v_mov_b32_e32 v78, v15
	v_pk_fma_f32 v[108:109], v[108:109], v[156:157], v[118:119] neg_lo:[0,0,1] neg_hi:[0,0,1]
	v_pk_fma_f32 v[44:45], v[44:45], v[156:157], v[114:115]
	s_waitcnt vmcnt(0) lgkmcnt(0)
	v_pk_mul_f32 v[184:185], v[46:47], v[190:191]
	v_pk_mul_f32 v[46:47], v[110:111], v[190:191]
	v_pk_mul_f32 v[110:111], v[14:15], v[178:179]
	v_mov_b32_e32 v149, v184
	v_mov_b32_e32 v151, v185
	v_mov_b32_e32 v161, v110
	v_mov_b32_e32 v175, v111
	v_pk_add_f32 v[148:149], v[148:149], v[150:151] neg_lo:[0,1] neg_hi:[0,1]
	v_pk_add_f32 v[150:151], v[160:161], v[174:175] neg_lo:[0,1] neg_hi:[0,1]
	v_pk_mul_f32 v[14:15], v[78:79], v[178:179]
	v_mov_b32_e32 v159, v46
	v_mov_b32_e32 v181, v14
	v_mov_b32_e32 v177, v15
	v_pk_add_f32 v[14:15], v[180:181], v[176:177]
	v_mul_f32_e32 v160, v74, v94
	v_mul_f32_e32 v162, v10, v95
	v_mul_f32_e32 v94, v10, v94
	v_or_b32_e32 v10, 0x60, v154
	v_mul_f32_e32 v174, v74, v95
	v_lshrrev_b32_e32 v74, 6, v10
	v_cndmask_b32_e32 v10, v10, v74, vcc
	v_lshlrev_b32_e32 v10, 5, v10
	v_and_or_b32 v10, v10, s54, v170
	v_lshlrev_b32_e32 v134, 3, v10
	v_or_b32_e32 v10, 0x61, v154
	v_lshrrev_b32_e32 v74, 6, v10
	v_cndmask_b32_e32 v10, v10, v74, vcc
	v_lshlrev_b32_e32 v10, 5, v10
	v_and_or_b32 v10, v10, s54, v170
	v_lshl_add_u64 v[176:177], s[4:5], 0, v[134:135]
	v_lshlrev_b32_e32 v134, 3, v10
	v_or_b32_e32 v10, 0x62, v154
	v_lshrrev_b32_e32 v74, 6, v10
	v_cndmask_b32_e32 v10, v10, v74, vcc
	v_lshlrev_b32_e32 v10, 5, v10
	v_and_or_b32 v10, v10, s54, v170
	v_lshl_add_u64 v[178:179], s[4:5], 0, v[134:135]
	v_lshlrev_b32_e32 v134, 3, v10
	v_or_b32_e32 v10, 0x63, v154
	v_lshrrev_b32_e32 v74, 6, v10
	v_cndmask_b32_e32 v10, v10, v74, vcc
	v_lshlrev_b32_e32 v10, 5, v10
	v_mov_b32_e32 v153, v47
	v_and_or_b32 v10, v10, s54, v170
	v_pk_add_f32 v[46:47], v[158:159], v[152:153]
	v_mul_f32_e32 v152, v42, v197
	v_mul_f32_e32 v158, v42, v196
	v_mov_b32_e32 v42, v107
	v_lshl_add_u64 v[184:185], s[4:5], 0, v[134:135]
	v_lshlrev_b32_e32 v134, 3, v10
	v_or_b32_e32 v10, 0x70, v154
	v_mov_b32_e32 v78, v91
	v_mov_b32_e32 v79, v193
	v_mov_b32_e32 v91, v192
	v_pk_mul_f32 v[192:193], v[42:43], v[82:83]
	v_lshrrev_b32_e32 v42, 6, v10
	v_cndmask_b32_e32 v10, v10, v42, vcc
	v_lshlrev_b32_e32 v10, 5, v10
	v_and_or_b32 v10, v10, s54, v170
	v_lshl_add_u64 v[188:189], s[4:5], 0, v[134:135]
	v_lshlrev_b32_e32 v134, 3, v10
	v_or_b32_e32 v10, 0x71, v154
	v_lshrrev_b32_e32 v74, 6, v10
	v_cndmask_b32_e32 v10, v10, v74, vcc
	v_lshlrev_b32_e32 v10, 5, v10
	v_and_or_b32 v10, v10, s54, v170
	v_mul_f32_e32 v126, v106, v196
	v_mul_f32_e32 v156, v106, v197
	v_mov_b32_e32 v127, v192
	v_mov_b32_e32 v153, v193
	v_mov_b32_e32 v106, v43
	v_lshl_add_u64 v[42:43], s[4:5], 0, v[134:135]
	v_lshlrev_b32_e32 v134, 3, v10
	v_pk_mul_f32 v[114:115], v[40:41], v[78:79]
	v_pk_add_f32 v[152:153], v[126:127], v[152:153] neg_lo:[0,1] neg_hi:[0,1]
	v_lshl_add_u64 v[126:127], s[4:5], 0, v[134:135]
	v_or_b32_e32 v10, 0x72, v154
	v_pk_mul_f32 v[110:111], v[104:105], v[78:79]
	v_mov_b32_e32 v118, v87
	v_mov_b32_e32 v119, v195
	v_mov_b32_e32 v87, v194
	flat_load_dwordx2 v[180:181], v[176:177]
	flat_load_dwordx2 v[182:183], v[178:179]
	s_nop 0
	flat_load_dwordx2 v[178:179], v[178:179] offset:128
	s_nop 0
	flat_load_dwordx2 v[176:177], v[176:177] offset:128
	s_nop 0
	flat_load_dwordx2 v[186:187], v[184:185]
	s_nop 0
	flat_load_dwordx2 v[184:185], v[184:185] offset:128
	v_pk_fma_f32 v[104:105], v[104:105], v[90:91], v[114:115] neg_lo:[0,0,1] neg_hi:[0,0,1]
	flat_load_dwordx2 v[190:191], v[188:189]
	flat_load_dwordx2 v[114:115], v[188:189] offset:128
	s_nop 0
	flat_load_dwordx2 v[188:189], v[42:43]
	flat_load_dwordx2 v[192:193], v[126:127]
	s_nop 0
	flat_load_dwordx2 v[126:127], v[126:127] offset:128
	s_nop 0
	flat_load_dwordx2 v[194:195], v[42:43] offset:128
	v_lshrrev_b32_e32 v42, 6, v10
	v_cndmask_b32_e32 v10, v10, v42, vcc
	v_lshlrev_b32_e32 v10, 5, v10
	v_and_or_b32 v10, v10, s54, v170
	v_lshlrev_b32_e32 v134, 3, v10
	v_lshl_add_u64 v[42:43], s[4:5], 0, v[134:135]
	v_or_b32_e32 v10, 0x73, v154
	flat_load_dwordx2 v[196:197], v[42:43]
	flat_load_dwordx2 v[198:199], v[42:43] offset:128
	v_lshrrev_b32_e32 v42, 6, v10
	v_cndmask_b32_e32 v10, v10, v42, vcc
	v_lshlrev_b32_e32 v10, 5, v10
	v_and_or_b32 v10, v10, s54, v170
	v_lshlrev_b32_e32 v134, 3, v10
	v_mov_b32_e32 v10, v75
	v_lshl_add_u64 v[200:201], s[4:5], 0, v[134:135]
	v_pk_mul_f32 v[42:43], v[106:107], v[82:83]
	v_pk_mul_f32 v[82:83], v[10:11], v[122:123]
	flat_load_dwordx2 v[202:203], v[200:201]
	v_mov_b32_e32 v161, v82
	v_mov_b32_e32 v163, v83
	flat_load_dwordx2 v[82:83], v[200:201] offset:128
	v_mov_b32_e32 v74, v11
	v_pk_mul_f32 v[78:79], v[72:73], v[118:119]
	v_pk_mul_f32 v[118:119], v[8:9], v[118:119]
	v_mov_b32_e32 v159, v42
	v_mov_b32_e32 v157, v43
	v_pk_mul_f32 v[10:11], v[74:75], v[122:123]
	v_pk_add_f32 v[42:43], v[158:159], v[156:157]
	v_pk_fma_f32 v[72:73], v[72:73], v[86:87], v[118:119] neg_lo:[0,0,1] neg_hi:[0,0,1]
	v_pk_add_f32 v[154:155], v[160:161], v[162:163] neg_lo:[0,1] neg_hi:[0,1]
	v_mov_b32_e32 v95, v10
	v_mov_b32_e32 v175, v11
	v_pk_fma_f32 v[8:9], v[8:9], v[86:87], v[78:79]
	v_pk_fma_f32 v[40:41], v[40:41], v[90:91], v[110:111]
	v_pk_add_f32 v[10:11], v[94:95], v[174:175]
	v_mov_b32_e32 v134, v173
	s_waitcnt vmcnt(0) lgkmcnt(0)
	v_mov_b32_e32 v74, v181
	v_mov_b32_e32 v75, v183
	v_pk_mul_f32 v[78:79], v[100:101], v[74:75]
	v_mov_b32_e32 v181, v182
	v_pk_mul_f32 v[74:75], v[36:37], v[74:75]
	v_mul_f32_e32 v106, v38, v187
	v_mul_f32_e32 v118, v38, v186
	v_mul_f32_e32 v158, v2, v185
	v_mul_f32_e32 v162, v2, v184
	v_mov_b32_e32 v38, v103
	v_mov_b32_e32 v2, v71
	v_mul_f32_e32 v94, v102, v186
	v_mul_f32_e32 v110, v102, v187
	v_mul_f32_e32 v122, v70, v184
	v_mul_f32_e32 v160, v70, v185
	v_pk_mul_f32 v[156:157], v[38:39], v[190:191]
	v_pk_fma_f32 v[100:101], v[100:101], v[180:181], v[74:75] neg_lo:[0,0,1] neg_hi:[0,0,1]
	v_mov_b32_e32 v102, v39
	v_pk_mul_f32 v[74:75], v[2:3], v[114:115]
	v_mov_b32_e32 v70, v3
	v_mov_b32_e32 v86, v177
	v_mov_b32_e32 v87, v179
	v_mov_b32_e32 v95, v156
	v_mov_b32_e32 v107, v157
	v_pk_mul_f32 v[38:39], v[102:103], v[190:191]
	v_mov_b32_e32 v123, v74
	v_mov_b32_e32 v159, v75
	v_pk_mul_f32 v[2:3], v[70:71], v[114:115]
	v_mov_b32_e32 v70, v189
	v_mov_b32_e32 v71, v193
	v_pk_mul_f32 v[90:91], v[68:69], v[86:87]
	v_mov_b32_e32 v177, v178
	v_pk_add_f32 v[156:157], v[94:95], v[106:107] neg_lo:[0,1] neg_hi:[0,1]
	v_mov_b32_e32 v119, v38
	v_mov_b32_e32 v111, v39
	v_pk_add_f32 v[158:159], v[122:123], v[158:159] neg_lo:[0,1] neg_hi:[0,1]
	v_pk_mul_f32 v[74:75], v[96:97], v[70:71]
	v_mov_b32_e32 v189, v192
	v_pk_mul_f32 v[70:71], v[32:33], v[70:71]
	v_mul_f32_e32 v94, v34, v197
	v_mul_f32_e32 v106, v34, v196
	v_mul_f32_e32 v114, v6, v199
	v_mul_f32_e32 v122, v6, v198
	v_mov_b32_e32 v34, v99
	v_mov_b32_e32 v6, v67
	v_pk_mul_f32 v[86:87], v[0:1], v[86:87]
	v_pk_fma_f32 v[36:37], v[36:37], v[180:181], v[78:79]
	v_pk_add_f32 v[38:39], v[118:119], v[110:111]
	v_pk_fma_f32 v[0:1], v[0:1], v[176:177], v[90:91]
	v_mov_b32_e32 v78, v195
	v_mov_b32_e32 v79, v127
	v_mov_b32_e32 v195, v126
	v_mul_f32_e32 v90, v98, v196
	v_mul_f32_e32 v102, v98, v197
	v_mul_f32_e32 v110, v66, v198
	v_mul_f32_e32 v118, v66, v199
	v_pk_mul_f32 v[126:127], v[34:35], v[202:203]
	v_pk_fma_f32 v[96:97], v[96:97], v[188:189], v[70:71] neg_lo:[0,0,1] neg_hi:[0,0,1]
	v_mov_b32_e32 v98, v35
	v_pk_mul_f32 v[70:71], v[6:7], v[82:83]
	v_mov_b32_e32 v66, v7
	v_mov_b32_e32 v163, v2
	v_mov_b32_e32 v161, v3
	v_mov_b32_e32 v91, v126
	v_mov_b32_e32 v95, v127
	v_pk_mul_f32 v[34:35], v[98:99], v[202:203]
	v_mov_b32_e32 v111, v70
	v_mov_b32_e32 v115, v71
	v_pk_mul_f32 v[6:7], v[66:67], v[82:83]
	v_pk_fma_f32 v[68:69], v[68:69], v[176:177], v[86:87] neg_lo:[0,0,1] neg_hi:[0,0,1]
	v_pk_add_f32 v[2:3], v[162:163], v[160:161]
	v_pk_mul_f32 v[86:87], v[64:65], v[78:79]
	v_pk_mul_f32 v[78:79], v[4:5], v[78:79]
	v_pk_add_f32 v[160:161], v[90:91], v[94:95] neg_lo:[0,1] neg_hi:[0,1]
	v_mov_b32_e32 v107, v34
	v_mov_b32_e32 v103, v35
	v_pk_add_f32 v[162:163], v[110:111], v[114:115] neg_lo:[0,1] neg_hi:[0,1]
	v_mov_b32_e32 v123, v6
	v_mov_b32_e32 v119, v7
	v_pk_fma_f32 v[32:33], v[32:33], v[188:189], v[74:75]
	v_pk_add_f32 v[34:35], v[106:107], v[102:103]
	v_pk_fma_f32 v[64:65], v[64:65], v[194:195], v[78:79] neg_lo:[0,0,1] neg_hi:[0,0,1]
	v_pk_fma_f32 v[4:5], v[4:5], v[194:195], v[86:87]
	v_pk_add_f32 v[6:7], v[122:123], v[118:119]
	v_mov_b32_e32 v119, v129
	v_mov_b32_e32 v118, v128
	v_mov_b32_e32 v87, v131
	v_mov_b32_e32 v86, v130
	v_mov_b32_e32 v127, v137
	v_mov_b32_e32 v126, v136
	v_mov_b32_e32 v95, v139
	v_mov_b32_e32 v94, v138
	v_mov_b32_e32 v123, v141
	v_mov_b32_e32 v122, v140
	v_mov_b32_e32 v91, v143
	v_mov_b32_e32 v90, v142
	v_mov_b32_e32 v115, v145
	v_mov_b32_e32 v114, v144
	v_mov_b32_e32 v83, v147
	v_mov_b32_e32 v82, v146
	v_mov_b32_e32 v111, v149
	v_mov_b32_e32 v110, v148
	v_mov_b32_e32 v79, v151
	v_mov_b32_e32 v78, v150
	v_mov_b32_e32 v107, v153
	v_mov_b32_e32 v106, v152
	v_mov_b32_e32 v75, v155
	v_mov_b32_e32 v74, v154
	v_mov_b32_e32 v103, v157
	v_mov_b32_e32 v102, v156
	v_mov_b32_e32 v71, v159
	v_mov_b32_e32 v70, v158
	v_mov_b32_e32 v99, v161
	v_mov_b32_e32 v98, v160
	v_mov_b32_e32 v67, v163
	v_mov_b32_e32 v66, v162
	s_cbranch_execz .LBB0_155
	s_mov_b64 s[4:5], 0x10800000
	s_mov_b64 s[42:43], 0x12800000
	s_mov_b64 s[36:37], 12
	s_branch .LBB0_156

.LBB0_163:
	s_cmp_lg_u32 s67, 5
	s_cselect_b64 s[4:5], -1, 0
	s_and_b32 s6, s26, -10
	s_cmp_lg_u32 s6, 4
	s_cselect_b64 s[30:31], -1, 0
	v_mov_b32_e32 v0, s19
	s_and_b64 s[34:35], s[30:31], s[4:5]
	ds_read_b64 v[0:1], v0
	s_and_b64 s[4:5], exec, s[28:29]
	s_cselect_b32 s4, 0x8000, 0
	s_add_i32 s4, s66, s4
	s_ashr_i32 s5, s4, 31
	s_lshl_b64 s[4:5], s[4:5], 11
	s_waitcnt lgkmcnt(0)
	v_readfirstlane_b32 s38, v0
	v_readfirstlane_b32 s39, v1
	v_lshl_add_u64 v[0:1], v[0:1], 0, s[4:5]
	v_lshl_add_u64 v[128:129], v[0:1], 0, s[8:9]
	s_mov_b64 s[30:31], -1
	s_and_b64 vcc, exec, s[34:35]
	s_cbranch_vccz .LBB0_175
	v_mov_b32_e32 v10, v132
	s_ashr_i32 s27, s26, 31
	v_lshlrev_b32_e32 v1, 4, v10
	v_and_b32_e32 v0, 32, v10
	v_lshrrev_b32_e32 v2, 1, v10
	v_bitop3_b32 v0, v1, v0, 48 bitop3:0x6c
	v_bfe_u32 v11, v10, 2, 4
	v_and_b32_e32 v12, 32, v2
	v_lshrrev_b32_e32 v13, 1, v0
	v_ashrrev_i32_e32 v14, 3, v10
	v_or_b32_e32 v4, v13, v12
	v_and_or_b32 v0, v14, s48, v11
	v_and_b32_e32 v3, 0xfffffc00, v1
	v_lshl_or_b32 v134, v0, 10, v4
	v_add_u32_e32 v0, 0x2000, v1
	v_add_u32_e32 v2, 0x4000, v1
	v_add_u32_e32 v1, 0x6000, v1
	v_ashrrev_i32_e32 v15, 7, v0
	v_ashrrev_i32_e32 v16, 7, v2
	v_ashrrev_i32_e32 v17, 7, v1
	s_lshl_b64 s[30:31], s[26:27], 19
	v_and_or_b32 v0, v15, s48, v11
	v_and_or_b32 v2, v16, s48, v11
	v_and_or_b32 v1, v17, s48, v11
	v_add_u32_e32 v150, 0, v3
	s_add_u32 s30, s38, s30
	v_lshl_or_b32 v0, v0, 10, v4
	v_lshl_or_b32 v2, v2, 10, v4
	v_lshl_or_b32 v4, v1, 10, v4
	v_add_u32_e32 v1, 0x8000, v150
	v_lshlrev_b64 v[6:7], 1, v[134:135]
	v_readfirstlane_b32 s6, v150
	s_addc_u32 s31, s39, s31
	v_lshl_add_u64 v[8:9], v[128:129], 0, v[6:7]
	s_mov_b32 m0, s6
	v_readfirstlane_b32 s6, v1
	v_mov_b32_e32 v1, v135
	v_add_u32_e32 v3, 0x2000, v150
	global_load_lds_dwordx4 v[8:9], off
	v_lshl_add_u64 v[6:7], s[30:31], 0, v[6:7]
	s_mov_b32 m0, s6
	v_lshlrev_b64 v[0:1], 1, v[0:1]
	v_readfirstlane_b32 s6, v3
	v_add_u32_e32 v3, 0xa000, v150
	global_load_lds_dwordx4 v[6:7], off
	v_lshl_add_u64 v[6:7], v[128:129], 0, v[0:1]
	s_mov_b32 m0, s6
	v_readfirstlane_b32 s6, v3
	global_load_lds_dwordx4 v[6:7], off
	v_lshl_add_u64 v[0:1], s[30:31], 0, v[0:1]
	s_mov_b32 m0, s6
	v_mov_b32_e32 v3, v135
	v_add_u32_e32 v5, 0x4000, v150
	global_load_lds_dwordx4 v[0:1], off
	v_lshlrev_b64 v[0:1], 1, v[2:3]
	v_readfirstlane_b32 s6, v5
	v_lshl_add_u64 v[2:3], v[128:129], 0, v[0:1]
	s_mov_b32 m0, s6
	v_lshl_add_u64 v[0:1], s[30:31], 0, v[0:1]
	global_load_lds_dwordx4 v[2:3], off
	v_add_u32_e32 v2, 0xc000, v150
	v_mov_b32_e32 v5, v135
	v_readfirstlane_b32 s6, v2
	s_mov_b32 m0, s6
	v_and_b32_e32 v18, 15, v10
	global_load_lds_dwordx4 v[0:1], off
	v_lshlrev_b64 v[0:1], 1, v[4:5]
	v_add_u32_e32 v4, 0x6000, v150
	v_lshl_add_u64 v[2:3], v[128:129], 0, v[0:1]
	v_readfirstlane_b32 s6, v4
	s_mov_b32 m0, s6
	v_lshl_add_u64 v[0:1], s[30:31], 0, v[0:1]
	global_load_lds_dwordx4 v[2:3], off
	v_add_u32_e32 v2, 0xe000, v150
	v_lshlrev_b32_e32 v6, 10, v11
	v_readfirstlane_b32 s6, v2
	s_mov_b32 m0, s6
	v_lshlrev_b32_e32 v2, 2, v10
	global_load_lds_dwordx4 v[0:1], off
	v_and_b32_e32 v0, 48, v10
	v_lshlrev_b32_e32 v1, 6, v18
	v_and_b32_e32 v2, 32, v2
	v_bitop3_b32 v151, v1, v2, v0 bitop3:0x36
	v_lshlrev_b32_e32 v1, 7, v10
	v_and_b32_e32 v152, 0x6000, v1
	v_lshlrev_b32_e32 v1, 6, v10
	v_and_b32_e32 v153, 0xffffc000, v1
	v_and_b32_e32 v1, 0x3c0, v1
	v_bitop3_b32 v155, v1, v2, v0 bitop3:0x36
	v_lshlrev_b32_e32 v0, 10, v17
	v_and_or_b32 v0, v0, s49, v13
	v_lshlrev_b32_e32 v2, 10, v16
	v_or3_b32 v134, v0, v6, v12
	v_and_or_b32 v2, v2, s49, v13
	v_lshlrev_b32_e32 v4, 10, v15
	v_lshlrev_b64 v[0:1], 1, v[134:135]
	s_add_u32 s30, s30, 0x80
	v_or3_b32 v134, v2, v6, v12
	v_and_or_b32 v4, v4, s49, v13
	v_lshlrev_b32_e32 v7, 10, v14
	s_addc_u32 s31, s31, 0
	v_lshlrev_b64 v[2:3], 1, v[134:135]
	v_or3_b32 v134, v4, v6, v12
	v_and_or_b32 v7, v7, s49, v13
	v_lshlrev_b64 v[4:5], 1, v[134:135]
	v_or3_b32 v134, v7, v6, v12
	s_add_u32 s6, s38, s4
	v_lshlrev_b64 v[6:7], 1, v[134:135]
	s_addc_u32 s27, s39, s5
	v_lshl_add_u64 v[130:131], s[30:31], 0, v[0:1]
	v_lshl_add_u64 v[136:137], s[30:31], 0, v[2:3]
	v_lshl_add_u64 v[138:139], s[30:31], 0, v[4:5]
	v_lshl_add_u64 v[140:141], s[30:31], 0, v[6:7]
	s_add_u32 s30, s6, 0x2400080
	s_waitcnt vmcnt(0)
	s_addc_u32 s31, s27, 0
	v_lshl_add_u64 v[142:143], s[30:31], 0, v[0:1]
	v_mov_b32_e32 v0, 0
	v_or_b32_e32 v154, 0x800, v153
	v_or_b32_e32 v156, 0x1000, v153
	v_or_b32_e32 v157, 0x1800, v153
	v_or_b32_e32 v158, 0x2000, v153
	v_or_b32_e32 v159, 0x2800, v153
	v_or_b32_e32 v160, 0x3000, v153
	v_or_b32_e32 v161, 0x3800, v153
	v_lshl_add_u64 v[144:145], s[30:31], 0, v[2:3]
	v_lshl_add_u64 v[146:147], s[30:31], 0, v[4:5]
	v_lshl_add_u64 v[148:149], s[30:31], 0, v[6:7]
	s_mov_b32 s6, 0
	s_mov_b64 s[30:31], 0
	v_mov_b32_e32 v1, v0
	v_mov_b32_e32 v2, v0
	v_mov_b32_e32 v3, v0
	v_mov_b32_e32 v4, v0
	v_mov_b32_e32 v5, v0
	v_mov_b32_e32 v6, v0
	v_mov_b32_e32 v7, v0
	v_mov_b32_e32 v8, v0
	v_mov_b32_e32 v9, v0
	v_mov_b32_e32 v10, v0
	v_mov_b32_e32 v11, v0
	v_mov_b32_e32 v12, v0
	v_mov_b32_e32 v13, v0
	v_mov_b32_e32 v14, v0
	v_mov_b32_e32 v15, v0
	v_mov_b32_e32 v16, v0
	v_mov_b32_e32 v17, v0
	v_mov_b32_e32 v18, v0
	v_mov_b32_e32 v19, v0
	v_mov_b32_e32 v20, v0
	v_mov_b32_e32 v21, v0
	v_mov_b32_e32 v22, v0
	v_mov_b32_e32 v23, v0
	v_mov_b32_e32 v24, v0
	v_mov_b32_e32 v25, v0
	v_mov_b32_e32 v26, v0
	v_mov_b32_e32 v27, v0
	v_mov_b32_e32 v28, v0
	v_mov_b32_e32 v29, v0
	v_mov_b32_e32 v30, v0
	v_mov_b32_e32 v31, v0
	v_mov_b32_e32 v32, v0
	v_mov_b32_e32 v33, v0
	v_mov_b32_e32 v34, v0
	v_mov_b32_e32 v35, v0
	v_mov_b32_e32 v36, v0
	v_mov_b32_e32 v37, v0
	v_mov_b32_e32 v38, v0
	v_mov_b32_e32 v39, v0
	v_mov_b32_e32 v40, v0
	v_mov_b32_e32 v41, v0
	v_mov_b32_e32 v42, v0
	v_mov_b32_e32 v43, v0
	v_mov_b32_e32 v44, v0
	v_mov_b32_e32 v45, v0
	v_mov_b32_e32 v46, v0
	v_mov_b32_e32 v47, v0
	v_mov_b32_e32 v48, v0
	v_mov_b32_e32 v49, v0
	v_mov_b32_e32 v50, v0
	v_mov_b32_e32 v51, v0
	v_mov_b32_e32 v52, v0
	v_mov_b32_e32 v53, v0
	v_mov_b32_e32 v54, v0
	v_mov_b32_e32 v55, v0
	v_mov_b32_e32 v56, v0
	v_mov_b32_e32 v57, v0
	v_mov_b32_e32 v58, v0
	v_mov_b32_e32 v59, v0
	v_mov_b32_e32 v60, v0
	v_mov_b32_e32 v61, v0
	v_mov_b32_e32 v62, v0
	v_mov_b32_e32 v63, v0
	v_mov_b32_e32 v64, v0
	v_mov_b32_e32 v65, v0
	v_mov_b32_e32 v66, v0
	v_mov_b32_e32 v67, v0
	v_mov_b32_e32 v68, v0
	v_mov_b32_e32 v69, v0
	v_mov_b32_e32 v70, v0
	v_mov_b32_e32 v71, v0
	v_mov_b32_e32 v72, v0
	v_mov_b32_e32 v73, v0
	v_mov_b32_e32 v74, v0
	v_mov_b32_e32 v75, v0
	v_mov_b32_e32 v76, v0
	v_mov_b32_e32 v77, v0
	v_mov_b32_e32 v78, v0
	v_mov_b32_e32 v79, v0
	v_mov_b32_e32 v80, v0
	v_mov_b32_e32 v81, v0
	v_mov_b32_e32 v82, v0
	v_mov_b32_e32 v83, v0
	v_mov_b32_e32 v84, v0
	v_mov_b32_e32 v85, v0
	v_mov_b32_e32 v86, v0
	v_mov_b32_e32 v87, v0
	v_mov_b32_e32 v88, v0
	v_mov_b32_e32 v89, v0
	v_mov_b32_e32 v90, v0
	v_mov_b32_e32 v91, v0
	v_mov_b32_e32 v92, v0
	v_mov_b32_e32 v93, v0
	v_mov_b32_e32 v94, v0
	v_mov_b32_e32 v95, v0
	v_mov_b32_e32 v96, v0
	v_mov_b32_e32 v97, v0
	v_mov_b32_e32 v98, v0
	v_mov_b32_e32 v99, v0
	v_mov_b32_e32 v100, v0
	v_mov_b32_e32 v101, v0
	v_mov_b32_e32 v102, v0
	v_mov_b32_e32 v103, v0
	v_mov_b32_e32 v104, v0
	v_mov_b32_e32 v105, v0
	v_mov_b32_e32 v106, v0
	v_mov_b32_e32 v107, v0
	v_mov_b32_e32 v108, v0
	v_mov_b32_e32 v109, v0
	v_mov_b32_e32 v110, v0
	v_mov_b32_e32 v111, v0
	v_mov_b32_e32 v112, v0
	v_mov_b32_e32 v113, v0
	v_mov_b32_e32 v114, v0
	v_mov_b32_e32 v115, v0
	v_mov_b32_e32 v116, v0
	v_mov_b32_e32 v117, v0
	v_mov_b32_e32 v118, v0
	v_mov_b32_e32 v119, v0
	v_mov_b32_e32 v120, v0
	v_mov_b32_e32 v121, v0
	v_mov_b32_e32 v122, v0
	v_mov_b32_e32 v123, v0
	v_mov_b32_e32 v124, v0
	v_mov_b32_e32 v125, v0
	v_mov_b32_e32 v126, v0
	v_mov_b32_e32 v127, v0
	s_waitcnt vmcnt(0) lgkmcnt(0)
	s_barrier
	v_readfirstlane_b32 s100, v150
	s_mov_b64 s[98:99], 0x80
	s_and_b32 s27, s6, 0x10000
	s_xor_b32 s34, s27, 0x10000
	s_add_i32 s27, s27, 0
	v_add3_u32 v134, s27, v151, v152
	v_add3_u32 v162, s27, v151, v153
	v_add3_u32 v163, s27, v155, v154
	v_add3_u32 v200, s27, v155, v156
	v_add3_u32 v201, s27, v155, v157
	v_add3_u32 v202, s27, v155, v158
	v_add3_u32 v203, s27, v155, v159
	v_add3_u32 v204, s27, v155, v160
	v_add3_u32 v205, s27, v155, v161
	ds_read_b128 v[184:187], v134 offset:32768
	ds_read_b128 v[168:171], v162
	ds_read_b128 v[172:175], v163
	ds_read_b128 v[176:179], v200
	ds_read_b128 v[180:183], v201
	ds_read_b128 v[188:191], v134 offset:34816
	ds_read_b128 v[192:195], v134 offset:36864
	ds_read_b128 v[196:199], v134 offset:38912
	s_add_i32 s101, s100, s34
	s_mov_b32 m0, s101
	s_nop 0
	global_load_lds_dwordx4 v[148:149], off
	s_add_i32 m0, s101, 0x8000
	s_nop 0
	global_load_lds_dwordx4 v[140:141], off
	s_add_i32 m0, s101, 0x2000
	s_nop 0
	global_load_lds_dwordx4 v[146:147], off
	s_add_i32 m0, s101, 0xa000
	s_nop 0
	global_load_lds_dwordx4 v[138:139], off
	s_add_i32 m0, s101, 0x4000
	s_nop 0
	global_load_lds_dwordx4 v[144:145], off
	s_add_i32 m0, s101, 0xc000
	s_nop 0
	global_load_lds_dwordx4 v[136:137], off
	s_add_i32 m0, s101, 0x6000
	s_nop 0
	global_load_lds_dwordx4 v[142:143], off
	s_add_i32 m0, s101, 0xe000
	s_nop 0
	global_load_lds_dwordx4 v[130:131], off
.LBB0_165:
	s_and_b32 s27, s6, 0x10000
	s_xor_b32 s34, s27, 0x10000
	s_add_i32 s27, s27, 0
	s_waitcnt lgkmcnt(3)
	v_mfma_f32_16x16x32_bf16 v[108:111], v[184:187], v[168:171], v[108:111]
	v_mfma_f32_16x16x32_bf16 v[92:95], v[184:187], v[172:175], v[92:95]
	v_mfma_f32_16x16x32_bf16 v[76:79], v[184:187], v[176:179], v[76:79]
	v_mfma_f32_16x16x32_bf16 v[60:63], v[184:187], v[180:183], v[60:63]
	ds_read_b128 v[240:243], v202
	ds_read_b128 v[244:247], v203
	s_waitcnt lgkmcnt(4)
	v_mfma_f32_16x16x32_bf16 v[104:107], v[188:191], v[168:171], v[104:107]
	v_mfma_f32_16x16x32_bf16 v[88:91], v[188:191], v[172:175], v[88:91]
	v_mfma_f32_16x16x32_bf16 v[72:75], v[188:191], v[176:179], v[72:75]
	v_mfma_f32_16x16x32_bf16 v[56:59], v[188:191], v[180:183], v[56:59]
	ds_read_b128 v[248:251], v204
	ds_read_b128 v[252:255], v205
	s_waitcnt lgkmcnt(5)
	v_mfma_f32_16x16x32_bf16 v[100:103], v[192:195], v[168:171], v[100:103]
	v_mfma_f32_16x16x32_bf16 v[84:87], v[192:195], v[172:175], v[84:87]
	v_mfma_f32_16x16x32_bf16 v[68:71], v[192:195], v[176:179], v[68:71]
	v_mfma_f32_16x16x32_bf16 v[52:55], v[192:195], v[180:183], v[52:55]
	s_waitcnt lgkmcnt(4)
	v_mfma_f32_16x16x32_bf16 v[96:99], v[196:199], v[168:171], v[96:99]
	v_mfma_f32_16x16x32_bf16 v[80:83], v[196:199], v[172:175], v[80:83]
	v_mfma_f32_16x16x32_bf16 v[64:67], v[196:199], v[176:179], v[64:67]
	v_mfma_f32_16x16x32_bf16 v[48:51], v[196:199], v[180:183], v[48:51]
	ds_read_b128 v[168:171], v162 offset:1024
	ds_read_b128 v[172:175], v163 offset:1024
	ds_read_b128 v[176:179], v200 offset:1024
	ds_read_b128 v[180:183], v201 offset:1024
	s_waitcnt lgkmcnt(4)
	v_mfma_f32_16x16x32_bf16 v[44:47], v[184:187], v[240:243], v[44:47]
	v_mfma_f32_16x16x32_bf16 v[28:31], v[184:187], v[244:247], v[28:31]
	v_mfma_f32_16x16x32_bf16 v[12:15], v[184:187], v[248:251], v[12:15]
	v_mfma_f32_16x16x32_bf16 v[112:115], v[184:187], v[252:255], v[112:115]
	ds_read_b128 v[184:187], v134 offset:33792
	v_mfma_f32_16x16x32_bf16 v[40:43], v[188:191], v[240:243], v[40:43]
	v_mfma_f32_16x16x32_bf16 v[24:27], v[188:191], v[244:247], v[24:27]
	v_mfma_f32_16x16x32_bf16 v[8:11], v[188:191], v[248:251], v[8:11]
	v_mfma_f32_16x16x32_bf16 v[116:119], v[188:191], v[252:255], v[116:119]
	ds_read_b128 v[188:191], v134 offset:35840
	v_mfma_f32_16x16x32_bf16 v[36:39], v[192:195], v[240:243], v[36:39]
	v_mfma_f32_16x16x32_bf16 v[20:23], v[192:195], v[244:247], v[20:23]
	v_mfma_f32_16x16x32_bf16 v[4:7], v[192:195], v[248:251], v[4:7]
	v_mfma_f32_16x16x32_bf16 v[120:123], v[192:195], v[252:255], v[120:123]
	ds_read_b128 v[192:195], v134 offset:37888
	v_mfma_f32_16x16x32_bf16 v[32:35], v[196:199], v[240:243], v[32:35]
	v_mfma_f32_16x16x32_bf16 v[16:19], v[196:199], v[244:247], v[16:19]
	v_mfma_f32_16x16x32_bf16 v[0:3], v[196:199], v[248:251], v[0:3]
	v_mfma_f32_16x16x32_bf16 v[124:127], v[196:199], v[252:255], v[124:127]
	ds_read_b128 v[196:199], v134 offset:39936
	s_waitcnt lgkmcnt(3)
	v_mfma_f32_16x16x32_bf16 v[108:111], v[184:187], v[168:171], v[108:111]
	v_mfma_f32_16x16x32_bf16 v[92:95], v[184:187], v[172:175], v[92:95]
	v_mfma_f32_16x16x32_bf16 v[76:79], v[184:187], v[176:179], v[76:79]
	v_mfma_f32_16x16x32_bf16 v[60:63], v[184:187], v[180:183], v[60:63]
	ds_read_b128 v[240:243], v202 offset:1024
	ds_read_b128 v[244:247], v203 offset:1024
	s_waitcnt lgkmcnt(4)
	v_mfma_f32_16x16x32_bf16 v[104:107], v[188:191], v[168:171], v[104:107]
	v_mfma_f32_16x16x32_bf16 v[88:91], v[188:191], v[172:175], v[88:91]
	v_mfma_f32_16x16x32_bf16 v[72:75], v[188:191], v[176:179], v[72:75]
	v_mfma_f32_16x16x32_bf16 v[56:59], v[188:191], v[180:183], v[56:59]
	ds_read_b128 v[248:251], v204 offset:1024
	ds_read_b128 v[252:255], v205 offset:1024
	s_waitcnt lgkmcnt(5)
	v_mfma_f32_16x16x32_bf16 v[100:103], v[192:195], v[168:171], v[100:103]
	v_mfma_f32_16x16x32_bf16 v[84:87], v[192:195], v[172:175], v[84:87]
	v_mfma_f32_16x16x32_bf16 v[68:71], v[192:195], v[176:179], v[68:71]
	v_mfma_f32_16x16x32_bf16 v[52:55], v[192:195], v[180:183], v[52:55]
	s_waitcnt lgkmcnt(4)
	v_mfma_f32_16x16x32_bf16 v[96:99], v[196:199], v[168:171], v[96:99]
	v_mfma_f32_16x16x32_bf16 v[80:83], v[196:199], v[172:175], v[80:83]
	v_mfma_f32_16x16x32_bf16 v[64:67], v[196:199], v[176:179], v[64:67]
	v_mfma_f32_16x16x32_bf16 v[48:51], v[196:199], v[180:183], v[48:51]
	s_waitcnt vmcnt(0) lgkmcnt(0)
	s_barrier
	s_add_i32 s101, s100, s27
	v_mfma_f32_16x16x32_bf16 v[44:47], v[184:187], v[240:243], v[44:47]
	v_mfma_f32_16x16x32_bf16 v[28:31], v[184:187], v[244:247], v[28:31]
	v_mfma_f32_16x16x32_bf16 v[12:15], v[184:187], v[248:251], v[12:15]
	v_mfma_f32_16x16x32_bf16 v[112:115], v[184:187], v[252:255], v[112:115]
	v_add3_u32 v134, s34, v151, v152
	ds_read_b128 v[184:187], v134 offset:32768
	v_add3_u32 v162, s34, v151, v153
	v_add3_u32 v163, s34, v155, v154
	v_add3_u32 v200, s34, v155, v156
	v_add3_u32 v201, s34, v155, v157
	ds_read_b128 v[168:171], v162
	ds_read_b128 v[172:175], v163
	ds_read_b128 v[176:179], v200
	ds_read_b128 v[180:183], v201
	s_cmpk_eq_i32 s30, 0x700
	s_cbranch_scc1 .Lpk_165_0
	s_mov_b32 m0, s101
	v_lshl_add_u64 v[148:149], v[148:149], 0, s[98:99]
	global_load_lds_dwordx4 v[148:149], off
.Lpk_165_0:
	s_cmpk_eq_i32 s30, 0x700
	s_cbranch_scc1 .Lpk_165_1
	s_add_i32 m0, s101, 0x8000
	v_lshl_add_u64 v[140:141], v[140:141], 0, s[98:99]
	global_load_lds_dwordx4 v[140:141], off
.Lpk_165_1:
	v_mfma_f32_16x16x32_bf16 v[40:43], v[188:191], v[240:243], v[40:43]
	v_mfma_f32_16x16x32_bf16 v[24:27], v[188:191], v[244:247], v[24:27]
	v_mfma_f32_16x16x32_bf16 v[8:11], v[188:191], v[248:251], v[8:11]
	v_mfma_f32_16x16x32_bf16 v[116:119], v[188:191], v[252:255], v[116:119]
	ds_read_b128 v[188:191], v134 offset:34816
	v_add3_u32 v202, s34, v155, v158
	v_add3_u32 v203, s34, v155, v159
	v_add3_u32 v204, s34, v155, v160
	v_add3_u32 v205, s34, v155, v161
	s_cmpk_eq_i32 s30, 0x700
	s_cbranch_scc1 .Lpk_165_2
	s_add_i32 m0, s101, 0x2000
	v_lshl_add_u64 v[146:147], v[146:147], 0, s[98:99]
	global_load_lds_dwordx4 v[146:147], off
.Lpk_165_2:
	s_cmpk_eq_i32 s30, 0x700
	s_cbranch_scc1 .Lpk_165_3
	s_add_i32 m0, s101, 0xa000
	v_lshl_add_u64 v[138:139], v[138:139], 0, s[98:99]
	global_load_lds_dwordx4 v[138:139], off
.Lpk_165_3:
	v_mfma_f32_16x16x32_bf16 v[36:39], v[192:195], v[240:243], v[36:39]
	v_mfma_f32_16x16x32_bf16 v[20:23], v[192:195], v[244:247], v[20:23]
	v_mfma_f32_16x16x32_bf16 v[4:7], v[192:195], v[248:251], v[4:7]
	v_mfma_f32_16x16x32_bf16 v[120:123], v[192:195], v[252:255], v[120:123]
	ds_read_b128 v[192:195], v134 offset:36864
	s_cmpk_eq_i32 s30, 0x700
	s_cbranch_scc1 .Lpk_165_4
	s_add_i32 m0, s101, 0x4000
	v_lshl_add_u64 v[144:145], v[144:145], 0, s[98:99]
	global_load_lds_dwordx4 v[144:145], off
.Lpk_165_4:
	s_cmpk_eq_i32 s30, 0x700
	s_cbranch_scc1 .Lpk_165_5
	s_add_i32 m0, s101, 0xc000
	v_lshl_add_u64 v[136:137], v[136:137], 0, s[98:99]
	global_load_lds_dwordx4 v[136:137], off
.Lpk_165_5:
	v_mfma_f32_16x16x32_bf16 v[32:35], v[196:199], v[240:243], v[32:35]
	v_mfma_f32_16x16x32_bf16 v[16:19], v[196:199], v[244:247], v[16:19]
	v_mfma_f32_16x16x32_bf16 v[0:3], v[196:199], v[248:251], v[0:3]
	v_mfma_f32_16x16x32_bf16 v[124:127], v[196:199], v[252:255], v[124:127]
	ds_read_b128 v[196:199], v134 offset:38912
	s_cmpk_eq_i32 s30, 0x700
	s_cbranch_scc1 .Lpk_165_6
	s_add_i32 m0, s101, 0x6000
	v_lshl_add_u64 v[142:143], v[142:143], 0, s[98:99]
	global_load_lds_dwordx4 v[142:143], off
.Lpk_165_6:
	s_cmpk_eq_i32 s30, 0x700
	s_cbranch_scc1 .Lpk_165_7
	s_add_i32 m0, s101, 0xe000
	v_lshl_add_u64 v[130:131], v[130:131], 0, s[98:99]
	global_load_lds_dwordx4 v[130:131], off
.Lpk_165_7:
	s_add_i32 s6, s6, 0x10000
	s_add_u32 s30, s30, 0x80
	s_addc_u32 s31, s31, 0
	s_cmpk_lg_i32 s30, 0x780
	s_cbranch_scc1 .LBB0_165
	s_waitcnt lgkmcnt(0)
	s_add_i32 s27, 0, 0x10000
	v_add3_u32 v130, s27, v155, v161
	v_add3_u32 v131, s27, v155, v160
	v_add3_u32 v134, s27, v155, v159
	v_add3_u32 v192, s27, v155, v158
	v_add3_u32 v193, s27, v155, v157
	v_add3_u32 v162, s27, v155, v156
	v_add3_u32 v163, s27, v155, v154
	v_add3_u32 v153, s27, v151, v153
	v_add3_u32 v152, s52, v151, v152
	ds_read_b128 v[136:139], v130
	ds_read_b128 v[140:143], v131
	ds_read_b128 v[144:147], v134
	ds_read_b128 v[158:161], v192
	ds_read_b128 v[168:171], v193
	ds_read_b128 v[172:175], v162
	ds_read_b128 v[154:157], v163
	ds_read_b128 v[176:179], v153
	ds_read_b128 v[148:151], v152
	s_waitcnt lgkmcnt(0)
	v_mfma_f32_16x16x32_bf16 v[12:15], v[148:151], v[140:143], v[12:15]
	v_mfma_f32_16x16x32_bf16 v[180:183], v[148:151], v[136:139], v[112:115]
	s_nop 2
	ds_read_b128 v[112:115], v152 offset:2048
	s_waitcnt lgkmcnt(0)
	v_mfma_f32_16x16x32_bf16 v[8:11], v[112:115], v[140:143], v[8:11]
	v_mfma_f32_16x16x32_bf16 v[184:187], v[112:115], v[136:139], v[116:119]
	s_nop 2
	ds_read_b128 v[116:119], v152 offset:4096
	s_waitcnt lgkmcnt(0)
	v_mfma_f32_16x16x32_bf16 v[4:7], v[116:119], v[140:143], v[4:7]
	v_mfma_f32_16x16x32_bf16 v[108:111], v[148:151], v[176:179], v[108:111]
	v_mfma_f32_16x16x32_bf16 v[92:95], v[148:151], v[154:157], v[92:95]
	v_mfma_f32_16x16x32_bf16 v[76:79], v[148:151], v[172:175], v[76:79]
	v_mfma_f32_16x16x32_bf16 v[104:107], v[112:115], v[176:179], v[104:107]
	v_mfma_f32_16x16x32_bf16 v[88:91], v[112:115], v[154:157], v[88:91]
	v_mfma_f32_16x16x32_bf16 v[72:75], v[112:115], v[172:175], v[72:75]
	v_mfma_f32_16x16x32_bf16 v[188:191], v[116:119], v[136:139], v[120:123]
	v_mfma_f32_16x16x32_bf16 v[100:103], v[116:119], v[176:179], v[100:103]
	v_mfma_f32_16x16x32_bf16 v[84:87], v[116:119], v[154:157], v[84:87]
	v_mfma_f32_16x16x32_bf16 v[68:71], v[116:119], v[172:175], v[68:71]
	ds_read_b128 v[120:123], v152 offset:6144
	s_waitcnt lgkmcnt(0)
	v_mfma_f32_16x16x32_bf16 v[136:139], v[120:123], v[136:139], v[124:127]
	v_mfma_f32_16x16x32_bf16 v[96:99], v[120:123], v[176:179], v[96:99]
	v_mfma_f32_16x16x32_bf16 v[80:83], v[120:123], v[154:157], v[80:83]
	v_mfma_f32_16x16x32_bf16 v[64:67], v[120:123], v[172:175], v[64:67]
	v_mfma_f32_16x16x32_bf16 v[48:51], v[120:123], v[168:171], v[48:51]
	v_mfma_f32_16x16x32_bf16 v[52:55], v[116:119], v[168:171], v[52:55]
	v_mfma_f32_16x16x32_bf16 v[56:59], v[112:115], v[168:171], v[56:59]
	v_mfma_f32_16x16x32_bf16 v[60:63], v[148:151], v[168:171], v[60:63]
	v_mfma_f32_16x16x32_bf16 v[44:47], v[148:151], v[158:161], v[44:47]
	v_mfma_f32_16x16x32_bf16 v[40:43], v[112:115], v[158:161], v[40:43]
	v_mfma_f32_16x16x32_bf16 v[36:39], v[116:119], v[158:161], v[36:39]
	v_mfma_f32_16x16x32_bf16 v[32:35], v[120:123], v[158:161], v[32:35]
	v_mfma_f32_16x16x32_bf16 v[28:31], v[148:151], v[144:147], v[28:31]
	v_mfma_f32_16x16x32_bf16 v[24:27], v[112:115], v[144:147], v[24:27]
	v_mfma_f32_16x16x32_bf16 v[20:23], v[116:119], v[144:147], v[20:23]
	v_mfma_f32_16x16x32_bf16 v[16:19], v[120:123], v[144:147], v[16:19]
	v_mfma_f32_16x16x32_bf16 v[0:3], v[120:123], v[140:143], v[0:3]
	ds_read_b128 v[140:143], v152 offset:1024
	ds_read_b128 v[144:147], v152 offset:3072
	ds_read_b128 v[148:151], v152 offset:5120
	ds_read_b128 v[112:115], v153 offset:1024
	ds_read_b128 v[152:155], v152 offset:7168
	ds_read_b128 v[156:159], v163 offset:1024
	ds_read_b128 v[160:163], v162 offset:1024
	ds_read_b128 v[168:171], v193 offset:1024
	s_waitcnt lgkmcnt(4)
	v_mfma_f32_16x16x32_bf16 v[124:127], v[140:143], v[112:115], v[108:111]
	v_mfma_f32_16x16x32_bf16 v[120:123], v[144:147], v[112:115], v[104:107]
	v_mfma_f32_16x16x32_bf16 v[116:119], v[148:151], v[112:115], v[100:103]
	s_waitcnt lgkmcnt(3)
	v_mfma_f32_16x16x32_bf16 v[108:111], v[152:155], v[112:115], v[96:99]
	ds_read_b128 v[172:175], v192 offset:1024
	s_waitcnt lgkmcnt(3)
	v_mfma_f32_16x16x32_bf16 v[112:115], v[140:143], v[156:159], v[92:95]
	v_mfma_f32_16x16x32_bf16 v[104:107], v[144:147], v[156:159], v[88:91]
	v_mfma_f32_16x16x32_bf16 v[100:103], v[148:151], v[156:159], v[84:87]
	v_mfma_f32_16x16x32_bf16 v[96:99], v[152:155], v[156:159], v[80:83]
	ds_read_b128 v[156:159], v134 offset:1024
	s_waitcnt lgkmcnt(3)
	v_mfma_f32_16x16x32_bf16 v[92:95], v[140:143], v[160:163], v[76:79]
	v_mfma_f32_16x16x32_bf16 v[88:91], v[144:147], v[160:163], v[72:75]
	v_mfma_f32_16x16x32_bf16 v[84:87], v[148:151], v[160:163], v[68:71]
	v_mfma_f32_16x16x32_bf16 v[80:83], v[152:155], v[160:163], v[64:67]
	ds_read_b128 v[160:163], v131 offset:1024
	s_waitcnt lgkmcnt(3)
	v_mfma_f32_16x16x32_bf16 v[76:79], v[140:143], v[168:171], v[60:63]
	v_mfma_f32_16x16x32_bf16 v[72:75], v[144:147], v[168:171], v[56:59]
	v_mfma_f32_16x16x32_bf16 v[68:71], v[148:151], v[168:171], v[52:55]
	v_mfma_f32_16x16x32_bf16 v[64:67], v[152:155], v[168:171], v[48:51]
	ds_read_b128 v[168:171], v130 offset:1024
	s_waitcnt lgkmcnt(3)
	v_mfma_f32_16x16x32_bf16 v[60:63], v[140:143], v[172:175], v[44:47]
	v_mfma_f32_16x16x32_bf16 v[56:59], v[144:147], v[172:175], v[40:43]
	v_mfma_f32_16x16x32_bf16 v[52:55], v[148:151], v[172:175], v[36:39]
	v_mfma_f32_16x16x32_bf16 v[48:51], v[152:155], v[172:175], v[32:35]
	s_waitcnt lgkmcnt(2)
	v_mfma_f32_16x16x32_bf16 v[44:47], v[140:143], v[156:159], v[28:31]
	v_mfma_f32_16x16x32_bf16 v[40:43], v[144:147], v[156:159], v[24:27]
	v_mfma_f32_16x16x32_bf16 v[36:39], v[148:151], v[156:159], v[20:23]
	v_mfma_f32_16x16x32_bf16 v[32:35], v[152:155], v[156:159], v[16:19]
	s_waitcnt lgkmcnt(1)
	v_mfma_f32_16x16x32_bf16 v[28:31], v[140:143], v[160:163], v[12:15]
	v_mfma_f32_16x16x32_bf16 v[24:27], v[144:147], v[160:163], v[8:11]
	v_mfma_f32_16x16x32_bf16 v[20:23], v[148:151], v[160:163], v[4:7]
	v_mfma_f32_16x16x32_bf16 v[16:19], v[152:155], v[160:163], v[0:3]
	s_waitcnt lgkmcnt(0)
	v_mfma_f32_16x16x32_bf16 v[12:15], v[140:143], v[168:171], v[180:183]
	v_mfma_f32_16x16x32_bf16 v[8:11], v[144:147], v[168:171], v[184:187]
	v_mfma_f32_16x16x32_bf16 v[0:3], v[148:151], v[168:171], v[188:191]
	v_mfma_f32_16x16x32_bf16 v[4:7], v[152:155], v[168:171], v[136:139]
	s_waitcnt vmcnt(0)
	s_nop 2
	v_mov_b32_e32 v138, v132
	s_cmp_gt_u32 s26, 1
	s_barrier
	s_cbranch_scc0 .LBB0_169
	v_mov_b32_e32 v130, s19
	ds_read_b64 v[136:137], v130
	s_cmp_gt_u32 s26, 3
	s_cbranch_scc0 .LBB0_170
	s_lshl_b32 s6, s26, 8
	s_waitcnt lgkmcnt(0)
	v_lshl_add_u64 v[130:131], v[136:137], 0, s[20:21]
	s_add_i32 s34, s6, 0xfffff200
	s_mov_b64 s[30:31], 0x400
	s_cbranch_execz .LBB0_171
	s_branch .LBB0_172

.LBB0_175:
	s_and_b64 vcc, exec, s[30:31]
	s_cbranch_vccz .LBB0_179
	v_mov_b32_e32 v10, v132
	s_lshl_b32 s6, s26, 19
	v_lshlrev_b32_e32 v1, 4, v10
	v_and_b32_e32 v0, 32, v10
	v_lshrrev_b32_e32 v2, 1, v10
	v_bitop3_b32 v0, v1, v0, 48 bitop3:0x6c
	v_bfe_u32 v11, v10, 2, 4
	v_and_b32_e32 v12, 32, v2
	v_lshrrev_b32_e32 v13, 1, v0
	v_ashrrev_i32_e32 v14, 3, v10
	v_or_b32_e32 v4, v13, v12
	v_and_or_b32 v0, v14, s48, v11
	v_and_b32_e32 v3, 0xfffffc00, v1
	v_lshl_or_b32 v134, v0, 10, v4
	v_add_u32_e32 v0, 0x2000, v1
	v_add_u32_e32 v2, 0x4000, v1
	v_add_u32_e32 v1, 0x6000, v1
	v_ashrrev_i32_e32 v15, 7, v0
	v_ashrrev_i32_e32 v16, 7, v2
	v_ashrrev_i32_e32 v17, 7, v1
	v_and_or_b32 v0, v15, s48, v11
	v_and_or_b32 v2, v16, s48, v11
	v_and_or_b32 v1, v17, s48, v11
	v_add_u32_e32 v148, 0, v3
	s_add_u32 s30, s38, s6
	v_lshl_or_b32 v0, v0, 10, v4
	v_lshl_or_b32 v2, v2, 10, v4
	v_lshl_or_b32 v4, v1, 10, v4
	v_add_u32_e32 v1, 0x8000, v148
	v_lshlrev_b64 v[6:7], 1, v[134:135]
	v_readfirstlane_b32 s6, v148
	s_addc_u32 s31, s39, 0
	v_lshl_add_u64 v[8:9], v[128:129], 0, v[6:7]
	s_mov_b32 m0, s6
	v_readfirstlane_b32 s6, v1
	v_mov_b32_e32 v1, v135
	v_add_u32_e32 v3, 0x2000, v148
	global_load_lds_dwordx4 v[8:9], off
	v_lshl_add_u64 v[6:7], s[30:31], 0, v[6:7]
	s_mov_b32 m0, s6
	v_lshlrev_b64 v[0:1], 1, v[0:1]
	v_readfirstlane_b32 s6, v3
	v_add_u32_e32 v3, 0xa000, v148
	global_load_lds_dwordx4 v[6:7], off
	v_lshl_add_u64 v[6:7], v[128:129], 0, v[0:1]
	s_mov_b32 m0, s6
	v_readfirstlane_b32 s6, v3
	global_load_lds_dwordx4 v[6:7], off
	v_lshl_add_u64 v[0:1], s[30:31], 0, v[0:1]
	s_mov_b32 m0, s6
	v_mov_b32_e32 v3, v135
	v_add_u32_e32 v5, 0x4000, v148
	global_load_lds_dwordx4 v[0:1], off
	v_lshlrev_b64 v[0:1], 1, v[2:3]
	v_readfirstlane_b32 s6, v5
	v_lshl_add_u64 v[2:3], v[128:129], 0, v[0:1]
	s_mov_b32 m0, s6
	v_lshl_add_u64 v[0:1], s[30:31], 0, v[0:1]
	global_load_lds_dwordx4 v[2:3], off
	v_add_u32_e32 v2, 0xc000, v148
	v_mov_b32_e32 v5, v135
	v_readfirstlane_b32 s6, v2
	s_mov_b32 m0, s6
	v_lshlrev_b32_e32 v6, 10, v11
	global_load_lds_dwordx4 v[0:1], off
	v_lshlrev_b64 v[0:1], 1, v[4:5]
	v_add_u32_e32 v4, 0x6000, v148
	v_lshl_add_u64 v[2:3], v[128:129], 0, v[0:1]
	v_readfirstlane_b32 s6, v4
	s_mov_b32 m0, s6
	v_lshl_add_u64 v[0:1], s[30:31], 0, v[0:1]
	global_load_lds_dwordx4 v[2:3], off
	v_add_u32_e32 v2, 0xe000, v148
	s_add_u32 s30, s30, 0x80
	v_readfirstlane_b32 s6, v2
	s_mov_b32 m0, s6
	v_lshlrev_b32_e32 v2, 2, v10
	global_load_lds_dwordx4 v[0:1], off
	v_and_b32_e32 v0, 15, v10
	v_and_b32_e32 v1, 48, v10
	v_lshlrev_b32_e32 v0, 6, v0
	v_and_b32_e32 v2, 32, v2
	v_bitop3_b32 v149, v0, v2, v1 bitop3:0x36
	v_lshlrev_b32_e32 v0, 7, v10
	v_and_b32_e32 v150, 0x6000, v0
	v_lshlrev_b32_e32 v0, 6, v10
	v_and_b32_e32 v151, 0xffffc000, v0
	v_and_b32_e32 v0, 0x3c0, v0
	v_bitop3_b32 v153, v0, v2, v1 bitop3:0x36
	v_lshlrev_b32_e32 v0, 10, v17
	v_and_or_b32 v0, v0, s49, v13
	s_addc_u32 s31, s31, 0
	v_lshlrev_b32_e32 v2, 10, v16
	v_or3_b32 v134, v0, v6, v12
	v_and_or_b32 v2, v2, s49, v13
	v_lshlrev_b32_e32 v4, 10, v15
	s_add_u32 s4, s38, s4
	v_lshlrev_b64 v[0:1], 1, v[134:135]
	v_or3_b32 v134, v2, v6, v12
	v_and_or_b32 v4, v4, s49, v13
	v_lshlrev_b32_e32 v7, 10, v14
	s_addc_u32 s5, s39, s5
	v_lshlrev_b64 v[2:3], 1, v[134:135]
	v_or3_b32 v134, v4, v6, v12
	v_and_or_b32 v7, v7, s49, v13
	s_add_u32 s4, s4, 0x2400080
	s_waitcnt vmcnt(0)
	v_lshlrev_b64 v[4:5], 1, v[134:135]
	v_or3_b32 v134, v7, v6, v12
	s_addc_u32 s5, s5, 0
	v_lshl_add_u64 v[128:129], s[30:31], 0, v[0:1]
	v_lshlrev_b64 v[6:7], 1, v[134:135]
	v_lshl_add_u64 v[140:141], s[4:5], 0, v[0:1]
	v_mov_b32_e32 v0, 0
	v_or_b32_e32 v152, 0x800, v151
	v_or_b32_e32 v154, 0x1000, v151
	v_or_b32_e32 v155, 0x1800, v151
	v_or_b32_e32 v156, 0x2000, v151
	v_or_b32_e32 v157, 0x2800, v151
	v_or_b32_e32 v158, 0x3000, v151
	v_or_b32_e32 v159, 0x3800, v151
	v_lshl_add_u64 v[130:131], s[30:31], 0, v[2:3]
	v_lshl_add_u64 v[136:137], s[30:31], 0, v[4:5]
	v_lshl_add_u64 v[138:139], s[30:31], 0, v[6:7]
	v_lshl_add_u64 v[142:143], s[4:5], 0, v[2:3]
	v_lshl_add_u64 v[144:145], s[4:5], 0, v[4:5]
	v_lshl_add_u64 v[146:147], s[4:5], 0, v[6:7]
	s_mov_b32 s6, 0
	s_mov_b64 s[4:5], 0
	v_mov_b32_e32 v1, v0
	v_mov_b32_e32 v2, v0
	v_mov_b32_e32 v3, v0
	v_mov_b32_e32 v4, v0
	v_mov_b32_e32 v5, v0
	v_mov_b32_e32 v6, v0
	v_mov_b32_e32 v7, v0
	v_mov_b32_e32 v8, v0
	v_mov_b32_e32 v9, v0
	v_mov_b32_e32 v10, v0
	v_mov_b32_e32 v11, v0
	v_mov_b32_e32 v12, v0
	v_mov_b32_e32 v13, v0
	v_mov_b32_e32 v14, v0
	v_mov_b32_e32 v15, v0
	v_mov_b32_e32 v16, v0
	v_mov_b32_e32 v17, v0
	v_mov_b32_e32 v18, v0
	v_mov_b32_e32 v19, v0
	v_mov_b32_e32 v20, v0
	v_mov_b32_e32 v21, v0
	v_mov_b32_e32 v22, v0
	v_mov_b32_e32 v23, v0
	v_mov_b32_e32 v24, v0
	v_mov_b32_e32 v25, v0
	v_mov_b32_e32 v26, v0
	v_mov_b32_e32 v27, v0
	v_mov_b32_e32 v28, v0
	v_mov_b32_e32 v29, v0
	v_mov_b32_e32 v30, v0
	v_mov_b32_e32 v31, v0
	v_mov_b32_e32 v32, v0
	v_mov_b32_e32 v33, v0
	v_mov_b32_e32 v34, v0
	v_mov_b32_e32 v35, v0
	v_mov_b32_e32 v36, v0
	v_mov_b32_e32 v37, v0
	v_mov_b32_e32 v38, v0
	v_mov_b32_e32 v39, v0
	v_mov_b32_e32 v40, v0
	v_mov_b32_e32 v41, v0
	v_mov_b32_e32 v42, v0
	v_mov_b32_e32 v43, v0
	v_mov_b32_e32 v44, v0
	v_mov_b32_e32 v45, v0
	v_mov_b32_e32 v46, v0
	v_mov_b32_e32 v47, v0
	v_mov_b32_e32 v48, v0
	v_mov_b32_e32 v49, v0
	v_mov_b32_e32 v50, v0
	v_mov_b32_e32 v51, v0
	v_mov_b32_e32 v52, v0
	v_mov_b32_e32 v53, v0
	v_mov_b32_e32 v54, v0
	v_mov_b32_e32 v55, v0
	v_mov_b32_e32 v56, v0
	v_mov_b32_e32 v57, v0
	v_mov_b32_e32 v58, v0
	v_mov_b32_e32 v59, v0
	v_mov_b32_e32 v60, v0
	v_mov_b32_e32 v61, v0
	v_mov_b32_e32 v62, v0
	v_mov_b32_e32 v63, v0
	v_mov_b32_e32 v64, v0
	v_mov_b32_e32 v65, v0
	v_mov_b32_e32 v66, v0
	v_mov_b32_e32 v67, v0
	v_mov_b32_e32 v68, v0
	v_mov_b32_e32 v69, v0
	v_mov_b32_e32 v70, v0
	v_mov_b32_e32 v71, v0
	v_mov_b32_e32 v72, v0
	v_mov_b32_e32 v73, v0
	v_mov_b32_e32 v74, v0
	v_mov_b32_e32 v75, v0
	v_mov_b32_e32 v76, v0
	v_mov_b32_e32 v77, v0
	v_mov_b32_e32 v78, v0
	v_mov_b32_e32 v79, v0
	v_mov_b32_e32 v80, v0
	v_mov_b32_e32 v81, v0
	v_mov_b32_e32 v82, v0
	v_mov_b32_e32 v83, v0
	v_mov_b32_e32 v84, v0
	v_mov_b32_e32 v85, v0
	v_mov_b32_e32 v86, v0
	v_mov_b32_e32 v87, v0
	v_mov_b32_e32 v88, v0
	v_mov_b32_e32 v89, v0
	v_mov_b32_e32 v90, v0
	v_mov_b32_e32 v91, v0
	v_mov_b32_e32 v92, v0
	v_mov_b32_e32 v93, v0
	v_mov_b32_e32 v94, v0
	v_mov_b32_e32 v95, v0
	v_mov_b32_e32 v96, v0
	v_mov_b32_e32 v97, v0
	v_mov_b32_e32 v98, v0
	v_mov_b32_e32 v99, v0
	v_mov_b32_e32 v100, v0
	v_mov_b32_e32 v101, v0
	v_mov_b32_e32 v102, v0
	v_mov_b32_e32 v103, v0
	v_mov_b32_e32 v104, v0
	v_mov_b32_e32 v105, v0
	v_mov_b32_e32 v106, v0
	v_mov_b32_e32 v107, v0
	v_mov_b32_e32 v108, v0
	v_mov_b32_e32 v109, v0
	v_mov_b32_e32 v110, v0
	v_mov_b32_e32 v111, v0
	v_mov_b32_e32 v112, v0
	v_mov_b32_e32 v113, v0
	v_mov_b32_e32 v114, v0
	v_mov_b32_e32 v115, v0
	v_mov_b32_e32 v116, v0
	v_mov_b32_e32 v117, v0
	v_mov_b32_e32 v118, v0
	v_mov_b32_e32 v119, v0
	v_mov_b32_e32 v120, v0
	v_mov_b32_e32 v121, v0
	v_mov_b32_e32 v122, v0
	v_mov_b32_e32 v123, v0
	v_mov_b32_e32 v124, v0
	v_mov_b32_e32 v125, v0
	v_mov_b32_e32 v126, v0
	v_mov_b32_e32 v127, v0
	s_waitcnt vmcnt(0) lgkmcnt(0)
	s_barrier
	v_readfirstlane_b32 s100, v148
	s_mov_b64 s[98:99], 0x80
	s_and_b32 s27, s6, 0x10000
	s_xor_b32 s30, s27, 0x10000
	s_add_i32 s27, s27, 0
	v_add3_u32 v134, s27, v149, v150
	v_add3_u32 v196, s27, v149, v151
	v_add3_u32 v197, s27, v153, v152
	v_add3_u32 v198, s27, v153, v154
	v_add3_u32 v199, s27, v153, v155
	v_add3_u32 v200, s27, v153, v156
	v_add3_u32 v201, s27, v153, v157
	v_add3_u32 v202, s27, v153, v158
	v_add3_u32 v203, s27, v153, v159
	ds_read_b128 v[180:183], v134 offset:32768
	ds_read_b128 v[160:163], v196
	ds_read_b128 v[168:171], v197
	ds_read_b128 v[172:175], v198
	ds_read_b128 v[176:179], v199
	ds_read_b128 v[184:187], v134 offset:34816
	ds_read_b128 v[188:191], v134 offset:36864
	ds_read_b128 v[192:195], v134 offset:38912
	s_add_i32 s101, s100, s30
	s_mov_b32 m0, s101
	s_nop 0
	global_load_lds_dwordx4 v[146:147], off
	s_add_i32 m0, s101, 0x8000
	s_nop 0
	global_load_lds_dwordx4 v[138:139], off
	s_add_i32 m0, s101, 0x2000
	s_nop 0
	global_load_lds_dwordx4 v[144:145], off
	s_add_i32 m0, s101, 0xa000
	s_nop 0
	global_load_lds_dwordx4 v[136:137], off
	s_add_i32 m0, s101, 0x4000
	s_nop 0
	global_load_lds_dwordx4 v[142:143], off
	s_add_i32 m0, s101, 0xc000
	s_nop 0
	global_load_lds_dwordx4 v[130:131], off
	s_add_i32 m0, s101, 0x6000
	s_nop 0
	global_load_lds_dwordx4 v[140:141], off
	s_add_i32 m0, s101, 0xe000
	s_nop 0
	global_load_lds_dwordx4 v[128:129], off
.LBB0_177:
	s_and_b32 s27, s6, 0x10000
	s_xor_b32 s30, s27, 0x10000
	s_add_i32 s27, s27, 0
	s_waitcnt lgkmcnt(3)
	v_mfma_f32_16x16x32_bf16 v[108:111], v[160:163], v[180:183], v[108:111]
	v_mfma_f32_16x16x32_bf16 v[92:95], v[168:171], v[180:183], v[92:95]
	v_mfma_f32_16x16x32_bf16 v[76:79], v[172:175], v[180:183], v[76:79]
	v_mfma_f32_16x16x32_bf16 v[60:63], v[176:179], v[180:183], v[60:63]
	ds_read_b128 v[240:243], v200
	ds_read_b128 v[244:247], v201
	s_waitcnt lgkmcnt(4)
	v_mfma_f32_16x16x32_bf16 v[104:107], v[160:163], v[184:187], v[104:107]
	v_mfma_f32_16x16x32_bf16 v[88:91], v[168:171], v[184:187], v[88:91]
	v_mfma_f32_16x16x32_bf16 v[72:75], v[172:175], v[184:187], v[72:75]
	v_mfma_f32_16x16x32_bf16 v[56:59], v[176:179], v[184:187], v[56:59]
	ds_read_b128 v[248:251], v202
	ds_read_b128 v[252:255], v203
	s_waitcnt lgkmcnt(5)
	v_mfma_f32_16x16x32_bf16 v[100:103], v[160:163], v[188:191], v[100:103]
	v_mfma_f32_16x16x32_bf16 v[84:87], v[168:171], v[188:191], v[84:87]
	v_mfma_f32_16x16x32_bf16 v[68:71], v[172:175], v[188:191], v[68:71]
	v_mfma_f32_16x16x32_bf16 v[52:55], v[176:179], v[188:191], v[52:55]
	s_waitcnt lgkmcnt(4)
	v_mfma_f32_16x16x32_bf16 v[96:99], v[160:163], v[192:195], v[96:99]
	v_mfma_f32_16x16x32_bf16 v[80:83], v[168:171], v[192:195], v[80:83]
	v_mfma_f32_16x16x32_bf16 v[64:67], v[172:175], v[192:195], v[64:67]
	v_mfma_f32_16x16x32_bf16 v[48:51], v[176:179], v[192:195], v[48:51]
	ds_read_b128 v[160:163], v196 offset:1024
	ds_read_b128 v[168:171], v197 offset:1024
	ds_read_b128 v[172:175], v198 offset:1024
	ds_read_b128 v[176:179], v199 offset:1024
	s_waitcnt lgkmcnt(4)
	v_mfma_f32_16x16x32_bf16 v[44:47], v[240:243], v[180:183], v[44:47]
	v_mfma_f32_16x16x32_bf16 v[28:31], v[244:247], v[180:183], v[28:31]
	v_mfma_f32_16x16x32_bf16 v[12:15], v[248:251], v[180:183], v[12:15]
	v_mfma_f32_16x16x32_bf16 v[112:115], v[252:255], v[180:183], v[112:115]
	ds_read_b128 v[180:183], v134 offset:33792
	v_mfma_f32_16x16x32_bf16 v[40:43], v[240:243], v[184:187], v[40:43]
	v_mfma_f32_16x16x32_bf16 v[24:27], v[244:247], v[184:187], v[24:27]
	v_mfma_f32_16x16x32_bf16 v[8:11], v[248:251], v[184:187], v[8:11]
	v_mfma_f32_16x16x32_bf16 v[116:119], v[252:255], v[184:187], v[116:119]
	ds_read_b128 v[184:187], v134 offset:35840
	v_mfma_f32_16x16x32_bf16 v[36:39], v[240:243], v[188:191], v[36:39]
	v_mfma_f32_16x16x32_bf16 v[20:23], v[244:247], v[188:191], v[20:23]
	v_mfma_f32_16x16x32_bf16 v[4:7], v[248:251], v[188:191], v[4:7]
	v_mfma_f32_16x16x32_bf16 v[120:123], v[252:255], v[188:191], v[120:123]
	ds_read_b128 v[188:191], v134 offset:37888
	v_mfma_f32_16x16x32_bf16 v[32:35], v[240:243], v[192:195], v[32:35]
	v_mfma_f32_16x16x32_bf16 v[16:19], v[244:247], v[192:195], v[16:19]
	v_mfma_f32_16x16x32_bf16 v[0:3], v[248:251], v[192:195], v[0:3]
	v_mfma_f32_16x16x32_bf16 v[124:127], v[252:255], v[192:195], v[124:127]
	ds_read_b128 v[192:195], v134 offset:39936
	s_waitcnt lgkmcnt(3)
	v_mfma_f32_16x16x32_bf16 v[108:111], v[160:163], v[180:183], v[108:111]
	v_mfma_f32_16x16x32_bf16 v[92:95], v[168:171], v[180:183], v[92:95]
	v_mfma_f32_16x16x32_bf16 v[76:79], v[172:175], v[180:183], v[76:79]
	v_mfma_f32_16x16x32_bf16 v[60:63], v[176:179], v[180:183], v[60:63]
	ds_read_b128 v[240:243], v200 offset:1024
	ds_read_b128 v[244:247], v201 offset:1024
	s_waitcnt lgkmcnt(4)
	v_mfma_f32_16x16x32_bf16 v[104:107], v[160:163], v[184:187], v[104:107]
	v_mfma_f32_16x16x32_bf16 v[88:91], v[168:171], v[184:187], v[88:91]
	v_mfma_f32_16x16x32_bf16 v[72:75], v[172:175], v[184:187], v[72:75]
	v_mfma_f32_16x16x32_bf16 v[56:59], v[176:179], v[184:187], v[56:59]
	ds_read_b128 v[248:251], v202 offset:1024
	ds_read_b128 v[252:255], v203 offset:1024
	s_waitcnt lgkmcnt(5)
	v_mfma_f32_16x16x32_bf16 v[100:103], v[160:163], v[188:191], v[100:103]
	v_mfma_f32_16x16x32_bf16 v[84:87], v[168:171], v[188:191], v[84:87]
	v_mfma_f32_16x16x32_bf16 v[68:71], v[172:175], v[188:191], v[68:71]
	v_mfma_f32_16x16x32_bf16 v[52:55], v[176:179], v[188:191], v[52:55]
	s_waitcnt lgkmcnt(4)
	v_mfma_f32_16x16x32_bf16 v[96:99], v[160:163], v[192:195], v[96:99]
	v_mfma_f32_16x16x32_bf16 v[80:83], v[168:171], v[192:195], v[80:83]
	v_mfma_f32_16x16x32_bf16 v[64:67], v[172:175], v[192:195], v[64:67]
	v_mfma_f32_16x16x32_bf16 v[48:51], v[176:179], v[192:195], v[48:51]
	s_waitcnt vmcnt(0) lgkmcnt(0)
	s_barrier
	s_add_i32 s101, s100, s27
	v_mfma_f32_16x16x32_bf16 v[44:47], v[240:243], v[180:183], v[44:47]
	v_mfma_f32_16x16x32_bf16 v[28:31], v[244:247], v[180:183], v[28:31]
	v_mfma_f32_16x16x32_bf16 v[12:15], v[248:251], v[180:183], v[12:15]
	v_mfma_f32_16x16x32_bf16 v[112:115], v[252:255], v[180:183], v[112:115]
	v_add3_u32 v134, s30, v149, v150
	ds_read_b128 v[180:183], v134 offset:32768
	v_add3_u32 v196, s30, v149, v151
	v_add3_u32 v197, s30, v153, v152
	v_add3_u32 v198, s30, v153, v154
	v_add3_u32 v199, s30, v153, v155
	ds_read_b128 v[160:163], v196
	ds_read_b128 v[168:171], v197
	ds_read_b128 v[172:175], v198
	ds_read_b128 v[176:179], v199
	s_cmpk_eq_i32 s4, 0x700
	s_cbranch_scc1 .Lpk_177_0
	s_mov_b32 m0, s101
	v_lshl_add_u64 v[146:147], v[146:147], 0, s[98:99]
	global_load_lds_dwordx4 v[146:147], off

.Lpk_177_1:
	v_mfma_f32_16x16x32_bf16 v[40:43], v[240:243], v[184:187], v[40:43]
	v_mfma_f32_16x16x32_bf16 v[24:27], v[244:247], v[184:187], v[24:27]
	v_mfma_f32_16x16x32_bf16 v[8:11], v[248:251], v[184:187], v[8:11]
	v_mfma_f32_16x16x32_bf16 v[116:119], v[252:255], v[184:187], v[116:119]
	ds_read_b128 v[184:187], v134 offset:34816
	v_add3_u32 v200, s30, v153, v156
	v_add3_u32 v201, s30, v153, v157
	v_add3_u32 v202, s30, v153, v158
	v_add3_u32 v203, s30, v153, v159
	s_cmpk_eq_i32 s4, 0x700
	s_cbranch_scc1 .Lpk_177_2
	s_add_i32 m0, s101, 0x2000
	v_lshl_add_u64 v[144:145], v[144:145], 0, s[98:99]
	global_load_lds_dwordx4 v[144:145], off

.Lpk_177_3:
	v_mfma_f32_16x16x32_bf16 v[36:39], v[240:243], v[188:191], v[36:39]
	v_mfma_f32_16x16x32_bf16 v[20:23], v[244:247], v[188:191], v[20:23]
	v_mfma_f32_16x16x32_bf16 v[4:7], v[248:251], v[188:191], v[4:7]
	v_mfma_f32_16x16x32_bf16 v[120:123], v[252:255], v[188:191], v[120:123]
	ds_read_b128 v[188:191], v134 offset:36864
	s_cmpk_eq_i32 s4, 0x700
	s_cbranch_scc1 .Lpk_177_4
	s_add_i32 m0, s101, 0x4000
	v_lshl_add_u64 v[142:143], v[142:143], 0, s[98:99]
	global_load_lds_dwordx4 v[142:143], off

.Lpk_177_5:
	v_mfma_f32_16x16x32_bf16 v[32:35], v[240:243], v[192:195], v[32:35]
	v_mfma_f32_16x16x32_bf16 v[16:19], v[244:247], v[192:195], v[16:19]
	v_mfma_f32_16x16x32_bf16 v[0:3], v[248:251], v[192:195], v[0:3]
	v_mfma_f32_16x16x32_bf16 v[124:127], v[252:255], v[192:195], v[124:127]
	ds_read_b128 v[192:195], v134 offset:38912
	s_cmpk_eq_i32 s4, 0x700
	s_cbranch_scc1 .Lpk_177_6
	s_add_i32 m0, s101, 0x6000
	v_lshl_add_u64 v[140:141], v[140:141], 0, s[98:99]
	global_load_lds_dwordx4 v[140:141], off

.Lpk_177_7:
	s_add_i32 s6, s6, 0x10000
	s_add_u32 s4, s4, 0x80
	s_addc_u32 s5, s5, 0
	s_cmpk_lg_i32 s4, 0x780
	s_cbranch_scc1 .LBB0_177
	s_waitcnt lgkmcnt(0)
	s_add_i32 s5, 0, 0x10000
	v_add3_u32 v184, s5, v153, v158
	ds_read_b128 v[136:139], v184
	v_add3_u32 v134, s5, v153, v159
	v_add3_u32 v185, s5, v153, v157
	v_add3_u32 v186, s5, v153, v156
	v_add3_u32 v187, s5, v153, v155
	v_add3_u32 v188, s5, v153, v154
	v_add3_u32 v189, s5, v153, v152
	v_add3_u32 v190, s5, v149, v151
	v_add3_u32 v191, s52, v149, v150
	ds_read_b128 v[128:131], v134
	ds_read_b128 v[140:143], v185
	ds_read_b128 v[144:147], v186
	ds_read_b128 v[156:159], v187
	ds_read_b128 v[160:163], v188
	ds_read_b128 v[152:155], v189
	ds_read_b128 v[168:171], v190
	ds_read_b128 v[176:179], v191 offset:4096
	s_waitcnt lgkmcnt(0)
	v_mfma_f32_16x16x32_bf16 v[4:7], v[136:139], v[176:179], v[4:7]
	ds_read_b128 v[148:151], v191
	s_waitcnt lgkmcnt(0)
	v_mfma_f32_16x16x32_bf16 v[112:115], v[128:131], v[148:151], v[112:115]
	v_mfma_f32_16x16x32_bf16 v[60:63], v[156:159], v[148:151], v[60:63]
	ds_read_b128 v[172:175], v191 offset:2048
	s_waitcnt lgkmcnt(0)
	v_mfma_f32_16x16x32_bf16 v[116:119], v[128:131], v[172:175], v[116:119]
	v_mfma_f32_16x16x32_bf16 v[56:59], v[156:159], v[172:175], v[56:59]
	v_mfma_f32_16x16x32_bf16 v[120:123], v[128:131], v[176:179], v[120:123]
	ds_read_b128 v[180:183], v191 offset:6144
	s_waitcnt lgkmcnt(0)
	v_mfma_f32_16x16x32_bf16 v[124:127], v[128:131], v[180:183], v[124:127]
	v_mfma_f32_16x16x32_bf16 v[128:131], v[156:159], v[180:183], v[48:51]
	v_mfma_f32_16x16x32_bf16 v[48:51], v[168:171], v[176:179], v[100:103]
	v_mfma_f32_16x16x32_bf16 v[100:103], v[156:159], v[176:179], v[52:55]
	v_mfma_f32_16x16x32_bf16 v[156:159], v[136:139], v[172:175], v[8:11]
	v_mfma_f32_16x16x32_bf16 v[92:95], v[152:155], v[148:151], v[92:95]
	v_mfma_f32_16x16x32_bf16 v[76:79], v[160:163], v[148:151], v[76:79]
	v_mfma_f32_16x16x32_bf16 v[44:47], v[144:147], v[148:151], v[44:47]
	v_mfma_f32_16x16x32_bf16 v[52:55], v[168:171], v[172:175], v[104:107]
	v_mfma_f32_16x16x32_bf16 v[104:107], v[168:171], v[148:151], v[108:111]
	v_mfma_f32_16x16x32_bf16 v[28:31], v[140:143], v[148:151], v[28:31]
	v_mfma_f32_16x16x32_bf16 v[148:151], v[136:139], v[148:151], v[12:15]
	v_mfma_f32_16x16x32_bf16 v[88:91], v[152:155], v[172:175], v[88:91]
	v_mfma_f32_16x16x32_bf16 v[72:75], v[160:163], v[172:175], v[72:75]
	v_mfma_f32_16x16x32_bf16 v[84:87], v[152:155], v[176:179], v[84:87]
	v_mfma_f32_16x16x32_bf16 v[68:71], v[160:163], v[176:179], v[68:71]
	v_mfma_f32_16x16x32_bf16 v[96:99], v[168:171], v[180:183], v[96:99]
	v_mfma_f32_16x16x32_bf16 v[80:83], v[152:155], v[180:183], v[80:83]
	v_mfma_f32_16x16x32_bf16 v[64:67], v[160:163], v[180:183], v[64:67]
	v_mfma_f32_16x16x32_bf16 v[40:43], v[144:147], v[172:175], v[40:43]
	v_mfma_f32_16x16x32_bf16 v[36:39], v[144:147], v[176:179], v[36:39]
	v_mfma_f32_16x16x32_bf16 v[108:111], v[144:147], v[180:183], v[32:35]
	v_mfma_f32_16x16x32_bf16 v[144:147], v[140:143], v[172:175], v[24:27]
	v_mfma_f32_16x16x32_bf16 v[152:155], v[140:143], v[176:179], v[20:23]
	v_mfma_f32_16x16x32_bf16 v[140:143], v[140:143], v[180:183], v[16:19]
	v_mfma_f32_16x16x32_bf16 v[136:139], v[136:139], v[180:183], v[0:3]
	s_nop 2
	ds_read_b128 v[0:3], v190 offset:1024
	ds_read_b128 v[8:11], v189 offset:1024
	ds_read_b128 v[16:19], v188 offset:1024
	ds_read_b128 v[20:23], v187 offset:1024
	ds_read_b128 v[160:163], v191 offset:1024
	ds_read_b128 v[168:171], v191 offset:3072
	ds_read_b128 v[172:175], v191 offset:5120
	ds_read_b128 v[176:179], v191 offset:7168
	s_waitcnt lgkmcnt(3)
	v_mfma_f32_16x16x32_bf16 v[104:107], v[0:3], v[160:163], v[104:107]
	s_waitcnt lgkmcnt(2)
	v_mfma_f32_16x16x32_bf16 v[180:183], v[0:3], v[168:171], v[52:55]
	s_waitcnt lgkmcnt(1)
	v_mfma_f32_16x16x32_bf16 v[32:35], v[0:3], v[172:175], v[48:51]
	s_waitcnt lgkmcnt(0)
	v_mfma_f32_16x16x32_bf16 v[0:3], v[0:3], v[176:179], v[96:99]
	ds_read_b128 v[24:27], v186 offset:1024
	v_mfma_f32_16x16x32_bf16 v[92:95], v[8:11], v[160:163], v[92:95]
	v_mfma_f32_16x16x32_bf16 v[88:91], v[8:11], v[168:171], v[88:91]
	v_mfma_f32_16x16x32_bf16 v[48:51], v[8:11], v[172:175], v[84:87]
	v_mfma_f32_16x16x32_bf16 v[12:15], v[8:11], v[176:179], v[80:83]
	ds_read_b128 v[8:11], v185 offset:1024
	v_mfma_f32_16x16x32_bf16 v[76:79], v[16:19], v[160:163], v[76:79]
	v_mfma_f32_16x16x32_bf16 v[72:75], v[16:19], v[168:171], v[72:75]
	v_mfma_f32_16x16x32_bf16 v[52:55], v[16:19], v[172:175], v[68:71]
	v_mfma_f32_16x16x32_bf16 v[16:19], v[16:19], v[176:179], v[64:67]
	s_nop 2
	ds_read_b128 v[64:67], v184 offset:1024
	v_mfma_f32_16x16x32_bf16 v[68:71], v[20:23], v[160:163], v[60:63]
	v_mfma_f32_16x16x32_bf16 v[80:83], v[20:23], v[168:171], v[56:59]
	v_mfma_f32_16x16x32_bf16 v[56:59], v[20:23], v[172:175], v[100:103]
	v_mfma_f32_16x16x32_bf16 v[20:23], v[20:23], v[176:179], v[128:131]
	ds_read_b128 v[84:87], v134 offset:1024
	s_waitcnt lgkmcnt(3)
	v_mfma_f32_16x16x32_bf16 v[96:99], v[24:27], v[160:163], v[44:47]
	v_mfma_f32_16x16x32_bf16 v[100:103], v[24:27], v[168:171], v[40:43]
	v_mfma_f32_16x16x32_bf16 v[60:63], v[24:27], v[172:175], v[36:39]
	v_mfma_f32_16x16x32_bf16 v[24:27], v[24:27], v[176:179], v[108:111]
	s_waitcnt lgkmcnt(2)
	v_mfma_f32_16x16x32_bf16 v[108:111], v[8:11], v[160:163], v[28:31]
	v_mfma_f32_16x16x32_bf16 v[128:131], v[8:11], v[168:171], v[144:147]
	v_mfma_f32_16x16x32_bf16 v[44:47], v[8:11], v[172:175], v[152:155]
	v_mfma_f32_16x16x32_bf16 v[8:11], v[8:11], v[176:179], v[140:143]
	s_waitcnt lgkmcnt(1)
	v_mfma_f32_16x16x32_bf16 v[140:143], v[64:67], v[160:163], v[148:151]
	v_mfma_f32_16x16x32_bf16 v[144:147], v[64:67], v[168:171], v[156:159]
	v_mfma_f32_16x16x32_bf16 v[40:43], v[64:67], v[172:175], v[4:7]
	v_mfma_f32_16x16x32_bf16 v[4:7], v[64:67], v[176:179], v[136:139]
	s_waitcnt lgkmcnt(0)
	v_mfma_f32_16x16x32_bf16 v[112:115], v[84:87], v[160:163], v[112:115]
	v_mfma_f32_16x16x32_bf16 v[116:119], v[84:87], v[168:171], v[116:119]
	v_mfma_f32_16x16x32_bf16 v[36:39], v[84:87], v[172:175], v[120:123]
	v_mfma_f32_16x16x32_bf16 v[28:31], v[84:87], v[176:179], v[124:127]
	v_mov_b32_e32 v65, v132
	v_mov_b32_e32 v64, s19
	s_waitcnt vmcnt(0)
	s_barrier
	ds_read_b64 v[66:67], v64
	s_and_b32 s4, s26, 14
	s_and_b64 s[30:31], exec, s[28:29]
	s_cselect_b32 s6, s59, 0x14800000
	s_cselect_b32 s27, s60, 0xa800000
	s_cmp_eq_u32 s4, 4
	s_cselect_b32 s6, s27, s6
	s_cselect_b32 s4, 0xfffffc00, s61
	s_cselect_b32 s27, 9, 10
	s_waitcnt lgkmcnt(0)
	v_lshl_add_u64 v[66:67], v[66:67], 0, s[6:7]
	s_lshl_b32 s6, s26, 8
	s_add_i32 s6, s4, s6
	s_and_b32 s34, s66, 0xf00
	s_and_b64 s[30:31], exec, s[28:29]
	s_cselect_b32 s4, 8, 12
	s_ashr_i32 s30, s66, s4
	s_ashr_i32 s31, s30, 31
	s_lshl_b64 s[30:31], s[30:31], s27
	s_ashr_i32 s27, s6, 31
	s_add_u32 s6, s30, s6
	v_and_b32_e32 v84, 0xc0, v65
	s_addc_u32 s27, s31, s27
	v_or_b32_e32 v84, s6, v84
	v_mov_b32_e32 v85, s27
	v_lshlrev_b64 v[84:85], s4, v[84:85]
	s_and_b64 s[30:31], exec, s[28:29]
	v_lshl_add_u64 v[66:67], v[84:85], 1, v[66:67]
	s_cselect_b32 s6, 0, s34
	v_ashrrev_i32_e32 v84, 1, v65
	s_lshl_b32 s6, s6, 1
	v_and_b32_e32 v84, 0xffffff80, v84
	v_lshrrev_b32_e32 v87, 6, v65
	v_lshl_add_u64 v[66:67], v[66:67], 0, s[6:7]
	v_ashrrev_i32_e32 v85, 31, v84
	v_bfe_u32 v64, v65, 4, 2
	v_and_b32_e32 v86, 15, v65
	v_lshl_add_u64 v[84:85], v[84:85], 1, v[66:67]
	v_mul_lo_u32 v66, v87, s55
	v_lshlrev_b32_e32 v65, 4, v65
	v_add_u32_e32 v66, s5, v66
	v_lshlrev_b32_e32 v67, 3, v64
	v_mul_u32_u24_e32 v86, 0x110, v86
	v_and_b32_e32 v134, 0xf0, v65
	v_mul_u32_u24_e32 v65, 0x110, v64
	v_add3_u32 v86, v66, v67, v86
	v_add3_u32 v87, v66, v134, v65
	v_cvt_pk_bf16_f32 v66, v104, v105
	v_cvt_pk_bf16_f32 v67, v106, v107
	ds_write_b64 v86, v[66:67]
	v_cvt_pk_bf16_f32 v66, v92, v93
	v_cvt_pk_bf16_f32 v67, v94, v95
	ds_write_b64 v86, v[66:67] offset:32
	v_cvt_pk_bf16_f32 v66, v76, v77
	v_cvt_pk_bf16_f32 v67, v78, v79
	ds_write_b64 v86, v[66:67] offset:64
	v_cvt_pk_bf16_f32 v66, v68, v69
	v_cvt_pk_bf16_f32 v67, v70, v71
	ds_write_b64 v86, v[66:67] offset:96
	v_cvt_pk_bf16_f32 v66, v96, v97
	v_cvt_pk_bf16_f32 v67, v98, v99
	ds_write_b64 v86, v[66:67] offset:128
	v_cvt_pk_bf16_f32 v66, v108, v109
	v_cvt_pk_bf16_f32 v67, v110, v111
	ds_write_b64 v86, v[66:67] offset:160
	v_cvt_pk_bf16_f32 v66, v140, v141
	v_cvt_pk_bf16_f32 v67, v142, v143
	ds_write_b64 v86, v[66:67] offset:192
	v_cvt_pk_bf16_f32 v66, v112, v113
	v_cvt_pk_bf16_f32 v67, v114, v115
	ds_write_b64 v86, v[66:67] offset:224
	v_cvt_pk_bf16_f32 v66, v180, v181
	v_cvt_pk_bf16_f32 v67, v182, v183
	ds_write_b64 v86, v[66:67] offset:4352
	v_cvt_pk_bf16_f32 v66, v88, v89
	v_cvt_pk_bf16_f32 v67, v90, v91
	ds_write_b64 v86, v[66:67] offset:4384
	v_cvt_pk_bf16_f32 v66, v72, v73
	v_cvt_pk_bf16_f32 v67, v74, v75
	ds_write_b64 v86, v[66:67] offset:4416
	v_cvt_pk_bf16_f32 v66, v80, v81
	v_cvt_pk_bf16_f32 v67, v82, v83
	ds_write_b64 v86, v[66:67] offset:4448
	v_cvt_pk_bf16_f32 v66, v100, v101
	v_cvt_pk_bf16_f32 v67, v102, v103
	ds_write_b64 v86, v[66:67] offset:4480
	v_cvt_pk_bf16_f32 v66, v128, v129
	v_cvt_pk_bf16_f32 v67, v130, v131
	ds_write_b64 v86, v[66:67] offset:4512
	v_cvt_pk_bf16_f32 v66, v144, v145
	v_cvt_pk_bf16_f32 v67, v146, v147
	ds_write_b64 v86, v[66:67] offset:4544
	v_cvt_pk_bf16_f32 v66, v116, v117
	v_cvt_pk_bf16_f32 v67, v118, v119
	ds_write_b64 v86, v[66:67] offset:4576
	ds_read_b128 v[66:69], v87
	v_mov_b32_e32 v65, v135
	v_lshl_add_u64 v[70:71], v[84:85], 0, v[134:135]
	v_lshlrev_b64 v[72:73], s4, v[64:65]
	v_lshl_add_u64 v[72:73], v[72:73], 1, v[70:71]
	s_waitcnt lgkmcnt(0)
	flat_store_dwordx4 v[72:73], v[66:69] nt
	ds_read_b128 v[66:69], v87 offset:1088
	v_or_b32_e32 v134, 4, v64
	v_lshlrev_b64 v[72:73], s4, v[134:135]
	v_lshl_add_u64 v[72:73], v[72:73], 1, v[70:71]
	v_or_b32_e32 v134, 8, v64
	s_waitcnt lgkmcnt(0)
	flat_store_dwordx4 v[72:73], v[66:69] nt
	ds_read_b128 v[66:69], v87 offset:2176
	v_lshlrev_b64 v[72:73], s4, v[134:135]
	v_lshl_add_u64 v[72:73], v[72:73], 1, v[70:71]
	v_or_b32_e32 v134, 12, v64
	v_cvt_pk_bf16_f32 v32, v32, v33
	s_waitcnt lgkmcnt(0)
	flat_store_dwordx4 v[72:73], v[66:69] nt
	ds_read_b128 v[66:69], v87 offset:3264
	v_lshlrev_b64 v[72:73], s4, v[134:135]
	v_lshl_add_u64 v[72:73], v[72:73], 1, v[70:71]
	v_or_b32_e32 v134, 16, v64
	v_cvt_pk_bf16_f32 v33, v34, v35
	s_waitcnt lgkmcnt(0)
	flat_store_dwordx4 v[72:73], v[66:69] nt
	ds_read_b128 v[66:69], v87 offset:4352
	v_lshlrev_b64 v[72:73], s4, v[134:135]
	v_lshl_add_u64 v[72:73], v[72:73], 1, v[70:71]
	v_or_b32_e32 v134, 20, v64
	v_cvt_pk_bf16_f32 v0, v0, v1
	s_waitcnt lgkmcnt(0)
	flat_store_dwordx4 v[72:73], v[66:69] nt
	ds_read_b128 v[66:69], v87 offset:5440
	v_lshlrev_b64 v[72:73], s4, v[134:135]
	v_lshl_add_u64 v[72:73], v[72:73], 1, v[70:71]
	v_or_b32_e32 v134, 24, v64
	v_cvt_pk_bf16_f32 v1, v2, v3
	s_waitcnt lgkmcnt(0)
	flat_store_dwordx4 v[72:73], v[66:69] nt
	ds_read_b128 v[66:69], v87 offset:6528
	v_lshlrev_b64 v[72:73], s4, v[134:135]
	v_lshl_add_u64 v[72:73], v[72:73], 1, v[70:71]
	v_or_b32_e32 v134, 28, v64
	s_waitcnt lgkmcnt(0)
	flat_store_dwordx4 v[72:73], v[66:69] nt
	ds_read_b128 v[66:69], v87 offset:7616
	v_lshlrev_b64 v[72:73], s4, v[134:135]
	v_lshl_add_u64 v[72:73], v[72:73], 1, v[70:71]
	v_or_b32_e32 v134, 32, v64
	s_waitcnt lgkmcnt(0)
	flat_store_dwordx4 v[72:73], v[66:69] nt
	ds_write_b64 v86, v[32:33]
	v_cvt_pk_bf16_f32 v32, v48, v49
	v_cvt_pk_bf16_f32 v33, v50, v51
	ds_write_b64 v86, v[0:1] offset:4352
	v_cvt_pk_bf16_f32 v0, v12, v13
	v_cvt_pk_bf16_f32 v1, v14, v15
	ds_write_b64 v86, v[32:33] offset:32
	v_cvt_pk_bf16_f32 v32, v52, v53
	v_cvt_pk_bf16_f32 v33, v54, v55
	ds_write_b64 v86, v[0:1] offset:4384
	v_cvt_pk_bf16_f32 v0, v16, v17
	v_cvt_pk_bf16_f32 v1, v18, v19
	ds_write_b64 v86, v[32:33] offset:64
	v_cvt_pk_bf16_f32 v32, v56, v57
	v_cvt_pk_bf16_f32 v33, v58, v59
	ds_write_b64 v86, v[0:1] offset:4416
	v_cvt_pk_bf16_f32 v0, v20, v21
	v_cvt_pk_bf16_f32 v1, v22, v23
	ds_write_b64 v86, v[32:33] offset:96
	v_cvt_pk_bf16_f32 v32, v60, v61
	v_cvt_pk_bf16_f32 v33, v62, v63
	ds_write_b64 v86, v[0:1] offset:4448
	v_cvt_pk_bf16_f32 v0, v24, v25
	v_cvt_pk_bf16_f32 v1, v26, v27
	ds_write_b64 v86, v[32:33] offset:128
	v_cvt_pk_bf16_f32 v32, v44, v45
	v_cvt_pk_bf16_f32 v33, v46, v47
	ds_write_b64 v86, v[0:1] offset:4480
	v_cvt_pk_bf16_f32 v0, v8, v9
	v_cvt_pk_bf16_f32 v1, v10, v11
	ds_write_b64 v86, v[32:33] offset:160
	v_cvt_pk_bf16_f32 v32, v40, v41
	v_cvt_pk_bf16_f32 v33, v42, v43
	ds_write_b64 v86, v[0:1] offset:4512
	v_cvt_pk_bf16_f32 v0, v4, v5
	v_cvt_pk_bf16_f32 v1, v6, v7
	ds_write_b64 v86, v[32:33] offset:192
	v_cvt_pk_bf16_f32 v32, v36, v37
	v_cvt_pk_bf16_f32 v33, v38, v39
	ds_write_b64 v86, v[0:1] offset:4544
	v_cvt_pk_bf16_f32 v0, v28, v29
	v_cvt_pk_bf16_f32 v1, v30, v31
	ds_write_b64 v86, v[32:33] offset:224
	ds_write_b64 v86, v[0:1] offset:4576
	ds_read_b128 v[0:3], v87
	v_lshlrev_b64 v[4:5], s4, v[134:135]
	v_lshl_add_u64 v[4:5], v[4:5], 1, v[70:71]
	v_or_b32_e32 v134, 36, v64
	s_waitcnt lgkmcnt(0)
	flat_store_dwordx4 v[4:5], v[0:3] nt
	ds_read_b128 v[0:3], v87 offset:1088
	v_lshlrev_b64 v[4:5], s4, v[134:135]
	v_lshl_add_u64 v[4:5], v[4:5], 1, v[70:71]
	v_or_b32_e32 v134, 40, v64
	s_waitcnt lgkmcnt(0)
	flat_store_dwordx4 v[4:5], v[0:3] nt
	ds_read_b128 v[0:3], v87 offset:2176
	v_lshlrev_b64 v[4:5], s4, v[134:135]
	v_lshl_add_u64 v[4:5], v[4:5], 1, v[70:71]
	v_or_b32_e32 v134, 44, v64
	s_waitcnt lgkmcnt(0)
	flat_store_dwordx4 v[4:5], v[0:3] nt
	ds_read_b128 v[0:3], v87 offset:3264
	v_lshlrev_b64 v[4:5], s4, v[134:135]
	v_lshl_add_u64 v[4:5], v[4:5], 1, v[70:71]
	v_or_b32_e32 v134, 48, v64
	s_waitcnt lgkmcnt(0)
	flat_store_dwordx4 v[4:5], v[0:3] nt
	ds_read_b128 v[0:3], v87 offset:4352
	v_lshlrev_b64 v[4:5], s4, v[134:135]
	v_lshl_add_u64 v[4:5], v[4:5], 1, v[70:71]
	v_or_b32_e32 v134, 52, v64
	s_waitcnt lgkmcnt(0)
	flat_store_dwordx4 v[4:5], v[0:3] nt
	ds_read_b128 v[0:3], v87 offset:5440
	v_lshlrev_b64 v[4:5], s4, v[134:135]
	v_lshl_add_u64 v[4:5], v[4:5], 1, v[70:71]
	v_or_b32_e32 v134, 56, v64
	s_waitcnt lgkmcnt(0)
	flat_store_dwordx4 v[4:5], v[0:3] nt
	ds_read_b128 v[0:3], v87 offset:6528
	v_lshlrev_b64 v[4:5], s4, v[134:135]
	v_lshl_add_u64 v[4:5], v[4:5], 1, v[70:71]
	v_or_b32_e32 v134, 60, v64
	s_waitcnt lgkmcnt(0)
	flat_store_dwordx4 v[4:5], v[0:3] nt
	ds_read_b128 v[0:3], v87 offset:7616
	v_lshlrev_b64 v[4:5], s4, v[134:135]
	v_lshl_add_u64 v[4:5], v[4:5], 1, v[70:71]
	s_waitcnt lgkmcnt(0)
	flat_store_dwordx4 v[4:5], v[0:3] nt

.LBB0_180:
	s_nop 0
	v_mov_b32_e32 v0, s19
	v_mov_b32_e32 v16, v132
	ds_read_b64 v[128:129], v0
	s_and_b64 s[4:5], exec, s[28:29]
	v_lshlrev_b32_e32 v7, 4, v16
	v_and_b32_e32 v6, 32, v16
	v_lshrrev_b32_e32 v8, 1, v16
	v_bitop3_b32 v6, v7, v6, 48 bitop3:0x6c
	s_cselect_b32 s4, 0x8000, 0
	v_bfe_u32 v17, v16, 2, 4
	v_and_b32_e32 v18, 32, v8
	v_lshrrev_b32_e32 v19, 1, v6
	v_ashrrev_i32_e32 v20, 3, v16
	s_add_i32 s4, s66, s4
	v_or_b32_e32 v10, v19, v18
	v_and_or_b32 v6, v20, s48, v17
	s_ashr_i32 s5, s4, 31
	v_and_b32_e32 v9, 0xfffffc00, v7
	v_lshl_or_b32 v134, v6, 10, v10
	v_add_u32_e32 v6, 0x2000, v7
	v_add_u32_e32 v8, 0x4000, v7
	v_add_u32_e32 v7, 0x6000, v7
	s_lshl_b64 s[4:5], s[4:5], 11
	s_ashr_i32 s27, s26, 31
	v_ashrrev_i32_e32 v21, 7, v6
	v_ashrrev_i32_e32 v22, 7, v8
	v_ashrrev_i32_e32 v23, 7, v7
	s_waitcnt lgkmcnt(0)
	v_lshl_add_u64 v[0:1], v[128:129], 0, s[4:5]
	s_lshl_b64 s[4:5], s[26:27], 19
	v_and_or_b32 v6, v21, s48, v17
	v_and_or_b32 v8, v22, s48, v17
	v_and_or_b32 v7, v23, s48, v17
	v_add_u32_e32 v150, 0, v9
	v_lshl_add_u64 v[2:3], v[0:1], 0, s[8:9]
	v_lshl_add_u64 v[4:5], v[128:129], 0, s[4:5]
	v_lshl_or_b32 v6, v6, 10, v10
	v_lshl_or_b32 v8, v8, 10, v10
	v_lshl_or_b32 v10, v7, 10, v10
	v_add_u32_e32 v7, 0x8000, v150
	v_lshlrev_b64 v[12:13], 1, v[134:135]
	v_readfirstlane_b32 s4, v150
	v_lshl_add_u64 v[14:15], v[2:3], 0, v[12:13]
	s_mov_b32 m0, s4
	v_readfirstlane_b32 s4, v7
	v_mov_b32_e32 v7, v135
	v_add_u32_e32 v9, 0x2000, v150
	global_load_lds_dwordx4 v[14:15], off
	v_lshl_add_u64 v[12:13], v[4:5], 0, v[12:13]
	s_mov_b32 m0, s4
	v_lshlrev_b64 v[6:7], 1, v[6:7]
	v_readfirstlane_b32 s4, v9
	v_add_u32_e32 v9, 0xa000, v150
	global_load_lds_dwordx4 v[12:13], off
	v_lshl_add_u64 v[12:13], v[2:3], 0, v[6:7]
	s_mov_b32 m0, s4
	v_readfirstlane_b32 s4, v9
	global_load_lds_dwordx4 v[12:13], off
	v_lshl_add_u64 v[6:7], v[4:5], 0, v[6:7]
	s_mov_b32 m0, s4
	v_mov_b32_e32 v9, v135
	v_add_u32_e32 v11, 0x4000, v150
	global_load_lds_dwordx4 v[6:7], off
	v_lshlrev_b64 v[6:7], 1, v[8:9]
	v_readfirstlane_b32 s4, v11
	v_lshl_add_u64 v[8:9], v[2:3], 0, v[6:7]
	s_mov_b32 m0, s4
	v_lshl_add_u64 v[6:7], v[4:5], 0, v[6:7]
	global_load_lds_dwordx4 v[8:9], off
	v_add_u32_e32 v8, 0xc000, v150
	v_mov_b32_e32 v11, v135
	v_readfirstlane_b32 s4, v8
	s_mov_b32 m0, s4
	v_add_u32_e32 v8, 0x6000, v150
	global_load_lds_dwordx4 v[6:7], off
	v_lshlrev_b64 v[6:7], 1, v[10:11]
	v_readfirstlane_b32 s4, v8
	v_lshl_add_u64 v[2:3], v[2:3], 0, v[6:7]
	s_mov_b32 m0, s4
	v_and_b32_e32 v24, 15, v16
	global_load_lds_dwordx4 v[2:3], off
	v_lshl_add_u64 v[2:3], v[4:5], 0, v[6:7]
	v_add_u32_e32 v6, 0xe000, v150
	v_lshlrev_b32_e32 v10, 10, v17
	v_readfirstlane_b32 s4, v6
	s_mov_b32 m0, s4
	v_lshlrev_b32_e32 v6, 2, v16
	global_load_lds_dwordx4 v[2:3], off
	v_and_b32_e32 v2, 48, v16
	v_lshlrev_b32_e32 v3, 6, v24
	v_and_b32_e32 v6, 32, v6
	v_bitop3_b32 v151, v3, v6, v2 bitop3:0x36
	v_lshlrev_b32_e32 v3, 7, v16
	v_and_b32_e32 v152, 0x6000, v3
	v_lshlrev_b32_e32 v3, 6, v16
	v_and_b32_e32 v153, 0xffffc000, v3
	v_and_b32_e32 v3, 0x3c0, v3
	v_bitop3_b32 v154, v3, v6, v2 bitop3:0x36
	v_lshlrev_b32_e32 v2, 10, v23
	v_and_or_b32 v2, v2, s49, v19
	v_lshlrev_b32_e32 v6, 10, v22
	v_or3_b32 v134, v2, v10, v18
	v_and_or_b32 v6, v6, s49, v19
	v_lshlrev_b32_e32 v8, 10, v21
	v_lshlrev_b64 v[2:3], 1, v[134:135]
	v_or3_b32 v134, v6, v10, v18
	v_and_or_b32 v8, v8, s49, v19
	v_lshlrev_b32_e32 v11, 10, v20
	v_lshlrev_b64 v[6:7], 1, v[134:135]
	v_or3_b32 v134, v8, v10, v18
	v_and_or_b32 v11, v11, s49, v19
	s_waitcnt vmcnt(0)
	v_lshl_add_u64 v[4:5], v[4:5], 0, s[10:11]
	v_lshlrev_b64 v[8:9], 1, v[134:135]
	v_or3_b32 v134, v11, v10, v18
	v_lshl_add_u64 v[0:1], v[0:1], 0, s[12:13]
	v_lshl_add_u64 v[138:139], v[4:5], 0, v[8:9]
	v_lshlrev_b64 v[10:11], 1, v[134:135]
	v_lshl_add_u64 v[146:147], v[0:1], 0, v[8:9]
	v_mov_b32_e32 v8, 0
	s_mov_b32 s6, 0
	v_lshl_add_u64 v[130:131], v[4:5], 0, v[2:3]
	v_lshl_add_u64 v[136:137], v[4:5], 0, v[6:7]
	v_lshl_add_u64 v[140:141], v[4:5], 0, v[10:11]
	v_lshl_add_u64 v[142:143], v[0:1], 0, v[2:3]
	v_lshl_add_u64 v[144:145], v[0:1], 0, v[6:7]
	v_lshl_add_u64 v[148:149], v[0:1], 0, v[10:11]
	s_mov_b64 s[4:5], 0
	v_mov_b32_e32 v9, v8
	v_mov_b32_e32 v10, v8
	v_mov_b32_e32 v11, v8
	v_mov_b32_e32 v20, v8
	v_mov_b32_e32 v21, v8
	v_mov_b32_e32 v22, v8
	v_mov_b32_e32 v23, v8
	v_mov_b32_e32 v28, v8
	v_mov_b32_e32 v29, v8
	v_mov_b32_e32 v30, v8
	v_mov_b32_e32 v31, v8
	v_mov_b32_e32 v36, v8
	v_mov_b32_e32 v37, v8
	v_mov_b32_e32 v38, v8
	v_mov_b32_e32 v39, v8
	v_mov_b32_e32 v0, v8
	v_mov_b32_e32 v1, v8
	v_mov_b32_e32 v2, v8
	v_mov_b32_e32 v3, v8
	v_mov_b32_e32 v4, v8
	v_mov_b32_e32 v5, v8
	v_mov_b32_e32 v6, v8
	v_mov_b32_e32 v7, v8
	v_mov_b32_e32 v12, v8
	v_mov_b32_e32 v13, v8
	v_mov_b32_e32 v14, v8
	v_mov_b32_e32 v15, v8
	v_mov_b32_e32 v16, v8
	v_mov_b32_e32 v17, v8
	v_mov_b32_e32 v18, v8
	v_mov_b32_e32 v19, v8
	v_mov_b32_e32 v24, v8
	v_mov_b32_e32 v25, v8
	v_mov_b32_e32 v26, v8
	v_mov_b32_e32 v27, v8
	v_mov_b32_e32 v32, v8
	v_mov_b32_e32 v33, v8
	v_mov_b32_e32 v34, v8
	v_mov_b32_e32 v35, v8
	v_mov_b32_e32 v40, v8
	v_mov_b32_e32 v41, v8
	v_mov_b32_e32 v42, v8
	v_mov_b32_e32 v43, v8
	v_mov_b32_e32 v44, v8
	v_mov_b32_e32 v45, v8
	v_mov_b32_e32 v46, v8
	v_mov_b32_e32 v47, v8
	v_mov_b32_e32 v48, v8
	v_mov_b32_e32 v49, v8
	v_mov_b32_e32 v50, v8
	v_mov_b32_e32 v51, v8
	v_mov_b32_e32 v52, v8
	v_mov_b32_e32 v53, v8
	v_mov_b32_e32 v54, v8
	v_mov_b32_e32 v55, v8
	v_mov_b32_e32 v56, v8
	v_mov_b32_e32 v57, v8
	v_mov_b32_e32 v58, v8
	v_mov_b32_e32 v59, v8
	v_mov_b32_e32 v60, v8
	v_mov_b32_e32 v61, v8
	v_mov_b32_e32 v62, v8
	v_mov_b32_e32 v63, v8
	v_mov_b32_e32 v64, v8
	v_mov_b32_e32 v65, v8
	v_mov_b32_e32 v66, v8
	v_mov_b32_e32 v67, v8
	v_mov_b32_e32 v68, v8
	v_mov_b32_e32 v69, v8
	v_mov_b32_e32 v70, v8
	v_mov_b32_e32 v71, v8
	v_mov_b32_e32 v72, v8
	v_mov_b32_e32 v73, v8
	v_mov_b32_e32 v74, v8
	v_mov_b32_e32 v75, v8
	v_mov_b32_e32 v76, v8
	v_mov_b32_e32 v77, v8
	v_mov_b32_e32 v78, v8
	v_mov_b32_e32 v79, v8
	v_mov_b32_e32 v80, v8
	v_mov_b32_e32 v81, v8
	v_mov_b32_e32 v82, v8
	v_mov_b32_e32 v83, v8
	v_mov_b32_e32 v84, v8
	v_mov_b32_e32 v85, v8
	v_mov_b32_e32 v86, v8
	v_mov_b32_e32 v87, v8
	v_mov_b32_e32 v88, v8
	v_mov_b32_e32 v89, v8
	v_mov_b32_e32 v90, v8
	v_mov_b32_e32 v91, v8
	v_mov_b32_e32 v92, v8
	v_mov_b32_e32 v93, v8
	v_mov_b32_e32 v94, v8
	v_mov_b32_e32 v95, v8
	v_mov_b32_e32 v96, v8
	v_mov_b32_e32 v97, v8
	v_mov_b32_e32 v98, v8
	v_mov_b32_e32 v99, v8
	v_mov_b32_e32 v100, v8
	v_mov_b32_e32 v101, v8
	v_mov_b32_e32 v102, v8
	v_mov_b32_e32 v103, v8
	v_mov_b32_e32 v104, v8
	v_mov_b32_e32 v105, v8
	v_mov_b32_e32 v106, v8
	v_mov_b32_e32 v107, v8
	v_mov_b32_e32 v108, v8
	v_mov_b32_e32 v109, v8
	v_mov_b32_e32 v110, v8
	v_mov_b32_e32 v111, v8
	v_mov_b32_e32 v112, v8
	v_mov_b32_e32 v113, v8
	v_mov_b32_e32 v114, v8
	v_mov_b32_e32 v115, v8
	v_mov_b32_e32 v116, v8
	v_mov_b32_e32 v117, v8
	v_mov_b32_e32 v118, v8
	v_mov_b32_e32 v119, v8
	v_mov_b32_e32 v120, v8
	v_mov_b32_e32 v121, v8
	v_mov_b32_e32 v122, v8
	v_mov_b32_e32 v123, v8
	v_mov_b32_e32 v124, v8
	v_mov_b32_e32 v125, v8
	v_mov_b32_e32 v126, v8
	v_mov_b32_e32 v127, v8
	v_or_b32_e32 v134, 0x800, v153
	v_or_b32_e32 v155, 0x1000, v153
	v_or_b32_e32 v156, 0x1800, v153
	v_or_b32_e32 v157, 0x2000, v153
	v_or_b32_e32 v158, 0x2800, v153
	v_or_b32_e32 v159, 0x3000, v153
	v_or_b32_e32 v160, 0x3800, v153
	s_waitcnt vmcnt(0) lgkmcnt(0)
	s_barrier
	v_readfirstlane_b32 s100, v150
	s_mov_b64 s[98:99], 0x80
	s_and_b32 s27, s6, 0x10000
	s_xor_b32 s28, s27, 0x10000
	s_add_i32 s27, s27, 0
	v_add3_u32 v161, s27, v151, v152
	v_add3_u32 v162, s27, v151, v153
	v_add3_u32 v163, s27, v154, v134
	v_add3_u32 v200, s27, v154, v155
	v_add3_u32 v201, s27, v154, v156
	v_add3_u32 v202, s27, v154, v157
	v_add3_u32 v203, s27, v154, v158
	v_add3_u32 v204, s27, v154, v159
	v_add3_u32 v205, s27, v154, v160
	ds_read_b128 v[184:187], v161 offset:32768
	ds_read_b128 v[168:171], v162
	ds_read_b128 v[172:175], v163
	ds_read_b128 v[176:179], v200
	ds_read_b128 v[180:183], v201
	ds_read_b128 v[188:191], v161 offset:34816
	ds_read_b128 v[192:195], v161 offset:36864
	ds_read_b128 v[196:199], v161 offset:38912
	s_add_i32 s101, s100, s28
	s_mov_b32 m0, s101
	s_nop 0
	global_load_lds_dwordx4 v[148:149], off
	s_add_i32 m0, s101, 0x8000
	s_nop 0
	global_load_lds_dwordx4 v[140:141], off
	s_add_i32 m0, s101, 0x2000
	s_nop 0
	global_load_lds_dwordx4 v[146:147], off
	s_add_i32 m0, s101, 0xa000
	s_nop 0
	global_load_lds_dwordx4 v[138:139], off
	s_add_i32 m0, s101, 0x4000
	s_nop 0
	global_load_lds_dwordx4 v[144:145], off
	s_add_i32 m0, s101, 0xc000
	s_nop 0
	global_load_lds_dwordx4 v[136:137], off
	s_add_i32 m0, s101, 0x6000
	s_nop 0
	global_load_lds_dwordx4 v[142:143], off
	s_add_i32 m0, s101, 0xe000
	s_nop 0
	global_load_lds_dwordx4 v[130:131], off
.LBB0_181:
	s_and_b32 s27, s6, 0x10000
	s_xor_b32 s28, s27, 0x10000
	s_add_i32 s27, s27, 0
	s_waitcnt lgkmcnt(3)
	v_mfma_f32_16x16x32_bf16 v[124:127], v[184:187], v[168:171], v[124:127]
	v_mfma_f32_16x16x32_bf16 v[108:111], v[184:187], v[172:175], v[108:111]
	v_mfma_f32_16x16x32_bf16 v[92:95], v[184:187], v[176:179], v[92:95]
	v_mfma_f32_16x16x32_bf16 v[76:79], v[184:187], v[180:183], v[76:79]
	ds_read_b128 v[240:243], v202
	ds_read_b128 v[244:247], v203
	s_waitcnt lgkmcnt(4)
	v_mfma_f32_16x16x32_bf16 v[120:123], v[188:191], v[168:171], v[120:123]
	v_mfma_f32_16x16x32_bf16 v[104:107], v[188:191], v[172:175], v[104:107]
	v_mfma_f32_16x16x32_bf16 v[88:91], v[188:191], v[176:179], v[88:91]
	v_mfma_f32_16x16x32_bf16 v[72:75], v[188:191], v[180:183], v[72:75]
	ds_read_b128 v[248:251], v204
	ds_read_b128 v[252:255], v205
	s_waitcnt lgkmcnt(5)
	v_mfma_f32_16x16x32_bf16 v[116:119], v[192:195], v[168:171], v[116:119]
	v_mfma_f32_16x16x32_bf16 v[100:103], v[192:195], v[172:175], v[100:103]
	v_mfma_f32_16x16x32_bf16 v[84:87], v[192:195], v[176:179], v[84:87]
	v_mfma_f32_16x16x32_bf16 v[68:71], v[192:195], v[180:183], v[68:71]
	s_waitcnt lgkmcnt(4)
	v_mfma_f32_16x16x32_bf16 v[112:115], v[196:199], v[168:171], v[112:115]
	v_mfma_f32_16x16x32_bf16 v[96:99], v[196:199], v[172:175], v[96:99]
	v_mfma_f32_16x16x32_bf16 v[80:83], v[196:199], v[176:179], v[80:83]
	v_mfma_f32_16x16x32_bf16 v[64:67], v[196:199], v[180:183], v[64:67]
	ds_read_b128 v[168:171], v162 offset:1024
	ds_read_b128 v[172:175], v163 offset:1024
	ds_read_b128 v[176:179], v200 offset:1024
	ds_read_b128 v[180:183], v201 offset:1024
	s_waitcnt lgkmcnt(4)
	v_mfma_f32_16x16x32_bf16 v[60:63], v[184:187], v[240:243], v[60:63]
	v_mfma_f32_16x16x32_bf16 v[44:47], v[184:187], v[244:247], v[44:47]
	v_mfma_f32_16x16x32_bf16 v[16:19], v[184:187], v[248:251], v[16:19]
	v_mfma_f32_16x16x32_bf16 v[36:39], v[184:187], v[252:255], v[36:39]
	ds_read_b128 v[184:187], v161 offset:33792
	v_mfma_f32_16x16x32_bf16 v[56:59], v[188:191], v[240:243], v[56:59]
	v_mfma_f32_16x16x32_bf16 v[40:43], v[188:191], v[244:247], v[40:43]
	v_mfma_f32_16x16x32_bf16 v[12:15], v[188:191], v[248:251], v[12:15]
	v_mfma_f32_16x16x32_bf16 v[28:31], v[188:191], v[252:255], v[28:31]
	ds_read_b128 v[188:191], v161 offset:35840
	v_mfma_f32_16x16x32_bf16 v[52:55], v[192:195], v[240:243], v[52:55]
	v_mfma_f32_16x16x32_bf16 v[32:35], v[192:195], v[244:247], v[32:35]
	v_mfma_f32_16x16x32_bf16 v[4:7], v[192:195], v[248:251], v[4:7]
	v_mfma_f32_16x16x32_bf16 v[20:23], v[192:195], v[252:255], v[20:23]
	ds_read_b128 v[192:195], v161 offset:37888
	v_mfma_f32_16x16x32_bf16 v[48:51], v[196:199], v[240:243], v[48:51]
	v_mfma_f32_16x16x32_bf16 v[24:27], v[196:199], v[244:247], v[24:27]
	v_mfma_f32_16x16x32_bf16 v[0:3], v[196:199], v[248:251], v[0:3]
	v_mfma_f32_16x16x32_bf16 v[8:11], v[196:199], v[252:255], v[8:11]
	ds_read_b128 v[196:199], v161 offset:39936
	s_waitcnt lgkmcnt(3)
	v_mfma_f32_16x16x32_bf16 v[124:127], v[184:187], v[168:171], v[124:127]
	v_mfma_f32_16x16x32_bf16 v[108:111], v[184:187], v[172:175], v[108:111]
	v_mfma_f32_16x16x32_bf16 v[92:95], v[184:187], v[176:179], v[92:95]
	v_mfma_f32_16x16x32_bf16 v[76:79], v[184:187], v[180:183], v[76:79]
	ds_read_b128 v[240:243], v202 offset:1024
	ds_read_b128 v[244:247], v203 offset:1024
	s_waitcnt lgkmcnt(4)
	v_mfma_f32_16x16x32_bf16 v[120:123], v[188:191], v[168:171], v[120:123]
	v_mfma_f32_16x16x32_bf16 v[104:107], v[188:191], v[172:175], v[104:107]
	v_mfma_f32_16x16x32_bf16 v[88:91], v[188:191], v[176:179], v[88:91]
	v_mfma_f32_16x16x32_bf16 v[72:75], v[188:191], v[180:183], v[72:75]
	ds_read_b128 v[248:251], v204 offset:1024
	ds_read_b128 v[252:255], v205 offset:1024
	s_waitcnt lgkmcnt(5)
	v_mfma_f32_16x16x32_bf16 v[116:119], v[192:195], v[168:171], v[116:119]
	v_mfma_f32_16x16x32_bf16 v[100:103], v[192:195], v[172:175], v[100:103]
	v_mfma_f32_16x16x32_bf16 v[84:87], v[192:195], v[176:179], v[84:87]
	v_mfma_f32_16x16x32_bf16 v[68:71], v[192:195], v[180:183], v[68:71]
	s_waitcnt lgkmcnt(4)
	v_mfma_f32_16x16x32_bf16 v[112:115], v[196:199], v[168:171], v[112:115]
	v_mfma_f32_16x16x32_bf16 v[96:99], v[196:199], v[172:175], v[96:99]
	v_mfma_f32_16x16x32_bf16 v[80:83], v[196:199], v[176:179], v[80:83]
	v_mfma_f32_16x16x32_bf16 v[64:67], v[196:199], v[180:183], v[64:67]
	s_waitcnt vmcnt(0) lgkmcnt(0)
	s_barrier
	s_add_i32 s101, s100, s27
	v_mfma_f32_16x16x32_bf16 v[60:63], v[184:187], v[240:243], v[60:63]
	v_mfma_f32_16x16x32_bf16 v[44:47], v[184:187], v[244:247], v[44:47]
	v_mfma_f32_16x16x32_bf16 v[16:19], v[184:187], v[248:251], v[16:19]
	v_mfma_f32_16x16x32_bf16 v[36:39], v[184:187], v[252:255], v[36:39]
	v_add3_u32 v161, s28, v151, v152
	ds_read_b128 v[184:187], v161 offset:32768
	v_add3_u32 v162, s28, v151, v153
	v_add3_u32 v163, s28, v154, v134
	v_add3_u32 v200, s28, v154, v155
	v_add3_u32 v201, s28, v154, v156
	ds_read_b128 v[168:171], v162
	ds_read_b128 v[172:175], v163
	ds_read_b128 v[176:179], v200
	ds_read_b128 v[180:183], v201
	s_cmpk_eq_i32 s4, 0x700
	s_cbranch_scc1 .Lpk_181_0
	s_mov_b32 m0, s101
	v_lshl_add_u64 v[148:149], v[148:149], 0, s[98:99]
	global_load_lds_dwordx4 v[148:149], off
.Lpk_181_0:
	s_cmpk_eq_i32 s4, 0x700
	s_cbranch_scc1 .Lpk_181_1
	s_add_i32 m0, s101, 0x8000
	v_lshl_add_u64 v[140:141], v[140:141], 0, s[98:99]
	global_load_lds_dwordx4 v[140:141], off
.Lpk_181_1:
	v_mfma_f32_16x16x32_bf16 v[56:59], v[188:191], v[240:243], v[56:59]
	v_mfma_f32_16x16x32_bf16 v[40:43], v[188:191], v[244:247], v[40:43]
	v_mfma_f32_16x16x32_bf16 v[12:15], v[188:191], v[248:251], v[12:15]
	v_mfma_f32_16x16x32_bf16 v[28:31], v[188:191], v[252:255], v[28:31]
	ds_read_b128 v[188:191], v161 offset:34816
	v_add3_u32 v202, s28, v154, v157
	v_add3_u32 v203, s28, v154, v158
	v_add3_u32 v204, s28, v154, v159
	v_add3_u32 v205, s28, v154, v160
	s_cmpk_eq_i32 s4, 0x700
	s_cbranch_scc1 .Lpk_181_2
	s_add_i32 m0, s101, 0x2000
	v_lshl_add_u64 v[146:147], v[146:147], 0, s[98:99]
	global_load_lds_dwordx4 v[146:147], off
.Lpk_181_2:
	s_cmpk_eq_i32 s4, 0x700
	s_cbranch_scc1 .Lpk_181_3
	s_add_i32 m0, s101, 0xa000
	v_lshl_add_u64 v[138:139], v[138:139], 0, s[98:99]
	global_load_lds_dwordx4 v[138:139], off
.Lpk_181_3:
	v_mfma_f32_16x16x32_bf16 v[52:55], v[192:195], v[240:243], v[52:55]
	v_mfma_f32_16x16x32_bf16 v[32:35], v[192:195], v[244:247], v[32:35]
	v_mfma_f32_16x16x32_bf16 v[4:7], v[192:195], v[248:251], v[4:7]
	v_mfma_f32_16x16x32_bf16 v[20:23], v[192:195], v[252:255], v[20:23]
	ds_read_b128 v[192:195], v161 offset:36864
	s_cmpk_eq_i32 s4, 0x700
	s_cbranch_scc1 .Lpk_181_4
	s_add_i32 m0, s101, 0x4000
	v_lshl_add_u64 v[144:145], v[144:145], 0, s[98:99]
	global_load_lds_dwordx4 v[144:145], off
.Lpk_181_4:
	s_cmpk_eq_i32 s4, 0x700
	s_cbranch_scc1 .Lpk_181_5
	s_add_i32 m0, s101, 0xc000
	v_lshl_add_u64 v[136:137], v[136:137], 0, s[98:99]
	global_load_lds_dwordx4 v[136:137], off
.Lpk_181_5:
	v_mfma_f32_16x16x32_bf16 v[48:51], v[196:199], v[240:243], v[48:51]
	v_mfma_f32_16x16x32_bf16 v[24:27], v[196:199], v[244:247], v[24:27]
	v_mfma_f32_16x16x32_bf16 v[0:3], v[196:199], v[248:251], v[0:3]
	v_mfma_f32_16x16x32_bf16 v[8:11], v[196:199], v[252:255], v[8:11]
	ds_read_b128 v[196:199], v161 offset:38912
	s_cmpk_eq_i32 s4, 0x700
	s_cbranch_scc1 .Lpk_181_6
	s_add_i32 m0, s101, 0x6000
	v_lshl_add_u64 v[142:143], v[142:143], 0, s[98:99]
	global_load_lds_dwordx4 v[142:143], off
.Lpk_181_6:
	s_cmpk_eq_i32 s4, 0x700
	s_cbranch_scc1 .Lpk_181_7
	s_add_i32 m0, s101, 0xe000
	v_lshl_add_u64 v[130:131], v[130:131], 0, s[98:99]
	global_load_lds_dwordx4 v[130:131], off
.Lpk_181_7:
	s_add_i32 s6, s6, 0x10000
	s_add_u32 s4, s4, 0x80
	s_addc_u32 s5, s5, 0
	s_cmpk_lg_i32 s4, 0x780
	s_cbranch_scc1 .LBB0_181
	s_waitcnt lgkmcnt(0)
	s_add_i32 s4, 0, 0x10000
	v_add3_u32 v130, s4, v154, v160
	v_add3_u32 v131, s4, v154, v159
	v_add3_u32 v212, s4, v154, v158
	v_add3_u32 v213, s4, v154, v157
	v_add3_u32 v214, s4, v154, v156
	v_add3_u32 v215, s4, v154, v155
	v_add3_u32 v134, s4, v154, v134
	v_add3_u32 v216, s4, v151, v153
	v_add3_u32 v217, s52, v151, v152
	ds_read_b128 v[136:139], v130
	ds_read_b128 v[140:143], v131
	ds_read_b128 v[144:147], v212
	ds_read_b128 v[158:161], v213
	ds_read_b128 v[168:171], v214
	ds_read_b128 v[172:175], v215
	ds_read_b128 v[154:157], v134
	ds_read_b128 v[176:179], v216
	ds_read_b128 v[148:151], v217
	s_waitcnt lgkmcnt(0)
	v_mfma_f32_16x16x32_bf16 v[16:19], v[148:151], v[140:143], v[16:19]
	v_mfma_f32_16x16x32_bf16 v[180:183], v[148:151], v[136:139], v[36:39]
	s_nop 2
	ds_read_b128 v[36:39], v217 offset:2048
	s_waitcnt lgkmcnt(0)
	v_mfma_f32_16x16x32_bf16 v[12:15], v[36:39], v[140:143], v[12:15]
	v_mfma_f32_16x16x32_bf16 v[184:187], v[36:39], v[136:139], v[28:31]
	s_nop 2
	ds_read_b128 v[28:31], v217 offset:4096
	s_waitcnt lgkmcnt(0)
	v_mfma_f32_16x16x32_bf16 v[4:7], v[28:31], v[140:143], v[4:7]
	v_mfma_f32_16x16x32_bf16 v[92:95], v[148:151], v[172:175], v[92:95]
	v_mfma_f32_16x16x32_bf16 v[76:79], v[148:151], v[168:171], v[76:79]
	v_mfma_f32_16x16x32_bf16 v[60:63], v[148:151], v[158:161], v[60:63]
	v_mfma_f32_16x16x32_bf16 v[204:207], v[36:39], v[172:175], v[88:91]
	v_mfma_f32_16x16x32_bf16 v[208:211], v[36:39], v[168:171], v[72:75]
	v_mfma_f32_16x16x32_bf16 v[72:75], v[148:151], v[176:179], v[124:127]
	v_mfma_f32_16x16x32_bf16 v[188:191], v[28:31], v[136:139], v[20:23]
	v_mfma_f32_16x16x32_bf16 v[84:87], v[28:31], v[172:175], v[84:87]
	v_mfma_f32_16x16x32_bf16 v[68:71], v[28:31], v[168:171], v[68:71]
	v_mfma_f32_16x16x32_bf16 v[88:91], v[148:151], v[154:157], v[108:111]
	ds_read_b128 v[20:23], v217 offset:6144
	s_waitcnt lgkmcnt(0)
	v_mfma_f32_16x16x32_bf16 v[136:139], v[20:23], v[136:139], v[8:11]
	v_mfma_f32_16x16x32_bf16 v[8:11], v[20:23], v[176:179], v[112:115]
	v_mfma_f32_16x16x32_bf16 v[192:195], v[20:23], v[154:157], v[96:99]
	v_mfma_f32_16x16x32_bf16 v[196:199], v[20:23], v[172:175], v[80:83]
	v_mfma_f32_16x16x32_bf16 v[200:203], v[20:23], v[168:171], v[64:67]
	v_mfma_f32_16x16x32_bf16 v[64:67], v[28:31], v[176:179], v[116:119]
	v_mfma_f32_16x16x32_bf16 v[80:83], v[28:31], v[154:157], v[100:103]
	v_mfma_f32_16x16x32_bf16 v[96:99], v[36:39], v[176:179], v[120:123]
	v_mfma_f32_16x16x32_bf16 v[100:103], v[36:39], v[154:157], v[104:107]
	v_mfma_f32_16x16x32_bf16 v[152:155], v[36:39], v[158:161], v[56:59]
	v_mfma_f32_16x16x32_bf16 v[52:55], v[28:31], v[158:161], v[52:55]
	v_mfma_f32_16x16x32_bf16 v[156:159], v[20:23], v[158:161], v[48:51]
	v_mfma_f32_16x16x32_bf16 v[44:47], v[148:151], v[144:147], v[44:47]
	v_mfma_f32_16x16x32_bf16 v[160:163], v[36:39], v[144:147], v[40:43]
	v_mfma_f32_16x16x32_bf16 v[168:171], v[28:31], v[144:147], v[32:35]
	v_mfma_f32_16x16x32_bf16 v[24:27], v[20:23], v[144:147], v[24:27]
	v_mfma_f32_16x16x32_bf16 v[0:3], v[20:23], v[140:143], v[0:3]
	ds_read_b128 v[140:143], v217 offset:1024
	ds_read_b128 v[144:147], v217 offset:3072
	ds_read_b128 v[148:151], v217 offset:5120
	ds_read_b128 v[172:175], v217 offset:7168
	ds_read_b128 v[20:23], v216 offset:1024
	ds_read_b128 v[28:31], v134 offset:1024
	ds_read_b128 v[32:35], v215 offset:1024
	ds_read_b128 v[36:39], v214 offset:1024
	s_waitcnt lgkmcnt(3)
	v_mfma_f32_16x16x32_bf16 v[108:111], v[140:143], v[20:23], v[72:75]
	v_mfma_f32_16x16x32_bf16 v[104:107], v[144:147], v[20:23], v[96:99]
	v_mfma_f32_16x16x32_bf16 v[116:119], v[148:151], v[20:23], v[64:67]
	v_mfma_f32_16x16x32_bf16 v[112:115], v[172:175], v[20:23], v[8:11]
	s_nop 2
	ds_read_b128 v[8:11], v213 offset:1024
	s_waitcnt lgkmcnt(3)
	v_mfma_f32_16x16x32_bf16 v[120:123], v[140:143], v[28:31], v[88:91]
	v_mfma_f32_16x16x32_bf16 v[96:99], v[144:147], v[28:31], v[100:103]
	v_mfma_f32_16x16x32_bf16 v[124:127], v[148:151], v[28:31], v[80:83]
	v_mfma_f32_16x16x32_bf16 v[100:103], v[172:175], v[28:31], v[192:195]
	ds_read_b128 v[20:23], v212 offset:1024
	s_waitcnt lgkmcnt(3)
	v_mfma_f32_16x16x32_bf16 v[88:91], v[140:143], v[32:35], v[92:95]
	v_mfma_f32_16x16x32_bf16 v[80:83], v[144:147], v[32:35], v[204:207]
	v_mfma_f32_16x16x32_bf16 v[92:95], v[148:151], v[32:35], v[84:87]
	v_mfma_f32_16x16x32_bf16 v[84:87], v[172:175], v[32:35], v[196:199]
	ds_read_b128 v[176:179], v131 offset:1024
	s_waitcnt lgkmcnt(3)
	v_mfma_f32_16x16x32_bf16 v[72:75], v[140:143], v[36:39], v[76:79]
	v_mfma_f32_16x16x32_bf16 v[64:67], v[144:147], v[36:39], v[208:211]
	v_mfma_f32_16x16x32_bf16 v[76:79], v[148:151], v[36:39], v[68:71]
	v_mfma_f32_16x16x32_bf16 v[68:71], v[172:175], v[36:39], v[200:203]
	ds_read_b128 v[192:195], v130 offset:1024
	s_waitcnt lgkmcnt(3)
	v_mfma_f32_16x16x32_bf16 v[56:59], v[140:143], v[8:11], v[60:63]
	v_mfma_f32_16x16x32_bf16 v[48:51], v[144:147], v[8:11], v[152:155]
	v_mfma_f32_16x16x32_bf16 v[60:63], v[148:151], v[8:11], v[52:55]
	v_mfma_f32_16x16x32_bf16 v[52:55], v[172:175], v[8:11], v[156:159]
	s_waitcnt lgkmcnt(2)
	v_mfma_f32_16x16x32_bf16 v[40:43], v[140:143], v[20:23], v[44:47]
	v_mfma_f32_16x16x32_bf16 v[32:35], v[144:147], v[20:23], v[160:163]
	v_mfma_f32_16x16x32_bf16 v[44:47], v[148:151], v[20:23], v[168:171]
	v_mfma_f32_16x16x32_bf16 v[36:39], v[172:175], v[20:23], v[24:27]
	s_waitcnt lgkmcnt(1)
	v_mfma_f32_16x16x32_bf16 v[24:27], v[140:143], v[176:179], v[16:19]
	v_mfma_f32_16x16x32_bf16 v[16:19], v[144:147], v[176:179], v[12:15]
	v_mfma_f32_16x16x32_bf16 v[28:31], v[148:151], v[176:179], v[4:7]
	v_mfma_f32_16x16x32_bf16 v[20:23], v[172:175], v[176:179], v[0:3]
	s_waitcnt lgkmcnt(0)
	v_mfma_f32_16x16x32_bf16 v[8:11], v[140:143], v[192:195], v[180:183]
	v_mfma_f32_16x16x32_bf16 v[0:3], v[144:147], v[192:195], v[184:187]
	v_mfma_f32_16x16x32_bf16 v[12:15], v[148:151], v[192:195], v[188:191]
	v_mfma_f32_16x16x32_bf16 v[4:7], v[172:175], v[192:195], v[136:139]
	v_mov_b32_e32 v147, v132
	s_waitcnt vmcnt(0)
	s_barrier
	s_lshl_b32 s26, s26, 8
	v_and_b32_e32 v146, 15, v147
	v_ashrrev_i32_e32 v130, 1, v147
	v_bfe_u32 v148, v147, 4, 2
	v_and_b32_e32 v149, 0xffffff80, v130
	v_or_b32_e32 v130, s66, v146
	v_add_u32_e32 v150, v130, v149
	v_and_b32_e32 v130, 64, v147
	v_lshlrev_b32_e32 v134, 5, v148
	v_lshl_add_u64 v[128:129], v[128:129], 0, v[134:135]
	v_lshrrev_b32_e32 v151, 6, v150
	v_cmp_eq_u32_e32 vcc, 0, v130
	v_lshl_add_u64 v[136:137], v[128:129], 0, s[14:15]
	v_or_b32_e32 v130, 48, v146
	v_cndmask_b32_e32 v128, v146, v151, vcc
	v_lshlrev_b32_e32 v128, 8, v128
	v_and_b32_e32 v134, 0x3f00, v128
	v_lshl_add_u64 v[128:129], v[136:137], 0, v[134:135]
	flat_load_dwordx4 v[138:141], v[128:129]
	flat_load_dwordx4 v[142:145], v[128:129] offset:16
	flat_load_dwordx4 v[152:155], v[128:129] offset:128
	flat_load_dwordx4 v[156:159], v[128:129] offset:144
	v_or_b32_e32 v128, 16, v146
	v_cndmask_b32_e32 v128, v128, v151, vcc
	v_lshlrev_b32_e32 v128, 8, v128
	v_and_b32_e32 v134, 0x3f00, v128
	v_lshl_add_u64 v[128:129], v[136:137], 0, v[134:135]
	flat_load_dwordx4 v[160:163], v[128:129]
	flat_load_dwordx4 v[168:171], v[128:129] offset:16
	flat_load_dwordx4 v[172:175], v[128:129] offset:128
	flat_load_dwordx4 v[176:179], v[128:129] offset:144
	v_or_b32_e32 v128, 32, v146
	v_cndmask_b32_e32 v128, v128, v151, vcc
	v_lshlrev_b32_e32 v128, 8, v128
	v_and_b32_e32 v134, 0x3f00, v128
	v_lshl_add_u64 v[128:129], v[136:137], 0, v[134:135]
	flat_load_dwordx4 v[180:183], v[128:129]
	flat_load_dwordx4 v[184:187], v[128:129] offset:16
	flat_load_dwordx4 v[188:191], v[128:129] offset:128
	flat_load_dwordx4 v[192:195], v[128:129] offset:144
	v_cndmask_b32_e32 v130, v130, v151, vcc
	v_lshlrev_b32_e32 v130, 8, v130
	v_and_b32_e32 v134, 0x3f00, v130
	v_lshl_add_u64 v[204:205], v[136:137], 0, v[134:135]
	flat_load_dwordx4 v[196:199], v[204:205]
	flat_load_dwordx4 v[200:203], v[204:205] offset:16
	flat_load_dwordx4 v[128:131], v[204:205] offset:128
	v_or_b32_e32 v134, 1, v151
	v_cndmask_b32_e32 v134, v146, v134, vcc
	v_lshlrev_b32_e32 v134, 8, v134
	v_and_b32_e32 v134, 0x3f00, v134
	s_ashr_i32 s27, s26, 31
	s_waitcnt vmcnt(0) lgkmcnt(0)
	v_mov_b32_e32 v206, v139
	v_mov_b32_e32 v207, v141
	v_mov_b32_e32 v139, v140
	v_mov_b32_e32 v140, v143
	v_mov_b32_e32 v141, v145
	v_mov_b32_e32 v143, v144
	v_mov_b32_e32 v144, v153
	v_mov_b32_e32 v145, v155
	v_mov_b32_e32 v153, v154
	v_mov_b32_e32 v154, v157
	v_mov_b32_e32 v155, v159
	v_mov_b32_e32 v157, v158
	v_pk_mul_f32 v[158:159], v[108:109], v[206:207]
	v_pk_mul_f32 v[206:207], v[116:117], v[206:207]
	v_pk_mul_f32 v[208:209], v[110:111], v[140:141]
	v_pk_mul_f32 v[210:211], v[118:119], v[140:141]
	v_pk_mul_f32 v[214:215], v[112:113], v[144:145]
	v_pk_mul_f32 v[216:217], v[106:107], v[154:155]
	v_pk_mul_f32 v[154:155], v[114:115], v[154:155]
	v_mov_b32_e32 v218, v161
	v_mov_b32_e32 v219, v163
	v_mov_b32_e32 v161, v162
	v_mov_b32_e32 v162, v169
	v_mov_b32_e32 v163, v171
	v_pk_mul_f32 v[212:213], v[104:105], v[144:145]
	v_mov_b32_e32 v169, v170
	v_pk_fma_f32 v[116:117], v[116:117], v[138:139], v[158:159]
	v_pk_fma_f32 v[140:141], v[108:109], v[138:139], v[206:207] neg_lo:[0,0,1] neg_hi:[0,0,1]
	v_pk_fma_f32 v[118:119], v[118:119], v[142:143], v[208:209]
	v_pk_fma_f32 v[144:145], v[110:111], v[142:143], v[210:211] neg_lo:[0,0,1] neg_hi:[0,0,1]
	v_pk_fma_f32 v[138:139], v[104:105], v[152:153], v[214:215] neg_lo:[0,0,1] neg_hi:[0,0,1]
	v_pk_fma_f32 v[142:143], v[106:107], v[156:157], v[154:155] neg_lo:[0,0,1] neg_hi:[0,0,1]
	v_pk_mul_f32 v[104:105], v[120:121], v[218:219]
	v_pk_mul_f32 v[106:107], v[124:125], v[218:219]
	v_pk_mul_f32 v[108:109], v[122:123], v[162:163]
	v_pk_fma_f32 v[110:111], v[112:113], v[152:153], v[212:213]
	v_pk_fma_f32 v[112:113], v[114:115], v[156:157], v[216:217]
	v_pk_mul_f32 v[152:153], v[126:127], v[162:163]
	v_pk_fma_f32 v[104:105], v[124:125], v[160:161], v[104:105]
	v_pk_fma_f32 v[114:115], v[120:121], v[160:161], v[106:107] neg_lo:[0,0,1] neg_hi:[0,0,1]
	v_pk_fma_f32 v[106:107], v[126:127], v[168:169], v[108:109]
	flat_load_dwordx4 v[124:127], v[204:205] offset:144
	v_pk_fma_f32 v[120:121], v[122:123], v[168:169], v[152:153] neg_lo:[0,0,1] neg_hi:[0,0,1]
	v_lshl_add_u64 v[168:169], v[136:137], 0, v[134:135]
	flat_load_dwordx4 v[152:155], v[168:169]
	flat_load_dwordx4 v[156:159], v[168:169] offset:16
	v_mov_b32_e32 v122, v173
	v_mov_b32_e32 v123, v175
	v_pk_mul_f32 v[108:109], v[96:97], v[122:123]
	v_mov_b32_e32 v173, v174
	v_pk_fma_f32 v[108:109], v[100:101], v[172:173], v[108:109]
	v_pk_mul_f32 v[100:101], v[100:101], v[122:123]
	v_mov_b32_e32 v122, v177
	v_mov_b32_e32 v123, v179
	v_pk_fma_f32 v[96:97], v[96:97], v[172:173], v[100:101] neg_lo:[0,0,1] neg_hi:[0,0,1]
	v_pk_mul_f32 v[100:101], v[98:99], v[122:123]
	v_mov_b32_e32 v177, v178
	v_pk_fma_f32 v[100:101], v[102:103], v[176:177], v[100:101]
	v_pk_mul_f32 v[102:103], v[102:103], v[122:123]
	v_mov_b32_e32 v122, v181
	v_mov_b32_e32 v123, v183
	v_pk_fma_f32 v[102:103], v[98:99], v[176:177], v[102:103] neg_lo:[0,0,1] neg_hi:[0,0,1]
	v_pk_mul_f32 v[98:99], v[88:89], v[122:123]
	v_mov_b32_e32 v181, v182
	v_pk_fma_f32 v[98:99], v[92:93], v[180:181], v[98:99]
	v_pk_mul_f32 v[92:93], v[92:93], v[122:123]
	v_mov_b32_e32 v122, v185
	v_mov_b32_e32 v123, v187
	v_pk_fma_f32 v[92:93], v[88:89], v[180:181], v[92:93] neg_lo:[0,0,1] neg_hi:[0,0,1]
	v_pk_mul_f32 v[88:89], v[90:91], v[122:123]
	v_mov_b32_e32 v185, v186
	v_pk_fma_f32 v[88:89], v[94:95], v[184:185], v[88:89]
	v_pk_mul_f32 v[94:95], v[94:95], v[122:123]
	v_mov_b32_e32 v122, v189
	v_mov_b32_e32 v123, v191
	v_pk_fma_f32 v[94:95], v[90:91], v[184:185], v[94:95] neg_lo:[0,0,1] neg_hi:[0,0,1]
	v_pk_mul_f32 v[90:91], v[80:81], v[122:123]
	v_mov_b32_e32 v189, v190
	v_pk_fma_f32 v[90:91], v[84:85], v[188:189], v[90:91]
	v_pk_mul_f32 v[84:85], v[84:85], v[122:123]
	v_mov_b32_e32 v122, v193
	v_mov_b32_e32 v123, v195
	v_pk_fma_f32 v[84:85], v[80:81], v[188:189], v[84:85] neg_lo:[0,0,1] neg_hi:[0,0,1]
	v_pk_mul_f32 v[80:81], v[82:83], v[122:123]
	v_mov_b32_e32 v193, v194
	v_pk_fma_f32 v[80:81], v[86:87], v[192:193], v[80:81]
	v_pk_mul_f32 v[86:87], v[86:87], v[122:123]
	v_or_b32_e32 v122, 0x50, v150
	flat_load_dwordx4 v[160:163], v[168:169] offset:128
	v_lshrrev_b32_e32 v123, 6, v122
	v_cndmask_b32_e32 v122, v122, v123, vcc
	v_lshlrev_b32_e32 v122, 8, v122
	flat_load_dwordx4 v[168:171], v[168:169] offset:144
	v_and_b32_e32 v134, 0x3f00, v122
	v_lshl_add_u64 v[122:123], v[136:137], 0, v[134:135]
	v_mov_b32_e32 v180, v197
	v_mov_b32_e32 v181, v199
	flat_load_dwordx4 v[172:175], v[122:123]
	v_pk_fma_f32 v[86:87], v[82:83], v[192:193], v[86:87] neg_lo:[0,0,1] neg_hi:[0,0,1]
	v_pk_mul_f32 v[82:83], v[72:73], v[180:181]
	v_mov_b32_e32 v197, v198
	v_pk_fma_f32 v[82:83], v[76:77], v[196:197], v[82:83]
	v_pk_mul_f32 v[76:77], v[76:77], v[180:181]
	v_mov_b32_e32 v184, v201
	v_mov_b32_e32 v185, v203
	flat_load_dwordx4 v[176:179], v[122:123] offset:16
	v_pk_fma_f32 v[72:73], v[72:73], v[196:197], v[76:77] neg_lo:[0,0,1] neg_hi:[0,0,1]
	v_pk_mul_f32 v[76:77], v[74:75], v[184:185]
	v_mov_b32_e32 v201, v202
	flat_load_dwordx4 v[180:183], v[122:123] offset:128
	v_pk_fma_f32 v[76:77], v[78:79], v[200:201], v[76:77]
	v_pk_mul_f32 v[78:79], v[78:79], v[184:185]
	flat_load_dwordx4 v[184:187], v[122:123] offset:144
	v_or_b32_e32 v122, 0x60, v150
	v_lshrrev_b32_e32 v123, 6, v122
	v_cndmask_b32_e32 v122, v122, v123, vcc
	v_lshlrev_b32_e32 v122, 8, v122
	v_and_b32_e32 v134, 0x3f00, v122
	v_mov_b32_e32 v192, v129
	v_mov_b32_e32 v193, v131
	v_lshl_add_u64 v[194:195], v[136:137], 0, v[134:135]
	v_pk_fma_f32 v[74:75], v[74:75], v[200:201], v[78:79] neg_lo:[0,0,1] neg_hi:[0,0,1]
	v_pk_mul_f32 v[78:79], v[64:65], v[192:193]
	flat_load_dwordx4 v[188:191], v[194:195]
	v_mov_b32_e32 v129, v130
	v_pk_fma_f32 v[78:79], v[68:69], v[128:129], v[78:79]
	v_pk_mul_f32 v[68:69], v[68:69], v[192:193]
	v_cvt_pk_bf16_f32 v96, v96, v97
	v_pk_fma_f32 v[68:69], v[64:65], v[128:129], v[68:69] neg_lo:[0,0,1] neg_hi:[0,0,1]
	s_waitcnt vmcnt(0) lgkmcnt(0)
	v_mov_b32_e32 v64, v125
	v_mov_b32_e32 v65, v127
	flat_load_dwordx4 v[128:131], v[194:195] offset:16
	v_pk_mul_f32 v[122:123], v[66:67], v[64:65]
	v_mov_b32_e32 v125, v126
	v_pk_mul_f32 v[64:65], v[70:71], v[64:65]
	v_pk_fma_f32 v[122:123], v[70:71], v[124:125], v[122:123]
	v_pk_fma_f32 v[66:67], v[66:67], v[124:125], v[64:65] neg_lo:[0,0,1] neg_hi:[0,0,1]
	flat_load_dwordx4 v[124:127], v[194:195] offset:128
	v_mov_b32_e32 v70, v153
	v_mov_b32_e32 v71, v155
	v_pk_mul_f32 v[64:65], v[56:57], v[70:71]
	v_mov_b32_e32 v153, v154
	v_pk_fma_f32 v[64:65], v[60:61], v[152:153], v[64:65]
	v_pk_mul_f32 v[60:61], v[60:61], v[70:71]
	v_mov_b32_e32 v70, v157
	v_pk_fma_f32 v[56:57], v[56:57], v[152:153], v[60:61] neg_lo:[0,0,1] neg_hi:[0,0,1]
	v_or_b32_e32 v60, 0x70, v150
	v_lshrrev_b32_e32 v61, 6, v60
	v_cndmask_b32_e32 v60, v60, v61, vcc
	v_lshlrev_b32_e32 v60, 8, v60
	flat_load_dwordx4 v[152:155], v[194:195] offset:144
	v_and_b32_e32 v134, 0x3f00, v60
	v_lshl_add_u64 v[136:137], v[136:137], 0, v[134:135]
	flat_load_dwordx4 v[192:195], v[136:137]
	v_mov_b32_e32 v71, v159
	v_pk_mul_f32 v[60:61], v[58:59], v[70:71]
	v_mov_b32_e32 v157, v158
	flat_load_dwordx4 v[196:199], v[136:137] offset:16
	v_pk_fma_f32 v[60:61], v[62:63], v[156:157], v[60:61]
	v_pk_mul_f32 v[62:63], v[62:63], v[70:71]
	v_cvt_pk_bf16_f32 v97, v102, v103
	v_pk_fma_f32 v[62:63], v[58:59], v[156:157], v[62:63] neg_lo:[0,0,1] neg_hi:[0,0,1]
	flat_load_dwordx4 v[156:159], v[136:137] offset:128
	v_cvt_pk_bf16_f32 v84, v84, v85
	v_cvt_pk_bf16_f32 v85, v86, v87
	v_cvt_pk_bf16_f32 v110, v110, v111
	v_cvt_pk_bf16_f32 v111, v112, v113
	v_cvt_pk_bf16_f32 v68, v68, v69
	v_mov_b32_e32 v70, v161
	v_mov_b32_e32 v71, v163
	v_pk_mul_f32 v[58:59], v[48:49], v[70:71]
	v_mov_b32_e32 v161, v162
	v_pk_fma_f32 v[58:59], v[52:53], v[160:161], v[58:59]
	v_pk_mul_f32 v[52:53], v[52:53], v[70:71]
	v_cvt_pk_bf16_f32 v69, v66, v67
	v_pk_fma_f32 v[70:71], v[48:49], v[160:161], v[52:53] neg_lo:[0,0,1] neg_hi:[0,0,1]
	v_mov_b32_e32 v48, v169
	v_mov_b32_e32 v49, v171
	v_pk_mul_f32 v[52:53], v[50:51], v[48:49]
	v_mov_b32_e32 v169, v170
	v_pk_fma_f32 v[52:53], v[54:55], v[168:169], v[52:53]
	v_pk_mul_f32 v[48:49], v[54:55], v[48:49]
	v_mov_b32_e32 v54, v173
	v_mov_b32_e32 v55, v175
	v_pk_fma_f32 v[50:51], v[50:51], v[168:169], v[48:49] neg_lo:[0,0,1] neg_hi:[0,0,1]
	v_pk_mul_f32 v[48:49], v[40:41], v[54:55]
	v_mov_b32_e32 v173, v174
	v_pk_fma_f32 v[48:49], v[44:45], v[172:173], v[48:49]
	v_pk_mul_f32 v[44:45], v[44:45], v[54:55]
	v_mov_b32_e32 v54, v177
	v_mov_b32_e32 v55, v179
	v_pk_fma_f32 v[44:45], v[40:41], v[172:173], v[44:45] neg_lo:[0,0,1] neg_hi:[0,0,1]
	v_pk_mul_f32 v[40:41], v[42:43], v[54:55]
	v_mov_b32_e32 v177, v178
	v_pk_fma_f32 v[40:41], v[46:47], v[176:177], v[40:41]
	v_pk_mul_f32 v[46:47], v[46:47], v[54:55]
	v_mov_b32_e32 v54, v181
	v_mov_b32_e32 v55, v183
	v_pk_fma_f32 v[46:47], v[42:43], v[176:177], v[46:47] neg_lo:[0,0,1] neg_hi:[0,0,1]
	v_pk_mul_f32 v[42:43], v[32:33], v[54:55]
	v_mov_b32_e32 v181, v182
	v_pk_fma_f32 v[42:43], v[36:37], v[180:181], v[42:43]
	v_pk_mul_f32 v[36:37], v[36:37], v[54:55]
	v_cvt_pk_bf16_f32 v66, v82, v83
	v_pk_fma_f32 v[54:55], v[32:33], v[180:181], v[36:37] neg_lo:[0,0,1] neg_hi:[0,0,1]
	v_mov_b32_e32 v32, v185
	v_mov_b32_e32 v33, v187
	v_pk_mul_f32 v[36:37], v[34:35], v[32:33]
	v_mov_b32_e32 v185, v186
	v_pk_fma_f32 v[36:37], v[38:39], v[184:185], v[36:37]
	v_pk_mul_f32 v[32:33], v[38:39], v[32:33]
	v_mov_b32_e32 v38, v189
	v_mov_b32_e32 v39, v191
	v_pk_fma_f32 v[34:35], v[34:35], v[184:185], v[32:33] neg_lo:[0,0,1] neg_hi:[0,0,1]
	v_pk_mul_f32 v[32:33], v[24:25], v[38:39]
	v_mov_b32_e32 v189, v190
	v_pk_fma_f32 v[32:33], v[28:29], v[188:189], v[32:33]
	v_pk_mul_f32 v[28:29], v[28:29], v[38:39]
	s_waitcnt vmcnt(0) lgkmcnt(0)
	v_mov_b32_e32 v38, v129
	v_mov_b32_e32 v39, v131
	v_pk_fma_f32 v[28:29], v[24:25], v[188:189], v[28:29] neg_lo:[0,0,1] neg_hi:[0,0,1]
	v_pk_mul_f32 v[24:25], v[26:27], v[38:39]
	v_mov_b32_e32 v129, v130
	v_pk_fma_f32 v[24:25], v[30:31], v[128:129], v[24:25]
	v_pk_mul_f32 v[30:31], v[30:31], v[38:39]
	v_mov_b32_e32 v38, v125
	v_mov_b32_e32 v39, v127
	v_pk_fma_f32 v[30:31], v[26:27], v[128:129], v[30:31] neg_lo:[0,0,1] neg_hi:[0,0,1]
	v_pk_mul_f32 v[26:27], v[16:17], v[38:39]
	v_mov_b32_e32 v125, v126
	v_pk_fma_f32 v[26:27], v[20:21], v[124:125], v[26:27]
	v_pk_mul_f32 v[20:21], v[20:21], v[38:39]
	v_add_u32_e32 v128, s66, v149
	v_pk_fma_f32 v[38:39], v[16:17], v[124:125], v[20:21] neg_lo:[0,0,1] neg_hi:[0,0,1]
	flat_load_dwordx4 v[124:127], v[136:137] offset:144
	v_mov_b32_e32 v16, v153
	v_mov_b32_e32 v17, v155
	v_pk_mul_f32 v[20:21], v[18:19], v[16:17]
	v_mov_b32_e32 v153, v154
	v_pk_fma_f32 v[20:21], v[22:23], v[152:153], v[20:21]
	v_pk_mul_f32 v[16:17], v[22:23], v[16:17]
	v_mov_b32_e32 v22, v193
	v_mov_b32_e32 v23, v195
	v_pk_fma_f32 v[18:19], v[18:19], v[152:153], v[16:17] neg_lo:[0,0,1] neg_hi:[0,0,1]
	v_pk_mul_f32 v[16:17], v[8:9], v[22:23]
	v_mov_b32_e32 v193, v194
	v_pk_fma_f32 v[16:17], v[12:13], v[192:193], v[16:17]
	v_pk_mul_f32 v[12:13], v[12:13], v[22:23]
	v_mov_b32_e32 v22, v197
	v_mov_b32_e32 v23, v199
	v_pk_fma_f32 v[12:13], v[8:9], v[192:193], v[12:13] neg_lo:[0,0,1] neg_hi:[0,0,1]
	v_pk_mul_f32 v[8:9], v[10:11], v[22:23]
	v_mov_b32_e32 v197, v198
	v_pk_fma_f32 v[8:9], v[14:15], v[196:197], v[8:9]
	v_pk_mul_f32 v[14:15], v[14:15], v[22:23]
	v_mov_b32_e32 v22, v157
	v_mov_b32_e32 v23, v159
	v_pk_fma_f32 v[10:11], v[10:11], v[196:197], v[14:15] neg_lo:[0,0,1] neg_hi:[0,0,1]
	v_pk_mul_f32 v[14:15], v[0:1], v[22:23]
	v_mov_b32_e32 v157, v158
	v_pk_fma_f32 v[14:15], v[4:5], v[156:157], v[14:15]
	v_pk_mul_f32 v[4:5], v[4:5], v[22:23]
	v_mov_b32_e32 v22, s19
	ds_read_b64 v[22:23], v22
	v_ashrrev_i32_e32 v129, 31, v128
	v_lshlrev_b64 v[128:129], 10, v[128:129]
	v_lshrrev_b32_e32 v130, 6, v147
	v_mul_u32_u24_e32 v136, 0x90, v146
	s_waitcnt lgkmcnt(0)
	v_lshl_add_u64 v[22:23], v[22:23], 0, v[128:129]
	v_and_b32_e32 v128, 0xc0, v147
	v_lshl_add_u64 v[22:23], s[26:27], 1, v[22:23]
	v_lshlrev_b32_e32 v134, 1, v128
	v_mul_lo_u32 v128, v130, s55
	v_lshlrev_b32_e32 v130, 4, v147
	v_lshl_add_u64 v[22:23], v[22:23], 0, v[134:135]
	v_add_u32_e32 v128, s4, v128
	v_lshlrev_b32_e32 v129, 3, v148
	v_and_b32_e32 v134, 0x70, v130
	v_bfe_u32 v130, v147, 3, 3
	v_mul_u32_u24_e32 v131, 0x90, v130
	v_add3_u32 v136, v128, v129, v136
	v_add3_u32 v131, v128, v134, v131
	v_cvt_pk_bf16_f32 v128, v140, v141
	v_cvt_pk_bf16_f32 v129, v144, v145
	ds_write_b64 v136, v[96:97] offset:2336
	v_cvt_pk_bf16_f32 v96, v104, v105
	v_cvt_pk_bf16_f32 v97, v106, v107
	ds_write_b64 v136, v[84:85] offset:4640
	v_cvt_pk_bf16_f32 v84, v98, v99
	v_cvt_pk_bf16_f32 v85, v88, v89
	v_cvt_pk_bf16_f32 v67, v76, v77
	ds_write_b64 v136, v[128:129]
	v_cvt_pk_bf16_f32 v128, v138, v139
	v_cvt_pk_bf16_f32 v129, v142, v143
	v_cvt_pk_bf16_f32 v116, v116, v117
	v_cvt_pk_bf16_f32 v117, v118, v119
	ds_write_b64 v136, v[110:111] offset:96
	v_cvt_pk_bf16_f32 v110, v114, v115
	v_cvt_pk_bf16_f32 v111, v120, v121
	ds_write_b64 v136, v[96:97] offset:2368
	v_cvt_pk_bf16_f32 v96, v108, v109
	v_cvt_pk_bf16_f32 v97, v100, v101
	v_cvt_pk_bf16_f32 v92, v92, v93
	v_cvt_pk_bf16_f32 v93, v94, v95
	ds_write_b64 v136, v[84:85] offset:4672
	v_cvt_pk_bf16_f32 v84, v90, v91
	v_cvt_pk_bf16_f32 v85, v80, v81
	v_cvt_pk_bf16_f32 v72, v72, v73
	v_cvt_pk_bf16_f32 v73, v74, v75
	ds_write_b64 v136, v[66:67] offset:6976
	v_cvt_pk_bf16_f32 v66, v78, v79
	v_cvt_pk_bf16_f32 v67, v122, v123
	ds_write_b64 v136, v[128:129] offset:32
	ds_write_b64 v136, v[116:117] offset:64
	ds_write_b64 v136, v[110:111] offset:2304
	ds_write_b64 v136, v[96:97] offset:2400
	ds_write_b64 v136, v[92:93] offset:4608
	ds_write_b64 v136, v[84:85] offset:4704
	ds_write_b64 v136, v[72:73] offset:6912
	ds_write_b64 v136, v[68:69] offset:6944
	ds_write_b64 v136, v[66:67] offset:7008
	ds_read_b128 v[66:69], v131
	v_lshl_add_u64 v[22:23], v[22:23], 0, v[134:135]
	v_lshl_add_u64 v[22:23], v[22:23], 0, s[24:25]
	v_lshlrev_b32_e32 v134, 10, v130
	v_lshl_add_u64 v[72:73], v[22:23], 0, v[134:135]
	s_waitcnt lgkmcnt(0)
	flat_store_dwordx4 v[72:73], v[66:69] nt
	ds_read_b128 v[66:69], v131 offset:1152
	v_pk_fma_f32 v[0:1], v[0:1], v[156:157], v[4:5] neg_lo:[0,0,1] neg_hi:[0,0,1]
	v_or_b32_e32 v4, 0x2000, v134
	v_mov_b32_e32 v5, v135
	v_lshl_add_u64 v[4:5], v[22:23], 0, v[4:5]
	s_waitcnt lgkmcnt(0)
	flat_store_dwordx4 v[4:5], v[66:69] nt
	ds_read_b128 v[66:69], v131 offset:2304
	v_or_b32_e32 v74, 0x4000, v134
	v_mov_b32_e32 v75, v135
	v_lshl_add_u64 v[74:75], v[22:23], 0, v[74:75]
	v_or_b32_e32 v76, 0x8000, v134
	s_waitcnt lgkmcnt(0)
	flat_store_dwordx4 v[74:75], v[66:69] nt
	ds_read_b128 v[66:69], v131 offset:3456
	v_or_b32_e32 v74, 0x6000, v134
	v_mov_b32_e32 v75, v135
	v_lshl_add_u64 v[74:75], v[22:23], 0, v[74:75]
	v_mov_b32_e32 v77, v135
	s_waitcnt lgkmcnt(0)
	flat_store_dwordx4 v[74:75], v[66:69] nt
	ds_read_b128 v[66:69], v131 offset:4608
	v_lshl_add_u64 v[76:77], v[22:23], 0, v[76:77]
	s_waitcnt vmcnt(0)
	v_mov_b32_e32 v4, v125
	v_mov_b32_e32 v5, v127
	v_pk_mul_f32 v[74:75], v[2:3], v[4:5]
	s_waitcnt lgkmcnt(0)
	flat_store_dwordx4 v[76:77], v[66:69] nt
	ds_read_b128 v[66:69], v131 offset:5760
	v_or_b32_e32 v76, 0xa000, v134
	v_mov_b32_e32 v77, v135
	v_lshl_add_u64 v[76:77], v[22:23], 0, v[76:77]
	v_mov_b32_e32 v125, v126
	s_waitcnt lgkmcnt(0)
	flat_store_dwordx4 v[76:77], v[66:69] nt
	ds_read_b128 v[66:69], v131 offset:6912
	v_or_b32_e32 v76, 0xc000, v134
	v_mov_b32_e32 v77, v135
	v_lshl_add_u64 v[76:77], v[22:23], 0, v[76:77]
	v_pk_mul_f32 v[4:5], v[6:7], v[4:5]
	s_waitcnt lgkmcnt(0)
	flat_store_dwordx4 v[76:77], v[66:69] nt
	ds_read_b128 v[66:69], v131 offset:8064
	v_or_b32_e32 v134, 0xe000, v134
	v_pk_fma_f32 v[2:3], v[2:3], v[124:125], v[4:5] neg_lo:[0,0,1] neg_hi:[0,0,1]
	v_lshl_add_u64 v[4:5], v[22:23], 0, v[134:135]
	v_cvt_pk_bf16_f32 v0, v0, v1
	s_waitcnt lgkmcnt(0)
	flat_store_dwordx4 v[4:5], v[66:69] nt
	v_cvt_pk_bf16_f32 v4, v56, v57
	v_cvt_pk_bf16_f32 v5, v62, v63
	ds_write_b64 v136, v[4:5]
	v_cvt_pk_bf16_f32 v4, v70, v71
	v_cvt_pk_bf16_f32 v5, v50, v51
	ds_write_b64 v136, v[4:5] offset:32
	v_cvt_pk_bf16_f32 v4, v64, v65
	v_cvt_pk_bf16_f32 v5, v60, v61
	ds_write_b64 v136, v[4:5] offset:64
	v_cvt_pk_bf16_f32 v4, v58, v59
	v_cvt_pk_bf16_f32 v5, v52, v53
	ds_write_b64 v136, v[4:5] offset:96
	v_cvt_pk_bf16_f32 v4, v44, v45
	v_cvt_pk_bf16_f32 v5, v46, v47
	ds_write_b64 v136, v[4:5] offset:2304
	v_cvt_pk_bf16_f32 v4, v54, v55
	v_cvt_pk_bf16_f32 v5, v34, v35
	ds_write_b64 v136, v[4:5] offset:2336
	v_cvt_pk_bf16_f32 v4, v48, v49
	v_cvt_pk_bf16_f32 v5, v40, v41
	ds_write_b64 v136, v[4:5] offset:2368
	v_cvt_pk_bf16_f32 v4, v42, v43
	v_cvt_pk_bf16_f32 v5, v36, v37
	ds_write_b64 v136, v[4:5] offset:2400
	v_cvt_pk_bf16_f32 v4, v28, v29
	v_cvt_pk_bf16_f32 v5, v30, v31
	ds_write_b64 v136, v[4:5] offset:4608
	v_cvt_pk_bf16_f32 v4, v38, v39
	v_cvt_pk_bf16_f32 v5, v18, v19
	ds_write_b64 v136, v[4:5] offset:4640
	v_cvt_pk_bf16_f32 v4, v32, v33
	v_cvt_pk_bf16_f32 v5, v24, v25
	v_cvt_pk_bf16_f32 v1, v2, v3
	v_pk_fma_f32 v[74:75], v[6:7], v[124:125], v[74:75]
	ds_write_b64 v136, v[4:5] offset:4672
	v_cvt_pk_bf16_f32 v4, v26, v27
	v_cvt_pk_bf16_f32 v5, v20, v21
	ds_write_b64 v136, v[0:1] offset:6944
	v_cvt_pk_bf16_f32 v0, v16, v17
	v_cvt_pk_bf16_f32 v1, v8, v9
	ds_write_b64 v136, v[4:5] offset:4704
	v_cvt_pk_bf16_f32 v4, v12, v13
	v_cvt_pk_bf16_f32 v5, v10, v11
	ds_write_b64 v136, v[0:1] offset:6976
	v_cvt_pk_bf16_f32 v0, v14, v15
	v_cvt_pk_bf16_f32 v1, v74, v75
	ds_write_b64 v136, v[4:5] offset:6912
	ds_write_b64 v136, v[0:1] offset:7008
	ds_read_b128 v[0:3], v131
	v_add_co_u32_e32 v4, vcc, s50, v72
	s_nop 1
	v_addc_co_u32_e32 v5, vcc, 0, v73, vcc
	s_waitcnt lgkmcnt(0)
	flat_store_dwordx4 v[4:5], v[0:3] nt
	ds_read_b128 v[0:3], v131 offset:1152
	v_add_co_u32_e32 v4, vcc, s62, v72
	s_nop 1
	v_addc_co_u32_e32 v5, vcc, 0, v73, vcc
	s_waitcnt lgkmcnt(0)
	flat_store_dwordx4 v[4:5], v[0:3] nt
	ds_read_b128 v[0:3], v131 offset:2304
	v_add_co_u32_e32 v4, vcc, s63, v72
	s_nop 1
	v_addc_co_u32_e32 v5, vcc, 0, v73, vcc
	s_waitcnt lgkmcnt(0)
	flat_store_dwordx4 v[4:5], v[0:3] nt
	ds_read_b128 v[0:3], v131 offset:3456
	v_add_co_u32_e32 v4, vcc, s64, v72
	s_nop 1
	v_addc_co_u32_e32 v5, vcc, 0, v73, vcc
	s_waitcnt lgkmcnt(0)
	flat_store_dwordx4 v[4:5], v[0:3] nt
	ds_read_b128 v[0:3], v131 offset:4608
	v_add_co_u32_e32 v4, vcc, s51, v72
	s_nop 1
	v_addc_co_u32_e32 v5, vcc, 0, v73, vcc
	s_waitcnt lgkmcnt(0)
	flat_store_dwordx4 v[4:5], v[0:3] nt
	ds_read_b128 v[0:3], v131 offset:5760
	v_add_co_u32_e32 v4, vcc, 0x1a000, v72
	s_nop 1
	v_addc_co_u32_e32 v5, vcc, 0, v73, vcc
	s_waitcnt lgkmcnt(0)
	flat_store_dwordx4 v[4:5], v[0:3] nt
	ds_read_b128 v[0:3], v131 offset:6912
	v_add_co_u32_e32 v4, vcc, 0x1c000, v72
	s_nop 1
	v_addc_co_u32_e32 v5, vcc, 0, v73, vcc
	s_waitcnt lgkmcnt(0)
	flat_store_dwordx4 v[4:5], v[0:3] nt
	ds_read_b128 v[0:3], v131 offset:8064
	v_add_co_u32_e32 v4, vcc, 0x1e000, v72
	s_nop 1
	v_addc_co_u32_e32 v5, vcc, 0, v73, vcc
	s_waitcnt lgkmcnt(0)
	flat_store_dwordx4 v[4:5], v[0:3] nt
	s_branch .LBB0_137

.LBB0_323:
	ds_bpermute_b32 v0, v134, v164
	v_lshlrev_b32_e32 v69, 3, v152
	v_lshlrev_b32_e32 v70, 6, v105
	v_and_b32_e32 v69, 0xfffff000, v69
	v_mov_b32_e32 v2, s3
	s_waitcnt lgkmcnt(0)
	v_add_f32_e32 v0, v164, v0
	ds_bpermute_b32 v68, v136, v0
	ds_read_b64 v[2:3], v2
	v_mov_b32_e32 v105, v1
	s_add_i32 s90, s90, 1
	s_cmp_eq_u32 s90, 11
	s_waitcnt lgkmcnt(1)
	v_add_f32_e32 v0, v0, v68
	v_div_scale_f32 v71, s[34:35], v0, v0, 1.0
	v_rcp_f32_e32 v72, v71
	v_or3_b32 v68, v69, v70, v107
	v_div_scale_f32 v69, vcc, 1.0, v0, 1.0
	v_fma_f32 v70, -v71, v72, 1.0
	v_fmac_f32_e32 v72, v70, v72
	v_mul_f32_e32 v70, v69, v72
	v_fma_f32 v73, -v71, v70, v69
	v_fmac_f32_e32 v70, v73, v72
	v_fma_f32 v69, -v71, v70, v69
	v_div_fmas_f32 v69, v69, v72, v70
	v_div_fixup_f32 v70, v69, v0, 1.0
	v_ashrrev_i32_e32 v69, 31, v68
	v_lshlrev_b64 v[68:69], 10, v[68:69]
	s_waitcnt lgkmcnt(0)
	v_lshl_add_u64 v[2:3], v[2:3], 0, v[68:69]
	v_lshlrev_b32_e32 v0, 1, v106
	v_lshl_add_u64 v[2:3], v[2:3], 0, v[0:1]
	v_lshl_add_u64 v[2:3], v[2:3], 0, v[104:105]
	v_lshl_add_u64 v[68:69], v[2:3], 0, s[52:53]
	v_pk_mul_f32 v[64:65], v[64:65], v[70:71] op_sel_hi:[1,0]
	v_pk_mul_f32 v[66:67], v[66:67], v[70:71] op_sel_hi:[1,0]
	v_add_co_u32_e32 v2, vcc, s82, v2
	v_cvt_pk_bf16_f32 v64, v64, v65
	v_cvt_pk_bf16_f32 v65, v66, v67
	v_addc_co_u32_e32 v3, vcc, 0, v3, vcc
	global_store_dwordx2 v[2:3], v[64:65], off
	v_pk_mul_f32 v[2:3], v[60:61], v[70:71] op_sel_hi:[1,0]
	v_pk_mul_f32 v[60:61], v[62:63], v[70:71] op_sel_hi:[1,0]
	v_cvt_pk_bf16_f32 v2, v2, v3
	v_cvt_pk_bf16_f32 v3, v60, v61
	global_store_dwordx2 v[68:69], v[2:3], off offset:32
	v_pk_mul_f32 v[2:3], v[56:57], v[70:71] op_sel_hi:[1,0]
	v_pk_mul_f32 v[56:57], v[58:59], v[70:71] op_sel_hi:[1,0]
	v_cvt_pk_bf16_f32 v2, v2, v3
	v_cvt_pk_bf16_f32 v3, v56, v57
	global_store_dwordx2 v[68:69], v[2:3], off offset:64
	v_pk_mul_f32 v[2:3], v[52:53], v[70:71] op_sel_hi:[1,0]
	v_pk_mul_f32 v[52:53], v[54:55], v[70:71] op_sel_hi:[1,0]
	v_cvt_pk_bf16_f32 v2, v2, v3
	v_cvt_pk_bf16_f32 v3, v52, v53
	global_store_dwordx2 v[68:69], v[2:3], off offset:96
	s_cbranch_scc1 .LBB0_378

.LBB0_335:
	v_lshlrev_b32_e32 v0, 1, v106
	v_lshl_add_u64 v[2:3], v[2:3], 0, v[0:1]
	v_lshlrev_b32_e32 v0, 1, v100
	v_lshl_add_u64 v[2:3], v[2:3], 0, v[0:1]
	v_add_co_u32_e32 v72, vcc, s86, v2
	s_waitcnt lgkmcnt(0)
	v_lshl_add_u64 v[68:69], s[38:39], 1, v[70:71]
	v_addc_co_u32_e32 v73, vcc, 0, v3, vcc
	v_add_co_u32_e32 v76, vcc, s87, v2
	v_lshlrev_b32_e32 v0, 1, v102
	s_nop 0
	v_addc_co_u32_e32 v77, vcc, 0, v3, vcc
	v_lshl_add_u64 v[88:89], v[68:69], 0, v[0:1]
	global_load_dwordx4 v[4:7], v[2:3], off
	v_add_co_u32_e32 v2, vcc, 0x18000, v2
	s_lshl_b32 s38, s56, 1
	s_nop 0
	v_addc_co_u32_e32 v3, vcc, 0, v3, vcc
	global_load_dwordx4 v[8:11], v[72:73], off
	s_nop 0
	global_load_dwordx4 v[12:15], v[76:77], off
	s_nop 0
	global_load_dwordx4 v[16:19], v[2:3], off
	global_load_dwordx4 v[20:23], v[88:89], off
	v_lshl_add_u64 v[2:3], v[88:89], 0, s[38:39]
	v_lshl_add_u64 v[96:97], v[2:3], 0, s[38:39]
	global_load_dwordx4 v[24:27], v[2:3], off
	global_load_dwordx4 v[28:31], v[96:97], off
	v_lshl_add_u64 v[2:3], v[96:97], 0, s[38:39]
	global_load_dwordx4 v[32:35], v[2:3], off
	s_mov_b64 s[56:57], 0
.LBB0_336:
	s_and_b64 vcc, exec, s[56:57]
	s_cbranch_vccz .LBB0_367
	s_andn2_b64 vcc, exec, s[54:55]
	s_cbranch_vccnz .LBB0_339
	v_mov_b32_e32 v0, s3
	ds_read_b64 v[2:3], v0
	v_mov_b32_e32 v123, v1
	v_lshlrev_b32_e32 v0, 1, v100
	v_mov_b32_e32 v125, v1
	s_waitcnt lgkmcnt(0)
	v_lshl_add_u64 v[4:5], v[2:3], 0, v[112:113]
	v_lshl_add_u64 v[6:7], v[2:3], 0, v[114:115]
	v_lshl_add_u64 v[4:5], v[4:5], 0, v[122:123]
	v_lshl_add_u64 v[12:13], v[4:5], 0, v[0:1]
	v_lshl_add_u64 v[4:5], v[6:7], 0, v[124:125]
	v_lshlrev_b32_e32 v6, 1, v102
	v_mov_b32_e32 v7, v1
	v_lshl_add_u64 v[28:29], v[4:5], 0, v[6:7]
	v_add_co_u32_e32 v4, vcc, s74, v12
	v_lshl_add_u64 v[2:3], v[2:3], 0, v[116:117]
	s_nop 0
	v_addc_co_u32_e32 v5, vcc, 0, v13, vcc
	v_add_co_u32_e32 v8, vcc, s75, v12
	v_lshl_add_u64 v[2:3], v[2:3], 0, v[122:123]
	s_nop 0
	v_addc_co_u32_e32 v9, vcc, 0, v13, vcc
	v_add_co_u32_e32 v14, vcc, s76, v12
	v_lshl_add_u64 v[2:3], v[2:3], 0, v[0:1]
	s_nop 0
	v_addc_co_u32_e32 v15, vcc, 0, v13, vcc
	v_add_co_u32_e32 v16, vcc, s77, v12
	global_load_dwordx4 v[4:7], v[4:5], off
	s_nop 0
	global_load_dwordx4 v[8:11], v[8:9], off
	v_addc_co_u32_e32 v17, vcc, 0, v13, vcc
	v_add_co_u32_e32 v20, vcc, s78, v28
	global_load_dwordx4 v[12:15], v[14:15], off
	s_nop 0
	global_load_dwordx4 v[16:19], v[16:17], off
	v_addc_co_u32_e32 v21, vcc, 0, v29, vcc
	v_add_co_u32_e32 v24, vcc, s79, v28
	s_nop 1
	v_addc_co_u32_e32 v25, vcc, 0, v29, vcc
	v_add_co_u32_e32 v30, vcc, s80, v28
	global_load_dwordx4 v[20:23], v[20:21], off
	s_nop 0
	global_load_dwordx4 v[24:27], v[24:25], off
	v_addc_co_u32_e32 v31, vcc, 0, v29, vcc
	v_add_co_u32_e32 v32, vcc, s81, v28
	s_nop 1
	v_addc_co_u32_e32 v33, vcc, 0, v29, vcc
	v_add_co_u32_e32 v44, vcc, 0x6800000, v2
	global_load_dwordx4 v[28:31], v[30:31], off
	s_nop 0
	global_load_dwordx4 v[32:35], v[32:33], off
	v_addc_co_u32_e32 v45, vcc, 0, v3, vcc
	v_add_co_u32_e32 v2, vcc, 0x6808000, v2
	s_nop 1
	v_addc_co_u32_e32 v3, vcc, 0, v3, vcc
	global_load_dwordx4 v[44:47], v[44:45], off
	s_nop 0
	global_load_dwordx4 v[48:51], v[2:3], off

.LBB0_340:
	s_cmp_gt_u32 s91, 3
	s_cselect_b64 vcc, -1, 0
	s_waitcnt lgkmcnt(0)
	v_cndmask_b32_e64 v79, v126, 0, vcc
	v_add_u32_e32 v0, v79, v129
	v_mad_u32_u24 v0, v0, s83, v155
	ds_read_b128 v[68:71], v0 offset:9216
	ds_read_b128 v[72:75], v0 offset:9280
	ds_read_b128 v[80:83], v0 offset:11520
	ds_read_b128 v[84:87], v0 offset:11584
	v_lshl_add_u32 v0, s91, 1, v163
	s_or_b64 s[34:35], vcc, s[36:37]
	s_waitcnt lgkmcnt(3)
	v_mfma_f32_16x16x32_bf16 v[68:71], v[68:71], v[40:43], 0
	v_mul_lo_u32 v2, v0, 31
	s_nor_b64 s[56:57], s[34:35], s[4:5]
	s_waitcnt lgkmcnt(1)
	v_mfma_f32_16x16x32_bf16 v[80:83], v[80:83], v[40:43], 0
	v_mfma_f32_16x16x32_bf16 v[72:75], v[72:75], v[36:39], v[68:71]
	s_waitcnt lgkmcnt(0)
	v_mfma_f32_16x16x32_bf16 v[68:71], v[84:87], v[36:39], v[80:83]
	s_nop 5
	v_cndmask_b32_e32 v76, v151, v72, vcc
	s_and_saveexec_b64 s[34:35], s[56:57]
	s_cbranch_execz .LBB0_342
	v_lshl_add_u32 v0, v2, 2, v140
	ds_read_b32 v0, v0 offset:45056
	s_waitcnt lgkmcnt(0)
	v_add_f32_e32 v76, v72, v0

.LBB0_367:
	s_andn2_b64 vcc, exec, s[34:35]
	s_cbranch_vccnz .LBB0_340

.LBB0_379:
	s_and_b64 vcc, exec, s[0:1]
	s_cbranch_vccz .LBB0_463
	v_bfe_u32 v100, v147, 2, 1
	s_add_i32 s0, 0, 0x24048
	s_add_i32 s1, 0, 0x24050
	v_mov_b32_e32 v0, s1
	v_mov_b32_e32 v1, s0
	v_cmp_eq_u32_e64 s[0:1], 0, v100
	v_bfe_u32 v2, v147, 3, 2
	v_mov_b32_e32 v137, 0
	v_cndmask_b32_e64 v0, v0, v1, s[0:1]
	ds_read_b64 v[0:1], v0
	v_lshlrev_b32_e32 v2, 2, v2
	v_mov_b32_e32 v3, v137
	s_add_i32 s12, 0, 0x240a8
	v_ashrrev_i32_e32 v5, 3, v147
	s_waitcnt lgkmcnt(0)
	v_lshl_add_u64 v[0:1], v[0:1], 0, v[2:3]
	global_load_dword v44, v[0:1], off
	v_and_b32_e32 v1, 4, v147
	v_lshrrev_b32_e32 v0, 3, v147
	v_cmp_ne_u32_e64 s[6:7], 0, v1
	v_mov_b32_e32 v1, s12
	v_bfi_b32 v96, -4, v5, v0
	ds_read_b64 v[0:1], v1
	v_mov_b32_e32 v2, 0x1ce00000
	v_mov_b32_e32 v3, 0x1cc00000
	v_lshlrev_b32_e32 v4, 6, v147
	v_and_b32_e32 v106, 0xc0, v4
	v_cndmask_b32_e64 v136, v2, v3, s[0:1]
	v_lshlrev_b32_e32 v2, 8, v96
	v_lshl_or_b32 v102, v96, 7, v135
	v_or3_b32 v104, v2, v106, v135
	v_ashrrev_i32_e32 v103, 31, v102
	v_ashrrev_i32_e32 v105, 31, v104
	v_lshlrev_b64 v[2:3], 9, v[102:103]
	v_lshlrev_b64 v[4:5], 9, v[104:105]
	s_waitcnt lgkmcnt(0)
	v_lshl_add_u64 v[6:7], v[0:1], 0, v[136:137]
	v_and_b32_e32 v134, 0x78, v158
	s_mov_b64 s[4:5], 0x1d000000
	v_lshlrev_b32_e32 v136, 8, v100
	v_lshl_add_u64 v[0:1], v[0:1], 0, v[4:5]
	v_lshl_add_u64 v[28:29], v[6:7], 0, v[2:3]
	v_lshlrev_b32_e32 v98, 1, v134
	v_mov_b32_e32 v99, v137
	v_lshl_add_u64 v[30:31], v[0:1], 0, s[4:5]
	v_lshl_add_u64 v[0:1], v[28:29], 0, v[136:137]
	s_movk_i32 s9, 0x2000
	v_lshl_add_u64 v[32:33], v[0:1], 0, v[98:99]
	v_add_co_u32_e32 v12, vcc, s9, v32
	s_movk_i32 s10, 0x4000
	s_nop 0
	v_addc_co_u32_e32 v13, vcc, 0, v33, vcc
	v_add_co_u32_e32 v14, vcc, s10, v32
	s_movk_i32 s11, 0x6000
	s_nop 0
	v_addc_co_u32_e32 v15, vcc, 0, v33, vcc
	v_add_co_u32_e32 v34, vcc, s11, v32
	s_mov_b32 s13, 0x8000
	s_nop 0
	v_addc_co_u32_e32 v35, vcc, 0, v33, vcc
	v_add_co_u32_e32 v36, vcc, s13, v32
	s_mov_b32 s14, 0xa000
	s_nop 0
	v_addc_co_u32_e32 v37, vcc, 0, v33, vcc
	v_add_co_u32_e32 v38, vcc, s14, v32
	s_mov_b32 s15, 0xc000
	s_nop 0
	v_addc_co_u32_e32 v39, vcc, 0, v33, vcc
	v_add_co_u32_e32 v42, vcc, s15, v32
	s_mov_b32 s16, 0xe000
	v_lshl_add_u64 v[2:3], v[30:31], 0, v[136:137]
	v_addc_co_u32_e32 v43, vcc, 0, v33, vcc
	v_lshl_add_u64 v[40:41], v[2:3], 0, v[98:99]
	global_load_dwordx4 v[0:3], v[12:13], off
	global_load_dwordx4 v[4:7], v[14:15], off
	global_load_dwordx4 v[8:11], v[34:35], off
	global_load_dwordx4 v[16:19], v[36:37], off
	global_load_dwordx4 v[20:23], v[38:39], off
	global_load_dwordx4 v[24:27], v[42:43], off
	v_add_co_u32_e32 v42, vcc, s16, v32
	s_mov_b32 s8, 0x3fb8aa3b
	s_nop 0
	v_addc_co_u32_e32 v43, vcc, 0, v33, vcc
	v_add_co_u32_e32 v48, vcc, s9, v40
	v_xor_b32_e32 v136, 0x100, v136
	s_nop 0
	v_addc_co_u32_e32 v49, vcc, 0, v41, vcc
	v_lshl_add_u64 v[28:29], v[28:29], 0, v[136:137]
	v_lshl_add_u64 v[76:77], v[28:29], 0, v[98:99]
	v_lshl_add_u64 v[28:29], v[30:31], 0, v[136:137]
	v_lshl_add_u64 v[88:89], v[28:29], 0, v[98:99]
	v_mov_b32_e32 v97, 0x12800000
	s_mov_b32 s4, 0xc2ce8ed0
	s_waitcnt vmcnt(0)
	v_mul_f32_e32 v107, 0x43000000, v44
	v_mul_f32_e32 v108, 0x3fb8aa3b, v107
	v_fma_f32 v12, v107, s8, -v108
	v_fmamk_f32 v110, v107, 0x32a5705f, v12
	global_load_dwordx4 v[12:15], v[32:33], off
	global_load_dwordx4 v[36:39], v[40:41], off
	s_nop 0
	global_load_dwordx4 v[32:35], v[42:43], off
	global_load_dwordx4 v[44:47], v[48:49], off
	v_add_co_u32_e32 v42, vcc, s10, v40
	v_rndne_f32_e32 v109, v108
	s_nop 0
	v_addc_co_u32_e32 v43, vcc, 0, v41, vcc
	v_add_co_u32_e32 v40, vcc, s11, v40
	v_sub_f32_e32 v99, v108, v109
	s_nop 0
	v_addc_co_u32_e32 v41, vcc, 0, v41, vcc
	v_add_co_u32_e32 v48, vcc, s9, v76
	global_load_dwordx4 v[60:63], v[42:43], off
	global_load_dwordx4 v[64:67], v[40:41], off
	v_addc_co_u32_e32 v49, vcc, 0, v77, vcc
	v_add_co_u32_e32 v50, vcc, s10, v76
	v_add_f32_e32 v99, v99, v110
	s_nop 0
	v_addc_co_u32_e32 v51, vcc, 0, v77, vcc
	v_add_co_u32_e32 v52, vcc, s11, v76
	global_load_dwordx4 v[28:31], v[48:49], off
	global_load_dwordx4 v[40:43], v[50:51], off
	v_addc_co_u32_e32 v53, vcc, 0, v77, vcc
	v_add_co_u32_e32 v54, vcc, s13, v76
	v_exp_f32_e32 v99, v99
	s_nop 0
	v_addc_co_u32_e32 v55, vcc, 0, v77, vcc
	global_load_dwordx4 v[48:51], v[52:53], off
	global_load_dwordx4 v[56:59], v[54:55], off
	v_add_co_u32_e32 v52, vcc, s14, v76
	v_cvt_i32_f32_e32 v108, v109
	s_nop 0
	v_addc_co_u32_e32 v53, vcc, 0, v77, vcc
	v_add_co_u32_e32 v54, vcc, s15, v76
	v_mov_b32_e32 v109, 0x10800000
	s_nop 0
	v_addc_co_u32_e32 v55, vcc, 0, v77, vcc
	v_add_co_u32_e32 v90, vcc, s16, v76
	global_load_dwordx4 v[68:71], v[52:53], off
	global_load_dwordx4 v[72:75], v[54:55], off
	v_addc_co_u32_e32 v91, vcc, 0, v77, vcc
	v_add_co_u32_e32 v92, vcc, s9, v88
	global_load_dwordx4 v[52:55], v[76:77], off
	global_load_dwordx4 v[80:83], v[88:89], off
	v_addc_co_u32_e32 v93, vcc, 0, v89, vcc
	global_load_dwordx4 v[76:79], v[90:91], off
	global_load_dwordx4 v[84:87], v[92:93], off
	v_add_co_u32_e32 v90, vcc, s10, v88
	v_cndmask_b32_e64 v138, v97, v109, s[0:1]
	s_nop 0
	v_addc_co_u32_e32 v91, vcc, 0, v89, vcc
	v_add_co_u32_e32 v92, vcc, s11, v88
	v_ldexp_f32 v97, v99, v108
	s_nop 0
	v_addc_co_u32_e32 v93, vcc, 0, v89, vcc
	global_load_dwordx4 v[88:91], v[90:91], off
	s_nop 0
	global_load_dwordx4 v[92:95], v[92:93], off
	v_cmp_ngt_f32_e32 vcc, s4, v107
	s_mov_b32 s4, 0x42b17218
	v_mov_b32_e32 v99, 0x7f800000
	v_cndmask_b32_e32 v97, 0, v97, vcc
	v_cmp_nlt_f32_e32 vcc, s4, v107
	v_and_b32_e32 v165, 48, v101
	v_or_b32_e32 v163, v165, v129
	v_cndmask_b32_e32 v140, v99, v97, vcc
	v_mul_u32_u24_e32 v97, 0x88, v135
	v_lshlrev_b32_e32 v97, 1, v97
	v_add3_u32 v159, v161, v97, v98
	v_or_b32_e32 v98, v106, v163
	s_movk_i32 s4, 0x110
	v_mul_u32_u24_e32 v164, 0x88, v129
	v_ashrrev_i32_e32 v97, 31, v96
	v_lshlrev_b32_e32 v98, 7, v98
	s_mov_b32 s3, 0
	v_mov_b32_e32 v139, v137
	v_mov_b32_e32 v141, v140
	v_mov_b32_e32 v142, v140
	v_mov_b32_e32 v143, v140
	v_mad_u32_u24 v166, v163, s4, v155
	v_lshl_add_u32 v167, v164, 1, v155
	v_lshlrev_b64 v[144:145], 13, v[102:103]
	v_lshlrev_b64 v[146:147], 13, v[104:105]
	v_lshlrev_b64 v[148:149], 22, v[96:97]
	v_lshlrev_b32_e32 v150, 16, v100
	v_mov_b32_e32 v151, v137
	s_mov_b32 s13, 30
	s_add_i32 s14, 0, 0x240a0
	v_lshlrev_b32_e32 v152, 1, v98
	s_mov_b32 s15, 0x20000
	s_mov_b32 s16, 0x40000
	s_mov_b32 s17, 0x60000
	s_mov_b32 s18, 0x80000
	s_mov_b32 s19, 0xa0000
	s_mov_b32 s20, 0xc0000
	s_mov_b32 s21, 0xe0000
	s_mov_b32 s22, 0x14800000
	s_mov_b32 s23, 0
	v_mov_b32_e32 v124, v137
	v_mov_b32_e32 v125, v137
	v_mov_b32_e32 v126, v137
	v_mov_b32_e32 v127, v137
	v_mov_b32_e32 v120, v137
	v_mov_b32_e32 v121, v137
	v_mov_b32_e32 v122, v137
	v_mov_b32_e32 v123, v137
	v_mov_b32_e32 v112, v137
	v_mov_b32_e32 v113, v137
	v_mov_b32_e32 v114, v137
	v_mov_b32_e32 v115, v137
	v_mov_b32_e32 v108, v137
	v_mov_b32_e32 v109, v137
	v_mov_b32_e32 v110, v137
	v_mov_b32_e32 v111, v137
	v_mov_b32_e32 v104, v137
	v_mov_b32_e32 v105, v137
	v_mov_b32_e32 v106, v137
	v_mov_b32_e32 v107, v137
	v_mov_b32_e32 v100, v137
	v_mov_b32_e32 v101, v137
	v_mov_b32_e32 v102, v137
	v_mov_b32_e32 v103, v137
	v_mov_b32_e32 v96, v137
	v_mov_b32_e32 v97, v137
	v_mov_b32_e32 v98, v137
	v_mov_b32_e32 v99, v137
	v_mov_b32_e32 v116, v137
	v_mov_b32_e32 v117, v137
	v_mov_b32_e32 v118, v137
	v_mov_b32_e32 v119, v137
	s_branch .LBB0_382

.LBB0_382:
	s_lshl_b32 s24, s23, 1
	s_cmp_lg_u32 s3, 0
	s_cselect_b64 s[8:9], -1, 0
	s_and_b64 vcc, exec, s[8:9]
	s_waitcnt lgkmcnt(0)
	s_barrier
	s_waitcnt vmcnt(12)
	s_cbranch_vccz .LBB0_404
	s_and_saveexec_b64 s[4:5], s[6:7]
	s_xor_b64 s[4:5], exec, s[4:5]
	s_sub_i32 s10, 33, s24
	s_or_saveexec_b64 s[4:5], s[4:5]
	v_mov_b32_e32 v136, s10
	s_xor_b64 exec, exec, s[4:5]
	s_add_i32 s10, s3, -2
	v_mov_b32_e32 v136, s10
	s_or_b64 exec, exec, s[4:5]
	s_cbranch_execnz .LBB0_389

.LBB0_389:
	v_cndmask_b32_e64 v130, 0, 1, s[8:9]
	v_cmp_ne_u32_e64 s[4:5], 1, v130
	s_andn2_b64 vcc, exec, s[8:9]
	v_lshlrev_b32_e32 v130, 1, v128
	s_cbranch_vccnz .LBB0_391
	v_mov_b32_e32 v131, s14
	ds_read_b64 v[168:169], v131
	v_lshlrev_b64 v[170:171], 17, v[136:137]
	v_mov_b32_e32 v153, v137
	v_mov_b32_e32 v131, v137
	v_cvt_pk_bf16_f32 v172, v124, v125
	s_waitcnt lgkmcnt(0)
	v_lshl_add_u64 v[168:169], v[168:169], 0, v[170:171]
	v_lshl_add_u64 v[168:169], v[168:169], 0, v[148:149]
	v_lshl_add_u64 v[168:169], v[168:169], 0, v[150:151]
	v_lshl_add_u64 v[168:169], v[168:169], 0, v[152:153]
	v_lshl_add_u64 v[168:169], v[168:169], 0, v[130:131]
	v_cvt_pk_bf16_f32 v170, v120, v121
	v_cvt_pk_bf16_f32 v171, v122, v123
	global_store_dwordx2 v[168:169], v[170:171], off offset:32
	v_cvt_pk_bf16_f32 v170, v112, v113
	v_cvt_pk_bf16_f32 v171, v114, v115
	global_store_dwordx2 v[168:169], v[170:171], off offset:64
	v_cvt_pk_bf16_f32 v170, v108, v109
	v_cvt_pk_bf16_f32 v171, v110, v111
	global_store_dwordx2 v[168:169], v[170:171], off offset:96
	v_cvt_pk_bf16_f32 v170, v104, v105
	v_cvt_pk_bf16_f32 v171, v106, v107
	global_store_dwordx2 v[168:169], v[170:171], off offset:128
	v_cvt_pk_bf16_f32 v170, v100, v101
	v_cvt_pk_bf16_f32 v171, v102, v103
	global_store_dwordx2 v[168:169], v[170:171], off offset:160
	v_cvt_pk_bf16_f32 v170, v96, v97
	v_cvt_pk_bf16_f32 v171, v98, v99
	v_cvt_pk_bf16_f32 v173, v126, v127
	global_store_dwordx2 v[168:169], v[170:171], off offset:192
	v_cvt_pk_bf16_f32 v170, v116, v117
	v_cvt_pk_bf16_f32 v171, v118, v119
	global_store_dwordx2 v[168:169], v[172:173], off
	global_store_dwordx2 v[168:169], v[170:171], off offset:224
.LBB0_391:
	s_cmp_lg_u32 s3, 32
	s_cselect_b64 s[10:11], -1, 0
	s_cmp_eq_u32 s3, 32
	ds_write_b128 v159, v[12:15]
	ds_write_b128 v159, v[0:3] offset:4352
	ds_write_b128 v159, v[4:7] offset:8704
	ds_write_b128 v159, v[8:11] offset:13056
	ds_write_b128 v159, v[16:19] offset:17408
	ds_write_b128 v159, v[20:23] offset:21760
	ds_write_b128 v159, v[24:27] offset:26112
	ds_write_b128 v159, v[32:35] offset:30464
	ds_write_b128 v159, v[36:39] offset:34816
	ds_write_b128 v159, v[44:47] offset:39168
	ds_write_b128 v159, v[60:63] offset:43520
	ds_write_b128 v159, v[64:67] offset:47872
	s_cbranch_scc1 .LBB0_393
	v_mov_b32_e32 v0, s12
	ds_read_b64 v[0:1], v0
	s_add_i32 s25, s13, 1
	v_mov_b32_e32 v2, s3
	v_mov_b32_e32 v3, s25
	v_cndmask_b32_e64 v4, v3, v2, s[0:1]
	s_waitcnt lgkmcnt(0)
	v_lshl_add_u64 v[2:3], v[0:1], 0, v[138:139]
	v_lshl_add_u64 v[2:3], v[2:3], 0, v[144:145]
	v_lshlrev_b32_e32 v136, 8, v4
	v_lshl_add_u64 v[2:3], v[2:3], 0, v[136:137]
	v_lshlrev_b32_e32 v4, 1, v134
	v_mov_b32_e32 v5, v137
	v_lshl_add_u64 v[0:1], v[0:1], 0, v[146:147]
	v_lshl_add_u64 v[24:25], v[2:3], 0, v[4:5]
	v_lshl_add_u64 v[0:1], v[0:1], 0, v[136:137]
	v_lshl_add_u64 v[60:61], v[0:1], 0, v[4:5]
	v_add_co_u32_e32 v0, vcc, s15, v24
	s_nop 1
	v_addc_co_u32_e32 v1, vcc, 0, v25, vcc
	v_add_co_u32_e32 v4, vcc, s16, v24
	global_load_dwordx4 v[12:15], v[24:25], off
	s_nop 0
	global_load_dwordx4 v[0:3], v[0:1], off
	v_addc_co_u32_e32 v5, vcc, 0, v25, vcc
	v_add_co_u32_e32 v8, vcc, s17, v24
	s_nop 1
	v_addc_co_u32_e32 v9, vcc, 0, v25, vcc
	v_add_co_u32_e32 v16, vcc, s18, v24
	global_load_dwordx4 v[4:7], v[4:5], off
	s_nop 0
	global_load_dwordx4 v[8:11], v[8:9], off
	v_addc_co_u32_e32 v17, vcc, 0, v25, vcc
	v_add_co_u32_e32 v20, vcc, s19, v24
	s_nop 1
	v_addc_co_u32_e32 v21, vcc, 0, v25, vcc
	v_add_co_u32_e32 v26, vcc, s20, v24
	global_load_dwordx4 v[16:19], v[16:17], off
	s_nop 0
	global_load_dwordx4 v[20:23], v[20:21], off
	v_addc_co_u32_e32 v27, vcc, 0, v25, vcc
	v_add_co_u32_e32 v32, vcc, s21, v24
	s_nop 1
	v_addc_co_u32_e32 v33, vcc, 0, v25, vcc
	v_add_co_u32_e32 v36, vcc, s22, v60
	global_load_dwordx4 v[24:27], v[26:27], off
	s_nop 0
	global_load_dwordx4 v[32:35], v[32:33], off
	v_addc_co_u32_e32 v37, vcc, 0, v61, vcc
	v_add_co_u32_e32 v44, vcc, 0x14820000, v60
	s_nop 1
	v_addc_co_u32_e32 v45, vcc, 0, v61, vcc
	v_add_co_u32_e32 v62, vcc, 0x14840000, v60
	global_load_dwordx4 v[36:39], v[36:37], off
	s_nop 0
	global_load_dwordx4 v[44:47], v[44:45], off
	v_addc_co_u32_e32 v63, vcc, 0, v61, vcc
	v_add_co_u32_e32 v64, vcc, 0x14860000, v60
	s_nop 1
	v_addc_co_u32_e32 v65, vcc, 0, v61, vcc
	global_load_dwordx4 v[60:63], v[62:63], off
	s_nop 0
	global_load_dwordx4 v[64:67], v[64:65], off
.LBB0_393:
	s_waitcnt lgkmcnt(0)
	s_barrier
	ds_read_b128 v[168:171], v167
	ds_read_b128 v[172:175], v166 offset:34816
	ds_read_b128 v[176:179], v167 offset:4352
	v_pk_mul_f32 v[126:127], v[142:143], v[126:127]
	v_pk_mul_f32 v[124:125], v[140:141], v[124:125]
	ds_read_b128 v[180:183], v167 offset:8704
	ds_read_b128 v[184:187], v166 offset:34880
	ds_read_b128 v[188:191], v167 offset:64
	v_pk_mul_f32 v[122:123], v[142:143], v[122:123]
	s_waitcnt lgkmcnt(0)
	v_mfma_f32_16x16x32_bf16 v[124:127], v[168:171], v[172:175], v[124:127]
	ds_read_b128 v[168:171], v167 offset:13056
	ds_read_b128 v[192:195], v167 offset:4416
	v_pk_mul_f32 v[120:121], v[140:141], v[120:121]
	v_pk_mul_f32 v[114:115], v[142:143], v[114:115]
	v_pk_mul_f32 v[112:113], v[140:141], v[112:113]
	v_pk_mul_f32 v[110:111], v[142:143], v[110:111]
	v_pk_mul_f32 v[108:109], v[140:141], v[108:109]
	v_mfma_f32_16x16x32_bf16 v[120:123], v[176:179], v[172:175], v[120:123]
	ds_read_b128 v[176:179], v167 offset:17408
	ds_read_b128 v[196:199], v167 offset:8768
	v_pk_mul_f32 v[106:107], v[142:143], v[106:107]
	v_pk_mul_f32 v[104:105], v[140:141], v[104:105]
	v_mfma_f32_16x16x32_bf16 v[112:115], v[180:183], v[172:175], v[112:115]
	ds_read_b128 v[180:183], v167 offset:21760
	ds_read_b128 v[200:203], v167 offset:13120
	v_pk_mul_f32 v[102:103], v[142:143], v[102:103]
	v_pk_mul_f32 v[100:101], v[140:141], v[100:101]
	s_waitcnt lgkmcnt(0)
	v_mfma_f32_16x16x32_bf16 v[108:111], v[168:171], v[172:175], v[108:111]
	ds_read_b128 v[168:171], v167 offset:26112
	ds_read_b128 v[204:207], v167 offset:17472
	v_pk_mul_f32 v[98:99], v[142:143], v[98:99]
	v_pk_mul_f32 v[96:97], v[140:141], v[96:97]
	v_mfma_f32_16x16x32_bf16 v[104:107], v[176:179], v[172:175], v[104:107]
	ds_read_b128 v[176:179], v167 offset:30464
	ds_read_b128 v[208:211], v167 offset:21824
	v_pk_mul_f32 v[118:119], v[142:143], v[118:119]
	v_pk_mul_f32 v[116:117], v[140:141], v[116:117]
	v_mfma_f32_16x16x32_bf16 v[100:103], v[180:183], v[172:175], v[100:103]
	ds_read_b128 v[180:183], v167 offset:26176
	s_and_b64 vcc, exec, s[8:9]
	s_waitcnt lgkmcnt(0)
	v_mfma_f32_16x16x32_bf16 v[96:99], v[168:171], v[172:175], v[96:99]
	ds_read_b128 v[168:171], v167 offset:30528
	v_mfma_f32_16x16x32_bf16 v[116:119], v[176:179], v[172:175], v[116:119]
	ds_read_b128 v[172:175], v167 offset:128
	v_mfma_f32_16x16x32_bf16 v[124:127], v[188:191], v[184:187], v[124:127]
	v_mfma_f32_16x16x32_bf16 v[96:99], v[180:183], v[184:187], v[96:99]
	s_waitcnt lgkmcnt(0)
	v_mfma_f32_16x16x32_bf16 v[116:119], v[168:171], v[184:187], v[116:119]
	ds_read_b128 v[168:171], v166 offset:34944
	ds_read_b128 v[176:179], v166 offset:35008
	ds_read_b128 v[180:183], v167 offset:192
	v_mfma_f32_16x16x32_bf16 v[120:123], v[192:195], v[184:187], v[120:123]
	v_mfma_f32_16x16x32_bf16 v[112:115], v[196:199], v[184:187], v[112:115]
	v_mfma_f32_16x16x32_bf16 v[108:111], v[200:203], v[184:187], v[108:111]
	v_mfma_f32_16x16x32_bf16 v[104:107], v[204:207], v[184:187], v[104:107]
	v_mfma_f32_16x16x32_bf16 v[100:103], v[208:211], v[184:187], v[100:103]
	s_waitcnt lgkmcnt(0)
	v_mfma_f32_16x16x32_bf16 v[124:127], v[172:175], v[168:171], v[124:127]
	ds_read_b128 v[172:175], v167 offset:4480
	ds_read_b128 v[184:187], v167 offset:4544
	s_waitcnt lgkmcnt(0)
	v_mfma_f32_16x16x32_bf16 v[120:123], v[172:175], v[168:171], v[120:123]
	ds_read_b128 v[172:175], v167 offset:8832
	ds_read_b128 v[188:191], v167 offset:8896
	s_waitcnt lgkmcnt(0)
	v_mfma_f32_16x16x32_bf16 v[112:115], v[172:175], v[168:171], v[112:115]
	ds_read_b128 v[172:175], v167 offset:13184
	ds_read_b128 v[192:195], v167 offset:13248
	s_waitcnt lgkmcnt(0)
	v_mfma_f32_16x16x32_bf16 v[108:111], v[172:175], v[168:171], v[108:111]
	ds_read_b128 v[172:175], v167 offset:17536
	ds_read_b128 v[196:199], v167 offset:17600
	s_waitcnt lgkmcnt(0)
	v_mfma_f32_16x16x32_bf16 v[104:107], v[172:175], v[168:171], v[104:107]
	ds_read_b128 v[172:175], v167 offset:21888
	ds_read_b128 v[200:203], v167 offset:21952
	s_waitcnt lgkmcnt(0)
	v_mfma_f32_16x16x32_bf16 v[100:103], v[172:175], v[168:171], v[100:103]
	ds_read_b128 v[172:175], v167 offset:26240
	ds_read_b128 v[204:207], v167 offset:26304
	s_waitcnt lgkmcnt(0)
	v_mfma_f32_16x16x32_bf16 v[96:99], v[172:175], v[168:171], v[96:99]
	ds_read_b128 v[172:175], v167 offset:30592
	ds_read_b128 v[208:211], v167 offset:30656
	s_waitcnt lgkmcnt(0)
	s_barrier
	s_waitcnt vmcnt(8)
	v_mfma_f32_16x16x32_bf16 v[168:171], v[172:175], v[168:171], v[116:119]
	v_mfma_f32_16x16x32_bf16 v[124:127], v[180:183], v[176:179], v[124:127]
	v_mfma_f32_16x16x32_bf16 v[120:123], v[184:187], v[176:179], v[120:123]
	v_mfma_f32_16x16x32_bf16 v[116:119], v[188:191], v[176:179], v[112:115]
	v_mfma_f32_16x16x32_bf16 v[112:115], v[192:195], v[176:179], v[108:111]
	v_mfma_f32_16x16x32_bf16 v[108:111], v[196:199], v[176:179], v[104:107]
	v_mfma_f32_16x16x32_bf16 v[104:107], v[200:203], v[176:179], v[100:103]
	v_mfma_f32_16x16x32_bf16 v[100:103], v[204:207], v[176:179], v[96:99]
	v_mfma_f32_16x16x32_bf16 v[96:99], v[208:211], v[176:179], v[168:171]
	s_cbranch_vccz .LBB0_405
	s_and_saveexec_b64 s[8:9], s[6:7]
	s_xor_b64 s[8:9], exec, s[8:9]
	s_or_b32 s24, s24, 1
	s_sub_i32 s25, 33, s24
	s_or_saveexec_b64 s[8:9], s[8:9]
	v_mov_b32_e32 v136, s25
	s_xor_b64 exec, exec, s[8:9]
	s_add_i32 s24, s3, -1
	v_mov_b32_e32 v136, s24
	s_or_b64 exec, exec, s[8:9]
	s_add_i32 s8, s3, 1
	s_cbranch_execnz .LBB0_400

.LBB0_400:
	s_and_b64 vcc, exec, s[4:5]
	s_cbranch_vccnz .LBB0_402
	v_mov_b32_e32 v131, s14
	ds_read_b64 v[168:169], v131
	v_lshlrev_b64 v[170:171], 17, v[136:137]
	v_mov_b32_e32 v153, v137
	v_mov_b32_e32 v131, v137
	v_cvt_pk_bf16_f32 v172, v124, v125
	s_waitcnt lgkmcnt(0)
	v_lshl_add_u64 v[168:169], v[168:169], 0, v[170:171]
	v_lshl_add_u64 v[168:169], v[168:169], 0, v[148:149]
	v_lshl_add_u64 v[168:169], v[168:169], 0, v[150:151]
	v_lshl_add_u64 v[168:169], v[168:169], 0, v[152:153]
	v_lshl_add_u64 v[168:169], v[168:169], 0, v[130:131]
	v_cvt_pk_bf16_f32 v170, v120, v121
	v_cvt_pk_bf16_f32 v171, v122, v123
	global_store_dwordx2 v[168:169], v[170:171], off offset:32
	v_cvt_pk_bf16_f32 v170, v116, v117
	v_cvt_pk_bf16_f32 v171, v118, v119
	global_store_dwordx2 v[168:169], v[170:171], off offset:64
	v_cvt_pk_bf16_f32 v170, v112, v113
	v_cvt_pk_bf16_f32 v171, v114, v115
	global_store_dwordx2 v[168:169], v[170:171], off offset:96
	v_cvt_pk_bf16_f32 v170, v108, v109
	v_cvt_pk_bf16_f32 v171, v110, v111
	global_store_dwordx2 v[168:169], v[170:171], off offset:128
	v_cvt_pk_bf16_f32 v170, v104, v105
	v_cvt_pk_bf16_f32 v171, v106, v107
	global_store_dwordx2 v[168:169], v[170:171], off offset:160
	v_cvt_pk_bf16_f32 v170, v100, v101
	v_cvt_pk_bf16_f32 v171, v102, v103
	v_cvt_pk_bf16_f32 v173, v126, v127
	global_store_dwordx2 v[168:169], v[170:171], off offset:192
	v_cvt_pk_bf16_f32 v170, v96, v97
	v_cvt_pk_bf16_f32 v171, v98, v99
	global_store_dwordx2 v[168:169], v[172:173], off
	global_store_dwordx2 v[168:169], v[170:171], off offset:224
.LBB0_402:
	s_andn2_b64 vcc, exec, s[10:11]
	ds_write_b128 v159, v[52:55]
	ds_write_b128 v159, v[28:31] offset:4352
	ds_write_b128 v159, v[40:43] offset:8704
	ds_write_b128 v159, v[48:51] offset:13056
	ds_write_b128 v159, v[56:59] offset:17408
	ds_write_b128 v159, v[68:71] offset:21760
	ds_write_b128 v159, v[72:75] offset:26112
	ds_write_b128 v159, v[76:79] offset:30464
	ds_write_b128 v159, v[80:83] offset:34816
	ds_write_b128 v159, v[84:87] offset:39168
	ds_write_b128 v159, v[88:91] offset:43520
	ds_write_b128 v159, v[92:95] offset:47872
	s_cbranch_vccnz .LBB0_381
	v_mov_b32_e32 v28, s12
	ds_read_b64 v[28:29], v28
	v_mov_b32_e32 v30, s13
	v_mov_b32_e32 v31, s8
	v_cndmask_b32_e64 v30, v30, v31, s[0:1]
	v_lshlrev_b32_e32 v136, 8, v30
	s_waitcnt lgkmcnt(0)
	v_lshl_add_u64 v[30:31], v[28:29], 0, v[138:139]
	v_lshl_add_u64 v[30:31], v[30:31], 0, v[144:145]
	v_lshl_add_u64 v[30:31], v[30:31], 0, v[136:137]
	v_lshlrev_b32_e32 v40, 1, v134
	v_mov_b32_e32 v41, v137
	v_lshl_add_u64 v[28:29], v[28:29], 0, v[146:147]
	v_lshl_add_u64 v[72:73], v[30:31], 0, v[40:41]
	v_lshl_add_u64 v[28:29], v[28:29], 0, v[136:137]
	v_lshl_add_u64 v[88:89], v[28:29], 0, v[40:41]
	v_add_co_u32_e32 v28, vcc, s15, v72
	s_nop 1
	v_addc_co_u32_e32 v29, vcc, 0, v73, vcc
	v_add_co_u32_e32 v40, vcc, s16, v72
	global_load_dwordx4 v[52:55], v[72:73], off
	s_nop 0
	global_load_dwordx4 v[28:31], v[28:29], off
	v_addc_co_u32_e32 v41, vcc, 0, v73, vcc
	v_add_co_u32_e32 v48, vcc, s17, v72
	s_nop 1
	v_addc_co_u32_e32 v49, vcc, 0, v73, vcc
	v_add_co_u32_e32 v56, vcc, s18, v72
	global_load_dwordx4 v[40:43], v[40:41], off
	s_nop 0
	global_load_dwordx4 v[48:51], v[48:49], off
	v_addc_co_u32_e32 v57, vcc, 0, v73, vcc
	v_add_co_u32_e32 v68, vcc, s19, v72
	s_nop 1
	v_addc_co_u32_e32 v69, vcc, 0, v73, vcc
	v_add_co_u32_e32 v74, vcc, s20, v72
	global_load_dwordx4 v[56:59], v[56:57], off
	s_nop 0
	global_load_dwordx4 v[68:71], v[68:69], off
	v_addc_co_u32_e32 v75, vcc, 0, v73, vcc
	v_add_co_u32_e32 v76, vcc, s21, v72
	s_nop 1
	v_addc_co_u32_e32 v77, vcc, 0, v73, vcc
	v_add_co_u32_e32 v80, vcc, s22, v88
	global_load_dwordx4 v[72:75], v[74:75], off
	s_nop 0
	global_load_dwordx4 v[76:79], v[76:77], off
	v_addc_co_u32_e32 v81, vcc, 0, v89, vcc
	v_add_co_u32_e32 v84, vcc, 0x14820000, v88
	s_nop 1
	v_addc_co_u32_e32 v85, vcc, 0, v89, vcc
	v_add_co_u32_e32 v90, vcc, 0x14840000, v88
	global_load_dwordx4 v[80:83], v[80:81], off
	s_nop 0
	global_load_dwordx4 v[84:87], v[84:85], off
	v_addc_co_u32_e32 v91, vcc, 0, v89, vcc
	v_add_co_u32_e32 v92, vcc, 0x14860000, v88
	s_nop 1
	v_addc_co_u32_e32 v93, vcc, 0, v89, vcc
	global_load_dwordx4 v[88:91], v[90:91], off
	s_nop 0
	global_load_dwordx4 v[92:95], v[92:93], off
	s_branch .LBB0_381

.LBB0_407:
	ds_bpermute_b32 v0, v126, v152
	v_lshlrev_b32_e32 v69, 3, v148
	v_lshlrev_b32_e32 v70, 6, v131
	v_and_b32_e32 v69, 0xfffff000, v69
	v_mov_b32_e32 v2, s3
	s_waitcnt lgkmcnt(0)
	v_add_f32_e32 v0, v152, v0
	ds_bpermute_b32 v68, v127, v0
	ds_read_b64 v[2:3], v2
	v_mov_b32_e32 v131, v1
	s_add_i32 s82, s82, 1
	s_cmp_eq_u32 s82, 5
	s_waitcnt lgkmcnt(1)
	v_add_f32_e32 v0, v0, v68
	v_div_scale_f32 v71, s[34:35], v0, v0, 1.0
	v_rcp_f32_e32 v72, v71
	v_or3_b32 v68, v69, v70, v163
	v_div_scale_f32 v69, vcc, 1.0, v0, 1.0
	v_fma_f32 v70, -v71, v72, 1.0
	v_fmac_f32_e32 v72, v70, v72
	v_mul_f32_e32 v70, v69, v72
	v_fma_f32 v73, -v71, v70, v69
	v_fmac_f32_e32 v70, v73, v72
	v_fma_f32 v69, -v71, v70, v69
	v_div_fmas_f32 v69, v69, v72, v70
	v_div_fixup_f32 v70, v69, v0, 1.0
	v_ashrrev_i32_e32 v69, 31, v68
	v_lshlrev_b64 v[68:69], 10, v[68:69]
	s_waitcnt lgkmcnt(0)
	v_lshl_add_u64 v[2:3], v[2:3], 0, v[68:69]
	v_lshlrev_b32_e32 v0, 1, v104
	v_lshl_add_u64 v[2:3], v[2:3], 0, v[0:1]
	v_lshl_add_u64 v[2:3], v[2:3], 0, v[130:131]
	v_lshl_add_u64 v[68:69], v[2:3], 0, s[52:53]
	v_pk_mul_f32 v[64:65], v[64:65], v[70:71] op_sel_hi:[1,0]
	v_pk_mul_f32 v[66:67], v[66:67], v[70:71] op_sel_hi:[1,0]
	v_add_co_u32_e32 v2, vcc, s74, v2
	v_cvt_pk_bf16_f32 v64, v64, v65
	v_cvt_pk_bf16_f32 v65, v66, v67
	v_addc_co_u32_e32 v3, vcc, 0, v3, vcc
	global_store_dwordx2 v[2:3], v[64:65], off
	v_pk_mul_f32 v[2:3], v[60:61], v[70:71] op_sel_hi:[1,0]
	v_pk_mul_f32 v[60:61], v[62:63], v[70:71] op_sel_hi:[1,0]
	v_cvt_pk_bf16_f32 v2, v2, v3
	v_cvt_pk_bf16_f32 v3, v60, v61
	global_store_dwordx2 v[68:69], v[2:3], off offset:32
	v_pk_mul_f32 v[2:3], v[56:57], v[70:71] op_sel_hi:[1,0]
	v_pk_mul_f32 v[56:57], v[58:59], v[70:71] op_sel_hi:[1,0]
	v_cvt_pk_bf16_f32 v2, v2, v3
	v_cvt_pk_bf16_f32 v3, v56, v57
	global_store_dwordx2 v[68:69], v[2:3], off offset:64
	v_pk_mul_f32 v[2:3], v[52:53], v[70:71] op_sel_hi:[1,0]
	v_pk_mul_f32 v[52:53], v[54:55], v[70:71] op_sel_hi:[1,0]
	v_cvt_pk_bf16_f32 v2, v2, v3
	v_cvt_pk_bf16_f32 v3, v52, v53
	global_store_dwordx2 v[68:69], v[2:3], off offset:96
	s_cbranch_scc1 .LBB0_462

.LBB0_419:
	v_lshlrev_b32_e32 v0, 1, v104
	v_lshl_add_u64 v[2:3], v[2:3], 0, v[0:1]
	v_lshlrev_b32_e32 v0, 1, v100
	v_lshl_add_u64 v[2:3], v[2:3], 0, v[0:1]
	v_add_co_u32_e32 v72, vcc, s78, v2
	s_waitcnt lgkmcnt(0)
	v_lshl_add_u64 v[68:69], s[38:39], 1, v[70:71]
	v_addc_co_u32_e32 v73, vcc, 0, v3, vcc
	v_add_co_u32_e32 v76, vcc, s79, v2
	v_mov_b32_e32 v103, v1
	s_nop 0
	v_addc_co_u32_e32 v77, vcc, 0, v3, vcc
	v_lshl_add_u64 v[88:89], v[68:69], 0, v[102:103]
	global_load_dwordx4 v[4:7], v[2:3], off
	v_add_co_u32_e32 v2, vcc, 0x18000, v2
	s_lshl_b32 s38, s56, 1
	s_nop 0
	v_addc_co_u32_e32 v3, vcc, 0, v3, vcc
	global_load_dwordx4 v[8:11], v[72:73], off
	s_nop 0
	global_load_dwordx4 v[12:15], v[76:77], off
	s_nop 0
	global_load_dwordx4 v[16:19], v[2:3], off
	global_load_dwordx4 v[20:23], v[88:89], off
	v_lshl_add_u64 v[2:3], v[88:89], 0, s[38:39]
	v_lshl_add_u64 v[96:97], v[2:3], 0, s[38:39]
	global_load_dwordx4 v[24:27], v[2:3], off
	global_load_dwordx4 v[28:31], v[96:97], off
	v_lshl_add_u64 v[2:3], v[96:97], 0, s[38:39]
	global_load_dwordx4 v[32:35], v[2:3], off
	s_mov_b64 s[56:57], 0
.LBB0_420:
	s_and_b64 vcc, exec, s[56:57]
	s_cbranch_vccz .LBB0_451
	s_andn2_b64 vcc, exec, s[54:55]
	s_cbranch_vccnz .LBB0_423
	v_mov_b32_e32 v0, s3
	ds_read_b64 v[2:3], v0
	v_mov_b32_e32 v121, v1
	v_lshlrev_b32_e32 v0, 1, v100
	v_mov_b32_e32 v123, v1
	v_mov_b32_e32 v103, v1
	s_waitcnt lgkmcnt(0)
	v_lshl_add_u64 v[4:5], v[2:3], 0, v[110:111]
	v_lshl_add_u64 v[6:7], v[2:3], 0, v[112:113]
	v_lshl_add_u64 v[4:5], v[4:5], 0, v[120:121]
	v_lshl_add_u64 v[12:13], v[4:5], 0, v[0:1]
	v_lshl_add_u64 v[4:5], v[6:7], 0, v[122:123]
	v_lshl_add_u64 v[28:29], v[4:5], 0, v[102:103]
	v_add_co_u32_e32 v4, vcc, 0x8800000, v12
	v_lshl_add_u64 v[2:3], v[2:3], 0, v[114:115]
	s_nop 0
	v_addc_co_u32_e32 v5, vcc, 0, v13, vcc
	v_add_co_u32_e32 v8, vcc, 0x8808000, v12
	v_lshl_add_u64 v[2:3], v[2:3], 0, v[120:121]
	s_nop 0
	v_addc_co_u32_e32 v9, vcc, 0, v13, vcc
	v_add_co_u32_e32 v14, vcc, 0x8810000, v12
	v_lshl_add_u64 v[2:3], v[2:3], 0, v[0:1]
	s_nop 0
	v_addc_co_u32_e32 v15, vcc, 0, v13, vcc
	v_add_co_u32_e32 v16, vcc, 0x8818000, v12
	global_load_dwordx4 v[4:7], v[4:5], off
	s_nop 0
	global_load_dwordx4 v[8:11], v[8:9], off
	v_addc_co_u32_e32 v17, vcc, 0, v13, vcc
	v_add_co_u32_e32 v20, vcc, 0xa800000, v28
	global_load_dwordx4 v[12:15], v[14:15], off
	s_nop 0
	global_load_dwordx4 v[16:19], v[16:17], off
	v_addc_co_u32_e32 v21, vcc, 0, v29, vcc
	v_add_co_u32_e32 v24, vcc, 0xa820000, v28
	s_nop 1
	v_addc_co_u32_e32 v25, vcc, 0, v29, vcc
	v_add_co_u32_e32 v30, vcc, 0xa840000, v28
	global_load_dwordx4 v[20:23], v[20:21], off
	s_nop 0
	global_load_dwordx4 v[24:27], v[24:25], off
	v_addc_co_u32_e32 v31, vcc, 0, v29, vcc
	v_add_co_u32_e32 v32, vcc, 0xa860000, v28
	s_nop 1
	v_addc_co_u32_e32 v33, vcc, 0, v29, vcc
	v_add_co_u32_e32 v44, vcc, 0x6800000, v2
	global_load_dwordx4 v[28:31], v[30:31], off
	s_nop 0
	global_load_dwordx4 v[32:35], v[32:33], off
	v_addc_co_u32_e32 v45, vcc, 0, v3, vcc
	v_add_co_u32_e32 v2, vcc, 0x6808000, v2
	s_nop 1
	v_addc_co_u32_e32 v3, vcc, 0, v3, vcc
	global_load_dwordx4 v[44:47], v[44:45], off
	s_nop 0
	global_load_dwordx4 v[48:51], v[2:3], off

.LBB0_424:
	s_cmp_gt_u32 s83, 3
	s_cselect_b64 vcc, -1, 0
	s_waitcnt lgkmcnt(0)
	v_cndmask_b32_e64 v79, v105, 0, vcc
	v_add_u32_e32 v0, v79, v129
	v_mad_u32_u24 v0, v0, s75, v155
	ds_read_b128 v[68:71], v0 offset:9216
	ds_read_b128 v[72:75], v0 offset:9280
	ds_read_b128 v[80:83], v0 offset:11520
	ds_read_b128 v[84:87], v0 offset:11584
	v_lshl_add_u32 v0, s83, 1, v151
	s_or_b64 s[34:35], vcc, s[36:37]
	s_waitcnt lgkmcnt(3)
	v_mfma_f32_16x16x32_bf16 v[68:71], v[68:71], v[40:43], 0
	v_mul_lo_u32 v2, v0, 31
	s_nor_b64 s[56:57], s[34:35], s[4:5]
	s_waitcnt lgkmcnt(1)
	v_mfma_f32_16x16x32_bf16 v[80:83], v[80:83], v[40:43], 0
	v_mfma_f32_16x16x32_bf16 v[72:75], v[72:75], v[36:39], v[68:71]
	s_waitcnt lgkmcnt(0)
	v_mfma_f32_16x16x32_bf16 v[68:71], v[84:87], v[36:39], v[80:83]
	s_nop 5
	v_cndmask_b32_e32 v76, v147, v72, vcc
	s_and_saveexec_b64 s[34:35], s[56:57]
	s_cbranch_execz .LBB0_426
	v_lshl_add_u32 v0, v2, 2, v137
	ds_read_b32 v0, v0 offset:45056
	s_waitcnt lgkmcnt(0)
	v_add_f32_e32 v76, v72, v0

.LBB0_792:
	s_ashr_i32 s0, s52, 31
	s_lshr_b32 s0, s0, 26
	s_add_i32 s0, s52, s0
	s_and_b32 s28, s0, 0xffc0
	s_sub_i32 s28, s52, s28
	s_bfe_i32 s29, s28, 0x80000
	s_bfe_u32 s29, s29, 0x4000b
	s_add_i32 s29, s28, s29
	v_mov_b32_e32 v150, v132
	s_bfe_i32 s30, s29, 0x80000
	s_and_b32 s29, s29, 0xf0
	ds_read_b128 v[0:3], v133
	s_sub_i32 s28, s28, s29
	s_sext_i32_i8 s28, s28
	s_lshl_b32 s0, s0, 6
	s_and_b32 s0, s0, 0xfffff000
	s_lshl_b32 s28, s28, 8
	s_sext_i32_i16 s30, s30
	s_add_i32 s28, s28, s0
	v_mov_b32_e32 v12, v132
	s_lshl_b32 s0, s30, 4
	s_waitcnt lgkmcnt(0)
	v_readfirstlane_b32 s31, v3
	v_readfirstlane_b32 s53, v2
	s_ashr_i32 s29, s28, 31
	s_and_b32 s30, s0, 0xffffff00
	v_lshlrev_b32_e32 v3, 4, v12
	v_and_b32_e32 v2, 32, v12
	s_lshl_b64 s[36:37], s[28:29], 11
	v_lshrrev_b32_e32 v4, 1, v12
	v_bitop3_b32 v2, v3, v2, 48 bitop3:0x6c
	s_add_u32 s54, s53, s36
	v_bfe_u32 v13, v12, 2, 4
	v_and_b32_e32 v14, 32, v4
	v_lshrrev_b32_e32 v15, 1, v2
	v_ashrrev_i32_e32 v16, 3, v12
	s_addc_u32 s55, s31, s37
	v_or_b32_e32 v6, v15, v14
	v_and_or_b32 v2, v16, s44, v13
	s_add_u32 s42, s54, 0x2400000
	v_and_b32_e32 v5, 0xfffffc00, v3
	v_lshl_or_b32 v130, v2, 10, v6
	v_add_u32_e32 v2, 0x2000, v3
	v_add_u32_e32 v4, 0x4000, v3
	v_add_u32_e32 v3, 0x6000, v3
	s_addc_u32 s43, s55, 0
	s_add_i32 s0, s30, 0x1200
	v_ashrrev_i32_e32 v17, 7, v2
	v_ashrrev_i32_e32 v18, 7, v4
	v_ashrrev_i32_e32 v19, 7, v3
	s_lshl_b64 s[38:39], s[0:1], 11
	v_and_or_b32 v2, v17, s44, v13
	v_and_or_b32 v4, v18, s44, v13
	v_and_or_b32 v3, v19, s44, v13
	v_add_u32_e32 v151, 0, v5
	s_add_u32 s38, s53, s38
	v_lshl_or_b32 v2, v2, 10, v6
	v_lshl_or_b32 v4, v4, 10, v6
	v_lshl_or_b32 v6, v3, 10, v6
	v_add_u32_e32 v3, 0x8000, v151
	v_lshlrev_b64 v[8:9], 1, v[130:131]
	v_readfirstlane_b32 s0, v151
	s_addc_u32 s39, s31, s39
	v_lshl_add_u64 v[10:11], s[42:43], 0, v[8:9]
	s_mov_b32 m0, s0
	v_readfirstlane_b32 s0, v3
	v_mov_b32_e32 v3, v131
	v_add_u32_e32 v5, 0x2000, v151
	global_load_lds_dwordx4 v[10:11], off
	v_lshl_add_u64 v[8:9], s[38:39], 0, v[8:9]
	s_mov_b32 m0, s0
	v_lshlrev_b64 v[2:3], 1, v[2:3]
	v_readfirstlane_b32 s0, v5
	v_add_u32_e32 v5, 0xa000, v151
	global_load_lds_dwordx4 v[8:9], off
	v_lshl_add_u64 v[8:9], s[42:43], 0, v[2:3]
	s_mov_b32 m0, s0
	v_readfirstlane_b32 s0, v5
	global_load_lds_dwordx4 v[8:9], off
	v_lshl_add_u64 v[2:3], s[38:39], 0, v[2:3]
	s_mov_b32 m0, s0
	v_mov_b32_e32 v5, v131
	v_add_u32_e32 v7, 0x4000, v151
	global_load_lds_dwordx4 v[2:3], off
	v_lshlrev_b64 v[2:3], 1, v[4:5]
	v_readfirstlane_b32 s0, v7
	v_lshl_add_u64 v[4:5], s[42:43], 0, v[2:3]
	s_mov_b32 m0, s0
	v_lshl_add_u64 v[2:3], s[38:39], 0, v[2:3]
	global_load_lds_dwordx4 v[4:5], off
	v_add_u32_e32 v4, 0xc000, v151
	v_mov_b32_e32 v7, v131
	v_readfirstlane_b32 s0, v4
	s_mov_b32 m0, s0
	v_and_b32_e32 v20, 15, v12
	global_load_lds_dwordx4 v[2:3], off
	v_lshlrev_b64 v[2:3], 1, v[6:7]
	v_add_u32_e32 v6, 0x6000, v151
	v_lshl_add_u64 v[4:5], s[42:43], 0, v[2:3]
	v_readfirstlane_b32 s0, v6
	s_mov_b32 m0, s0
	v_lshl_add_u64 v[2:3], s[38:39], 0, v[2:3]
	global_load_lds_dwordx4 v[4:5], off
	v_add_u32_e32 v4, 0xe000, v151
	v_lshlrev_b32_e32 v8, 10, v13
	v_readfirstlane_b32 s0, v4
	s_mov_b32 m0, s0
	v_lshlrev_b32_e32 v4, 2, v12
	global_load_lds_dwordx4 v[2:3], off
	v_and_b32_e32 v2, 48, v12
	v_lshlrev_b32_e32 v3, 6, v20
	v_and_b32_e32 v4, 32, v4
	v_bitop3_b32 v152, v3, v4, v2 bitop3:0x36
	v_lshlrev_b32_e32 v3, 7, v12
	v_and_b32_e32 v153, 0x6000, v3
	v_lshlrev_b32_e32 v3, 6, v12
	v_and_b32_e32 v154, 0xffffc000, v3
	v_and_b32_e32 v3, 0x3c0, v3
	v_bitop3_b32 v156, v3, v4, v2 bitop3:0x36
	v_lshlrev_b32_e32 v2, 10, v19
	v_and_or_b32 v2, v2, s45, v15
	v_lshlrev_b32_e32 v4, 10, v18
	v_or3_b32 v130, v2, v8, v14
	v_and_or_b32 v4, v4, s45, v15
	v_lshlrev_b32_e32 v6, 10, v17
	v_lshlrev_b64 v[2:3], 1, v[130:131]
	v_or3_b32 v130, v4, v8, v14
	v_and_or_b32 v6, v6, s45, v15
	v_lshlrev_b32_e32 v9, 10, v16
	v_lshlrev_b64 v[4:5], 1, v[130:131]
	v_or3_b32 v130, v6, v8, v14
	v_and_or_b32 v9, v9, s45, v15
	s_add_u32 s38, s38, 0x80
	v_lshlrev_b64 v[6:7], 1, v[130:131]
	v_or3_b32 v130, v9, v8, v14
	s_addc_u32 s39, s39, 0
	v_lshlrev_b64 v[8:9], 1, v[130:131]
	s_waitcnt vmcnt(0)
	v_lshl_add_u64 v[134:135], s[38:39], 0, v[2:3]
	v_lshl_add_u64 v[136:137], s[38:39], 0, v[4:5]
	v_lshl_add_u64 v[138:139], s[38:39], 0, v[6:7]
	v_lshl_add_u64 v[140:141], s[38:39], 0, v[8:9]
	s_add_u32 s38, s54, 0x2400080
	s_addc_u32 s39, s55, 0
	v_or_b32_e32 v155, 0x800, v154
	v_or_b32_e32 v157, 0x1000, v154
	v_or_b32_e32 v158, 0x1800, v154
	v_or_b32_e32 v159, 0x2000, v154
	v_or_b32_e32 v160, 0x2800, v154
	v_or_b32_e32 v161, 0x3000, v154
	v_or_b32_e32 v162, 0x3800, v154
	v_lshl_add_u64 v[142:143], s[38:39], 0, v[2:3]
	v_lshl_add_u64 v[144:145], s[38:39], 0, v[4:5]
	v_lshl_add_u64 v[146:147], s[38:39], 0, v[6:7]
	v_lshl_add_u64 v[148:149], s[38:39], 0, v[8:9]
	s_mov_b64 s[38:39], 0
	s_mov_b32 s0, 0
	v_mov_b32_e32 v14, 0
	v_mov_b32_e32 v15, v131
	v_mov_b32_e32 v16, v131
	v_mov_b32_e32 v17, v131
	v_mov_b32_e32 v22, 0
	v_mov_b32_e32 v23, v131
	v_mov_b32_e32 v24, v131
	v_mov_b32_e32 v25, v131
	v_mov_b32_e32 v30, 0
	v_mov_b32_e32 v31, v131
	v_mov_b32_e32 v32, v131
	v_mov_b32_e32 v33, v131
	v_mov_b32_e32 v38, 0
	v_mov_b32_e32 v39, v131
	v_mov_b32_e32 v40, v131
	v_mov_b32_e32 v41, v131
	v_mov_b32_e32 v2, 0
	v_mov_b32_e32 v3, v131
	v_mov_b32_e32 v4, v131
	v_mov_b32_e32 v5, v131
	v_mov_b32_e32 v6, 0
	v_mov_b32_e32 v7, v131
	v_mov_b32_e32 v8, v131
	v_mov_b32_e32 v9, v131
	v_mov_b32_e32 v10, 0
	v_mov_b32_e32 v11, v131
	v_mov_b32_e32 v12, v131
	v_mov_b32_e32 v13, v131
	v_mov_b32_e32 v18, 0
	v_mov_b32_e32 v19, v131
	v_mov_b32_e32 v20, v131
	v_mov_b32_e32 v21, v131
	v_mov_b32_e32 v26, 0
	v_mov_b32_e32 v27, v131
	v_mov_b32_e32 v28, v131
	v_mov_b32_e32 v29, v131
	v_mov_b32_e32 v34, 0
	v_mov_b32_e32 v35, v131
	v_mov_b32_e32 v36, v131
	v_mov_b32_e32 v37, v131
	v_mov_b32_e32 v42, 0
	v_mov_b32_e32 v43, v131
	v_mov_b32_e32 v44, v131
	v_mov_b32_e32 v45, v131
	v_mov_b32_e32 v46, 0
	v_mov_b32_e32 v47, v131
	v_mov_b32_e32 v48, v131
	v_mov_b32_e32 v49, v131
	v_mov_b32_e32 v50, 0
	v_mov_b32_e32 v51, v131
	v_mov_b32_e32 v52, v131
	v_mov_b32_e32 v53, v131
	v_mov_b32_e32 v54, 0
	v_mov_b32_e32 v55, v131
	v_mov_b32_e32 v56, v131
	v_mov_b32_e32 v57, v131
	v_mov_b32_e32 v58, 0
	v_mov_b32_e32 v59, v131
	v_mov_b32_e32 v60, v131
	v_mov_b32_e32 v61, v131
	v_mov_b32_e32 v62, 0
	v_mov_b32_e32 v63, v131
	v_mov_b32_e32 v64, v131
	v_mov_b32_e32 v65, v131
	v_mov_b32_e32 v66, 0
	v_mov_b32_e32 v67, v131
	v_mov_b32_e32 v68, v131
	v_mov_b32_e32 v69, v131
	v_mov_b32_e32 v70, 0
	v_mov_b32_e32 v71, v131
	v_mov_b32_e32 v72, v131
	v_mov_b32_e32 v73, v131
	v_mov_b32_e32 v74, 0
	v_mov_b32_e32 v75, v131
	v_mov_b32_e32 v76, v131
	v_mov_b32_e32 v77, v131
	v_mov_b32_e32 v78, 0
	v_mov_b32_e32 v79, v131
	v_mov_b32_e32 v80, v131
	v_mov_b32_e32 v81, v131
	v_mov_b32_e32 v82, 0
	v_mov_b32_e32 v83, v131
	v_mov_b32_e32 v84, v131
	v_mov_b32_e32 v85, v131
	v_mov_b32_e32 v86, 0
	v_mov_b32_e32 v87, v131
	v_mov_b32_e32 v88, v131
	v_mov_b32_e32 v89, v131
	v_mov_b32_e32 v90, 0
	v_mov_b32_e32 v91, v131
	v_mov_b32_e32 v92, v131
	v_mov_b32_e32 v93, v131
	v_mov_b32_e32 v94, 0
	v_mov_b32_e32 v95, v131
	v_mov_b32_e32 v96, v131
	v_mov_b32_e32 v97, v131
	v_mov_b32_e32 v98, 0
	v_mov_b32_e32 v99, v131
	v_mov_b32_e32 v100, v131
	v_mov_b32_e32 v101, v131
	v_mov_b32_e32 v102, 0
	v_mov_b32_e32 v103, v131
	v_mov_b32_e32 v104, v131
	v_mov_b32_e32 v105, v131
	v_mov_b32_e32 v106, 0
	v_mov_b32_e32 v107, v131
	v_mov_b32_e32 v108, v131
	v_mov_b32_e32 v109, v131
	v_mov_b32_e32 v110, 0
	v_mov_b32_e32 v111, v131
	v_mov_b32_e32 v112, v131
	v_mov_b32_e32 v113, v131
	v_mov_b32_e32 v114, 0
	v_mov_b32_e32 v115, v131
	v_mov_b32_e32 v116, v131
	v_mov_b32_e32 v117, v131
	v_mov_b32_e32 v118, 0
	v_mov_b32_e32 v119, v131
	v_mov_b32_e32 v120, v131
	v_mov_b32_e32 v121, v131
	v_mov_b32_e32 v122, 0
	v_mov_b32_e32 v123, v131
	v_mov_b32_e32 v124, v131
	v_mov_b32_e32 v125, v131
	v_mov_b32_e32 v126, 0
	v_mov_b32_e32 v127, v131
	v_mov_b32_e32 v128, v131
	v_mov_b32_e32 v129, v131
	s_waitcnt vmcnt(0) lgkmcnt(0)
	s_barrier
	v_readfirstlane_b32 s100, v151
	s_mov_b64 s[98:99], 0x80
	s_and_b32 s31, s0, 0x10000
	s_xor_b32 s42, s31, 0x10000
	s_add_i32 s31, s31, 0
	v_add3_u32 v130, s31, v152, v153
	v_add3_u32 v163, s31, v152, v154
	v_add3_u32 v196, s31, v156, v155
	v_add3_u32 v197, s31, v156, v157
	v_add3_u32 v198, s31, v156, v158
	v_add3_u32 v199, s31, v156, v159
	v_add3_u32 v200, s31, v156, v160
	v_add3_u32 v201, s31, v156, v161
	v_add3_u32 v202, s31, v156, v162
	ds_read_b128 v[180:183], v130 offset:32768
	ds_read_b128 v[164:167], v163
	ds_read_b128 v[168:171], v196
	ds_read_b128 v[172:175], v197
	ds_read_b128 v[176:179], v198
	ds_read_b128 v[184:187], v130 offset:34816
	ds_read_b128 v[188:191], v130 offset:36864
	ds_read_b128 v[192:195], v130 offset:38912
	s_add_i32 s101, s100, s42
	s_mov_b32 m0, s101
	s_nop 0
	global_load_lds_dwordx4 v[148:149], off
	s_add_i32 m0, s101, 0x8000
	s_nop 0
	global_load_lds_dwordx4 v[140:141], off
	s_add_i32 m0, s101, 0x2000
	s_nop 0
	global_load_lds_dwordx4 v[146:147], off
	s_add_i32 m0, s101, 0xa000
	s_nop 0
	global_load_lds_dwordx4 v[138:139], off
	s_add_i32 m0, s101, 0x4000
	s_nop 0
	global_load_lds_dwordx4 v[144:145], off
	s_add_i32 m0, s101, 0xc000
	s_nop 0
	global_load_lds_dwordx4 v[136:137], off
	s_add_i32 m0, s101, 0x6000
	s_nop 0
	global_load_lds_dwordx4 v[142:143], off
	s_add_i32 m0, s101, 0xe000
	s_nop 0
	global_load_lds_dwordx4 v[134:135], off
.LBB0_793:
	s_and_b32 s31, s0, 0x10000
	s_xor_b32 s42, s31, 0x10000
	s_add_i32 s31, s31, 0
	s_waitcnt lgkmcnt(3)
	v_mfma_f32_16x16x32_bf16 v[126:129], v[180:183], v[164:167], v[126:129]
	v_mfma_f32_16x16x32_bf16 v[110:113], v[180:183], v[168:171], v[110:113]
	v_mfma_f32_16x16x32_bf16 v[94:97], v[180:183], v[172:175], v[94:97]
	v_mfma_f32_16x16x32_bf16 v[78:81], v[180:183], v[176:179], v[78:81]
	ds_read_b128 v[240:243], v199
	ds_read_b128 v[244:247], v200
	s_waitcnt lgkmcnt(4)
	v_mfma_f32_16x16x32_bf16 v[122:125], v[184:187], v[164:167], v[122:125]
	v_mfma_f32_16x16x32_bf16 v[106:109], v[184:187], v[168:171], v[106:109]
	v_mfma_f32_16x16x32_bf16 v[90:93], v[184:187], v[172:175], v[90:93]
	v_mfma_f32_16x16x32_bf16 v[74:77], v[184:187], v[176:179], v[74:77]
	ds_read_b128 v[248:251], v201
	ds_read_b128 v[252:255], v202
	s_waitcnt lgkmcnt(5)
	v_mfma_f32_16x16x32_bf16 v[118:121], v[188:191], v[164:167], v[118:121]
	v_mfma_f32_16x16x32_bf16 v[102:105], v[188:191], v[168:171], v[102:105]
	v_mfma_f32_16x16x32_bf16 v[86:89], v[188:191], v[172:175], v[86:89]
	v_mfma_f32_16x16x32_bf16 v[70:73], v[188:191], v[176:179], v[70:73]
	s_waitcnt lgkmcnt(4)
	v_mfma_f32_16x16x32_bf16 v[114:117], v[192:195], v[164:167], v[114:117]
	v_mfma_f32_16x16x32_bf16 v[98:101], v[192:195], v[168:171], v[98:101]
	v_mfma_f32_16x16x32_bf16 v[82:85], v[192:195], v[172:175], v[82:85]
	v_mfma_f32_16x16x32_bf16 v[66:69], v[192:195], v[176:179], v[66:69]
	ds_read_b128 v[164:167], v163 offset:1024
	ds_read_b128 v[168:171], v196 offset:1024
	ds_read_b128 v[172:175], v197 offset:1024
	ds_read_b128 v[176:179], v198 offset:1024
	s_waitcnt lgkmcnt(4)
	v_mfma_f32_16x16x32_bf16 v[62:65], v[180:183], v[240:243], v[62:65]
	v_mfma_f32_16x16x32_bf16 v[46:49], v[180:183], v[244:247], v[46:49]
	v_mfma_f32_16x16x32_bf16 v[18:21], v[180:183], v[248:251], v[18:21]
	v_mfma_f32_16x16x32_bf16 v[38:41], v[180:183], v[252:255], v[38:41]
	ds_read_b128 v[180:183], v130 offset:33792
	v_mfma_f32_16x16x32_bf16 v[58:61], v[184:187], v[240:243], v[58:61]
	v_mfma_f32_16x16x32_bf16 v[42:45], v[184:187], v[244:247], v[42:45]
	v_mfma_f32_16x16x32_bf16 v[10:13], v[184:187], v[248:251], v[10:13]
	v_mfma_f32_16x16x32_bf16 v[30:33], v[184:187], v[252:255], v[30:33]
	ds_read_b128 v[184:187], v130 offset:35840
	v_mfma_f32_16x16x32_bf16 v[54:57], v[188:191], v[240:243], v[54:57]
	v_mfma_f32_16x16x32_bf16 v[34:37], v[188:191], v[244:247], v[34:37]
	v_mfma_f32_16x16x32_bf16 v[6:9], v[188:191], v[248:251], v[6:9]
	v_mfma_f32_16x16x32_bf16 v[22:25], v[188:191], v[252:255], v[22:25]
	ds_read_b128 v[188:191], v130 offset:37888
	v_mfma_f32_16x16x32_bf16 v[50:53], v[192:195], v[240:243], v[50:53]
	v_mfma_f32_16x16x32_bf16 v[26:29], v[192:195], v[244:247], v[26:29]
	v_mfma_f32_16x16x32_bf16 v[2:5], v[192:195], v[248:251], v[2:5]
	v_mfma_f32_16x16x32_bf16 v[14:17], v[192:195], v[252:255], v[14:17]
	ds_read_b128 v[192:195], v130 offset:39936
	s_waitcnt lgkmcnt(3)
	v_mfma_f32_16x16x32_bf16 v[126:129], v[180:183], v[164:167], v[126:129]
	v_mfma_f32_16x16x32_bf16 v[110:113], v[180:183], v[168:171], v[110:113]
	v_mfma_f32_16x16x32_bf16 v[94:97], v[180:183], v[172:175], v[94:97]
	v_mfma_f32_16x16x32_bf16 v[78:81], v[180:183], v[176:179], v[78:81]
	ds_read_b128 v[240:243], v199 offset:1024
	ds_read_b128 v[244:247], v200 offset:1024
	s_waitcnt lgkmcnt(4)
	v_mfma_f32_16x16x32_bf16 v[122:125], v[184:187], v[164:167], v[122:125]
	v_mfma_f32_16x16x32_bf16 v[106:109], v[184:187], v[168:171], v[106:109]
	v_mfma_f32_16x16x32_bf16 v[90:93], v[184:187], v[172:175], v[90:93]
	v_mfma_f32_16x16x32_bf16 v[74:77], v[184:187], v[176:179], v[74:77]
	ds_read_b128 v[248:251], v201 offset:1024
	ds_read_b128 v[252:255], v202 offset:1024
	s_waitcnt lgkmcnt(5)
	v_mfma_f32_16x16x32_bf16 v[118:121], v[188:191], v[164:167], v[118:121]
	v_mfma_f32_16x16x32_bf16 v[102:105], v[188:191], v[168:171], v[102:105]
	v_mfma_f32_16x16x32_bf16 v[86:89], v[188:191], v[172:175], v[86:89]
	v_mfma_f32_16x16x32_bf16 v[70:73], v[188:191], v[176:179], v[70:73]
	s_waitcnt lgkmcnt(4)
	v_mfma_f32_16x16x32_bf16 v[114:117], v[192:195], v[164:167], v[114:117]
	v_mfma_f32_16x16x32_bf16 v[98:101], v[192:195], v[168:171], v[98:101]
	v_mfma_f32_16x16x32_bf16 v[82:85], v[192:195], v[172:175], v[82:85]
	v_mfma_f32_16x16x32_bf16 v[66:69], v[192:195], v[176:179], v[66:69]
	s_waitcnt vmcnt(0) lgkmcnt(0)
	s_barrier
	s_add_i32 s101, s100, s31
	v_mfma_f32_16x16x32_bf16 v[62:65], v[180:183], v[240:243], v[62:65]
	v_mfma_f32_16x16x32_bf16 v[46:49], v[180:183], v[244:247], v[46:49]
	v_mfma_f32_16x16x32_bf16 v[18:21], v[180:183], v[248:251], v[18:21]
	v_mfma_f32_16x16x32_bf16 v[38:41], v[180:183], v[252:255], v[38:41]
	v_add3_u32 v130, s42, v152, v153
	ds_read_b128 v[180:183], v130 offset:32768
	v_add3_u32 v163, s42, v152, v154
	v_add3_u32 v196, s42, v156, v155
	v_add3_u32 v197, s42, v156, v157
	v_add3_u32 v198, s42, v156, v158
	ds_read_b128 v[164:167], v163
	ds_read_b128 v[168:171], v196
	ds_read_b128 v[172:175], v197
	ds_read_b128 v[176:179], v198
	s_cmpk_eq_i32 s38, 0x700
	s_cbranch_scc1 .Lpk_793_0
	s_mov_b32 m0, s101
	v_lshl_add_u64 v[148:149], v[148:149], 0, s[98:99]
	global_load_lds_dwordx4 v[148:149], off
.Lpk_793_0:
	s_cmpk_eq_i32 s38, 0x700
	s_cbranch_scc1 .Lpk_793_1
	s_add_i32 m0, s101, 0x8000
	v_lshl_add_u64 v[140:141], v[140:141], 0, s[98:99]
	global_load_lds_dwordx4 v[140:141], off
.Lpk_793_1:
	v_mfma_f32_16x16x32_bf16 v[58:61], v[184:187], v[240:243], v[58:61]
	v_mfma_f32_16x16x32_bf16 v[42:45], v[184:187], v[244:247], v[42:45]
	v_mfma_f32_16x16x32_bf16 v[10:13], v[184:187], v[248:251], v[10:13]
	v_mfma_f32_16x16x32_bf16 v[30:33], v[184:187], v[252:255], v[30:33]
	ds_read_b128 v[184:187], v130 offset:34816
	v_add3_u32 v199, s42, v156, v159
	v_add3_u32 v200, s42, v156, v160
	v_add3_u32 v201, s42, v156, v161
	v_add3_u32 v202, s42, v156, v162
	s_cmpk_eq_i32 s38, 0x700
	s_cbranch_scc1 .Lpk_793_2
	s_add_i32 m0, s101, 0x2000
	v_lshl_add_u64 v[146:147], v[146:147], 0, s[98:99]
	global_load_lds_dwordx4 v[146:147], off
.Lpk_793_2:
	s_cmpk_eq_i32 s38, 0x700
	s_cbranch_scc1 .Lpk_793_3
	s_add_i32 m0, s101, 0xa000
	v_lshl_add_u64 v[138:139], v[138:139], 0, s[98:99]
	global_load_lds_dwordx4 v[138:139], off
.Lpk_793_3:
	v_mfma_f32_16x16x32_bf16 v[54:57], v[188:191], v[240:243], v[54:57]
	v_mfma_f32_16x16x32_bf16 v[34:37], v[188:191], v[244:247], v[34:37]
	v_mfma_f32_16x16x32_bf16 v[6:9], v[188:191], v[248:251], v[6:9]
	v_mfma_f32_16x16x32_bf16 v[22:25], v[188:191], v[252:255], v[22:25]
	ds_read_b128 v[188:191], v130 offset:36864
	s_cmpk_eq_i32 s38, 0x700
	s_cbranch_scc1 .Lpk_793_4
	s_add_i32 m0, s101, 0x4000
	v_lshl_add_u64 v[144:145], v[144:145], 0, s[98:99]
	global_load_lds_dwordx4 v[144:145], off
.Lpk_793_4:
	s_cmpk_eq_i32 s38, 0x700
	s_cbranch_scc1 .Lpk_793_5
	s_add_i32 m0, s101, 0xc000
	v_lshl_add_u64 v[136:137], v[136:137], 0, s[98:99]
	global_load_lds_dwordx4 v[136:137], off
.Lpk_793_5:
	v_mfma_f32_16x16x32_bf16 v[50:53], v[192:195], v[240:243], v[50:53]
	v_mfma_f32_16x16x32_bf16 v[26:29], v[192:195], v[244:247], v[26:29]
	v_mfma_f32_16x16x32_bf16 v[2:5], v[192:195], v[248:251], v[2:5]
	v_mfma_f32_16x16x32_bf16 v[14:17], v[192:195], v[252:255], v[14:17]
	ds_read_b128 v[192:195], v130 offset:38912
	s_cmpk_eq_i32 s38, 0x700
	s_cbranch_scc1 .Lpk_793_6
	s_add_i32 m0, s101, 0x6000
	v_lshl_add_u64 v[142:143], v[142:143], 0, s[98:99]
	global_load_lds_dwordx4 v[142:143], off
.Lpk_793_6:
	s_cmpk_eq_i32 s38, 0x700
	s_cbranch_scc1 .Lpk_793_7
	s_add_i32 m0, s101, 0xe000
	v_lshl_add_u64 v[134:135], v[134:135], 0, s[98:99]
	global_load_lds_dwordx4 v[134:135], off
.Lpk_793_7:
	s_add_i32 s0, s0, 0x10000
	s_add_u32 s38, s38, 0x80
	s_addc_u32 s39, s39, 0
	s_cmpk_lg_i32 s38, 0x780
	s_cbranch_scc1 .LBB0_793
	s_waitcnt lgkmcnt(0)
	v_add3_u32 v130, s46, v156, v162
	v_add3_u32 v151, s46, v156, v161
	v_add3_u32 v202, s46, v156, v160
	v_add3_u32 v198, s46, v156, v159
	v_add3_u32 v186, s46, v156, v158
	v_add3_u32 v187, s46, v156, v157
	v_add3_u32 v188, s46, v156, v155
	v_add3_u32 v189, s46, v152, v154
	v_add3_u32 v190, s47, v152, v153
	ds_read_b128 v[134:137], v130
	ds_read_b128 v[138:141], v151
	ds_read_b128 v[142:145], v202
	ds_read_b128 v[146:149], v198
	ds_read_b128 v[158:161], v186
	ds_read_b128 v[162:165], v187
	ds_read_b128 v[166:169], v188
	ds_read_b128 v[154:157], v189
	ds_read_b128 v[170:173], v190
	s_waitcnt lgkmcnt(0)
	v_mfma_f32_16x16x32_bf16 v[18:21], v[170:173], v[138:141], v[18:21]
	v_mfma_f32_16x16x32_bf16 v[174:177], v[170:173], v[134:137], v[38:41]
	s_nop 2
	ds_read_b128 v[38:41], v190 offset:2048
	s_waitcnt lgkmcnt(0)
	v_mfma_f32_16x16x32_bf16 v[10:13], v[38:41], v[138:141], v[10:13]
	v_mfma_f32_16x16x32_bf16 v[62:65], v[170:173], v[146:149], v[62:65]
	v_mfma_f32_16x16x32_bf16 v[30:33], v[38:41], v[134:137], v[30:33]
	v_mfma_f32_16x16x32_bf16 v[58:61], v[38:41], v[146:149], v[58:61]
	ds_read_b128 v[178:181], v190 offset:4096
	s_waitcnt lgkmcnt(0)
	v_mfma_f32_16x16x32_bf16 v[182:185], v[178:181], v[134:137], v[22:25]
	v_mfma_f32_16x16x32_bf16 v[54:57], v[178:181], v[146:149], v[54:57]
	s_nop 1
	ds_read_b128 v[22:25], v190 offset:6144
	s_waitcnt lgkmcnt(0)
	v_mfma_f32_16x16x32_bf16 v[134:137], v[22:25], v[134:137], v[14:17]
	v_mfma_f32_16x16x32_bf16 v[14:17], v[22:25], v[154:157], v[114:117]
	v_mfma_f32_16x16x32_bf16 v[114:117], v[22:25], v[158:161], v[66:69]
	v_mfma_f32_16x16x32_bf16 v[66:69], v[178:181], v[154:157], v[118:121]
	v_mfma_f32_16x16x32_bf16 v[118:121], v[178:181], v[158:161], v[70:73]
	v_mfma_f32_16x16x32_bf16 v[70:73], v[38:41], v[154:157], v[122:125]
	v_mfma_f32_16x16x32_bf16 v[122:125], v[38:41], v[158:161], v[74:77]
	v_mfma_f32_16x16x32_bf16 v[74:77], v[170:173], v[154:157], v[126:129]
	v_mfma_f32_16x16x32_bf16 v[126:129], v[170:173], v[158:161], v[78:81]
	v_mfma_f32_16x16x32_bf16 v[50:53], v[22:25], v[146:149], v[50:53]
	v_mfma_f32_16x16x32_bf16 v[146:149], v[170:173], v[142:145], v[46:49]
	v_mfma_f32_16x16x32_bf16 v[152:155], v[38:41], v[142:145], v[42:45]
	v_mfma_f32_16x16x32_bf16 v[156:159], v[178:181], v[142:145], v[34:37]
	v_mfma_f32_16x16x32_bf16 v[26:29], v[22:25], v[142:145], v[26:29]
	v_mfma_f32_16x16x32_bf16 v[142:145], v[178:181], v[138:141], v[6:9]
	v_mfma_f32_16x16x32_bf16 v[110:113], v[170:173], v[166:169], v[110:113]
	v_mfma_f32_16x16x32_bf16 v[94:97], v[170:173], v[162:165], v[94:97]
	v_mfma_f32_16x16x32_bf16 v[106:109], v[38:41], v[166:169], v[106:109]
	v_mfma_f32_16x16x32_bf16 v[90:93], v[38:41], v[162:165], v[90:93]
	v_mfma_f32_16x16x32_bf16 v[102:105], v[178:181], v[166:169], v[102:105]
	v_mfma_f32_16x16x32_bf16 v[86:89], v[178:181], v[162:165], v[86:89]
	v_mfma_f32_16x16x32_bf16 v[98:101], v[22:25], v[166:169], v[98:101]
	v_mfma_f32_16x16x32_bf16 v[82:85], v[22:25], v[162:165], v[82:85]
	v_mfma_f32_16x16x32_bf16 v[22:25], v[22:25], v[138:141], v[2:5]
	ds_read_b128 v[138:141], v190 offset:1024
	ds_read_b128 v[160:163], v190 offset:3072
	ds_read_b128 v[164:167], v190 offset:5120
	ds_read_b128 v[168:171], v190 offset:7168
	ds_read_b128 v[2:5], v189 offset:1024
	ds_read_b128 v[6:9], v188 offset:1024
	ds_read_b128 v[34:37], v187 offset:1024
	ds_read_b128 v[38:41], v186 offset:1024
	s_waitcnt lgkmcnt(3)
	v_mfma_f32_16x16x32_bf16 v[178:181], v[138:141], v[2:5], v[74:77]
	v_mfma_f32_16x16x32_bf16 v[186:189], v[160:163], v[2:5], v[70:73]
	v_mfma_f32_16x16x32_bf16 v[190:193], v[164:167], v[2:5], v[66:69]
	v_mfma_f32_16x16x32_bf16 v[194:197], v[168:171], v[2:5], v[14:17]
	ds_read_b128 v[2:5], v198 offset:1024
	s_waitcnt lgkmcnt(3)
	v_mfma_f32_16x16x32_bf16 v[110:113], v[138:141], v[6:9], v[110:113]
	v_mfma_f32_16x16x32_bf16 v[106:109], v[160:163], v[6:9], v[106:109]
	v_mfma_f32_16x16x32_bf16 v[102:105], v[164:167], v[6:9], v[102:105]
	v_mfma_f32_16x16x32_bf16 v[198:201], v[168:171], v[6:9], v[98:101]
	ds_read_b128 v[6:9], v202 offset:1024
	s_waitcnt lgkmcnt(3)
	v_mfma_f32_16x16x32_bf16 v[66:69], v[138:141], v[34:37], v[94:97]
	v_mfma_f32_16x16x32_bf16 v[70:73], v[160:163], v[34:37], v[90:93]
	v_mfma_f32_16x16x32_bf16 v[74:77], v[164:167], v[34:37], v[86:89]
	v_mfma_f32_16x16x32_bf16 v[78:81], v[168:171], v[34:37], v[82:85]
	ds_read_b128 v[14:17], v151 offset:1024
	s_waitcnt lgkmcnt(3)
	v_mfma_f32_16x16x32_bf16 v[82:85], v[138:141], v[38:41], v[126:129]
	v_mfma_f32_16x16x32_bf16 v[86:89], v[160:163], v[38:41], v[122:125]
	v_mfma_f32_16x16x32_bf16 v[90:93], v[164:167], v[38:41], v[118:121]
	v_mfma_f32_16x16x32_bf16 v[94:97], v[168:171], v[38:41], v[114:117]
	ds_read_b128 v[98:101], v130 offset:1024
	s_waitcnt lgkmcnt(3)
	v_mfma_f32_16x16x32_bf16 v[34:37], v[138:141], v[2:5], v[62:65]
	v_mfma_f32_16x16x32_bf16 v[38:41], v[160:163], v[2:5], v[58:61]
	v_mfma_f32_16x16x32_bf16 v[42:45], v[164:167], v[2:5], v[54:57]
	v_mfma_f32_16x16x32_bf16 v[46:49], v[168:171], v[2:5], v[50:53]
	s_waitcnt lgkmcnt(2)
	v_mfma_f32_16x16x32_bf16 v[50:53], v[138:141], v[6:9], v[146:149]
	v_mfma_f32_16x16x32_bf16 v[54:57], v[160:163], v[6:9], v[152:155]
	v_mfma_f32_16x16x32_bf16 v[58:61], v[164:167], v[6:9], v[156:159]
	v_mfma_f32_16x16x32_bf16 v[62:65], v[168:171], v[6:9], v[26:29]
	s_waitcnt lgkmcnt(1)
	v_mfma_f32_16x16x32_bf16 v[2:5], v[138:141], v[14:17], v[18:21]
	v_mfma_f32_16x16x32_bf16 v[6:9], v[160:163], v[14:17], v[10:13]
	v_mfma_f32_16x16x32_bf16 v[10:13], v[164:167], v[14:17], v[142:145]
	v_mfma_f32_16x16x32_bf16 v[14:17], v[168:171], v[14:17], v[22:25]
	s_waitcnt lgkmcnt(0)
	v_mfma_f32_16x16x32_bf16 v[18:21], v[138:141], v[98:101], v[174:177]
	v_mfma_f32_16x16x32_bf16 v[22:25], v[160:163], v[98:101], v[30:33]
	v_mfma_f32_16x16x32_bf16 v[26:29], v[164:167], v[98:101], v[182:185]
	v_mfma_f32_16x16x32_bf16 v[30:33], v[168:171], v[98:101], v[134:137]
	v_lshrrev_b32_e32 v98, 6, v150
	v_mul_lo_u32 v98, v98, s48
	v_add_u32_e32 v101, s46, v98
	v_lshlrev_b32_e32 v98, 2, v150
	v_and_b32_e32 v100, 15, v150
	v_and_b32_e32 v115, 60, v98
	v_ashrrev_i32_e32 v98, 1, v150
	v_bfe_u32 v99, v150, 4, 2
	v_and_b32_e32 v114, 48, v150
	v_and_b32_e32 v116, 0xffffff80, v98
	v_lshlrev_b32_e32 v98, 2, v115
	v_mul_u32_u24_e32 v117, 0x110, v99
	v_mul_u32_u24_e32 v100, 0x110, v100
	v_add3_u32 v98, v101, v98, v117
	v_add3_u32 v101, v101, v114, v100
	s_waitcnt vmcnt(0)
	s_barrier
	ds_write_b128 v101, v[178:181]
	ds_write_b128 v101, v[186:189] offset:64
	ds_write_b128 v101, v[190:193] offset:128
	ds_write_b128 v101, v[194:197] offset:192
	ds_write_b128 v101, v[110:113] offset:4352
	ds_write_b128 v101, v[106:109] offset:4416
	ds_write_b128 v101, v[102:105] offset:4480
	ds_write_b128 v101, v[198:201] offset:4544
	ds_read_b128 v[102:105], v98
	v_add_u32_e32 v100, s28, v116
	s_ashr_i32 s31, s30, 31
	v_and_or_b32 v106, v150, s49, v115
	s_lshl_b64 s[38:39], s[30:31], 1
	s_waitcnt lgkmcnt(0)
	v_mul_f32_e32 v102, 0xbfb8aa3b, v102
	v_mul_f32_e32 v103, 0xbfb8aa3b, v103
	v_mul_f32_e32 v104, 0xbfb8aa3b, v104
	v_mul_f32_e32 v105, 0xbfb8aa3b, v105
	v_exp_f32_e32 v102, v102
	v_exp_f32_e32 v103, v103
	v_exp_f32_e32 v104, v104
	v_exp_f32_e32 v105, v105
	v_add_f32_e32 v102, 1.0, v102
	v_add_f32_e32 v103, 1.0, v103
	v_add_f32_e32 v104, 1.0, v104
	v_add_f32_e32 v105, 1.0, v105
	v_rcp_f32_e32 v102, v102
	v_rcp_f32_e32 v103, v103
	v_rcp_f32_e32 v104, v104
	v_rcp_f32_e32 v105, v105
	v_lshl_add_u64 v[0:1], v[0:1], 0, s[38:39]
	v_cvt_pk_bf16_f32 v102, v102, v103
	v_lshlrev_b32_e32 v130, 1, v106
	v_cvt_pk_bf16_f32 v103, v104, v105
	v_or_b32_e32 v104, v100, v99
	v_ashrrev_i32_e32 v105, 31, v104
	v_lshl_add_u64 v[0:1], v[0:1], 0, v[130:131]
	v_lshlrev_b64 v[104:105], 11, v[104:105]
	v_lshl_add_u64 v[104:105], v[0:1], 0, v[104:105]
	flat_store_dwordx2 v[104:105], v[102:103]
	ds_read_b128 v[102:105], v98 offset:1088
	s_lshl_b64 s[42:43], s[28:29], 10
	s_mov_b32 s29, 0
	s_waitcnt lgkmcnt(0)
	v_mul_f32_e32 v102, 0xbfb8aa3b, v102
	v_exp_f32_e32 v102, v102
	v_mul_f32_e32 v103, 0xbfb8aa3b, v103
	v_exp_f32_e32 v103, v103
	v_add_f32_e32 v102, 1.0, v102
	v_rcp_f32_e32 v106, v102
	v_add_f32_e32 v102, 1.0, v103
	v_mul_f32_e32 v103, 0xbfb8aa3b, v104
	v_exp_f32_e32 v103, v103
	v_mul_f32_e32 v104, 0xbfb8aa3b, v105
	v_exp_f32_e32 v104, v104
	v_rcp_f32_e32 v105, v102
	v_add_f32_e32 v102, 1.0, v103
	v_rcp_f32_e32 v103, v102
	v_add_f32_e32 v102, 1.0, v104
	v_rcp_f32_e32 v107, v102
	v_or_b32_e32 v102, 4, v99
	v_cvt_pk_bf16_f32 v104, v106, v105
	v_or_b32_e32 v106, v100, v102
	v_cvt_pk_bf16_f32 v105, v103, v107
	v_ashrrev_i32_e32 v107, 31, v106
	v_lshlrev_b64 v[106:107], 11, v[106:107]
	v_lshl_add_u64 v[106:107], v[0:1], 0, v[106:107]
	flat_store_dwordx2 v[106:107], v[104:105]
	ds_read_b128 v[104:107], v98 offset:2176
	s_waitcnt lgkmcnt(0)
	v_mul_f32_e32 v103, 0xbfb8aa3b, v104
	v_exp_f32_e32 v103, v103
	v_mul_f32_e32 v104, 0xbfb8aa3b, v105
	v_exp_f32_e32 v104, v104
	v_add_f32_e32 v103, 1.0, v103
	v_rcp_f32_e32 v105, v103
	v_add_f32_e32 v103, 1.0, v104
	v_mul_f32_e32 v104, 0xbfb8aa3b, v106
	v_exp_f32_e32 v104, v104
	v_mul_f32_e32 v106, 0xbfb8aa3b, v107
	v_exp_f32_e32 v106, v106
	v_rcp_f32_e32 v107, v103
	v_add_f32_e32 v103, 1.0, v104
	v_rcp_f32_e32 v108, v103
	v_add_f32_e32 v103, 1.0, v106
	v_rcp_f32_e32 v106, v103
	v_or_b32_e32 v103, 8, v99
	v_cvt_pk_bf16_f32 v104, v105, v107
	v_cvt_pk_bf16_f32 v105, v108, v106
	v_or_b32_e32 v106, v100, v103
	v_ashrrev_i32_e32 v107, 31, v106
	v_lshlrev_b64 v[106:107], 11, v[106:107]
	v_lshl_add_u64 v[106:107], v[0:1], 0, v[106:107]
	flat_store_dwordx2 v[106:107], v[104:105]
	ds_read_b128 v[104:107], v98 offset:3264
	s_waitcnt lgkmcnt(0)
	v_mul_f32_e32 v104, 0xbfb8aa3b, v104
	v_exp_f32_e32 v104, v104
	v_mul_f32_e32 v105, 0xbfb8aa3b, v105
	v_exp_f32_e32 v105, v105
	v_add_f32_e32 v104, 1.0, v104
	v_rcp_f32_e32 v108, v104
	v_add_f32_e32 v104, 1.0, v105
	v_mul_f32_e32 v105, 0xbfb8aa3b, v106
	v_exp_f32_e32 v105, v105
	v_mul_f32_e32 v106, 0xbfb8aa3b, v107
	v_exp_f32_e32 v106, v106
	v_rcp_f32_e32 v107, v104
	v_add_f32_e32 v104, 1.0, v105
	v_rcp_f32_e32 v105, v104
	v_add_f32_e32 v104, 1.0, v106
	v_rcp_f32_e32 v109, v104
	v_or_b32_e32 v104, 12, v99
	v_cvt_pk_bf16_f32 v106, v108, v107
	v_or_b32_e32 v108, v100, v104
	v_cvt_pk_bf16_f32 v107, v105, v109
	v_ashrrev_i32_e32 v109, 31, v108
	v_lshlrev_b64 v[108:109], 11, v[108:109]
	v_lshl_add_u64 v[108:109], v[0:1], 0, v[108:109]
	flat_store_dwordx2 v[108:109], v[106:107]
	ds_read_b128 v[106:109], v98 offset:4352
	s_waitcnt lgkmcnt(0)
	v_mul_f32_e32 v105, 0xbfb8aa3b, v106
	v_exp_f32_e32 v105, v105
	v_mul_f32_e32 v106, 0xbfb8aa3b, v107
	v_exp_f32_e32 v106, v106
	v_add_f32_e32 v105, 1.0, v105
	v_rcp_f32_e32 v107, v105
	v_add_f32_e32 v105, 1.0, v106
	v_mul_f32_e32 v106, 0xbfb8aa3b, v108
	v_exp_f32_e32 v106, v106
	v_mul_f32_e32 v108, 0xbfb8aa3b, v109
	v_exp_f32_e32 v108, v108
	v_rcp_f32_e32 v109, v105
	v_add_f32_e32 v105, 1.0, v106
	v_rcp_f32_e32 v110, v105
	v_add_f32_e32 v105, 1.0, v108
	v_rcp_f32_e32 v108, v105
	v_or_b32_e32 v105, 16, v99
	v_cvt_pk_bf16_f32 v106, v107, v109
	v_cvt_pk_bf16_f32 v107, v110, v108
	v_or_b32_e32 v108, v100, v105
	v_ashrrev_i32_e32 v109, 31, v108
	v_lshlrev_b64 v[108:109], 11, v[108:109]
	v_lshl_add_u64 v[108:109], v[0:1], 0, v[108:109]
	flat_store_dwordx2 v[108:109], v[106:107]
	ds_read_b128 v[106:109], v98 offset:5440
	s_waitcnt lgkmcnt(0)
	v_mul_f32_e32 v106, 0xbfb8aa3b, v106
	v_exp_f32_e32 v106, v106
	v_mul_f32_e32 v107, 0xbfb8aa3b, v107
	v_exp_f32_e32 v107, v107
	v_add_f32_e32 v106, 1.0, v106
	v_rcp_f32_e32 v110, v106
	v_add_f32_e32 v106, 1.0, v107
	v_mul_f32_e32 v107, 0xbfb8aa3b, v108
	v_exp_f32_e32 v107, v107
	v_mul_f32_e32 v108, 0xbfb8aa3b, v109
	v_exp_f32_e32 v108, v108
	v_rcp_f32_e32 v109, v106
	v_add_f32_e32 v106, 1.0, v107
	v_rcp_f32_e32 v107, v106
	v_add_f32_e32 v106, 1.0, v108
	v_rcp_f32_e32 v111, v106
	v_or_b32_e32 v106, 20, v99
	v_cvt_pk_bf16_f32 v108, v110, v109
	v_or_b32_e32 v110, v100, v106
	v_cvt_pk_bf16_f32 v109, v107, v111
	v_ashrrev_i32_e32 v111, 31, v110
	v_lshlrev_b64 v[110:111], 11, v[110:111]
	v_lshl_add_u64 v[110:111], v[0:1], 0, v[110:111]
	flat_store_dwordx2 v[110:111], v[108:109]
	ds_read_b128 v[108:111], v98 offset:6528
	s_waitcnt lgkmcnt(0)
	v_mul_f32_e32 v107, 0xbfb8aa3b, v108
	v_exp_f32_e32 v107, v107
	v_mul_f32_e32 v108, 0xbfb8aa3b, v109
	v_exp_f32_e32 v108, v108
	v_add_f32_e32 v107, 1.0, v107
	v_rcp_f32_e32 v109, v107
	v_add_f32_e32 v107, 1.0, v108
	v_mul_f32_e32 v108, 0xbfb8aa3b, v110
	v_exp_f32_e32 v108, v108
	v_mul_f32_e32 v110, 0xbfb8aa3b, v111
	v_exp_f32_e32 v110, v110
	v_rcp_f32_e32 v111, v107
	v_add_f32_e32 v107, 1.0, v108
	v_rcp_f32_e32 v112, v107
	v_add_f32_e32 v107, 1.0, v110
	v_rcp_f32_e32 v110, v107
	v_or_b32_e32 v107, 24, v99
	v_cvt_pk_bf16_f32 v108, v109, v111
	v_cvt_pk_bf16_f32 v109, v112, v110
	v_or_b32_e32 v110, v100, v107
	v_ashrrev_i32_e32 v111, 31, v110
	v_lshlrev_b64 v[110:111], 11, v[110:111]
	v_lshl_add_u64 v[110:111], v[0:1], 0, v[110:111]
	flat_store_dwordx2 v[110:111], v[108:109]
	ds_read_b128 v[108:111], v98 offset:7616
	s_waitcnt lgkmcnt(0)
	v_mul_f32_e32 v108, 0xbfb8aa3b, v108
	v_exp_f32_e32 v108, v108
	v_mul_f32_e32 v109, 0xbfb8aa3b, v109
	v_exp_f32_e32 v109, v109
	v_add_f32_e32 v108, 1.0, v108
	v_rcp_f32_e32 v112, v108
	v_add_f32_e32 v108, 1.0, v109
	v_mul_f32_e32 v109, 0xbfb8aa3b, v110
	v_exp_f32_e32 v109, v109
	v_mul_f32_e32 v110, 0xbfb8aa3b, v111
	v_exp_f32_e32 v110, v110
	v_rcp_f32_e32 v111, v108
	v_add_f32_e32 v108, 1.0, v109
	v_rcp_f32_e32 v109, v108
	v_add_f32_e32 v108, 1.0, v110
	v_rcp_f32_e32 v113, v108
	v_or_b32_e32 v108, 28, v99
	v_cvt_pk_bf16_f32 v110, v112, v111
	v_or_b32_e32 v112, v100, v108
	v_cvt_pk_bf16_f32 v111, v109, v113
	v_ashrrev_i32_e32 v113, 31, v112
	v_lshlrev_b64 v[112:113], 11, v[112:113]
	v_lshl_add_u64 v[112:113], v[0:1], 0, v[112:113]
	flat_store_dwordx2 v[112:113], v[110:111]
	ds_write_b128 v101, v[66:69]
	ds_write_b128 v101, v[70:73] offset:64
	ds_write_b128 v101, v[74:77] offset:128
	ds_write_b128 v101, v[78:81] offset:192
	ds_write_b128 v101, v[82:85] offset:4352
	ds_write_b128 v101, v[86:89] offset:4416
	ds_write_b128 v101, v[90:93] offset:4480
	ds_write_b128 v101, v[94:97] offset:4544
	ds_read_b128 v[66:69], v98
	v_or_b32_e32 v70, 32, v100
	s_waitcnt lgkmcnt(0)
	v_mul_f32_e32 v66, 0xbfb8aa3b, v66
	v_mul_f32_e32 v67, 0xbfb8aa3b, v67
	v_mul_f32_e32 v68, 0xbfb8aa3b, v68
	v_mul_f32_e32 v69, 0xbfb8aa3b, v69
	v_exp_f32_e32 v66, v66
	v_exp_f32_e32 v67, v67
	v_exp_f32_e32 v68, v68
	v_exp_f32_e32 v69, v69
	v_add_f32_e32 v66, 1.0, v66
	v_add_f32_e32 v67, 1.0, v67
	v_add_f32_e32 v68, 1.0, v68
	v_add_f32_e32 v69, 1.0, v69
	v_rcp_f32_e32 v66, v66
	v_rcp_f32_e32 v67, v67
	v_rcp_f32_e32 v68, v68
	v_rcp_f32_e32 v69, v69
	v_cvt_pk_bf16_f32 v66, v66, v67
	v_cvt_pk_bf16_f32 v67, v68, v69
	v_or_b32_e32 v68, v70, v99
	v_ashrrev_i32_e32 v69, 31, v68
	v_lshlrev_b64 v[68:69], 11, v[68:69]
	v_lshl_add_u64 v[68:69], v[0:1], 0, v[68:69]
	flat_store_dwordx2 v[68:69], v[66:67]
	ds_read_b128 v[66:69], v98 offset:1088
	s_waitcnt lgkmcnt(0)
	v_mul_f32_e32 v66, 0xbfb8aa3b, v66
	v_mul_f32_e32 v67, 0xbfb8aa3b, v67
	v_mul_f32_e32 v68, 0xbfb8aa3b, v68
	v_mul_f32_e32 v69, 0xbfb8aa3b, v69
	v_exp_f32_e32 v66, v66
	v_exp_f32_e32 v67, v67
	v_exp_f32_e32 v68, v68
	v_exp_f32_e32 v69, v69
	v_add_f32_e32 v66, 1.0, v66
	v_add_f32_e32 v67, 1.0, v67
	v_add_f32_e32 v68, 1.0, v68
	v_add_f32_e32 v69, 1.0, v69
	v_rcp_f32_e32 v66, v66
	v_rcp_f32_e32 v67, v67
	v_rcp_f32_e32 v68, v68
	v_rcp_f32_e32 v69, v69
	v_cvt_pk_bf16_f32 v66, v66, v67
	v_cvt_pk_bf16_f32 v67, v68, v69
	v_or_b32_e32 v68, v70, v102
	v_ashrrev_i32_e32 v69, 31, v68
	v_lshlrev_b64 v[68:69], 11, v[68:69]
	v_lshl_add_u64 v[68:69], v[0:1], 0, v[68:69]
	flat_store_dwordx2 v[68:69], v[66:67]
	ds_read_b128 v[66:69], v98 offset:2176
	s_waitcnt lgkmcnt(0)
	v_mul_f32_e32 v66, 0xbfb8aa3b, v66
	v_mul_f32_e32 v67, 0xbfb8aa3b, v67
	v_mul_f32_e32 v68, 0xbfb8aa3b, v68
	v_mul_f32_e32 v69, 0xbfb8aa3b, v69
	v_exp_f32_e32 v66, v66
	v_exp_f32_e32 v67, v67
	v_exp_f32_e32 v68, v68
	v_exp_f32_e32 v69, v69
	v_add_f32_e32 v66, 1.0, v66
	v_add_f32_e32 v67, 1.0, v67
	v_add_f32_e32 v68, 1.0, v68
	v_add_f32_e32 v69, 1.0, v69
	v_rcp_f32_e32 v66, v66
	v_rcp_f32_e32 v67, v67
	v_rcp_f32_e32 v68, v68
	v_rcp_f32_e32 v69, v69
	v_cvt_pk_bf16_f32 v66, v66, v67
	v_cvt_pk_bf16_f32 v67, v68, v69
	v_or_b32_e32 v68, v70, v103
	v_ashrrev_i32_e32 v69, 31, v68
	v_lshlrev_b64 v[68:69], 11, v[68:69]
	v_lshl_add_u64 v[68:69], v[0:1], 0, v[68:69]
	flat_store_dwordx2 v[68:69], v[66:67]
	ds_read_b128 v[66:69], v98 offset:3264
	s_waitcnt lgkmcnt(0)
	v_mul_f32_e32 v66, 0xbfb8aa3b, v66
	v_mul_f32_e32 v67, 0xbfb8aa3b, v67
	v_mul_f32_e32 v68, 0xbfb8aa3b, v68
	v_mul_f32_e32 v69, 0xbfb8aa3b, v69
	v_exp_f32_e32 v66, v66
	v_exp_f32_e32 v67, v67
	v_exp_f32_e32 v68, v68
	v_exp_f32_e32 v69, v69
	v_add_f32_e32 v66, 1.0, v66
	v_add_f32_e32 v67, 1.0, v67
	v_add_f32_e32 v68, 1.0, v68
	v_add_f32_e32 v69, 1.0, v69
	v_rcp_f32_e32 v66, v66
	v_rcp_f32_e32 v67, v67
	v_rcp_f32_e32 v68, v68
	v_rcp_f32_e32 v69, v69
	v_cvt_pk_bf16_f32 v66, v66, v67
	v_cvt_pk_bf16_f32 v67, v68, v69
	v_or_b32_e32 v68, v70, v104
	v_ashrrev_i32_e32 v69, 31, v68
	v_lshlrev_b64 v[68:69], 11, v[68:69]
	v_lshl_add_u64 v[68:69], v[0:1], 0, v[68:69]
	flat_store_dwordx2 v[68:69], v[66:67]
	ds_read_b128 v[66:69], v98 offset:4352
	s_waitcnt lgkmcnt(0)
	v_mul_f32_e32 v66, 0xbfb8aa3b, v66
	v_mul_f32_e32 v67, 0xbfb8aa3b, v67
	v_mul_f32_e32 v68, 0xbfb8aa3b, v68
	v_mul_f32_e32 v69, 0xbfb8aa3b, v69
	v_exp_f32_e32 v66, v66
	v_exp_f32_e32 v67, v67
	v_exp_f32_e32 v68, v68
	v_exp_f32_e32 v69, v69
	v_add_f32_e32 v66, 1.0, v66
	v_add_f32_e32 v67, 1.0, v67
	v_add_f32_e32 v68, 1.0, v68
	v_add_f32_e32 v69, 1.0, v69
	v_rcp_f32_e32 v66, v66
	v_rcp_f32_e32 v67, v67
	v_rcp_f32_e32 v68, v68
	v_rcp_f32_e32 v69, v69
	v_cvt_pk_bf16_f32 v66, v66, v67
	v_cvt_pk_bf16_f32 v67, v68, v69
	v_or_b32_e32 v68, v70, v105
	v_ashrrev_i32_e32 v69, 31, v68
	v_lshlrev_b64 v[68:69], 11, v[68:69]
	v_lshl_add_u64 v[68:69], v[0:1], 0, v[68:69]
	flat_store_dwordx2 v[68:69], v[66:67]
	ds_read_b128 v[66:69], v98 offset:5440
	s_waitcnt lgkmcnt(0)
	v_mul_f32_e32 v66, 0xbfb8aa3b, v66
	v_mul_f32_e32 v67, 0xbfb8aa3b, v67
	v_mul_f32_e32 v68, 0xbfb8aa3b, v68
	v_mul_f32_e32 v69, 0xbfb8aa3b, v69
	v_exp_f32_e32 v66, v66
	v_exp_f32_e32 v67, v67
	v_exp_f32_e32 v68, v68
	v_exp_f32_e32 v69, v69
	v_add_f32_e32 v66, 1.0, v66
	v_add_f32_e32 v67, 1.0, v67
	v_add_f32_e32 v68, 1.0, v68
	v_add_f32_e32 v69, 1.0, v69
	v_rcp_f32_e32 v66, v66
	v_rcp_f32_e32 v67, v67
	v_rcp_f32_e32 v68, v68
	v_rcp_f32_e32 v69, v69
	v_cvt_pk_bf16_f32 v66, v66, v67
	v_cvt_pk_bf16_f32 v67, v68, v69
	v_or_b32_e32 v68, v70, v106
	v_ashrrev_i32_e32 v69, 31, v68
	v_lshlrev_b64 v[68:69], 11, v[68:69]
	v_lshl_add_u64 v[68:69], v[0:1], 0, v[68:69]
	flat_store_dwordx2 v[68:69], v[66:67]
	ds_read_b128 v[66:69], v98 offset:6528
	s_waitcnt lgkmcnt(0)
	v_mul_f32_e32 v66, 0xbfb8aa3b, v66
	v_mul_f32_e32 v67, 0xbfb8aa3b, v67
	v_mul_f32_e32 v68, 0xbfb8aa3b, v68
	v_mul_f32_e32 v69, 0xbfb8aa3b, v69
	v_exp_f32_e32 v66, v66
	v_exp_f32_e32 v67, v67
	v_exp_f32_e32 v68, v68
	v_exp_f32_e32 v69, v69
	v_add_f32_e32 v66, 1.0, v66
	v_add_f32_e32 v67, 1.0, v67
	v_add_f32_e32 v68, 1.0, v68
	v_add_f32_e32 v69, 1.0, v69
	v_rcp_f32_e32 v66, v66
	v_rcp_f32_e32 v67, v67
	v_rcp_f32_e32 v68, v68
	v_rcp_f32_e32 v69, v69
	v_cvt_pk_bf16_f32 v66, v66, v67
	v_cvt_pk_bf16_f32 v67, v68, v69
	v_or_b32_e32 v68, v70, v107
	v_ashrrev_i32_e32 v69, 31, v68
	v_lshlrev_b64 v[68:69], 11, v[68:69]
	v_lshl_add_u64 v[68:69], v[0:1], 0, v[68:69]
	flat_store_dwordx2 v[68:69], v[66:67]
	ds_read_b128 v[66:69], v98 offset:7616
	s_waitcnt lgkmcnt(0)
	v_mul_f32_e32 v66, 0xbfb8aa3b, v66
	v_mul_f32_e32 v67, 0xbfb8aa3b, v67
	v_mul_f32_e32 v68, 0xbfb8aa3b, v68
	v_mul_f32_e32 v69, 0xbfb8aa3b, v69
	v_exp_f32_e32 v66, v66
	v_exp_f32_e32 v67, v67
	v_exp_f32_e32 v68, v68
	v_exp_f32_e32 v69, v69
	v_add_f32_e32 v66, 1.0, v66
	v_add_f32_e32 v67, 1.0, v67
	v_add_f32_e32 v68, 1.0, v68
	v_add_f32_e32 v69, 1.0, v69
	v_rcp_f32_e32 v66, v66
	v_rcp_f32_e32 v67, v67
	v_rcp_f32_e32 v68, v68
	v_rcp_f32_e32 v69, v69
	v_cvt_pk_bf16_f32 v66, v66, v67
	v_cvt_pk_bf16_f32 v67, v68, v69
	v_or_b32_e32 v68, v70, v108
	v_ashrrev_i32_e32 v69, 31, v68
	v_lshlrev_b64 v[68:69], 11, v[68:69]
	v_lshl_add_u64 v[68:69], v[0:1], 0, v[68:69]
	flat_store_dwordx2 v[68:69], v[66:67]
	ds_write_b128 v101, v[34:37]
	ds_write_b128 v101, v[38:41] offset:64
	ds_write_b128 v101, v[42:45] offset:128
	ds_write_b128 v101, v[46:49] offset:192
	ds_write_b128 v101, v[50:53] offset:4352
	ds_write_b128 v101, v[54:57] offset:4416
	ds_write_b128 v101, v[58:61] offset:4480
	ds_write_b128 v101, v[62:65] offset:4544
	ds_read_b128 v[34:37], v98
	v_or_b32_e32 v38, 64, v100
	s_waitcnt lgkmcnt(0)
	v_mul_f32_e32 v34, 0xbfb8aa3b, v34
	v_mul_f32_e32 v35, 0xbfb8aa3b, v35
	v_mul_f32_e32 v36, 0xbfb8aa3b, v36
	v_mul_f32_e32 v37, 0xbfb8aa3b, v37
	v_exp_f32_e32 v34, v34
	v_exp_f32_e32 v35, v35
	v_exp_f32_e32 v36, v36
	v_exp_f32_e32 v37, v37
	v_add_f32_e32 v34, 1.0, v34
	v_add_f32_e32 v35, 1.0, v35
	v_add_f32_e32 v36, 1.0, v36
	v_add_f32_e32 v37, 1.0, v37
	v_rcp_f32_e32 v34, v34
	v_rcp_f32_e32 v35, v35
	v_rcp_f32_e32 v36, v36
	v_rcp_f32_e32 v37, v37
	v_cvt_pk_bf16_f32 v34, v34, v35
	v_cvt_pk_bf16_f32 v35, v36, v37
	v_or_b32_e32 v36, v38, v99
	v_ashrrev_i32_e32 v37, 31, v36
	v_lshlrev_b64 v[36:37], 11, v[36:37]
	v_lshl_add_u64 v[36:37], v[0:1], 0, v[36:37]
	flat_store_dwordx2 v[36:37], v[34:35]
	ds_read_b128 v[34:37], v98 offset:1088
	s_waitcnt lgkmcnt(0)
	v_mul_f32_e32 v34, 0xbfb8aa3b, v34
	v_mul_f32_e32 v35, 0xbfb8aa3b, v35
	v_mul_f32_e32 v36, 0xbfb8aa3b, v36
	v_mul_f32_e32 v37, 0xbfb8aa3b, v37
	v_exp_f32_e32 v34, v34
	v_exp_f32_e32 v35, v35
	v_exp_f32_e32 v36, v36
	v_exp_f32_e32 v37, v37
	v_add_f32_e32 v34, 1.0, v34
	v_add_f32_e32 v35, 1.0, v35
	v_add_f32_e32 v36, 1.0, v36
	v_add_f32_e32 v37, 1.0, v37
	v_rcp_f32_e32 v34, v34
	v_rcp_f32_e32 v35, v35
	v_rcp_f32_e32 v36, v36
	v_rcp_f32_e32 v37, v37
	v_cvt_pk_bf16_f32 v34, v34, v35
	v_cvt_pk_bf16_f32 v35, v36, v37
	v_or_b32_e32 v36, v38, v102
	v_ashrrev_i32_e32 v37, 31, v36
	v_lshlrev_b64 v[36:37], 11, v[36:37]
	v_lshl_add_u64 v[36:37], v[0:1], 0, v[36:37]
	flat_store_dwordx2 v[36:37], v[34:35]
	ds_read_b128 v[34:37], v98 offset:2176
	s_waitcnt lgkmcnt(0)
	v_mul_f32_e32 v34, 0xbfb8aa3b, v34
	v_mul_f32_e32 v35, 0xbfb8aa3b, v35
	v_mul_f32_e32 v36, 0xbfb8aa3b, v36
	v_mul_f32_e32 v37, 0xbfb8aa3b, v37
	v_exp_f32_e32 v34, v34
	v_exp_f32_e32 v35, v35
	v_exp_f32_e32 v36, v36
	v_exp_f32_e32 v37, v37
	v_add_f32_e32 v34, 1.0, v34
	v_add_f32_e32 v35, 1.0, v35
	v_add_f32_e32 v36, 1.0, v36
	v_add_f32_e32 v37, 1.0, v37
	v_rcp_f32_e32 v34, v34
	v_rcp_f32_e32 v35, v35
	v_rcp_f32_e32 v36, v36
	v_rcp_f32_e32 v37, v37
	v_cvt_pk_bf16_f32 v34, v34, v35
	v_cvt_pk_bf16_f32 v35, v36, v37
	v_or_b32_e32 v36, v38, v103
	v_ashrrev_i32_e32 v37, 31, v36
	v_lshlrev_b64 v[36:37], 11, v[36:37]
	v_lshl_add_u64 v[36:37], v[0:1], 0, v[36:37]
	flat_store_dwordx2 v[36:37], v[34:35]
	ds_read_b128 v[34:37], v98 offset:3264
	s_waitcnt lgkmcnt(0)
	v_mul_f32_e32 v34, 0xbfb8aa3b, v34
	v_mul_f32_e32 v35, 0xbfb8aa3b, v35
	v_mul_f32_e32 v36, 0xbfb8aa3b, v36
	v_mul_f32_e32 v37, 0xbfb8aa3b, v37
	v_exp_f32_e32 v34, v34
	v_exp_f32_e32 v35, v35
	v_exp_f32_e32 v36, v36
	v_exp_f32_e32 v37, v37
	v_add_f32_e32 v34, 1.0, v34
	v_add_f32_e32 v35, 1.0, v35
	v_add_f32_e32 v36, 1.0, v36
	v_add_f32_e32 v37, 1.0, v37
	v_rcp_f32_e32 v34, v34
	v_rcp_f32_e32 v35, v35
	v_rcp_f32_e32 v36, v36
	v_rcp_f32_e32 v37, v37
	v_cvt_pk_bf16_f32 v34, v34, v35
	v_cvt_pk_bf16_f32 v35, v36, v37
	v_or_b32_e32 v36, v38, v104
	v_ashrrev_i32_e32 v37, 31, v36
	v_lshlrev_b64 v[36:37], 11, v[36:37]
	v_lshl_add_u64 v[36:37], v[0:1], 0, v[36:37]
	flat_store_dwordx2 v[36:37], v[34:35]
	ds_read_b128 v[34:37], v98 offset:4352
	s_waitcnt lgkmcnt(0)
	v_mul_f32_e32 v34, 0xbfb8aa3b, v34
	v_mul_f32_e32 v35, 0xbfb8aa3b, v35
	v_mul_f32_e32 v36, 0xbfb8aa3b, v36
	v_mul_f32_e32 v37, 0xbfb8aa3b, v37
	v_exp_f32_e32 v34, v34
	v_exp_f32_e32 v35, v35
	v_exp_f32_e32 v36, v36
	v_exp_f32_e32 v37, v37
	v_add_f32_e32 v34, 1.0, v34
	v_add_f32_e32 v35, 1.0, v35
	v_add_f32_e32 v36, 1.0, v36
	v_add_f32_e32 v37, 1.0, v37
	v_rcp_f32_e32 v34, v34
	v_rcp_f32_e32 v35, v35
	v_rcp_f32_e32 v36, v36
	v_rcp_f32_e32 v37, v37
	v_cvt_pk_bf16_f32 v34, v34, v35
	v_cvt_pk_bf16_f32 v35, v36, v37
	v_or_b32_e32 v36, v38, v105
	v_ashrrev_i32_e32 v37, 31, v36
	v_lshlrev_b64 v[36:37], 11, v[36:37]
	v_lshl_add_u64 v[36:37], v[0:1], 0, v[36:37]
	flat_store_dwordx2 v[36:37], v[34:35]
	ds_read_b128 v[34:37], v98 offset:5440
	s_waitcnt lgkmcnt(0)
	v_mul_f32_e32 v34, 0xbfb8aa3b, v34
	v_mul_f32_e32 v35, 0xbfb8aa3b, v35
	v_mul_f32_e32 v36, 0xbfb8aa3b, v36
	v_mul_f32_e32 v37, 0xbfb8aa3b, v37
	v_exp_f32_e32 v34, v34
	v_exp_f32_e32 v35, v35
	v_exp_f32_e32 v36, v36
	v_exp_f32_e32 v37, v37
	v_add_f32_e32 v34, 1.0, v34
	v_add_f32_e32 v35, 1.0, v35
	v_add_f32_e32 v36, 1.0, v36
	v_add_f32_e32 v37, 1.0, v37
	v_rcp_f32_e32 v34, v34
	v_rcp_f32_e32 v35, v35
	v_rcp_f32_e32 v36, v36
	v_rcp_f32_e32 v37, v37
	v_cvt_pk_bf16_f32 v34, v34, v35
	v_cvt_pk_bf16_f32 v35, v36, v37
	v_or_b32_e32 v36, v38, v106
	v_ashrrev_i32_e32 v37, 31, v36
	v_lshlrev_b64 v[36:37], 11, v[36:37]
	v_lshl_add_u64 v[36:37], v[0:1], 0, v[36:37]
	flat_store_dwordx2 v[36:37], v[34:35]
	ds_read_b128 v[34:37], v98 offset:6528
	s_waitcnt lgkmcnt(0)
	v_mul_f32_e32 v34, 0xbfb8aa3b, v34
	v_mul_f32_e32 v35, 0xbfb8aa3b, v35
	v_mul_f32_e32 v36, 0xbfb8aa3b, v36
	v_mul_f32_e32 v37, 0xbfb8aa3b, v37
	v_exp_f32_e32 v34, v34
	v_exp_f32_e32 v35, v35
	v_exp_f32_e32 v36, v36
	v_exp_f32_e32 v37, v37
	v_add_f32_e32 v34, 1.0, v34
	v_add_f32_e32 v35, 1.0, v35
	v_add_f32_e32 v36, 1.0, v36
	v_add_f32_e32 v37, 1.0, v37
	v_rcp_f32_e32 v34, v34
	v_rcp_f32_e32 v35, v35
	v_rcp_f32_e32 v36, v36
	v_rcp_f32_e32 v37, v37
	v_cvt_pk_bf16_f32 v34, v34, v35
	v_cvt_pk_bf16_f32 v35, v36, v37
	v_or_b32_e32 v36, v38, v107
	v_ashrrev_i32_e32 v37, 31, v36
	v_lshlrev_b64 v[36:37], 11, v[36:37]
	v_lshl_add_u64 v[36:37], v[0:1], 0, v[36:37]
	flat_store_dwordx2 v[36:37], v[34:35]
	ds_read_b128 v[34:37], v98 offset:7616
	s_waitcnt lgkmcnt(0)
	v_mul_f32_e32 v34, 0xbfb8aa3b, v34
	v_mul_f32_e32 v35, 0xbfb8aa3b, v35
	v_mul_f32_e32 v36, 0xbfb8aa3b, v36
	v_mul_f32_e32 v37, 0xbfb8aa3b, v37
	v_exp_f32_e32 v34, v34
	v_exp_f32_e32 v35, v35
	v_exp_f32_e32 v36, v36
	v_exp_f32_e32 v37, v37
	v_add_f32_e32 v34, 1.0, v34
	v_add_f32_e32 v35, 1.0, v35
	v_add_f32_e32 v36, 1.0, v36
	v_add_f32_e32 v37, 1.0, v37
	v_rcp_f32_e32 v34, v34
	v_rcp_f32_e32 v35, v35
	v_rcp_f32_e32 v36, v36
	v_rcp_f32_e32 v37, v37
	v_cvt_pk_bf16_f32 v34, v34, v35
	v_cvt_pk_bf16_f32 v35, v36, v37
	v_or_b32_e32 v36, v38, v108
	v_ashrrev_i32_e32 v37, 31, v36
	v_lshlrev_b64 v[36:37], 11, v[36:37]
	v_lshl_add_u64 v[36:37], v[0:1], 0, v[36:37]
	flat_store_dwordx2 v[36:37], v[34:35]
	ds_write_b128 v101, v[2:5]
	ds_write_b128 v101, v[6:9] offset:64
	ds_write_b128 v101, v[10:13] offset:128
	ds_write_b128 v101, v[14:17] offset:192
	ds_write_b128 v101, v[18:21] offset:4352
	ds_write_b128 v101, v[22:25] offset:4416
	ds_write_b128 v101, v[26:29] offset:4480
	ds_write_b128 v101, v[30:33] offset:4544
	ds_read_b128 v[2:5], v98
	v_or_b32_e32 v6, 0x60, v100
	v_mov_b32_e32 v20, v132
	v_mov_b32_e32 v7, v131
	v_mov_b32_e32 v11, v131
	s_waitcnt lgkmcnt(0)
	v_mul_f32_e32 v2, 0xbfb8aa3b, v2
	v_mul_f32_e32 v3, 0xbfb8aa3b, v3
	v_mul_f32_e32 v4, 0xbfb8aa3b, v4
	v_mul_f32_e32 v5, 0xbfb8aa3b, v5
	v_exp_f32_e32 v2, v2
	v_exp_f32_e32 v3, v3
	v_exp_f32_e32 v4, v4
	v_exp_f32_e32 v5, v5
	v_add_f32_e32 v2, 1.0, v2
	v_add_f32_e32 v3, 1.0, v3
	v_add_f32_e32 v4, 1.0, v4
	v_add_f32_e32 v5, 1.0, v5
	v_rcp_f32_e32 v2, v2
	v_rcp_f32_e32 v3, v3
	v_rcp_f32_e32 v4, v4
	v_rcp_f32_e32 v5, v5
	v_mov_b32_e32 v19, v131
	v_cvt_pk_bf16_f32 v2, v2, v3
	v_cvt_pk_bf16_f32 v3, v4, v5
	v_or_b32_e32 v4, v6, v99
	v_ashrrev_i32_e32 v5, 31, v4
	v_lshlrev_b64 v[4:5], 11, v[4:5]
	v_lshl_add_u64 v[4:5], v[0:1], 0, v[4:5]
	flat_store_dwordx2 v[4:5], v[2:3]
	ds_read_b128 v[2:5], v98 offset:1088
	s_waitcnt lgkmcnt(0)
	v_mul_f32_e32 v2, 0xbfb8aa3b, v2
	v_mul_f32_e32 v3, 0xbfb8aa3b, v3
	v_mul_f32_e32 v4, 0xbfb8aa3b, v4
	v_mul_f32_e32 v5, 0xbfb8aa3b, v5
	v_exp_f32_e32 v2, v2
	v_exp_f32_e32 v3, v3
	v_exp_f32_e32 v4, v4
	v_exp_f32_e32 v5, v5
	v_add_f32_e32 v2, 1.0, v2
	v_add_f32_e32 v3, 1.0, v3
	v_add_f32_e32 v4, 1.0, v4
	v_add_f32_e32 v5, 1.0, v5
	v_rcp_f32_e32 v2, v2
	v_rcp_f32_e32 v3, v3
	v_rcp_f32_e32 v4, v4
	v_rcp_f32_e32 v5, v5
	v_cvt_pk_bf16_f32 v2, v2, v3
	v_cvt_pk_bf16_f32 v3, v4, v5
	v_or_b32_e32 v4, v6, v102
	v_ashrrev_i32_e32 v5, 31, v4
	v_lshlrev_b64 v[4:5], 11, v[4:5]
	v_lshl_add_u64 v[4:5], v[0:1], 0, v[4:5]
	flat_store_dwordx2 v[4:5], v[2:3]
	ds_read_b128 v[2:5], v98 offset:2176
	s_waitcnt lgkmcnt(0)
	v_mul_f32_e32 v2, 0xbfb8aa3b, v2
	v_mul_f32_e32 v3, 0xbfb8aa3b, v3
	v_mul_f32_e32 v4, 0xbfb8aa3b, v4
	v_mul_f32_e32 v5, 0xbfb8aa3b, v5
	v_exp_f32_e32 v2, v2
	v_exp_f32_e32 v3, v3
	v_exp_f32_e32 v4, v4
	v_exp_f32_e32 v5, v5
	v_add_f32_e32 v2, 1.0, v2
	v_add_f32_e32 v3, 1.0, v3
	v_add_f32_e32 v4, 1.0, v4
	v_add_f32_e32 v5, 1.0, v5
	v_rcp_f32_e32 v2, v2
	v_rcp_f32_e32 v3, v3
	v_rcp_f32_e32 v4, v4
	v_rcp_f32_e32 v5, v5
	v_cvt_pk_bf16_f32 v2, v2, v3
	v_cvt_pk_bf16_f32 v3, v4, v5
	v_or_b32_e32 v4, v6, v103
	v_ashrrev_i32_e32 v5, 31, v4
	v_lshlrev_b64 v[4:5], 11, v[4:5]
	v_lshl_add_u64 v[4:5], v[0:1], 0, v[4:5]
	flat_store_dwordx2 v[4:5], v[2:3]
	ds_read_b128 v[2:5], v98 offset:3264
	s_waitcnt lgkmcnt(0)
	v_mul_f32_e32 v2, 0xbfb8aa3b, v2
	v_mul_f32_e32 v3, 0xbfb8aa3b, v3
	v_mul_f32_e32 v4, 0xbfb8aa3b, v4
	v_mul_f32_e32 v5, 0xbfb8aa3b, v5
	v_exp_f32_e32 v2, v2
	v_exp_f32_e32 v3, v3
	v_exp_f32_e32 v4, v4
	v_exp_f32_e32 v5, v5
	v_add_f32_e32 v2, 1.0, v2
	v_add_f32_e32 v3, 1.0, v3
	v_add_f32_e32 v4, 1.0, v4
	v_add_f32_e32 v5, 1.0, v5
	v_rcp_f32_e32 v2, v2
	v_rcp_f32_e32 v3, v3
	v_rcp_f32_e32 v4, v4
	v_rcp_f32_e32 v5, v5
	v_cvt_pk_bf16_f32 v2, v2, v3
	v_cvt_pk_bf16_f32 v3, v4, v5
	v_or_b32_e32 v4, v6, v104
	v_ashrrev_i32_e32 v5, 31, v4
	v_lshlrev_b64 v[4:5], 11, v[4:5]
	v_lshl_add_u64 v[4:5], v[0:1], 0, v[4:5]
	flat_store_dwordx2 v[4:5], v[2:3]
	ds_read_b128 v[2:5], v98 offset:4352
	s_waitcnt lgkmcnt(0)
	v_mul_f32_e32 v2, 0xbfb8aa3b, v2
	v_mul_f32_e32 v3, 0xbfb8aa3b, v3
	v_mul_f32_e32 v4, 0xbfb8aa3b, v4
	v_mul_f32_e32 v5, 0xbfb8aa3b, v5
	v_exp_f32_e32 v2, v2
	v_exp_f32_e32 v3, v3
	v_exp_f32_e32 v4, v4
	v_exp_f32_e32 v5, v5
	v_add_f32_e32 v2, 1.0, v2
	v_add_f32_e32 v3, 1.0, v3
	v_add_f32_e32 v4, 1.0, v4
	v_add_f32_e32 v5, 1.0, v5
	v_rcp_f32_e32 v2, v2
	v_rcp_f32_e32 v3, v3
	v_rcp_f32_e32 v4, v4
	v_rcp_f32_e32 v5, v5
	v_cvt_pk_bf16_f32 v2, v2, v3
	v_cvt_pk_bf16_f32 v3, v4, v5
	v_or_b32_e32 v4, v6, v105
	v_ashrrev_i32_e32 v5, 31, v4
	v_lshlrev_b64 v[4:5], 11, v[4:5]
	v_lshl_add_u64 v[4:5], v[0:1], 0, v[4:5]
	flat_store_dwordx2 v[4:5], v[2:3]
	ds_read_b128 v[2:5], v98 offset:5440
	s_waitcnt lgkmcnt(0)
	v_mul_f32_e32 v2, 0xbfb8aa3b, v2
	v_mul_f32_e32 v3, 0xbfb8aa3b, v3
	v_mul_f32_e32 v4, 0xbfb8aa3b, v4
	v_mul_f32_e32 v5, 0xbfb8aa3b, v5
	v_exp_f32_e32 v2, v2
	v_exp_f32_e32 v3, v3
	v_exp_f32_e32 v4, v4
	v_exp_f32_e32 v5, v5
	v_add_f32_e32 v2, 1.0, v2
	v_add_f32_e32 v3, 1.0, v3
	v_add_f32_e32 v4, 1.0, v4
	v_add_f32_e32 v5, 1.0, v5
	v_rcp_f32_e32 v2, v2
	v_rcp_f32_e32 v3, v3
	v_rcp_f32_e32 v4, v4
	v_rcp_f32_e32 v5, v5
	v_cvt_pk_bf16_f32 v2, v2, v3
	v_cvt_pk_bf16_f32 v3, v4, v5
	v_or_b32_e32 v4, v6, v106
	v_ashrrev_i32_e32 v5, 31, v4
	v_lshlrev_b64 v[4:5], 11, v[4:5]
	v_lshl_add_u64 v[4:5], v[0:1], 0, v[4:5]
	flat_store_dwordx2 v[4:5], v[2:3]
	ds_read_b128 v[2:5], v98 offset:6528
	s_waitcnt lgkmcnt(0)
	v_mul_f32_e32 v2, 0xbfb8aa3b, v2
	v_mul_f32_e32 v3, 0xbfb8aa3b, v3
	v_mul_f32_e32 v4, 0xbfb8aa3b, v4
	v_mul_f32_e32 v5, 0xbfb8aa3b, v5
	v_exp_f32_e32 v2, v2
	v_exp_f32_e32 v3, v3
	v_exp_f32_e32 v4, v4
	v_exp_f32_e32 v5, v5
	v_add_f32_e32 v2, 1.0, v2
	v_add_f32_e32 v3, 1.0, v3
	v_add_f32_e32 v4, 1.0, v4
	v_add_f32_e32 v5, 1.0, v5
	v_rcp_f32_e32 v2, v2
	v_rcp_f32_e32 v3, v3
	v_rcp_f32_e32 v4, v4
	v_rcp_f32_e32 v5, v5
	v_cvt_pk_bf16_f32 v2, v2, v3
	v_cvt_pk_bf16_f32 v3, v4, v5
	v_or_b32_e32 v4, v6, v107
	v_ashrrev_i32_e32 v5, 31, v4
	v_lshlrev_b64 v[4:5], 11, v[4:5]
	v_lshl_add_u64 v[4:5], v[0:1], 0, v[4:5]
	flat_store_dwordx2 v[4:5], v[2:3]
	ds_read_b128 v[2:5], v98 offset:7616
	v_mov_b32_e32 v98, v132
	s_waitcnt lgkmcnt(0)
	v_mul_f32_e32 v2, 0xbfb8aa3b, v2
	v_mul_f32_e32 v3, 0xbfb8aa3b, v3
	v_mul_f32_e32 v4, 0xbfb8aa3b, v4
	v_mul_f32_e32 v5, 0xbfb8aa3b, v5
	v_exp_f32_e32 v2, v2
	v_exp_f32_e32 v3, v3
	v_exp_f32_e32 v4, v4
	v_exp_f32_e32 v5, v5
	v_add_f32_e32 v2, 1.0, v2
	v_add_f32_e32 v3, 1.0, v3
	v_add_f32_e32 v4, 1.0, v4
	v_add_f32_e32 v5, 1.0, v5
	v_rcp_f32_e32 v2, v2
	v_rcp_f32_e32 v3, v3
	v_rcp_f32_e32 v4, v4
	v_rcp_f32_e32 v5, v5
	v_cvt_pk_bf16_f32 v2, v2, v3
	v_cvt_pk_bf16_f32 v3, v4, v5
	v_or_b32_e32 v4, v6, v108
	v_ashrrev_i32_e32 v5, 31, v4
	v_lshlrev_b64 v[4:5], 11, v[4:5]
	v_lshl_add_u64 v[0:1], v[0:1], 0, v[4:5]
	flat_store_dwordx2 v[0:1], v[2:3]
	v_mov_b32_e32 v0, s3
	ds_read_b128 v[0:3], v0
	s_waitcnt lgkmcnt(0)
	v_lshl_add_u64 v[4:5], v[2:3], 0, s[42:43]
	s_lshl_b64 s[42:43], s[30:31], 10
	v_lshl_add_u64 v[2:3], v[2:3], 0, s[42:43]
	v_lshl_add_u64 v[16:17], v[2:3], 0, s[12:13]
	v_lshlrev_b32_e32 v2, 4, v20
	v_and_b32_e32 v3, 32, v20
	v_bitop3_b32 v3, v2, v3, 48 bitop3:0x6c
	v_lshl_add_u64 v[14:15], v[4:5], 0, s[10:11]
	v_lshrrev_b32_e32 v5, 1, v20
	v_lshrrev_b32_e32 v3, 1, v3
	v_bfe_u32 v4, v20, 2, 4
	v_and_or_b32 v3, v5, 32, v3
	v_lshrrev_b32_e32 v5, 3, v20
	v_and_or_b32 v5, v5, s50, v4
	v_lshl_or_b32 v130, v5, 9, v3
	v_add_u32_e32 v5, 0x2000, v2
	v_lshrrev_b32_e32 v5, 7, v5
	v_and_or_b32 v5, v5, s50, v4
	v_lshl_or_b32 v6, v5, 9, v3
	v_add_u32_e32 v5, 0x4000, v2
	v_and_b32_e32 v21, 0xfffffc00, v2
	v_lshrrev_b32_e32 v5, 7, v5
	v_add_u32_e32 v2, 0x6000, v2
	v_and_or_b32 v5, v5, s50, v4
	v_lshrrev_b32_e32 v2, 7, v2
	v_add_u32_e32 v45, 0, v21
	v_lshl_or_b32 v10, v5, 9, v3
	v_and_or_b32 v2, v2, s50, v4
	v_add_u32_e32 v44, 0x8000, v45
	v_lshlrev_b64 v[4:5], 1, v[130:131]
	v_readfirstlane_b32 s60, v45
	v_lshl_or_b32 v18, v2, 9, v3
	v_lshl_add_u64 v[2:3], v[14:15], 0, v[4:5]
	s_mov_b32 m0, s60
	v_readfirstlane_b32 s58, v44
	v_add_u32_e32 v46, 0x2000, v45
	global_load_lds_dwordx4 v[2:3], off
	v_lshl_add_u64 v[4:5], v[16:17], 0, v[4:5]
	s_mov_b32 m0, s58
	v_lshlrev_b64 v[8:9], 1, v[6:7]
	v_readfirstlane_b32 s59, v46
	v_add_u32_e32 v47, 0xa000, v45
	global_load_lds_dwordx4 v[4:5], off
	v_lshl_add_u64 v[6:7], v[14:15], 0, v[8:9]
	s_mov_b32 m0, s59
	v_readfirstlane_b32 s61, v47
	v_add_u32_e32 v48, 0x4000, v45
	global_load_lds_dwordx4 v[6:7], off
	v_lshl_add_u64 v[8:9], v[16:17], 0, v[8:9]
	s_mov_b32 m0, s61
	v_lshlrev_b64 v[12:13], 1, v[10:11]
	v_readfirstlane_b32 s62, v48
	v_add_u32_e32 v49, 0xc000, v45
	v_lshlrev_b64 v[18:19], 1, v[18:19]
	v_and_b32_e32 v22, 15, v20
	global_load_lds_dwordx4 v[8:9], off
	v_lshl_add_u64 v[10:11], v[14:15], 0, v[12:13]
	s_mov_b32 m0, s62
	v_lshl_add_u64 v[12:13], v[16:17], 0, v[12:13]
	v_readfirstlane_b32 s63, v49
	v_lshl_add_u64 v[14:15], v[14:15], 0, v[18:19]
	v_add_u32_e32 v50, 0x6000, v45
	v_lshl_add_u64 v[16:17], v[16:17], 0, v[18:19]
	v_lshlrev_b32_e32 v19, 2, v20
	global_load_lds_dwordx4 v[10:11], off
	s_mov_b32 m0, s63
	v_readfirstlane_b32 s64, v50
	v_add_u32_e32 v51, 0xe000, v45
	v_and_b32_e32 v23, 48, v20
	v_lshlrev_b32_e32 v18, 6, v22
	v_and_b32_e32 v22, 32, v19
	global_load_lds_dwordx4 v[12:13], off
	s_mov_b32 m0, s64
	v_readfirstlane_b32 s65, v51
	v_bitop3_b32 v96, v18, v22, v23 bitop3:0x36
	v_lshlrev_b32_e32 v18, 7, v20
	v_add_u32_e32 v37, s46, v21
	global_load_lds_dwordx4 v[14:15], off
	s_mov_b32 m0, s65
	v_and_b32_e32 v97, 0x6000, v18
	v_lshlrev_b32_e32 v18, 6, v20
	v_add_u32_e32 v36, s47, v21
	v_readfirstlane_b32 s53, v37
	global_load_lds_dwordx4 v[16:17], off
	v_and_b32_e32 v99, 0xffffc000, v18
	v_and_b32_e32 v20, 0x3c0, v18
	v_lshl_add_u64 v[18:19], v[2:3], 0, s[6:7]
	s_mov_b32 m0, s53
	v_readfirstlane_b32 s0, v36
	v_add_u32_e32 v38, 0x2000, v37
	s_waitcnt vmcnt(0)
	s_waitcnt vmcnt(0) lgkmcnt(0)
	s_barrier
	global_load_lds_dwordx4 v[18:19], off
	v_lshl_add_u64 v[18:19], v[4:5], 0, s[6:7]
	s_mov_b32 m0, s0
	v_readfirstlane_b32 s42, v38
	v_add_u32_e32 v39, 0x2000, v36
	global_load_lds_dwordx4 v[18:19], off
	v_lshl_add_u64 v[18:19], v[6:7], 0, s[6:7]
	s_mov_b32 m0, s42
	v_readfirstlane_b32 s43, v39
	v_add_u32_e32 v40, 0x4000, v37
	global_load_lds_dwordx4 v[18:19], off
	v_lshl_add_u64 v[18:19], v[8:9], 0, s[6:7]
	s_mov_b32 m0, s43
	v_readfirstlane_b32 s54, v40
	v_add_u32_e32 v41, 0x4000, v36
	global_load_lds_dwordx4 v[18:19], off
	v_lshl_add_u64 v[18:19], v[10:11], 0, s[6:7]
	s_mov_b32 m0, s54
	v_readfirstlane_b32 s55, v41
	v_add_u32_e32 v42, 0x6000, v37
	global_load_lds_dwordx4 v[18:19], off
	v_lshl_add_u64 v[18:19], v[12:13], 0, s[6:7]
	s_mov_b32 m0, s55
	v_readfirstlane_b32 s56, v42
	v_add_u32_e32 v43, 0x6000, v36
	global_load_lds_dwordx4 v[18:19], off
	v_lshl_add_u64 v[18:19], v[14:15], 0, s[6:7]
	s_mov_b32 m0, s56
	v_readfirstlane_b32 s57, v43
	global_load_lds_dwordx4 v[18:19], off
	v_lshl_add_u64 v[18:19], v[16:17], 0, s[6:7]
	s_mov_b32 m0, s57
	v_add_u32_e32 v129, 0, v96
	global_load_lds_dwordx4 v[18:19], off
	v_add_u32_e32 v18, v129, v97
	ds_read_b128 v[24:27], v18 offset:32768
	ds_read_b128 v[56:59], v18 offset:34816
	ds_read_b128 v[64:67], v18 offset:36864
	ds_read_b128 v[72:75], v18 offset:38912
	v_bitop3_b32 v130, v20, v22, v23 bitop3:0x36
	v_add_u32_e32 v23, 0, v130
	v_or_b32_e32 v222, 0x3000, v99
	v_add_u32_e32 v20, v23, v222
	ds_read_b128 v[32:35], v20
	v_or_b32_e32 v223, 0x2800, v99
	v_add_u32_e32 v21, v23, v223
	s_waitcnt lgkmcnt(0)
	v_mfma_f32_16x16x32_bf16 v[76:79], v[24:27], v[32:35], 0
	v_or_b32_e32 v128, 0x3800, v99
	v_or_b32_e32 v218, 0x2000, v99
	v_or_b32_e32 v219, 0x1000, v99
	v_mfma_f32_16x16x32_bf16 v[80:83], v[56:59], v[32:35], 0
	v_or_b32_e32 v220, 0x1800, v99
	v_add_u32_e32 v19, v23, v128
	v_add_u32_e32 v22, v23, v218
	v_mfma_f32_16x16x32_bf16 v[84:87], v[64:67], v[32:35], 0
	ds_read_b128 v[28:31], v19
	ds_read_b128 v[112:115], v22
	v_mfma_f32_16x16x32_bf16 v[88:91], v[72:75], v[32:35], 0
	ds_read_b128 v[32:35], v21
	s_waitcnt lgkmcnt(0)
	v_mfma_f32_16x16x32_bf16 v[92:95], v[24:27], v[32:35], 0
	v_mfma_f32_16x16x32_bf16 v[100:103], v[56:59], v[32:35], 0
	v_mfma_f32_16x16x32_bf16 v[104:107], v[64:67], v[32:35], 0
	v_mfma_f32_16x16x32_bf16 v[108:111], v[72:75], v[32:35], 0
	v_add_u32_e32 v32, v129, v99
	v_or_b32_e32 v129, 0x800, v99
	v_add_u32_e32 v33, v23, v129
	v_add_u32_e32 v34, v23, v219
	v_add_u32_e32 v35, v23, v220
	ds_read_b128 v[134:137], v32
	ds_read_b128 v[150:153], v33
	ds_read_b128 v[166:169], v34
	ds_read_b128 v[182:185], v35
	s_waitcnt lgkmcnt(0)
	v_mfma_f32_16x16x32_bf16 v[178:181], v[64:67], v[166:169], 0
	v_mfma_f32_16x16x32_bf16 v[162:165], v[64:67], v[150:153], 0
	v_mfma_f32_16x16x32_bf16 v[146:149], v[64:67], v[134:137], 0
	v_mfma_f32_16x16x32_bf16 v[68:71], v[64:67], v[28:31], 0
	v_mfma_f32_16x16x32_bf16 v[124:127], v[64:67], v[112:115], 0
	v_mfma_f32_16x16x32_bf16 v[64:67], v[64:67], v[182:185], 0
	v_mfma_f32_16x16x32_bf16 v[174:177], v[56:59], v[166:169], 0
	v_mfma_f32_16x16x32_bf16 v[158:161], v[56:59], v[150:153], 0
	v_mfma_f32_16x16x32_bf16 v[142:145], v[56:59], v[134:137], 0
	v_mfma_f32_16x16x32_bf16 v[60:63], v[56:59], v[28:31], 0
	v_mfma_f32_16x16x32_bf16 v[120:123], v[56:59], v[112:115], 0
	v_mfma_f32_16x16x32_bf16 v[56:59], v[56:59], v[182:185], 0
	v_mfma_f32_16x16x32_bf16 v[170:173], v[24:27], v[166:169], 0
	v_mfma_f32_16x16x32_bf16 v[154:157], v[24:27], v[150:153], 0
	v_mfma_f32_16x16x32_bf16 v[138:141], v[24:27], v[134:137], 0
	v_mfma_f32_16x16x32_bf16 v[52:55], v[24:27], v[28:31], 0
	v_mfma_f32_16x16x32_bf16 v[116:119], v[24:27], v[112:115], 0
	v_mfma_f32_16x16x32_bf16 v[24:27], v[24:27], v[182:185], 0
	v_mfma_f32_16x16x32_bf16 v[166:169], v[72:75], v[166:169], 0
	v_mfma_f32_16x16x32_bf16 v[150:153], v[72:75], v[150:153], 0
	v_mfma_f32_16x16x32_bf16 v[134:137], v[72:75], v[134:137], 0
	v_mfma_f32_16x16x32_bf16 v[28:31], v[72:75], v[28:31], 0
	v_mfma_f32_16x16x32_bf16 v[112:115], v[72:75], v[112:115], 0
	v_mfma_f32_16x16x32_bf16 v[72:75], v[72:75], v[182:185], 0
	ds_read_b128 v[182:185], v18 offset:33792
	ds_read_b128 v[186:189], v18 offset:35840
	ds_read_b128 v[190:193], v18 offset:37888
	ds_read_b128 v[198:201], v18 offset:39936
	ds_read_b128 v[194:197], v32 offset:1024
	ds_read_b128 v[202:205], v33 offset:1024
	ds_read_b128 v[206:209], v34 offset:1024
	ds_read_b128 v[210:213], v35 offset:1024
	s_waitcnt lgkmcnt(0)
	v_mfma_f32_16x16x32_bf16 v[138:141], v[182:185], v[194:197], v[138:141]
	v_mfma_f32_16x16x32_bf16 v[142:145], v[186:189], v[194:197], v[142:145]
	v_mfma_f32_16x16x32_bf16 v[146:149], v[190:193], v[194:197], v[146:149]
	v_mfma_f32_16x16x32_bf16 v[134:137], v[198:201], v[194:197], v[134:137]
	ds_read_b128 v[194:197], v22 offset:1024
	v_mfma_f32_16x16x32_bf16 v[154:157], v[182:185], v[202:205], v[154:157]
	v_mfma_f32_16x16x32_bf16 v[158:161], v[186:189], v[202:205], v[158:161]
	v_mfma_f32_16x16x32_bf16 v[162:165], v[190:193], v[202:205], v[162:165]
	v_mfma_f32_16x16x32_bf16 v[150:153], v[198:201], v[202:205], v[150:153]
	ds_read_b128 v[202:205], v21 offset:1024
	v_mfma_f32_16x16x32_bf16 v[170:173], v[182:185], v[206:209], v[170:173]
	v_mfma_f32_16x16x32_bf16 v[174:177], v[186:189], v[206:209], v[174:177]
	v_mfma_f32_16x16x32_bf16 v[178:181], v[190:193], v[206:209], v[178:181]
	v_mfma_f32_16x16x32_bf16 v[166:169], v[198:201], v[206:209], v[166:169]
	ds_read_b128 v[206:209], v20 offset:1024
	v_mfma_f32_16x16x32_bf16 v[214:217], v[182:185], v[210:213], v[24:27]
	v_mfma_f32_16x16x32_bf16 v[56:59], v[186:189], v[210:213], v[56:59]
	v_mfma_f32_16x16x32_bf16 v[64:67], v[190:193], v[210:213], v[64:67]
	v_mfma_f32_16x16x32_bf16 v[72:75], v[198:201], v[210:213], v[72:75]
	ds_read_b128 v[24:27], v19 offset:1024
	s_waitcnt lgkmcnt(0)
	v_mfma_f32_16x16x32_bf16 v[116:119], v[182:185], v[194:197], v[116:119]
	v_mfma_f32_16x16x32_bf16 v[120:123], v[186:189], v[194:197], v[120:123]
	v_mfma_f32_16x16x32_bf16 v[124:127], v[190:193], v[194:197], v[124:127]
	v_mfma_f32_16x16x32_bf16 v[112:115], v[198:201], v[194:197], v[112:115]
	v_mfma_f32_16x16x32_bf16 v[92:95], v[182:185], v[202:205], v[92:95]
	v_mfma_f32_16x16x32_bf16 v[100:103], v[186:189], v[202:205], v[100:103]
	v_mfma_f32_16x16x32_bf16 v[104:107], v[190:193], v[202:205], v[104:107]
	v_mfma_f32_16x16x32_bf16 v[108:111], v[198:201], v[202:205], v[108:111]
	v_mfma_f32_16x16x32_bf16 v[76:79], v[182:185], v[206:209], v[76:79]
	v_mfma_f32_16x16x32_bf16 v[80:83], v[186:189], v[206:209], v[80:83]
	v_mfma_f32_16x16x32_bf16 v[84:87], v[190:193], v[206:209], v[84:87]
	v_mfma_f32_16x16x32_bf16 v[88:91], v[198:201], v[206:209], v[88:91]
	v_mfma_f32_16x16x32_bf16 v[52:55], v[182:185], v[24:27], v[52:55]
	v_mfma_f32_16x16x32_bf16 v[60:63], v[186:189], v[24:27], v[60:63]
	v_mfma_f32_16x16x32_bf16 v[68:71], v[190:193], v[24:27], v[68:71]
	v_mfma_f32_16x16x32_bf16 v[182:185], v[198:201], v[24:27], v[28:31]
	s_mov_b32 m0, s60
	v_lshl_add_u64 v[24:25], v[2:3], 0, s[14:15]
	s_waitcnt vmcnt(0)
	s_waitcnt vmcnt(0)
	s_barrier
	global_load_lds_dwordx4 v[24:25], off
	v_lshl_add_u64 v[24:25], v[4:5], 0, s[14:15]
	s_mov_b32 m0, s58
	v_add3_u32 v23, s47, v96, v97
	global_load_lds_dwordx4 v[24:25], off
	v_lshl_add_u64 v[24:25], v[6:7], 0, s[14:15]
	s_mov_b32 m0, s59
	s_nop 0
	global_load_lds_dwordx4 v[24:25], off
	v_lshl_add_u64 v[24:25], v[8:9], 0, s[14:15]
	s_mov_b32 m0, s61
	s_nop 0
	global_load_lds_dwordx4 v[24:25], off
	v_lshl_add_u64 v[24:25], v[10:11], 0, s[14:15]
	s_mov_b32 m0, s62
	s_nop 0
	global_load_lds_dwordx4 v[24:25], off
	v_lshl_add_u64 v[24:25], v[12:13], 0, s[14:15]
	s_mov_b32 m0, s63
	s_nop 0
	global_load_lds_dwordx4 v[24:25], off
	v_lshl_add_u64 v[24:25], v[14:15], 0, s[14:15]
	s_mov_b32 m0, s64
	s_nop 0
	global_load_lds_dwordx4 v[24:25], off
	v_lshl_add_u64 v[24:25], v[16:17], 0, s[14:15]
	s_mov_b32 m0, s65
	s_nop 0
	global_load_lds_dwordx4 v[24:25], off
	ds_read_b128 v[186:189], v23
	ds_read_b128 v[190:193], v23 offset:2048
	ds_read_b128 v[194:197], v23 offset:4096
	ds_read_b128 v[198:201], v23 offset:6144
	v_add3_u32 v24, s46, v96, v99
	v_add_u32_e32 v96, s46, v130
	ds_read_b128 v[28:31], v24
	v_add_u32_e32 v25, v96, v129
	v_add_u32_e32 v26, v96, v219
	v_add_u32_e32 v27, v96, v220
	ds_read_b128 v[202:205], v25
	ds_read_b128 v[206:209], v26
	ds_read_b128 v[210:213], v27
	s_waitcnt lgkmcnt(0)
	v_mfma_f32_16x16x32_bf16 v[138:141], v[186:189], v[28:31], v[138:141]
	v_mfma_f32_16x16x32_bf16 v[142:145], v[190:193], v[28:31], v[142:145]
	v_mfma_f32_16x16x32_bf16 v[146:149], v[194:197], v[28:31], v[146:149]
	v_mfma_f32_16x16x32_bf16 v[134:137], v[198:201], v[28:31], v[134:137]
	v_add_u32_e32 v28, v96, v218
	v_add_u32_e32 v29, v96, v223
	v_add_u32_e32 v30, v96, v222
	v_add_u32_e32 v31, v96, v128
	ds_read_b128 v[218:221], v28
	v_mfma_f32_16x16x32_bf16 v[154:157], v[186:189], v[202:205], v[154:157]
	v_mfma_f32_16x16x32_bf16 v[158:161], v[190:193], v[202:205], v[158:161]
	v_mfma_f32_16x16x32_bf16 v[162:165], v[194:197], v[202:205], v[162:165]
	v_mfma_f32_16x16x32_bf16 v[150:153], v[198:201], v[202:205], v[150:153]
	ds_read_b128 v[202:205], v29
	v_mfma_f32_16x16x32_bf16 v[170:173], v[186:189], v[206:209], v[170:173]
	v_mfma_f32_16x16x32_bf16 v[174:177], v[190:193], v[206:209], v[174:177]
	v_mfma_f32_16x16x32_bf16 v[178:181], v[194:197], v[206:209], v[178:181]
	v_mfma_f32_16x16x32_bf16 v[166:169], v[198:201], v[206:209], v[166:169]
	ds_read_b128 v[206:209], v30
	v_mfma_f32_16x16x32_bf16 v[214:217], v[186:189], v[210:213], v[214:217]
	v_mfma_f32_16x16x32_bf16 v[56:59], v[190:193], v[210:213], v[56:59]
	v_mfma_f32_16x16x32_bf16 v[64:67], v[194:197], v[210:213], v[64:67]
	v_mfma_f32_16x16x32_bf16 v[72:75], v[198:201], v[210:213], v[72:75]
	ds_read_b128 v[210:213], v31
	s_waitcnt lgkmcnt(0)
	v_mfma_f32_16x16x32_bf16 v[116:119], v[186:189], v[218:221], v[116:119]
	v_mfma_f32_16x16x32_bf16 v[120:123], v[190:193], v[218:221], v[120:123]
	v_mfma_f32_16x16x32_bf16 v[124:127], v[194:197], v[218:221], v[124:127]
	v_mfma_f32_16x16x32_bf16 v[112:115], v[198:201], v[218:221], v[112:115]
	v_mfma_f32_16x16x32_bf16 v[92:95], v[186:189], v[202:205], v[92:95]
	v_mfma_f32_16x16x32_bf16 v[100:103], v[190:193], v[202:205], v[100:103]
	v_mfma_f32_16x16x32_bf16 v[104:107], v[194:197], v[202:205], v[104:107]
	v_mfma_f32_16x16x32_bf16 v[108:111], v[198:201], v[202:205], v[108:111]
	v_mfma_f32_16x16x32_bf16 v[76:79], v[186:189], v[206:209], v[76:79]
	v_mfma_f32_16x16x32_bf16 v[80:83], v[190:193], v[206:209], v[80:83]
	v_mfma_f32_16x16x32_bf16 v[84:87], v[194:197], v[206:209], v[84:87]
	v_mfma_f32_16x16x32_bf16 v[88:91], v[198:201], v[206:209], v[88:91]
	v_mfma_f32_16x16x32_bf16 v[52:55], v[186:189], v[210:213], v[52:55]
	v_mfma_f32_16x16x32_bf16 v[60:63], v[190:193], v[210:213], v[60:63]
	v_mfma_f32_16x16x32_bf16 v[68:71], v[194:197], v[210:213], v[68:71]
	v_mfma_f32_16x16x32_bf16 v[182:185], v[198:201], v[210:213], v[182:185]
	ds_read_b128 v[186:189], v23 offset:1024
	ds_read_b128 v[190:193], v23 offset:3072
	ds_read_b128 v[194:197], v23 offset:5120
	ds_read_b128 v[202:205], v23 offset:7168
	ds_read_b128 v[198:201], v24 offset:1024
	ds_read_b128 v[206:209], v25 offset:1024
	ds_read_b128 v[210:213], v26 offset:1024
	ds_read_b128 v[218:221], v27 offset:1024
	s_waitcnt lgkmcnt(0)
	v_mfma_f32_16x16x32_bf16 v[138:141], v[186:189], v[198:201], v[138:141]
	v_mfma_f32_16x16x32_bf16 v[142:145], v[190:193], v[198:201], v[142:145]
	v_mfma_f32_16x16x32_bf16 v[146:149], v[194:197], v[198:201], v[146:149]
	v_mfma_f32_16x16x32_bf16 v[134:137], v[202:205], v[198:201], v[134:137]
	ds_read_b128 v[198:201], v28 offset:1024
	v_mfma_f32_16x16x32_bf16 v[154:157], v[186:189], v[206:209], v[154:157]
	v_mfma_f32_16x16x32_bf16 v[158:161], v[190:193], v[206:209], v[158:161]
	v_mfma_f32_16x16x32_bf16 v[162:165], v[194:197], v[206:209], v[162:165]
	v_mfma_f32_16x16x32_bf16 v[150:153], v[202:205], v[206:209], v[150:153]
	ds_read_b128 v[206:209], v29 offset:1024
	v_mfma_f32_16x16x32_bf16 v[170:173], v[186:189], v[210:213], v[170:173]
	v_mfma_f32_16x16x32_bf16 v[174:177], v[190:193], v[210:213], v[174:177]
	v_mfma_f32_16x16x32_bf16 v[178:181], v[194:197], v[210:213], v[178:181]
	v_mfma_f32_16x16x32_bf16 v[166:169], v[202:205], v[210:213], v[166:169]
	ds_read_b128 v[210:213], v30 offset:1024
	v_mfma_f32_16x16x32_bf16 v[214:217], v[186:189], v[218:221], v[214:217]
	v_mfma_f32_16x16x32_bf16 v[56:59], v[190:193], v[218:221], v[56:59]
	v_mfma_f32_16x16x32_bf16 v[64:67], v[194:197], v[218:221], v[64:67]
	v_mfma_f32_16x16x32_bf16 v[72:75], v[202:205], v[218:221], v[72:75]
	ds_read_b128 v[218:221], v31 offset:1024
	s_waitcnt lgkmcnt(0)
	v_mfma_f32_16x16x32_bf16 v[116:119], v[186:189], v[198:201], v[116:119]
	v_mfma_f32_16x16x32_bf16 v[120:123], v[190:193], v[198:201], v[120:123]
	v_mfma_f32_16x16x32_bf16 v[124:127], v[194:197], v[198:201], v[124:127]
	v_mfma_f32_16x16x32_bf16 v[112:115], v[202:205], v[198:201], v[112:115]
	v_mfma_f32_16x16x32_bf16 v[92:95], v[186:189], v[206:209], v[92:95]
	v_mfma_f32_16x16x32_bf16 v[100:103], v[190:193], v[206:209], v[100:103]
	v_mfma_f32_16x16x32_bf16 v[104:107], v[194:197], v[206:209], v[104:107]
	v_mfma_f32_16x16x32_bf16 v[108:111], v[202:205], v[206:209], v[108:111]
	v_mfma_f32_16x16x32_bf16 v[76:79], v[186:189], v[210:213], v[76:79]
	v_mfma_f32_16x16x32_bf16 v[80:83], v[190:193], v[210:213], v[80:83]
	v_mfma_f32_16x16x32_bf16 v[84:87], v[194:197], v[210:213], v[84:87]
	v_mfma_f32_16x16x32_bf16 v[88:91], v[202:205], v[210:213], v[88:91]
	v_mfma_f32_16x16x32_bf16 v[52:55], v[186:189], v[218:221], v[52:55]
	v_mfma_f32_16x16x32_bf16 v[60:63], v[190:193], v[218:221], v[60:63]
	v_mfma_f32_16x16x32_bf16 v[68:71], v[194:197], v[218:221], v[68:71]
	v_mfma_f32_16x16x32_bf16 v[182:185], v[202:205], v[218:221], v[182:185]
	s_mov_b32 m0, s53
	v_lshl_add_u64 v[96:97], v[2:3], 0, s[16:17]
	s_waitcnt vmcnt(0)
	s_waitcnt vmcnt(0)
	s_barrier
	global_load_lds_dwordx4 v[96:97], off
	v_lshl_add_u64 v[96:97], v[4:5], 0, s[16:17]
	s_mov_b32 m0, s0
	s_nop 0
	global_load_lds_dwordx4 v[96:97], off
	v_lshl_add_u64 v[96:97], v[6:7], 0, s[16:17]
	s_mov_b32 m0, s42
	s_nop 0
	global_load_lds_dwordx4 v[96:97], off
	v_lshl_add_u64 v[96:97], v[8:9], 0, s[16:17]
	s_mov_b32 m0, s43
	s_nop 0
	global_load_lds_dwordx4 v[96:97], off
	v_lshl_add_u64 v[96:97], v[10:11], 0, s[16:17]
	s_mov_b32 m0, s54
	s_nop 0
	global_load_lds_dwordx4 v[96:97], off
	v_lshl_add_u64 v[96:97], v[12:13], 0, s[16:17]
	s_mov_b32 m0, s55
	s_nop 0
	global_load_lds_dwordx4 v[96:97], off
	v_lshl_add_u64 v[96:97], v[14:15], 0, s[16:17]
	s_mov_b32 m0, s56
	s_nop 0
	global_load_lds_dwordx4 v[96:97], off
	v_lshl_add_u64 v[96:97], v[16:17], 0, s[16:17]
	s_mov_b32 m0, s57
	s_nop 0
	global_load_lds_dwordx4 v[96:97], off
	ds_read_b128 v[186:189], v18 offset:32768
	ds_read_b128 v[190:193], v18 offset:34816
	ds_read_b128 v[194:197], v18 offset:36864
	ds_read_b128 v[202:205], v18 offset:38912
	ds_read_b128 v[198:201], v32
	ds_read_b128 v[206:209], v33
	ds_read_b128 v[210:213], v34
	ds_read_b128 v[218:221], v35
	s_waitcnt lgkmcnt(0)
	v_mfma_f32_16x16x32_bf16 v[138:141], v[186:189], v[198:201], v[138:141]
	v_mfma_f32_16x16x32_bf16 v[142:145], v[190:193], v[198:201], v[142:145]
	v_mfma_f32_16x16x32_bf16 v[146:149], v[194:197], v[198:201], v[146:149]
	v_mfma_f32_16x16x32_bf16 v[134:137], v[202:205], v[198:201], v[134:137]
	ds_read_b128 v[198:201], v22
	v_mfma_f32_16x16x32_bf16 v[154:157], v[186:189], v[206:209], v[154:157]
	v_mfma_f32_16x16x32_bf16 v[158:161], v[190:193], v[206:209], v[158:161]
	v_mfma_f32_16x16x32_bf16 v[162:165], v[194:197], v[206:209], v[162:165]
	v_mfma_f32_16x16x32_bf16 v[150:153], v[202:205], v[206:209], v[150:153]
	ds_read_b128 v[206:209], v21
	v_mfma_f32_16x16x32_bf16 v[170:173], v[186:189], v[210:213], v[170:173]
	v_mfma_f32_16x16x32_bf16 v[174:177], v[190:193], v[210:213], v[174:177]
	v_mfma_f32_16x16x32_bf16 v[178:181], v[194:197], v[210:213], v[178:181]
	v_mfma_f32_16x16x32_bf16 v[166:169], v[202:205], v[210:213], v[166:169]
	ds_read_b128 v[210:213], v20
	v_mfma_f32_16x16x32_bf16 v[214:217], v[186:189], v[218:221], v[214:217]
	v_mfma_f32_16x16x32_bf16 v[56:59], v[190:193], v[218:221], v[56:59]
	v_mfma_f32_16x16x32_bf16 v[64:67], v[194:197], v[218:221], v[64:67]
	v_mfma_f32_16x16x32_bf16 v[72:75], v[202:205], v[218:221], v[72:75]
	ds_read_b128 v[218:221], v19
	s_waitcnt lgkmcnt(0)
	v_mfma_f32_16x16x32_bf16 v[116:119], v[186:189], v[198:201], v[116:119]
	v_mfma_f32_16x16x32_bf16 v[120:123], v[190:193], v[198:201], v[120:123]
	v_mfma_f32_16x16x32_bf16 v[124:127], v[194:197], v[198:201], v[124:127]
	v_mfma_f32_16x16x32_bf16 v[112:115], v[202:205], v[198:201], v[112:115]
	v_mfma_f32_16x16x32_bf16 v[92:95], v[186:189], v[206:209], v[92:95]
	v_mfma_f32_16x16x32_bf16 v[100:103], v[190:193], v[206:209], v[100:103]
	v_mfma_f32_16x16x32_bf16 v[104:107], v[194:197], v[206:209], v[104:107]
	v_mfma_f32_16x16x32_bf16 v[108:111], v[202:205], v[206:209], v[108:111]
	v_mfma_f32_16x16x32_bf16 v[76:79], v[186:189], v[210:213], v[76:79]
	v_mfma_f32_16x16x32_bf16 v[80:83], v[190:193], v[210:213], v[80:83]
	v_mfma_f32_16x16x32_bf16 v[84:87], v[194:197], v[210:213], v[84:87]
	v_mfma_f32_16x16x32_bf16 v[88:91], v[202:205], v[210:213], v[88:91]
	v_mfma_f32_16x16x32_bf16 v[52:55], v[186:189], v[218:221], v[52:55]
	v_mfma_f32_16x16x32_bf16 v[60:63], v[190:193], v[218:221], v[60:63]
	v_mfma_f32_16x16x32_bf16 v[68:71], v[194:197], v[218:221], v[68:71]
	v_mfma_f32_16x16x32_bf16 v[182:185], v[202:205], v[218:221], v[182:185]
	ds_read_b128 v[186:189], v18 offset:33792
	ds_read_b128 v[190:193], v18 offset:35840
	ds_read_b128 v[194:197], v18 offset:37888
	ds_read_b128 v[202:205], v18 offset:39936
	ds_read_b128 v[198:201], v32 offset:1024
	ds_read_b128 v[206:209], v33 offset:1024
	ds_read_b128 v[210:213], v34 offset:1024
	ds_read_b128 v[218:221], v35 offset:1024
	s_waitcnt lgkmcnt(0)
	v_mfma_f32_16x16x32_bf16 v[138:141], v[186:189], v[198:201], v[138:141]
	v_mfma_f32_16x16x32_bf16 v[142:145], v[190:193], v[198:201], v[142:145]
	v_mfma_f32_16x16x32_bf16 v[146:149], v[194:197], v[198:201], v[146:149]
	v_mfma_f32_16x16x32_bf16 v[134:137], v[202:205], v[198:201], v[134:137]
	ds_read_b128 v[198:201], v22 offset:1024
	v_mfma_f32_16x16x32_bf16 v[154:157], v[186:189], v[206:209], v[154:157]
	v_mfma_f32_16x16x32_bf16 v[158:161], v[190:193], v[206:209], v[158:161]
	v_mfma_f32_16x16x32_bf16 v[162:165], v[194:197], v[206:209], v[162:165]
	v_mfma_f32_16x16x32_bf16 v[150:153], v[202:205], v[206:209], v[150:153]
	ds_read_b128 v[206:209], v21 offset:1024
	v_mfma_f32_16x16x32_bf16 v[170:173], v[186:189], v[210:213], v[170:173]
	v_mfma_f32_16x16x32_bf16 v[174:177], v[190:193], v[210:213], v[174:177]
	v_mfma_f32_16x16x32_bf16 v[178:181], v[194:197], v[210:213], v[178:181]
	v_mfma_f32_16x16x32_bf16 v[166:169], v[202:205], v[210:213], v[166:169]
	ds_read_b128 v[210:213], v20 offset:1024
	v_mfma_f32_16x16x32_bf16 v[214:217], v[186:189], v[218:221], v[214:217]
	v_mfma_f32_16x16x32_bf16 v[56:59], v[190:193], v[218:221], v[56:59]
	v_mfma_f32_16x16x32_bf16 v[64:67], v[194:197], v[218:221], v[64:67]
	v_mfma_f32_16x16x32_bf16 v[72:75], v[202:205], v[218:221], v[72:75]
	ds_read_b128 v[218:221], v19 offset:1024
	s_waitcnt lgkmcnt(0)
	v_mfma_f32_16x16x32_bf16 v[116:119], v[186:189], v[198:201], v[116:119]
	v_mfma_f32_16x16x32_bf16 v[120:123], v[190:193], v[198:201], v[120:123]
	v_mfma_f32_16x16x32_bf16 v[124:127], v[194:197], v[198:201], v[124:127]
	v_mfma_f32_16x16x32_bf16 v[112:115], v[202:205], v[198:201], v[112:115]
	v_mfma_f32_16x16x32_bf16 v[92:95], v[186:189], v[206:209], v[92:95]
	v_mfma_f32_16x16x32_bf16 v[100:103], v[190:193], v[206:209], v[100:103]
	v_mfma_f32_16x16x32_bf16 v[104:107], v[194:197], v[206:209], v[104:107]
	v_mfma_f32_16x16x32_bf16 v[108:111], v[202:205], v[206:209], v[108:111]
	v_mfma_f32_16x16x32_bf16 v[76:79], v[186:189], v[210:213], v[76:79]
	v_mfma_f32_16x16x32_bf16 v[80:83], v[190:193], v[210:213], v[80:83]
	v_mfma_f32_16x16x32_bf16 v[84:87], v[194:197], v[210:213], v[84:87]
	v_mfma_f32_16x16x32_bf16 v[88:91], v[202:205], v[210:213], v[88:91]
	v_mfma_f32_16x16x32_bf16 v[52:55], v[186:189], v[218:221], v[52:55]
	v_mfma_f32_16x16x32_bf16 v[60:63], v[190:193], v[218:221], v[60:63]
	v_mfma_f32_16x16x32_bf16 v[68:71], v[194:197], v[218:221], v[68:71]
	v_mfma_f32_16x16x32_bf16 v[182:185], v[202:205], v[218:221], v[182:185]
	v_readfirstlane_b32 s56, v45
	v_lshl_add_u64 v[96:97], v[2:3], 0, s[18:19]
	s_mov_b32 m0, s56
	v_readfirstlane_b32 s0, v44
	s_waitcnt vmcnt(0)
	s_waitcnt vmcnt(0)
	s_barrier
	global_load_lds_dwordx4 v[96:97], off
	v_lshl_add_u64 v[96:97], v[4:5], 0, s[18:19]
	s_mov_b32 m0, s0
	v_readfirstlane_b32 s42, v46
	global_load_lds_dwordx4 v[96:97], off
	v_lshl_add_u64 v[44:45], v[6:7], 0, s[18:19]
	s_mov_b32 m0, s42
	v_readfirstlane_b32 s43, v47
	global_load_lds_dwordx4 v[44:45], off
	v_lshl_add_u64 v[44:45], v[8:9], 0, s[18:19]
	s_mov_b32 m0, s43
	v_readfirstlane_b32 s53, v48
	global_load_lds_dwordx4 v[44:45], off
	v_lshl_add_u64 v[44:45], v[10:11], 0, s[18:19]
	s_mov_b32 m0, s53
	v_readfirstlane_b32 s54, v49
	global_load_lds_dwordx4 v[44:45], off
	v_lshl_add_u64 v[44:45], v[12:13], 0, s[18:19]
	s_mov_b32 m0, s54
	v_readfirstlane_b32 s55, v50
	global_load_lds_dwordx4 v[44:45], off
	v_lshl_add_u64 v[44:45], v[14:15], 0, s[18:19]
	s_mov_b32 m0, s55
	v_readfirstlane_b32 s57, v51
	global_load_lds_dwordx4 v[44:45], off
	v_lshl_add_u64 v[44:45], v[16:17], 0, s[18:19]
	s_mov_b32 m0, s57
	s_nop 0
	global_load_lds_dwordx4 v[44:45], off
	ds_read_b128 v[44:47], v23
	ds_read_b128 v[48:51], v23 offset:2048
	ds_read_b128 v[186:189], v23 offset:4096
	ds_read_b128 v[194:197], v23 offset:6144
	ds_read_b128 v[190:193], v24
	ds_read_b128 v[198:201], v25
	ds_read_b128 v[202:205], v26
	ds_read_b128 v[206:209], v27
	s_waitcnt lgkmcnt(0)
	v_mfma_f32_16x16x32_bf16 v[138:141], v[44:47], v[190:193], v[138:141]
	v_mfma_f32_16x16x32_bf16 v[142:145], v[48:51], v[190:193], v[142:145]
	v_mfma_f32_16x16x32_bf16 v[146:149], v[186:189], v[190:193], v[146:149]
	v_mfma_f32_16x16x32_bf16 v[134:137], v[194:197], v[190:193], v[134:137]
	ds_read_b128 v[190:193], v28
	v_mfma_f32_16x16x32_bf16 v[154:157], v[44:47], v[198:201], v[154:157]
	v_mfma_f32_16x16x32_bf16 v[158:161], v[48:51], v[198:201], v[158:161]
	v_mfma_f32_16x16x32_bf16 v[162:165], v[186:189], v[198:201], v[162:165]
	v_mfma_f32_16x16x32_bf16 v[150:153], v[194:197], v[198:201], v[150:153]
	ds_read_b128 v[198:201], v29
	v_mfma_f32_16x16x32_bf16 v[170:173], v[44:47], v[202:205], v[170:173]
	v_mfma_f32_16x16x32_bf16 v[174:177], v[48:51], v[202:205], v[174:177]
	v_mfma_f32_16x16x32_bf16 v[178:181], v[186:189], v[202:205], v[178:181]
	v_mfma_f32_16x16x32_bf16 v[166:169], v[194:197], v[202:205], v[166:169]
	ds_read_b128 v[202:205], v30
	v_mfma_f32_16x16x32_bf16 v[210:213], v[44:47], v[206:209], v[214:217]
	v_mfma_f32_16x16x32_bf16 v[56:59], v[48:51], v[206:209], v[56:59]
	v_mfma_f32_16x16x32_bf16 v[64:67], v[186:189], v[206:209], v[64:67]
	v_mfma_f32_16x16x32_bf16 v[72:75], v[194:197], v[206:209], v[72:75]
	ds_read_b128 v[206:209], v31
	s_waitcnt lgkmcnt(0)
	v_mfma_f32_16x16x32_bf16 v[116:119], v[44:47], v[190:193], v[116:119]
	v_mfma_f32_16x16x32_bf16 v[120:123], v[48:51], v[190:193], v[120:123]
	v_mfma_f32_16x16x32_bf16 v[124:127], v[186:189], v[190:193], v[124:127]
	v_mfma_f32_16x16x32_bf16 v[112:115], v[194:197], v[190:193], v[112:115]
	v_mfma_f32_16x16x32_bf16 v[92:95], v[44:47], v[198:201], v[92:95]
	v_mfma_f32_16x16x32_bf16 v[100:103], v[48:51], v[198:201], v[100:103]
	v_mfma_f32_16x16x32_bf16 v[104:107], v[186:189], v[198:201], v[104:107]
	v_mfma_f32_16x16x32_bf16 v[108:111], v[194:197], v[198:201], v[108:111]
	v_mfma_f32_16x16x32_bf16 v[76:79], v[44:47], v[202:205], v[76:79]
	v_mfma_f32_16x16x32_bf16 v[80:83], v[48:51], v[202:205], v[80:83]
	v_mfma_f32_16x16x32_bf16 v[84:87], v[186:189], v[202:205], v[84:87]
	v_mfma_f32_16x16x32_bf16 v[88:91], v[194:197], v[202:205], v[88:91]
	v_mfma_f32_16x16x32_bf16 v[44:47], v[44:47], v[206:209], v[52:55]
	v_mfma_f32_16x16x32_bf16 v[48:51], v[48:51], v[206:209], v[60:63]
	v_mfma_f32_16x16x32_bf16 v[52:55], v[186:189], v[206:209], v[68:71]
	v_mfma_f32_16x16x32_bf16 v[60:63], v[194:197], v[206:209], v[182:185]
	s_nop 1
	ds_read_b128 v[68:71], v23 offset:1024
	ds_read_b128 v[182:185], v23 offset:3072
	ds_read_b128 v[186:189], v23 offset:5120
	ds_read_b128 v[194:197], v23 offset:7168
	ds_read_b128 v[190:193], v24 offset:1024
	ds_read_b128 v[198:201], v25 offset:1024
	ds_read_b128 v[202:205], v26 offset:1024
	ds_read_b128 v[206:209], v27 offset:1024
	s_waitcnt lgkmcnt(0)
	v_mfma_f32_16x16x32_bf16 v[138:141], v[68:71], v[190:193], v[138:141]
	v_mfma_f32_16x16x32_bf16 v[142:145], v[182:185], v[190:193], v[142:145]
	v_mfma_f32_16x16x32_bf16 v[146:149], v[186:189], v[190:193], v[146:149]
	v_mfma_f32_16x16x32_bf16 v[134:137], v[194:197], v[190:193], v[134:137]
	ds_read_b128 v[190:193], v28 offset:1024
	v_mfma_f32_16x16x32_bf16 v[154:157], v[68:71], v[198:201], v[154:157]
	v_mfma_f32_16x16x32_bf16 v[158:161], v[182:185], v[198:201], v[158:161]
	v_mfma_f32_16x16x32_bf16 v[162:165], v[186:189], v[198:201], v[162:165]
	v_mfma_f32_16x16x32_bf16 v[150:153], v[194:197], v[198:201], v[150:153]
	ds_read_b128 v[198:201], v29 offset:1024
	v_mfma_f32_16x16x32_bf16 v[170:173], v[68:71], v[202:205], v[170:173]
	v_mfma_f32_16x16x32_bf16 v[174:177], v[182:185], v[202:205], v[174:177]
	v_mfma_f32_16x16x32_bf16 v[178:181], v[186:189], v[202:205], v[178:181]
	v_mfma_f32_16x16x32_bf16 v[166:169], v[194:197], v[202:205], v[166:169]
	ds_read_b128 v[202:205], v30 offset:1024
	v_mfma_f32_16x16x32_bf16 v[210:213], v[68:71], v[206:209], v[210:213]
	v_mfma_f32_16x16x32_bf16 v[56:59], v[182:185], v[206:209], v[56:59]
	v_mfma_f32_16x16x32_bf16 v[64:67], v[186:189], v[206:209], v[64:67]
	v_mfma_f32_16x16x32_bf16 v[72:75], v[194:197], v[206:209], v[72:75]
	ds_read_b128 v[206:209], v31 offset:1024
	s_waitcnt lgkmcnt(0)
	v_mfma_f32_16x16x32_bf16 v[116:119], v[68:71], v[190:193], v[116:119]
	v_mfma_f32_16x16x32_bf16 v[120:123], v[182:185], v[190:193], v[120:123]
	v_mfma_f32_16x16x32_bf16 v[124:127], v[186:189], v[190:193], v[124:127]
	v_mfma_f32_16x16x32_bf16 v[112:115], v[194:197], v[190:193], v[112:115]
	v_mfma_f32_16x16x32_bf16 v[92:95], v[68:71], v[198:201], v[92:95]
	v_mfma_f32_16x16x32_bf16 v[100:103], v[182:185], v[198:201], v[100:103]
	v_mfma_f32_16x16x32_bf16 v[104:107], v[186:189], v[198:201], v[104:107]
	v_mfma_f32_16x16x32_bf16 v[108:111], v[194:197], v[198:201], v[108:111]
	v_mfma_f32_16x16x32_bf16 v[76:79], v[68:71], v[202:205], v[76:79]
	v_mfma_f32_16x16x32_bf16 v[80:83], v[182:185], v[202:205], v[80:83]
	v_mfma_f32_16x16x32_bf16 v[84:87], v[186:189], v[202:205], v[84:87]
	v_mfma_f32_16x16x32_bf16 v[88:91], v[194:197], v[202:205], v[88:91]
	v_mfma_f32_16x16x32_bf16 v[44:47], v[68:71], v[206:209], v[44:47]
	v_mfma_f32_16x16x32_bf16 v[48:51], v[182:185], v[206:209], v[48:51]
	v_mfma_f32_16x16x32_bf16 v[52:55], v[186:189], v[206:209], v[52:55]
	v_mfma_f32_16x16x32_bf16 v[60:63], v[194:197], v[206:209], v[60:63]
	v_readfirstlane_b32 s64, v37
	v_lshl_add_u64 v[68:69], v[2:3], 0, s[20:21]
	s_mov_b32 m0, s64
	v_readfirstlane_b32 s58, v36
	s_waitcnt vmcnt(0)
	s_waitcnt vmcnt(0)
	s_barrier
	global_load_lds_dwordx4 v[68:69], off
	v_lshl_add_u64 v[68:69], v[4:5], 0, s[20:21]
	s_mov_b32 m0, s58
	v_readfirstlane_b32 s59, v38
	global_load_lds_dwordx4 v[68:69], off
	v_lshl_add_u64 v[36:37], v[6:7], 0, s[20:21]
	s_mov_b32 m0, s59
	v_readfirstlane_b32 s60, v39
	global_load_lds_dwordx4 v[36:37], off
	v_lshl_add_u64 v[36:37], v[8:9], 0, s[20:21]
	s_mov_b32 m0, s60
	v_readfirstlane_b32 s61, v40
	global_load_lds_dwordx4 v[36:37], off
	v_lshl_add_u64 v[36:37], v[10:11], 0, s[20:21]
	s_mov_b32 m0, s61
	v_readfirstlane_b32 s62, v41
	global_load_lds_dwordx4 v[36:37], off
	v_lshl_add_u64 v[36:37], v[12:13], 0, s[20:21]
	s_mov_b32 m0, s62
	v_readfirstlane_b32 s63, v42
	global_load_lds_dwordx4 v[36:37], off
	v_lshl_add_u64 v[36:37], v[14:15], 0, s[20:21]
	s_mov_b32 m0, s63
	v_readfirstlane_b32 s65, v43
	global_load_lds_dwordx4 v[36:37], off
	v_lshl_add_u64 v[36:37], v[16:17], 0, s[20:21]
	s_mov_b32 m0, s65
	s_nop 0
	global_load_lds_dwordx4 v[36:37], off
	ds_read_b128 v[36:39], v18 offset:32768
	ds_read_b128 v[40:43], v18 offset:34816
	ds_read_b128 v[68:71], v18 offset:36864
	ds_read_b128 v[186:189], v18 offset:38912
	ds_read_b128 v[182:185], v32
	ds_read_b128 v[190:193], v33
	ds_read_b128 v[194:197], v34
	ds_read_b128 v[198:201], v35
	s_waitcnt lgkmcnt(0)
	v_mfma_f32_16x16x32_bf16 v[138:141], v[36:39], v[182:185], v[138:141]
	v_mfma_f32_16x16x32_bf16 v[142:145], v[40:43], v[182:185], v[142:145]
	v_mfma_f32_16x16x32_bf16 v[146:149], v[68:71], v[182:185], v[146:149]
	v_mfma_f32_16x16x32_bf16 v[134:137], v[186:189], v[182:185], v[134:137]
	ds_read_b128 v[182:185], v22
	v_mfma_f32_16x16x32_bf16 v[154:157], v[36:39], v[190:193], v[154:157]
	v_mfma_f32_16x16x32_bf16 v[158:161], v[40:43], v[190:193], v[158:161]
	v_mfma_f32_16x16x32_bf16 v[162:165], v[68:71], v[190:193], v[162:165]
	v_mfma_f32_16x16x32_bf16 v[150:153], v[186:189], v[190:193], v[150:153]
	ds_read_b128 v[190:193], v21
	v_mfma_f32_16x16x32_bf16 v[170:173], v[36:39], v[194:197], v[170:173]
	v_mfma_f32_16x16x32_bf16 v[174:177], v[40:43], v[194:197], v[174:177]
	v_mfma_f32_16x16x32_bf16 v[178:181], v[68:71], v[194:197], v[178:181]
	v_mfma_f32_16x16x32_bf16 v[166:169], v[186:189], v[194:197], v[166:169]
	ds_read_b128 v[194:197], v20
	v_mfma_f32_16x16x32_bf16 v[202:205], v[36:39], v[198:201], v[210:213]
	v_mfma_f32_16x16x32_bf16 v[56:59], v[40:43], v[198:201], v[56:59]
	v_mfma_f32_16x16x32_bf16 v[64:67], v[68:71], v[198:201], v[64:67]
	v_mfma_f32_16x16x32_bf16 v[72:75], v[186:189], v[198:201], v[72:75]
	ds_read_b128 v[198:201], v19
	s_waitcnt lgkmcnt(0)
	v_mfma_f32_16x16x32_bf16 v[116:119], v[36:39], v[182:185], v[116:119]
	v_mfma_f32_16x16x32_bf16 v[120:123], v[40:43], v[182:185], v[120:123]
	v_mfma_f32_16x16x32_bf16 v[124:127], v[68:71], v[182:185], v[124:127]
	v_mfma_f32_16x16x32_bf16 v[112:115], v[186:189], v[182:185], v[112:115]
	v_mfma_f32_16x16x32_bf16 v[92:95], v[36:39], v[190:193], v[92:95]
	v_mfma_f32_16x16x32_bf16 v[100:103], v[40:43], v[190:193], v[100:103]
	v_mfma_f32_16x16x32_bf16 v[104:107], v[68:71], v[190:193], v[104:107]
	v_mfma_f32_16x16x32_bf16 v[108:111], v[186:189], v[190:193], v[108:111]
	v_mfma_f32_16x16x32_bf16 v[76:79], v[36:39], v[194:197], v[76:79]
	v_mfma_f32_16x16x32_bf16 v[80:83], v[40:43], v[194:197], v[80:83]
	v_mfma_f32_16x16x32_bf16 v[84:87], v[68:71], v[194:197], v[84:87]
	v_mfma_f32_16x16x32_bf16 v[88:91], v[186:189], v[194:197], v[88:91]
	v_mfma_f32_16x16x32_bf16 v[36:39], v[36:39], v[198:201], v[44:47]
	v_mfma_f32_16x16x32_bf16 v[40:43], v[40:43], v[198:201], v[48:51]
	v_mfma_f32_16x16x32_bf16 v[44:47], v[68:71], v[198:201], v[52:55]
	v_mfma_f32_16x16x32_bf16 v[48:51], v[186:189], v[198:201], v[60:63]
	s_nop 1
	ds_read_b128 v[52:55], v18 offset:33792
	ds_read_b128 v[60:63], v18 offset:35840
	ds_read_b128 v[68:71], v18 offset:37888
	ds_read_b128 v[186:189], v18 offset:39936
	ds_read_b128 v[182:185], v32 offset:1024
	ds_read_b128 v[190:193], v33 offset:1024
	ds_read_b128 v[194:197], v34 offset:1024
	ds_read_b128 v[198:201], v35 offset:1024
	s_waitcnt lgkmcnt(0)
	v_mfma_f32_16x16x32_bf16 v[138:141], v[52:55], v[182:185], v[138:141]
	v_mfma_f32_16x16x32_bf16 v[142:145], v[60:63], v[182:185], v[142:145]
	v_mfma_f32_16x16x32_bf16 v[146:149], v[68:71], v[182:185], v[146:149]
	v_mfma_f32_16x16x32_bf16 v[134:137], v[186:189], v[182:185], v[134:137]
	ds_read_b128 v[182:185], v22 offset:1024
	v_mfma_f32_16x16x32_bf16 v[154:157], v[52:55], v[190:193], v[154:157]
	v_mfma_f32_16x16x32_bf16 v[158:161], v[60:63], v[190:193], v[158:161]
	v_mfma_f32_16x16x32_bf16 v[162:165], v[68:71], v[190:193], v[162:165]
	v_mfma_f32_16x16x32_bf16 v[150:153], v[186:189], v[190:193], v[150:153]
	ds_read_b128 v[190:193], v21 offset:1024
	v_mfma_f32_16x16x32_bf16 v[170:173], v[52:55], v[194:197], v[170:173]
	v_mfma_f32_16x16x32_bf16 v[174:177], v[60:63], v[194:197], v[174:177]
	v_mfma_f32_16x16x32_bf16 v[178:181], v[68:71], v[194:197], v[178:181]
	v_mfma_f32_16x16x32_bf16 v[166:169], v[186:189], v[194:197], v[166:169]
	ds_read_b128 v[194:197], v20 offset:1024
	v_mfma_f32_16x16x32_bf16 v[202:205], v[52:55], v[198:201], v[202:205]
	v_mfma_f32_16x16x32_bf16 v[56:59], v[60:63], v[198:201], v[56:59]
	v_mfma_f32_16x16x32_bf16 v[64:67], v[68:71], v[198:201], v[64:67]
	v_mfma_f32_16x16x32_bf16 v[72:75], v[186:189], v[198:201], v[72:75]
	ds_read_b128 v[198:201], v19 offset:1024
	s_waitcnt lgkmcnt(0)
	v_mfma_f32_16x16x32_bf16 v[116:119], v[52:55], v[182:185], v[116:119]
	v_mfma_f32_16x16x32_bf16 v[120:123], v[60:63], v[182:185], v[120:123]
	v_mfma_f32_16x16x32_bf16 v[124:127], v[68:71], v[182:185], v[124:127]
	v_mfma_f32_16x16x32_bf16 v[112:115], v[186:189], v[182:185], v[112:115]
	v_mfma_f32_16x16x32_bf16 v[92:95], v[52:55], v[190:193], v[92:95]
	v_mfma_f32_16x16x32_bf16 v[100:103], v[60:63], v[190:193], v[100:103]
	v_mfma_f32_16x16x32_bf16 v[104:107], v[68:71], v[190:193], v[104:107]
	v_mfma_f32_16x16x32_bf16 v[108:111], v[186:189], v[190:193], v[108:111]
	v_mfma_f32_16x16x32_bf16 v[76:79], v[52:55], v[194:197], v[76:79]
	v_mfma_f32_16x16x32_bf16 v[80:83], v[60:63], v[194:197], v[80:83]
	v_mfma_f32_16x16x32_bf16 v[84:87], v[68:71], v[194:197], v[84:87]
	v_mfma_f32_16x16x32_bf16 v[88:91], v[186:189], v[194:197], v[88:91]
	v_mfma_f32_16x16x32_bf16 v[36:39], v[52:55], v[198:201], v[36:39]
	v_mfma_f32_16x16x32_bf16 v[40:43], v[60:63], v[198:201], v[40:43]
	v_mfma_f32_16x16x32_bf16 v[44:47], v[68:71], v[198:201], v[44:47]
	v_mfma_f32_16x16x32_bf16 v[48:51], v[186:189], v[198:201], v[48:51]
	s_mov_b32 m0, s56
	v_lshl_add_u64 v[52:53], v[2:3], 0, s[22:23]
	s_waitcnt vmcnt(0)
	s_waitcnt vmcnt(0)
	s_barrier
	global_load_lds_dwordx4 v[52:53], off
	v_lshl_add_u64 v[52:53], v[4:5], 0, s[22:23]
	s_mov_b32 m0, s0
	s_nop 0
	global_load_lds_dwordx4 v[52:53], off
	v_lshl_add_u64 v[52:53], v[6:7], 0, s[22:23]
	s_mov_b32 m0, s42
	s_nop 0
	global_load_lds_dwordx4 v[52:53], off
	v_lshl_add_u64 v[52:53], v[8:9], 0, s[22:23]
	s_mov_b32 m0, s43
	s_nop 0
	global_load_lds_dwordx4 v[52:53], off
	v_lshl_add_u64 v[52:53], v[10:11], 0, s[22:23]
	s_mov_b32 m0, s53
	s_nop 0
	global_load_lds_dwordx4 v[52:53], off
	v_lshl_add_u64 v[52:53], v[12:13], 0, s[22:23]
	s_mov_b32 m0, s54
	s_nop 0
	global_load_lds_dwordx4 v[52:53], off
	v_lshl_add_u64 v[52:53], v[14:15], 0, s[22:23]
	s_mov_b32 m0, s55
	s_nop 0
	global_load_lds_dwordx4 v[52:53], off
	v_lshl_add_u64 v[52:53], v[16:17], 0, s[22:23]
	s_mov_b32 m0, s57
	s_nop 0
	global_load_lds_dwordx4 v[52:53], off
	ds_read_b128 v[52:55], v23
	ds_read_b128 v[60:63], v23 offset:2048
	ds_read_b128 v[68:71], v23 offset:4096
	ds_read_b128 v[186:189], v23 offset:6144
	ds_read_b128 v[182:185], v24
	ds_read_b128 v[190:193], v25
	ds_read_b128 v[194:197], v26
	ds_read_b128 v[198:201], v27
	s_waitcnt lgkmcnt(0)
	v_mfma_f32_16x16x32_bf16 v[138:141], v[52:55], v[182:185], v[138:141]
	v_mfma_f32_16x16x32_bf16 v[142:145], v[60:63], v[182:185], v[142:145]
	v_mfma_f32_16x16x32_bf16 v[146:149], v[68:71], v[182:185], v[146:149]
	v_mfma_f32_16x16x32_bf16 v[134:137], v[186:189], v[182:185], v[134:137]
	ds_read_b128 v[182:185], v28
	v_mfma_f32_16x16x32_bf16 v[154:157], v[52:55], v[190:193], v[154:157]
	v_mfma_f32_16x16x32_bf16 v[158:161], v[60:63], v[190:193], v[158:161]
	v_mfma_f32_16x16x32_bf16 v[162:165], v[68:71], v[190:193], v[162:165]
	v_mfma_f32_16x16x32_bf16 v[150:153], v[186:189], v[190:193], v[150:153]
	ds_read_b128 v[190:193], v29
	v_mfma_f32_16x16x32_bf16 v[170:173], v[52:55], v[194:197], v[170:173]
	v_mfma_f32_16x16x32_bf16 v[174:177], v[60:63], v[194:197], v[174:177]
	v_mfma_f32_16x16x32_bf16 v[178:181], v[68:71], v[194:197], v[178:181]
	v_mfma_f32_16x16x32_bf16 v[166:169], v[186:189], v[194:197], v[166:169]
	ds_read_b128 v[194:197], v30
	v_mfma_f32_16x16x32_bf16 v[202:205], v[52:55], v[198:201], v[202:205]
	v_mfma_f32_16x16x32_bf16 v[56:59], v[60:63], v[198:201], v[56:59]
	v_mfma_f32_16x16x32_bf16 v[64:67], v[68:71], v[198:201], v[64:67]
	v_mfma_f32_16x16x32_bf16 v[72:75], v[186:189], v[198:201], v[72:75]
	ds_read_b128 v[198:201], v31
	s_waitcnt lgkmcnt(0)
	v_mfma_f32_16x16x32_bf16 v[116:119], v[52:55], v[182:185], v[116:119]
	v_mfma_f32_16x16x32_bf16 v[120:123], v[60:63], v[182:185], v[120:123]
	v_mfma_f32_16x16x32_bf16 v[124:127], v[68:71], v[182:185], v[124:127]
	v_mfma_f32_16x16x32_bf16 v[112:115], v[186:189], v[182:185], v[112:115]
	v_mfma_f32_16x16x32_bf16 v[92:95], v[52:55], v[190:193], v[92:95]
	v_mfma_f32_16x16x32_bf16 v[100:103], v[60:63], v[190:193], v[100:103]
	v_mfma_f32_16x16x32_bf16 v[104:107], v[68:71], v[190:193], v[104:107]
	v_mfma_f32_16x16x32_bf16 v[108:111], v[186:189], v[190:193], v[108:111]
	v_mfma_f32_16x16x32_bf16 v[76:79], v[52:55], v[194:197], v[76:79]
	v_mfma_f32_16x16x32_bf16 v[80:83], v[60:63], v[194:197], v[80:83]
	v_mfma_f32_16x16x32_bf16 v[84:87], v[68:71], v[194:197], v[84:87]
	v_mfma_f32_16x16x32_bf16 v[88:91], v[186:189], v[194:197], v[88:91]
	v_mfma_f32_16x16x32_bf16 v[36:39], v[52:55], v[198:201], v[36:39]
	v_mfma_f32_16x16x32_bf16 v[40:43], v[60:63], v[198:201], v[40:43]
	v_mfma_f32_16x16x32_bf16 v[44:47], v[68:71], v[198:201], v[44:47]
	v_mfma_f32_16x16x32_bf16 v[48:51], v[186:189], v[198:201], v[48:51]
	ds_read_b128 v[52:55], v23 offset:1024
	ds_read_b128 v[60:63], v23 offset:3072
	ds_read_b128 v[68:71], v23 offset:5120
	ds_read_b128 v[186:189], v23 offset:7168
	ds_read_b128 v[182:185], v24 offset:1024
	ds_read_b128 v[190:193], v25 offset:1024
	ds_read_b128 v[194:197], v26 offset:1024
	ds_read_b128 v[198:201], v27 offset:1024
	s_waitcnt lgkmcnt(0)
	v_mfma_f32_16x16x32_bf16 v[138:141], v[52:55], v[182:185], v[138:141]
	v_mfma_f32_16x16x32_bf16 v[142:145], v[60:63], v[182:185], v[142:145]
	v_mfma_f32_16x16x32_bf16 v[146:149], v[68:71], v[182:185], v[146:149]
	v_mfma_f32_16x16x32_bf16 v[134:137], v[186:189], v[182:185], v[134:137]
	ds_read_b128 v[182:185], v28 offset:1024
	v_mfma_f32_16x16x32_bf16 v[154:157], v[52:55], v[190:193], v[154:157]
	v_mfma_f32_16x16x32_bf16 v[158:161], v[60:63], v[190:193], v[158:161]
	v_mfma_f32_16x16x32_bf16 v[162:165], v[68:71], v[190:193], v[162:165]
	v_mfma_f32_16x16x32_bf16 v[150:153], v[186:189], v[190:193], v[150:153]
	ds_read_b128 v[190:193], v29 offset:1024
	v_mfma_f32_16x16x32_bf16 v[170:173], v[52:55], v[194:197], v[170:173]
	v_mfma_f32_16x16x32_bf16 v[174:177], v[60:63], v[194:197], v[174:177]
	v_mfma_f32_16x16x32_bf16 v[178:181], v[68:71], v[194:197], v[178:181]
	v_mfma_f32_16x16x32_bf16 v[166:169], v[186:189], v[194:197], v[166:169]
	ds_read_b128 v[194:197], v30 offset:1024
	v_mfma_f32_16x16x32_bf16 v[202:205], v[52:55], v[198:201], v[202:205]
	v_mfma_f32_16x16x32_bf16 v[56:59], v[60:63], v[198:201], v[56:59]
	v_mfma_f32_16x16x32_bf16 v[64:67], v[68:71], v[198:201], v[64:67]
	v_mfma_f32_16x16x32_bf16 v[72:75], v[186:189], v[198:201], v[72:75]
	ds_read_b128 v[198:201], v31 offset:1024
	s_waitcnt lgkmcnt(0)
	v_mfma_f32_16x16x32_bf16 v[116:119], v[52:55], v[182:185], v[116:119]
	v_mfma_f32_16x16x32_bf16 v[120:123], v[60:63], v[182:185], v[120:123]
	v_mfma_f32_16x16x32_bf16 v[124:127], v[68:71], v[182:185], v[124:127]
	v_mfma_f32_16x16x32_bf16 v[112:115], v[186:189], v[182:185], v[112:115]
	v_mfma_f32_16x16x32_bf16 v[92:95], v[52:55], v[190:193], v[92:95]
	v_mfma_f32_16x16x32_bf16 v[100:103], v[60:63], v[190:193], v[100:103]
	v_mfma_f32_16x16x32_bf16 v[104:107], v[68:71], v[190:193], v[104:107]
	v_mfma_f32_16x16x32_bf16 v[108:111], v[186:189], v[190:193], v[108:111]
	v_mfma_f32_16x16x32_bf16 v[76:79], v[52:55], v[194:197], v[76:79]
	v_mfma_f32_16x16x32_bf16 v[80:83], v[60:63], v[194:197], v[80:83]
	v_mfma_f32_16x16x32_bf16 v[84:87], v[68:71], v[194:197], v[84:87]
	v_mfma_f32_16x16x32_bf16 v[88:91], v[186:189], v[194:197], v[88:91]
	v_mfma_f32_16x16x32_bf16 v[36:39], v[52:55], v[198:201], v[36:39]
	v_mfma_f32_16x16x32_bf16 v[40:43], v[60:63], v[198:201], v[40:43]
	v_mfma_f32_16x16x32_bf16 v[44:47], v[68:71], v[198:201], v[44:47]
	v_mfma_f32_16x16x32_bf16 v[48:51], v[186:189], v[198:201], v[48:51]
	s_mov_b32 m0, s64
	v_lshl_add_u64 v[2:3], v[2:3], 0, s[24:25]
	s_waitcnt vmcnt(0)
	s_waitcnt vmcnt(0)
	s_barrier
	global_load_lds_dwordx4 v[2:3], off
	v_lshl_add_u64 v[2:3], v[4:5], 0, s[24:25]
	s_mov_b32 m0, s58
	s_nop 0
	global_load_lds_dwordx4 v[2:3], off
	v_lshl_add_u64 v[2:3], v[6:7], 0, s[24:25]
	s_mov_b32 m0, s59
	s_nop 0
	global_load_lds_dwordx4 v[2:3], off
	v_lshl_add_u64 v[2:3], v[8:9], 0, s[24:25]
	s_mov_b32 m0, s60
	s_nop 0
	global_load_lds_dwordx4 v[2:3], off
	v_lshl_add_u64 v[2:3], v[10:11], 0, s[24:25]
	s_mov_b32 m0, s61
	s_nop 0
	global_load_lds_dwordx4 v[2:3], off
	v_lshl_add_u64 v[2:3], v[12:13], 0, s[24:25]
	s_mov_b32 m0, s62
	s_nop 0
	global_load_lds_dwordx4 v[2:3], off
	v_lshl_add_u64 v[2:3], v[14:15], 0, s[24:25]
	s_mov_b32 m0, s63
	s_nop 0
	global_load_lds_dwordx4 v[2:3], off
	v_lshl_add_u64 v[2:3], v[16:17], 0, s[24:25]
	s_mov_b32 m0, s65
	s_nop 0
	global_load_lds_dwordx4 v[2:3], off
	ds_read_b128 v[2:5], v18 offset:32768
	ds_read_b128 v[6:9], v18 offset:34816
	ds_read_b128 v[10:13], v18 offset:36864
	ds_read_b128 v[52:55], v18 offset:38912
	ds_read_b128 v[14:17], v32
	ds_read_b128 v[60:63], v33
	ds_read_b128 v[68:71], v34
	ds_read_b128 v[182:185], v35
	s_waitcnt lgkmcnt(0)
	v_mfma_f32_16x16x32_bf16 v[138:141], v[2:5], v[14:17], v[138:141]
	v_mfma_f32_16x16x32_bf16 v[142:145], v[6:9], v[14:17], v[142:145]
	v_mfma_f32_16x16x32_bf16 v[146:149], v[10:13], v[14:17], v[146:149]
	v_mfma_f32_16x16x32_bf16 v[14:17], v[52:55], v[14:17], v[134:137]
	s_nop 2
	ds_read_b128 v[134:137], v22
	v_mfma_f32_16x16x32_bf16 v[154:157], v[2:5], v[60:63], v[154:157]
	v_mfma_f32_16x16x32_bf16 v[158:161], v[6:9], v[60:63], v[158:161]
	v_mfma_f32_16x16x32_bf16 v[162:165], v[10:13], v[60:63], v[162:165]
	v_mfma_f32_16x16x32_bf16 v[60:63], v[52:55], v[60:63], v[150:153]
	s_nop 2
	ds_read_b128 v[150:153], v21
	v_mfma_f32_16x16x32_bf16 v[170:173], v[2:5], v[68:71], v[170:173]
	v_mfma_f32_16x16x32_bf16 v[174:177], v[6:9], v[68:71], v[174:177]
	v_mfma_f32_16x16x32_bf16 v[178:181], v[10:13], v[68:71], v[178:181]
	v_mfma_f32_16x16x32_bf16 v[68:71], v[52:55], v[68:71], v[166:169]
	s_nop 2
	ds_read_b128 v[166:169], v20
	v_mfma_f32_16x16x32_bf16 v[186:189], v[2:5], v[182:185], v[202:205]
	v_mfma_f32_16x16x32_bf16 v[56:59], v[6:9], v[182:185], v[56:59]
	v_mfma_f32_16x16x32_bf16 v[64:67], v[10:13], v[182:185], v[64:67]
	v_mfma_f32_16x16x32_bf16 v[72:75], v[52:55], v[182:185], v[72:75]
	ds_read_b128 v[182:185], v19
	s_waitcnt lgkmcnt(0)
	v_mfma_f32_16x16x32_bf16 v[116:119], v[2:5], v[134:137], v[116:119]
	v_mfma_f32_16x16x32_bf16 v[120:123], v[6:9], v[134:137], v[120:123]
	v_mfma_f32_16x16x32_bf16 v[124:127], v[10:13], v[134:137], v[124:127]
	v_mfma_f32_16x16x32_bf16 v[112:115], v[52:55], v[134:137], v[112:115]
	v_mfma_f32_16x16x32_bf16 v[92:95], v[2:5], v[150:153], v[92:95]
	v_mfma_f32_16x16x32_bf16 v[100:103], v[6:9], v[150:153], v[100:103]
	v_mfma_f32_16x16x32_bf16 v[104:107], v[10:13], v[150:153], v[104:107]
	v_mfma_f32_16x16x32_bf16 v[108:111], v[52:55], v[150:153], v[108:111]
	v_mfma_f32_16x16x32_bf16 v[76:79], v[2:5], v[166:169], v[76:79]
	v_mfma_f32_16x16x32_bf16 v[80:83], v[6:9], v[166:169], v[80:83]
	v_mfma_f32_16x16x32_bf16 v[84:87], v[10:13], v[166:169], v[84:87]
	v_mfma_f32_16x16x32_bf16 v[88:91], v[52:55], v[166:169], v[88:91]
	v_mfma_f32_16x16x32_bf16 v[2:5], v[2:5], v[182:185], v[36:39]
	v_mfma_f32_16x16x32_bf16 v[6:9], v[6:9], v[182:185], v[40:43]
	v_mfma_f32_16x16x32_bf16 v[10:13], v[10:13], v[182:185], v[44:47]
	v_mfma_f32_16x16x32_bf16 v[36:39], v[52:55], v[182:185], v[48:51]
	s_nop 0
	ds_read_b128 v[40:43], v18 offset:33792
	ds_read_b128 v[44:47], v18 offset:35840
	ds_read_b128 v[48:51], v18 offset:37888
	ds_read_b128 v[134:137], v18 offset:39936
	ds_read_b128 v[52:55], v32 offset:1024
	ds_read_b128 v[150:153], v33 offset:1024
	ds_read_b128 v[166:169], v34 offset:1024
	ds_read_b128 v[32:35], v35 offset:1024
	s_waitcnt lgkmcnt(0)
	v_mfma_f32_16x16x32_bf16 v[138:141], v[40:43], v[52:55], v[138:141]
	v_mfma_f32_16x16x32_bf16 v[142:145], v[44:47], v[52:55], v[142:145]
	v_mfma_f32_16x16x32_bf16 v[146:149], v[48:51], v[52:55], v[146:149]
	v_mfma_f32_16x16x32_bf16 v[14:17], v[134:137], v[52:55], v[14:17]
	ds_read_b128 v[52:55], v22 offset:1024
	v_mfma_f32_16x16x32_bf16 v[154:157], v[40:43], v[150:153], v[154:157]
	v_mfma_f32_16x16x32_bf16 v[158:161], v[44:47], v[150:153], v[158:161]
	v_mfma_f32_16x16x32_bf16 v[162:165], v[48:51], v[150:153], v[162:165]
	v_mfma_f32_16x16x32_bf16 v[60:63], v[134:137], v[150:153], v[60:63]
	ds_read_b128 v[150:153], v21 offset:1024
	v_mfma_f32_16x16x32_bf16 v[170:173], v[40:43], v[166:169], v[170:173]
	v_mfma_f32_16x16x32_bf16 v[174:177], v[44:47], v[166:169], v[174:177]
	v_mfma_f32_16x16x32_bf16 v[178:181], v[48:51], v[166:169], v[178:181]
	v_mfma_f32_16x16x32_bf16 v[68:71], v[134:137], v[166:169], v[68:71]
	ds_read_b128 v[166:169], v20 offset:1024
	v_mfma_f32_16x16x32_bf16 v[182:185], v[40:43], v[32:35], v[186:189]
	v_mfma_f32_16x16x32_bf16 v[56:59], v[44:47], v[32:35], v[56:59]
	v_mfma_f32_16x16x32_bf16 v[64:67], v[48:51], v[32:35], v[64:67]
	v_mfma_f32_16x16x32_bf16 v[32:35], v[134:137], v[32:35], v[72:75]
	ds_read_b128 v[18:21], v19 offset:1024
	s_waitcnt lgkmcnt(0)
	v_mfma_f32_16x16x32_bf16 v[72:75], v[40:43], v[52:55], v[116:119]
	v_mfma_f32_16x16x32_bf16 v[116:119], v[44:47], v[52:55], v[120:123]
	v_mfma_f32_16x16x32_bf16 v[120:123], v[48:51], v[52:55], v[124:127]
	v_mfma_f32_16x16x32_bf16 v[52:55], v[134:137], v[52:55], v[112:115]
	v_mfma_f32_16x16x32_bf16 v[92:95], v[40:43], v[150:153], v[92:95]
	v_mfma_f32_16x16x32_bf16 v[100:103], v[44:47], v[150:153], v[100:103]
	v_mfma_f32_16x16x32_bf16 v[104:107], v[48:51], v[150:153], v[104:107]
	v_mfma_f32_16x16x32_bf16 v[108:111], v[134:137], v[150:153], v[108:111]
	v_mfma_f32_16x16x32_bf16 v[76:79], v[40:43], v[166:169], v[76:79]
	v_mfma_f32_16x16x32_bf16 v[80:83], v[44:47], v[166:169], v[80:83]
	v_mfma_f32_16x16x32_bf16 v[84:87], v[48:51], v[166:169], v[84:87]
	v_mfma_f32_16x16x32_bf16 v[88:91], v[134:137], v[166:169], v[88:91]
	v_mfma_f32_16x16x32_bf16 v[2:5], v[40:43], v[18:21], v[2:5]
	v_mfma_f32_16x16x32_bf16 v[6:9], v[44:47], v[18:21], v[6:9]
	v_mfma_f32_16x16x32_bf16 v[10:13], v[48:51], v[18:21], v[10:13]
	v_mfma_f32_16x16x32_bf16 v[18:21], v[134:137], v[18:21], v[36:39]
	s_waitcnt vmcnt(0)
	s_waitcnt vmcnt(0)
	s_barrier
	s_nop 0
	ds_read_b128 v[36:39], v31
	ds_read_b128 v[40:43], v30
	ds_read_b128 v[44:47], v29
	ds_read_b128 v[48:51], v28
	ds_read_b128 v[112:115], v27
	ds_read_b128 v[124:127], v26
	ds_read_b128 v[134:137], v25
	ds_read_b128 v[150:153], v24
	ds_read_b128 v[166:169], v23
	s_waitcnt lgkmcnt(0)
	v_mfma_f32_16x16x32_bf16 v[186:189], v[166:169], v[36:39], v[2:5]
	s_nop 2
	ds_read_b128 v[2:5], v23 offset:2048
	s_waitcnt lgkmcnt(0)
	v_mfma_f32_16x16x32_bf16 v[190:193], v[2:5], v[36:39], v[6:9]
	s_nop 2
	ds_read_b128 v[6:9], v23 offset:4096
	s_waitcnt lgkmcnt(0)
	v_mfma_f32_16x16x32_bf16 v[194:197], v[6:9], v[36:39], v[10:13]
	s_nop 2
	ds_read_b128 v[10:13], v23 offset:6144
	s_waitcnt lgkmcnt(0)
	v_mfma_f32_16x16x32_bf16 v[198:201], v[10:13], v[36:39], v[18:21]
	v_mfma_f32_16x16x32_bf16 v[18:21], v[10:13], v[134:137], v[60:63]
	v_mfma_f32_16x16x32_bf16 v[36:39], v[10:13], v[124:127], v[68:71]
	v_mfma_f32_16x16x32_bf16 v[68:71], v[6:9], v[134:137], v[162:165]
	v_mfma_f32_16x16x32_bf16 v[162:165], v[6:9], v[112:115], v[64:67]
	v_mfma_f32_16x16x32_bf16 v[64:67], v[2:5], v[150:153], v[142:145]
	v_mfma_f32_16x16x32_bf16 v[142:145], v[2:5], v[134:137], v[158:161]
	v_mfma_f32_16x16x32_bf16 v[134:137], v[166:169], v[134:137], v[154:157]
	v_mfma_f32_16x16x32_bf16 v[154:157], v[166:169], v[40:43], v[76:79]
	v_mfma_f32_16x16x32_bf16 v[60:63], v[6:9], v[150:153], v[146:149]
	v_mfma_f32_16x16x32_bf16 v[146:149], v[6:9], v[124:127], v[178:181]
	v_mfma_f32_16x16x32_bf16 v[158:161], v[2:5], v[124:127], v[174:177]
	v_mfma_f32_16x16x32_bf16 v[124:127], v[166:169], v[124:127], v[170:173]
	v_mfma_f32_16x16x32_bf16 v[170:173], v[6:9], v[40:43], v[84:87]
	v_mfma_f32_16x16x32_bf16 v[138:141], v[166:169], v[150:153], v[138:141]
	v_mfma_f32_16x16x32_bf16 v[56:59], v[2:5], v[112:115], v[56:59]
	v_mfma_f32_16x16x32_bf16 v[116:119], v[2:5], v[48:51], v[116:119]
	v_mfma_f32_16x16x32_bf16 v[120:123], v[6:9], v[48:51], v[120:123]
	v_mfma_f32_16x16x32_bf16 v[14:17], v[10:13], v[150:153], v[14:17]
	v_mfma_f32_16x16x32_bf16 v[150:153], v[166:169], v[48:51], v[72:75]
	v_mfma_f32_16x16x32_bf16 v[48:51], v[10:13], v[48:51], v[52:55]
	v_mfma_f32_16x16x32_bf16 v[52:55], v[166:169], v[44:47], v[92:95]
	v_mfma_f32_16x16x32_bf16 v[32:35], v[10:13], v[112:115], v[32:35]
	v_mfma_f32_16x16x32_bf16 v[112:115], v[166:169], v[112:115], v[182:185]
	v_mfma_f32_16x16x32_bf16 v[166:169], v[2:5], v[40:43], v[80:83]
	v_mfma_f32_16x16x32_bf16 v[104:107], v[6:9], v[44:47], v[104:107]
	v_mfma_f32_16x16x32_bf16 v[108:111], v[10:13], v[44:47], v[108:111]
	v_mfma_f32_16x16x32_bf16 v[100:103], v[2:5], v[44:47], v[100:103]
	v_mfma_f32_16x16x32_bf16 v[174:177], v[10:13], v[40:43], v[88:91]
	ds_read_b128 v[178:181], v23 offset:1024
	ds_read_b128 v[182:185], v23 offset:3072
	ds_read_b128 v[202:205], v23 offset:5120
	ds_read_b128 v[206:209], v23 offset:7168
	ds_read_b128 v[2:5], v24 offset:1024
	ds_read_b128 v[6:9], v25 offset:1024
	ds_read_b128 v[10:13], v26 offset:1024
	ds_read_b128 v[22:25], v27 offset:1024
	s_waitcnt lgkmcnt(3)
	v_mfma_f32_16x16x32_bf16 v[138:141], v[178:181], v[2:5], v[138:141]
	v_mfma_f32_16x16x32_bf16 v[210:213], v[182:185], v[2:5], v[64:67]
	v_mfma_f32_16x16x32_bf16 v[214:217], v[202:205], v[2:5], v[60:63]
	v_mfma_f32_16x16x32_bf16 v[218:221], v[206:209], v[2:5], v[14:17]
	ds_read_b128 v[2:5], v28 offset:1024
	s_waitcnt lgkmcnt(3)
	v_mfma_f32_16x16x32_bf16 v[134:137], v[178:181], v[6:9], v[134:137]
	v_mfma_f32_16x16x32_bf16 v[142:145], v[182:185], v[6:9], v[142:145]
	v_mfma_f32_16x16x32_bf16 v[222:225], v[202:205], v[6:9], v[68:71]
	v_mfma_f32_16x16x32_bf16 v[226:229], v[206:209], v[6:9], v[18:21]
	ds_read_b128 v[6:9], v29 offset:1024
	s_waitcnt lgkmcnt(3)
	v_mfma_f32_16x16x32_bf16 v[66:69], v[178:181], v[10:13], v[124:127]
	v_mfma_f32_16x16x32_bf16 v[70:73], v[182:185], v[10:13], v[158:161]
	v_mfma_f32_16x16x32_bf16 v[74:77], v[202:205], v[10:13], v[146:149]
	v_mfma_f32_16x16x32_bf16 v[78:81], v[206:209], v[10:13], v[36:39]
	ds_read_b128 v[14:17], v30 offset:1024
	s_waitcnt lgkmcnt(3)
	v_mfma_f32_16x16x32_bf16 v[82:85], v[178:181], v[22:25], v[112:115]
	v_mfma_f32_16x16x32_bf16 v[86:89], v[182:185], v[22:25], v[56:59]
	v_mfma_f32_16x16x32_bf16 v[90:93], v[202:205], v[22:25], v[162:165]
	v_mfma_f32_16x16x32_bf16 v[94:97], v[206:209], v[22:25], v[32:35]
	s_nop 2
	ds_read_b128 v[30:33], v31 offset:1024
	s_waitcnt lgkmcnt(3)
	v_mfma_f32_16x16x32_bf16 v[34:37], v[178:181], v[2:5], v[150:153]
	v_mfma_f32_16x16x32_bf16 v[38:41], v[182:185], v[2:5], v[116:119]
	v_mfma_f32_16x16x32_bf16 v[42:45], v[202:205], v[2:5], v[120:123]
	v_mfma_f32_16x16x32_bf16 v[46:49], v[206:209], v[2:5], v[48:51]
	s_waitcnt lgkmcnt(2)
	v_mfma_f32_16x16x32_bf16 v[50:53], v[178:181], v[6:9], v[52:55]
	v_mfma_f32_16x16x32_bf16 v[54:57], v[182:185], v[6:9], v[100:103]
	v_mfma_f32_16x16x32_bf16 v[58:61], v[202:205], v[6:9], v[104:107]
	v_mfma_f32_16x16x32_bf16 v[62:65], v[206:209], v[6:9], v[108:111]
	s_waitcnt lgkmcnt(1)
	v_mfma_f32_16x16x32_bf16 v[2:5], v[178:181], v[14:17], v[154:157]
	v_mfma_f32_16x16x32_bf16 v[6:9], v[182:185], v[14:17], v[166:169]
	v_mfma_f32_16x16x32_bf16 v[10:13], v[202:205], v[14:17], v[170:173]
	v_mfma_f32_16x16x32_bf16 v[14:17], v[206:209], v[14:17], v[174:177]
	s_waitcnt lgkmcnt(0)
	v_mfma_f32_16x16x32_bf16 v[18:21], v[178:181], v[30:33], v[186:189]
	v_mfma_f32_16x16x32_bf16 v[22:25], v[182:185], v[30:33], v[190:193]
	v_mfma_f32_16x16x32_bf16 v[26:29], v[202:205], v[30:33], v[194:197]
	v_mfma_f32_16x16x32_bf16 v[30:33], v[206:209], v[30:33], v[198:201]
	v_lshlrev_b32_e32 v101, 2, v98
	v_and_b32_e32 v112, 60, v101
	v_ashrrev_i32_e32 v101, 1, v98
	v_lshrrev_b32_e32 v99, 6, v98
	v_and_b32_e32 v101, 0xffffff80, v101
	v_and_b32_e32 v100, 15, v98
	v_mul_lo_u32 v99, v99, s48
	v_add_u32_e32 v107, s28, v101
	v_bfe_u32 v108, v98, 4, 2
	v_add_u32_e32 v109, s46, v99
	v_and_b32_e32 v99, 48, v98
	v_and_or_b32 v102, v98, s49, v112
	v_mul_u32_u24_e32 v98, 0x110, v100
	v_or_b32_e32 v100, v107, v108
	v_lshl_add_u64 v[0:1], v[0:1], 0, s[38:39]
	v_lshlrev_b32_e32 v130, 1, v102
	v_ashrrev_i32_e32 v101, 31, v100
	v_lshl_add_u64 v[0:1], v[0:1], 0, v[130:131]
	v_add3_u32 v99, v109, v99, v98
	v_lshlrev_b64 v[100:101], 11, v[100:101]
	s_waitcnt vmcnt(0)
	s_barrier
	ds_write_b128 v99, v[138:141]
	ds_write_b128 v99, v[210:213] offset:64
	ds_write_b128 v99, v[214:217] offset:128
	ds_write_b128 v99, v[218:221] offset:192
	ds_write_b128 v99, v[134:137] offset:4352
	ds_write_b128 v99, v[142:145] offset:4416
	ds_write_b128 v99, v[222:225] offset:4480
	ds_write_b128 v99, v[226:229] offset:4544
	v_lshl_add_u64 v[114:115], v[0:1], 0, v[100:101]
	flat_load_dwordx2 v[116:117], v[114:115]
	v_or_b32_e32 v100, 4, v108
	v_or_b32_e32 v102, v107, v100
	v_ashrrev_i32_e32 v103, 31, v102
	v_lshlrev_b64 v[102:103], 11, v[102:103]
	v_lshl_add_u64 v[118:119], v[0:1], 0, v[102:103]
	flat_load_dwordx2 v[120:121], v[118:119]
	v_or_b32_e32 v101, 8, v108
	v_or_b32_e32 v102, v107, v101
	v_ashrrev_i32_e32 v103, 31, v102
	v_lshlrev_b64 v[102:103], 11, v[102:103]
	v_lshl_add_u64 v[122:123], v[0:1], 0, v[102:103]
	flat_load_dwordx2 v[124:125], v[122:123]
	v_or_b32_e32 v102, 12, v108
	v_or_b32_e32 v104, v107, v102
	v_ashrrev_i32_e32 v105, 31, v104
	v_lshlrev_b64 v[104:105], 11, v[104:105]
	v_lshl_add_u64 v[126:127], v[0:1], 0, v[104:105]
	flat_load_dwordx2 v[128:129], v[126:127]
	v_or_b32_e32 v103, 16, v108
	v_or_b32_e32 v104, v107, v103
	v_ashrrev_i32_e32 v105, 31, v104
	v_lshlrev_b64 v[104:105], 11, v[104:105]
	v_lshl_add_u64 v[134:135], v[0:1], 0, v[104:105]
	flat_load_dwordx2 v[136:137], v[134:135]
	v_or_b32_e32 v104, 20, v108
	v_or_b32_e32 v110, v107, v104
	v_ashrrev_i32_e32 v111, 31, v110
	v_lshlrev_b64 v[110:111], 11, v[110:111]
	v_lshl_add_u64 v[138:139], v[0:1], 0, v[110:111]
	flat_load_dwordx2 v[140:141], v[138:139]
	v_or_b32_e32 v105, 24, v108
	v_or_b32_e32 v110, v107, v105
	v_ashrrev_i32_e32 v111, 31, v110
	v_lshlrev_b64 v[110:111], 11, v[110:111]
	v_lshl_add_u64 v[142:143], v[0:1], 0, v[110:111]
	flat_load_dwordx2 v[144:145], v[142:143]
	v_or_b32_e32 v106, 28, v108
	v_or_b32_e32 v146, v107, v106
	v_ashrrev_i32_e32 v147, 31, v146
	v_lshlrev_b64 v[146:147], 11, v[146:147]
	v_lshl_add_u64 v[146:147], v[0:1], 0, v[146:147]
	flat_load_dwordx2 v[148:149], v[146:147]
	v_mul_u32_u24_e32 v98, 0x110, v108
	v_lshlrev_b32_e32 v110, 2, v112
	v_add3_u32 v98, v109, v110, v98
	ds_read_b128 v[110:113], v98
	s_add_i32 s0, s30, 0x1600
	s_lshl_b64 s[42:43], s[0:1], 11
	s_waitcnt vmcnt(0) lgkmcnt(0)
	v_and_b32_e32 v151, 0xffff0000, v116
	v_lshlrev_b32_e32 v150, 16, v116
	v_and_b32_e32 v153, 0xffff0000, v117
	v_lshlrev_b32_e32 v152, 16, v117
	v_pk_mul_f32 v[110:111], v[110:111], v[150:151]
	v_pk_mul_f32 v[112:113], v[112:113], v[152:153]
	v_cvt_pk_bf16_f32 v110, v110, v111
	v_cvt_pk_bf16_f32 v111, v112, v113
	flat_store_dwordx2 v[114:115], v[110:111]
	ds_read_b128 v[110:113], v98 offset:1088
	v_and_b32_e32 v115, 0xffff0000, v120
	v_lshlrev_b32_e32 v114, 16, v120
	v_and_b32_e32 v117, 0xffff0000, v121
	v_lshlrev_b32_e32 v116, 16, v121
	s_waitcnt lgkmcnt(0)
	v_pk_mul_f32 v[110:111], v[110:111], v[114:115]
	v_pk_mul_f32 v[112:113], v[112:113], v[116:117]
	v_cvt_pk_bf16_f32 v110, v110, v111
	v_cvt_pk_bf16_f32 v111, v112, v113
	flat_store_dwordx2 v[118:119], v[110:111]
	ds_read_b128 v[110:113], v98 offset:2176
	v_and_b32_e32 v115, 0xffff0000, v124
	v_lshlrev_b32_e32 v114, 16, v124
	v_and_b32_e32 v117, 0xffff0000, v125
	v_lshlrev_b32_e32 v116, 16, v125
	s_waitcnt lgkmcnt(0)
	v_pk_mul_f32 v[110:111], v[110:111], v[114:115]
	v_pk_mul_f32 v[112:113], v[112:113], v[116:117]
	v_cvt_pk_bf16_f32 v110, v110, v111
	v_cvt_pk_bf16_f32 v111, v112, v113
	flat_store_dwordx2 v[122:123], v[110:111]
	ds_read_b128 v[110:113], v98 offset:3264
	v_and_b32_e32 v115, 0xffff0000, v128
	v_lshlrev_b32_e32 v114, 16, v128
	v_mov_b32_e32 v150, v132
	s_waitcnt lgkmcnt(0)
	v_pk_mul_f32 v[110:111], v[110:111], v[114:115]
	v_and_b32_e32 v115, 0xffff0000, v129
	v_lshlrev_b32_e32 v114, 16, v129
	v_pk_mul_f32 v[112:113], v[112:113], v[114:115]
	v_cvt_pk_bf16_f32 v110, v110, v111
	v_cvt_pk_bf16_f32 v111, v112, v113
	flat_store_dwordx2 v[126:127], v[110:111]
	ds_read_b128 v[110:113], v98 offset:4352
	v_and_b32_e32 v115, 0xffff0000, v136
	v_lshlrev_b32_e32 v114, 16, v136
	s_waitcnt lgkmcnt(0)
	v_pk_mul_f32 v[110:111], v[110:111], v[114:115]
	v_and_b32_e32 v115, 0xffff0000, v137
	v_lshlrev_b32_e32 v114, 16, v137
	v_pk_mul_f32 v[112:113], v[112:113], v[114:115]
	v_cvt_pk_bf16_f32 v110, v110, v111
	v_cvt_pk_bf16_f32 v111, v112, v113
	flat_store_dwordx2 v[134:135], v[110:111]
	ds_read_b128 v[110:113], v98 offset:5440
	v_and_b32_e32 v115, 0xffff0000, v140
	v_lshlrev_b32_e32 v114, 16, v140
	s_waitcnt lgkmcnt(0)
	v_pk_mul_f32 v[110:111], v[110:111], v[114:115]
	v_and_b32_e32 v115, 0xffff0000, v141
	v_lshlrev_b32_e32 v114, 16, v141
	v_pk_mul_f32 v[112:113], v[112:113], v[114:115]
	v_cvt_pk_bf16_f32 v110, v110, v111
	v_cvt_pk_bf16_f32 v111, v112, v113
	flat_store_dwordx2 v[138:139], v[110:111]
	ds_read_b128 v[110:113], v98 offset:6528
	v_and_b32_e32 v115, 0xffff0000, v144
	v_lshlrev_b32_e32 v114, 16, v144
	s_waitcnt lgkmcnt(0)
	v_pk_mul_f32 v[110:111], v[110:111], v[114:115]
	v_and_b32_e32 v115, 0xffff0000, v145
	v_lshlrev_b32_e32 v114, 16, v145
	v_pk_mul_f32 v[112:113], v[112:113], v[114:115]
	v_cvt_pk_bf16_f32 v110, v110, v111
	v_cvt_pk_bf16_f32 v111, v112, v113
	flat_store_dwordx2 v[142:143], v[110:111]
	ds_read_b128 v[110:113], v98 offset:7616
	v_and_b32_e32 v115, 0xffff0000, v148
	v_lshlrev_b32_e32 v114, 16, v148
	s_waitcnt lgkmcnt(0)
	v_pk_mul_f32 v[110:111], v[110:111], v[114:115]
	v_and_b32_e32 v115, 0xffff0000, v149
	v_lshlrev_b32_e32 v114, 16, v149
	v_pk_mul_f32 v[112:113], v[112:113], v[114:115]
	v_cvt_pk_bf16_f32 v110, v110, v111
	v_cvt_pk_bf16_f32 v111, v112, v113
	flat_store_dwordx2 v[146:147], v[110:111]
	ds_write_b128 v99, v[66:69]
	v_or_b32_e32 v68, 32, v107
	v_or_b32_e32 v66, v68, v108
	v_ashrrev_i32_e32 v67, 31, v66
	v_lshlrev_b64 v[66:67], 11, v[66:67]
	ds_write_b128 v99, v[70:73] offset:64
	ds_write_b128 v99, v[74:77] offset:128
	ds_write_b128 v99, v[78:81] offset:192
	ds_write_b128 v99, v[82:85] offset:4352
	ds_write_b128 v99, v[86:89] offset:4416
	ds_write_b128 v99, v[90:93] offset:4480
	ds_write_b128 v99, v[94:97] offset:4544
	v_lshl_add_u64 v[70:71], v[0:1], 0, v[66:67]
	flat_load_dwordx2 v[72:73], v[70:71]
	v_or_b32_e32 v66, v68, v100
	v_ashrrev_i32_e32 v67, 31, v66
	v_lshlrev_b64 v[66:67], 11, v[66:67]
	v_lshl_add_u64 v[74:75], v[0:1], 0, v[66:67]
	flat_load_dwordx2 v[76:77], v[74:75]
	v_or_b32_e32 v66, v68, v101
	v_ashrrev_i32_e32 v67, 31, v66
	v_lshlrev_b64 v[66:67], 11, v[66:67]
	v_lshl_add_u64 v[78:79], v[0:1], 0, v[66:67]
	flat_load_dwordx2 v[80:81], v[78:79]
	v_or_b32_e32 v66, v68, v102
	v_ashrrev_i32_e32 v67, 31, v66
	v_lshlrev_b64 v[66:67], 11, v[66:67]
	v_lshl_add_u64 v[82:83], v[0:1], 0, v[66:67]
	flat_load_dwordx2 v[84:85], v[82:83]
	v_or_b32_e32 v66, v68, v103
	v_ashrrev_i32_e32 v67, 31, v66
	v_lshlrev_b64 v[66:67], 11, v[66:67]
	v_lshl_add_u64 v[86:87], v[0:1], 0, v[66:67]
	flat_load_dwordx2 v[88:89], v[86:87]
	v_or_b32_e32 v66, v68, v104
	v_ashrrev_i32_e32 v67, 31, v66
	v_lshlrev_b64 v[66:67], 11, v[66:67]
	v_lshl_add_u64 v[90:91], v[0:1], 0, v[66:67]
	flat_load_dwordx2 v[92:93], v[90:91]
	v_or_b32_e32 v66, v68, v105
	v_ashrrev_i32_e32 v67, 31, v66
	v_lshlrev_b64 v[66:67], 11, v[66:67]
	v_lshl_add_u64 v[94:95], v[0:1], 0, v[66:67]
	flat_load_dwordx2 v[96:97], v[94:95]
	v_or_b32_e32 v66, v68, v106
	v_ashrrev_i32_e32 v67, 31, v66
	v_lshlrev_b64 v[66:67], 11, v[66:67]
	v_lshl_add_u64 v[110:111], v[0:1], 0, v[66:67]
	flat_load_dwordx2 v[112:113], v[110:111]
	ds_read_b128 v[66:69], v98
	s_waitcnt vmcnt(0) lgkmcnt(0)
	v_and_b32_e32 v115, 0xffff0000, v72
	v_lshlrev_b32_e32 v114, 16, v72
	v_and_b32_e32 v117, 0xffff0000, v73
	v_lshlrev_b32_e32 v116, 16, v73
	v_pk_mul_f32 v[66:67], v[66:67], v[114:115]
	v_pk_mul_f32 v[68:69], v[68:69], v[116:117]
	v_cvt_pk_bf16_f32 v66, v66, v67
	v_cvt_pk_bf16_f32 v67, v68, v69
	flat_store_dwordx2 v[70:71], v[66:67]
	ds_read_b128 v[66:69], v98 offset:1088
	v_and_b32_e32 v71, 0xffff0000, v76
	v_lshlrev_b32_e32 v70, 16, v76
	v_and_b32_e32 v73, 0xffff0000, v77
	v_lshlrev_b32_e32 v72, 16, v77
	s_waitcnt lgkmcnt(0)
	v_pk_mul_f32 v[66:67], v[66:67], v[70:71]
	v_pk_mul_f32 v[68:69], v[68:69], v[72:73]
	v_cvt_pk_bf16_f32 v66, v66, v67
	v_cvt_pk_bf16_f32 v67, v68, v69
	flat_store_dwordx2 v[74:75], v[66:67]
	ds_read_b128 v[66:69], v98 offset:2176
	v_and_b32_e32 v71, 0xffff0000, v80
	v_lshlrev_b32_e32 v70, 16, v80
	v_and_b32_e32 v73, 0xffff0000, v81
	v_lshlrev_b32_e32 v72, 16, v81
	s_waitcnt lgkmcnt(0)
	v_pk_mul_f32 v[66:67], v[66:67], v[70:71]
	v_pk_mul_f32 v[68:69], v[68:69], v[72:73]
	v_cvt_pk_bf16_f32 v66, v66, v67
	v_cvt_pk_bf16_f32 v67, v68, v69
	flat_store_dwordx2 v[78:79], v[66:67]
	ds_read_b128 v[66:69], v98 offset:3264
	v_and_b32_e32 v71, 0xffff0000, v84
	v_lshlrev_b32_e32 v70, 16, v84
	v_and_b32_e32 v73, 0xffff0000, v85
	v_lshlrev_b32_e32 v72, 16, v85
	s_waitcnt lgkmcnt(0)
	v_pk_mul_f32 v[66:67], v[66:67], v[70:71]
	v_pk_mul_f32 v[68:69], v[68:69], v[72:73]
	v_cvt_pk_bf16_f32 v66, v66, v67
	v_cvt_pk_bf16_f32 v67, v68, v69
	flat_store_dwordx2 v[82:83], v[66:67]
	ds_read_b128 v[66:69], v98 offset:4352
	v_and_b32_e32 v71, 0xffff0000, v88
	v_lshlrev_b32_e32 v70, 16, v88
	v_and_b32_e32 v73, 0xffff0000, v89
	v_lshlrev_b32_e32 v72, 16, v89
	s_waitcnt lgkmcnt(0)
	v_pk_mul_f32 v[66:67], v[66:67], v[70:71]
	v_pk_mul_f32 v[68:69], v[68:69], v[72:73]
	v_cvt_pk_bf16_f32 v66, v66, v67
	v_cvt_pk_bf16_f32 v67, v68, v69
	flat_store_dwordx2 v[86:87], v[66:67]
	ds_read_b128 v[66:69], v98 offset:5440
	v_and_b32_e32 v71, 0xffff0000, v92
	v_lshlrev_b32_e32 v70, 16, v92
	v_and_b32_e32 v73, 0xffff0000, v93
	v_lshlrev_b32_e32 v72, 16, v93
	s_waitcnt lgkmcnt(0)
	v_pk_mul_f32 v[66:67], v[66:67], v[70:71]
	v_pk_mul_f32 v[68:69], v[68:69], v[72:73]
	v_cvt_pk_bf16_f32 v66, v66, v67
	v_cvt_pk_bf16_f32 v67, v68, v69
	flat_store_dwordx2 v[90:91], v[66:67]
	ds_read_b128 v[66:69], v98 offset:6528
	v_and_b32_e32 v71, 0xffff0000, v96
	v_lshlrev_b32_e32 v70, 16, v96
	v_and_b32_e32 v73, 0xffff0000, v97
	v_lshlrev_b32_e32 v72, 16, v97
	s_waitcnt lgkmcnt(0)
	v_pk_mul_f32 v[66:67], v[66:67], v[70:71]
	v_pk_mul_f32 v[68:69], v[68:69], v[72:73]
	v_cvt_pk_bf16_f32 v66, v66, v67
	v_cvt_pk_bf16_f32 v67, v68, v69
	flat_store_dwordx2 v[94:95], v[66:67]
	ds_read_b128 v[66:69], v98 offset:7616
	v_and_b32_e32 v71, 0xffff0000, v112
	v_lshlrev_b32_e32 v70, 16, v112
	v_and_b32_e32 v73, 0xffff0000, v113
	v_lshlrev_b32_e32 v72, 16, v113
	s_waitcnt lgkmcnt(0)
	v_pk_mul_f32 v[66:67], v[66:67], v[70:71]
	v_pk_mul_f32 v[68:69], v[68:69], v[72:73]
	v_cvt_pk_bf16_f32 v66, v66, v67
	v_cvt_pk_bf16_f32 v67, v68, v69
	flat_store_dwordx2 v[110:111], v[66:67]
	ds_write_b128 v99, v[34:37]
	v_or_b32_e32 v36, 64, v107
	v_or_b32_e32 v34, v36, v108
	v_ashrrev_i32_e32 v35, 31, v34
	v_lshlrev_b64 v[34:35], 11, v[34:35]
	ds_write_b128 v99, v[38:41] offset:64
	ds_write_b128 v99, v[42:45] offset:128
	ds_write_b128 v99, v[46:49] offset:192
	ds_write_b128 v99, v[50:53] offset:4352
	ds_write_b128 v99, v[54:57] offset:4416
	ds_write_b128 v99, v[58:61] offset:4480
	ds_write_b128 v99, v[62:65] offset:4544
	v_lshl_add_u64 v[38:39], v[0:1], 0, v[34:35]
	flat_load_dwordx2 v[40:41], v[38:39]
	v_or_b32_e32 v34, v36, v100
	v_ashrrev_i32_e32 v35, 31, v34
	v_lshlrev_b64 v[34:35], 11, v[34:35]
	v_lshl_add_u64 v[42:43], v[0:1], 0, v[34:35]
	flat_load_dwordx2 v[44:45], v[42:43]
	v_or_b32_e32 v34, v36, v101
	v_ashrrev_i32_e32 v35, 31, v34
	v_lshlrev_b64 v[34:35], 11, v[34:35]
	v_lshl_add_u64 v[46:47], v[0:1], 0, v[34:35]
	flat_load_dwordx2 v[48:49], v[46:47]
	v_or_b32_e32 v34, v36, v102
	v_ashrrev_i32_e32 v35, 31, v34
	v_lshlrev_b64 v[34:35], 11, v[34:35]
	v_lshl_add_u64 v[50:51], v[0:1], 0, v[34:35]
	flat_load_dwordx2 v[52:53], v[50:51]
	v_or_b32_e32 v34, v36, v103
	v_ashrrev_i32_e32 v35, 31, v34
	v_lshlrev_b64 v[34:35], 11, v[34:35]
	v_lshl_add_u64 v[54:55], v[0:1], 0, v[34:35]
	flat_load_dwordx2 v[56:57], v[54:55]
	v_or_b32_e32 v34, v36, v104
	v_ashrrev_i32_e32 v35, 31, v34
	v_lshlrev_b64 v[34:35], 11, v[34:35]
	v_lshl_add_u64 v[58:59], v[0:1], 0, v[34:35]
	flat_load_dwordx2 v[60:61], v[58:59]
	v_or_b32_e32 v34, v36, v105
	v_ashrrev_i32_e32 v35, 31, v34
	v_lshlrev_b64 v[34:35], 11, v[34:35]
	v_lshl_add_u64 v[62:63], v[0:1], 0, v[34:35]
	flat_load_dwordx2 v[64:65], v[62:63]
	v_or_b32_e32 v34, v36, v106
	v_ashrrev_i32_e32 v35, 31, v34
	v_lshlrev_b64 v[34:35], 11, v[34:35]
	v_lshl_add_u64 v[66:67], v[0:1], 0, v[34:35]
	flat_load_dwordx2 v[68:69], v[66:67]
	ds_read_b128 v[34:37], v98
	v_or_b32_e32 v76, 0x60, v107
	v_or_b32_e32 v70, v76, v108
	v_ashrrev_i32_e32 v71, 31, v70
	s_waitcnt vmcnt(0) lgkmcnt(0)
	v_and_b32_e32 v73, 0xffff0000, v40
	v_lshlrev_b32_e32 v72, 16, v40
	v_and_b32_e32 v75, 0xffff0000, v41
	v_lshlrev_b32_e32 v74, 16, v41
	v_pk_mul_f32 v[34:35], v[34:35], v[72:73]
	v_pk_mul_f32 v[36:37], v[36:37], v[74:75]
	v_cvt_pk_bf16_f32 v34, v34, v35
	v_cvt_pk_bf16_f32 v35, v36, v37
	flat_store_dwordx2 v[38:39], v[34:35]
	ds_read_b128 v[34:37], v98 offset:1088
	v_and_b32_e32 v39, 0xffff0000, v44
	v_lshlrev_b32_e32 v38, 16, v44
	v_and_b32_e32 v41, 0xffff0000, v45
	v_lshlrev_b32_e32 v40, 16, v45
	s_waitcnt lgkmcnt(0)
	v_pk_mul_f32 v[34:35], v[34:35], v[38:39]
	v_pk_mul_f32 v[36:37], v[36:37], v[40:41]
	v_cvt_pk_bf16_f32 v34, v34, v35
	v_cvt_pk_bf16_f32 v35, v36, v37
	flat_store_dwordx2 v[42:43], v[34:35]
	ds_read_b128 v[34:37], v98 offset:2176
	v_and_b32_e32 v39, 0xffff0000, v48
	v_lshlrev_b32_e32 v38, 16, v48
	v_and_b32_e32 v41, 0xffff0000, v49
	v_lshlrev_b32_e32 v40, 16, v49
	s_waitcnt lgkmcnt(0)
	v_pk_mul_f32 v[34:35], v[34:35], v[38:39]
	v_pk_mul_f32 v[36:37], v[36:37], v[40:41]
	v_cvt_pk_bf16_f32 v34, v34, v35
	v_cvt_pk_bf16_f32 v35, v36, v37
	flat_store_dwordx2 v[46:47], v[34:35]
	ds_read_b128 v[34:37], v98 offset:3264
	v_and_b32_e32 v39, 0xffff0000, v52
	v_lshlrev_b32_e32 v38, 16, v52
	v_and_b32_e32 v41, 0xffff0000, v53
	v_lshlrev_b32_e32 v40, 16, v53
	s_waitcnt lgkmcnt(0)
	v_pk_mul_f32 v[34:35], v[34:35], v[38:39]
	v_pk_mul_f32 v[36:37], v[36:37], v[40:41]
	v_cvt_pk_bf16_f32 v34, v34, v35
	v_cvt_pk_bf16_f32 v35, v36, v37
	flat_store_dwordx2 v[50:51], v[34:35]
	ds_read_b128 v[34:37], v98 offset:4352
	v_and_b32_e32 v39, 0xffff0000, v56
	v_lshlrev_b32_e32 v38, 16, v56
	v_and_b32_e32 v41, 0xffff0000, v57
	v_lshlrev_b32_e32 v40, 16, v57
	s_waitcnt lgkmcnt(0)
	v_pk_mul_f32 v[34:35], v[34:35], v[38:39]
	v_pk_mul_f32 v[36:37], v[36:37], v[40:41]
	v_cvt_pk_bf16_f32 v34, v34, v35
	v_cvt_pk_bf16_f32 v35, v36, v37
	flat_store_dwordx2 v[54:55], v[34:35]
	ds_read_b128 v[34:37], v98 offset:5440
	v_and_b32_e32 v39, 0xffff0000, v60
	v_lshlrev_b32_e32 v38, 16, v60
	v_and_b32_e32 v41, 0xffff0000, v61
	v_lshlrev_b32_e32 v40, 16, v61
	s_waitcnt lgkmcnt(0)
	v_pk_mul_f32 v[34:35], v[34:35], v[38:39]
	v_pk_mul_f32 v[36:37], v[36:37], v[40:41]
	v_cvt_pk_bf16_f32 v34, v34, v35
	v_cvt_pk_bf16_f32 v35, v36, v37
	flat_store_dwordx2 v[58:59], v[34:35]
	ds_read_b128 v[34:37], v98 offset:6528
	v_and_b32_e32 v39, 0xffff0000, v64
	v_lshlrev_b32_e32 v38, 16, v64
	v_and_b32_e32 v41, 0xffff0000, v65
	v_lshlrev_b32_e32 v40, 16, v65
	s_waitcnt lgkmcnt(0)
	v_pk_mul_f32 v[34:35], v[34:35], v[38:39]
	v_pk_mul_f32 v[36:37], v[36:37], v[40:41]
	v_cvt_pk_bf16_f32 v34, v34, v35
	v_cvt_pk_bf16_f32 v35, v36, v37
	flat_store_dwordx2 v[62:63], v[34:35]
	ds_read_b128 v[34:37], v98 offset:7616
	v_and_b32_e32 v39, 0xffff0000, v68
	v_lshlrev_b32_e32 v38, 16, v68
	v_and_b32_e32 v41, 0xffff0000, v69
	v_lshlrev_b32_e32 v40, 16, v69
	s_waitcnt lgkmcnt(0)
	v_pk_mul_f32 v[34:35], v[34:35], v[38:39]
	v_pk_mul_f32 v[36:37], v[36:37], v[40:41]
	v_cvt_pk_bf16_f32 v34, v34, v35
	v_cvt_pk_bf16_f32 v35, v36, v37
	flat_store_dwordx2 v[66:67], v[34:35]
	ds_write_b128 v99, v[2:5]
	v_lshlrev_b64 v[2:3], 11, v[70:71]
	ds_write_b128 v99, v[6:9] offset:64
	ds_write_b128 v99, v[10:13] offset:128
	ds_write_b128 v99, v[14:17] offset:192
	ds_write_b128 v99, v[18:21] offset:4352
	ds_write_b128 v99, v[22:25] offset:4416
	ds_write_b128 v99, v[26:29] offset:4480
	ds_write_b128 v99, v[30:33] offset:4544
	v_lshl_add_u64 v[4:5], v[0:1], 0, v[2:3]
	flat_load_dwordx2 v[6:7], v[4:5]
	v_or_b32_e32 v2, v76, v100
	v_ashrrev_i32_e32 v3, 31, v2
	v_lshlrev_b64 v[2:3], 11, v[2:3]
	v_lshl_add_u64 v[8:9], v[0:1], 0, v[2:3]
	flat_load_dwordx2 v[10:11], v[8:9]
	v_or_b32_e32 v2, v76, v101
	v_ashrrev_i32_e32 v3, 31, v2
	v_lshlrev_b64 v[2:3], 11, v[2:3]
	v_lshl_add_u64 v[12:13], v[0:1], 0, v[2:3]
	flat_load_dwordx2 v[14:15], v[12:13]
	v_or_b32_e32 v2, v76, v102
	v_ashrrev_i32_e32 v3, 31, v2
	v_lshlrev_b64 v[2:3], 11, v[2:3]
	v_lshl_add_u64 v[16:17], v[0:1], 0, v[2:3]
	flat_load_dwordx2 v[18:19], v[16:17]
	v_or_b32_e32 v2, v76, v103
	v_ashrrev_i32_e32 v3, 31, v2
	v_lshlrev_b64 v[2:3], 11, v[2:3]
	v_lshl_add_u64 v[20:21], v[0:1], 0, v[2:3]
	flat_load_dwordx2 v[22:23], v[20:21]
	v_or_b32_e32 v2, v76, v104
	v_ashrrev_i32_e32 v3, 31, v2
	v_lshlrev_b64 v[2:3], 11, v[2:3]
	v_lshl_add_u64 v[24:25], v[0:1], 0, v[2:3]
	flat_load_dwordx2 v[26:27], v[24:25]
	v_or_b32_e32 v2, v76, v105
	v_ashrrev_i32_e32 v3, 31, v2
	v_lshlrev_b64 v[2:3], 11, v[2:3]
	v_lshl_add_u64 v[28:29], v[0:1], 0, v[2:3]
	flat_load_dwordx2 v[30:31], v[28:29]
	v_or_b32_e32 v2, v76, v106
	v_ashrrev_i32_e32 v3, 31, v2
	v_lshlrev_b64 v[2:3], 11, v[2:3]
	v_lshl_add_u64 v[32:33], v[0:1], 0, v[2:3]
	flat_load_dwordx2 v[34:35], v[32:33]
	ds_read_b128 v[0:3], v98
	v_mov_b32_e32 v40, s51
	v_mov_b32_e32 v41, v132
	s_waitcnt vmcnt(0) lgkmcnt(0)
	v_and_b32_e32 v37, 0xffff0000, v6
	v_lshlrev_b32_e32 v36, 16, v6
	v_and_b32_e32 v39, 0xffff0000, v7
	v_lshlrev_b32_e32 v38, 16, v7
	v_pk_mul_f32 v[0:1], v[0:1], v[36:37]
	v_pk_mul_f32 v[2:3], v[2:3], v[38:39]
	v_cvt_pk_bf16_f32 v0, v0, v1
	v_cvt_pk_bf16_f32 v1, v2, v3
	flat_store_dwordx2 v[4:5], v[0:1]
	ds_read_b128 v[0:3], v98 offset:1088
	v_and_b32_e32 v5, 0xffff0000, v10
	v_lshlrev_b32_e32 v4, 16, v10
	v_and_b32_e32 v7, 0xffff0000, v11
	v_lshlrev_b32_e32 v6, 16, v11
	s_waitcnt lgkmcnt(0)
	v_pk_mul_f32 v[0:1], v[0:1], v[4:5]
	v_pk_mul_f32 v[2:3], v[2:3], v[6:7]
	v_cvt_pk_bf16_f32 v0, v0, v1
	v_cvt_pk_bf16_f32 v1, v2, v3
	flat_store_dwordx2 v[8:9], v[0:1]
	ds_read_b128 v[0:3], v98 offset:2176
	v_and_b32_e32 v5, 0xffff0000, v14
	v_lshlrev_b32_e32 v4, 16, v14
	v_and_b32_e32 v7, 0xffff0000, v15
	v_lshlrev_b32_e32 v6, 16, v15
	s_waitcnt lgkmcnt(0)
	v_pk_mul_f32 v[0:1], v[0:1], v[4:5]
	v_pk_mul_f32 v[2:3], v[2:3], v[6:7]
	v_cvt_pk_bf16_f32 v0, v0, v1
	v_cvt_pk_bf16_f32 v1, v2, v3
	flat_store_dwordx2 v[12:13], v[0:1]
	ds_read_b128 v[0:3], v98 offset:3264
	v_and_b32_e32 v5, 0xffff0000, v18
	v_lshlrev_b32_e32 v4, 16, v18
	v_and_b32_e32 v7, 0xffff0000, v19
	v_lshlrev_b32_e32 v6, 16, v19
	s_waitcnt lgkmcnt(0)
	v_pk_mul_f32 v[0:1], v[0:1], v[4:5]
	v_pk_mul_f32 v[2:3], v[2:3], v[6:7]
	v_cvt_pk_bf16_f32 v0, v0, v1
	v_cvt_pk_bf16_f32 v1, v2, v3
	flat_store_dwordx2 v[16:17], v[0:1]
	ds_read_b128 v[0:3], v98 offset:4352
	v_and_b32_e32 v5, 0xffff0000, v22
	v_lshlrev_b32_e32 v4, 16, v22
	v_and_b32_e32 v7, 0xffff0000, v23
	v_lshlrev_b32_e32 v6, 16, v23
	s_waitcnt lgkmcnt(0)
	v_pk_mul_f32 v[0:1], v[0:1], v[4:5]
	v_pk_mul_f32 v[2:3], v[2:3], v[6:7]
	v_cvt_pk_bf16_f32 v0, v0, v1
	v_cvt_pk_bf16_f32 v1, v2, v3
	flat_store_dwordx2 v[20:21], v[0:1]
	ds_read_b128 v[0:3], v98 offset:5440
	v_and_b32_e32 v5, 0xffff0000, v26
	v_lshlrev_b32_e32 v4, 16, v26
	v_and_b32_e32 v7, 0xffff0000, v27
	v_lshlrev_b32_e32 v6, 16, v27
	s_waitcnt lgkmcnt(0)
	v_pk_mul_f32 v[0:1], v[0:1], v[4:5]
	v_pk_mul_f32 v[2:3], v[2:3], v[6:7]
	v_cvt_pk_bf16_f32 v0, v0, v1
	v_cvt_pk_bf16_f32 v1, v2, v3
	flat_store_dwordx2 v[24:25], v[0:1]
	ds_read_b128 v[0:3], v98 offset:6528
	v_and_b32_e32 v5, 0xffff0000, v30
	v_lshlrev_b32_e32 v4, 16, v30
	v_and_b32_e32 v7, 0xffff0000, v31
	v_lshlrev_b32_e32 v6, 16, v31
	s_waitcnt lgkmcnt(0)
	v_pk_mul_f32 v[0:1], v[0:1], v[4:5]
	v_pk_mul_f32 v[2:3], v[2:3], v[6:7]
	v_cvt_pk_bf16_f32 v0, v0, v1
	v_cvt_pk_bf16_f32 v1, v2, v3
	flat_store_dwordx2 v[28:29], v[0:1]
	ds_read_b128 v[0:3], v98 offset:7616
	v_and_b32_e32 v5, 0xffff0000, v34
	v_lshlrev_b32_e32 v4, 16, v34
	v_and_b32_e32 v7, 0xffff0000, v35
	v_lshlrev_b32_e32 v6, 16, v35
	s_waitcnt lgkmcnt(0)
	v_pk_mul_f32 v[0:1], v[0:1], v[4:5]
	v_pk_mul_f32 v[2:3], v[2:3], v[6:7]
	v_cvt_pk_bf16_f32 v0, v0, v1
	v_cvt_pk_bf16_f32 v1, v2, v3
	flat_store_dwordx2 v[32:33], v[0:1]
	ds_read_b64 v[128:129], v40
	s_waitcnt lgkmcnt(0)
	v_lshl_add_u64 v[2:3], v[128:129], 0, s[42:43]
	v_lshlrev_b32_e32 v5, 4, v41
	v_and_b32_e32 v0, 32, v41
	v_lshrrev_b32_e32 v1, 1, v41
	v_bitop3_b32 v0, v5, v0, 48 bitop3:0x6c
	v_bfe_u32 v16, v41, 2, 4
	v_ashrrev_i32_e32 v17, 3, v41
	v_and_b32_e32 v9, 0xfffffc00, v5
	v_and_b32_e32 v18, 32, v1
	v_add_u32_e32 v1, 0x2000, v5
	v_lshrrev_b32_e32 v19, 1, v0
	v_add_u32_e32 v8, 0x4000, v5
	v_add_u32_e32 v5, 0x6000, v5
	v_and_or_b32 v4, v17, s44, v16
	v_ashrrev_i32_e32 v20, 7, v1
	v_or_b32_e32 v10, v19, v18
	v_ashrrev_i32_e32 v21, 7, v8
	v_ashrrev_i32_e32 v22, 7, v5
	v_and_or_b32 v6, v20, s44, v16
	v_lshl_add_u64 v[0:1], v[128:129], 0, s[36:37]
	v_lshl_or_b32 v130, v4, 10, v10
	v_and_or_b32 v8, v21, s44, v16
	v_and_or_b32 v5, v22, s44, v16
	v_add_u32_e32 v151, 0, v9
	v_lshl_or_b32 v4, v6, 10, v10
	v_lshl_add_u64 v[6:7], v[0:1], 0, s[4:5]
	v_lshl_or_b32 v8, v8, 10, v10
	v_lshl_or_b32 v10, v5, 10, v10
	v_add_u32_e32 v5, 0x8000, v151
	v_lshlrev_b64 v[12:13], 1, v[130:131]
	v_readfirstlane_b32 s0, v151
	v_lshl_add_u64 v[14:15], v[6:7], 0, v[12:13]
	s_mov_b32 m0, s0
	v_readfirstlane_b32 s0, v5
	v_mov_b32_e32 v5, v131
	v_add_u32_e32 v9, 0x2000, v151
	global_load_lds_dwordx4 v[14:15], off
	v_lshl_add_u64 v[12:13], v[2:3], 0, v[12:13]
	s_mov_b32 m0, s0
	v_lshlrev_b64 v[4:5], 1, v[4:5]
	v_readfirstlane_b32 s0, v9
	v_add_u32_e32 v9, 0xa000, v151
	global_load_lds_dwordx4 v[12:13], off
	v_lshl_add_u64 v[12:13], v[6:7], 0, v[4:5]
	s_mov_b32 m0, s0
	v_readfirstlane_b32 s0, v9
	global_load_lds_dwordx4 v[12:13], off
	v_lshl_add_u64 v[4:5], v[2:3], 0, v[4:5]
	s_mov_b32 m0, s0
	v_mov_b32_e32 v9, v131
	v_add_u32_e32 v11, 0x4000, v151
	global_load_lds_dwordx4 v[4:5], off
	v_lshlrev_b64 v[4:5], 1, v[8:9]
	v_readfirstlane_b32 s0, v11
	v_lshl_add_u64 v[8:9], v[6:7], 0, v[4:5]
	s_mov_b32 m0, s0
	v_lshl_add_u64 v[4:5], v[2:3], 0, v[4:5]
	global_load_lds_dwordx4 v[8:9], off
	v_add_u32_e32 v8, 0xc000, v151
	v_mov_b32_e32 v11, v131
	v_readfirstlane_b32 s0, v8
	s_mov_b32 m0, s0
	v_add_u32_e32 v8, 0x6000, v151
	global_load_lds_dwordx4 v[4:5], off
	v_lshlrev_b64 v[4:5], 1, v[10:11]
	v_readfirstlane_b32 s0, v8
	v_lshl_add_u64 v[6:7], v[6:7], 0, v[4:5]
	s_mov_b32 m0, s0
	v_lshl_add_u64 v[4:5], v[2:3], 0, v[4:5]
	global_load_lds_dwordx4 v[6:7], off
	v_add_u32_e32 v6, 0xe000, v151
	v_and_b32_e32 v23, 15, v41
	v_readfirstlane_b32 s0, v6
	s_mov_b32 m0, s0
	v_lshlrev_b32_e32 v6, 2, v41
	global_load_lds_dwordx4 v[4:5], off
	v_and_b32_e32 v4, 48, v41
	v_lshlrev_b32_e32 v5, 6, v23
	v_and_b32_e32 v6, 32, v6
	v_bitop3_b32 v152, v5, v6, v4 bitop3:0x36
	v_lshlrev_b32_e32 v5, 7, v41
	v_and_b32_e32 v153, 0x6000, v5
	v_lshlrev_b32_e32 v5, 6, v41
	v_and_b32_e32 v154, 0xffffc000, v5
	v_and_b32_e32 v5, 0x3c0, v5
	v_bitop3_b32 v156, v5, v6, v4 bitop3:0x36
	v_lshlrev_b32_e32 v4, 10, v22
	v_and_or_b32 v4, v4, s45, v19
	v_lshlrev_b32_e32 v10, 10, v16
	v_lshlrev_b32_e32 v6, 10, v21
	v_or3_b32 v130, v4, v10, v18
	v_and_or_b32 v6, v6, s45, v19
	v_lshlrev_b32_e32 v8, 10, v20
	v_lshlrev_b64 v[4:5], 1, v[130:131]
	v_or3_b32 v130, v6, v10, v18
	v_and_or_b32 v8, v8, s45, v19
	v_lshlrev_b32_e32 v11, 10, v17
	v_lshlrev_b64 v[6:7], 1, v[130:131]
	v_or3_b32 v130, v8, v10, v18
	v_and_or_b32 v11, v11, s45, v19
	s_waitcnt vmcnt(0)
	v_lshl_add_u64 v[2:3], v[2:3], 0, s[6:7]
	v_lshlrev_b64 v[8:9], 1, v[130:131]
	v_or3_b32 v130, v11, v10, v18
	v_lshl_add_u64 v[0:1], v[0:1], 0, s[8:9]
	v_lshl_add_u64 v[138:139], v[2:3], 0, v[8:9]
	v_lshlrev_b64 v[10:11], 1, v[130:131]
	v_lshl_add_u64 v[146:147], v[0:1], 0, v[8:9]
	v_mov_b32_e32 v8, 0
	v_or_b32_e32 v155, 0x800, v154
	v_or_b32_e32 v157, 0x1000, v154
	v_or_b32_e32 v158, 0x1800, v154
	v_or_b32_e32 v159, 0x2000, v154
	v_or_b32_e32 v160, 0x2800, v154
	v_or_b32_e32 v161, 0x3000, v154
	v_or_b32_e32 v162, 0x3800, v154
	v_lshl_add_u64 v[134:135], v[2:3], 0, v[4:5]
	v_lshl_add_u64 v[136:137], v[2:3], 0, v[6:7]
	v_lshl_add_u64 v[140:141], v[2:3], 0, v[10:11]
	v_lshl_add_u64 v[142:143], v[0:1], 0, v[4:5]
	v_lshl_add_u64 v[144:145], v[0:1], 0, v[6:7]
	v_lshl_add_u64 v[148:149], v[0:1], 0, v[10:11]
	s_mov_b64 s[42:43], 0
	v_mov_b32_e32 v9, v8
	v_mov_b32_e32 v10, v8
	v_mov_b32_e32 v11, v8
	v_mov_b32_e32 v20, v8
	v_mov_b32_e32 v21, v8
	v_mov_b32_e32 v22, v8
	v_mov_b32_e32 v23, v8
	v_mov_b32_e32 v28, v8
	v_mov_b32_e32 v29, v8
	v_mov_b32_e32 v30, v8
	v_mov_b32_e32 v31, v8
	v_mov_b32_e32 v36, v8
	v_mov_b32_e32 v37, v8
	v_mov_b32_e32 v38, v8
	v_mov_b32_e32 v39, v8
	v_mov_b32_e32 v0, v8
	v_mov_b32_e32 v1, v8
	v_mov_b32_e32 v2, v8
	v_mov_b32_e32 v3, v8
	v_mov_b32_e32 v4, v8
	v_mov_b32_e32 v5, v8
	v_mov_b32_e32 v6, v8
	v_mov_b32_e32 v7, v8
	v_mov_b32_e32 v12, v8
	v_mov_b32_e32 v13, v8
	v_mov_b32_e32 v14, v8
	v_mov_b32_e32 v15, v8
	v_mov_b32_e32 v16, v8
	v_mov_b32_e32 v17, v8
	v_mov_b32_e32 v18, v8
	v_mov_b32_e32 v19, v8
	v_mov_b32_e32 v24, v8
	v_mov_b32_e32 v25, v8
	v_mov_b32_e32 v26, v8
	v_mov_b32_e32 v27, v8
	v_mov_b32_e32 v32, v8
	v_mov_b32_e32 v33, v8
	v_mov_b32_e32 v34, v8
	v_mov_b32_e32 v35, v8
	v_mov_b32_e32 v40, v8
	v_mov_b32_e32 v41, v8
	v_mov_b32_e32 v42, v8
	v_mov_b32_e32 v43, v8
	v_mov_b32_e32 v44, v8
	v_mov_b32_e32 v45, v8
	v_mov_b32_e32 v46, v8
	v_mov_b32_e32 v47, v8
	v_mov_b32_e32 v48, v8
	v_mov_b32_e32 v49, v8
	v_mov_b32_e32 v50, v8
	v_mov_b32_e32 v51, v8
	v_mov_b32_e32 v52, v8
	v_mov_b32_e32 v53, v8
	v_mov_b32_e32 v54, v8
	v_mov_b32_e32 v55, v8
	v_mov_b32_e32 v56, v8
	v_mov_b32_e32 v57, v8
	v_mov_b32_e32 v58, v8
	v_mov_b32_e32 v59, v8
	v_mov_b32_e32 v60, v8
	v_mov_b32_e32 v61, v8
	v_mov_b32_e32 v62, v8
	v_mov_b32_e32 v63, v8
	v_mov_b32_e32 v64, v8
	v_mov_b32_e32 v65, v8
	v_mov_b32_e32 v66, v8
	v_mov_b32_e32 v67, v8
	v_mov_b32_e32 v68, v8
	v_mov_b32_e32 v69, v8
	v_mov_b32_e32 v70, v8
	v_mov_b32_e32 v71, v8
	v_mov_b32_e32 v72, v8
	v_mov_b32_e32 v73, v8
	v_mov_b32_e32 v74, v8
	v_mov_b32_e32 v75, v8
	v_mov_b32_e32 v76, v8
	v_mov_b32_e32 v77, v8
	v_mov_b32_e32 v78, v8
	v_mov_b32_e32 v79, v8
	v_mov_b32_e32 v80, v8
	v_mov_b32_e32 v81, v8
	v_mov_b32_e32 v82, v8
	v_mov_b32_e32 v83, v8
	v_mov_b32_e32 v84, v8
	v_mov_b32_e32 v85, v8
	v_mov_b32_e32 v86, v8
	v_mov_b32_e32 v87, v8
	v_mov_b32_e32 v88, v8
	v_mov_b32_e32 v89, v8
	v_mov_b32_e32 v90, v8
	v_mov_b32_e32 v91, v8
	v_mov_b32_e32 v92, v8
	v_mov_b32_e32 v93, v8
	v_mov_b32_e32 v94, v8
	v_mov_b32_e32 v95, v8
	v_mov_b32_e32 v96, v8
	v_mov_b32_e32 v97, v8
	v_mov_b32_e32 v98, v8
	v_mov_b32_e32 v99, v8
	v_mov_b32_e32 v100, v8
	v_mov_b32_e32 v101, v8
	v_mov_b32_e32 v102, v8
	v_mov_b32_e32 v103, v8
	v_mov_b32_e32 v104, v8
	v_mov_b32_e32 v105, v8
	v_mov_b32_e32 v106, v8
	v_mov_b32_e32 v107, v8
	v_mov_b32_e32 v108, v8
	v_mov_b32_e32 v109, v8
	v_mov_b32_e32 v110, v8
	v_mov_b32_e32 v111, v8
	v_mov_b32_e32 v112, v8
	v_mov_b32_e32 v113, v8
	v_mov_b32_e32 v114, v8
	v_mov_b32_e32 v115, v8
	v_mov_b32_e32 v116, v8
	v_mov_b32_e32 v117, v8
	v_mov_b32_e32 v118, v8
	v_mov_b32_e32 v119, v8
	v_mov_b32_e32 v120, v8
	v_mov_b32_e32 v121, v8
	v_mov_b32_e32 v122, v8
	v_mov_b32_e32 v123, v8
	v_mov_b32_e32 v124, v8
	v_mov_b32_e32 v125, v8
	v_mov_b32_e32 v126, v8
	v_mov_b32_e32 v127, v8
	s_waitcnt vmcnt(0) lgkmcnt(0)
	s_barrier
	v_readfirstlane_b32 s100, v151
	s_mov_b64 s[98:99], 0x80
	s_and_b32 s0, s29, 0x10000
	s_xor_b32 s53, s0, 0x10000
	s_add_i32 s0, s0, 0
	v_add3_u32 v130, s0, v152, v153
	v_add3_u32 v163, s0, v152, v154
	v_add3_u32 v196, s0, v156, v155
	v_add3_u32 v197, s0, v156, v157
	v_add3_u32 v198, s0, v156, v158
	v_add3_u32 v199, s0, v156, v159
	v_add3_u32 v200, s0, v156, v160
	v_add3_u32 v201, s0, v156, v161
	v_add3_u32 v202, s0, v156, v162
	ds_read_b128 v[180:183], v130 offset:32768
	ds_read_b128 v[164:167], v163
	ds_read_b128 v[168:171], v196
	ds_read_b128 v[172:175], v197
	ds_read_b128 v[176:179], v198
	ds_read_b128 v[184:187], v130 offset:34816
	ds_read_b128 v[188:191], v130 offset:36864
	ds_read_b128 v[192:195], v130 offset:38912
	s_add_i32 s101, s100, s53
	s_mov_b32 m0, s101
	s_nop 0
	global_load_lds_dwordx4 v[148:149], off
	s_add_i32 m0, s101, 0x8000
	s_nop 0
	global_load_lds_dwordx4 v[140:141], off
	s_add_i32 m0, s101, 0x2000
	s_nop 0
	global_load_lds_dwordx4 v[146:147], off
	s_add_i32 m0, s101, 0xa000
	s_nop 0
	global_load_lds_dwordx4 v[138:139], off
	s_add_i32 m0, s101, 0x4000
	s_nop 0
	global_load_lds_dwordx4 v[144:145], off
	s_add_i32 m0, s101, 0xc000
	s_nop 0
	global_load_lds_dwordx4 v[136:137], off
	s_add_i32 m0, s101, 0x6000
	s_nop 0
	global_load_lds_dwordx4 v[142:143], off
	s_add_i32 m0, s101, 0xe000
	s_nop 0
	global_load_lds_dwordx4 v[134:135], off
.LBB0_795:
	s_and_b32 s0, s29, 0x10000
	s_xor_b32 s53, s0, 0x10000
	s_add_i32 s0, s0, 0
	s_waitcnt lgkmcnt(3)
	v_mfma_f32_16x16x32_bf16 v[124:127], v[180:183], v[164:167], v[124:127]
	v_mfma_f32_16x16x32_bf16 v[108:111], v[180:183], v[168:171], v[108:111]
	v_mfma_f32_16x16x32_bf16 v[92:95], v[180:183], v[172:175], v[92:95]
	v_mfma_f32_16x16x32_bf16 v[76:79], v[180:183], v[176:179], v[76:79]
	ds_read_b128 v[240:243], v199
	ds_read_b128 v[244:247], v200
	s_waitcnt lgkmcnt(4)
	v_mfma_f32_16x16x32_bf16 v[120:123], v[184:187], v[164:167], v[120:123]
	v_mfma_f32_16x16x32_bf16 v[104:107], v[184:187], v[168:171], v[104:107]
	v_mfma_f32_16x16x32_bf16 v[88:91], v[184:187], v[172:175], v[88:91]
	v_mfma_f32_16x16x32_bf16 v[72:75], v[184:187], v[176:179], v[72:75]
	ds_read_b128 v[248:251], v201
	ds_read_b128 v[252:255], v202
	s_waitcnt lgkmcnt(5)
	v_mfma_f32_16x16x32_bf16 v[116:119], v[188:191], v[164:167], v[116:119]
	v_mfma_f32_16x16x32_bf16 v[100:103], v[188:191], v[168:171], v[100:103]
	v_mfma_f32_16x16x32_bf16 v[84:87], v[188:191], v[172:175], v[84:87]
	v_mfma_f32_16x16x32_bf16 v[68:71], v[188:191], v[176:179], v[68:71]
	s_waitcnt lgkmcnt(4)
	v_mfma_f32_16x16x32_bf16 v[112:115], v[192:195], v[164:167], v[112:115]
	v_mfma_f32_16x16x32_bf16 v[96:99], v[192:195], v[168:171], v[96:99]
	v_mfma_f32_16x16x32_bf16 v[80:83], v[192:195], v[172:175], v[80:83]
	v_mfma_f32_16x16x32_bf16 v[64:67], v[192:195], v[176:179], v[64:67]
	ds_read_b128 v[164:167], v163 offset:1024
	ds_read_b128 v[168:171], v196 offset:1024
	ds_read_b128 v[172:175], v197 offset:1024
	ds_read_b128 v[176:179], v198 offset:1024
	s_waitcnt lgkmcnt(4)
	v_mfma_f32_16x16x32_bf16 v[60:63], v[180:183], v[240:243], v[60:63]
	v_mfma_f32_16x16x32_bf16 v[44:47], v[180:183], v[244:247], v[44:47]
	v_mfma_f32_16x16x32_bf16 v[16:19], v[180:183], v[248:251], v[16:19]
	v_mfma_f32_16x16x32_bf16 v[36:39], v[180:183], v[252:255], v[36:39]
	ds_read_b128 v[180:183], v130 offset:33792
	v_mfma_f32_16x16x32_bf16 v[56:59], v[184:187], v[240:243], v[56:59]
	v_mfma_f32_16x16x32_bf16 v[40:43], v[184:187], v[244:247], v[40:43]
	v_mfma_f32_16x16x32_bf16 v[12:15], v[184:187], v[248:251], v[12:15]
	v_mfma_f32_16x16x32_bf16 v[28:31], v[184:187], v[252:255], v[28:31]
	ds_read_b128 v[184:187], v130 offset:35840
	v_mfma_f32_16x16x32_bf16 v[52:55], v[188:191], v[240:243], v[52:55]
	v_mfma_f32_16x16x32_bf16 v[32:35], v[188:191], v[244:247], v[32:35]
	v_mfma_f32_16x16x32_bf16 v[4:7], v[188:191], v[248:251], v[4:7]
	v_mfma_f32_16x16x32_bf16 v[20:23], v[188:191], v[252:255], v[20:23]
	ds_read_b128 v[188:191], v130 offset:37888
	v_mfma_f32_16x16x32_bf16 v[48:51], v[192:195], v[240:243], v[48:51]
	v_mfma_f32_16x16x32_bf16 v[24:27], v[192:195], v[244:247], v[24:27]
	v_mfma_f32_16x16x32_bf16 v[0:3], v[192:195], v[248:251], v[0:3]
	v_mfma_f32_16x16x32_bf16 v[8:11], v[192:195], v[252:255], v[8:11]
	ds_read_b128 v[192:195], v130 offset:39936
	s_waitcnt lgkmcnt(3)
	v_mfma_f32_16x16x32_bf16 v[124:127], v[180:183], v[164:167], v[124:127]
	v_mfma_f32_16x16x32_bf16 v[108:111], v[180:183], v[168:171], v[108:111]
	v_mfma_f32_16x16x32_bf16 v[92:95], v[180:183], v[172:175], v[92:95]
	v_mfma_f32_16x16x32_bf16 v[76:79], v[180:183], v[176:179], v[76:79]
	ds_read_b128 v[240:243], v199 offset:1024
	ds_read_b128 v[244:247], v200 offset:1024
	s_waitcnt lgkmcnt(4)
	v_mfma_f32_16x16x32_bf16 v[120:123], v[184:187], v[164:167], v[120:123]
	v_mfma_f32_16x16x32_bf16 v[104:107], v[184:187], v[168:171], v[104:107]
	v_mfma_f32_16x16x32_bf16 v[88:91], v[184:187], v[172:175], v[88:91]
	v_mfma_f32_16x16x32_bf16 v[72:75], v[184:187], v[176:179], v[72:75]
	ds_read_b128 v[248:251], v201 offset:1024
	ds_read_b128 v[252:255], v202 offset:1024
	s_waitcnt lgkmcnt(5)
	v_mfma_f32_16x16x32_bf16 v[116:119], v[188:191], v[164:167], v[116:119]
	v_mfma_f32_16x16x32_bf16 v[100:103], v[188:191], v[168:171], v[100:103]
	v_mfma_f32_16x16x32_bf16 v[84:87], v[188:191], v[172:175], v[84:87]
	v_mfma_f32_16x16x32_bf16 v[68:71], v[188:191], v[176:179], v[68:71]
	s_waitcnt lgkmcnt(4)
	v_mfma_f32_16x16x32_bf16 v[112:115], v[192:195], v[164:167], v[112:115]
	v_mfma_f32_16x16x32_bf16 v[96:99], v[192:195], v[168:171], v[96:99]
	v_mfma_f32_16x16x32_bf16 v[80:83], v[192:195], v[172:175], v[80:83]
	v_mfma_f32_16x16x32_bf16 v[64:67], v[192:195], v[176:179], v[64:67]
	s_waitcnt vmcnt(0) lgkmcnt(0)
	s_barrier
	s_add_i32 s101, s100, s0
	v_mfma_f32_16x16x32_bf16 v[60:63], v[180:183], v[240:243], v[60:63]
	v_mfma_f32_16x16x32_bf16 v[44:47], v[180:183], v[244:247], v[44:47]
	v_mfma_f32_16x16x32_bf16 v[16:19], v[180:183], v[248:251], v[16:19]
	v_mfma_f32_16x16x32_bf16 v[36:39], v[180:183], v[252:255], v[36:39]
	v_add3_u32 v130, s53, v152, v153
	ds_read_b128 v[180:183], v130 offset:32768
	v_add3_u32 v163, s53, v152, v154
	v_add3_u32 v196, s53, v156, v155
	v_add3_u32 v197, s53, v156, v157
	v_add3_u32 v198, s53, v156, v158
	ds_read_b128 v[164:167], v163
	ds_read_b128 v[168:171], v196
	ds_read_b128 v[172:175], v197
	ds_read_b128 v[176:179], v198
	s_cmpk_eq_i32 s42, 0x700
	s_cbranch_scc1 .Lpk_795_0
	s_mov_b32 m0, s101
	v_lshl_add_u64 v[148:149], v[148:149], 0, s[98:99]
	global_load_lds_dwordx4 v[148:149], off
.Lpk_795_0:
	s_cmpk_eq_i32 s42, 0x700
	s_cbranch_scc1 .Lpk_795_1
	s_add_i32 m0, s101, 0x8000
	v_lshl_add_u64 v[140:141], v[140:141], 0, s[98:99]
	global_load_lds_dwordx4 v[140:141], off
.Lpk_795_1:
	v_mfma_f32_16x16x32_bf16 v[56:59], v[184:187], v[240:243], v[56:59]
	v_mfma_f32_16x16x32_bf16 v[40:43], v[184:187], v[244:247], v[40:43]
	v_mfma_f32_16x16x32_bf16 v[12:15], v[184:187], v[248:251], v[12:15]
	v_mfma_f32_16x16x32_bf16 v[28:31], v[184:187], v[252:255], v[28:31]
	ds_read_b128 v[184:187], v130 offset:34816
	v_add3_u32 v199, s53, v156, v159
	v_add3_u32 v200, s53, v156, v160
	v_add3_u32 v201, s53, v156, v161
	v_add3_u32 v202, s53, v156, v162
	s_cmpk_eq_i32 s42, 0x700
	s_cbranch_scc1 .Lpk_795_2
	s_add_i32 m0, s101, 0x2000
	v_lshl_add_u64 v[146:147], v[146:147], 0, s[98:99]
	global_load_lds_dwordx4 v[146:147], off
.Lpk_795_2:
	s_cmpk_eq_i32 s42, 0x700
	s_cbranch_scc1 .Lpk_795_3
	s_add_i32 m0, s101, 0xa000
	v_lshl_add_u64 v[138:139], v[138:139], 0, s[98:99]
	global_load_lds_dwordx4 v[138:139], off
.Lpk_795_3:
	v_mfma_f32_16x16x32_bf16 v[52:55], v[188:191], v[240:243], v[52:55]
	v_mfma_f32_16x16x32_bf16 v[32:35], v[188:191], v[244:247], v[32:35]
	v_mfma_f32_16x16x32_bf16 v[4:7], v[188:191], v[248:251], v[4:7]
	v_mfma_f32_16x16x32_bf16 v[20:23], v[188:191], v[252:255], v[20:23]
	ds_read_b128 v[188:191], v130 offset:36864
	s_cmpk_eq_i32 s42, 0x700
	s_cbranch_scc1 .Lpk_795_4
	s_add_i32 m0, s101, 0x4000
	v_lshl_add_u64 v[144:145], v[144:145], 0, s[98:99]
	global_load_lds_dwordx4 v[144:145], off
.Lpk_795_4:
	s_cmpk_eq_i32 s42, 0x700
	s_cbranch_scc1 .Lpk_795_5
	s_add_i32 m0, s101, 0xc000
	v_lshl_add_u64 v[136:137], v[136:137], 0, s[98:99]
	global_load_lds_dwordx4 v[136:137], off
.Lpk_795_5:
	v_mfma_f32_16x16x32_bf16 v[48:51], v[192:195], v[240:243], v[48:51]
	v_mfma_f32_16x16x32_bf16 v[24:27], v[192:195], v[244:247], v[24:27]
	v_mfma_f32_16x16x32_bf16 v[0:3], v[192:195], v[248:251], v[0:3]
	v_mfma_f32_16x16x32_bf16 v[8:11], v[192:195], v[252:255], v[8:11]
	ds_read_b128 v[192:195], v130 offset:38912
	s_cmpk_eq_i32 s42, 0x700
	s_cbranch_scc1 .Lpk_795_6
	s_add_i32 m0, s101, 0x6000
	v_lshl_add_u64 v[142:143], v[142:143], 0, s[98:99]
	global_load_lds_dwordx4 v[142:143], off
.Lpk_795_6:
	s_cmpk_eq_i32 s42, 0x700
	s_cbranch_scc1 .Lpk_795_7
	s_add_i32 m0, s101, 0xe000
	v_lshl_add_u64 v[134:135], v[134:135], 0, s[98:99]
	global_load_lds_dwordx4 v[134:135], off
.Lpk_795_7:
	s_add_i32 s29, s29, 0x10000
	s_add_u32 s42, s42, 0x80
	s_addc_u32 s43, s43, 0
	s_cmpk_lg_i32 s42, 0x780
	s_cbranch_scc1 .LBB0_795
	s_waitcnt lgkmcnt(0)
	v_add3_u32 v130, s46, v156, v162
	v_add3_u32 v151, s46, v156, v161
	v_add3_u32 v206, s46, v156, v160
	v_add3_u32 v198, s46, v156, v159
	v_add3_u32 v186, s46, v156, v158
	v_add3_u32 v187, s46, v156, v157
	v_add3_u32 v188, s46, v156, v155
	v_add3_u32 v189, s46, v152, v154
	v_add3_u32 v190, s47, v152, v153
	ds_read_b128 v[134:137], v130
	ds_read_b128 v[138:141], v151
	ds_read_b128 v[142:145], v206
	ds_read_b128 v[146:149], v198
	ds_read_b128 v[158:161], v186
	ds_read_b128 v[162:165], v187
	ds_read_b128 v[166:169], v188
	ds_read_b128 v[154:157], v189
	ds_read_b128 v[170:173], v190
	s_waitcnt lgkmcnt(0)
	v_mfma_f32_16x16x32_bf16 v[16:19], v[170:173], v[138:141], v[16:19]
	v_mfma_f32_16x16x32_bf16 v[174:177], v[170:173], v[134:137], v[36:39]
	s_nop 2
	ds_read_b128 v[36:39], v190 offset:2048
	s_waitcnt lgkmcnt(0)
	v_mfma_f32_16x16x32_bf16 v[12:15], v[36:39], v[138:141], v[12:15]
	v_mfma_f32_16x16x32_bf16 v[60:63], v[170:173], v[146:149], v[60:63]
	v_mfma_f32_16x16x32_bf16 v[28:31], v[36:39], v[134:137], v[28:31]
	v_mfma_f32_16x16x32_bf16 v[56:59], v[36:39], v[146:149], v[56:59]
	ds_read_b128 v[178:181], v190 offset:4096
	s_waitcnt lgkmcnt(0)
	v_mfma_f32_16x16x32_bf16 v[182:185], v[178:181], v[134:137], v[20:23]
	v_mfma_f32_16x16x32_bf16 v[52:55], v[178:181], v[146:149], v[52:55]
	s_nop 1
	ds_read_b128 v[20:23], v190 offset:6144
	s_waitcnt lgkmcnt(0)
	v_mfma_f32_16x16x32_bf16 v[134:137], v[20:23], v[134:137], v[8:11]
	v_mfma_f32_16x16x32_bf16 v[8:11], v[20:23], v[154:157], v[112:115]
	v_mfma_f32_16x16x32_bf16 v[112:115], v[20:23], v[158:161], v[64:67]
	v_mfma_f32_16x16x32_bf16 v[64:67], v[178:181], v[154:157], v[116:119]
	v_mfma_f32_16x16x32_bf16 v[116:119], v[178:181], v[158:161], v[68:71]
	v_mfma_f32_16x16x32_bf16 v[68:71], v[36:39], v[154:157], v[120:123]
	v_mfma_f32_16x16x32_bf16 v[120:123], v[36:39], v[158:161], v[72:75]
	v_mfma_f32_16x16x32_bf16 v[72:75], v[170:173], v[154:157], v[124:127]
	v_mfma_f32_16x16x32_bf16 v[124:127], v[170:173], v[158:161], v[76:79]
	v_mfma_f32_16x16x32_bf16 v[48:51], v[20:23], v[146:149], v[48:51]
	v_mfma_f32_16x16x32_bf16 v[146:149], v[170:173], v[142:145], v[44:47]
	v_mfma_f32_16x16x32_bf16 v[152:155], v[36:39], v[142:145], v[40:43]
	v_mfma_f32_16x16x32_bf16 v[156:159], v[178:181], v[142:145], v[32:35]
	v_mfma_f32_16x16x32_bf16 v[24:27], v[20:23], v[142:145], v[24:27]
	v_mfma_f32_16x16x32_bf16 v[142:145], v[178:181], v[138:141], v[4:7]
	v_mfma_f32_16x16x32_bf16 v[108:111], v[170:173], v[166:169], v[108:111]
	v_mfma_f32_16x16x32_bf16 v[92:95], v[170:173], v[162:165], v[92:95]
	v_mfma_f32_16x16x32_bf16 v[104:107], v[36:39], v[166:169], v[104:107]
	v_mfma_f32_16x16x32_bf16 v[88:91], v[36:39], v[162:165], v[88:91]
	v_mfma_f32_16x16x32_bf16 v[100:103], v[178:181], v[166:169], v[100:103]
	v_mfma_f32_16x16x32_bf16 v[84:87], v[178:181], v[162:165], v[84:87]
	v_mfma_f32_16x16x32_bf16 v[96:99], v[20:23], v[166:169], v[96:99]
	v_mfma_f32_16x16x32_bf16 v[80:83], v[20:23], v[162:165], v[80:83]
	v_mfma_f32_16x16x32_bf16 v[20:23], v[20:23], v[138:141], v[0:3]
	ds_read_b128 v[138:141], v190 offset:1024
	ds_read_b128 v[160:163], v190 offset:3072
	ds_read_b128 v[164:167], v190 offset:5120
	ds_read_b128 v[168:171], v190 offset:7168
	ds_read_b128 v[0:3], v189 offset:1024
	ds_read_b128 v[4:7], v188 offset:1024
	ds_read_b128 v[32:35], v187 offset:1024
	ds_read_b128 v[36:39], v186 offset:1024
	s_waitcnt lgkmcnt(3)
	v_mfma_f32_16x16x32_bf16 v[178:181], v[138:141], v[0:3], v[72:75]
	v_mfma_f32_16x16x32_bf16 v[186:189], v[160:163], v[0:3], v[68:71]
	v_mfma_f32_16x16x32_bf16 v[190:193], v[164:167], v[0:3], v[64:67]
	v_mfma_f32_16x16x32_bf16 v[194:197], v[168:171], v[0:3], v[8:11]
	ds_read_b128 v[0:3], v198 offset:1024
	s_waitcnt lgkmcnt(3)
	v_mfma_f32_16x16x32_bf16 v[108:111], v[138:141], v[4:7], v[108:111]
	v_mfma_f32_16x16x32_bf16 v[104:107], v[160:163], v[4:7], v[104:107]
	v_mfma_f32_16x16x32_bf16 v[198:201], v[164:167], v[4:7], v[100:103]
	v_mfma_f32_16x16x32_bf16 v[202:205], v[168:171], v[4:7], v[96:99]
	ds_read_b128 v[4:7], v206 offset:1024
	s_waitcnt lgkmcnt(3)
	v_mfma_f32_16x16x32_bf16 v[64:67], v[138:141], v[32:35], v[92:95]
	v_mfma_f32_16x16x32_bf16 v[68:71], v[160:163], v[32:35], v[88:91]
	v_mfma_f32_16x16x32_bf16 v[72:75], v[164:167], v[32:35], v[84:87]
	v_mfma_f32_16x16x32_bf16 v[76:79], v[168:171], v[32:35], v[80:83]
	ds_read_b128 v[96:99], v151 offset:1024
	s_waitcnt lgkmcnt(3)
	v_mfma_f32_16x16x32_bf16 v[80:83], v[138:141], v[36:39], v[124:127]
	v_mfma_f32_16x16x32_bf16 v[84:87], v[160:163], v[36:39], v[120:123]
	v_mfma_f32_16x16x32_bf16 v[88:91], v[164:167], v[36:39], v[116:119]
	v_mfma_f32_16x16x32_bf16 v[92:95], v[168:171], v[36:39], v[112:115]
	ds_read_b128 v[100:103], v130 offset:1024
	s_waitcnt lgkmcnt(3)
	v_mfma_f32_16x16x32_bf16 v[32:35], v[138:141], v[0:3], v[60:63]
	v_mfma_f32_16x16x32_bf16 v[36:39], v[160:163], v[0:3], v[56:59]
	v_mfma_f32_16x16x32_bf16 v[40:43], v[164:167], v[0:3], v[52:55]
	v_mfma_f32_16x16x32_bf16 v[44:47], v[168:171], v[0:3], v[48:51]
	s_waitcnt lgkmcnt(2)
	v_mfma_f32_16x16x32_bf16 v[48:51], v[138:141], v[4:7], v[146:149]
	v_mfma_f32_16x16x32_bf16 v[52:55], v[160:163], v[4:7], v[152:155]
	v_mfma_f32_16x16x32_bf16 v[56:59], v[164:167], v[4:7], v[156:159]
	v_mfma_f32_16x16x32_bf16 v[60:63], v[168:171], v[4:7], v[24:27]
	s_waitcnt lgkmcnt(1)
	v_mfma_f32_16x16x32_bf16 v[0:3], v[138:141], v[96:99], v[16:19]
	v_mfma_f32_16x16x32_bf16 v[4:7], v[160:163], v[96:99], v[12:15]
	v_mfma_f32_16x16x32_bf16 v[8:11], v[164:167], v[96:99], v[142:145]
	v_mfma_f32_16x16x32_bf16 v[12:15], v[168:171], v[96:99], v[20:23]
	s_waitcnt lgkmcnt(0)
	v_mfma_f32_16x16x32_bf16 v[16:19], v[138:141], v[100:103], v[174:177]
	v_mfma_f32_16x16x32_bf16 v[20:23], v[160:163], v[100:103], v[28:31]
	v_mfma_f32_16x16x32_bf16 v[24:27], v[164:167], v[100:103], v[182:185]
	v_mfma_f32_16x16x32_bf16 v[28:31], v[168:171], v[100:103], v[134:137]
	v_lshrrev_b32_e32 v96, 6, v150
	v_lshlrev_b32_e32 v98, 2, v150
	v_and_b32_e32 v97, 15, v150
	v_mul_lo_u32 v96, v96, s48
	v_and_b32_e32 v112, 60, v98
	v_bfe_u32 v99, v150, 4, 2
	v_add_u32_e32 v96, s46, v96
	v_and_b32_e32 v100, 48, v150
	v_lshlrev_b32_e32 v98, 2, v112
	v_mul_u32_u24_e32 v101, 0x110, v99
	v_mul_u32_u24_e32 v97, 0x110, v97
	v_add3_u32 v98, v96, v98, v101
	v_add3_u32 v101, v96, v100, v97
	s_waitcnt vmcnt(0)
	s_barrier
	ds_write_b128 v101, v[178:181]
	ds_write_b128 v101, v[186:189] offset:64
	ds_write_b128 v101, v[190:193] offset:128
	ds_write_b128 v101, v[194:197] offset:192
	ds_write_b128 v101, v[108:111] offset:4352
	ds_write_b128 v101, v[104:107] offset:4416
	ds_write_b128 v101, v[198:201] offset:4480
	ds_write_b128 v101, v[202:205] offset:4544
	ds_read_b128 v[102:105], v98
	v_ashrrev_i32_e32 v113, 1, v150
	v_and_b32_e32 v96, 0xffffff80, v113
	v_and_or_b32 v106, v150, s49, v112
	v_add_u32_e32 v100, s28, v96
	s_waitcnt lgkmcnt(0)
	v_mul_f32_e32 v102, 0xbfb8aa3b, v102
	v_mul_f32_e32 v103, 0xbfb8aa3b, v103
	v_mul_f32_e32 v104, 0xbfb8aa3b, v104
	v_mul_f32_e32 v105, 0xbfb8aa3b, v105
	v_exp_f32_e32 v102, v102
	v_exp_f32_e32 v103, v103
	v_exp_f32_e32 v104, v104
	v_exp_f32_e32 v105, v105
	v_add_f32_e32 v102, 1.0, v102
	v_add_f32_e32 v103, 1.0, v103
	v_add_f32_e32 v104, 1.0, v104
	v_add_f32_e32 v105, 1.0, v105
	v_rcp_f32_e32 v102, v102
	v_rcp_f32_e32 v103, v103
	v_rcp_f32_e32 v104, v104
	v_rcp_f32_e32 v105, v105
	v_lshl_add_u64 v[96:97], v[128:129], 0, s[38:39]
	v_lshlrev_b32_e32 v130, 1, v106
	v_cvt_pk_bf16_f32 v102, v102, v103
	v_cvt_pk_bf16_f32 v103, v104, v105
	v_or_b32_e32 v104, v100, v99
	v_lshl_add_u64 v[96:97], v[96:97], 0, v[130:131]
	v_ashrrev_i32_e32 v105, 31, v104
	v_lshl_add_u64 v[96:97], v[96:97], 0, s[26:27]
	v_lshlrev_b64 v[104:105], 11, v[104:105]
	v_lshl_add_u64 v[104:105], v[96:97], 0, v[104:105]
	flat_store_dwordx2 v[104:105], v[102:103]
	ds_read_b128 v[102:105], v98 offset:1088
	v_mov_b32_e32 v150, v132
	s_waitcnt lgkmcnt(0)
	v_mul_f32_e32 v102, 0xbfb8aa3b, v102
	v_exp_f32_e32 v102, v102
	v_mul_f32_e32 v103, 0xbfb8aa3b, v103
	v_exp_f32_e32 v103, v103
	v_add_f32_e32 v102, 1.0, v102
	v_rcp_f32_e32 v106, v102
	v_add_f32_e32 v102, 1.0, v103
	v_mul_f32_e32 v103, 0xbfb8aa3b, v104
	v_exp_f32_e32 v103, v103
	v_mul_f32_e32 v104, 0xbfb8aa3b, v105
	v_exp_f32_e32 v104, v104
	v_rcp_f32_e32 v105, v102
	v_add_f32_e32 v102, 1.0, v103
	v_rcp_f32_e32 v103, v102
	v_add_f32_e32 v102, 1.0, v104
	v_rcp_f32_e32 v107, v102
	v_or_b32_e32 v102, 4, v99
	v_cvt_pk_bf16_f32 v104, v106, v105
	v_or_b32_e32 v106, v100, v102
	v_cvt_pk_bf16_f32 v105, v103, v107
	v_ashrrev_i32_e32 v107, 31, v106
	v_lshlrev_b64 v[106:107], 11, v[106:107]
	v_lshl_add_u64 v[106:107], v[96:97], 0, v[106:107]
	flat_store_dwordx2 v[106:107], v[104:105]
	ds_read_b128 v[104:107], v98 offset:2176
	s_waitcnt lgkmcnt(0)
	v_mul_f32_e32 v103, 0xbfb8aa3b, v104
	v_exp_f32_e32 v103, v103
	v_mul_f32_e32 v104, 0xbfb8aa3b, v105
	v_exp_f32_e32 v104, v104
	v_add_f32_e32 v103, 1.0, v103
	v_rcp_f32_e32 v105, v103
	v_add_f32_e32 v103, 1.0, v104
	v_mul_f32_e32 v104, 0xbfb8aa3b, v106
	v_exp_f32_e32 v104, v104
	v_mul_f32_e32 v106, 0xbfb8aa3b, v107
	v_exp_f32_e32 v106, v106
	v_rcp_f32_e32 v107, v103
	v_add_f32_e32 v103, 1.0, v104
	v_rcp_f32_e32 v108, v103
	v_add_f32_e32 v103, 1.0, v106
	v_rcp_f32_e32 v106, v103
	v_or_b32_e32 v103, 8, v99
	v_cvt_pk_bf16_f32 v104, v105, v107
	v_cvt_pk_bf16_f32 v105, v108, v106
	v_or_b32_e32 v106, v100, v103
	v_ashrrev_i32_e32 v107, 31, v106
	v_lshlrev_b64 v[106:107], 11, v[106:107]
	v_lshl_add_u64 v[106:107], v[96:97], 0, v[106:107]
	flat_store_dwordx2 v[106:107], v[104:105]
	ds_read_b128 v[104:107], v98 offset:3264
	s_waitcnt lgkmcnt(0)
	v_mul_f32_e32 v104, 0xbfb8aa3b, v104
	v_exp_f32_e32 v104, v104
	v_mul_f32_e32 v105, 0xbfb8aa3b, v105
	v_exp_f32_e32 v105, v105
	v_add_f32_e32 v104, 1.0, v104
	v_rcp_f32_e32 v108, v104
	v_add_f32_e32 v104, 1.0, v105
	v_mul_f32_e32 v105, 0xbfb8aa3b, v106
	v_exp_f32_e32 v105, v105
	v_mul_f32_e32 v106, 0xbfb8aa3b, v107
	v_exp_f32_e32 v106, v106
	v_rcp_f32_e32 v107, v104
	v_add_f32_e32 v104, 1.0, v105
	v_rcp_f32_e32 v105, v104
	v_add_f32_e32 v104, 1.0, v106
	v_rcp_f32_e32 v109, v104
	v_or_b32_e32 v104, 12, v99
	v_cvt_pk_bf16_f32 v106, v108, v107
	v_or_b32_e32 v108, v100, v104
	v_cvt_pk_bf16_f32 v107, v105, v109
	v_ashrrev_i32_e32 v109, 31, v108
	v_lshlrev_b64 v[108:109], 11, v[108:109]
	v_lshl_add_u64 v[108:109], v[96:97], 0, v[108:109]
	flat_store_dwordx2 v[108:109], v[106:107]
	ds_read_b128 v[106:109], v98 offset:4352
	s_waitcnt lgkmcnt(0)
	v_mul_f32_e32 v105, 0xbfb8aa3b, v106
	v_exp_f32_e32 v105, v105
	v_mul_f32_e32 v106, 0xbfb8aa3b, v107
	v_exp_f32_e32 v106, v106
	v_add_f32_e32 v105, 1.0, v105
	v_rcp_f32_e32 v107, v105
	v_add_f32_e32 v105, 1.0, v106
	v_mul_f32_e32 v106, 0xbfb8aa3b, v108
	v_exp_f32_e32 v106, v106
	v_mul_f32_e32 v108, 0xbfb8aa3b, v109
	v_exp_f32_e32 v108, v108
	v_rcp_f32_e32 v109, v105
	v_add_f32_e32 v105, 1.0, v106
	v_rcp_f32_e32 v110, v105
	v_add_f32_e32 v105, 1.0, v108
	v_rcp_f32_e32 v108, v105
	v_or_b32_e32 v105, 16, v99
	v_cvt_pk_bf16_f32 v106, v107, v109
	v_cvt_pk_bf16_f32 v107, v110, v108
	v_or_b32_e32 v108, v100, v105
	v_ashrrev_i32_e32 v109, 31, v108
	v_lshlrev_b64 v[108:109], 11, v[108:109]
	v_lshl_add_u64 v[108:109], v[96:97], 0, v[108:109]
	flat_store_dwordx2 v[108:109], v[106:107]
	ds_read_b128 v[106:109], v98 offset:5440
	s_waitcnt lgkmcnt(0)
	v_mul_f32_e32 v106, 0xbfb8aa3b, v106
	v_exp_f32_e32 v106, v106
	v_mul_f32_e32 v107, 0xbfb8aa3b, v107
	v_exp_f32_e32 v107, v107
	v_add_f32_e32 v106, 1.0, v106
	v_rcp_f32_e32 v110, v106
	v_add_f32_e32 v106, 1.0, v107
	v_mul_f32_e32 v107, 0xbfb8aa3b, v108
	v_exp_f32_e32 v107, v107
	v_mul_f32_e32 v108, 0xbfb8aa3b, v109
	v_exp_f32_e32 v108, v108
	v_rcp_f32_e32 v109, v106
	v_add_f32_e32 v106, 1.0, v107
	v_rcp_f32_e32 v107, v106
	v_add_f32_e32 v106, 1.0, v108
	v_rcp_f32_e32 v111, v106
	v_or_b32_e32 v106, 20, v99
	v_cvt_pk_bf16_f32 v108, v110, v109
	v_or_b32_e32 v110, v100, v106
	v_cvt_pk_bf16_f32 v109, v107, v111
	v_ashrrev_i32_e32 v111, 31, v110
	v_lshlrev_b64 v[110:111], 11, v[110:111]
	v_lshl_add_u64 v[110:111], v[96:97], 0, v[110:111]
	flat_store_dwordx2 v[110:111], v[108:109]
	ds_read_b128 v[108:111], v98 offset:6528
	s_waitcnt lgkmcnt(0)
	v_mul_f32_e32 v107, 0xbfb8aa3b, v108
	v_exp_f32_e32 v107, v107
	v_mul_f32_e32 v108, 0xbfb8aa3b, v109
	v_exp_f32_e32 v108, v108
	v_add_f32_e32 v107, 1.0, v107
	v_rcp_f32_e32 v109, v107
	v_add_f32_e32 v107, 1.0, v108
	v_mul_f32_e32 v108, 0xbfb8aa3b, v110
	v_exp_f32_e32 v108, v108
	v_mul_f32_e32 v110, 0xbfb8aa3b, v111
	v_exp_f32_e32 v110, v110
	v_rcp_f32_e32 v111, v107
	v_add_f32_e32 v107, 1.0, v108
	v_rcp_f32_e32 v112, v107
	v_add_f32_e32 v107, 1.0, v110
	v_rcp_f32_e32 v110, v107
	v_or_b32_e32 v107, 24, v99
	v_cvt_pk_bf16_f32 v108, v109, v111
	v_cvt_pk_bf16_f32 v109, v112, v110
	v_or_b32_e32 v110, v100, v107
	v_ashrrev_i32_e32 v111, 31, v110
	v_lshlrev_b64 v[110:111], 11, v[110:111]
	v_lshl_add_u64 v[110:111], v[96:97], 0, v[110:111]
	flat_store_dwordx2 v[110:111], v[108:109]
	ds_read_b128 v[108:111], v98 offset:7616
	s_waitcnt lgkmcnt(0)
	v_mul_f32_e32 v108, 0xbfb8aa3b, v108
	v_exp_f32_e32 v108, v108
	v_mul_f32_e32 v109, 0xbfb8aa3b, v109
	v_exp_f32_e32 v109, v109
	v_add_f32_e32 v108, 1.0, v108
	v_rcp_f32_e32 v112, v108
	v_add_f32_e32 v108, 1.0, v109
	v_mul_f32_e32 v109, 0xbfb8aa3b, v110
	v_exp_f32_e32 v109, v109
	v_mul_f32_e32 v110, 0xbfb8aa3b, v111
	v_exp_f32_e32 v110, v110
	v_rcp_f32_e32 v111, v108
	v_add_f32_e32 v108, 1.0, v109
	v_rcp_f32_e32 v109, v108
	v_add_f32_e32 v108, 1.0, v110
	v_rcp_f32_e32 v113, v108
	v_or_b32_e32 v108, 28, v99
	v_cvt_pk_bf16_f32 v110, v112, v111
	v_or_b32_e32 v112, v100, v108
	v_cvt_pk_bf16_f32 v111, v109, v113
	v_ashrrev_i32_e32 v113, 31, v112
	v_lshlrev_b64 v[112:113], 11, v[112:113]
	v_lshl_add_u64 v[112:113], v[96:97], 0, v[112:113]
	flat_store_dwordx2 v[112:113], v[110:111]
	ds_write_b128 v101, v[64:67]
	ds_write_b128 v101, v[68:71] offset:64
	ds_write_b128 v101, v[72:75] offset:128
	ds_write_b128 v101, v[76:79] offset:192
	ds_write_b128 v101, v[80:83] offset:4352
	ds_write_b128 v101, v[84:87] offset:4416
	ds_write_b128 v101, v[88:91] offset:4480
	ds_write_b128 v101, v[92:95] offset:4544
	ds_read_b128 v[64:67], v98
	v_or_b32_e32 v68, 32, v100
	s_waitcnt lgkmcnt(0)
	v_mul_f32_e32 v64, 0xbfb8aa3b, v64
	v_mul_f32_e32 v65, 0xbfb8aa3b, v65
	v_mul_f32_e32 v66, 0xbfb8aa3b, v66
	v_mul_f32_e32 v67, 0xbfb8aa3b, v67
	v_exp_f32_e32 v64, v64
	v_exp_f32_e32 v65, v65
	v_exp_f32_e32 v66, v66
	v_exp_f32_e32 v67, v67
	v_add_f32_e32 v64, 1.0, v64
	v_add_f32_e32 v65, 1.0, v65
	v_add_f32_e32 v66, 1.0, v66
	v_add_f32_e32 v67, 1.0, v67
	v_rcp_f32_e32 v64, v64
	v_rcp_f32_e32 v65, v65
	v_rcp_f32_e32 v66, v66
	v_rcp_f32_e32 v67, v67
	v_cvt_pk_bf16_f32 v64, v64, v65
	v_cvt_pk_bf16_f32 v65, v66, v67
	v_or_b32_e32 v66, v68, v99
	v_ashrrev_i32_e32 v67, 31, v66
	v_lshlrev_b64 v[66:67], 11, v[66:67]
	v_lshl_add_u64 v[66:67], v[96:97], 0, v[66:67]
	flat_store_dwordx2 v[66:67], v[64:65]
	ds_read_b128 v[64:67], v98 offset:1088
	s_waitcnt lgkmcnt(0)
	v_mul_f32_e32 v64, 0xbfb8aa3b, v64
	v_mul_f32_e32 v65, 0xbfb8aa3b, v65
	v_mul_f32_e32 v66, 0xbfb8aa3b, v66
	v_mul_f32_e32 v67, 0xbfb8aa3b, v67
	v_exp_f32_e32 v64, v64
	v_exp_f32_e32 v65, v65
	v_exp_f32_e32 v66, v66
	v_exp_f32_e32 v67, v67
	v_add_f32_e32 v64, 1.0, v64
	v_add_f32_e32 v65, 1.0, v65
	v_add_f32_e32 v66, 1.0, v66
	v_add_f32_e32 v67, 1.0, v67
	v_rcp_f32_e32 v64, v64
	v_rcp_f32_e32 v65, v65
	v_rcp_f32_e32 v66, v66
	v_rcp_f32_e32 v67, v67
	v_cvt_pk_bf16_f32 v64, v64, v65
	v_cvt_pk_bf16_f32 v65, v66, v67
	v_or_b32_e32 v66, v68, v102
	v_ashrrev_i32_e32 v67, 31, v66
	v_lshlrev_b64 v[66:67], 11, v[66:67]
	v_lshl_add_u64 v[66:67], v[96:97], 0, v[66:67]
	flat_store_dwordx2 v[66:67], v[64:65]
	ds_read_b128 v[64:67], v98 offset:2176
	s_waitcnt lgkmcnt(0)
	v_mul_f32_e32 v64, 0xbfb8aa3b, v64
	v_mul_f32_e32 v65, 0xbfb8aa3b, v65
	v_mul_f32_e32 v66, 0xbfb8aa3b, v66
	v_mul_f32_e32 v67, 0xbfb8aa3b, v67
	v_exp_f32_e32 v64, v64
	v_exp_f32_e32 v65, v65
	v_exp_f32_e32 v66, v66
	v_exp_f32_e32 v67, v67
	v_add_f32_e32 v64, 1.0, v64
	v_add_f32_e32 v65, 1.0, v65
	v_add_f32_e32 v66, 1.0, v66
	v_add_f32_e32 v67, 1.0, v67
	v_rcp_f32_e32 v64, v64
	v_rcp_f32_e32 v65, v65
	v_rcp_f32_e32 v66, v66
	v_rcp_f32_e32 v67, v67
	v_cvt_pk_bf16_f32 v64, v64, v65
	v_cvt_pk_bf16_f32 v65, v66, v67
	v_or_b32_e32 v66, v68, v103
	v_ashrrev_i32_e32 v67, 31, v66
	v_lshlrev_b64 v[66:67], 11, v[66:67]
	v_lshl_add_u64 v[66:67], v[96:97], 0, v[66:67]
	flat_store_dwordx2 v[66:67], v[64:65]
	ds_read_b128 v[64:67], v98 offset:3264
	s_waitcnt lgkmcnt(0)
	v_mul_f32_e32 v64, 0xbfb8aa3b, v64
	v_mul_f32_e32 v65, 0xbfb8aa3b, v65
	v_mul_f32_e32 v66, 0xbfb8aa3b, v66
	v_mul_f32_e32 v67, 0xbfb8aa3b, v67
	v_exp_f32_e32 v64, v64
	v_exp_f32_e32 v65, v65
	v_exp_f32_e32 v66, v66
	v_exp_f32_e32 v67, v67
	v_add_f32_e32 v64, 1.0, v64
	v_add_f32_e32 v65, 1.0, v65
	v_add_f32_e32 v66, 1.0, v66
	v_add_f32_e32 v67, 1.0, v67
	v_rcp_f32_e32 v64, v64
	v_rcp_f32_e32 v65, v65
	v_rcp_f32_e32 v66, v66
	v_rcp_f32_e32 v67, v67
	v_cvt_pk_bf16_f32 v64, v64, v65
	v_cvt_pk_bf16_f32 v65, v66, v67
	v_or_b32_e32 v66, v68, v104
	v_ashrrev_i32_e32 v67, 31, v66
	v_lshlrev_b64 v[66:67], 11, v[66:67]
	v_lshl_add_u64 v[66:67], v[96:97], 0, v[66:67]
	flat_store_dwordx2 v[66:67], v[64:65]
	ds_read_b128 v[64:67], v98 offset:4352
	s_waitcnt lgkmcnt(0)
	v_mul_f32_e32 v64, 0xbfb8aa3b, v64
	v_mul_f32_e32 v65, 0xbfb8aa3b, v65
	v_mul_f32_e32 v66, 0xbfb8aa3b, v66
	v_mul_f32_e32 v67, 0xbfb8aa3b, v67
	v_exp_f32_e32 v64, v64
	v_exp_f32_e32 v65, v65
	v_exp_f32_e32 v66, v66
	v_exp_f32_e32 v67, v67
	v_add_f32_e32 v64, 1.0, v64
	v_add_f32_e32 v65, 1.0, v65
	v_add_f32_e32 v66, 1.0, v66
	v_add_f32_e32 v67, 1.0, v67
	v_rcp_f32_e32 v64, v64
	v_rcp_f32_e32 v65, v65
	v_rcp_f32_e32 v66, v66
	v_rcp_f32_e32 v67, v67
	v_cvt_pk_bf16_f32 v64, v64, v65
	v_cvt_pk_bf16_f32 v65, v66, v67
	v_or_b32_e32 v66, v68, v105
	v_ashrrev_i32_e32 v67, 31, v66
	v_lshlrev_b64 v[66:67], 11, v[66:67]
	v_lshl_add_u64 v[66:67], v[96:97], 0, v[66:67]
	flat_store_dwordx2 v[66:67], v[64:65]
	ds_read_b128 v[64:67], v98 offset:5440
	s_waitcnt lgkmcnt(0)
	v_mul_f32_e32 v64, 0xbfb8aa3b, v64
	v_mul_f32_e32 v65, 0xbfb8aa3b, v65
	v_mul_f32_e32 v66, 0xbfb8aa3b, v66
	v_mul_f32_e32 v67, 0xbfb8aa3b, v67
	v_exp_f32_e32 v64, v64
	v_exp_f32_e32 v65, v65
	v_exp_f32_e32 v66, v66
	v_exp_f32_e32 v67, v67
	v_add_f32_e32 v64, 1.0, v64
	v_add_f32_e32 v65, 1.0, v65
	v_add_f32_e32 v66, 1.0, v66
	v_add_f32_e32 v67, 1.0, v67
	v_rcp_f32_e32 v64, v64
	v_rcp_f32_e32 v65, v65
	v_rcp_f32_e32 v66, v66
	v_rcp_f32_e32 v67, v67
	v_cvt_pk_bf16_f32 v64, v64, v65
	v_cvt_pk_bf16_f32 v65, v66, v67
	v_or_b32_e32 v66, v68, v106
	v_ashrrev_i32_e32 v67, 31, v66
	v_lshlrev_b64 v[66:67], 11, v[66:67]
	v_lshl_add_u64 v[66:67], v[96:97], 0, v[66:67]
	flat_store_dwordx2 v[66:67], v[64:65]
	ds_read_b128 v[64:67], v98 offset:6528
	s_waitcnt lgkmcnt(0)
	v_mul_f32_e32 v64, 0xbfb8aa3b, v64
	v_mul_f32_e32 v65, 0xbfb8aa3b, v65
	v_mul_f32_e32 v66, 0xbfb8aa3b, v66
	v_mul_f32_e32 v67, 0xbfb8aa3b, v67
	v_exp_f32_e32 v64, v64
	v_exp_f32_e32 v65, v65
	v_exp_f32_e32 v66, v66
	v_exp_f32_e32 v67, v67
	v_add_f32_e32 v64, 1.0, v64
	v_add_f32_e32 v65, 1.0, v65
	v_add_f32_e32 v66, 1.0, v66
	v_add_f32_e32 v67, 1.0, v67
	v_rcp_f32_e32 v64, v64
	v_rcp_f32_e32 v65, v65
	v_rcp_f32_e32 v66, v66
	v_rcp_f32_e32 v67, v67
	v_cvt_pk_bf16_f32 v64, v64, v65
	v_cvt_pk_bf16_f32 v65, v66, v67
	v_or_b32_e32 v66, v68, v107
	v_ashrrev_i32_e32 v67, 31, v66
	v_lshlrev_b64 v[66:67], 11, v[66:67]
	v_lshl_add_u64 v[66:67], v[96:97], 0, v[66:67]
	flat_store_dwordx2 v[66:67], v[64:65]
	ds_read_b128 v[64:67], v98 offset:7616
	s_waitcnt lgkmcnt(0)
	v_mul_f32_e32 v64, 0xbfb8aa3b, v64
	v_mul_f32_e32 v65, 0xbfb8aa3b, v65
	v_mul_f32_e32 v66, 0xbfb8aa3b, v66
	v_mul_f32_e32 v67, 0xbfb8aa3b, v67
	v_exp_f32_e32 v64, v64
	v_exp_f32_e32 v65, v65
	v_exp_f32_e32 v66, v66
	v_exp_f32_e32 v67, v67
	v_add_f32_e32 v64, 1.0, v64
	v_add_f32_e32 v65, 1.0, v65
	v_add_f32_e32 v66, 1.0, v66
	v_add_f32_e32 v67, 1.0, v67
	v_rcp_f32_e32 v64, v64
	v_rcp_f32_e32 v65, v65
	v_rcp_f32_e32 v66, v66
	v_rcp_f32_e32 v67, v67
	v_cvt_pk_bf16_f32 v64, v64, v65
	v_cvt_pk_bf16_f32 v65, v66, v67
	v_or_b32_e32 v66, v68, v108
	v_ashrrev_i32_e32 v67, 31, v66
	v_lshlrev_b64 v[66:67], 11, v[66:67]
	v_lshl_add_u64 v[66:67], v[96:97], 0, v[66:67]
	flat_store_dwordx2 v[66:67], v[64:65]
	ds_write_b128 v101, v[32:35]
	ds_write_b128 v101, v[36:39] offset:64
	ds_write_b128 v101, v[40:43] offset:128
	ds_write_b128 v101, v[44:47] offset:192
	ds_write_b128 v101, v[48:51] offset:4352
	ds_write_b128 v101, v[52:55] offset:4416
	ds_write_b128 v101, v[56:59] offset:4480
	ds_write_b128 v101, v[60:63] offset:4544
	ds_read_b128 v[32:35], v98
	v_or_b32_e32 v36, 64, v100
	s_waitcnt lgkmcnt(0)
	v_mul_f32_e32 v32, 0xbfb8aa3b, v32
	v_mul_f32_e32 v33, 0xbfb8aa3b, v33
	v_mul_f32_e32 v34, 0xbfb8aa3b, v34
	v_mul_f32_e32 v35, 0xbfb8aa3b, v35
	v_exp_f32_e32 v32, v32
	v_exp_f32_e32 v33, v33
	v_exp_f32_e32 v34, v34
	v_exp_f32_e32 v35, v35
	v_add_f32_e32 v32, 1.0, v32
	v_add_f32_e32 v33, 1.0, v33
	v_add_f32_e32 v34, 1.0, v34
	v_add_f32_e32 v35, 1.0, v35
	v_rcp_f32_e32 v32, v32
	v_rcp_f32_e32 v33, v33
	v_rcp_f32_e32 v34, v34
	v_rcp_f32_e32 v35, v35
	v_cvt_pk_bf16_f32 v32, v32, v33
	v_cvt_pk_bf16_f32 v33, v34, v35
	v_or_b32_e32 v34, v36, v99
	v_ashrrev_i32_e32 v35, 31, v34
	v_lshlrev_b64 v[34:35], 11, v[34:35]
	v_lshl_add_u64 v[34:35], v[96:97], 0, v[34:35]
	flat_store_dwordx2 v[34:35], v[32:33]
	ds_read_b128 v[32:35], v98 offset:1088
	s_waitcnt lgkmcnt(0)
	v_mul_f32_e32 v32, 0xbfb8aa3b, v32
	v_mul_f32_e32 v33, 0xbfb8aa3b, v33
	v_mul_f32_e32 v34, 0xbfb8aa3b, v34
	v_mul_f32_e32 v35, 0xbfb8aa3b, v35
	v_exp_f32_e32 v32, v32
	v_exp_f32_e32 v33, v33
	v_exp_f32_e32 v34, v34
	v_exp_f32_e32 v35, v35
	v_add_f32_e32 v32, 1.0, v32
	v_add_f32_e32 v33, 1.0, v33
	v_add_f32_e32 v34, 1.0, v34
	v_add_f32_e32 v35, 1.0, v35
	v_rcp_f32_e32 v32, v32
	v_rcp_f32_e32 v33, v33
	v_rcp_f32_e32 v34, v34
	v_rcp_f32_e32 v35, v35
	v_cvt_pk_bf16_f32 v32, v32, v33
	v_cvt_pk_bf16_f32 v33, v34, v35
	v_or_b32_e32 v34, v36, v102
	v_ashrrev_i32_e32 v35, 31, v34
	v_lshlrev_b64 v[34:35], 11, v[34:35]
	v_lshl_add_u64 v[34:35], v[96:97], 0, v[34:35]
	flat_store_dwordx2 v[34:35], v[32:33]
	ds_read_b128 v[32:35], v98 offset:2176
	s_waitcnt lgkmcnt(0)
	v_mul_f32_e32 v32, 0xbfb8aa3b, v32
	v_mul_f32_e32 v33, 0xbfb8aa3b, v33
	v_mul_f32_e32 v34, 0xbfb8aa3b, v34
	v_mul_f32_e32 v35, 0xbfb8aa3b, v35
	v_exp_f32_e32 v32, v32
	v_exp_f32_e32 v33, v33
	v_exp_f32_e32 v34, v34
	v_exp_f32_e32 v35, v35
	v_add_f32_e32 v32, 1.0, v32
	v_add_f32_e32 v33, 1.0, v33
	v_add_f32_e32 v34, 1.0, v34
	v_add_f32_e32 v35, 1.0, v35
	v_rcp_f32_e32 v32, v32
	v_rcp_f32_e32 v33, v33
	v_rcp_f32_e32 v34, v34
	v_rcp_f32_e32 v35, v35
	v_cvt_pk_bf16_f32 v32, v32, v33
	v_cvt_pk_bf16_f32 v33, v34, v35
	v_or_b32_e32 v34, v36, v103
	v_ashrrev_i32_e32 v35, 31, v34
	v_lshlrev_b64 v[34:35], 11, v[34:35]
	v_lshl_add_u64 v[34:35], v[96:97], 0, v[34:35]
	flat_store_dwordx2 v[34:35], v[32:33]
	ds_read_b128 v[32:35], v98 offset:3264
	s_waitcnt lgkmcnt(0)
	v_mul_f32_e32 v32, 0xbfb8aa3b, v32
	v_mul_f32_e32 v33, 0xbfb8aa3b, v33
	v_mul_f32_e32 v34, 0xbfb8aa3b, v34
	v_mul_f32_e32 v35, 0xbfb8aa3b, v35
	v_exp_f32_e32 v32, v32
	v_exp_f32_e32 v33, v33
	v_exp_f32_e32 v34, v34
	v_exp_f32_e32 v35, v35
	v_add_f32_e32 v32, 1.0, v32
	v_add_f32_e32 v33, 1.0, v33
	v_add_f32_e32 v34, 1.0, v34
	v_add_f32_e32 v35, 1.0, v35
	v_rcp_f32_e32 v32, v32
	v_rcp_f32_e32 v33, v33
	v_rcp_f32_e32 v34, v34
	v_rcp_f32_e32 v35, v35
	v_cvt_pk_bf16_f32 v32, v32, v33
	v_cvt_pk_bf16_f32 v33, v34, v35
	v_or_b32_e32 v34, v36, v104
	v_ashrrev_i32_e32 v35, 31, v34
	v_lshlrev_b64 v[34:35], 11, v[34:35]
	v_lshl_add_u64 v[34:35], v[96:97], 0, v[34:35]
	flat_store_dwordx2 v[34:35], v[32:33]
	ds_read_b128 v[32:35], v98 offset:4352
	s_waitcnt lgkmcnt(0)
	v_mul_f32_e32 v32, 0xbfb8aa3b, v32
	v_mul_f32_e32 v33, 0xbfb8aa3b, v33
	v_mul_f32_e32 v34, 0xbfb8aa3b, v34
	v_mul_f32_e32 v35, 0xbfb8aa3b, v35
	v_exp_f32_e32 v32, v32
	v_exp_f32_e32 v33, v33
	v_exp_f32_e32 v34, v34
	v_exp_f32_e32 v35, v35
	v_add_f32_e32 v32, 1.0, v32
	v_add_f32_e32 v33, 1.0, v33
	v_add_f32_e32 v34, 1.0, v34
	v_add_f32_e32 v35, 1.0, v35
	v_rcp_f32_e32 v32, v32
	v_rcp_f32_e32 v33, v33
	v_rcp_f32_e32 v34, v34
	v_rcp_f32_e32 v35, v35
	v_cvt_pk_bf16_f32 v32, v32, v33
	v_cvt_pk_bf16_f32 v33, v34, v35
	v_or_b32_e32 v34, v36, v105
	v_ashrrev_i32_e32 v35, 31, v34
	v_lshlrev_b64 v[34:35], 11, v[34:35]
	v_lshl_add_u64 v[34:35], v[96:97], 0, v[34:35]
	flat_store_dwordx2 v[34:35], v[32:33]
	ds_read_b128 v[32:35], v98 offset:5440
	s_waitcnt lgkmcnt(0)
	v_mul_f32_e32 v32, 0xbfb8aa3b, v32
	v_mul_f32_e32 v33, 0xbfb8aa3b, v33
	v_mul_f32_e32 v34, 0xbfb8aa3b, v34
	v_mul_f32_e32 v35, 0xbfb8aa3b, v35
	v_exp_f32_e32 v32, v32
	v_exp_f32_e32 v33, v33
	v_exp_f32_e32 v34, v34
	v_exp_f32_e32 v35, v35
	v_add_f32_e32 v32, 1.0, v32
	v_add_f32_e32 v33, 1.0, v33
	v_add_f32_e32 v34, 1.0, v34
	v_add_f32_e32 v35, 1.0, v35
	v_rcp_f32_e32 v32, v32
	v_rcp_f32_e32 v33, v33
	v_rcp_f32_e32 v34, v34
	v_rcp_f32_e32 v35, v35
	v_cvt_pk_bf16_f32 v32, v32, v33
	v_cvt_pk_bf16_f32 v33, v34, v35
	v_or_b32_e32 v34, v36, v106
	v_ashrrev_i32_e32 v35, 31, v34
	v_lshlrev_b64 v[34:35], 11, v[34:35]
	v_lshl_add_u64 v[34:35], v[96:97], 0, v[34:35]
	flat_store_dwordx2 v[34:35], v[32:33]
	ds_read_b128 v[32:35], v98 offset:6528
	s_waitcnt lgkmcnt(0)
	v_mul_f32_e32 v32, 0xbfb8aa3b, v32
	v_mul_f32_e32 v33, 0xbfb8aa3b, v33
	v_mul_f32_e32 v34, 0xbfb8aa3b, v34
	v_mul_f32_e32 v35, 0xbfb8aa3b, v35
	v_exp_f32_e32 v32, v32
	v_exp_f32_e32 v33, v33
	v_exp_f32_e32 v34, v34
	v_exp_f32_e32 v35, v35
	v_add_f32_e32 v32, 1.0, v32
	v_add_f32_e32 v33, 1.0, v33
	v_add_f32_e32 v34, 1.0, v34
	v_add_f32_e32 v35, 1.0, v35
	v_rcp_f32_e32 v32, v32
	v_rcp_f32_e32 v33, v33
	v_rcp_f32_e32 v34, v34
	v_rcp_f32_e32 v35, v35
	v_cvt_pk_bf16_f32 v32, v32, v33
	v_cvt_pk_bf16_f32 v33, v34, v35
	v_or_b32_e32 v34, v36, v107
	v_ashrrev_i32_e32 v35, 31, v34
	v_lshlrev_b64 v[34:35], 11, v[34:35]
	v_lshl_add_u64 v[34:35], v[96:97], 0, v[34:35]
	flat_store_dwordx2 v[34:35], v[32:33]
	ds_read_b128 v[32:35], v98 offset:7616
	s_waitcnt lgkmcnt(0)
	v_mul_f32_e32 v32, 0xbfb8aa3b, v32
	v_mul_f32_e32 v33, 0xbfb8aa3b, v33
	v_mul_f32_e32 v34, 0xbfb8aa3b, v34
	v_mul_f32_e32 v35, 0xbfb8aa3b, v35
	v_exp_f32_e32 v32, v32
	v_exp_f32_e32 v33, v33
	v_exp_f32_e32 v34, v34
	v_exp_f32_e32 v35, v35
	v_add_f32_e32 v32, 1.0, v32
	v_add_f32_e32 v33, 1.0, v33
	v_add_f32_e32 v34, 1.0, v34
	v_add_f32_e32 v35, 1.0, v35
	v_rcp_f32_e32 v32, v32
	v_rcp_f32_e32 v33, v33
	v_rcp_f32_e32 v34, v34
	v_rcp_f32_e32 v35, v35
	v_cvt_pk_bf16_f32 v32, v32, v33
	v_cvt_pk_bf16_f32 v33, v34, v35
	v_or_b32_e32 v34, v36, v108
	v_ashrrev_i32_e32 v35, 31, v34
	v_lshlrev_b64 v[34:35], 11, v[34:35]
	v_lshl_add_u64 v[34:35], v[96:97], 0, v[34:35]
	flat_store_dwordx2 v[34:35], v[32:33]
	ds_write_b128 v101, v[0:3]
	ds_write_b128 v101, v[4:7] offset:64
	ds_write_b128 v101, v[8:11] offset:128
	ds_write_b128 v101, v[12:15] offset:192
	ds_write_b128 v101, v[16:19] offset:4352
	ds_write_b128 v101, v[20:23] offset:4416
	ds_write_b128 v101, v[24:27] offset:4480
	ds_write_b128 v101, v[28:31] offset:4544
	ds_read_b128 v[0:3], v98
	v_or_b32_e32 v4, 0x60, v100
	v_mov_b32_e32 v12, v132
	s_waitcnt lgkmcnt(0)
	v_mul_f32_e32 v0, 0xbfb8aa3b, v0
	v_mul_f32_e32 v1, 0xbfb8aa3b, v1
	v_mul_f32_e32 v2, 0xbfb8aa3b, v2
	v_mul_f32_e32 v3, 0xbfb8aa3b, v3
	v_exp_f32_e32 v0, v0
	v_exp_f32_e32 v1, v1
	v_exp_f32_e32 v2, v2
	v_exp_f32_e32 v3, v3
	v_add_f32_e32 v0, 1.0, v0
	v_add_f32_e32 v1, 1.0, v1
	v_add_f32_e32 v2, 1.0, v2
	v_add_f32_e32 v3, 1.0, v3
	v_rcp_f32_e32 v0, v0
	v_rcp_f32_e32 v1, v1
	v_rcp_f32_e32 v2, v2
	v_rcp_f32_e32 v3, v3
	v_cvt_pk_bf16_f32 v0, v0, v1
	v_cvt_pk_bf16_f32 v1, v2, v3
	v_or_b32_e32 v2, v4, v99
	v_ashrrev_i32_e32 v3, 31, v2
	v_lshlrev_b64 v[2:3], 11, v[2:3]
	v_lshl_add_u64 v[2:3], v[96:97], 0, v[2:3]
	flat_store_dwordx2 v[2:3], v[0:1]
	ds_read_b128 v[0:3], v98 offset:1088
	s_waitcnt lgkmcnt(0)
	v_mul_f32_e32 v0, 0xbfb8aa3b, v0
	v_mul_f32_e32 v1, 0xbfb8aa3b, v1
	v_mul_f32_e32 v2, 0xbfb8aa3b, v2
	v_mul_f32_e32 v3, 0xbfb8aa3b, v3
	v_exp_f32_e32 v0, v0
	v_exp_f32_e32 v1, v1
	v_exp_f32_e32 v2, v2
	v_exp_f32_e32 v3, v3
	v_add_f32_e32 v0, 1.0, v0
	v_add_f32_e32 v1, 1.0, v1
	v_add_f32_e32 v2, 1.0, v2
	v_add_f32_e32 v3, 1.0, v3
	v_rcp_f32_e32 v0, v0
	v_rcp_f32_e32 v1, v1
	v_rcp_f32_e32 v2, v2
	v_rcp_f32_e32 v3, v3
	v_cvt_pk_bf16_f32 v0, v0, v1
	v_cvt_pk_bf16_f32 v1, v2, v3
	v_or_b32_e32 v2, v4, v102
	v_ashrrev_i32_e32 v3, 31, v2
	v_lshlrev_b64 v[2:3], 11, v[2:3]
	v_lshl_add_u64 v[2:3], v[96:97], 0, v[2:3]
	flat_store_dwordx2 v[2:3], v[0:1]
	ds_read_b128 v[0:3], v98 offset:2176
	s_waitcnt lgkmcnt(0)
	v_mul_f32_e32 v0, 0xbfb8aa3b, v0
	v_mul_f32_e32 v1, 0xbfb8aa3b, v1
	v_mul_f32_e32 v2, 0xbfb8aa3b, v2
	v_mul_f32_e32 v3, 0xbfb8aa3b, v3
	v_exp_f32_e32 v0, v0
	v_exp_f32_e32 v1, v1
	v_exp_f32_e32 v2, v2
	v_exp_f32_e32 v3, v3
	v_add_f32_e32 v0, 1.0, v0
	v_add_f32_e32 v1, 1.0, v1
	v_add_f32_e32 v2, 1.0, v2
	v_add_f32_e32 v3, 1.0, v3
	v_rcp_f32_e32 v0, v0
	v_rcp_f32_e32 v1, v1
	v_rcp_f32_e32 v2, v2
	v_rcp_f32_e32 v3, v3
	v_cvt_pk_bf16_f32 v0, v0, v1
	v_cvt_pk_bf16_f32 v1, v2, v3
	v_or_b32_e32 v2, v4, v103
	v_ashrrev_i32_e32 v3, 31, v2
	v_lshlrev_b64 v[2:3], 11, v[2:3]
	v_lshl_add_u64 v[2:3], v[96:97], 0, v[2:3]
	flat_store_dwordx2 v[2:3], v[0:1]
	ds_read_b128 v[0:3], v98 offset:3264
	s_waitcnt lgkmcnt(0)
	v_mul_f32_e32 v0, 0xbfb8aa3b, v0
	v_mul_f32_e32 v1, 0xbfb8aa3b, v1
	v_mul_f32_e32 v2, 0xbfb8aa3b, v2
	v_mul_f32_e32 v3, 0xbfb8aa3b, v3
	v_exp_f32_e32 v0, v0
	v_exp_f32_e32 v1, v1
	v_exp_f32_e32 v2, v2
	v_exp_f32_e32 v3, v3
	v_add_f32_e32 v0, 1.0, v0
	v_add_f32_e32 v1, 1.0, v1
	v_add_f32_e32 v2, 1.0, v2
	v_add_f32_e32 v3, 1.0, v3
	v_rcp_f32_e32 v0, v0
	v_rcp_f32_e32 v1, v1
	v_rcp_f32_e32 v2, v2
	v_rcp_f32_e32 v3, v3
	v_cvt_pk_bf16_f32 v0, v0, v1
	v_cvt_pk_bf16_f32 v1, v2, v3
	v_or_b32_e32 v2, v4, v104
	v_ashrrev_i32_e32 v3, 31, v2
	v_lshlrev_b64 v[2:3], 11, v[2:3]
	v_lshl_add_u64 v[2:3], v[96:97], 0, v[2:3]
	flat_store_dwordx2 v[2:3], v[0:1]
	ds_read_b128 v[0:3], v98 offset:4352
	s_waitcnt lgkmcnt(0)
	v_mul_f32_e32 v0, 0xbfb8aa3b, v0
	v_mul_f32_e32 v1, 0xbfb8aa3b, v1
	v_mul_f32_e32 v2, 0xbfb8aa3b, v2
	v_mul_f32_e32 v3, 0xbfb8aa3b, v3
	v_exp_f32_e32 v0, v0
	v_exp_f32_e32 v1, v1
	v_exp_f32_e32 v2, v2
	v_exp_f32_e32 v3, v3
	v_add_f32_e32 v0, 1.0, v0
	v_add_f32_e32 v1, 1.0, v1
	v_add_f32_e32 v2, 1.0, v2
	v_add_f32_e32 v3, 1.0, v3
	v_rcp_f32_e32 v0, v0
	v_rcp_f32_e32 v1, v1
	v_rcp_f32_e32 v2, v2
	v_rcp_f32_e32 v3, v3
	v_cvt_pk_bf16_f32 v0, v0, v1
	v_cvt_pk_bf16_f32 v1, v2, v3
	v_or_b32_e32 v2, v4, v105
	v_ashrrev_i32_e32 v3, 31, v2
	v_lshlrev_b64 v[2:3], 11, v[2:3]
	v_lshl_add_u64 v[2:3], v[96:97], 0, v[2:3]
	flat_store_dwordx2 v[2:3], v[0:1]
	ds_read_b128 v[0:3], v98 offset:5440
	s_waitcnt lgkmcnt(0)
	v_mul_f32_e32 v0, 0xbfb8aa3b, v0
	v_mul_f32_e32 v1, 0xbfb8aa3b, v1
	v_mul_f32_e32 v2, 0xbfb8aa3b, v2
	v_mul_f32_e32 v3, 0xbfb8aa3b, v3
	v_exp_f32_e32 v0, v0
	v_exp_f32_e32 v1, v1
	v_exp_f32_e32 v2, v2
	v_exp_f32_e32 v3, v3
	v_add_f32_e32 v0, 1.0, v0
	v_add_f32_e32 v1, 1.0, v1
	v_add_f32_e32 v2, 1.0, v2
	v_add_f32_e32 v3, 1.0, v3
	v_rcp_f32_e32 v0, v0
	v_rcp_f32_e32 v1, v1
	v_rcp_f32_e32 v2, v2
	v_rcp_f32_e32 v3, v3
	v_cvt_pk_bf16_f32 v0, v0, v1
	v_cvt_pk_bf16_f32 v1, v2, v3
	v_or_b32_e32 v2, v4, v106
	v_ashrrev_i32_e32 v3, 31, v2
	v_lshlrev_b64 v[2:3], 11, v[2:3]
	v_lshl_add_u64 v[2:3], v[96:97], 0, v[2:3]
	flat_store_dwordx2 v[2:3], v[0:1]
	ds_read_b128 v[0:3], v98 offset:6528
	s_waitcnt lgkmcnt(0)
	v_mul_f32_e32 v0, 0xbfb8aa3b, v0
	v_mul_f32_e32 v1, 0xbfb8aa3b, v1
	v_mul_f32_e32 v2, 0xbfb8aa3b, v2
	v_mul_f32_e32 v3, 0xbfb8aa3b, v3
	v_exp_f32_e32 v0, v0
	v_exp_f32_e32 v1, v1
	v_exp_f32_e32 v2, v2
	v_exp_f32_e32 v3, v3
	v_add_f32_e32 v0, 1.0, v0
	v_add_f32_e32 v1, 1.0, v1
	v_add_f32_e32 v2, 1.0, v2
	v_add_f32_e32 v3, 1.0, v3
	v_rcp_f32_e32 v0, v0
	v_rcp_f32_e32 v1, v1
	v_rcp_f32_e32 v2, v2
	v_rcp_f32_e32 v3, v3
	v_cvt_pk_bf16_f32 v0, v0, v1
	v_cvt_pk_bf16_f32 v1, v2, v3
	v_or_b32_e32 v2, v4, v107
	v_ashrrev_i32_e32 v3, 31, v2
	v_lshlrev_b64 v[2:3], 11, v[2:3]
	v_lshl_add_u64 v[2:3], v[96:97], 0, v[2:3]
	flat_store_dwordx2 v[2:3], v[0:1]
	ds_read_b128 v[0:3], v98 offset:7616
	s_waitcnt lgkmcnt(0)
	v_mul_f32_e32 v0, 0xbfb8aa3b, v0
	v_mul_f32_e32 v1, 0xbfb8aa3b, v1
	v_mul_f32_e32 v2, 0xbfb8aa3b, v2
	v_mul_f32_e32 v3, 0xbfb8aa3b, v3
	v_exp_f32_e32 v0, v0
	v_exp_f32_e32 v1, v1
	v_exp_f32_e32 v2, v2
	v_exp_f32_e32 v3, v3
	v_add_f32_e32 v0, 1.0, v0
	v_add_f32_e32 v1, 1.0, v1
	v_add_f32_e32 v2, 1.0, v2
	v_add_f32_e32 v3, 1.0, v3
	v_rcp_f32_e32 v0, v0
	v_rcp_f32_e32 v1, v1
	v_rcp_f32_e32 v2, v2
	v_rcp_f32_e32 v3, v3
	v_cvt_pk_bf16_f32 v0, v0, v1
	v_cvt_pk_bf16_f32 v1, v2, v3
	v_or_b32_e32 v2, v4, v108
	v_ashrrev_i32_e32 v3, 31, v2
	v_lshlrev_b64 v[2:3], 11, v[2:3]
	v_lshl_add_u64 v[2:3], v[96:97], 0, v[2:3]
	flat_store_dwordx2 v[2:3], v[0:1]
	v_mov_b32_e32 v0, s3
	ds_read_b128 v[0:3], v0
	s_waitcnt lgkmcnt(0)
	v_readfirstlane_b32 s0, v3
	v_readfirstlane_b32 s29, v2
	v_lshlrev_b32_e32 v3, 4, v12
	v_and_b32_e32 v2, 32, v12
	s_add_u32 s42, s29, s36
	v_lshrrev_b32_e32 v4, 1, v12
	v_bitop3_b32 v2, v3, v2, 48 bitop3:0x6c
	s_addc_u32 s43, s0, s37
	v_bfe_u32 v13, v12, 2, 4
	v_and_b32_e32 v14, 32, v4
	v_lshrrev_b32_e32 v15, 1, v2
	v_ashrrev_i32_e32 v16, 3, v12
	s_add_u32 s36, s42, 0x18800000
	v_or_b32_e32 v6, v15, v14
	v_and_or_b32 v2, v16, s44, v13
	s_addc_u32 s37, s43, 0
	s_lshl_b64 s[38:39], s[30:31], 11
	v_and_b32_e32 v5, 0xfffffc00, v3
	v_lshl_or_b32 v130, v2, 10, v6
	v_add_u32_e32 v2, 0x2000, v3
	v_add_u32_e32 v4, 0x4000, v3
	v_add_u32_e32 v3, 0x6000, v3
	s_add_u32 s53, s29, s38
	v_ashrrev_i32_e32 v17, 7, v2
	v_ashrrev_i32_e32 v18, 7, v4
	v_ashrrev_i32_e32 v19, 7, v3
	s_addc_u32 s54, s0, s39
	v_and_or_b32 v2, v17, s44, v13
	v_and_or_b32 v4, v18, s44, v13
	v_and_or_b32 v3, v19, s44, v13
	v_add_u32_e32 v151, 0, v5
	s_add_u32 s38, s53, 0xe00000
	v_lshl_or_b32 v2, v2, 10, v6
	v_lshl_or_b32 v4, v4, 10, v6
	v_lshl_or_b32 v6, v3, 10, v6
	v_add_u32_e32 v3, 0x8000, v151
	v_lshlrev_b64 v[8:9], 1, v[130:131]
	v_readfirstlane_b32 s55, v151
	s_addc_u32 s39, s54, 0
	v_lshl_add_u64 v[10:11], s[36:37], 0, v[8:9]
	s_mov_b32 m0, s55
	v_readfirstlane_b32 s55, v3
	v_mov_b32_e32 v3, v131
	v_add_u32_e32 v5, 0x2000, v151
	global_load_lds_dwordx4 v[10:11], off
	v_lshl_add_u64 v[8:9], s[38:39], 0, v[8:9]
	s_mov_b32 m0, s55
	v_lshlrev_b64 v[2:3], 1, v[2:3]
	v_readfirstlane_b32 s55, v5
	v_add_u32_e32 v5, 0xa000, v151
	global_load_lds_dwordx4 v[8:9], off
	v_lshl_add_u64 v[8:9], s[36:37], 0, v[2:3]
	s_mov_b32 m0, s55
	v_readfirstlane_b32 s55, v5
	global_load_lds_dwordx4 v[8:9], off
	v_lshl_add_u64 v[2:3], s[38:39], 0, v[2:3]
	s_mov_b32 m0, s55
	v_mov_b32_e32 v5, v131
	v_add_u32_e32 v7, 0x4000, v151
	global_load_lds_dwordx4 v[2:3], off
	v_lshlrev_b64 v[2:3], 1, v[4:5]
	v_readfirstlane_b32 s55, v7
	v_lshl_add_u64 v[4:5], s[36:37], 0, v[2:3]
	s_mov_b32 m0, s55
	v_lshl_add_u64 v[2:3], s[38:39], 0, v[2:3]
	global_load_lds_dwordx4 v[4:5], off
	v_add_u32_e32 v4, 0xc000, v151
	v_mov_b32_e32 v7, v131
	v_readfirstlane_b32 s55, v4
	s_mov_b32 m0, s55
	v_and_b32_e32 v20, 15, v12
	global_load_lds_dwordx4 v[2:3], off
	v_lshlrev_b64 v[2:3], 1, v[6:7]
	v_add_u32_e32 v6, 0x6000, v151
	v_lshl_add_u64 v[4:5], s[36:37], 0, v[2:3]
	v_readfirstlane_b32 s36, v6
	s_mov_b32 m0, s36
	v_lshl_add_u64 v[2:3], s[38:39], 0, v[2:3]
	global_load_lds_dwordx4 v[4:5], off
	v_add_u32_e32 v4, 0xe000, v151
	v_lshlrev_b32_e32 v8, 10, v13
	v_readfirstlane_b32 s36, v4
	s_mov_b32 m0, s36
	v_lshlrev_b32_e32 v4, 2, v12
	global_load_lds_dwordx4 v[2:3], off
	v_and_b32_e32 v2, 48, v12
	v_lshlrev_b32_e32 v3, 6, v20
	v_and_b32_e32 v4, 32, v4
	v_bitop3_b32 v152, v3, v4, v2 bitop3:0x36
	v_lshlrev_b32_e32 v3, 7, v12
	v_and_b32_e32 v153, 0x6000, v3
	v_lshlrev_b32_e32 v3, 6, v12
	v_and_b32_e32 v154, 0xffffc000, v3
	v_and_b32_e32 v3, 0x3c0, v3
	v_bitop3_b32 v156, v3, v4, v2 bitop3:0x36
	v_lshlrev_b32_e32 v2, 10, v19
	v_and_or_b32 v2, v2, s45, v15
	v_lshlrev_b32_e32 v4, 10, v18
	v_or3_b32 v130, v2, v8, v14
	v_and_or_b32 v4, v4, s45, v15
	v_lshlrev_b32_e32 v6, 10, v17
	v_lshlrev_b64 v[2:3], 1, v[130:131]
	v_or3_b32 v130, v4, v8, v14
	v_and_or_b32 v6, v6, s45, v15
	v_lshlrev_b32_e32 v9, 10, v16
	v_lshlrev_b64 v[4:5], 1, v[130:131]
	v_or3_b32 v130, v6, v8, v14
	v_and_or_b32 v9, v9, s45, v15
	s_add_u32 s36, s53, 0xe00080
	v_lshlrev_b64 v[6:7], 1, v[130:131]
	v_or3_b32 v130, v9, v8, v14
	s_addc_u32 s37, s54, 0
	v_lshlrev_b64 v[8:9], 1, v[130:131]
	s_waitcnt vmcnt(0)
	v_lshl_add_u64 v[134:135], s[36:37], 0, v[2:3]
	v_lshl_add_u64 v[136:137], s[36:37], 0, v[4:5]
	v_lshl_add_u64 v[138:139], s[36:37], 0, v[6:7]
	v_lshl_add_u64 v[140:141], s[36:37], 0, v[8:9]
	s_add_u32 s36, s42, 0x18800080
	s_addc_u32 s37, s43, 0
	v_mov_b32_e32 v10, 0
	v_or_b32_e32 v155, 0x800, v154
	v_or_b32_e32 v157, 0x1000, v154
	v_or_b32_e32 v158, 0x1800, v154
	v_or_b32_e32 v159, 0x2000, v154
	v_or_b32_e32 v160, 0x2800, v154
	v_or_b32_e32 v161, 0x3000, v154
	v_or_b32_e32 v162, 0x3800, v154
	v_lshl_add_u64 v[142:143], s[36:37], 0, v[2:3]
	v_lshl_add_u64 v[144:145], s[36:37], 0, v[4:5]
	v_lshl_add_u64 v[146:147], s[36:37], 0, v[6:7]
	v_lshl_add_u64 v[148:149], s[36:37], 0, v[8:9]
	s_mov_b32 s38, 0
	s_mov_b64 s[36:37], 0
	v_mov_b32_e32 v11, v10
	v_mov_b32_e32 v12, v10
	v_mov_b32_e32 v13, v10
	v_mov_b32_e32 v22, v10
	v_mov_b32_e32 v23, v10
	v_mov_b32_e32 v24, v10
	v_mov_b32_e32 v25, v10
	v_mov_b32_e32 v30, v10
	v_mov_b32_e32 v31, v10
	v_mov_b32_e32 v32, v10
	v_mov_b32_e32 v33, v10
	v_mov_b32_e32 v38, v10
	v_mov_b32_e32 v39, v10
	v_mov_b32_e32 v40, v10
	v_mov_b32_e32 v41, v10
	v_mov_b32_e32 v2, v10
	v_mov_b32_e32 v3, v10
	v_mov_b32_e32 v4, v10
	v_mov_b32_e32 v5, v10
	v_mov_b32_e32 v6, v10
	v_mov_b32_e32 v7, v10
	v_mov_b32_e32 v8, v10
	v_mov_b32_e32 v9, v10
	v_mov_b32_e32 v14, v10
	v_mov_b32_e32 v15, v10
	v_mov_b32_e32 v16, v10
	v_mov_b32_e32 v17, v10
	v_mov_b32_e32 v18, v10
	v_mov_b32_e32 v19, v10
	v_mov_b32_e32 v20, v10
	v_mov_b32_e32 v21, v10
	v_mov_b32_e32 v26, v10
	v_mov_b32_e32 v27, v10
	v_mov_b32_e32 v28, v10
	v_mov_b32_e32 v29, v10
	v_mov_b32_e32 v34, v10
	v_mov_b32_e32 v35, v10
	v_mov_b32_e32 v36, v10
	v_mov_b32_e32 v37, v10
	v_mov_b32_e32 v42, v10
	v_mov_b32_e32 v43, v10
	v_mov_b32_e32 v44, v10
	v_mov_b32_e32 v45, v10
	v_mov_b32_e32 v46, v10
	v_mov_b32_e32 v47, v10
	v_mov_b32_e32 v48, v10
	v_mov_b32_e32 v49, v10
	v_mov_b32_e32 v50, v10
	v_mov_b32_e32 v51, v10
	v_mov_b32_e32 v52, v10
	v_mov_b32_e32 v53, v10
	v_mov_b32_e32 v54, v10
	v_mov_b32_e32 v55, v10
	v_mov_b32_e32 v56, v10
	v_mov_b32_e32 v57, v10
	v_mov_b32_e32 v58, v10
	v_mov_b32_e32 v59, v10
	v_mov_b32_e32 v60, v10
	v_mov_b32_e32 v61, v10
	v_mov_b32_e32 v62, v10
	v_mov_b32_e32 v63, v10
	v_mov_b32_e32 v64, v10
	v_mov_b32_e32 v65, v10
	v_mov_b32_e32 v66, v10
	v_mov_b32_e32 v67, v10
	v_mov_b32_e32 v68, v10
	v_mov_b32_e32 v69, v10
	v_mov_b32_e32 v70, v10
	v_mov_b32_e32 v71, v10
	v_mov_b32_e32 v72, v10
	v_mov_b32_e32 v73, v10
	v_mov_b32_e32 v74, v10
	v_mov_b32_e32 v75, v10
	v_mov_b32_e32 v76, v10
	v_mov_b32_e32 v77, v10
	v_mov_b32_e32 v78, v10
	v_mov_b32_e32 v79, v10
	v_mov_b32_e32 v80, v10
	v_mov_b32_e32 v81, v10
	v_mov_b32_e32 v82, v10
	v_mov_b32_e32 v83, v10
	v_mov_b32_e32 v84, v10
	v_mov_b32_e32 v85, v10
	v_mov_b32_e32 v86, v10
	v_mov_b32_e32 v87, v10
	v_mov_b32_e32 v88, v10
	v_mov_b32_e32 v89, v10
	v_mov_b32_e32 v90, v10
	v_mov_b32_e32 v91, v10
	v_mov_b32_e32 v92, v10
	v_mov_b32_e32 v93, v10
	v_mov_b32_e32 v94, v10
	v_mov_b32_e32 v95, v10
	v_mov_b32_e32 v96, v10
	v_mov_b32_e32 v97, v10
	v_mov_b32_e32 v98, v10
	v_mov_b32_e32 v99, v10
	v_mov_b32_e32 v100, v10
	v_mov_b32_e32 v101, v10
	v_mov_b32_e32 v102, v10
	v_mov_b32_e32 v103, v10
	v_mov_b32_e32 v104, v10
	v_mov_b32_e32 v105, v10
	v_mov_b32_e32 v106, v10
	v_mov_b32_e32 v107, v10
	v_mov_b32_e32 v108, v10
	v_mov_b32_e32 v109, v10
	v_mov_b32_e32 v110, v10
	v_mov_b32_e32 v111, v10
	v_mov_b32_e32 v112, v10
	v_mov_b32_e32 v113, v10
	v_mov_b32_e32 v114, v10
	v_mov_b32_e32 v115, v10
	v_mov_b32_e32 v116, v10
	v_mov_b32_e32 v117, v10
	v_mov_b32_e32 v118, v10
	v_mov_b32_e32 v119, v10
	v_mov_b32_e32 v120, v10
	v_mov_b32_e32 v121, v10
	v_mov_b32_e32 v122, v10
	v_mov_b32_e32 v123, v10
	v_mov_b32_e32 v124, v10
	v_mov_b32_e32 v125, v10
	v_mov_b32_e32 v126, v10
	v_mov_b32_e32 v127, v10
	v_mov_b32_e32 v128, v10
	v_mov_b32_e32 v129, v10
	s_waitcnt vmcnt(0) lgkmcnt(0)
	s_barrier
	v_readfirstlane_b32 s100, v151
	s_mov_b64 s[98:99], 0x80
	s_and_b32 s39, s38, 0x10000
	s_xor_b32 s42, s39, 0x10000
	s_add_i32 s39, s39, 0
	v_add3_u32 v130, s39, v152, v153
	v_add3_u32 v163, s39, v152, v154
	v_add3_u32 v196, s39, v156, v155
	v_add3_u32 v197, s39, v156, v157
	v_add3_u32 v198, s39, v156, v158
	v_add3_u32 v199, s39, v156, v159
	v_add3_u32 v200, s39, v156, v160
	v_add3_u32 v201, s39, v156, v161
	v_add3_u32 v202, s39, v156, v162
	ds_read_b128 v[180:183], v130 offset:32768
	ds_read_b128 v[164:167], v163
	ds_read_b128 v[168:171], v196
	ds_read_b128 v[172:175], v197
	ds_read_b128 v[176:179], v198
	ds_read_b128 v[184:187], v130 offset:34816
	ds_read_b128 v[188:191], v130 offset:36864
	ds_read_b128 v[192:195], v130 offset:38912
	s_add_i32 s101, s100, s42
	s_mov_b32 m0, s101
	s_nop 0
	global_load_lds_dwordx4 v[148:149], off
	s_add_i32 m0, s101, 0x8000
	s_nop 0
	global_load_lds_dwordx4 v[140:141], off
	s_add_i32 m0, s101, 0x2000
	s_nop 0
	global_load_lds_dwordx4 v[146:147], off
	s_add_i32 m0, s101, 0xa000
	s_nop 0
	global_load_lds_dwordx4 v[138:139], off
	s_add_i32 m0, s101, 0x4000
	s_nop 0
	global_load_lds_dwordx4 v[144:145], off
	s_add_i32 m0, s101, 0xc000
	s_nop 0
	global_load_lds_dwordx4 v[136:137], off
	s_add_i32 m0, s101, 0x6000
	s_nop 0
	global_load_lds_dwordx4 v[142:143], off
	s_add_i32 m0, s101, 0xe000
	s_nop 0
	global_load_lds_dwordx4 v[134:135], off
.LBB0_797:
	s_and_b32 s39, s38, 0x10000
	s_xor_b32 s42, s39, 0x10000
	s_add_i32 s39, s39, 0
	s_waitcnt lgkmcnt(3)
	v_mfma_f32_16x16x32_bf16 v[126:129], v[180:183], v[164:167], v[126:129]
	v_mfma_f32_16x16x32_bf16 v[110:113], v[180:183], v[168:171], v[110:113]
	v_mfma_f32_16x16x32_bf16 v[94:97], v[180:183], v[172:175], v[94:97]
	v_mfma_f32_16x16x32_bf16 v[78:81], v[180:183], v[176:179], v[78:81]
	ds_read_b128 v[240:243], v199
	ds_read_b128 v[244:247], v200
	s_waitcnt lgkmcnt(4)
	v_mfma_f32_16x16x32_bf16 v[122:125], v[184:187], v[164:167], v[122:125]
	v_mfma_f32_16x16x32_bf16 v[106:109], v[184:187], v[168:171], v[106:109]
	v_mfma_f32_16x16x32_bf16 v[90:93], v[184:187], v[172:175], v[90:93]
	v_mfma_f32_16x16x32_bf16 v[74:77], v[184:187], v[176:179], v[74:77]
	ds_read_b128 v[248:251], v201
	ds_read_b128 v[252:255], v202
	s_waitcnt lgkmcnt(5)
	v_mfma_f32_16x16x32_bf16 v[118:121], v[188:191], v[164:167], v[118:121]
	v_mfma_f32_16x16x32_bf16 v[102:105], v[188:191], v[168:171], v[102:105]
	v_mfma_f32_16x16x32_bf16 v[86:89], v[188:191], v[172:175], v[86:89]
	v_mfma_f32_16x16x32_bf16 v[70:73], v[188:191], v[176:179], v[70:73]
	s_waitcnt lgkmcnt(4)
	v_mfma_f32_16x16x32_bf16 v[114:117], v[192:195], v[164:167], v[114:117]
	v_mfma_f32_16x16x32_bf16 v[98:101], v[192:195], v[168:171], v[98:101]
	v_mfma_f32_16x16x32_bf16 v[82:85], v[192:195], v[172:175], v[82:85]
	v_mfma_f32_16x16x32_bf16 v[66:69], v[192:195], v[176:179], v[66:69]
	ds_read_b128 v[164:167], v163 offset:1024
	ds_read_b128 v[168:171], v196 offset:1024
	ds_read_b128 v[172:175], v197 offset:1024
	ds_read_b128 v[176:179], v198 offset:1024
	s_waitcnt lgkmcnt(4)
	v_mfma_f32_16x16x32_bf16 v[62:65], v[180:183], v[240:243], v[62:65]
	v_mfma_f32_16x16x32_bf16 v[46:49], v[180:183], v[244:247], v[46:49]
	v_mfma_f32_16x16x32_bf16 v[18:21], v[180:183], v[248:251], v[18:21]
	v_mfma_f32_16x16x32_bf16 v[38:41], v[180:183], v[252:255], v[38:41]
	ds_read_b128 v[180:183], v130 offset:33792
	v_mfma_f32_16x16x32_bf16 v[58:61], v[184:187], v[240:243], v[58:61]
	v_mfma_f32_16x16x32_bf16 v[42:45], v[184:187], v[244:247], v[42:45]
	v_mfma_f32_16x16x32_bf16 v[14:17], v[184:187], v[248:251], v[14:17]
	v_mfma_f32_16x16x32_bf16 v[30:33], v[184:187], v[252:255], v[30:33]
	ds_read_b128 v[184:187], v130 offset:35840
	v_mfma_f32_16x16x32_bf16 v[54:57], v[188:191], v[240:243], v[54:57]
	v_mfma_f32_16x16x32_bf16 v[34:37], v[188:191], v[244:247], v[34:37]
	v_mfma_f32_16x16x32_bf16 v[6:9], v[188:191], v[248:251], v[6:9]
	v_mfma_f32_16x16x32_bf16 v[22:25], v[188:191], v[252:255], v[22:25]
	ds_read_b128 v[188:191], v130 offset:37888
	v_mfma_f32_16x16x32_bf16 v[50:53], v[192:195], v[240:243], v[50:53]
	v_mfma_f32_16x16x32_bf16 v[26:29], v[192:195], v[244:247], v[26:29]
	v_mfma_f32_16x16x32_bf16 v[2:5], v[192:195], v[248:251], v[2:5]
	v_mfma_f32_16x16x32_bf16 v[10:13], v[192:195], v[252:255], v[10:13]
	ds_read_b128 v[192:195], v130 offset:39936
	s_waitcnt lgkmcnt(3)
	v_mfma_f32_16x16x32_bf16 v[126:129], v[180:183], v[164:167], v[126:129]
	v_mfma_f32_16x16x32_bf16 v[110:113], v[180:183], v[168:171], v[110:113]
	v_mfma_f32_16x16x32_bf16 v[94:97], v[180:183], v[172:175], v[94:97]
	v_mfma_f32_16x16x32_bf16 v[78:81], v[180:183], v[176:179], v[78:81]
	ds_read_b128 v[240:243], v199 offset:1024
	ds_read_b128 v[244:247], v200 offset:1024
	s_waitcnt lgkmcnt(4)
	v_mfma_f32_16x16x32_bf16 v[122:125], v[184:187], v[164:167], v[122:125]
	v_mfma_f32_16x16x32_bf16 v[106:109], v[184:187], v[168:171], v[106:109]
	v_mfma_f32_16x16x32_bf16 v[90:93], v[184:187], v[172:175], v[90:93]
	v_mfma_f32_16x16x32_bf16 v[74:77], v[184:187], v[176:179], v[74:77]
	ds_read_b128 v[248:251], v201 offset:1024
	ds_read_b128 v[252:255], v202 offset:1024
	s_waitcnt lgkmcnt(5)
	v_mfma_f32_16x16x32_bf16 v[118:121], v[188:191], v[164:167], v[118:121]
	v_mfma_f32_16x16x32_bf16 v[102:105], v[188:191], v[168:171], v[102:105]
	v_mfma_f32_16x16x32_bf16 v[86:89], v[188:191], v[172:175], v[86:89]
	v_mfma_f32_16x16x32_bf16 v[70:73], v[188:191], v[176:179], v[70:73]
	s_waitcnt lgkmcnt(4)
	v_mfma_f32_16x16x32_bf16 v[114:117], v[192:195], v[164:167], v[114:117]
	v_mfma_f32_16x16x32_bf16 v[98:101], v[192:195], v[168:171], v[98:101]
	v_mfma_f32_16x16x32_bf16 v[82:85], v[192:195], v[172:175], v[82:85]
	v_mfma_f32_16x16x32_bf16 v[66:69], v[192:195], v[176:179], v[66:69]
	s_waitcnt vmcnt(0) lgkmcnt(0)
	s_barrier
	s_add_i32 s101, s100, s39
	v_mfma_f32_16x16x32_bf16 v[62:65], v[180:183], v[240:243], v[62:65]
	v_mfma_f32_16x16x32_bf16 v[46:49], v[180:183], v[244:247], v[46:49]
	v_mfma_f32_16x16x32_bf16 v[18:21], v[180:183], v[248:251], v[18:21]
	v_mfma_f32_16x16x32_bf16 v[38:41], v[180:183], v[252:255], v[38:41]
	v_add3_u32 v130, s42, v152, v153
	ds_read_b128 v[180:183], v130 offset:32768
	v_add3_u32 v163, s42, v152, v154
	v_add3_u32 v196, s42, v156, v155
	v_add3_u32 v197, s42, v156, v157
	v_add3_u32 v198, s42, v156, v158
	ds_read_b128 v[164:167], v163
	ds_read_b128 v[168:171], v196
	ds_read_b128 v[172:175], v197
	ds_read_b128 v[176:179], v198
	s_cmpk_eq_i32 s36, 0x700
	s_cbranch_scc1 .Lpk_797_0
	s_mov_b32 m0, s101
	v_lshl_add_u64 v[148:149], v[148:149], 0, s[98:99]
	global_load_lds_dwordx4 v[148:149], off
.Lpk_797_0:
	s_cmpk_eq_i32 s36, 0x700
	s_cbranch_scc1 .Lpk_797_1
	s_add_i32 m0, s101, 0x8000
	v_lshl_add_u64 v[140:141], v[140:141], 0, s[98:99]
	global_load_lds_dwordx4 v[140:141], off
.Lpk_797_1:
	v_mfma_f32_16x16x32_bf16 v[58:61], v[184:187], v[240:243], v[58:61]
	v_mfma_f32_16x16x32_bf16 v[42:45], v[184:187], v[244:247], v[42:45]
	v_mfma_f32_16x16x32_bf16 v[14:17], v[184:187], v[248:251], v[14:17]
	v_mfma_f32_16x16x32_bf16 v[30:33], v[184:187], v[252:255], v[30:33]
	ds_read_b128 v[184:187], v130 offset:34816
	v_add3_u32 v199, s42, v156, v159
	v_add3_u32 v200, s42, v156, v160
	v_add3_u32 v201, s42, v156, v161
	v_add3_u32 v202, s42, v156, v162
	s_cmpk_eq_i32 s36, 0x700
	s_cbranch_scc1 .Lpk_797_2
	s_add_i32 m0, s101, 0x2000
	v_lshl_add_u64 v[146:147], v[146:147], 0, s[98:99]
	global_load_lds_dwordx4 v[146:147], off
.Lpk_797_2:
	s_cmpk_eq_i32 s36, 0x700
	s_cbranch_scc1 .Lpk_797_3
	s_add_i32 m0, s101, 0xa000
	v_lshl_add_u64 v[138:139], v[138:139], 0, s[98:99]
	global_load_lds_dwordx4 v[138:139], off
.Lpk_797_3:
	v_mfma_f32_16x16x32_bf16 v[54:57], v[188:191], v[240:243], v[54:57]
	v_mfma_f32_16x16x32_bf16 v[34:37], v[188:191], v[244:247], v[34:37]
	v_mfma_f32_16x16x32_bf16 v[6:9], v[188:191], v[248:251], v[6:9]
	v_mfma_f32_16x16x32_bf16 v[22:25], v[188:191], v[252:255], v[22:25]
	ds_read_b128 v[188:191], v130 offset:36864
	s_cmpk_eq_i32 s36, 0x700
	s_cbranch_scc1 .Lpk_797_4
	s_add_i32 m0, s101, 0x4000
	v_lshl_add_u64 v[144:145], v[144:145], 0, s[98:99]
	global_load_lds_dwordx4 v[144:145], off
.Lpk_797_4:
	s_cmpk_eq_i32 s36, 0x700
	s_cbranch_scc1 .Lpk_797_5
	s_add_i32 m0, s101, 0xc000
	v_lshl_add_u64 v[136:137], v[136:137], 0, s[98:99]
	global_load_lds_dwordx4 v[136:137], off
.Lpk_797_5:
	v_mfma_f32_16x16x32_bf16 v[50:53], v[192:195], v[240:243], v[50:53]
	v_mfma_f32_16x16x32_bf16 v[26:29], v[192:195], v[244:247], v[26:29]
	v_mfma_f32_16x16x32_bf16 v[2:5], v[192:195], v[248:251], v[2:5]
	v_mfma_f32_16x16x32_bf16 v[10:13], v[192:195], v[252:255], v[10:13]
	ds_read_b128 v[192:195], v130 offset:38912
	s_cmpk_eq_i32 s36, 0x700
	s_cbranch_scc1 .Lpk_797_6
	s_add_i32 m0, s101, 0x6000
	v_lshl_add_u64 v[142:143], v[142:143], 0, s[98:99]
	global_load_lds_dwordx4 v[142:143], off
.Lpk_797_6:
	s_cmpk_eq_i32 s36, 0x700
	s_cbranch_scc1 .Lpk_797_7
	s_add_i32 m0, s101, 0xe000
	v_lshl_add_u64 v[134:135], v[134:135], 0, s[98:99]
	global_load_lds_dwordx4 v[134:135], off
.Lpk_797_7:
	s_add_i32 s38, s38, 0x10000
	s_add_u32 s36, s36, 0x80
	s_addc_u32 s37, s37, 0
	s_cmpk_lg_i32 s36, 0x780
	s_cbranch_scc1 .LBB0_797
	s_waitcnt lgkmcnt(0)
	v_add3_u32 v130, s46, v156, v162
	v_add3_u32 v151, s46, v156, v161
	v_add3_u32 v210, s46, v156, v160
	v_add3_u32 v198, s46, v156, v159
	v_add3_u32 v186, s46, v156, v158
	v_add3_u32 v187, s46, v156, v157
	v_add3_u32 v188, s46, v156, v155
	v_add3_u32 v189, s46, v152, v154
	v_add3_u32 v190, s47, v152, v153
	ds_read_b128 v[134:137], v130
	ds_read_b128 v[138:141], v151
	ds_read_b128 v[142:145], v210
	ds_read_b128 v[146:149], v198
	ds_read_b128 v[158:161], v186
	ds_read_b128 v[162:165], v187
	ds_read_b128 v[166:169], v188
	ds_read_b128 v[154:157], v189
	ds_read_b128 v[170:173], v190
	s_waitcnt lgkmcnt(0)
	v_mfma_f32_16x16x32_bf16 v[18:21], v[170:173], v[138:141], v[18:21]
	s_add_u32 s36, s29, 0xc800000
	s_addc_u32 s37, s0, 0
	v_mfma_f32_16x16x32_bf16 v[174:177], v[170:173], v[134:137], v[38:41]
	s_nop 2
	ds_read_b128 v[38:41], v190 offset:2048
	s_waitcnt lgkmcnt(0)
	v_mfma_f32_16x16x32_bf16 v[14:17], v[38:41], v[138:141], v[14:17]
	v_mfma_f32_16x16x32_bf16 v[62:65], v[170:173], v[146:149], v[62:65]
	v_mfma_f32_16x16x32_bf16 v[30:33], v[38:41], v[134:137], v[30:33]
	v_mfma_f32_16x16x32_bf16 v[58:61], v[38:41], v[146:149], v[58:61]
	ds_read_b128 v[178:181], v190 offset:4096
	s_waitcnt lgkmcnt(0)
	v_mfma_f32_16x16x32_bf16 v[182:185], v[178:181], v[134:137], v[22:25]
	v_mfma_f32_16x16x32_bf16 v[54:57], v[178:181], v[146:149], v[54:57]
	s_nop 1
	ds_read_b128 v[22:25], v190 offset:6144
	s_waitcnt lgkmcnt(0)
	v_mfma_f32_16x16x32_bf16 v[134:137], v[22:25], v[134:137], v[10:13]
	v_mfma_f32_16x16x32_bf16 v[10:13], v[22:25], v[154:157], v[114:117]
	v_mfma_f32_16x16x32_bf16 v[114:117], v[22:25], v[158:161], v[66:69]
	v_mfma_f32_16x16x32_bf16 v[66:69], v[178:181], v[154:157], v[118:121]
	v_mfma_f32_16x16x32_bf16 v[118:121], v[178:181], v[158:161], v[70:73]
	v_mfma_f32_16x16x32_bf16 v[70:73], v[38:41], v[154:157], v[122:125]
	v_mfma_f32_16x16x32_bf16 v[122:125], v[38:41], v[158:161], v[74:77]
	v_mfma_f32_16x16x32_bf16 v[74:77], v[170:173], v[154:157], v[126:129]
	v_mfma_f32_16x16x32_bf16 v[126:129], v[170:173], v[158:161], v[78:81]
	v_mfma_f32_16x16x32_bf16 v[50:53], v[22:25], v[146:149], v[50:53]
	v_mfma_f32_16x16x32_bf16 v[146:149], v[170:173], v[142:145], v[46:49]
	v_mfma_f32_16x16x32_bf16 v[152:155], v[38:41], v[142:145], v[42:45]
	v_mfma_f32_16x16x32_bf16 v[156:159], v[178:181], v[142:145], v[34:37]
	v_mfma_f32_16x16x32_bf16 v[26:29], v[22:25], v[142:145], v[26:29]
	v_mfma_f32_16x16x32_bf16 v[142:145], v[178:181], v[138:141], v[6:9]
	v_mfma_f32_16x16x32_bf16 v[110:113], v[170:173], v[166:169], v[110:113]
	v_mfma_f32_16x16x32_bf16 v[94:97], v[170:173], v[162:165], v[94:97]
	v_mfma_f32_16x16x32_bf16 v[106:109], v[38:41], v[166:169], v[106:109]
	v_mfma_f32_16x16x32_bf16 v[90:93], v[38:41], v[162:165], v[90:93]
	v_mfma_f32_16x16x32_bf16 v[102:105], v[178:181], v[166:169], v[102:105]
	v_mfma_f32_16x16x32_bf16 v[86:89], v[178:181], v[162:165], v[86:89]
	v_mfma_f32_16x16x32_bf16 v[98:101], v[22:25], v[166:169], v[98:101]
	v_mfma_f32_16x16x32_bf16 v[82:85], v[22:25], v[162:165], v[82:85]
	v_mfma_f32_16x16x32_bf16 v[22:25], v[22:25], v[138:141], v[2:5]
	ds_read_b128 v[138:141], v190 offset:1024
	ds_read_b128 v[160:163], v190 offset:3072
	ds_read_b128 v[164:167], v190 offset:5120
	ds_read_b128 v[168:171], v190 offset:7168
	ds_read_b128 v[2:5], v189 offset:1024
	ds_read_b128 v[6:9], v188 offset:1024
	ds_read_b128 v[34:37], v187 offset:1024
	ds_read_b128 v[38:41], v186 offset:1024
	s_waitcnt lgkmcnt(3)
	v_mfma_f32_16x16x32_bf16 v[178:181], v[138:141], v[2:5], v[74:77]
	v_mfma_f32_16x16x32_bf16 v[186:189], v[160:163], v[2:5], v[70:73]
	v_mfma_f32_16x16x32_bf16 v[190:193], v[164:167], v[2:5], v[66:69]
	v_mfma_f32_16x16x32_bf16 v[194:197], v[168:171], v[2:5], v[10:13]
	ds_read_b128 v[2:5], v198 offset:1024
	s_waitcnt lgkmcnt(3)
	v_mfma_f32_16x16x32_bf16 v[110:113], v[138:141], v[6:9], v[110:113]
	v_mfma_f32_16x16x32_bf16 v[198:201], v[160:163], v[6:9], v[106:109]
	v_mfma_f32_16x16x32_bf16 v[202:205], v[164:167], v[6:9], v[102:105]
	v_mfma_f32_16x16x32_bf16 v[206:209], v[168:171], v[6:9], v[98:101]
	ds_read_b128 v[6:9], v210 offset:1024
	s_waitcnt lgkmcnt(3)
	v_mfma_f32_16x16x32_bf16 v[66:69], v[138:141], v[34:37], v[94:97]
	v_mfma_f32_16x16x32_bf16 v[70:73], v[160:163], v[34:37], v[90:93]
	v_mfma_f32_16x16x32_bf16 v[74:77], v[164:167], v[34:37], v[86:89]
	v_mfma_f32_16x16x32_bf16 v[78:81], v[168:171], v[34:37], v[82:85]
	ds_read_b128 v[98:101], v151 offset:1024
	s_waitcnt lgkmcnt(3)
	v_mfma_f32_16x16x32_bf16 v[82:85], v[138:141], v[38:41], v[126:129]
	v_mfma_f32_16x16x32_bf16 v[86:89], v[160:163], v[38:41], v[122:125]
	v_mfma_f32_16x16x32_bf16 v[90:93], v[164:167], v[38:41], v[118:121]
	v_mfma_f32_16x16x32_bf16 v[94:97], v[168:171], v[38:41], v[114:117]
	ds_read_b128 v[102:105], v130 offset:1024
	s_waitcnt lgkmcnt(3)
	v_mfma_f32_16x16x32_bf16 v[34:37], v[138:141], v[2:5], v[62:65]
	v_mfma_f32_16x16x32_bf16 v[38:41], v[160:163], v[2:5], v[58:61]
	v_mfma_f32_16x16x32_bf16 v[42:45], v[164:167], v[2:5], v[54:57]
	v_mfma_f32_16x16x32_bf16 v[46:49], v[168:171], v[2:5], v[50:53]
	s_waitcnt lgkmcnt(2)
	v_mfma_f32_16x16x32_bf16 v[50:53], v[138:141], v[6:9], v[146:149]
	v_mfma_f32_16x16x32_bf16 v[54:57], v[160:163], v[6:9], v[152:155]
	v_mfma_f32_16x16x32_bf16 v[58:61], v[164:167], v[6:9], v[156:159]
	v_mfma_f32_16x16x32_bf16 v[62:65], v[168:171], v[6:9], v[26:29]
	s_waitcnt lgkmcnt(1)
	v_mfma_f32_16x16x32_bf16 v[2:5], v[138:141], v[98:101], v[18:21]
	v_mfma_f32_16x16x32_bf16 v[6:9], v[160:163], v[98:101], v[14:17]
	v_mfma_f32_16x16x32_bf16 v[10:13], v[164:167], v[98:101], v[142:145]
	v_mfma_f32_16x16x32_bf16 v[14:17], v[168:171], v[98:101], v[22:25]
	s_waitcnt lgkmcnt(0)
	v_mfma_f32_16x16x32_bf16 v[18:21], v[138:141], v[102:105], v[174:177]
	v_mfma_f32_16x16x32_bf16 v[22:25], v[160:163], v[102:105], v[30:33]
	v_mfma_f32_16x16x32_bf16 v[26:29], v[164:167], v[102:105], v[182:185]
	v_mfma_f32_16x16x32_bf16 v[30:33], v[168:171], v[102:105], v[134:137]
	v_lshrrev_b32_e32 v98, 6, v150
	v_mul_lo_u32 v98, v98, s48
	v_add_u32_e32 v105, s46, v98
	v_lshlrev_b32_e32 v98, 2, v150
	v_and_b32_e32 v109, 60, v98
	v_ashrrev_i32_e32 v98, 1, v150
	v_and_b32_e32 v98, 0xffffff80, v98
	v_add_u32_e32 v104, s28, v98
	v_bfe_u32 v108, v150, 4, 2
	v_or_b32_e32 v102, v104, v108
	v_and_b32_e32 v99, 0xc0, v150
	v_ashrrev_i32_e32 v103, 31, v102
	v_and_b32_e32 v100, 15, v150
	v_or3_b32 v98, v109, v99, s30
	v_mov_b32_e32 v99, s31
	v_lshlrev_b64 v[102:103], 10, v[102:103]
	v_and_b32_e32 v101, 48, v150
	v_mul_u32_u24_e32 v100, 0x110, v100
	v_lshl_add_u64 v[102:103], v[102:103], 0, v[98:99]
	v_add3_u32 v101, v105, v101, v100
	v_lshlrev_b64 v[106:107], 1, v[102:103]
	s_waitcnt vmcnt(0)
	s_barrier
	ds_write_b128 v101, v[178:181]
	ds_write_b128 v101, v[186:189] offset:64
	ds_write_b128 v101, v[190:193] offset:128
	ds_write_b128 v101, v[194:197] offset:192
	ds_write_b128 v101, v[110:113] offset:4352
	ds_write_b128 v101, v[198:201] offset:4416
	ds_write_b128 v101, v[202:205] offset:4480
	ds_write_b128 v101, v[206:209] offset:4544
	v_lshl_add_u64 v[102:103], v[0:1], 0, v[106:107]
	flat_load_dwordx2 v[114:115], v[102:103]
	v_lshl_add_u64 v[102:103], s[36:37], 0, v[106:107]
	flat_load_dwordx2 v[116:117], v[102:103]
	v_mul_u32_u24_e32 v100, 0x110, v108
	v_lshlrev_b32_e32 v103, 2, v109
	v_add3_u32 v100, v105, v103, v100
	ds_read_b128 v[110:113], v100
	v_or_b32_e32 v102, 4, v108
	v_or_b32_e32 v118, v104, v102
	v_ashrrev_i32_e32 v119, 31, v118
	s_add_u32 s28, s29, 0x14800000
	v_lshlrev_b64 v[118:119], 10, v[118:119]
	s_addc_u32 s29, s0, 0
	v_lshl_add_u64 v[118:119], v[118:119], 0, v[98:99]
	v_lshlrev_b64 v[118:119], 1, v[118:119]
	v_lshl_add_u64 v[106:107], s[28:29], 0, v[106:107]
	v_lshl_add_u64 v[120:121], v[0:1], 0, v[118:119]
	v_or_b32_e32 v103, 8, v108
	v_or_b32_e32 v105, 12, v108
	v_or_b32_e32 v109, 24, v108
	s_add_i32 s52, s52, s40
	s_cmpk_gt_i32 s52, 0x1ff
	s_waitcnt vmcnt(0) lgkmcnt(0)
	v_and_b32_e32 v123, 0xffff0000, v114
	v_lshlrev_b32_e32 v122, 16, v114
	v_and_b32_e32 v125, 0xffff0000, v116
	v_lshlrev_b32_e32 v124, 16, v116
	v_and_b32_e32 v127, 0xffff0000, v115
	v_lshlrev_b32_e32 v126, 16, v115
	v_and_b32_e32 v115, 0xffff0000, v117
	v_lshlrev_b32_e32 v114, 16, v117
	v_pk_fma_f32 v[110:111], v[110:111], v[124:125], v[122:123]
	v_pk_fma_f32 v[112:113], v[112:113], v[114:115], v[126:127]
	v_cvt_pk_bf16_f32 v110, v110, v111
	v_cvt_pk_bf16_f32 v111, v112, v113
	flat_store_dwordx2 v[106:107], v[110:111]
	v_lshl_add_u64 v[110:111], s[36:37], 0, v[118:119]
	flat_load_dwordx2 v[106:107], v[120:121]
	flat_load_dwordx2 v[114:115], v[110:111]
	v_or_b32_e32 v110, v104, v103
	v_ashrrev_i32_e32 v111, 31, v110
	v_lshlrev_b64 v[110:111], 10, v[110:111]
	v_lshl_add_u64 v[110:111], v[110:111], 0, v[98:99]
	v_lshlrev_b64 v[116:117], 1, v[110:111]
	ds_read_b128 v[110:113], v100 offset:1088
	v_lshl_add_u64 v[118:119], s[28:29], 0, v[118:119]
	v_lshl_add_u64 v[120:121], v[0:1], 0, v[116:117]
	s_waitcnt vmcnt(0) lgkmcnt(0)
	v_and_b32_e32 v123, 0xffff0000, v106
	v_lshlrev_b32_e32 v122, 16, v106
	v_and_b32_e32 v125, 0xffff0000, v114
	v_lshlrev_b32_e32 v124, 16, v114
	v_and_b32_e32 v127, 0xffff0000, v107
	v_lshlrev_b32_e32 v126, 16, v107
	v_and_b32_e32 v107, 0xffff0000, v115
	v_lshlrev_b32_e32 v106, 16, v115
	v_pk_fma_f32 v[110:111], v[110:111], v[124:125], v[122:123]
	v_pk_fma_f32 v[106:107], v[112:113], v[106:107], v[126:127]
	v_cvt_pk_bf16_f32 v110, v110, v111
	v_cvt_pk_bf16_f32 v111, v106, v107
	flat_store_dwordx2 v[118:119], v[110:111]
	v_lshl_add_u64 v[110:111], s[36:37], 0, v[116:117]
	flat_load_dwordx2 v[106:107], v[120:121]
	flat_load_dwordx2 v[114:115], v[110:111]
	v_or_b32_e32 v110, v104, v105
	v_ashrrev_i32_e32 v111, 31, v110
	v_lshlrev_b64 v[110:111], 10, v[110:111]
	v_lshl_add_u64 v[110:111], v[110:111], 0, v[98:99]
	v_lshlrev_b64 v[118:119], 1, v[110:111]
	ds_read_b128 v[110:113], v100 offset:2176
	v_lshl_add_u64 v[116:117], s[28:29], 0, v[116:117]
	v_lshl_add_u64 v[120:121], v[0:1], 0, v[118:119]
	s_waitcnt vmcnt(0) lgkmcnt(0)
	v_and_b32_e32 v123, 0xffff0000, v106
	v_lshlrev_b32_e32 v122, 16, v106
	v_and_b32_e32 v125, 0xffff0000, v114
	v_lshlrev_b32_e32 v124, 16, v114
	v_and_b32_e32 v127, 0xffff0000, v107
	v_lshlrev_b32_e32 v126, 16, v107
	v_and_b32_e32 v107, 0xffff0000, v115
	v_lshlrev_b32_e32 v106, 16, v115
	v_pk_fma_f32 v[110:111], v[110:111], v[124:125], v[122:123]
	v_pk_fma_f32 v[106:107], v[112:113], v[106:107], v[126:127]
	v_cvt_pk_bf16_f32 v110, v110, v111
	v_cvt_pk_bf16_f32 v111, v106, v107
	flat_store_dwordx2 v[116:117], v[110:111]
	v_lshl_add_u64 v[106:107], s[36:37], 0, v[118:119]
	flat_load_dwordx2 v[114:115], v[120:121]
	flat_load_dwordx2 v[116:117], v[106:107]
	v_or_b32_e32 v106, 16, v108
	v_or_b32_e32 v110, v104, v106
	v_ashrrev_i32_e32 v111, 31, v110
	v_lshlrev_b64 v[110:111], 10, v[110:111]
	v_lshl_add_u64 v[110:111], v[110:111], 0, v[98:99]
	v_lshlrev_b64 v[120:121], 1, v[110:111]
	ds_read_b128 v[110:113], v100 offset:3264
	v_lshl_add_u64 v[118:119], s[28:29], 0, v[118:119]
	v_lshl_add_u64 v[122:123], v[0:1], 0, v[120:121]
	v_or_b32_e32 v107, 20, v108
	s_waitcnt vmcnt(0) lgkmcnt(0)
	v_and_b32_e32 v125, 0xffff0000, v114
	v_lshlrev_b32_e32 v124, 16, v114
	v_and_b32_e32 v127, 0xffff0000, v116
	v_lshlrev_b32_e32 v126, 16, v116
	v_and_b32_e32 v129, 0xffff0000, v115
	v_lshlrev_b32_e32 v128, 16, v115
	v_and_b32_e32 v115, 0xffff0000, v117
	v_lshlrev_b32_e32 v114, 16, v117
	v_pk_fma_f32 v[110:111], v[110:111], v[126:127], v[124:125]
	v_pk_fma_f32 v[112:113], v[112:113], v[114:115], v[128:129]
	v_cvt_pk_bf16_f32 v110, v110, v111
	v_cvt_pk_bf16_f32 v111, v112, v113
	flat_store_dwordx2 v[118:119], v[110:111]
	v_lshl_add_u64 v[110:111], s[36:37], 0, v[120:121]
	flat_load_dwordx2 v[114:115], v[122:123]
	flat_load_dwordx2 v[116:117], v[110:111]
	v_or_b32_e32 v110, v104, v107
	v_ashrrev_i32_e32 v111, 31, v110
	v_lshlrev_b64 v[110:111], 10, v[110:111]
	v_lshl_add_u64 v[110:111], v[110:111], 0, v[98:99]
	v_lshlrev_b64 v[118:119], 1, v[110:111]
	ds_read_b128 v[110:113], v100 offset:4352
	v_lshl_add_u64 v[120:121], s[28:29], 0, v[120:121]
	v_lshl_add_u64 v[122:123], v[0:1], 0, v[118:119]
	s_waitcnt vmcnt(0) lgkmcnt(0)
	v_and_b32_e32 v125, 0xffff0000, v114
	v_lshlrev_b32_e32 v124, 16, v114
	v_and_b32_e32 v127, 0xffff0000, v116
	v_lshlrev_b32_e32 v126, 16, v116
	v_and_b32_e32 v129, 0xffff0000, v115
	v_lshlrev_b32_e32 v128, 16, v115
	v_and_b32_e32 v115, 0xffff0000, v117
	v_lshlrev_b32_e32 v114, 16, v117
	v_pk_fma_f32 v[110:111], v[110:111], v[126:127], v[124:125]
	v_pk_fma_f32 v[112:113], v[112:113], v[114:115], v[128:129]
	v_cvt_pk_bf16_f32 v110, v110, v111
	v_cvt_pk_bf16_f32 v111, v112, v113
	flat_store_dwordx2 v[120:121], v[110:111]
	v_lshl_add_u64 v[110:111], s[36:37], 0, v[118:119]
	flat_load_dwordx2 v[114:115], v[122:123]
	flat_load_dwordx2 v[116:117], v[110:111]
	v_or_b32_e32 v110, v104, v109
	v_ashrrev_i32_e32 v111, 31, v110
	v_lshlrev_b64 v[110:111], 10, v[110:111]
	v_lshl_add_u64 v[110:111], v[110:111], 0, v[98:99]
	v_lshlrev_b64 v[120:121], 1, v[110:111]
	ds_read_b128 v[110:113], v100 offset:5440
	v_lshl_add_u64 v[118:119], s[28:29], 0, v[118:119]
	v_lshl_add_u64 v[122:123], v[0:1], 0, v[120:121]
	s_waitcnt vmcnt(0) lgkmcnt(0)
	v_and_b32_e32 v125, 0xffff0000, v114
	v_lshlrev_b32_e32 v124, 16, v114
	v_and_b32_e32 v127, 0xffff0000, v116
	v_lshlrev_b32_e32 v126, 16, v116
	v_and_b32_e32 v129, 0xffff0000, v115
	v_lshlrev_b32_e32 v128, 16, v115
	v_and_b32_e32 v115, 0xffff0000, v117
	v_lshlrev_b32_e32 v114, 16, v117
	v_pk_fma_f32 v[110:111], v[110:111], v[126:127], v[124:125]
	v_pk_fma_f32 v[112:113], v[112:113], v[114:115], v[128:129]
	v_cvt_pk_bf16_f32 v110, v110, v111
	v_cvt_pk_bf16_f32 v111, v112, v113
	flat_store_dwordx2 v[118:119], v[110:111]
	v_lshl_add_u64 v[110:111], s[36:37], 0, v[120:121]
	flat_load_dwordx2 v[116:117], v[122:123]
	flat_load_dwordx2 v[118:119], v[110:111]
	v_or_b32_e32 v110, 28, v108
	v_or_b32_e32 v112, v104, v110
	v_ashrrev_i32_e32 v113, 31, v112
	v_lshlrev_b64 v[112:113], 10, v[112:113]
	v_lshl_add_u64 v[112:113], v[112:113], 0, v[98:99]
	v_lshlrev_b64 v[122:123], 1, v[112:113]
	ds_read_b128 v[112:115], v100 offset:6528
	v_lshl_add_u64 v[120:121], s[28:29], 0, v[120:121]
	v_lshl_add_u64 v[124:125], v[0:1], 0, v[122:123]
	v_or_b32_e32 v111, 32, v104
	s_waitcnt vmcnt(0) lgkmcnt(0)
	v_and_b32_e32 v127, 0xffff0000, v116
	v_lshlrev_b32_e32 v126, 16, v116
	v_and_b32_e32 v129, 0xffff0000, v118
	v_lshlrev_b32_e32 v128, 16, v118
	v_and_b32_e32 v135, 0xffff0000, v117
	v_lshlrev_b32_e32 v134, 16, v117
	v_and_b32_e32 v117, 0xffff0000, v119
	v_lshlrev_b32_e32 v116, 16, v119
	v_pk_fma_f32 v[112:113], v[112:113], v[128:129], v[126:127]
	v_pk_fma_f32 v[114:115], v[114:115], v[116:117], v[134:135]
	v_cvt_pk_bf16_f32 v112, v112, v113
	v_cvt_pk_bf16_f32 v113, v114, v115
	flat_store_dwordx2 v[120:121], v[112:113]
	v_lshl_add_u64 v[112:113], s[36:37], 0, v[122:123]
	flat_load_dwordx2 v[116:117], v[124:125]
	flat_load_dwordx2 v[118:119], v[112:113]
	v_or_b32_e32 v112, v111, v108
	v_ashrrev_i32_e32 v113, 31, v112
	v_lshlrev_b64 v[112:113], 10, v[112:113]
	v_lshl_add_u64 v[112:113], v[112:113], 0, v[98:99]
	v_lshl_add_u64 v[120:121], s[28:29], 0, v[122:123]
	v_lshlrev_b64 v[122:123], 1, v[112:113]
	ds_read_b128 v[112:115], v100 offset:7616
	v_lshl_add_u64 v[124:125], v[0:1], 0, v[122:123]
	s_waitcnt vmcnt(0) lgkmcnt(0)
	v_and_b32_e32 v127, 0xffff0000, v116
	v_lshlrev_b32_e32 v126, 16, v116
	v_and_b32_e32 v129, 0xffff0000, v118
	v_lshlrev_b32_e32 v128, 16, v118
	v_and_b32_e32 v135, 0xffff0000, v117
	v_lshlrev_b32_e32 v134, 16, v117
	v_and_b32_e32 v117, 0xffff0000, v119
	v_lshlrev_b32_e32 v116, 16, v119
	v_pk_fma_f32 v[112:113], v[112:113], v[128:129], v[126:127]
	v_pk_fma_f32 v[114:115], v[114:115], v[116:117], v[134:135]
	v_cvt_pk_bf16_f32 v112, v112, v113
	v_cvt_pk_bf16_f32 v113, v114, v115
	flat_store_dwordx2 v[120:121], v[112:113]
	ds_write_b128 v101, v[66:69]
	ds_write_b128 v101, v[70:73] offset:64
	ds_write_b128 v101, v[74:77] offset:128
	ds_write_b128 v101, v[78:81] offset:192
	ds_write_b128 v101, v[82:85] offset:4352
	ds_write_b128 v101, v[86:89] offset:4416
	ds_write_b128 v101, v[90:93] offset:4480
	ds_write_b128 v101, v[94:97] offset:4544
	v_lshl_add_u64 v[66:67], s[36:37], 0, v[122:123]
	flat_load_dwordx2 v[70:71], v[124:125]
	flat_load_dwordx2 v[72:73], v[66:67]
	v_or_b32_e32 v66, v111, v102
	v_ashrrev_i32_e32 v67, 31, v66
	v_lshlrev_b64 v[66:67], 10, v[66:67]
	v_lshl_add_u64 v[66:67], v[66:67], 0, v[98:99]
	v_lshlrev_b64 v[74:75], 1, v[66:67]
	ds_read_b128 v[66:69], v100
	v_lshl_add_u64 v[76:77], s[28:29], 0, v[122:123]
	v_lshl_add_u64 v[78:79], v[0:1], 0, v[74:75]
	v_or_b32_e32 v86, 64, v104
	s_waitcnt vmcnt(0) lgkmcnt(0)
	v_and_b32_e32 v81, 0xffff0000, v70
	v_lshlrev_b32_e32 v80, 16, v70
	v_and_b32_e32 v83, 0xffff0000, v72
	v_lshlrev_b32_e32 v82, 16, v72
	v_and_b32_e32 v85, 0xffff0000, v71
	v_lshlrev_b32_e32 v84, 16, v71
	v_and_b32_e32 v71, 0xffff0000, v73
	v_lshlrev_b32_e32 v70, 16, v73
	v_pk_fma_f32 v[66:67], v[66:67], v[82:83], v[80:81]
	v_pk_fma_f32 v[68:69], v[68:69], v[70:71], v[84:85]
	v_cvt_pk_bf16_f32 v66, v66, v67
	v_cvt_pk_bf16_f32 v67, v68, v69
	flat_store_dwordx2 v[76:77], v[66:67]
	v_lshl_add_u64 v[66:67], s[36:37], 0, v[74:75]
	flat_load_dwordx2 v[70:71], v[78:79]
	flat_load_dwordx2 v[72:73], v[66:67]
	v_or_b32_e32 v66, v111, v103
	v_ashrrev_i32_e32 v67, 31, v66
	v_lshlrev_b64 v[66:67], 10, v[66:67]
	v_lshl_add_u64 v[66:67], v[66:67], 0, v[98:99]
	v_lshlrev_b64 v[76:77], 1, v[66:67]
	ds_read_b128 v[66:69], v100 offset:1088
	v_lshl_add_u64 v[74:75], s[28:29], 0, v[74:75]
	v_lshl_add_u64 v[78:79], v[0:1], 0, v[76:77]
	s_waitcnt vmcnt(0) lgkmcnt(0)
	v_and_b32_e32 v81, 0xffff0000, v70
	v_lshlrev_b32_e32 v80, 16, v70
	v_and_b32_e32 v83, 0xffff0000, v72
	v_lshlrev_b32_e32 v82, 16, v72
	v_and_b32_e32 v85, 0xffff0000, v71
	v_lshlrev_b32_e32 v84, 16, v71
	v_and_b32_e32 v71, 0xffff0000, v73
	v_lshlrev_b32_e32 v70, 16, v73
	v_pk_fma_f32 v[66:67], v[66:67], v[82:83], v[80:81]
	v_pk_fma_f32 v[68:69], v[68:69], v[70:71], v[84:85]
	v_cvt_pk_bf16_f32 v66, v66, v67
	v_cvt_pk_bf16_f32 v67, v68, v69
	flat_store_dwordx2 v[74:75], v[66:67]
	v_lshl_add_u64 v[66:67], s[36:37], 0, v[76:77]
	flat_load_dwordx2 v[70:71], v[78:79]
	flat_load_dwordx2 v[72:73], v[66:67]
	v_or_b32_e32 v66, v111, v105
	v_ashrrev_i32_e32 v67, 31, v66
	v_lshlrev_b64 v[66:67], 10, v[66:67]
	v_lshl_add_u64 v[66:67], v[66:67], 0, v[98:99]
	v_lshlrev_b64 v[74:75], 1, v[66:67]
	ds_read_b128 v[66:69], v100 offset:2176
	v_lshl_add_u64 v[76:77], s[28:29], 0, v[76:77]
	v_lshl_add_u64 v[78:79], v[0:1], 0, v[74:75]
	s_waitcnt vmcnt(0) lgkmcnt(0)
	v_and_b32_e32 v81, 0xffff0000, v70
	v_lshlrev_b32_e32 v80, 16, v70
	v_and_b32_e32 v83, 0xffff0000, v72
	v_lshlrev_b32_e32 v82, 16, v72
	v_and_b32_e32 v85, 0xffff0000, v71
	v_lshlrev_b32_e32 v84, 16, v71
	v_and_b32_e32 v71, 0xffff0000, v73
	v_lshlrev_b32_e32 v70, 16, v73
	v_pk_fma_f32 v[66:67], v[66:67], v[82:83], v[80:81]
	v_pk_fma_f32 v[68:69], v[68:69], v[70:71], v[84:85]
	v_cvt_pk_bf16_f32 v66, v66, v67
	v_cvt_pk_bf16_f32 v67, v68, v69
	flat_store_dwordx2 v[76:77], v[66:67]
	v_lshl_add_u64 v[66:67], s[36:37], 0, v[74:75]
	flat_load_dwordx2 v[70:71], v[78:79]
	flat_load_dwordx2 v[72:73], v[66:67]
	v_or_b32_e32 v66, v111, v106
	v_ashrrev_i32_e32 v67, 31, v66
	v_lshlrev_b64 v[66:67], 10, v[66:67]
	v_lshl_add_u64 v[66:67], v[66:67], 0, v[98:99]
	v_lshlrev_b64 v[76:77], 1, v[66:67]
	ds_read_b128 v[66:69], v100 offset:3264
	v_lshl_add_u64 v[74:75], s[28:29], 0, v[74:75]
	v_lshl_add_u64 v[78:79], v[0:1], 0, v[76:77]
	s_waitcnt vmcnt(0) lgkmcnt(0)
	v_and_b32_e32 v81, 0xffff0000, v70
	v_lshlrev_b32_e32 v80, 16, v70
	v_and_b32_e32 v83, 0xffff0000, v72
	v_lshlrev_b32_e32 v82, 16, v72
	v_and_b32_e32 v85, 0xffff0000, v71
	v_lshlrev_b32_e32 v84, 16, v71
	v_and_b32_e32 v71, 0xffff0000, v73
	v_lshlrev_b32_e32 v70, 16, v73
	v_pk_fma_f32 v[66:67], v[66:67], v[82:83], v[80:81]
	v_pk_fma_f32 v[68:69], v[68:69], v[70:71], v[84:85]
	v_cvt_pk_bf16_f32 v66, v66, v67
	v_cvt_pk_bf16_f32 v67, v68, v69
	flat_store_dwordx2 v[74:75], v[66:67]
	v_lshl_add_u64 v[66:67], s[36:37], 0, v[76:77]
	flat_load_dwordx2 v[70:71], v[78:79]
	flat_load_dwordx2 v[72:73], v[66:67]
	v_or_b32_e32 v66, v111, v107
	v_ashrrev_i32_e32 v67, 31, v66
	v_lshlrev_b64 v[66:67], 10, v[66:67]
	v_lshl_add_u64 v[66:67], v[66:67], 0, v[98:99]
	v_lshlrev_b64 v[74:75], 1, v[66:67]
	ds_read_b128 v[66:69], v100 offset:4352
	v_lshl_add_u64 v[76:77], s[28:29], 0, v[76:77]
	v_lshl_add_u64 v[78:79], v[0:1], 0, v[74:75]
	s_waitcnt vmcnt(0) lgkmcnt(0)
	v_and_b32_e32 v81, 0xffff0000, v70
	v_lshlrev_b32_e32 v80, 16, v70
	v_and_b32_e32 v83, 0xffff0000, v72
	v_lshlrev_b32_e32 v82, 16, v72
	v_and_b32_e32 v85, 0xffff0000, v71
	v_lshlrev_b32_e32 v84, 16, v71
	v_and_b32_e32 v71, 0xffff0000, v73
	v_lshlrev_b32_e32 v70, 16, v73
	v_pk_fma_f32 v[66:67], v[66:67], v[82:83], v[80:81]
	v_pk_fma_f32 v[68:69], v[68:69], v[70:71], v[84:85]
	v_cvt_pk_bf16_f32 v66, v66, v67
	v_cvt_pk_bf16_f32 v67, v68, v69
	flat_store_dwordx2 v[76:77], v[66:67]
	v_lshl_add_u64 v[66:67], s[36:37], 0, v[74:75]
	flat_load_dwordx2 v[70:71], v[78:79]
	flat_load_dwordx2 v[72:73], v[66:67]
	v_or_b32_e32 v66, v111, v109
	v_ashrrev_i32_e32 v67, 31, v66
	v_lshlrev_b64 v[66:67], 10, v[66:67]
	v_lshl_add_u64 v[66:67], v[66:67], 0, v[98:99]
	v_lshlrev_b64 v[76:77], 1, v[66:67]
	ds_read_b128 v[66:69], v100 offset:5440
	v_lshl_add_u64 v[74:75], s[28:29], 0, v[74:75]
	v_lshl_add_u64 v[78:79], v[0:1], 0, v[76:77]
	s_waitcnt vmcnt(0) lgkmcnt(0)
	v_and_b32_e32 v81, 0xffff0000, v70
	v_lshlrev_b32_e32 v80, 16, v70
	v_and_b32_e32 v83, 0xffff0000, v72
	v_lshlrev_b32_e32 v82, 16, v72
	v_and_b32_e32 v85, 0xffff0000, v71
	v_lshlrev_b32_e32 v84, 16, v71
	v_and_b32_e32 v71, 0xffff0000, v73
	v_lshlrev_b32_e32 v70, 16, v73
	v_pk_fma_f32 v[66:67], v[66:67], v[82:83], v[80:81]
	v_pk_fma_f32 v[68:69], v[68:69], v[70:71], v[84:85]
	v_cvt_pk_bf16_f32 v66, v66, v67
	v_cvt_pk_bf16_f32 v67, v68, v69
	flat_store_dwordx2 v[74:75], v[66:67]
	v_lshl_add_u64 v[66:67], s[36:37], 0, v[76:77]
	flat_load_dwordx2 v[70:71], v[78:79]
	flat_load_dwordx2 v[72:73], v[66:67]
	v_or_b32_e32 v66, v111, v110
	v_ashrrev_i32_e32 v67, 31, v66
	v_lshlrev_b64 v[66:67], 10, v[66:67]
	v_lshl_add_u64 v[66:67], v[66:67], 0, v[98:99]
	v_lshlrev_b64 v[74:75], 1, v[66:67]
	ds_read_b128 v[66:69], v100 offset:6528
	v_lshl_add_u64 v[76:77], s[28:29], 0, v[76:77]
	v_lshl_add_u64 v[78:79], v[0:1], 0, v[74:75]
	s_waitcnt vmcnt(0) lgkmcnt(0)
	v_and_b32_e32 v81, 0xffff0000, v70
	v_lshlrev_b32_e32 v80, 16, v70
	v_and_b32_e32 v83, 0xffff0000, v72
	v_lshlrev_b32_e32 v82, 16, v72
	v_and_b32_e32 v85, 0xffff0000, v71
	v_lshlrev_b32_e32 v84, 16, v71
	v_and_b32_e32 v71, 0xffff0000, v73
	v_lshlrev_b32_e32 v70, 16, v73
	v_pk_fma_f32 v[66:67], v[66:67], v[82:83], v[80:81]
	v_pk_fma_f32 v[68:69], v[68:69], v[70:71], v[84:85]
	v_cvt_pk_bf16_f32 v66, v66, v67
	v_cvt_pk_bf16_f32 v67, v68, v69
	flat_store_dwordx2 v[76:77], v[66:67]
	v_lshl_add_u64 v[66:67], s[36:37], 0, v[74:75]
	flat_load_dwordx2 v[70:71], v[78:79]
	flat_load_dwordx2 v[72:73], v[66:67]
	v_or_b32_e32 v66, v86, v108
	v_ashrrev_i32_e32 v67, 31, v66
	v_lshlrev_b64 v[66:67], 10, v[66:67]
	v_lshl_add_u64 v[66:67], v[66:67], 0, v[98:99]
	v_lshlrev_b64 v[76:77], 1, v[66:67]
	ds_read_b128 v[66:69], v100 offset:7616
	v_lshl_add_u64 v[74:75], s[28:29], 0, v[74:75]
	v_lshl_add_u64 v[78:79], v[0:1], 0, v[76:77]
	s_waitcnt vmcnt(0) lgkmcnt(0)
	v_and_b32_e32 v81, 0xffff0000, v70
	v_lshlrev_b32_e32 v80, 16, v70
	v_and_b32_e32 v83, 0xffff0000, v72
	v_lshlrev_b32_e32 v82, 16, v72
	v_and_b32_e32 v85, 0xffff0000, v71
	v_lshlrev_b32_e32 v84, 16, v71
	v_and_b32_e32 v71, 0xffff0000, v73
	v_lshlrev_b32_e32 v70, 16, v73
	v_pk_fma_f32 v[66:67], v[66:67], v[82:83], v[80:81]
	v_pk_fma_f32 v[68:69], v[68:69], v[70:71], v[84:85]
	v_cvt_pk_bf16_f32 v66, v66, v67
	v_cvt_pk_bf16_f32 v67, v68, v69
	flat_store_dwordx2 v[74:75], v[66:67]
	ds_write_b128 v101, v[34:37]
	ds_write_b128 v101, v[38:41] offset:64
	ds_write_b128 v101, v[42:45] offset:128
	ds_write_b128 v101, v[46:49] offset:192
	ds_write_b128 v101, v[50:53] offset:4352
	ds_write_b128 v101, v[54:57] offset:4416
	ds_write_b128 v101, v[58:61] offset:4480
	ds_write_b128 v101, v[62:65] offset:4544
	v_lshl_add_u64 v[34:35], s[36:37], 0, v[76:77]
	flat_load_dwordx2 v[38:39], v[78:79]
	flat_load_dwordx2 v[40:41], v[34:35]
	v_or_b32_e32 v34, v86, v102
	v_ashrrev_i32_e32 v35, 31, v34
	v_lshlrev_b64 v[34:35], 10, v[34:35]
	v_lshl_add_u64 v[34:35], v[34:35], 0, v[98:99]
	v_lshlrev_b64 v[42:43], 1, v[34:35]
	ds_read_b128 v[34:37], v100
	v_lshl_add_u64 v[44:45], s[28:29], 0, v[76:77]
	v_lshl_add_u64 v[46:47], v[0:1], 0, v[42:43]
	v_or_b32_e32 v54, 0x60, v104
	s_waitcnt vmcnt(0) lgkmcnt(0)
	v_and_b32_e32 v49, 0xffff0000, v38
	v_lshlrev_b32_e32 v48, 16, v38
	v_and_b32_e32 v51, 0xffff0000, v40
	v_lshlrev_b32_e32 v50, 16, v40
	v_and_b32_e32 v53, 0xffff0000, v39
	v_lshlrev_b32_e32 v52, 16, v39
	v_and_b32_e32 v39, 0xffff0000, v41
	v_lshlrev_b32_e32 v38, 16, v41
	v_pk_fma_f32 v[34:35], v[34:35], v[50:51], v[48:49]
	v_pk_fma_f32 v[36:37], v[36:37], v[38:39], v[52:53]
	v_cvt_pk_bf16_f32 v34, v34, v35
	v_cvt_pk_bf16_f32 v35, v36, v37
	flat_store_dwordx2 v[44:45], v[34:35]
	v_lshl_add_u64 v[34:35], s[36:37], 0, v[42:43]
	flat_load_dwordx2 v[38:39], v[46:47]
	flat_load_dwordx2 v[40:41], v[34:35]
	v_or_b32_e32 v34, v86, v103
	v_ashrrev_i32_e32 v35, 31, v34
	v_lshlrev_b64 v[34:35], 10, v[34:35]
	v_lshl_add_u64 v[34:35], v[34:35], 0, v[98:99]
	v_lshlrev_b64 v[44:45], 1, v[34:35]
	ds_read_b128 v[34:37], v100 offset:1088
	v_lshl_add_u64 v[42:43], s[28:29], 0, v[42:43]
	v_lshl_add_u64 v[46:47], v[0:1], 0, v[44:45]
	s_waitcnt vmcnt(0) lgkmcnt(0)
	v_and_b32_e32 v49, 0xffff0000, v38
	v_lshlrev_b32_e32 v48, 16, v38
	v_and_b32_e32 v51, 0xffff0000, v40
	v_lshlrev_b32_e32 v50, 16, v40
	v_and_b32_e32 v53, 0xffff0000, v39
	v_lshlrev_b32_e32 v52, 16, v39
	v_and_b32_e32 v39, 0xffff0000, v41
	v_lshlrev_b32_e32 v38, 16, v41
	v_pk_fma_f32 v[34:35], v[34:35], v[50:51], v[48:49]
	v_pk_fma_f32 v[36:37], v[36:37], v[38:39], v[52:53]
	v_cvt_pk_bf16_f32 v34, v34, v35
	v_cvt_pk_bf16_f32 v35, v36, v37
	flat_store_dwordx2 v[42:43], v[34:35]
	v_lshl_add_u64 v[34:35], s[36:37], 0, v[44:45]
	flat_load_dwordx2 v[38:39], v[46:47]
	flat_load_dwordx2 v[40:41], v[34:35]
	v_or_b32_e32 v34, v86, v105
	v_ashrrev_i32_e32 v35, 31, v34
	v_lshlrev_b64 v[34:35], 10, v[34:35]
	v_lshl_add_u64 v[34:35], v[34:35], 0, v[98:99]
	v_lshlrev_b64 v[42:43], 1, v[34:35]
	ds_read_b128 v[34:37], v100 offset:2176
	v_lshl_add_u64 v[44:45], s[28:29], 0, v[44:45]
	v_lshl_add_u64 v[46:47], v[0:1], 0, v[42:43]
	s_waitcnt vmcnt(0) lgkmcnt(0)
	v_and_b32_e32 v49, 0xffff0000, v38
	v_lshlrev_b32_e32 v48, 16, v38
	v_and_b32_e32 v51, 0xffff0000, v40
	v_lshlrev_b32_e32 v50, 16, v40
	v_and_b32_e32 v53, 0xffff0000, v39
	v_lshlrev_b32_e32 v52, 16, v39
	v_and_b32_e32 v39, 0xffff0000, v41
	v_lshlrev_b32_e32 v38, 16, v41
	v_pk_fma_f32 v[34:35], v[34:35], v[50:51], v[48:49]
	v_pk_fma_f32 v[36:37], v[36:37], v[38:39], v[52:53]
	v_cvt_pk_bf16_f32 v34, v34, v35
	v_cvt_pk_bf16_f32 v35, v36, v37
	flat_store_dwordx2 v[44:45], v[34:35]
	v_lshl_add_u64 v[34:35], s[36:37], 0, v[42:43]
	flat_load_dwordx2 v[38:39], v[46:47]
	flat_load_dwordx2 v[40:41], v[34:35]
	v_or_b32_e32 v34, v86, v106
	v_ashrrev_i32_e32 v35, 31, v34
	v_lshlrev_b64 v[34:35], 10, v[34:35]
	v_lshl_add_u64 v[34:35], v[34:35], 0, v[98:99]
	v_lshlrev_b64 v[44:45], 1, v[34:35]
	ds_read_b128 v[34:37], v100 offset:3264
	v_lshl_add_u64 v[42:43], s[28:29], 0, v[42:43]
	v_lshl_add_u64 v[46:47], v[0:1], 0, v[44:45]
	s_waitcnt vmcnt(0) lgkmcnt(0)
	v_and_b32_e32 v49, 0xffff0000, v38
	v_lshlrev_b32_e32 v48, 16, v38
	v_and_b32_e32 v51, 0xffff0000, v40
	v_lshlrev_b32_e32 v50, 16, v40
	v_and_b32_e32 v53, 0xffff0000, v39
	v_lshlrev_b32_e32 v52, 16, v39
	v_and_b32_e32 v39, 0xffff0000, v41
	v_lshlrev_b32_e32 v38, 16, v41
	v_pk_fma_f32 v[34:35], v[34:35], v[50:51], v[48:49]
	v_pk_fma_f32 v[36:37], v[36:37], v[38:39], v[52:53]
	v_cvt_pk_bf16_f32 v34, v34, v35
	v_cvt_pk_bf16_f32 v35, v36, v37
	flat_store_dwordx2 v[42:43], v[34:35]
	v_lshl_add_u64 v[34:35], s[36:37], 0, v[44:45]
	flat_load_dwordx2 v[38:39], v[46:47]
	flat_load_dwordx2 v[40:41], v[34:35]
	v_or_b32_e32 v34, v86, v107
	v_ashrrev_i32_e32 v35, 31, v34
	v_lshlrev_b64 v[34:35], 10, v[34:35]
	v_lshl_add_u64 v[34:35], v[34:35], 0, v[98:99]
	v_lshlrev_b64 v[42:43], 1, v[34:35]
	ds_read_b128 v[34:37], v100 offset:4352
	v_lshl_add_u64 v[44:45], s[28:29], 0, v[44:45]
	v_lshl_add_u64 v[46:47], v[0:1], 0, v[42:43]
	s_waitcnt vmcnt(0) lgkmcnt(0)
	v_and_b32_e32 v49, 0xffff0000, v38
	v_lshlrev_b32_e32 v48, 16, v38
	v_and_b32_e32 v51, 0xffff0000, v40
	v_lshlrev_b32_e32 v50, 16, v40
	v_and_b32_e32 v53, 0xffff0000, v39
	v_lshlrev_b32_e32 v52, 16, v39
	v_and_b32_e32 v39, 0xffff0000, v41
	v_lshlrev_b32_e32 v38, 16, v41
	v_pk_fma_f32 v[34:35], v[34:35], v[50:51], v[48:49]
	v_pk_fma_f32 v[36:37], v[36:37], v[38:39], v[52:53]
	v_cvt_pk_bf16_f32 v34, v34, v35
	v_cvt_pk_bf16_f32 v35, v36, v37
	flat_store_dwordx2 v[44:45], v[34:35]
	v_lshl_add_u64 v[34:35], s[36:37], 0, v[42:43]
	flat_load_dwordx2 v[38:39], v[46:47]
	flat_load_dwordx2 v[40:41], v[34:35]
	v_or_b32_e32 v34, v86, v109
	v_ashrrev_i32_e32 v35, 31, v34
	v_lshlrev_b64 v[34:35], 10, v[34:35]
	v_lshl_add_u64 v[34:35], v[34:35], 0, v[98:99]
	v_lshlrev_b64 v[44:45], 1, v[34:35]
	ds_read_b128 v[34:37], v100 offset:5440
	v_lshl_add_u64 v[42:43], s[28:29], 0, v[42:43]
	v_lshl_add_u64 v[46:47], v[0:1], 0, v[44:45]
	s_waitcnt vmcnt(0) lgkmcnt(0)
	v_and_b32_e32 v49, 0xffff0000, v38
	v_lshlrev_b32_e32 v48, 16, v38
	v_and_b32_e32 v51, 0xffff0000, v40
	v_lshlrev_b32_e32 v50, 16, v40
	v_and_b32_e32 v53, 0xffff0000, v39
	v_lshlrev_b32_e32 v52, 16, v39
	v_and_b32_e32 v39, 0xffff0000, v41
	v_lshlrev_b32_e32 v38, 16, v41
	v_pk_fma_f32 v[34:35], v[34:35], v[50:51], v[48:49]
	v_pk_fma_f32 v[36:37], v[36:37], v[38:39], v[52:53]
	v_cvt_pk_bf16_f32 v34, v34, v35
	v_cvt_pk_bf16_f32 v35, v36, v37
	flat_store_dwordx2 v[42:43], v[34:35]
	v_lshl_add_u64 v[34:35], s[36:37], 0, v[44:45]
	flat_load_dwordx2 v[38:39], v[46:47]
	flat_load_dwordx2 v[40:41], v[34:35]
	v_or_b32_e32 v34, v86, v110
	v_ashrrev_i32_e32 v35, 31, v34
	v_lshlrev_b64 v[34:35], 10, v[34:35]
	v_lshl_add_u64 v[34:35], v[34:35], 0, v[98:99]
	v_lshlrev_b64 v[42:43], 1, v[34:35]
	ds_read_b128 v[34:37], v100 offset:6528
	v_lshl_add_u64 v[44:45], s[28:29], 0, v[44:45]
	v_lshl_add_u64 v[46:47], v[0:1], 0, v[42:43]
	s_waitcnt vmcnt(0) lgkmcnt(0)
	v_and_b32_e32 v49, 0xffff0000, v38
	v_lshlrev_b32_e32 v48, 16, v38
	v_and_b32_e32 v51, 0xffff0000, v40
	v_lshlrev_b32_e32 v50, 16, v40
	v_and_b32_e32 v53, 0xffff0000, v39
	v_lshlrev_b32_e32 v52, 16, v39
	v_and_b32_e32 v39, 0xffff0000, v41
	v_lshlrev_b32_e32 v38, 16, v41
	v_pk_fma_f32 v[34:35], v[34:35], v[50:51], v[48:49]
	v_pk_fma_f32 v[36:37], v[36:37], v[38:39], v[52:53]
	v_cvt_pk_bf16_f32 v34, v34, v35
	v_cvt_pk_bf16_f32 v35, v36, v37
	flat_store_dwordx2 v[44:45], v[34:35]
	v_lshl_add_u64 v[34:35], s[36:37], 0, v[42:43]
	flat_load_dwordx2 v[38:39], v[46:47]
	flat_load_dwordx2 v[40:41], v[34:35]
	v_or_b32_e32 v34, v54, v108
	v_ashrrev_i32_e32 v35, 31, v34
	v_lshlrev_b64 v[34:35], 10, v[34:35]
	v_lshl_add_u64 v[34:35], v[34:35], 0, v[98:99]
	v_lshlrev_b64 v[44:45], 1, v[34:35]
	ds_read_b128 v[34:37], v100 offset:7616
	v_lshl_add_u64 v[42:43], s[28:29], 0, v[42:43]
	v_lshl_add_u64 v[46:47], v[0:1], 0, v[44:45]
	s_waitcnt vmcnt(0) lgkmcnt(0)
	v_and_b32_e32 v49, 0xffff0000, v38
	v_lshlrev_b32_e32 v48, 16, v38
	v_and_b32_e32 v51, 0xffff0000, v40
	v_lshlrev_b32_e32 v50, 16, v40
	v_and_b32_e32 v53, 0xffff0000, v39
	v_lshlrev_b32_e32 v52, 16, v39
	v_and_b32_e32 v39, 0xffff0000, v41
	v_lshlrev_b32_e32 v38, 16, v41
	v_pk_fma_f32 v[34:35], v[34:35], v[50:51], v[48:49]
	v_pk_fma_f32 v[36:37], v[36:37], v[38:39], v[52:53]
	v_cvt_pk_bf16_f32 v34, v34, v35
	v_cvt_pk_bf16_f32 v35, v36, v37
	flat_store_dwordx2 v[42:43], v[34:35]
	ds_write_b128 v101, v[2:5]
	ds_write_b128 v101, v[6:9] offset:64
	ds_write_b128 v101, v[10:13] offset:128
	ds_write_b128 v101, v[14:17] offset:192
	ds_write_b128 v101, v[18:21] offset:4352
	ds_write_b128 v101, v[22:25] offset:4416
	ds_write_b128 v101, v[26:29] offset:4480
	ds_write_b128 v101, v[30:33] offset:4544
	v_lshl_add_u64 v[2:3], s[36:37], 0, v[44:45]
	flat_load_dwordx2 v[6:7], v[46:47]
	flat_load_dwordx2 v[8:9], v[2:3]
	v_or_b32_e32 v2, v54, v102
	v_ashrrev_i32_e32 v3, 31, v2
	v_lshlrev_b64 v[2:3], 10, v[2:3]
	v_lshl_add_u64 v[2:3], v[2:3], 0, v[98:99]
	v_lshlrev_b64 v[10:11], 1, v[2:3]
	ds_read_b128 v[2:5], v100
	v_lshl_add_u64 v[12:13], s[28:29], 0, v[44:45]
	v_lshl_add_u64 v[14:15], v[0:1], 0, v[10:11]
	s_waitcnt vmcnt(0) lgkmcnt(0)
	v_and_b32_e32 v17, 0xffff0000, v6
	v_lshlrev_b32_e32 v16, 16, v6
	v_and_b32_e32 v19, 0xffff0000, v8
	v_lshlrev_b32_e32 v18, 16, v8
	v_and_b32_e32 v21, 0xffff0000, v7
	v_lshlrev_b32_e32 v20, 16, v7
	v_and_b32_e32 v7, 0xffff0000, v9
	v_lshlrev_b32_e32 v6, 16, v9
	v_pk_fma_f32 v[2:3], v[2:3], v[18:19], v[16:17]
	v_pk_fma_f32 v[4:5], v[4:5], v[6:7], v[20:21]
	v_cvt_pk_bf16_f32 v2, v2, v3
	v_cvt_pk_bf16_f32 v3, v4, v5
	flat_store_dwordx2 v[12:13], v[2:3]
	v_lshl_add_u64 v[2:3], s[36:37], 0, v[10:11]
	flat_load_dwordx2 v[6:7], v[14:15]
	flat_load_dwordx2 v[8:9], v[2:3]
	v_or_b32_e32 v2, v54, v103
	v_ashrrev_i32_e32 v3, 31, v2
	v_lshlrev_b64 v[2:3], 10, v[2:3]
	v_lshl_add_u64 v[2:3], v[2:3], 0, v[98:99]
	v_lshlrev_b64 v[12:13], 1, v[2:3]
	ds_read_b128 v[2:5], v100 offset:1088
	v_lshl_add_u64 v[10:11], s[28:29], 0, v[10:11]
	v_lshl_add_u64 v[14:15], v[0:1], 0, v[12:13]
	s_waitcnt vmcnt(0) lgkmcnt(0)
	v_and_b32_e32 v17, 0xffff0000, v6
	v_lshlrev_b32_e32 v16, 16, v6
	v_and_b32_e32 v19, 0xffff0000, v8
	v_lshlrev_b32_e32 v18, 16, v8
	v_and_b32_e32 v21, 0xffff0000, v7
	v_lshlrev_b32_e32 v20, 16, v7
	v_and_b32_e32 v7, 0xffff0000, v9
	v_lshlrev_b32_e32 v6, 16, v9
	v_pk_fma_f32 v[2:3], v[2:3], v[18:19], v[16:17]
	v_pk_fma_f32 v[4:5], v[4:5], v[6:7], v[20:21]
	v_cvt_pk_bf16_f32 v2, v2, v3
	v_cvt_pk_bf16_f32 v3, v4, v5
	flat_store_dwordx2 v[10:11], v[2:3]
	v_lshl_add_u64 v[2:3], s[36:37], 0, v[12:13]
	flat_load_dwordx2 v[6:7], v[14:15]
	flat_load_dwordx2 v[8:9], v[2:3]
	v_or_b32_e32 v2, v54, v105
	v_ashrrev_i32_e32 v3, 31, v2
	v_lshlrev_b64 v[2:3], 10, v[2:3]
	v_lshl_add_u64 v[2:3], v[2:3], 0, v[98:99]
	v_lshlrev_b64 v[10:11], 1, v[2:3]
	ds_read_b128 v[2:5], v100 offset:2176
	v_lshl_add_u64 v[12:13], s[28:29], 0, v[12:13]
	v_lshl_add_u64 v[14:15], v[0:1], 0, v[10:11]
	s_waitcnt vmcnt(0) lgkmcnt(0)
	v_and_b32_e32 v17, 0xffff0000, v6
	v_lshlrev_b32_e32 v16, 16, v6
	v_and_b32_e32 v19, 0xffff0000, v8
	v_lshlrev_b32_e32 v18, 16, v8
	v_and_b32_e32 v21, 0xffff0000, v7
	v_lshlrev_b32_e32 v20, 16, v7
	v_and_b32_e32 v7, 0xffff0000, v9
	v_lshlrev_b32_e32 v6, 16, v9
	v_pk_fma_f32 v[2:3], v[2:3], v[18:19], v[16:17]
	v_pk_fma_f32 v[4:5], v[4:5], v[6:7], v[20:21]
	v_cvt_pk_bf16_f32 v2, v2, v3
	v_cvt_pk_bf16_f32 v3, v4, v5
	flat_store_dwordx2 v[12:13], v[2:3]
	v_lshl_add_u64 v[2:3], s[36:37], 0, v[10:11]
	flat_load_dwordx2 v[6:7], v[14:15]
	flat_load_dwordx2 v[8:9], v[2:3]
	v_or_b32_e32 v2, v54, v106
	v_ashrrev_i32_e32 v3, 31, v2
	v_lshlrev_b64 v[2:3], 10, v[2:3]
	v_lshl_add_u64 v[2:3], v[2:3], 0, v[98:99]
	v_lshlrev_b64 v[12:13], 1, v[2:3]
	ds_read_b128 v[2:5], v100 offset:3264
	v_lshl_add_u64 v[10:11], s[28:29], 0, v[10:11]
	v_lshl_add_u64 v[14:15], v[0:1], 0, v[12:13]
	s_waitcnt vmcnt(0) lgkmcnt(0)
	v_and_b32_e32 v17, 0xffff0000, v6
	v_lshlrev_b32_e32 v16, 16, v6
	v_and_b32_e32 v19, 0xffff0000, v8
	v_lshlrev_b32_e32 v18, 16, v8
	v_and_b32_e32 v21, 0xffff0000, v7
	v_lshlrev_b32_e32 v20, 16, v7
	v_and_b32_e32 v7, 0xffff0000, v9
	v_lshlrev_b32_e32 v6, 16, v9
	v_pk_fma_f32 v[2:3], v[2:3], v[18:19], v[16:17]
	v_pk_fma_f32 v[4:5], v[4:5], v[6:7], v[20:21]
	v_cvt_pk_bf16_f32 v2, v2, v3
	v_cvt_pk_bf16_f32 v3, v4, v5
	flat_store_dwordx2 v[10:11], v[2:3]
	v_lshl_add_u64 v[2:3], s[36:37], 0, v[12:13]
	flat_load_dwordx2 v[6:7], v[14:15]
	flat_load_dwordx2 v[8:9], v[2:3]
	v_or_b32_e32 v2, v54, v107
	v_ashrrev_i32_e32 v3, 31, v2
	v_lshlrev_b64 v[2:3], 10, v[2:3]
	v_lshl_add_u64 v[2:3], v[2:3], 0, v[98:99]
	v_lshlrev_b64 v[10:11], 1, v[2:3]
	ds_read_b128 v[2:5], v100 offset:4352
	v_lshl_add_u64 v[12:13], s[28:29], 0, v[12:13]
	v_lshl_add_u64 v[14:15], v[0:1], 0, v[10:11]
	s_waitcnt vmcnt(0) lgkmcnt(0)
	v_and_b32_e32 v17, 0xffff0000, v6
	v_lshlrev_b32_e32 v16, 16, v6
	v_and_b32_e32 v19, 0xffff0000, v8
	v_lshlrev_b32_e32 v18, 16, v8
	v_and_b32_e32 v21, 0xffff0000, v7
	v_lshlrev_b32_e32 v20, 16, v7
	v_and_b32_e32 v7, 0xffff0000, v9
	v_lshlrev_b32_e32 v6, 16, v9
	v_pk_fma_f32 v[2:3], v[2:3], v[18:19], v[16:17]
	v_pk_fma_f32 v[4:5], v[4:5], v[6:7], v[20:21]
	v_cvt_pk_bf16_f32 v2, v2, v3
	v_cvt_pk_bf16_f32 v3, v4, v5
	flat_store_dwordx2 v[12:13], v[2:3]
	v_lshl_add_u64 v[2:3], s[36:37], 0, v[10:11]
	flat_load_dwordx2 v[6:7], v[14:15]
	flat_load_dwordx2 v[8:9], v[2:3]
	v_or_b32_e32 v2, v54, v109
	v_ashrrev_i32_e32 v3, 31, v2
	v_lshlrev_b64 v[2:3], 10, v[2:3]
	v_lshl_add_u64 v[2:3], v[2:3], 0, v[98:99]
	v_lshlrev_b64 v[12:13], 1, v[2:3]
	ds_read_b128 v[2:5], v100 offset:5440
	v_lshl_add_u64 v[10:11], s[28:29], 0, v[10:11]
	v_lshl_add_u64 v[14:15], v[0:1], 0, v[12:13]
	s_waitcnt vmcnt(0) lgkmcnt(0)
	v_and_b32_e32 v17, 0xffff0000, v6
	v_lshlrev_b32_e32 v16, 16, v6
	v_and_b32_e32 v19, 0xffff0000, v8
	v_lshlrev_b32_e32 v18, 16, v8
	v_and_b32_e32 v21, 0xffff0000, v7
	v_lshlrev_b32_e32 v20, 16, v7
	v_and_b32_e32 v7, 0xffff0000, v9
	v_lshlrev_b32_e32 v6, 16, v9
	v_pk_fma_f32 v[2:3], v[2:3], v[18:19], v[16:17]
	v_pk_fma_f32 v[4:5], v[4:5], v[6:7], v[20:21]
	v_cvt_pk_bf16_f32 v2, v2, v3
	v_cvt_pk_bf16_f32 v3, v4, v5
	flat_store_dwordx2 v[10:11], v[2:3]
	v_lshl_add_u64 v[2:3], s[36:37], 0, v[12:13]
	flat_load_dwordx2 v[4:5], v[14:15]
	flat_load_dwordx2 v[6:7], v[2:3]
	v_or_b32_e32 v2, v54, v110
	v_ashrrev_i32_e32 v3, 31, v2
	v_lshlrev_b64 v[2:3], 10, v[2:3]
	v_lshl_add_u64 v[2:3], v[2:3], 0, v[98:99]
	v_lshlrev_b64 v[8:9], 1, v[2:3]
	v_lshl_add_u64 v[10:11], s[28:29], 0, v[12:13]
	v_lshl_add_u64 v[12:13], v[0:1], 0, v[8:9]
	ds_read_b128 v[0:3], v100 offset:6528
	s_waitcnt vmcnt(0) lgkmcnt(0)
	v_and_b32_e32 v15, 0xffff0000, v4
	v_lshlrev_b32_e32 v14, 16, v4
	v_and_b32_e32 v17, 0xffff0000, v6
	v_lshlrev_b32_e32 v16, 16, v6
	v_and_b32_e32 v19, 0xffff0000, v5
	v_lshlrev_b32_e32 v18, 16, v5
	v_and_b32_e32 v5, 0xffff0000, v7
	v_lshlrev_b32_e32 v4, 16, v7
	v_pk_fma_f32 v[0:1], v[0:1], v[16:17], v[14:15]
	v_pk_fma_f32 v[2:3], v[2:3], v[4:5], v[18:19]
	v_cvt_pk_bf16_f32 v0, v0, v1
	v_cvt_pk_bf16_f32 v1, v2, v3
	flat_store_dwordx2 v[10:11], v[0:1]
	v_lshl_add_u64 v[0:1], s[36:37], 0, v[8:9]
	flat_load_dwordx2 v[4:5], v[12:13]
	flat_load_dwordx2 v[6:7], v[0:1]
	ds_read_b128 v[0:3], v100 offset:7616
	v_lshl_add_u64 v[8:9], s[28:29], 0, v[8:9]
	s_waitcnt vmcnt(0) lgkmcnt(0)
	v_and_b32_e32 v11, 0xffff0000, v4
	v_lshlrev_b32_e32 v10, 16, v4
	v_and_b32_e32 v13, 0xffff0000, v6
	v_lshlrev_b32_e32 v12, 16, v6
	v_and_b32_e32 v15, 0xffff0000, v5
	v_lshlrev_b32_e32 v14, 16, v5
	v_and_b32_e32 v5, 0xffff0000, v7
	v_lshlrev_b32_e32 v4, 16, v7
	v_pk_fma_f32 v[0:1], v[0:1], v[12:13], v[10:11]
	v_pk_fma_f32 v[2:3], v[2:3], v[4:5], v[14:15]
	v_cvt_pk_bf16_f32 v0, v0, v1
	v_cvt_pk_bf16_f32 v1, v2, v3
	flat_store_dwordx2 v[8:9], v[0:1]
	s_cbranch_scc0 .LBB0_792

.LBB0_845:
	s_ashr_i32 s12, s27, 31
	s_lshr_b32 s12, s12, 26
	s_add_i32 s12, s27, s12
	s_ashr_i32 s13, s12, 6
	s_and_b32 s12, s12, 0xffc0
	s_sub_i32 s12, s27, s12
	s_bfe_i32 s14, s12, 0x80000
	s_bfe_u32 s14, s14, 0x4000b
	s_add_i32 s14, s12, s14
	s_lshl_b32 s28, s13, 4
	s_and_b32 s13, s14, 0xf0
	v_mov_b32_e32 v148, v132
	v_mov_b32_e32 v18, v132
	s_sub_i32 s12, s12, s13
	ds_read_b64 v[0:1], v133
	s_bfe_i32 s15, s14, 0x80000
	v_lshlrev_b32_e32 v9, 4, v18
	v_and_b32_e32 v8, 32, v18
	s_sext_i32_i8 s12, s12
	v_lshrrev_b32_e32 v10, 1, v18
	v_bitop3_b32 v8, v9, v8, 48 bitop3:0x6c
	s_sext_i32_i16 s15, s15
	s_add_i32 s28, s28, s12
	v_bfe_u32 v19, v18, 2, 4
	v_and_b32_e32 v20, 32, v10
	v_lshrrev_b32_e32 v21, 1, v8
	v_ashrrev_i32_e32 v22, 3, v18
	s_lshl_b32 s14, s28, 8
	s_lshl_b32 s12, s15, 4
	v_or_b32_e32 v12, v21, v20
	v_and_or_b32 v8, v22, s18, v19
	s_and_b32 s12, s12, 0xffffff00
	s_ashr_i32 s15, s14, 31
	v_and_b32_e32 v11, 0xfffffc00, v9
	v_lshl_or_b32 v128, v8, 10, v12
	v_add_u32_e32 v8, 0x2000, v9
	v_add_u32_e32 v10, 0x4000, v9
	v_add_u32_e32 v9, 0x6000, v9
	s_lshl_b64 s[16:17], s[14:15], 11
	s_ashr_i32 s13, s12, 31
	v_ashrrev_i32_e32 v23, 7, v8
	v_ashrrev_i32_e32 v24, 7, v10
	v_ashrrev_i32_e32 v25, 7, v9
	s_waitcnt lgkmcnt(0)
	v_lshl_add_u64 v[2:3], v[0:1], 0, s[16:17]
	s_lshl_b64 s[16:17], s[12:13], 11
	v_and_or_b32 v8, v23, s18, v19
	v_and_or_b32 v10, v24, s18, v19
	v_and_or_b32 v9, v25, s18, v19
	v_add_u32_e32 v149, 0, v11
	v_lshl_add_u64 v[4:5], v[2:3], 0, s[4:5]
	v_lshl_add_u64 v[0:1], v[0:1], 0, s[16:17]
	v_lshl_or_b32 v8, v8, 10, v12
	v_lshl_or_b32 v10, v10, 10, v12
	v_lshl_or_b32 v12, v9, 10, v12
	v_add_u32_e32 v9, 0x8000, v149
	v_lshlrev_b64 v[14:15], 1, v[128:129]
	v_readfirstlane_b32 s15, v149
	v_lshl_add_u64 v[6:7], v[0:1], 0, s[6:7]
	v_lshl_add_u64 v[16:17], v[4:5], 0, v[14:15]
	s_mov_b32 m0, s15
	v_readfirstlane_b32 s15, v9
	v_mov_b32_e32 v9, v129
	v_add_u32_e32 v11, 0x2000, v149
	global_load_lds_dwordx4 v[16:17], off
	v_lshl_add_u64 v[14:15], v[6:7], 0, v[14:15]
	s_mov_b32 m0, s15
	v_lshlrev_b64 v[8:9], 1, v[8:9]
	v_readfirstlane_b32 s15, v11
	v_add_u32_e32 v11, 0xa000, v149
	global_load_lds_dwordx4 v[14:15], off
	v_lshl_add_u64 v[14:15], v[4:5], 0, v[8:9]
	s_mov_b32 m0, s15
	v_readfirstlane_b32 s15, v11
	global_load_lds_dwordx4 v[14:15], off
	v_lshl_add_u64 v[8:9], v[6:7], 0, v[8:9]
	s_mov_b32 m0, s15
	v_mov_b32_e32 v11, v129
	v_add_u32_e32 v13, 0x4000, v149
	global_load_lds_dwordx4 v[8:9], off
	v_lshlrev_b64 v[8:9], 1, v[10:11]
	v_readfirstlane_b32 s15, v13
	v_lshl_add_u64 v[10:11], v[4:5], 0, v[8:9]
	s_mov_b32 m0, s15
	v_lshl_add_u64 v[8:9], v[6:7], 0, v[8:9]
	global_load_lds_dwordx4 v[10:11], off
	v_add_u32_e32 v10, 0xc000, v149
	v_mov_b32_e32 v13, v129
	v_readfirstlane_b32 s15, v10
	s_mov_b32 m0, s15
	v_add_u32_e32 v10, 0x6000, v149
	global_load_lds_dwordx4 v[8:9], off
	v_lshlrev_b64 v[8:9], 1, v[12:13]
	v_readfirstlane_b32 s15, v10
	v_lshl_add_u64 v[4:5], v[4:5], 0, v[8:9]
	s_mov_b32 m0, s15
	v_and_b32_e32 v26, 15, v18
	global_load_lds_dwordx4 v[4:5], off
	v_lshl_add_u64 v[4:5], v[6:7], 0, v[8:9]
	v_add_u32_e32 v6, 0xe000, v149
	v_lshlrev_b32_e32 v10, 10, v19
	v_readfirstlane_b32 s15, v6
	s_mov_b32 m0, s15
	v_lshlrev_b32_e32 v6, 2, v18
	global_load_lds_dwordx4 v[4:5], off
	v_and_b32_e32 v4, 48, v18
	v_lshlrev_b32_e32 v5, 6, v26
	v_and_b32_e32 v6, 32, v6
	v_bitop3_b32 v150, v5, v6, v4 bitop3:0x36
	v_lshlrev_b32_e32 v5, 7, v18
	v_and_b32_e32 v151, 0x6000, v5
	v_lshlrev_b32_e32 v5, 6, v18
	v_and_b32_e32 v152, 0xffffc000, v5
	v_and_b32_e32 v5, 0x3c0, v5
	v_bitop3_b32 v154, v5, v6, v4 bitop3:0x36
	v_lshlrev_b32_e32 v4, 10, v25
	v_and_or_b32 v4, v4, s19, v21
	v_lshlrev_b32_e32 v6, 10, v24
	v_or3_b32 v128, v4, v10, v20
	v_and_or_b32 v6, v6, s19, v21
	v_lshlrev_b32_e32 v8, 10, v23
	v_lshlrev_b64 v[4:5], 1, v[128:129]
	v_or3_b32 v128, v6, v10, v20
	v_and_or_b32 v8, v8, s19, v21
	v_lshlrev_b32_e32 v11, 10, v22
	v_lshlrev_b64 v[6:7], 1, v[128:129]
	v_or3_b32 v128, v8, v10, v20
	v_and_or_b32 v11, v11, s19, v21
	v_lshlrev_b64 v[8:9], 1, v[128:129]
	v_or3_b32 v128, v11, v10, v20
	s_waitcnt vmcnt(0)
	v_lshl_add_u64 v[0:1], v[0:1], 0, s[8:9]
	v_lshlrev_b64 v[10:11], 1, v[128:129]
	v_lshl_add_u64 v[130:131], v[0:1], 0, v[4:5]
	v_lshl_add_u64 v[134:135], v[0:1], 0, v[6:7]
	v_lshl_add_u64 v[136:137], v[0:1], 0, v[8:9]
	v_lshl_add_u64 v[138:139], v[0:1], 0, v[10:11]
	v_lshl_add_u64 v[0:1], v[2:3], 0, s[10:11]
	v_or_b32_e32 v153, 0x800, v152
	v_or_b32_e32 v155, 0x1000, v152
	v_or_b32_e32 v156, 0x1800, v152
	v_or_b32_e32 v157, 0x2000, v152
	v_or_b32_e32 v158, 0x2800, v152
	v_or_b32_e32 v159, 0x3000, v152
	v_or_b32_e32 v160, 0x3800, v152
	v_lshl_add_u64 v[140:141], v[0:1], 0, v[4:5]
	v_lshl_add_u64 v[142:143], v[0:1], 0, v[6:7]
	v_lshl_add_u64 v[144:145], v[0:1], 0, v[8:9]
	v_lshl_add_u64 v[146:147], v[0:1], 0, v[10:11]
	s_mov_b64 s[16:17], 0
	s_mov_b32 s15, 0
	v_mov_b32_e32 v12, 0
	v_mov_b32_e32 v14, v129
	v_mov_b32_e32 v15, v129
	v_mov_b32_e32 v20, 0
	v_mov_b32_e32 v21, v129
	v_mov_b32_e32 v22, v129
	v_mov_b32_e32 v23, v129
	v_mov_b32_e32 v28, 0
	v_mov_b32_e32 v29, v129
	v_mov_b32_e32 v30, v129
	v_mov_b32_e32 v31, v129
	v_mov_b32_e32 v36, 0
	v_mov_b32_e32 v37, v129
	v_mov_b32_e32 v38, v129
	v_mov_b32_e32 v39, v129
	v_mov_b32_e32 v0, 0
	v_mov_b32_e32 v1, v129
	v_mov_b32_e32 v2, v129
	v_mov_b32_e32 v3, v129
	v_mov_b32_e32 v4, 0
	v_mov_b32_e32 v5, v129
	v_mov_b32_e32 v6, v129
	v_mov_b32_e32 v7, v129
	v_mov_b32_e32 v8, 0
	v_mov_b32_e32 v9, v129
	v_mov_b32_e32 v10, v129
	v_mov_b32_e32 v11, v129
	v_mov_b32_e32 v16, 0
	v_mov_b32_e32 v17, v129
	v_mov_b32_e32 v18, v129
	v_mov_b32_e32 v19, v129
	v_mov_b32_e32 v24, 0
	v_mov_b32_e32 v25, v129
	v_mov_b32_e32 v26, v129
	v_mov_b32_e32 v27, v129
	v_mov_b32_e32 v32, 0
	v_mov_b32_e32 v33, v129
	v_mov_b32_e32 v34, v129
	v_mov_b32_e32 v35, v129
	v_mov_b32_e32 v40, 0
	v_mov_b32_e32 v41, v129
	v_mov_b32_e32 v42, v129
	v_mov_b32_e32 v43, v129
	v_mov_b32_e32 v44, 0
	v_mov_b32_e32 v45, v129
	v_mov_b32_e32 v46, v129
	v_mov_b32_e32 v47, v129
	v_mov_b32_e32 v48, 0
	v_mov_b32_e32 v49, v129
	v_mov_b32_e32 v50, v129
	v_mov_b32_e32 v51, v129
	v_mov_b32_e32 v52, 0
	v_mov_b32_e32 v53, v129
	v_mov_b32_e32 v54, v129
	v_mov_b32_e32 v55, v129
	v_mov_b32_e32 v56, 0
	v_mov_b32_e32 v57, v129
	v_mov_b32_e32 v58, v129
	v_mov_b32_e32 v59, v129
	v_mov_b32_e32 v60, 0
	v_mov_b32_e32 v61, v129
	v_mov_b32_e32 v62, v129
	v_mov_b32_e32 v63, v129
	v_mov_b32_e32 v64, 0
	v_mov_b32_e32 v65, v129
	v_mov_b32_e32 v66, v129
	v_mov_b32_e32 v67, v129
	v_mov_b32_e32 v68, 0
	v_mov_b32_e32 v69, v129
	v_mov_b32_e32 v70, v129
	v_mov_b32_e32 v71, v129
	v_mov_b32_e32 v72, 0
	v_mov_b32_e32 v73, v129
	v_mov_b32_e32 v74, v129
	v_mov_b32_e32 v75, v129
	v_mov_b32_e32 v76, 0
	v_mov_b32_e32 v77, v129
	v_mov_b32_e32 v78, v129
	v_mov_b32_e32 v79, v129
	v_mov_b32_e32 v80, 0
	v_mov_b32_e32 v81, v129
	v_mov_b32_e32 v82, v129
	v_mov_b32_e32 v83, v129
	v_mov_b32_e32 v84, 0
	v_mov_b32_e32 v85, v129
	v_mov_b32_e32 v86, v129
	v_mov_b32_e32 v87, v129
	v_mov_b32_e32 v88, 0
	v_mov_b32_e32 v89, v129
	v_mov_b32_e32 v90, v129
	v_mov_b32_e32 v91, v129
	v_mov_b32_e32 v92, 0
	v_mov_b32_e32 v93, v129
	v_mov_b32_e32 v94, v129
	v_mov_b32_e32 v95, v129
	v_mov_b32_e32 v96, 0
	v_mov_b32_e32 v97, v129
	v_mov_b32_e32 v98, v129
	v_mov_b32_e32 v99, v129
	v_mov_b32_e32 v100, 0
	v_mov_b32_e32 v101, v129
	v_mov_b32_e32 v102, v129
	v_mov_b32_e32 v103, v129
	v_mov_b32_e32 v104, 0
	v_mov_b32_e32 v105, v129
	v_mov_b32_e32 v106, v129
	v_mov_b32_e32 v107, v129
	v_mov_b32_e32 v108, 0
	v_mov_b32_e32 v109, v129
	v_mov_b32_e32 v110, v129
	v_mov_b32_e32 v111, v129
	v_mov_b32_e32 v112, 0
	v_mov_b32_e32 v113, v129
	v_mov_b32_e32 v114, v129
	v_mov_b32_e32 v115, v129
	v_mov_b32_e32 v116, 0
	v_mov_b32_e32 v117, v129
	v_mov_b32_e32 v118, v129
	v_mov_b32_e32 v119, v129
	v_mov_b32_e32 v120, 0
	v_mov_b32_e32 v121, v129
	v_mov_b32_e32 v122, v129
	v_mov_b32_e32 v123, v129
	v_mov_b32_e32 v124, 0
	v_mov_b32_e32 v125, v129
	v_mov_b32_e32 v126, v129
	v_mov_b32_e32 v127, v129
	s_waitcnt vmcnt(0) lgkmcnt(0)
	s_barrier
	v_readfirstlane_b32 s100, v149
	s_mov_b64 s[98:99], 0x80
	s_and_b32 s29, s15, 0x10000
	s_xor_b32 s30, s29, 0x10000
	s_add_i32 s29, s29, 0
	v_add3_u32 v128, s29, v150, v151
	v_add3_u32 v161, s29, v150, v152
	v_add3_u32 v194, s29, v154, v153
	v_add3_u32 v195, s29, v154, v155
	v_add3_u32 v196, s29, v154, v156
	v_add3_u32 v197, s29, v154, v157
	v_add3_u32 v198, s29, v154, v158
	v_add3_u32 v199, s29, v154, v159
	v_add3_u32 v200, s29, v154, v160
	ds_read_b128 v[178:181], v128 offset:32768
	ds_read_b128 v[162:165], v161
	ds_read_b128 v[166:169], v194
	ds_read_b128 v[170:173], v195
	ds_read_b128 v[174:177], v196
	ds_read_b128 v[182:185], v128 offset:34816
	ds_read_b128 v[186:189], v128 offset:36864
	ds_read_b128 v[190:193], v128 offset:38912
	s_add_i32 s101, s100, s30
	s_mov_b32 m0, s101
	s_nop 0
	global_load_lds_dwordx4 v[146:147], off
	s_add_i32 m0, s101, 0x8000
	s_nop 0
	global_load_lds_dwordx4 v[138:139], off
	s_add_i32 m0, s101, 0x2000
	s_nop 0
	global_load_lds_dwordx4 v[144:145], off
	s_add_i32 m0, s101, 0xa000
	s_nop 0
	global_load_lds_dwordx4 v[136:137], off
	s_add_i32 m0, s101, 0x4000
	s_nop 0
	global_load_lds_dwordx4 v[142:143], off
	s_add_i32 m0, s101, 0xc000
	s_nop 0
	global_load_lds_dwordx4 v[134:135], off
	s_add_i32 m0, s101, 0x6000
	s_nop 0
	global_load_lds_dwordx4 v[140:141], off
	s_add_i32 m0, s101, 0xe000
	s_nop 0
	global_load_lds_dwordx4 v[130:131], off
.LBB0_846:
	s_and_b32 s29, s15, 0x10000
	s_xor_b32 s30, s29, 0x10000
	s_add_i32 s29, s29, 0
	s_waitcnt lgkmcnt(3)
	v_mfma_f32_16x16x32_bf16 v[124:127], v[178:181], v[162:165], v[124:127]
	v_mfma_f32_16x16x32_bf16 v[108:111], v[178:181], v[166:169], v[108:111]
	v_mfma_f32_16x16x32_bf16 v[92:95], v[178:181], v[170:173], v[92:95]
	v_mfma_f32_16x16x32_bf16 v[76:79], v[178:181], v[174:177], v[76:79]
	ds_read_b128 v[240:243], v197
	ds_read_b128 v[244:247], v198
	s_waitcnt lgkmcnt(4)
	v_mfma_f32_16x16x32_bf16 v[120:123], v[182:185], v[162:165], v[120:123]
	v_mfma_f32_16x16x32_bf16 v[104:107], v[182:185], v[166:169], v[104:107]
	v_mfma_f32_16x16x32_bf16 v[88:91], v[182:185], v[170:173], v[88:91]
	v_mfma_f32_16x16x32_bf16 v[72:75], v[182:185], v[174:177], v[72:75]
	ds_read_b128 v[248:251], v199
	ds_read_b128 v[252:255], v200
	s_waitcnt lgkmcnt(5)
	v_mfma_f32_16x16x32_bf16 v[116:119], v[186:189], v[162:165], v[116:119]
	v_mfma_f32_16x16x32_bf16 v[100:103], v[186:189], v[166:169], v[100:103]
	v_mfma_f32_16x16x32_bf16 v[84:87], v[186:189], v[170:173], v[84:87]
	v_mfma_f32_16x16x32_bf16 v[68:71], v[186:189], v[174:177], v[68:71]
	s_waitcnt lgkmcnt(4)
	v_mfma_f32_16x16x32_bf16 v[112:115], v[190:193], v[162:165], v[112:115]
	v_mfma_f32_16x16x32_bf16 v[96:99], v[190:193], v[166:169], v[96:99]
	v_mfma_f32_16x16x32_bf16 v[80:83], v[190:193], v[170:173], v[80:83]
	v_mfma_f32_16x16x32_bf16 v[64:67], v[190:193], v[174:177], v[64:67]
	ds_read_b128 v[162:165], v161 offset:1024
	ds_read_b128 v[166:169], v194 offset:1024
	ds_read_b128 v[170:173], v195 offset:1024
	ds_read_b128 v[174:177], v196 offset:1024
	s_waitcnt lgkmcnt(4)
	v_mfma_f32_16x16x32_bf16 v[60:63], v[178:181], v[240:243], v[60:63]
	v_mfma_f32_16x16x32_bf16 v[44:47], v[178:181], v[244:247], v[44:47]
	v_mfma_f32_16x16x32_bf16 v[16:19], v[178:181], v[248:251], v[16:19]
	v_mfma_f32_16x16x32_bf16 v[36:39], v[178:181], v[252:255], v[36:39]
	ds_read_b128 v[178:181], v128 offset:33792
	v_mfma_f32_16x16x32_bf16 v[56:59], v[182:185], v[240:243], v[56:59]
	v_mfma_f32_16x16x32_bf16 v[40:43], v[182:185], v[244:247], v[40:43]
	v_mfma_f32_16x16x32_bf16 v[8:11], v[182:185], v[248:251], v[8:11]
	v_mfma_f32_16x16x32_bf16 v[28:31], v[182:185], v[252:255], v[28:31]
	ds_read_b128 v[182:185], v128 offset:35840
	v_mfma_f32_16x16x32_bf16 v[52:55], v[186:189], v[240:243], v[52:55]
	v_mfma_f32_16x16x32_bf16 v[32:35], v[186:189], v[244:247], v[32:35]
	v_mfma_f32_16x16x32_bf16 v[4:7], v[186:189], v[248:251], v[4:7]
	v_mfma_f32_16x16x32_bf16 v[20:23], v[186:189], v[252:255], v[20:23]
	ds_read_b128 v[186:189], v128 offset:37888
	v_mfma_f32_16x16x32_bf16 v[48:51], v[190:193], v[240:243], v[48:51]
	v_mfma_f32_16x16x32_bf16 v[24:27], v[190:193], v[244:247], v[24:27]
	v_mfma_f32_16x16x32_bf16 v[0:3], v[190:193], v[248:251], v[0:3]
	v_mfma_f32_16x16x32_bf16 v[12:15], v[190:193], v[252:255], v[12:15]
	ds_read_b128 v[190:193], v128 offset:39936
	s_waitcnt lgkmcnt(3)
	v_mfma_f32_16x16x32_bf16 v[124:127], v[178:181], v[162:165], v[124:127]
	v_mfma_f32_16x16x32_bf16 v[108:111], v[178:181], v[166:169], v[108:111]
	v_mfma_f32_16x16x32_bf16 v[92:95], v[178:181], v[170:173], v[92:95]
	v_mfma_f32_16x16x32_bf16 v[76:79], v[178:181], v[174:177], v[76:79]
	ds_read_b128 v[240:243], v197 offset:1024
	ds_read_b128 v[244:247], v198 offset:1024
	s_waitcnt lgkmcnt(4)
	v_mfma_f32_16x16x32_bf16 v[120:123], v[182:185], v[162:165], v[120:123]
	v_mfma_f32_16x16x32_bf16 v[104:107], v[182:185], v[166:169], v[104:107]
	v_mfma_f32_16x16x32_bf16 v[88:91], v[182:185], v[170:173], v[88:91]
	v_mfma_f32_16x16x32_bf16 v[72:75], v[182:185], v[174:177], v[72:75]
	ds_read_b128 v[248:251], v199 offset:1024
	ds_read_b128 v[252:255], v200 offset:1024
	s_waitcnt lgkmcnt(5)
	v_mfma_f32_16x16x32_bf16 v[116:119], v[186:189], v[162:165], v[116:119]
	v_mfma_f32_16x16x32_bf16 v[100:103], v[186:189], v[166:169], v[100:103]
	v_mfma_f32_16x16x32_bf16 v[84:87], v[186:189], v[170:173], v[84:87]
	v_mfma_f32_16x16x32_bf16 v[68:71], v[186:189], v[174:177], v[68:71]
	s_waitcnt lgkmcnt(4)
	v_mfma_f32_16x16x32_bf16 v[112:115], v[190:193], v[162:165], v[112:115]
	v_mfma_f32_16x16x32_bf16 v[96:99], v[190:193], v[166:169], v[96:99]
	v_mfma_f32_16x16x32_bf16 v[80:83], v[190:193], v[170:173], v[80:83]
	v_mfma_f32_16x16x32_bf16 v[64:67], v[190:193], v[174:177], v[64:67]
	s_waitcnt vmcnt(0) lgkmcnt(0)
	s_barrier
	s_add_i32 s101, s100, s29
	v_mfma_f32_16x16x32_bf16 v[60:63], v[178:181], v[240:243], v[60:63]
	v_mfma_f32_16x16x32_bf16 v[44:47], v[178:181], v[244:247], v[44:47]
	v_mfma_f32_16x16x32_bf16 v[16:19], v[178:181], v[248:251], v[16:19]
	v_mfma_f32_16x16x32_bf16 v[36:39], v[178:181], v[252:255], v[36:39]
	v_add3_u32 v128, s30, v150, v151
	ds_read_b128 v[178:181], v128 offset:32768
	v_add3_u32 v161, s30, v150, v152
	v_add3_u32 v194, s30, v154, v153
	v_add3_u32 v195, s30, v154, v155
	v_add3_u32 v196, s30, v154, v156
	ds_read_b128 v[162:165], v161
	ds_read_b128 v[166:169], v194
	ds_read_b128 v[170:173], v195
	ds_read_b128 v[174:177], v196
	s_cmpk_eq_i32 s16, 0x700
	s_cbranch_scc1 .Lpk_846_0
	s_mov_b32 m0, s101
	v_lshl_add_u64 v[146:147], v[146:147], 0, s[98:99]
	global_load_lds_dwordx4 v[146:147], off
.Lpk_846_0:
	s_cmpk_eq_i32 s16, 0x700
	s_cbranch_scc1 .Lpk_846_1
	s_add_i32 m0, s101, 0x8000
	v_lshl_add_u64 v[138:139], v[138:139], 0, s[98:99]
	global_load_lds_dwordx4 v[138:139], off
.Lpk_846_1:
	v_mfma_f32_16x16x32_bf16 v[56:59], v[182:185], v[240:243], v[56:59]
	v_mfma_f32_16x16x32_bf16 v[40:43], v[182:185], v[244:247], v[40:43]
	v_mfma_f32_16x16x32_bf16 v[8:11], v[182:185], v[248:251], v[8:11]
	v_mfma_f32_16x16x32_bf16 v[28:31], v[182:185], v[252:255], v[28:31]
	ds_read_b128 v[182:185], v128 offset:34816
	v_add3_u32 v197, s30, v154, v157
	v_add3_u32 v198, s30, v154, v158
	v_add3_u32 v199, s30, v154, v159
	v_add3_u32 v200, s30, v154, v160
	s_cmpk_eq_i32 s16, 0x700
	s_cbranch_scc1 .Lpk_846_2
	s_add_i32 m0, s101, 0x2000
	v_lshl_add_u64 v[144:145], v[144:145], 0, s[98:99]
	global_load_lds_dwordx4 v[144:145], off
.Lpk_846_2:
	s_cmpk_eq_i32 s16, 0x700
	s_cbranch_scc1 .Lpk_846_3
	s_add_i32 m0, s101, 0xa000
	v_lshl_add_u64 v[136:137], v[136:137], 0, s[98:99]
	global_load_lds_dwordx4 v[136:137], off
.Lpk_846_3:
	v_mfma_f32_16x16x32_bf16 v[52:55], v[186:189], v[240:243], v[52:55]
	v_mfma_f32_16x16x32_bf16 v[32:35], v[186:189], v[244:247], v[32:35]
	v_mfma_f32_16x16x32_bf16 v[4:7], v[186:189], v[248:251], v[4:7]
	v_mfma_f32_16x16x32_bf16 v[20:23], v[186:189], v[252:255], v[20:23]
	ds_read_b128 v[186:189], v128 offset:36864
	s_cmpk_eq_i32 s16, 0x700
	s_cbranch_scc1 .Lpk_846_4
	s_add_i32 m0, s101, 0x4000
	v_lshl_add_u64 v[142:143], v[142:143], 0, s[98:99]
	global_load_lds_dwordx4 v[142:143], off
.Lpk_846_4:
	s_cmpk_eq_i32 s16, 0x700
	s_cbranch_scc1 .Lpk_846_5
	s_add_i32 m0, s101, 0xc000
	v_lshl_add_u64 v[134:135], v[134:135], 0, s[98:99]
	global_load_lds_dwordx4 v[134:135], off
.Lpk_846_5:
	v_mfma_f32_16x16x32_bf16 v[48:51], v[190:193], v[240:243], v[48:51]
	v_mfma_f32_16x16x32_bf16 v[24:27], v[190:193], v[244:247], v[24:27]
	v_mfma_f32_16x16x32_bf16 v[0:3], v[190:193], v[248:251], v[0:3]
	v_mfma_f32_16x16x32_bf16 v[12:15], v[190:193], v[252:255], v[12:15]
	ds_read_b128 v[190:193], v128 offset:38912
	s_cmpk_eq_i32 s16, 0x700
	s_cbranch_scc1 .Lpk_846_6
	s_add_i32 m0, s101, 0x6000
	v_lshl_add_u64 v[140:141], v[140:141], 0, s[98:99]
	global_load_lds_dwordx4 v[140:141], off
.Lpk_846_6:
	s_cmpk_eq_i32 s16, 0x700
	s_cbranch_scc1 .Lpk_846_7
	s_add_i32 m0, s101, 0xe000
	v_lshl_add_u64 v[130:131], v[130:131], 0, s[98:99]
	global_load_lds_dwordx4 v[130:131], off
.Lpk_846_7:
	s_add_i32 s15, s15, 0x10000
	s_add_u32 s16, s16, 0x80
	s_addc_u32 s17, s17, 0
	s_cmpk_lg_i32 s16, 0x780
	s_cbranch_scc1 .LBB0_846
	s_waitcnt lgkmcnt(0)
	v_add3_u32 v128, s20, v154, v160
	v_add3_u32 v130, s20, v154, v159
	v_add3_u32 v131, s20, v154, v158
	v_add3_u32 v146, s20, v154, v157
	v_add3_u32 v147, s20, v154, v156
	v_add3_u32 v149, s20, v154, v155
	v_add3_u32 v186, s20, v154, v153
	v_add3_u32 v187, s20, v150, v152
	v_add3_u32 v188, s21, v150, v151
	ds_read_b128 v[134:137], v128
	ds_read_b128 v[138:141], v130
	ds_read_b128 v[142:145], v131
	ds_read_b128 v[158:161], v146
	ds_read_b128 v[162:165], v147
	ds_read_b128 v[166:169], v149
	ds_read_b128 v[154:157], v186
	ds_read_b128 v[170:173], v187
	ds_read_b128 v[150:153], v188
	s_waitcnt lgkmcnt(0)
	v_mfma_f32_16x16x32_bf16 v[16:19], v[150:153], v[138:141], v[16:19]
	v_mfma_f32_16x16x32_bf16 v[174:177], v[150:153], v[134:137], v[36:39]
	s_nop 2
	ds_read_b128 v[36:39], v188 offset:2048
	s_waitcnt lgkmcnt(0)
	v_mfma_f32_16x16x32_bf16 v[8:11], v[36:39], v[138:141], v[8:11]
	v_mfma_f32_16x16x32_bf16 v[108:111], v[150:153], v[154:157], v[108:111]
	v_mfma_f32_16x16x32_bf16 v[60:63], v[150:153], v[158:161], v[60:63]
	v_mfma_f32_16x16x32_bf16 v[28:31], v[36:39], v[134:137], v[28:31]
	v_mfma_f32_16x16x32_bf16 v[104:107], v[36:39], v[154:157], v[104:107]
	v_mfma_f32_16x16x32_bf16 v[56:59], v[36:39], v[158:161], v[56:59]
	ds_read_b128 v[178:181], v188 offset:4096
	s_waitcnt lgkmcnt(0)
	v_mfma_f32_16x16x32_bf16 v[182:185], v[178:181], v[134:137], v[20:23]
	v_mfma_f32_16x16x32_bf16 v[100:103], v[178:181], v[154:157], v[100:103]
	v_mfma_f32_16x16x32_bf16 v[52:55], v[178:181], v[158:161], v[52:55]
	s_nop 0
	ds_read_b128 v[20:23], v188 offset:6144
	s_waitcnt lgkmcnt(0)
	v_mfma_f32_16x16x32_bf16 v[134:137], v[20:23], v[134:137], v[12:15]
	v_mfma_f32_16x16x32_bf16 v[12:15], v[20:23], v[170:173], v[112:115]
	v_mfma_f32_16x16x32_bf16 v[96:99], v[20:23], v[154:157], v[96:99]
	v_mfma_f32_16x16x32_bf16 v[112:115], v[20:23], v[162:165], v[64:67]
	v_mfma_f32_16x16x32_bf16 v[64:67], v[178:181], v[170:173], v[116:119]
	v_mfma_f32_16x16x32_bf16 v[116:119], v[178:181], v[162:165], v[68:71]
	v_mfma_f32_16x16x32_bf16 v[68:71], v[36:39], v[170:173], v[120:123]
	v_mfma_f32_16x16x32_bf16 v[120:123], v[36:39], v[162:165], v[72:75]
	v_mfma_f32_16x16x32_bf16 v[72:75], v[150:153], v[170:173], v[124:127]
	v_mfma_f32_16x16x32_bf16 v[124:127], v[150:153], v[162:165], v[76:79]
	v_mfma_f32_16x16x32_bf16 v[48:51], v[20:23], v[158:161], v[48:51]
	v_mfma_f32_16x16x32_bf16 v[154:157], v[150:153], v[142:145], v[44:47]
	v_mfma_f32_16x16x32_bf16 v[158:161], v[36:39], v[142:145], v[40:43]
	v_mfma_f32_16x16x32_bf16 v[162:165], v[178:181], v[142:145], v[32:35]
	v_mfma_f32_16x16x32_bf16 v[24:27], v[20:23], v[142:145], v[24:27]
	v_mfma_f32_16x16x32_bf16 v[142:145], v[178:181], v[138:141], v[4:7]
	v_mfma_f32_16x16x32_bf16 v[92:95], v[150:153], v[166:169], v[92:95]
	v_mfma_f32_16x16x32_bf16 v[88:91], v[36:39], v[166:169], v[88:91]
	v_mfma_f32_16x16x32_bf16 v[84:87], v[178:181], v[166:169], v[84:87]
	v_mfma_f32_16x16x32_bf16 v[80:83], v[20:23], v[166:169], v[80:83]
	v_mfma_f32_16x16x32_bf16 v[20:23], v[20:23], v[138:141], v[0:3]
	ds_read_b128 v[138:141], v188 offset:1024
	ds_read_b128 v[150:153], v188 offset:3072
	ds_read_b128 v[166:169], v188 offset:5120
	ds_read_b128 v[170:173], v188 offset:7168
	ds_read_b128 v[0:3], v187 offset:1024
	ds_read_b128 v[4:7], v186 offset:1024
	ds_read_b128 v[32:35], v149 offset:1024
	ds_read_b128 v[36:39], v147 offset:1024
	s_waitcnt lgkmcnt(3)
	v_mfma_f32_16x16x32_bf16 v[178:181], v[138:141], v[0:3], v[72:75]
	v_mfma_f32_16x16x32_bf16 v[186:189], v[150:153], v[0:3], v[68:71]
	v_mfma_f32_16x16x32_bf16 v[190:193], v[166:169], v[0:3], v[64:67]
	v_mfma_f32_16x16x32_bf16 v[194:197], v[170:173], v[0:3], v[12:15]
	ds_read_b128 v[0:3], v146 offset:1024
	s_waitcnt lgkmcnt(3)
	v_mfma_f32_16x16x32_bf16 v[108:111], v[138:141], v[4:7], v[108:111]
	v_mfma_f32_16x16x32_bf16 v[198:201], v[150:153], v[4:7], v[104:107]
	v_mfma_f32_16x16x32_bf16 v[202:205], v[166:169], v[4:7], v[100:103]
	v_mfma_f32_16x16x32_bf16 v[98:101], v[170:173], v[4:7], v[96:99]
	ds_read_b128 v[4:7], v131 offset:1024
	s_waitcnt lgkmcnt(3)
	v_mfma_f32_16x16x32_bf16 v[64:67], v[138:141], v[32:35], v[92:95]
	v_mfma_f32_16x16x32_bf16 v[68:71], v[150:153], v[32:35], v[88:91]
	v_mfma_f32_16x16x32_bf16 v[72:75], v[166:169], v[32:35], v[84:87]
	v_mfma_f32_16x16x32_bf16 v[76:79], v[170:173], v[32:35], v[80:83]
	ds_read_b128 v[12:15], v130 offset:1024
	s_waitcnt lgkmcnt(3)
	v_mfma_f32_16x16x32_bf16 v[80:83], v[138:141], v[36:39], v[124:127]
	v_mfma_f32_16x16x32_bf16 v[84:87], v[150:153], v[36:39], v[120:123]
	v_mfma_f32_16x16x32_bf16 v[88:91], v[166:169], v[36:39], v[116:119]
	v_mfma_f32_16x16x32_bf16 v[92:95], v[170:173], v[36:39], v[112:115]
	ds_read_b128 v[102:105], v128 offset:1024
	s_waitcnt lgkmcnt(3)
	v_mfma_f32_16x16x32_bf16 v[32:35], v[138:141], v[0:3], v[60:63]
	v_mfma_f32_16x16x32_bf16 v[36:39], v[150:153], v[0:3], v[56:59]
	v_mfma_f32_16x16x32_bf16 v[40:43], v[166:169], v[0:3], v[52:55]
	v_mfma_f32_16x16x32_bf16 v[44:47], v[170:173], v[0:3], v[48:51]
	s_waitcnt lgkmcnt(2)
	v_mfma_f32_16x16x32_bf16 v[48:51], v[138:141], v[4:7], v[154:157]
	v_mfma_f32_16x16x32_bf16 v[52:55], v[150:153], v[4:7], v[158:161]
	v_mfma_f32_16x16x32_bf16 v[56:59], v[166:169], v[4:7], v[162:165]
	v_mfma_f32_16x16x32_bf16 v[60:63], v[170:173], v[4:7], v[24:27]
	s_waitcnt lgkmcnt(1)
	v_mfma_f32_16x16x32_bf16 v[0:3], v[138:141], v[12:15], v[16:19]
	v_mfma_f32_16x16x32_bf16 v[4:7], v[150:153], v[12:15], v[8:11]
	v_mfma_f32_16x16x32_bf16 v[8:11], v[166:169], v[12:15], v[142:145]
	v_mfma_f32_16x16x32_bf16 v[12:15], v[170:173], v[12:15], v[20:23]
	s_waitcnt lgkmcnt(0)
	v_mfma_f32_16x16x32_bf16 v[16:19], v[138:141], v[102:105], v[174:177]
	v_mfma_f32_16x16x32_bf16 v[20:23], v[150:153], v[102:105], v[28:31]
	v_mfma_f32_16x16x32_bf16 v[24:27], v[166:169], v[102:105], v[182:185]
	v_mfma_f32_16x16x32_bf16 v[28:31], v[170:173], v[102:105], v[134:137]
	v_lshrrev_b32_e32 v96, 6, v148
	v_mul_lo_u32 v96, v96, s22
	v_mov_b32_e32 v97, s3
	v_add_u32_e32 v118, s20, v96
	v_lshlrev_b32_e32 v96, 2, v148
	s_waitcnt vmcnt(0)
	s_barrier
	v_and_b32_e32 v102, 63, v132
	v_lshrrev_b32_e32 v103, 6, v132
	v_and_b32_e32 v104, 15, v102
	v_lshrrev_b32_e32 v105, 4, v102
	v_mul_u32_u24_e32 v112, 0x2400, v103
	v_add_u32_e32 v112, 0x10000, v112
	v_mul_u32_u24_e32 v128, 0x110, v104
	v_lshl_add_u32 v128, v105, 4, v128
	v_add_u32_e32 v128, v128, v112
	v_mul_u32_u24_e32 v134, 0x110, v105
	v_lshl_add_u32 v134, v104, 4, v134
	v_add_u32_e32 v134, v134, v112
	v_lshrrev_b32_e32 v113, 2, v103
	v_lshl_add_u32 v113, v113, 7, v105
	v_add_u32_e32 v113, s14, v113
	v_and_b32_e32 v114, 3, v103
	v_lshlrev_b32_e32 v114, 6, v114
	v_lshl_add_u32 v114, v104, 2, v114
	v_add_u32_e32 v114, s12, v114
	v_mov_b32_e32 v130, 0x24000
	ds_read_b64 v[96:97], v130
	v_mov_b32_e32 v130, 0x240a0
	ds_read_b64 v[106:107], v130
	v_mov_b32_e32 v130, 0x240a8
	ds_read_b64 v[124:125], v130
	s_lshr_b32 s100, s14, 12
	s_mul_i32 s100, s100, 0x6000
	s_add_i32 s100, s100, 0x2282000
	s_mov_b64 s[98:99], 0x4000
	v_lshlrev_b32_e32 v130, 12, v113
	v_lshl_add_u32 v130, v114, 2, v130
	v_mov_b32_e32 v131, 0
	s_waitcnt lgkmcnt(0)
	v_lshl_add_u64 v[96:97], v[96:97], 0, v[130:131]
	v_lshl_add_u64 v[106:107], v[106:107], 0, v[130:131]
	v_lshl_add_u32 v130, v114, 2, s100
	v_lshl_add_u64 v[124:125], v[124:125], 0, v[130:131]
	global_load_dwordx4 v[124:127], v[124:125], off
	ds_write_b128 v128, v[178:181]
	ds_write_b128 v128, v[186:189] offset:64
	ds_write_b128 v128, v[190:193] offset:128
	ds_write_b128 v128, v[194:197] offset:192
	ds_write_b128 v128, v[108:111] offset:4352
	ds_write_b128 v128, v[198:201] offset:4416
	ds_write_b128 v128, v[202:205] offset:4480
	ds_write_b128 v128, v[98:101] offset:4544
	s_waitcnt lgkmcnt(0)
	global_load_dwordx4 v[102:105], v[96:97], off nt
	v_lshl_add_u64 v[96:97], v[96:97], 0, s[98:99]
	global_load_dwordx4 v[112:115], v[96:97], off nt
	v_lshl_add_u64 v[96:97], v[96:97], 0, s[98:99]
	global_load_dwordx4 v[116:119], v[96:97], off nt
	v_lshl_add_u64 v[96:97], v[96:97], 0, s[98:99]
	global_load_dwordx4 v[120:123], v[96:97], off nt
	v_lshl_add_u64 v[96:97], v[96:97], 0, s[98:99]
	global_load_dwordx4 v[178:181], v[96:97], off nt
	v_lshl_add_u64 v[96:97], v[96:97], 0, s[98:99]
	global_load_dwordx4 v[186:189], v[96:97], off nt
	v_lshl_add_u64 v[96:97], v[96:97], 0, s[98:99]
	global_load_dwordx4 v[190:193], v[96:97], off nt
	v_lshl_add_u64 v[96:97], v[96:97], 0, s[98:99]
	global_load_dwordx4 v[194:197], v[96:97], off nt
	v_lshl_add_u64 v[96:97], v[96:97], 0, s[98:99]
	ds_read_b128 v[240:243], v134
	s_waitcnt vmcnt(7) lgkmcnt(0)
	v_pk_fma_f32 v[104:105], v[242:243], v[126:127], v[104:105]
	v_pk_fma_f32 v[102:103], v[240:241], v[124:125], v[102:103]
	global_store_dwordx4 v[106:107], v[102:105], off nt
	v_lshl_add_u64 v[106:107], v[106:107], 0, s[98:99]
	ds_read_b128 v[240:243], v134 offset:1088
	s_waitcnt vmcnt(7) lgkmcnt(0)
	v_pk_fma_f32 v[114:115], v[242:243], v[126:127], v[114:115]
	v_pk_fma_f32 v[112:113], v[240:241], v[124:125], v[112:113]
	global_store_dwordx4 v[106:107], v[112:115], off nt
	v_lshl_add_u64 v[106:107], v[106:107], 0, s[98:99]
	ds_read_b128 v[240:243], v134 offset:2176
	s_waitcnt vmcnt(7) lgkmcnt(0)
	v_pk_fma_f32 v[118:119], v[242:243], v[126:127], v[118:119]
	v_pk_fma_f32 v[116:117], v[240:241], v[124:125], v[116:117]
	global_store_dwordx4 v[106:107], v[116:119], off nt
	v_lshl_add_u64 v[106:107], v[106:107], 0, s[98:99]
	ds_read_b128 v[240:243], v134 offset:3264
	s_waitcnt vmcnt(7) lgkmcnt(0)
	v_pk_fma_f32 v[122:123], v[242:243], v[126:127], v[122:123]
	v_pk_fma_f32 v[120:121], v[240:241], v[124:125], v[120:121]
	global_store_dwordx4 v[106:107], v[120:123], off nt
	v_lshl_add_u64 v[106:107], v[106:107], 0, s[98:99]
	global_load_dwordx4 v[102:105], v[96:97], off nt
	v_lshl_add_u64 v[96:97], v[96:97], 0, s[98:99]
	global_load_dwordx4 v[112:115], v[96:97], off nt
	v_lshl_add_u64 v[96:97], v[96:97], 0, s[98:99]
	global_load_dwordx4 v[116:119], v[96:97], off nt
	v_lshl_add_u64 v[96:97], v[96:97], 0, s[98:99]
	global_load_dwordx4 v[120:123], v[96:97], off nt
	v_lshl_add_u64 v[96:97], v[96:97], 0, s[98:99]
	ds_read_b128 v[240:243], v134 offset:4352
	s_waitcnt vmcnt(11) lgkmcnt(0)
	v_pk_fma_f32 v[180:181], v[242:243], v[126:127], v[180:181]
	v_pk_fma_f32 v[178:179], v[240:241], v[124:125], v[178:179]
	global_store_dwordx4 v[106:107], v[178:181], off nt
	v_lshl_add_u64 v[106:107], v[106:107], 0, s[98:99]
	ds_read_b128 v[240:243], v134 offset:5440
	s_waitcnt vmcnt(11) lgkmcnt(0)
	v_pk_fma_f32 v[188:189], v[242:243], v[126:127], v[188:189]
	v_pk_fma_f32 v[186:187], v[240:241], v[124:125], v[186:187]
	global_store_dwordx4 v[106:107], v[186:189], off nt
	v_lshl_add_u64 v[106:107], v[106:107], 0, s[98:99]
	ds_read_b128 v[240:243], v134 offset:6528
	s_waitcnt vmcnt(11) lgkmcnt(0)
	v_pk_fma_f32 v[192:193], v[242:243], v[126:127], v[192:193]
	v_pk_fma_f32 v[190:191], v[240:241], v[124:125], v[190:191]
	global_store_dwordx4 v[106:107], v[190:193], off nt
	v_lshl_add_u64 v[106:107], v[106:107], 0, s[98:99]
	ds_read_b128 v[240:243], v134 offset:7616
	s_waitcnt vmcnt(11) lgkmcnt(0)
	v_pk_fma_f32 v[196:197], v[242:243], v[126:127], v[196:197]
	v_pk_fma_f32 v[194:195], v[240:241], v[124:125], v[194:195]
	global_store_dwordx4 v[106:107], v[194:197], off nt
	v_lshl_add_u64 v[106:107], v[106:107], 0, s[98:99]
	ds_write_b128 v128, v[64:67]
	ds_write_b128 v128, v[68:71] offset:64
	ds_write_b128 v128, v[72:75] offset:128
	ds_write_b128 v128, v[76:79] offset:192
	ds_write_b128 v128, v[80:83] offset:4352
	ds_write_b128 v128, v[84:87] offset:4416
	ds_write_b128 v128, v[88:91] offset:4480
	ds_write_b128 v128, v[92:95] offset:4544
	global_load_dwordx4 v[178:181], v[96:97], off nt
	v_lshl_add_u64 v[96:97], v[96:97], 0, s[98:99]
	global_load_dwordx4 v[186:189], v[96:97], off nt
	v_lshl_add_u64 v[96:97], v[96:97], 0, s[98:99]
	global_load_dwordx4 v[190:193], v[96:97], off nt
	v_lshl_add_u64 v[96:97], v[96:97], 0, s[98:99]
	global_load_dwordx4 v[194:197], v[96:97], off nt
	v_lshl_add_u64 v[96:97], v[96:97], 0, s[98:99]
	ds_read_b128 v[240:243], v134
	s_waitcnt vmcnt(11) lgkmcnt(0)
	v_pk_fma_f32 v[104:105], v[242:243], v[126:127], v[104:105]
	v_pk_fma_f32 v[102:103], v[240:241], v[124:125], v[102:103]
	global_store_dwordx4 v[106:107], v[102:105], off nt
	v_lshl_add_u64 v[106:107], v[106:107], 0, s[98:99]
	ds_read_b128 v[240:243], v134 offset:1088
	s_waitcnt vmcnt(11) lgkmcnt(0)
	v_pk_fma_f32 v[114:115], v[242:243], v[126:127], v[114:115]
	v_pk_fma_f32 v[112:113], v[240:241], v[124:125], v[112:113]
	global_store_dwordx4 v[106:107], v[112:115], off nt
	v_lshl_add_u64 v[106:107], v[106:107], 0, s[98:99]
	ds_read_b128 v[240:243], v134 offset:2176
	s_waitcnt vmcnt(11) lgkmcnt(0)
	v_pk_fma_f32 v[118:119], v[242:243], v[126:127], v[118:119]
	v_pk_fma_f32 v[116:117], v[240:241], v[124:125], v[116:117]
	global_store_dwordx4 v[106:107], v[116:119], off nt
	v_lshl_add_u64 v[106:107], v[106:107], 0, s[98:99]
	ds_read_b128 v[240:243], v134 offset:3264
	s_waitcnt vmcnt(11) lgkmcnt(0)
	v_pk_fma_f32 v[122:123], v[242:243], v[126:127], v[122:123]
	v_pk_fma_f32 v[120:121], v[240:241], v[124:125], v[120:121]
	global_store_dwordx4 v[106:107], v[120:123], off nt
	v_lshl_add_u64 v[106:107], v[106:107], 0, s[98:99]
	global_load_dwordx4 v[102:105], v[96:97], off nt
	v_lshl_add_u64 v[96:97], v[96:97], 0, s[98:99]
	global_load_dwordx4 v[112:115], v[96:97], off nt
	v_lshl_add_u64 v[96:97], v[96:97], 0, s[98:99]
	global_load_dwordx4 v[116:119], v[96:97], off nt
	v_lshl_add_u64 v[96:97], v[96:97], 0, s[98:99]
	global_load_dwordx4 v[120:123], v[96:97], off nt
	v_lshl_add_u64 v[96:97], v[96:97], 0, s[98:99]
	ds_read_b128 v[240:243], v134 offset:4352
	s_waitcnt vmcnt(11) lgkmcnt(0)
	v_pk_fma_f32 v[180:181], v[242:243], v[126:127], v[180:181]
	v_pk_fma_f32 v[178:179], v[240:241], v[124:125], v[178:179]
	global_store_dwordx4 v[106:107], v[178:181], off nt
	v_lshl_add_u64 v[106:107], v[106:107], 0, s[98:99]
	ds_read_b128 v[240:243], v134 offset:5440
	s_waitcnt vmcnt(11) lgkmcnt(0)
	v_pk_fma_f32 v[188:189], v[242:243], v[126:127], v[188:189]
	v_pk_fma_f32 v[186:187], v[240:241], v[124:125], v[186:187]
	global_store_dwordx4 v[106:107], v[186:189], off nt
	v_lshl_add_u64 v[106:107], v[106:107], 0, s[98:99]
	ds_read_b128 v[240:243], v134 offset:6528
	s_waitcnt vmcnt(11) lgkmcnt(0)
	v_pk_fma_f32 v[192:193], v[242:243], v[126:127], v[192:193]
	v_pk_fma_f32 v[190:191], v[240:241], v[124:125], v[190:191]
	global_store_dwordx4 v[106:107], v[190:193], off nt
	v_lshl_add_u64 v[106:107], v[106:107], 0, s[98:99]
	ds_read_b128 v[240:243], v134 offset:7616
	s_waitcnt vmcnt(11) lgkmcnt(0)
	v_pk_fma_f32 v[196:197], v[242:243], v[126:127], v[196:197]
	v_pk_fma_f32 v[194:195], v[240:241], v[124:125], v[194:195]
	global_store_dwordx4 v[106:107], v[194:197], off nt
	v_lshl_add_u64 v[106:107], v[106:107], 0, s[98:99]
	ds_write_b128 v128, v[32:35]
	ds_write_b128 v128, v[36:39] offset:64
	ds_write_b128 v128, v[40:43] offset:128
	ds_write_b128 v128, v[44:47] offset:192
	ds_write_b128 v128, v[48:51] offset:4352
	ds_write_b128 v128, v[52:55] offset:4416
	ds_write_b128 v128, v[56:59] offset:4480
	ds_write_b128 v128, v[60:63] offset:4544
	global_load_dwordx4 v[178:181], v[96:97], off nt
	v_lshl_add_u64 v[96:97], v[96:97], 0, s[98:99]
	global_load_dwordx4 v[186:189], v[96:97], off nt
	v_lshl_add_u64 v[96:97], v[96:97], 0, s[98:99]
	global_load_dwordx4 v[190:193], v[96:97], off nt
	v_lshl_add_u64 v[96:97], v[96:97], 0, s[98:99]
	global_load_dwordx4 v[194:197], v[96:97], off nt
	v_lshl_add_u64 v[96:97], v[96:97], 0, s[98:99]
	ds_read_b128 v[240:243], v134
	s_waitcnt vmcnt(11) lgkmcnt(0)
	v_pk_fma_f32 v[104:105], v[242:243], v[126:127], v[104:105]
	v_pk_fma_f32 v[102:103], v[240:241], v[124:125], v[102:103]
	global_store_dwordx4 v[106:107], v[102:105], off nt
	v_lshl_add_u64 v[106:107], v[106:107], 0, s[98:99]
	ds_read_b128 v[240:243], v134 offset:1088
	s_waitcnt vmcnt(11) lgkmcnt(0)
	v_pk_fma_f32 v[114:115], v[242:243], v[126:127], v[114:115]
	v_pk_fma_f32 v[112:113], v[240:241], v[124:125], v[112:113]
	global_store_dwordx4 v[106:107], v[112:115], off nt
	v_lshl_add_u64 v[106:107], v[106:107], 0, s[98:99]
	ds_read_b128 v[240:243], v134 offset:2176
	s_waitcnt vmcnt(11) lgkmcnt(0)
	v_pk_fma_f32 v[118:119], v[242:243], v[126:127], v[118:119]
	v_pk_fma_f32 v[116:117], v[240:241], v[124:125], v[116:117]
	global_store_dwordx4 v[106:107], v[116:119], off nt
	v_lshl_add_u64 v[106:107], v[106:107], 0, s[98:99]
	ds_read_b128 v[240:243], v134 offset:3264
	s_waitcnt vmcnt(11) lgkmcnt(0)
	v_pk_fma_f32 v[122:123], v[242:243], v[126:127], v[122:123]
	v_pk_fma_f32 v[120:121], v[240:241], v[124:125], v[120:121]
	global_store_dwordx4 v[106:107], v[120:123], off nt
	v_lshl_add_u64 v[106:107], v[106:107], 0, s[98:99]
	global_load_dwordx4 v[102:105], v[96:97], off nt
	v_lshl_add_u64 v[96:97], v[96:97], 0, s[98:99]
	global_load_dwordx4 v[112:115], v[96:97], off nt
	v_lshl_add_u64 v[96:97], v[96:97], 0, s[98:99]
	global_load_dwordx4 v[116:119], v[96:97], off nt
	v_lshl_add_u64 v[96:97], v[96:97], 0, s[98:99]
	global_load_dwordx4 v[120:123], v[96:97], off nt
	v_lshl_add_u64 v[96:97], v[96:97], 0, s[98:99]
	ds_read_b128 v[240:243], v134 offset:4352
	s_waitcnt vmcnt(11) lgkmcnt(0)
	v_pk_fma_f32 v[180:181], v[242:243], v[126:127], v[180:181]
	v_pk_fma_f32 v[178:179], v[240:241], v[124:125], v[178:179]
	global_store_dwordx4 v[106:107], v[178:181], off nt
	v_lshl_add_u64 v[106:107], v[106:107], 0, s[98:99]
	ds_read_b128 v[240:243], v134 offset:5440
	s_waitcnt vmcnt(11) lgkmcnt(0)
	v_pk_fma_f32 v[188:189], v[242:243], v[126:127], v[188:189]
	v_pk_fma_f32 v[186:187], v[240:241], v[124:125], v[186:187]
	global_store_dwordx4 v[106:107], v[186:189], off nt
	v_lshl_add_u64 v[106:107], v[106:107], 0, s[98:99]
	ds_read_b128 v[240:243], v134 offset:6528
	s_waitcnt vmcnt(11) lgkmcnt(0)
	v_pk_fma_f32 v[192:193], v[242:243], v[126:127], v[192:193]
	v_pk_fma_f32 v[190:191], v[240:241], v[124:125], v[190:191]
	global_store_dwordx4 v[106:107], v[190:193], off nt
	v_lshl_add_u64 v[106:107], v[106:107], 0, s[98:99]
	ds_read_b128 v[240:243], v134 offset:7616
	s_waitcnt vmcnt(11) lgkmcnt(0)
	v_pk_fma_f32 v[196:197], v[242:243], v[126:127], v[196:197]
	v_pk_fma_f32 v[194:195], v[240:241], v[124:125], v[194:195]
	global_store_dwordx4 v[106:107], v[194:197], off nt
	v_lshl_add_u64 v[106:107], v[106:107], 0, s[98:99]
	ds_write_b128 v128, v[0:3]
	ds_write_b128 v128, v[4:7] offset:64
	ds_write_b128 v128, v[8:11] offset:128
	ds_write_b128 v128, v[12:15] offset:192
	ds_write_b128 v128, v[16:19] offset:4352
	ds_write_b128 v128, v[20:23] offset:4416
	ds_write_b128 v128, v[24:27] offset:4480
	ds_write_b128 v128, v[28:31] offset:4544
	global_load_dwordx4 v[178:181], v[96:97], off nt
	v_lshl_add_u64 v[96:97], v[96:97], 0, s[98:99]
	global_load_dwordx4 v[186:189], v[96:97], off nt
	v_lshl_add_u64 v[96:97], v[96:97], 0, s[98:99]
	global_load_dwordx4 v[190:193], v[96:97], off nt
	v_lshl_add_u64 v[96:97], v[96:97], 0, s[98:99]
	global_load_dwordx4 v[194:197], v[96:97], off nt
	v_lshl_add_u64 v[96:97], v[96:97], 0, s[98:99]
	ds_read_b128 v[240:243], v134
	s_waitcnt vmcnt(11) lgkmcnt(0)
	v_pk_fma_f32 v[104:105], v[242:243], v[126:127], v[104:105]
	v_pk_fma_f32 v[102:103], v[240:241], v[124:125], v[102:103]
	global_store_dwordx4 v[106:107], v[102:105], off nt
	v_lshl_add_u64 v[106:107], v[106:107], 0, s[98:99]
	ds_read_b128 v[240:243], v134 offset:1088
	s_waitcnt vmcnt(11) lgkmcnt(0)
	v_pk_fma_f32 v[114:115], v[242:243], v[126:127], v[114:115]
	v_pk_fma_f32 v[112:113], v[240:241], v[124:125], v[112:113]
	global_store_dwordx4 v[106:107], v[112:115], off nt
	v_lshl_add_u64 v[106:107], v[106:107], 0, s[98:99]
	ds_read_b128 v[240:243], v134 offset:2176
	s_waitcnt vmcnt(11) lgkmcnt(0)
	v_pk_fma_f32 v[118:119], v[242:243], v[126:127], v[118:119]
	v_pk_fma_f32 v[116:117], v[240:241], v[124:125], v[116:117]
	global_store_dwordx4 v[106:107], v[116:119], off nt
	v_lshl_add_u64 v[106:107], v[106:107], 0, s[98:99]
	ds_read_b128 v[240:243], v134 offset:3264
	s_waitcnt vmcnt(11) lgkmcnt(0)
	v_pk_fma_f32 v[122:123], v[242:243], v[126:127], v[122:123]
	v_pk_fma_f32 v[120:121], v[240:241], v[124:125], v[120:121]
	global_store_dwordx4 v[106:107], v[120:123], off nt
	v_lshl_add_u64 v[106:107], v[106:107], 0, s[98:99]
	ds_read_b128 v[240:243], v134 offset:4352
	s_waitcnt vmcnt(7) lgkmcnt(0)
	v_pk_fma_f32 v[180:181], v[242:243], v[126:127], v[180:181]
	v_pk_fma_f32 v[178:179], v[240:241], v[124:125], v[178:179]
	global_store_dwordx4 v[106:107], v[178:181], off nt
	v_lshl_add_u64 v[106:107], v[106:107], 0, s[98:99]
	ds_read_b128 v[240:243], v134 offset:5440
	s_waitcnt vmcnt(7) lgkmcnt(0)
	v_pk_fma_f32 v[188:189], v[242:243], v[126:127], v[188:189]
	v_pk_fma_f32 v[186:187], v[240:241], v[124:125], v[186:187]
	global_store_dwordx4 v[106:107], v[186:189], off nt
	v_lshl_add_u64 v[106:107], v[106:107], 0, s[98:99]
	ds_read_b128 v[240:243], v134 offset:6528
	s_waitcnt vmcnt(7) lgkmcnt(0)
	v_pk_fma_f32 v[192:193], v[242:243], v[126:127], v[192:193]
	v_pk_fma_f32 v[190:191], v[240:241], v[124:125], v[190:191]
	global_store_dwordx4 v[106:107], v[190:193], off nt
	v_lshl_add_u64 v[106:107], v[106:107], 0, s[98:99]
	ds_read_b128 v[240:243], v134 offset:7616
	s_waitcnt vmcnt(7) lgkmcnt(0)
	v_pk_fma_f32 v[196:197], v[242:243], v[126:127], v[196:197]
	v_pk_fma_f32 v[194:195], v[240:241], v[124:125], v[194:195]
	global_store_dwordx4 v[106:107], v[194:197], off nt
	v_lshl_add_u64 v[106:107], v[106:107], 0, s[98:99]
	s_add_i32 s27, s27, s40
	s_cmpk_gt_i32 s27, 0x1ff
	s_cbranch_scc0 .LBB0_845

.LBB0_941:
	s_mul_hi_i32 s14, s39, 0x2aaaaaab
	s_lshr_b32 s15, s14, 31
	s_ashr_i32 s14, s14, 5
	s_add_i32 s15, s14, s15
	s_mul_i32 s14, s15, 0xc0
	s_sub_i32 s16, s39, s14
	s_sext_i32_i16 s14, s16
	s_bfe_u32 s14, s14, 0x4001b
	s_add_i32 s14, s16, s14
	s_sext_i32_i16 s17, s14
	s_and_b32 s14, s14, 0xfff0
	s_sub_i32 s14, s16, s14
	s_sext_i32_i16 s19, s14
	s_lshl_b32 s14, s17, 4
	s_and_b32 s14, s14, 0xffffff00
	v_mov_b32_e32 v148, v132
	v_mov_b32_e32 v18, v132
	s_add_i32 s17, s14, 0x500
	ds_read_b64 v[0:1], v133
	s_cmpk_lt_i32 s16, 0x60
	v_lshlrev_b32_e32 v9, 4, v18
	v_and_b32_e32 v8, 32, v18
	v_lshrrev_b32_e32 v10, 1, v18
	v_bitop3_b32 v8, v9, v8, 48 bitop3:0x6c
	s_cselect_b32 s18, s14, s17
	s_lshl_b32 s15, s15, 12
	s_lshl_b32 s16, s19, 8
	v_bfe_u32 v19, v18, 2, 4
	v_and_b32_e32 v20, 32, v10
	v_lshrrev_b32_e32 v21, 1, v8
	v_ashrrev_i32_e32 v22, 3, v18
	s_add_i32 s16, s16, s15
	v_or_b32_e32 v12, v21, v20
	v_and_or_b32 v8, v22, s20, v19
	s_ashr_i32 s17, s16, 31
	v_and_b32_e32 v11, 0xfffffc00, v9
	v_lshl_or_b32 v128, v8, 10, v12
	v_add_u32_e32 v8, 0x2000, v9
	v_add_u32_e32 v10, 0x4000, v9
	v_add_u32_e32 v9, 0x6000, v9
	s_lshl_b64 s[42:43], s[16:17], 11
	s_ashr_i32 s19, s18, 31
	v_ashrrev_i32_e32 v23, 7, v8
	v_ashrrev_i32_e32 v24, 7, v10
	v_ashrrev_i32_e32 v25, 7, v9
	s_waitcnt lgkmcnt(0)
	v_lshl_add_u64 v[2:3], v[0:1], 0, s[42:43]
	s_lshl_b64 s[18:19], s[18:19], 11
	v_and_or_b32 v8, v23, s20, v19
	v_and_or_b32 v10, v24, s20, v19
	v_and_or_b32 v9, v25, s20, v19
	v_add_u32_e32 v149, 0, v11
	v_lshl_add_u64 v[4:5], v[2:3], 0, s[4:5]
	v_lshl_add_u64 v[0:1], v[0:1], 0, s[18:19]
	v_lshl_or_b32 v8, v8, 10, v12
	v_lshl_or_b32 v10, v10, 10, v12
	v_lshl_or_b32 v12, v9, 10, v12
	v_add_u32_e32 v9, 0x8000, v149
	v_lshlrev_b64 v[14:15], 1, v[128:129]
	v_readfirstlane_b32 s15, v149
	v_lshl_add_u64 v[6:7], v[0:1], 0, s[6:7]
	v_lshl_add_u64 v[16:17], v[4:5], 0, v[14:15]
	s_mov_b32 m0, s15
	v_readfirstlane_b32 s15, v9
	v_mov_b32_e32 v9, v129
	v_add_u32_e32 v11, 0x2000, v149
	global_load_lds_dwordx4 v[16:17], off
	v_lshl_add_u64 v[14:15], v[6:7], 0, v[14:15]
	s_mov_b32 m0, s15
	v_lshlrev_b64 v[8:9], 1, v[8:9]
	v_readfirstlane_b32 s15, v11
	v_add_u32_e32 v11, 0xa000, v149
	global_load_lds_dwordx4 v[14:15], off
	v_lshl_add_u64 v[14:15], v[4:5], 0, v[8:9]
	s_mov_b32 m0, s15
	v_readfirstlane_b32 s15, v11
	global_load_lds_dwordx4 v[14:15], off
	v_lshl_add_u64 v[8:9], v[6:7], 0, v[8:9]
	s_mov_b32 m0, s15
	v_mov_b32_e32 v11, v129
	v_add_u32_e32 v13, 0x4000, v149
	global_load_lds_dwordx4 v[8:9], off
	v_lshlrev_b64 v[8:9], 1, v[10:11]
	v_readfirstlane_b32 s15, v13
	v_lshl_add_u64 v[10:11], v[4:5], 0, v[8:9]
	s_mov_b32 m0, s15
	v_lshl_add_u64 v[8:9], v[6:7], 0, v[8:9]
	global_load_lds_dwordx4 v[10:11], off
	v_add_u32_e32 v10, 0xc000, v149
	v_mov_b32_e32 v13, v129
	v_readfirstlane_b32 s15, v10
	s_mov_b32 m0, s15
	v_add_u32_e32 v10, 0x6000, v149
	global_load_lds_dwordx4 v[8:9], off
	v_lshlrev_b64 v[8:9], 1, v[12:13]
	v_readfirstlane_b32 s15, v10
	v_lshl_add_u64 v[4:5], v[4:5], 0, v[8:9]
	s_mov_b32 m0, s15
	v_and_b32_e32 v26, 15, v18
	global_load_lds_dwordx4 v[4:5], off
	v_lshl_add_u64 v[4:5], v[6:7], 0, v[8:9]
	v_add_u32_e32 v6, 0xe000, v149
	v_lshlrev_b32_e32 v10, 10, v19
	v_readfirstlane_b32 s15, v6
	s_mov_b32 m0, s15
	v_lshlrev_b32_e32 v6, 2, v18
	global_load_lds_dwordx4 v[4:5], off
	v_and_b32_e32 v4, 48, v18
	v_lshlrev_b32_e32 v5, 6, v26
	v_and_b32_e32 v6, 32, v6
	v_bitop3_b32 v150, v5, v6, v4 bitop3:0x36
	v_lshlrev_b32_e32 v5, 7, v18
	v_and_b32_e32 v151, 0x6000, v5
	v_lshlrev_b32_e32 v5, 6, v18
	v_and_b32_e32 v152, 0xffffc000, v5
	v_and_b32_e32 v5, 0x3c0, v5
	v_bitop3_b32 v154, v5, v6, v4 bitop3:0x36
	v_lshlrev_b32_e32 v4, 10, v25
	v_and_or_b32 v4, v4, s22, v21
	v_lshlrev_b32_e32 v6, 10, v24
	v_or3_b32 v128, v4, v10, v20
	v_and_or_b32 v6, v6, s22, v21
	v_lshlrev_b32_e32 v8, 10, v23
	v_lshlrev_b64 v[4:5], 1, v[128:129]
	v_or3_b32 v128, v6, v10, v20
	v_and_or_b32 v8, v8, s22, v21
	v_lshlrev_b32_e32 v11, 10, v22
	v_lshlrev_b64 v[6:7], 1, v[128:129]
	v_or3_b32 v128, v8, v10, v20
	v_and_or_b32 v11, v11, s22, v21
	v_lshlrev_b64 v[8:9], 1, v[128:129]
	v_or3_b32 v128, v11, v10, v20
	s_waitcnt vmcnt(0)
	v_lshl_add_u64 v[0:1], v[0:1], 0, s[8:9]
	v_lshlrev_b64 v[10:11], 1, v[128:129]
	v_lshl_add_u64 v[130:131], v[0:1], 0, v[4:5]
	v_lshl_add_u64 v[134:135], v[0:1], 0, v[6:7]
	v_lshl_add_u64 v[136:137], v[0:1], 0, v[8:9]
	v_lshl_add_u64 v[138:139], v[0:1], 0, v[10:11]
	v_lshl_add_u64 v[0:1], v[2:3], 0, s[10:11]
	v_or_b32_e32 v153, 0x800, v152
	v_or_b32_e32 v155, 0x1000, v152
	v_or_b32_e32 v156, 0x1800, v152
	v_or_b32_e32 v157, 0x2000, v152
	v_or_b32_e32 v158, 0x2800, v152
	v_or_b32_e32 v159, 0x3000, v152
	v_or_b32_e32 v160, 0x3800, v152
	v_lshl_add_u64 v[140:141], v[0:1], 0, v[4:5]
	v_lshl_add_u64 v[142:143], v[0:1], 0, v[6:7]
	v_lshl_add_u64 v[144:145], v[0:1], 0, v[8:9]
	v_lshl_add_u64 v[146:147], v[0:1], 0, v[10:11]
	s_mov_b64 s[18:19], 0
	s_mov_b32 s15, 0
	v_mov_b32_e32 v0, 0
	v_mov_b32_e32 v1, v129
	v_mov_b32_e32 v2, v129
	v_mov_b32_e32 v3, v129
	v_mov_b32_e32 v4, 0
	v_mov_b32_e32 v5, v129
	v_mov_b32_e32 v6, v129
	v_mov_b32_e32 v7, v129
	v_mov_b32_e32 v8, 0
	v_mov_b32_e32 v9, v129
	v_mov_b32_e32 v10, v129
	v_mov_b32_e32 v11, v129
	v_mov_b32_e32 v12, 0
	v_mov_b32_e32 v14, v129
	v_mov_b32_e32 v15, v129
	v_mov_b32_e32 v16, 0
	v_mov_b32_e32 v17, v129
	v_mov_b32_e32 v18, v129
	v_mov_b32_e32 v19, v129
	v_mov_b32_e32 v20, 0
	v_mov_b32_e32 v21, v129
	v_mov_b32_e32 v22, v129
	v_mov_b32_e32 v23, v129
	v_mov_b32_e32 v24, 0
	v_mov_b32_e32 v25, v129
	v_mov_b32_e32 v26, v129
	v_mov_b32_e32 v27, v129
	v_mov_b32_e32 v28, 0
	v_mov_b32_e32 v29, v129
	v_mov_b32_e32 v30, v129
	v_mov_b32_e32 v31, v129
	v_mov_b32_e32 v32, 0
	v_mov_b32_e32 v33, v129
	v_mov_b32_e32 v34, v129
	v_mov_b32_e32 v35, v129
	v_mov_b32_e32 v36, 0
	v_mov_b32_e32 v37, v129
	v_mov_b32_e32 v38, v129
	v_mov_b32_e32 v39, v129
	v_mov_b32_e32 v40, 0
	v_mov_b32_e32 v41, v129
	v_mov_b32_e32 v42, v129
	v_mov_b32_e32 v43, v129
	v_mov_b32_e32 v44, 0
	v_mov_b32_e32 v45, v129
	v_mov_b32_e32 v46, v129
	v_mov_b32_e32 v47, v129
	v_mov_b32_e32 v48, 0
	v_mov_b32_e32 v49, v129
	v_mov_b32_e32 v50, v129
	v_mov_b32_e32 v51, v129
	v_mov_b32_e32 v52, 0
	v_mov_b32_e32 v53, v129
	v_mov_b32_e32 v54, v129
	v_mov_b32_e32 v55, v129
	v_mov_b32_e32 v56, 0
	v_mov_b32_e32 v57, v129
	v_mov_b32_e32 v58, v129
	v_mov_b32_e32 v59, v129
	v_mov_b32_e32 v60, 0
	v_mov_b32_e32 v61, v129
	v_mov_b32_e32 v62, v129
	v_mov_b32_e32 v63, v129
	v_mov_b32_e32 v64, 0
	v_mov_b32_e32 v65, v129
	v_mov_b32_e32 v66, v129
	v_mov_b32_e32 v67, v129
	v_mov_b32_e32 v68, 0
	v_mov_b32_e32 v69, v129
	v_mov_b32_e32 v70, v129
	v_mov_b32_e32 v71, v129
	v_mov_b32_e32 v72, 0
	v_mov_b32_e32 v73, v129
	v_mov_b32_e32 v74, v129
	v_mov_b32_e32 v75, v129
	v_mov_b32_e32 v76, 0
	v_mov_b32_e32 v77, v129
	v_mov_b32_e32 v78, v129
	v_mov_b32_e32 v79, v129
	v_mov_b32_e32 v80, 0
	v_mov_b32_e32 v81, v129
	v_mov_b32_e32 v82, v129
	v_mov_b32_e32 v83, v129
	v_mov_b32_e32 v84, 0
	v_mov_b32_e32 v85, v129
	v_mov_b32_e32 v86, v129
	v_mov_b32_e32 v87, v129
	v_mov_b32_e32 v88, 0
	v_mov_b32_e32 v89, v129
	v_mov_b32_e32 v90, v129
	v_mov_b32_e32 v91, v129
	v_mov_b32_e32 v92, 0
	v_mov_b32_e32 v93, v129
	v_mov_b32_e32 v94, v129
	v_mov_b32_e32 v95, v129
	v_mov_b32_e32 v96, 0
	v_mov_b32_e32 v97, v129
	v_mov_b32_e32 v98, v129
	v_mov_b32_e32 v99, v129
	v_mov_b32_e32 v100, 0
	v_mov_b32_e32 v101, v129
	v_mov_b32_e32 v102, v129
	v_mov_b32_e32 v103, v129
	v_mov_b32_e32 v104, 0
	v_mov_b32_e32 v105, v129
	v_mov_b32_e32 v106, v129
	v_mov_b32_e32 v107, v129
	v_mov_b32_e32 v108, 0
	v_mov_b32_e32 v109, v129
	v_mov_b32_e32 v110, v129
	v_mov_b32_e32 v111, v129
	v_mov_b32_e32 v112, 0
	v_mov_b32_e32 v113, v129
	v_mov_b32_e32 v114, v129
	v_mov_b32_e32 v115, v129
	v_mov_b32_e32 v116, 0
	v_mov_b32_e32 v117, v129
	v_mov_b32_e32 v118, v129
	v_mov_b32_e32 v119, v129
	v_mov_b32_e32 v120, 0
	v_mov_b32_e32 v121, v129
	v_mov_b32_e32 v122, v129
	v_mov_b32_e32 v123, v129
	v_mov_b32_e32 v124, 0
	v_mov_b32_e32 v125, v129
	v_mov_b32_e32 v126, v129
	v_mov_b32_e32 v127, v129
	s_waitcnt vmcnt(0) lgkmcnt(0)
	s_barrier
	v_readfirstlane_b32 s100, v149
	s_mov_b64 s[98:99], 0x80
	s_and_b32 s17, s15, 0x10000
	s_xor_b32 s42, s17, 0x10000
	s_add_i32 s17, s17, 0
	v_add3_u32 v128, s17, v150, v151
	v_add3_u32 v161, s17, v150, v152
	v_add3_u32 v194, s17, v154, v153
	v_add3_u32 v195, s17, v154, v155
	v_add3_u32 v196, s17, v154, v156
	v_add3_u32 v197, s17, v154, v157
	v_add3_u32 v198, s17, v154, v158
	v_add3_u32 v199, s17, v154, v159
	v_add3_u32 v200, s17, v154, v160
	ds_read_b128 v[178:181], v128 offset:32768
	ds_read_b128 v[162:165], v161
	ds_read_b128 v[166:169], v194
	ds_read_b128 v[170:173], v195
	ds_read_b128 v[174:177], v196
	ds_read_b128 v[182:185], v128 offset:34816
	ds_read_b128 v[186:189], v128 offset:36864
	ds_read_b128 v[190:193], v128 offset:38912
	s_add_i32 s101, s100, s42
	s_mov_b32 m0, s101
	s_nop 0
	global_load_lds_dwordx4 v[146:147], off
	s_add_i32 m0, s101, 0x8000
	s_nop 0
	global_load_lds_dwordx4 v[138:139], off
	s_add_i32 m0, s101, 0x2000
	s_nop 0
	global_load_lds_dwordx4 v[144:145], off
	s_add_i32 m0, s101, 0xa000
	s_nop 0
	global_load_lds_dwordx4 v[136:137], off
	s_add_i32 m0, s101, 0x4000
	s_nop 0
	global_load_lds_dwordx4 v[142:143], off
	s_add_i32 m0, s101, 0xc000
	s_nop 0
	global_load_lds_dwordx4 v[134:135], off
	s_add_i32 m0, s101, 0x6000
	s_nop 0
	global_load_lds_dwordx4 v[140:141], off
	s_add_i32 m0, s101, 0xe000
	s_nop 0
	global_load_lds_dwordx4 v[130:131], off
.LBB0_942:
	s_and_b32 s17, s15, 0x10000
	s_xor_b32 s42, s17, 0x10000
	s_add_i32 s17, s17, 0
	s_waitcnt lgkmcnt(3)
	v_mfma_f32_16x16x32_bf16 v[108:111], v[178:181], v[162:165], v[108:111]
	v_mfma_f32_16x16x32_bf16 v[92:95], v[178:181], v[166:169], v[92:95]
	v_mfma_f32_16x16x32_bf16 v[76:79], v[178:181], v[170:173], v[76:79]
	v_mfma_f32_16x16x32_bf16 v[60:63], v[178:181], v[174:177], v[60:63]
	ds_read_b128 v[240:243], v197
	ds_read_b128 v[244:247], v198
	s_waitcnt lgkmcnt(4)
	v_mfma_f32_16x16x32_bf16 v[104:107], v[182:185], v[162:165], v[104:107]
	v_mfma_f32_16x16x32_bf16 v[88:91], v[182:185], v[166:169], v[88:91]
	v_mfma_f32_16x16x32_bf16 v[72:75], v[182:185], v[170:173], v[72:75]
	v_mfma_f32_16x16x32_bf16 v[56:59], v[182:185], v[174:177], v[56:59]
	ds_read_b128 v[248:251], v199
	ds_read_b128 v[252:255], v200
	s_waitcnt lgkmcnt(5)
	v_mfma_f32_16x16x32_bf16 v[100:103], v[186:189], v[162:165], v[100:103]
	v_mfma_f32_16x16x32_bf16 v[84:87], v[186:189], v[166:169], v[84:87]
	v_mfma_f32_16x16x32_bf16 v[68:71], v[186:189], v[170:173], v[68:71]
	v_mfma_f32_16x16x32_bf16 v[52:55], v[186:189], v[174:177], v[52:55]
	s_waitcnt lgkmcnt(4)
	v_mfma_f32_16x16x32_bf16 v[96:99], v[190:193], v[162:165], v[96:99]
	v_mfma_f32_16x16x32_bf16 v[80:83], v[190:193], v[166:169], v[80:83]
	v_mfma_f32_16x16x32_bf16 v[64:67], v[190:193], v[170:173], v[64:67]
	v_mfma_f32_16x16x32_bf16 v[48:51], v[190:193], v[174:177], v[48:51]
	ds_read_b128 v[162:165], v161 offset:1024
	ds_read_b128 v[166:169], v194 offset:1024
	ds_read_b128 v[170:173], v195 offset:1024
	ds_read_b128 v[174:177], v196 offset:1024
	s_waitcnt lgkmcnt(4)
	v_mfma_f32_16x16x32_bf16 v[44:47], v[178:181], v[240:243], v[44:47]
	v_mfma_f32_16x16x32_bf16 v[28:31], v[178:181], v[244:247], v[28:31]
	v_mfma_f32_16x16x32_bf16 v[12:15], v[178:181], v[248:251], v[12:15]
	v_mfma_f32_16x16x32_bf16 v[112:115], v[178:181], v[252:255], v[112:115]
	ds_read_b128 v[178:181], v128 offset:33792
	v_mfma_f32_16x16x32_bf16 v[40:43], v[182:185], v[240:243], v[40:43]
	v_mfma_f32_16x16x32_bf16 v[24:27], v[182:185], v[244:247], v[24:27]
	v_mfma_f32_16x16x32_bf16 v[8:11], v[182:185], v[248:251], v[8:11]
	v_mfma_f32_16x16x32_bf16 v[116:119], v[182:185], v[252:255], v[116:119]
	ds_read_b128 v[182:185], v128 offset:35840
	v_mfma_f32_16x16x32_bf16 v[36:39], v[186:189], v[240:243], v[36:39]
	v_mfma_f32_16x16x32_bf16 v[20:23], v[186:189], v[244:247], v[20:23]
	v_mfma_f32_16x16x32_bf16 v[4:7], v[186:189], v[248:251], v[4:7]
	v_mfma_f32_16x16x32_bf16 v[120:123], v[186:189], v[252:255], v[120:123]
	ds_read_b128 v[186:189], v128 offset:37888
	v_mfma_f32_16x16x32_bf16 v[32:35], v[190:193], v[240:243], v[32:35]
	v_mfma_f32_16x16x32_bf16 v[16:19], v[190:193], v[244:247], v[16:19]
	v_mfma_f32_16x16x32_bf16 v[0:3], v[190:193], v[248:251], v[0:3]
	v_mfma_f32_16x16x32_bf16 v[124:127], v[190:193], v[252:255], v[124:127]
	ds_read_b128 v[190:193], v128 offset:39936
	s_waitcnt lgkmcnt(3)
	v_mfma_f32_16x16x32_bf16 v[108:111], v[178:181], v[162:165], v[108:111]
	v_mfma_f32_16x16x32_bf16 v[92:95], v[178:181], v[166:169], v[92:95]
	v_mfma_f32_16x16x32_bf16 v[76:79], v[178:181], v[170:173], v[76:79]
	v_mfma_f32_16x16x32_bf16 v[60:63], v[178:181], v[174:177], v[60:63]
	ds_read_b128 v[240:243], v197 offset:1024
	ds_read_b128 v[244:247], v198 offset:1024
	s_waitcnt lgkmcnt(4)
	v_mfma_f32_16x16x32_bf16 v[104:107], v[182:185], v[162:165], v[104:107]
	v_mfma_f32_16x16x32_bf16 v[88:91], v[182:185], v[166:169], v[88:91]
	v_mfma_f32_16x16x32_bf16 v[72:75], v[182:185], v[170:173], v[72:75]
	v_mfma_f32_16x16x32_bf16 v[56:59], v[182:185], v[174:177], v[56:59]
	ds_read_b128 v[248:251], v199 offset:1024
	ds_read_b128 v[252:255], v200 offset:1024
	s_waitcnt lgkmcnt(5)
	v_mfma_f32_16x16x32_bf16 v[100:103], v[186:189], v[162:165], v[100:103]
	v_mfma_f32_16x16x32_bf16 v[84:87], v[186:189], v[166:169], v[84:87]
	v_mfma_f32_16x16x32_bf16 v[68:71], v[186:189], v[170:173], v[68:71]
	v_mfma_f32_16x16x32_bf16 v[52:55], v[186:189], v[174:177], v[52:55]
	s_waitcnt lgkmcnt(4)
	v_mfma_f32_16x16x32_bf16 v[96:99], v[190:193], v[162:165], v[96:99]
	v_mfma_f32_16x16x32_bf16 v[80:83], v[190:193], v[166:169], v[80:83]
	v_mfma_f32_16x16x32_bf16 v[64:67], v[190:193], v[170:173], v[64:67]
	v_mfma_f32_16x16x32_bf16 v[48:51], v[190:193], v[174:177], v[48:51]
	s_waitcnt vmcnt(0) lgkmcnt(0)
	s_barrier
	s_add_i32 s101, s100, s17
	v_mfma_f32_16x16x32_bf16 v[44:47], v[178:181], v[240:243], v[44:47]
	v_mfma_f32_16x16x32_bf16 v[28:31], v[178:181], v[244:247], v[28:31]
	v_mfma_f32_16x16x32_bf16 v[12:15], v[178:181], v[248:251], v[12:15]
	v_mfma_f32_16x16x32_bf16 v[112:115], v[178:181], v[252:255], v[112:115]
	v_add3_u32 v128, s42, v150, v151
	ds_read_b128 v[178:181], v128 offset:32768
	v_add3_u32 v161, s42, v150, v152
	v_add3_u32 v194, s42, v154, v153
	v_add3_u32 v195, s42, v154, v155
	v_add3_u32 v196, s42, v154, v156
	ds_read_b128 v[162:165], v161
	ds_read_b128 v[166:169], v194
	ds_read_b128 v[170:173], v195
	ds_read_b128 v[174:177], v196
	s_cmpk_eq_i32 s18, 0x700
	s_cbranch_scc1 .Lpk_942_0
	s_mov_b32 m0, s101
	v_lshl_add_u64 v[146:147], v[146:147], 0, s[98:99]
	global_load_lds_dwordx4 v[146:147], off
.Lpk_942_0:
	s_cmpk_eq_i32 s18, 0x700
	s_cbranch_scc1 .Lpk_942_1
	s_add_i32 m0, s101, 0x8000
	v_lshl_add_u64 v[138:139], v[138:139], 0, s[98:99]
	global_load_lds_dwordx4 v[138:139], off
.Lpk_942_1:
	v_mfma_f32_16x16x32_bf16 v[40:43], v[182:185], v[240:243], v[40:43]
	v_mfma_f32_16x16x32_bf16 v[24:27], v[182:185], v[244:247], v[24:27]
	v_mfma_f32_16x16x32_bf16 v[8:11], v[182:185], v[248:251], v[8:11]
	v_mfma_f32_16x16x32_bf16 v[116:119], v[182:185], v[252:255], v[116:119]
	ds_read_b128 v[182:185], v128 offset:34816
	v_add3_u32 v197, s42, v154, v157
	v_add3_u32 v198, s42, v154, v158
	v_add3_u32 v199, s42, v154, v159
	v_add3_u32 v200, s42, v154, v160
	s_cmpk_eq_i32 s18, 0x700
	s_cbranch_scc1 .Lpk_942_2
	s_add_i32 m0, s101, 0x2000
	v_lshl_add_u64 v[144:145], v[144:145], 0, s[98:99]
	global_load_lds_dwordx4 v[144:145], off
.Lpk_942_2:
	s_cmpk_eq_i32 s18, 0x700
	s_cbranch_scc1 .Lpk_942_3
	s_add_i32 m0, s101, 0xa000
	v_lshl_add_u64 v[136:137], v[136:137], 0, s[98:99]
	global_load_lds_dwordx4 v[136:137], off
.Lpk_942_3:
	v_mfma_f32_16x16x32_bf16 v[36:39], v[186:189], v[240:243], v[36:39]
	v_mfma_f32_16x16x32_bf16 v[20:23], v[186:189], v[244:247], v[20:23]
	v_mfma_f32_16x16x32_bf16 v[4:7], v[186:189], v[248:251], v[4:7]
	v_mfma_f32_16x16x32_bf16 v[120:123], v[186:189], v[252:255], v[120:123]
	ds_read_b128 v[186:189], v128 offset:36864
	s_cmpk_eq_i32 s18, 0x700
	s_cbranch_scc1 .Lpk_942_4
	s_add_i32 m0, s101, 0x4000
	v_lshl_add_u64 v[142:143], v[142:143], 0, s[98:99]
	global_load_lds_dwordx4 v[142:143], off
.Lpk_942_4:
	s_cmpk_eq_i32 s18, 0x700
	s_cbranch_scc1 .Lpk_942_5
	s_add_i32 m0, s101, 0xc000
	v_lshl_add_u64 v[134:135], v[134:135], 0, s[98:99]
	global_load_lds_dwordx4 v[134:135], off
.Lpk_942_5:
	v_mfma_f32_16x16x32_bf16 v[32:35], v[190:193], v[240:243], v[32:35]
	v_mfma_f32_16x16x32_bf16 v[16:19], v[190:193], v[244:247], v[16:19]
	v_mfma_f32_16x16x32_bf16 v[0:3], v[190:193], v[248:251], v[0:3]
	v_mfma_f32_16x16x32_bf16 v[124:127], v[190:193], v[252:255], v[124:127]
	ds_read_b128 v[190:193], v128 offset:38912
	s_cmpk_eq_i32 s18, 0x700
	s_cbranch_scc1 .Lpk_942_6
	s_add_i32 m0, s101, 0x6000
	v_lshl_add_u64 v[140:141], v[140:141], 0, s[98:99]
	global_load_lds_dwordx4 v[140:141], off
.Lpk_942_6:
	s_cmpk_eq_i32 s18, 0x700
	s_cbranch_scc1 .Lpk_942_7
	s_add_i32 m0, s101, 0xe000
	v_lshl_add_u64 v[130:131], v[130:131], 0, s[98:99]
	global_load_lds_dwordx4 v[130:131], off
.Lpk_942_7:
	s_add_i32 s15, s15, 0x10000
	s_add_u32 s18, s18, 0x80
	s_addc_u32 s19, s19, 0
	s_cmpk_lg_i32 s18, 0x780
	s_cbranch_scc1 .LBB0_942
	s_waitcnt lgkmcnt(0)
	v_add3_u32 v128, s24, v154, v160
	v_add3_u32 v130, s24, v154, v159
	v_add3_u32 v131, s24, v154, v158
	v_add3_u32 v146, s24, v154, v157
	v_add3_u32 v147, s24, v154, v156
	v_add3_u32 v149, s24, v154, v155
	v_add3_u32 v186, s24, v154, v153
	v_add3_u32 v187, s24, v150, v152
	v_add3_u32 v188, s26, v150, v151
	ds_read_b128 v[134:137], v128
	ds_read_b128 v[138:141], v130
	ds_read_b128 v[142:145], v131
	ds_read_b128 v[158:161], v146
	ds_read_b128 v[162:165], v147
	ds_read_b128 v[166:169], v149
	ds_read_b128 v[154:157], v186
	ds_read_b128 v[170:173], v187
	ds_read_b128 v[178:181], v188 offset:4096
	s_waitcnt lgkmcnt(0)
	v_mfma_f32_16x16x32_bf16 v[4:7], v[178:181], v[138:141], v[4:7]
	ds_read_b128 v[174:177], v188 offset:2048
	s_waitcnt lgkmcnt(0)
	v_mfma_f32_16x16x32_bf16 v[8:11], v[174:177], v[138:141], v[8:11]
	ds_read_b128 v[150:153], v188
	s_waitcnt lgkmcnt(0)
	v_mfma_f32_16x16x32_bf16 v[12:15], v[150:153], v[138:141], v[12:15]
	v_mfma_f32_16x16x32_bf16 v[112:115], v[150:153], v[134:137], v[112:115]
	v_mfma_f32_16x16x32_bf16 v[108:111], v[150:153], v[170:173], v[108:111]
	v_mfma_f32_16x16x32_bf16 v[92:95], v[150:153], v[154:157], v[92:95]
	v_mfma_f32_16x16x32_bf16 v[76:79], v[150:153], v[166:169], v[76:79]
	v_mfma_f32_16x16x32_bf16 v[116:119], v[174:177], v[134:137], v[116:119]
	v_mfma_f32_16x16x32_bf16 v[104:107], v[174:177], v[170:173], v[104:107]
	v_mfma_f32_16x16x32_bf16 v[88:91], v[174:177], v[154:157], v[88:91]
	v_mfma_f32_16x16x32_bf16 v[72:75], v[174:177], v[166:169], v[72:75]
	v_mfma_f32_16x16x32_bf16 v[120:123], v[178:181], v[134:137], v[120:123]
	v_mfma_f32_16x16x32_bf16 v[100:103], v[178:181], v[170:173], v[100:103]
	v_mfma_f32_16x16x32_bf16 v[84:87], v[178:181], v[154:157], v[84:87]
	v_mfma_f32_16x16x32_bf16 v[68:71], v[178:181], v[166:169], v[68:71]
	ds_read_b128 v[182:185], v188 offset:6144
	s_waitcnt lgkmcnt(0)
	v_mfma_f32_16x16x32_bf16 v[124:127], v[182:185], v[134:137], v[124:127]
	v_mfma_f32_16x16x32_bf16 v[96:99], v[182:185], v[170:173], v[96:99]
	v_mfma_f32_16x16x32_bf16 v[80:83], v[182:185], v[154:157], v[80:83]
	v_mfma_f32_16x16x32_bf16 v[64:67], v[182:185], v[166:169], v[64:67]
	v_mfma_f32_16x16x32_bf16 v[48:51], v[182:185], v[162:165], v[48:51]
	v_mfma_f32_16x16x32_bf16 v[52:55], v[178:181], v[162:165], v[52:55]
	v_mfma_f32_16x16x32_bf16 v[56:59], v[174:177], v[162:165], v[56:59]
	v_mfma_f32_16x16x32_bf16 v[60:63], v[150:153], v[162:165], v[60:63]
	v_mfma_f32_16x16x32_bf16 v[44:47], v[150:153], v[158:161], v[44:47]
	v_mfma_f32_16x16x32_bf16 v[40:43], v[174:177], v[158:161], v[40:43]
	v_mfma_f32_16x16x32_bf16 v[36:39], v[178:181], v[158:161], v[36:39]
	v_mfma_f32_16x16x32_bf16 v[32:35], v[182:185], v[158:161], v[32:35]
	v_mfma_f32_16x16x32_bf16 v[28:31], v[150:153], v[142:145], v[28:31]
	v_mfma_f32_16x16x32_bf16 v[24:27], v[174:177], v[142:145], v[24:27]
	v_mfma_f32_16x16x32_bf16 v[20:23], v[178:181], v[142:145], v[20:23]
	v_mfma_f32_16x16x32_bf16 v[16:19], v[182:185], v[142:145], v[16:19]
	v_mfma_f32_16x16x32_bf16 v[0:3], v[182:185], v[138:141], v[0:3]
	ds_read_b128 v[134:137], v188 offset:1024
	ds_read_b128 v[138:141], v188 offset:3072
	ds_read_b128 v[142:145], v188 offset:5120
	ds_read_b128 v[154:157], v188 offset:7168
	ds_read_b128 v[150:153], v187 offset:1024
	ds_read_b128 v[158:161], v186 offset:1024
	ds_read_b128 v[162:165], v149 offset:1024
	ds_read_b128 v[166:169], v147 offset:1024
	s_waitcnt lgkmcnt(3)
	v_mfma_f32_16x16x32_bf16 v[108:111], v[134:137], v[150:153], v[108:111]
	v_mfma_f32_16x16x32_bf16 v[104:107], v[138:141], v[150:153], v[104:107]
	v_mfma_f32_16x16x32_bf16 v[100:103], v[142:145], v[150:153], v[100:103]
	v_mfma_f32_16x16x32_bf16 v[96:99], v[154:157], v[150:153], v[96:99]
	ds_read_b128 v[150:153], v146 offset:1024
	s_waitcnt lgkmcnt(3)
	v_mfma_f32_16x16x32_bf16 v[92:95], v[134:137], v[158:161], v[92:95]
	v_mfma_f32_16x16x32_bf16 v[88:91], v[138:141], v[158:161], v[88:91]
	v_mfma_f32_16x16x32_bf16 v[84:87], v[142:145], v[158:161], v[84:87]
	v_mfma_f32_16x16x32_bf16 v[80:83], v[154:157], v[158:161], v[80:83]
	ds_read_b128 v[158:161], v131 offset:1024
	s_waitcnt lgkmcnt(3)
	v_mfma_f32_16x16x32_bf16 v[76:79], v[134:137], v[162:165], v[76:79]
	v_mfma_f32_16x16x32_bf16 v[72:75], v[138:141], v[162:165], v[72:75]
	v_mfma_f32_16x16x32_bf16 v[68:71], v[142:145], v[162:165], v[68:71]
	v_mfma_f32_16x16x32_bf16 v[64:67], v[154:157], v[162:165], v[64:67]
	ds_read_b128 v[162:165], v130 offset:1024
	s_waitcnt lgkmcnt(3)
	v_mfma_f32_16x16x32_bf16 v[60:63], v[134:137], v[166:169], v[60:63]
	v_mfma_f32_16x16x32_bf16 v[56:59], v[138:141], v[166:169], v[56:59]
	v_mfma_f32_16x16x32_bf16 v[52:55], v[142:145], v[166:169], v[52:55]
	v_mfma_f32_16x16x32_bf16 v[48:51], v[154:157], v[166:169], v[48:51]
	ds_read_b128 v[166:169], v128 offset:1024
	s_waitcnt lgkmcnt(3)
	v_mfma_f32_16x16x32_bf16 v[44:47], v[134:137], v[150:153], v[44:47]
	v_mfma_f32_16x16x32_bf16 v[40:43], v[138:141], v[150:153], v[40:43]
	v_mfma_f32_16x16x32_bf16 v[36:39], v[142:145], v[150:153], v[36:39]
	v_mfma_f32_16x16x32_bf16 v[32:35], v[154:157], v[150:153], v[32:35]
	s_waitcnt lgkmcnt(2)
	v_mfma_f32_16x16x32_bf16 v[28:31], v[134:137], v[158:161], v[28:31]
	v_mfma_f32_16x16x32_bf16 v[24:27], v[138:141], v[158:161], v[24:27]
	v_mfma_f32_16x16x32_bf16 v[20:23], v[142:145], v[158:161], v[20:23]
	v_mfma_f32_16x16x32_bf16 v[16:19], v[154:157], v[158:161], v[16:19]
	s_waitcnt lgkmcnt(1)
	v_mfma_f32_16x16x32_bf16 v[12:15], v[134:137], v[162:165], v[12:15]
	v_mfma_f32_16x16x32_bf16 v[8:11], v[138:141], v[162:165], v[8:11]
	v_mfma_f32_16x16x32_bf16 v[4:7], v[142:145], v[162:165], v[4:7]
	v_mfma_f32_16x16x32_bf16 v[0:3], v[154:157], v[162:165], v[0:3]
	s_waitcnt lgkmcnt(0)
	v_mfma_f32_16x16x32_bf16 v[112:115], v[134:137], v[166:169], v[112:115]
	v_mfma_f32_16x16x32_bf16 v[116:119], v[138:141], v[166:169], v[116:119]
	v_mfma_f32_16x16x32_bf16 v[120:123], v[142:145], v[166:169], v[120:123]
	v_mfma_f32_16x16x32_bf16 v[124:127], v[154:157], v[166:169], v[124:127]
	v_mov_b32_e32 v128, s3
	s_waitcnt vmcnt(0)
	s_barrier
	ds_read_b64 v[130:131], v128
	v_ashrrev_i32_e32 v128, 1, v148
	v_and_b32_e32 v128, 0xffffff80, v128
	v_add_u32_e32 v128, s16, v128
	s_ashr_i32 s15, s14, 31
	s_waitcnt lgkmcnt(0)
	v_mad_i64_i32 v[130:131], s[16:17], v128, s23, v[130:131]
	v_and_b32_e32 v128, 0xc0, v148
	v_lshrrev_b32_e32 v135, 6, v148
	v_lshl_add_u64 v[130:131], s[14:15], 1, v[130:131]
	v_lshlrev_b32_e32 v128, 1, v128
	v_lshl_add_u64 v[130:131], v[130:131], 0, v[128:129]
	v_mul_lo_u32 v128, v135, s27
	v_add_u32_e32 v135, s24, v128
	v_lshrrev_b32_e32 v128, 1, v148
	v_and_b32_e32 v136, 24, v128
	v_lshlrev_b32_e32 v128, 4, v148
	v_bfe_u32 v137, v148, 3, 3
	v_and_b32_e32 v134, 15, v148
	v_and_b32_e32 v128, 0x70, v128
	v_mul_u32_u24_e32 v138, 0x90, v137
	v_lshl_add_u64 v[130:131], v[130:131], 0, v[128:129]
	v_add3_u32 v138, v135, v128, v138
	v_mul_u32_u24_e32 v128, 0x90, v134
	v_add3_u32 v134, v135, v136, v128
	v_cvt_pk_bf16_f32 v108, v108, v109
	v_cvt_pk_bf16_f32 v109, v110, v111
	v_cvt_pk_bf16_f32 v104, v104, v105
	v_cvt_pk_bf16_f32 v105, v106, v107
	v_cvt_pk_bf16_f32 v100, v100, v101
	v_cvt_pk_bf16_f32 v101, v102, v103
	v_cvt_pk_bf16_f32 v96, v96, v97
	v_cvt_pk_bf16_f32 v97, v98, v99
	v_cvt_pk_bf16_f32 v92, v92, v93
	v_cvt_pk_bf16_f32 v93, v94, v95
	v_cvt_pk_bf16_f32 v88, v88, v89
	v_cvt_pk_bf16_f32 v89, v90, v91
	v_cvt_pk_bf16_f32 v84, v84, v85
	v_cvt_pk_bf16_f32 v85, v86, v87
	v_cvt_pk_bf16_f32 v80, v80, v81
	v_cvt_pk_bf16_f32 v81, v82, v83
	v_cvt_pk_bf16_f32 v76, v76, v77
	v_cvt_pk_bf16_f32 v77, v78, v79
	v_cvt_pk_bf16_f32 v72, v72, v73
	v_cvt_pk_bf16_f32 v73, v74, v75
	v_cvt_pk_bf16_f32 v68, v68, v69
	v_cvt_pk_bf16_f32 v69, v70, v71
	v_cvt_pk_bf16_f32 v64, v64, v65
	v_cvt_pk_bf16_f32 v65, v66, v67
	v_cvt_pk_bf16_f32 v60, v60, v61
	v_cvt_pk_bf16_f32 v61, v62, v63
	v_cvt_pk_bf16_f32 v56, v56, v57
	v_cvt_pk_bf16_f32 v57, v58, v59
	v_cvt_pk_bf16_f32 v52, v52, v53
	v_cvt_pk_bf16_f32 v53, v54, v55
	v_cvt_pk_bf16_f32 v48, v48, v49
	v_cvt_pk_bf16_f32 v49, v50, v51
	ds_write_b64 v134, v[108:109]
	ds_write_b64 v134, v[104:105] offset:32
	ds_write_b64 v134, v[100:101] offset:64
	ds_write_b64 v134, v[96:97] offset:96
	ds_write_b64 v134, v[92:93] offset:2304
	ds_write_b64 v134, v[88:89] offset:2336
	ds_write_b64 v134, v[84:85] offset:2368
	ds_write_b64 v134, v[80:81] offset:2400
	ds_write_b64 v134, v[76:77] offset:4608
	ds_write_b64 v134, v[72:73] offset:4640
	ds_write_b64 v134, v[68:69] offset:4672
	ds_write_b64 v134, v[64:65] offset:4704
	ds_write_b64 v134, v[60:61] offset:6912
	ds_write_b64 v134, v[56:57] offset:6944
	ds_write_b64 v134, v[52:53] offset:6976
	ds_write_b64 v134, v[48:49] offset:7008
	ds_read_b128 v[48:51], v138
	v_mul_u32_u24_e32 v54, 0xc00, v137
	v_lshl_add_u64 v[52:53], v[130:131], 0, s[12:13]
	v_lshlrev_b32_e32 v128, 1, v54
	v_lshl_add_u64 v[54:55], v[52:53], 0, v[128:129]
	s_waitcnt lgkmcnt(0)
	flat_store_dwordx4 v[54:55], v[48:51] nt
	ds_read_b128 v[48:51], v138 offset:1152
	v_add_co_u32_e32 v56, vcc, s21, v54
	v_cvt_pk_bf16_f32 v0, v0, v1
	s_nop 0
	v_addc_co_u32_e32 v57, vcc, 0, v55, vcc
	s_waitcnt lgkmcnt(0)
	flat_store_dwordx4 v[56:57], v[48:51] nt
	ds_read_b128 v[48:51], v138 offset:2304
	v_add_co_u32_e32 v56, vcc, s25, v54
	v_cvt_pk_bf16_f32 v1, v2, v3
	s_nop 0
	v_addc_co_u32_e32 v57, vcc, 0, v55, vcc
	s_waitcnt lgkmcnt(0)
	flat_store_dwordx4 v[56:57], v[48:51] nt
	ds_read_b128 v[48:51], v138 offset:3456
	v_add_co_u32_e32 v56, vcc, s28, v54
	v_cvt_pk_bf16_f32 v44, v44, v45
	s_nop 0
	v_addc_co_u32_e32 v57, vcc, 0, v55, vcc
	s_waitcnt lgkmcnt(0)
	flat_store_dwordx4 v[56:57], v[48:51] nt
	ds_read_b128 v[48:51], v138 offset:4608
	v_or_b32_e32 v56, 0x30000, v128
	v_mov_b32_e32 v57, v129
	v_lshl_add_u64 v[56:57], v[52:53], 0, v[56:57]
	v_cvt_pk_bf16_f32 v45, v46, v47
	s_waitcnt lgkmcnt(0)
	flat_store_dwordx4 v[56:57], v[48:51] nt
	ds_read_b128 v[48:51], v138 offset:5760
	v_add_u32_e32 v56, 0x3c000, v128
	v_mov_b32_e32 v57, v129
	v_lshl_add_u64 v[56:57], v[52:53], 0, v[56:57]
	v_cvt_pk_bf16_f32 v40, v40, v41
	s_waitcnt lgkmcnt(0)
	flat_store_dwordx4 v[56:57], v[48:51] nt
	ds_read_b128 v[48:51], v138 offset:6912
	v_add_u32_e32 v56, 0x48000, v128
	v_mov_b32_e32 v57, v129
	v_lshl_add_u64 v[56:57], v[52:53], 0, v[56:57]
	v_add_u32_e32 v128, 0x54000, v128
	s_waitcnt lgkmcnt(0)
	flat_store_dwordx4 v[56:57], v[48:51] nt
	ds_read_b128 v[48:51], v138 offset:8064
	v_lshl_add_u64 v[52:53], v[52:53], 0, v[128:129]
	v_cvt_pk_bf16_f32 v41, v42, v43
	v_cvt_pk_bf16_f32 v36, v36, v37
	v_cvt_pk_bf16_f32 v37, v38, v39
	s_waitcnt lgkmcnt(0)
	flat_store_dwordx4 v[52:53], v[48:51] nt
	ds_write_b64 v134, v[0:1] offset:4704
	v_cvt_pk_bf16_f32 v0, v112, v113
	v_cvt_pk_bf16_f32 v1, v114, v115
	ds_write_b64 v134, v[0:1] offset:6912
	v_cvt_pk_bf16_f32 v0, v116, v117
	v_cvt_pk_bf16_f32 v1, v118, v119
	ds_write_b64 v134, v[0:1] offset:6944
	v_cvt_pk_bf16_f32 v0, v120, v121
	v_cvt_pk_bf16_f32 v1, v122, v123
	v_cvt_pk_bf16_f32 v32, v32, v33
	v_cvt_pk_bf16_f32 v33, v34, v35
	v_cvt_pk_bf16_f32 v28, v28, v29
	v_cvt_pk_bf16_f32 v29, v30, v31
	v_cvt_pk_bf16_f32 v24, v24, v25
	v_cvt_pk_bf16_f32 v25, v26, v27
	v_cvt_pk_bf16_f32 v20, v20, v21
	v_cvt_pk_bf16_f32 v21, v22, v23
	v_cvt_pk_bf16_f32 v16, v16, v17
	v_cvt_pk_bf16_f32 v17, v18, v19
	v_cvt_pk_bf16_f32 v12, v12, v13
	v_cvt_pk_bf16_f32 v13, v14, v15
	v_cvt_pk_bf16_f32 v8, v8, v9
	v_cvt_pk_bf16_f32 v9, v10, v11
	v_cvt_pk_bf16_f32 v4, v4, v5
	v_cvt_pk_bf16_f32 v5, v6, v7
	ds_write_b64 v134, v[0:1] offset:6976
	v_cvt_pk_bf16_f32 v0, v124, v125
	v_cvt_pk_bf16_f32 v1, v126, v127
	ds_write_b64 v134, v[44:45]
	ds_write_b64 v134, v[40:41] offset:32
	ds_write_b64 v134, v[36:37] offset:64
	ds_write_b64 v134, v[32:33] offset:96
	ds_write_b64 v134, v[28:29] offset:2304
	ds_write_b64 v134, v[24:25] offset:2336
	ds_write_b64 v134, v[20:21] offset:2368
	ds_write_b64 v134, v[16:17] offset:2400
	ds_write_b64 v134, v[12:13] offset:4608
	ds_write_b64 v134, v[8:9] offset:4640
	ds_write_b64 v134, v[4:5] offset:4672
	ds_write_b64 v134, v[0:1] offset:7008
	ds_read_b128 v[0:3], v138
	v_add_co_u32_e32 v4, vcc, s29, v54
	s_add_i32 s39, s39, s40
	s_nop 0
	v_addc_co_u32_e32 v5, vcc, 0, v55, vcc
	s_waitcnt lgkmcnt(0)
	flat_store_dwordx4 v[4:5], v[0:3] nt
	ds_read_b128 v[0:3], v138 offset:1152
	v_add_co_u32_e32 v4, vcc, s30, v54
	s_cmpk_gt_i32 s39, 0x5ff
	s_nop 0
	v_addc_co_u32_e32 v5, vcc, 0, v55, vcc
	s_waitcnt lgkmcnt(0)
	flat_store_dwordx4 v[4:5], v[0:3] nt
	ds_read_b128 v[0:3], v138 offset:2304
	v_add_co_u32_e32 v4, vcc, s31, v54
	s_nop 1
	v_addc_co_u32_e32 v5, vcc, 0, v55, vcc
	s_waitcnt lgkmcnt(0)
	flat_store_dwordx4 v[4:5], v[0:3] nt
	ds_read_b128 v[0:3], v138 offset:3456
	v_add_co_u32_e32 v4, vcc, s34, v54
	s_nop 1
	v_addc_co_u32_e32 v5, vcc, 0, v55, vcc
	s_waitcnt lgkmcnt(0)
	flat_store_dwordx4 v[4:5], v[0:3] nt
	ds_read_b128 v[0:3], v138 offset:4608
	v_add_co_u32_e32 v4, vcc, s35, v54
	s_nop 1
	v_addc_co_u32_e32 v5, vcc, 0, v55, vcc
	s_waitcnt lgkmcnt(0)
	flat_store_dwordx4 v[4:5], v[0:3] nt
	ds_read_b128 v[0:3], v138 offset:5760
	v_add_co_u32_e32 v4, vcc, s38, v54
	s_nop 1
	v_addc_co_u32_e32 v5, vcc, 0, v55, vcc
	s_waitcnt lgkmcnt(0)
	flat_store_dwordx4 v[4:5], v[0:3] nt
	ds_read_b128 v[0:3], v138 offset:6912
	v_add_co_u32_e32 v4, vcc, 0xa8000, v54
	s_nop 1
	v_addc_co_u32_e32 v5, vcc, 0, v55, vcc
	s_waitcnt lgkmcnt(0)
	flat_store_dwordx4 v[4:5], v[0:3] nt
	ds_read_b128 v[0:3], v138 offset:8064
	v_add_co_u32_e32 v4, vcc, 0xb4000, v54
	s_nop 1
	v_addc_co_u32_e32 v5, vcc, 0, v55, vcc
	s_waitcnt lgkmcnt(0)
	flat_store_dwordx4 v[4:5], v[0:3] nt
	s_cbranch_scc0 .LBB0_941

.LBB0_1039:
	s_mul_hi_i32 s14, s42, 0x66666667
	s_lshr_b32 s15, s14, 31
	s_ashr_i32 s14, s14, 6
	s_add_i32 s15, s14, s15
	s_mul_i32 s14, s15, 0xa0
	s_sub_i32 s16, s42, s14
	s_sext_i32_i16 s14, s16
	s_bfe_u32 s14, s14, 0x4001b
	s_add_i32 s14, s16, s14
	s_sext_i32_i16 s17, s14
	s_and_b32 s14, s14, 0xfff0
	s_sub_i32 s14, s16, s14
	s_sext_i32_i16 s19, s14
	s_lshl_b32 s14, s17, 4
	s_and_b32 s14, s14, 0xffffff00
	v_mov_b32_e32 v148, v132
	v_mov_b32_e32 v18, v132
	s_cmpk_lt_i32 s16, 0x50
	ds_read_b64 v[0:1], v133
	s_cselect_b32 s16, s3, 0xc00
	v_lshlrev_b32_e32 v9, 4, v18
	v_and_b32_e32 v8, 32, v18
	v_lshrrev_b32_e32 v10, 1, v18
	v_bitop3_b32 v8, v9, v8, 48 bitop3:0x6c
	s_add_i32 s18, s14, s16
	s_lshl_b32 s15, s15, 12
	s_lshl_b32 s16, s19, 8
	v_bfe_u32 v19, v18, 2, 4
	v_and_b32_e32 v20, 32, v10
	v_lshrrev_b32_e32 v21, 1, v8
	v_ashrrev_i32_e32 v22, 3, v18
	s_add_i32 s16, s16, s15
	v_or_b32_e32 v12, v21, v20
	v_and_or_b32 v8, v22, s21, v19
	s_ashr_i32 s17, s16, 31
	v_and_b32_e32 v11, 0xfffffc00, v9
	v_lshl_or_b32 v128, v8, 10, v12
	v_add_u32_e32 v8, 0x2000, v9
	v_add_u32_e32 v10, 0x4000, v9
	v_add_u32_e32 v9, 0x6000, v9
	s_lshl_b64 s[44:45], s[16:17], 11
	s_ashr_i32 s19, s18, 31
	v_ashrrev_i32_e32 v23, 7, v8
	v_ashrrev_i32_e32 v24, 7, v10
	v_ashrrev_i32_e32 v25, 7, v9
	s_waitcnt lgkmcnt(0)
	v_lshl_add_u64 v[2:3], v[0:1], 0, s[44:45]
	s_lshl_b64 s[18:19], s[18:19], 11
	v_and_or_b32 v8, v23, s21, v19
	v_and_or_b32 v10, v24, s21, v19
	v_and_or_b32 v9, v25, s21, v19
	v_add_u32_e32 v149, 0, v11
	v_lshl_add_u64 v[4:5], v[2:3], 0, s[4:5]
	v_lshl_add_u64 v[0:1], v[0:1], 0, s[18:19]
	v_lshl_or_b32 v8, v8, 10, v12
	v_lshl_or_b32 v10, v10, 10, v12
	v_lshl_or_b32 v12, v9, 10, v12
	v_add_u32_e32 v9, 0x8000, v149
	v_lshlrev_b64 v[14:15], 1, v[128:129]
	v_readfirstlane_b32 s15, v149
	v_lshl_add_u64 v[6:7], v[0:1], 0, s[6:7]
	v_lshl_add_u64 v[16:17], v[4:5], 0, v[14:15]
	s_mov_b32 m0, s15
	v_readfirstlane_b32 s15, v9
	v_mov_b32_e32 v9, v129
	v_add_u32_e32 v11, 0x2000, v149
	global_load_lds_dwordx4 v[16:17], off
	v_lshl_add_u64 v[14:15], v[6:7], 0, v[14:15]
	s_mov_b32 m0, s15
	v_lshlrev_b64 v[8:9], 1, v[8:9]
	v_readfirstlane_b32 s15, v11
	v_add_u32_e32 v11, 0xa000, v149
	global_load_lds_dwordx4 v[14:15], off
	v_lshl_add_u64 v[14:15], v[4:5], 0, v[8:9]
	s_mov_b32 m0, s15
	v_readfirstlane_b32 s15, v11
	global_load_lds_dwordx4 v[14:15], off
	v_lshl_add_u64 v[8:9], v[6:7], 0, v[8:9]
	s_mov_b32 m0, s15
	v_mov_b32_e32 v11, v129
	v_add_u32_e32 v13, 0x4000, v149
	global_load_lds_dwordx4 v[8:9], off
	v_lshlrev_b64 v[8:9], 1, v[10:11]
	v_readfirstlane_b32 s15, v13
	v_lshl_add_u64 v[10:11], v[4:5], 0, v[8:9]
	s_mov_b32 m0, s15
	v_lshl_add_u64 v[8:9], v[6:7], 0, v[8:9]
	global_load_lds_dwordx4 v[10:11], off
	v_add_u32_e32 v10, 0xc000, v149
	v_mov_b32_e32 v13, v129
	v_readfirstlane_b32 s15, v10
	s_mov_b32 m0, s15
	v_add_u32_e32 v10, 0x6000, v149
	global_load_lds_dwordx4 v[8:9], off
	v_lshlrev_b64 v[8:9], 1, v[12:13]
	v_readfirstlane_b32 s15, v10
	v_lshl_add_u64 v[4:5], v[4:5], 0, v[8:9]
	s_mov_b32 m0, s15
	v_and_b32_e32 v26, 15, v18
	global_load_lds_dwordx4 v[4:5], off
	v_lshl_add_u64 v[4:5], v[6:7], 0, v[8:9]
	v_add_u32_e32 v6, 0xe000, v149
	v_lshlrev_b32_e32 v10, 10, v19
	v_readfirstlane_b32 s15, v6
	s_mov_b32 m0, s15
	v_lshlrev_b32_e32 v6, 2, v18
	global_load_lds_dwordx4 v[4:5], off
	v_and_b32_e32 v4, 48, v18
	v_lshlrev_b32_e32 v5, 6, v26
	v_and_b32_e32 v6, 32, v6
	v_bitop3_b32 v150, v5, v6, v4 bitop3:0x36
	v_lshlrev_b32_e32 v5, 7, v18
	v_and_b32_e32 v151, 0x6000, v5
	v_lshlrev_b32_e32 v5, 6, v18
	v_and_b32_e32 v152, 0xffffc000, v5
	v_and_b32_e32 v5, 0x3c0, v5
	v_bitop3_b32 v154, v5, v6, v4 bitop3:0x36
	v_lshlrev_b32_e32 v4, 10, v25
	v_and_or_b32 v4, v4, s23, v21
	v_lshlrev_b32_e32 v6, 10, v24
	v_or3_b32 v128, v4, v10, v20
	v_and_or_b32 v6, v6, s23, v21
	v_lshlrev_b32_e32 v8, 10, v23
	v_lshlrev_b64 v[4:5], 1, v[128:129]
	v_or3_b32 v128, v6, v10, v20
	v_and_or_b32 v8, v8, s23, v21
	v_lshlrev_b32_e32 v11, 10, v22
	v_lshlrev_b64 v[6:7], 1, v[128:129]
	v_or3_b32 v128, v8, v10, v20
	v_and_or_b32 v11, v11, s23, v21
	v_lshlrev_b64 v[8:9], 1, v[128:129]
	v_or3_b32 v128, v11, v10, v20
	s_waitcnt vmcnt(0)
	v_lshl_add_u64 v[0:1], v[0:1], 0, s[8:9]
	v_lshlrev_b64 v[10:11], 1, v[128:129]
	v_lshl_add_u64 v[130:131], v[0:1], 0, v[4:5]
	v_lshl_add_u64 v[134:135], v[0:1], 0, v[6:7]
	v_lshl_add_u64 v[136:137], v[0:1], 0, v[8:9]
	v_lshl_add_u64 v[138:139], v[0:1], 0, v[10:11]
	v_lshl_add_u64 v[0:1], v[2:3], 0, s[10:11]
	v_or_b32_e32 v153, 0x800, v152
	v_or_b32_e32 v155, 0x1000, v152
	v_or_b32_e32 v156, 0x1800, v152
	v_or_b32_e32 v157, 0x2000, v152
	v_or_b32_e32 v158, 0x2800, v152
	v_or_b32_e32 v159, 0x3000, v152
	v_or_b32_e32 v160, 0x3800, v152
	v_lshl_add_u64 v[140:141], v[0:1], 0, v[4:5]
	v_lshl_add_u64 v[142:143], v[0:1], 0, v[6:7]
	v_lshl_add_u64 v[144:145], v[0:1], 0, v[8:9]
	v_lshl_add_u64 v[146:147], v[0:1], 0, v[10:11]
	s_mov_b64 s[18:19], 0
	s_mov_b32 s15, 0
	v_mov_b32_e32 v0, 0
	v_mov_b32_e32 v1, v129
	v_mov_b32_e32 v2, v129
	v_mov_b32_e32 v3, v129
	v_mov_b32_e32 v4, 0
	v_mov_b32_e32 v5, v129
	v_mov_b32_e32 v6, v129
	v_mov_b32_e32 v7, v129
	v_mov_b32_e32 v8, 0
	v_mov_b32_e32 v9, v129
	v_mov_b32_e32 v10, v129
	v_mov_b32_e32 v11, v129
	v_mov_b32_e32 v12, 0
	v_mov_b32_e32 v14, v129
	v_mov_b32_e32 v15, v129
	v_mov_b32_e32 v16, 0
	v_mov_b32_e32 v17, v129
	v_mov_b32_e32 v18, v129
	v_mov_b32_e32 v19, v129
	v_mov_b32_e32 v20, 0
	v_mov_b32_e32 v21, v129
	v_mov_b32_e32 v22, v129
	v_mov_b32_e32 v23, v129
	v_mov_b32_e32 v24, 0
	v_mov_b32_e32 v25, v129
	v_mov_b32_e32 v26, v129
	v_mov_b32_e32 v27, v129
	v_mov_b32_e32 v28, 0
	v_mov_b32_e32 v29, v129
	v_mov_b32_e32 v30, v129
	v_mov_b32_e32 v31, v129
	v_mov_b32_e32 v32, 0
	v_mov_b32_e32 v33, v129
	v_mov_b32_e32 v34, v129
	v_mov_b32_e32 v35, v129
	v_mov_b32_e32 v36, 0
	v_mov_b32_e32 v37, v129
	v_mov_b32_e32 v38, v129
	v_mov_b32_e32 v39, v129
	v_mov_b32_e32 v40, 0
	v_mov_b32_e32 v41, v129
	v_mov_b32_e32 v42, v129
	v_mov_b32_e32 v43, v129
	v_mov_b32_e32 v44, 0
	v_mov_b32_e32 v45, v129
	v_mov_b32_e32 v46, v129
	v_mov_b32_e32 v47, v129
	v_mov_b32_e32 v48, 0
	v_mov_b32_e32 v49, v129
	v_mov_b32_e32 v50, v129
	v_mov_b32_e32 v51, v129
	v_mov_b32_e32 v52, 0
	v_mov_b32_e32 v53, v129
	v_mov_b32_e32 v54, v129
	v_mov_b32_e32 v55, v129
	v_mov_b32_e32 v56, 0
	v_mov_b32_e32 v57, v129
	v_mov_b32_e32 v58, v129
	v_mov_b32_e32 v59, v129
	v_mov_b32_e32 v60, 0
	v_mov_b32_e32 v61, v129
	v_mov_b32_e32 v62, v129
	v_mov_b32_e32 v63, v129
	v_mov_b32_e32 v64, 0
	v_mov_b32_e32 v65, v129
	v_mov_b32_e32 v66, v129
	v_mov_b32_e32 v67, v129
	v_mov_b32_e32 v68, 0
	v_mov_b32_e32 v69, v129
	v_mov_b32_e32 v70, v129
	v_mov_b32_e32 v71, v129
	v_mov_b32_e32 v72, 0
	v_mov_b32_e32 v73, v129
	v_mov_b32_e32 v74, v129
	v_mov_b32_e32 v75, v129
	v_mov_b32_e32 v76, 0
	v_mov_b32_e32 v77, v129
	v_mov_b32_e32 v78, v129
	v_mov_b32_e32 v79, v129
	v_mov_b32_e32 v80, 0
	v_mov_b32_e32 v81, v129
	v_mov_b32_e32 v82, v129
	v_mov_b32_e32 v83, v129
	v_mov_b32_e32 v84, 0
	v_mov_b32_e32 v85, v129
	v_mov_b32_e32 v86, v129
	v_mov_b32_e32 v87, v129
	v_mov_b32_e32 v88, 0
	v_mov_b32_e32 v89, v129
	v_mov_b32_e32 v90, v129
	v_mov_b32_e32 v91, v129
	v_mov_b32_e32 v92, 0
	v_mov_b32_e32 v93, v129
	v_mov_b32_e32 v94, v129
	v_mov_b32_e32 v95, v129
	v_mov_b32_e32 v96, 0
	v_mov_b32_e32 v97, v129
	v_mov_b32_e32 v98, v129
	v_mov_b32_e32 v99, v129
	v_mov_b32_e32 v100, 0
	v_mov_b32_e32 v101, v129
	v_mov_b32_e32 v102, v129
	v_mov_b32_e32 v103, v129
	v_mov_b32_e32 v104, 0
	v_mov_b32_e32 v105, v129
	v_mov_b32_e32 v106, v129
	v_mov_b32_e32 v107, v129
	v_mov_b32_e32 v108, 0
	v_mov_b32_e32 v109, v129
	v_mov_b32_e32 v110, v129
	v_mov_b32_e32 v111, v129
	v_mov_b32_e32 v112, 0
	v_mov_b32_e32 v113, v129
	v_mov_b32_e32 v114, v129
	v_mov_b32_e32 v115, v129
	v_mov_b32_e32 v116, 0
	v_mov_b32_e32 v117, v129
	v_mov_b32_e32 v118, v129
	v_mov_b32_e32 v119, v129
	v_mov_b32_e32 v120, 0
	v_mov_b32_e32 v121, v129
	v_mov_b32_e32 v122, v129
	v_mov_b32_e32 v123, v129
	v_mov_b32_e32 v124, 0
	v_mov_b32_e32 v125, v129
	v_mov_b32_e32 v126, v129
	v_mov_b32_e32 v127, v129
	s_waitcnt vmcnt(0) lgkmcnt(0)
	s_barrier
	v_readfirstlane_b32 s100, v149
	s_mov_b64 s[98:99], 0x80
	s_and_b32 s17, s15, 0x10000
	s_xor_b32 s43, s17, 0x10000
	s_add_i32 s17, s17, 0
	v_add3_u32 v128, s17, v150, v151
	v_add3_u32 v161, s17, v150, v152
	v_add3_u32 v194, s17, v154, v153
	v_add3_u32 v195, s17, v154, v155
	v_add3_u32 v196, s17, v154, v156
	v_add3_u32 v197, s17, v154, v157
	v_add3_u32 v198, s17, v154, v158
	v_add3_u32 v199, s17, v154, v159
	v_add3_u32 v200, s17, v154, v160
	ds_read_b128 v[178:181], v128 offset:32768
	ds_read_b128 v[162:165], v161
	ds_read_b128 v[166:169], v194
	ds_read_b128 v[170:173], v195
	ds_read_b128 v[174:177], v196
	ds_read_b128 v[182:185], v128 offset:34816
	ds_read_b128 v[186:189], v128 offset:36864
	ds_read_b128 v[190:193], v128 offset:38912
	s_add_i32 s101, s100, s43
	s_mov_b32 m0, s101
	s_nop 0
	global_load_lds_dwordx4 v[146:147], off
	s_add_i32 m0, s101, 0x8000
	s_nop 0
	global_load_lds_dwordx4 v[138:139], off
	s_add_i32 m0, s101, 0x2000
	s_nop 0
	global_load_lds_dwordx4 v[144:145], off
	s_add_i32 m0, s101, 0xa000
	s_nop 0
	global_load_lds_dwordx4 v[136:137], off
	s_add_i32 m0, s101, 0x4000
	s_nop 0
	global_load_lds_dwordx4 v[142:143], off
	s_add_i32 m0, s101, 0xc000
	s_nop 0
	global_load_lds_dwordx4 v[134:135], off
	s_add_i32 m0, s101, 0x6000
	s_nop 0
	global_load_lds_dwordx4 v[140:141], off
	s_add_i32 m0, s101, 0xe000
	s_nop 0
	global_load_lds_dwordx4 v[130:131], off
.LBB0_1040:
	s_and_b32 s17, s15, 0x10000
	s_xor_b32 s43, s17, 0x10000
	s_add_i32 s17, s17, 0
	s_waitcnt lgkmcnt(3)
	v_mfma_f32_16x16x32_bf16 v[108:111], v[178:181], v[162:165], v[108:111]
	v_mfma_f32_16x16x32_bf16 v[92:95], v[178:181], v[166:169], v[92:95]
	v_mfma_f32_16x16x32_bf16 v[76:79], v[178:181], v[170:173], v[76:79]
	v_mfma_f32_16x16x32_bf16 v[60:63], v[178:181], v[174:177], v[60:63]
	ds_read_b128 v[240:243], v197
	ds_read_b128 v[244:247], v198
	s_waitcnt lgkmcnt(4)
	v_mfma_f32_16x16x32_bf16 v[104:107], v[182:185], v[162:165], v[104:107]
	v_mfma_f32_16x16x32_bf16 v[88:91], v[182:185], v[166:169], v[88:91]
	v_mfma_f32_16x16x32_bf16 v[72:75], v[182:185], v[170:173], v[72:75]
	v_mfma_f32_16x16x32_bf16 v[56:59], v[182:185], v[174:177], v[56:59]
	ds_read_b128 v[248:251], v199
	ds_read_b128 v[252:255], v200
	s_waitcnt lgkmcnt(5)
	v_mfma_f32_16x16x32_bf16 v[100:103], v[186:189], v[162:165], v[100:103]
	v_mfma_f32_16x16x32_bf16 v[84:87], v[186:189], v[166:169], v[84:87]
	v_mfma_f32_16x16x32_bf16 v[68:71], v[186:189], v[170:173], v[68:71]
	v_mfma_f32_16x16x32_bf16 v[52:55], v[186:189], v[174:177], v[52:55]
	s_waitcnt lgkmcnt(4)
	v_mfma_f32_16x16x32_bf16 v[96:99], v[190:193], v[162:165], v[96:99]
	v_mfma_f32_16x16x32_bf16 v[80:83], v[190:193], v[166:169], v[80:83]
	v_mfma_f32_16x16x32_bf16 v[64:67], v[190:193], v[170:173], v[64:67]
	v_mfma_f32_16x16x32_bf16 v[48:51], v[190:193], v[174:177], v[48:51]
	ds_read_b128 v[162:165], v161 offset:1024
	ds_read_b128 v[166:169], v194 offset:1024
	ds_read_b128 v[170:173], v195 offset:1024
	ds_read_b128 v[174:177], v196 offset:1024
	s_waitcnt lgkmcnt(4)
	v_mfma_f32_16x16x32_bf16 v[44:47], v[178:181], v[240:243], v[44:47]
	v_mfma_f32_16x16x32_bf16 v[28:31], v[178:181], v[244:247], v[28:31]
	v_mfma_f32_16x16x32_bf16 v[12:15], v[178:181], v[248:251], v[12:15]
	v_mfma_f32_16x16x32_bf16 v[112:115], v[178:181], v[252:255], v[112:115]
	ds_read_b128 v[178:181], v128 offset:33792
	v_mfma_f32_16x16x32_bf16 v[40:43], v[182:185], v[240:243], v[40:43]
	v_mfma_f32_16x16x32_bf16 v[24:27], v[182:185], v[244:247], v[24:27]
	v_mfma_f32_16x16x32_bf16 v[8:11], v[182:185], v[248:251], v[8:11]
	v_mfma_f32_16x16x32_bf16 v[116:119], v[182:185], v[252:255], v[116:119]
	ds_read_b128 v[182:185], v128 offset:35840
	v_mfma_f32_16x16x32_bf16 v[36:39], v[186:189], v[240:243], v[36:39]
	v_mfma_f32_16x16x32_bf16 v[20:23], v[186:189], v[244:247], v[20:23]
	v_mfma_f32_16x16x32_bf16 v[4:7], v[186:189], v[248:251], v[4:7]
	v_mfma_f32_16x16x32_bf16 v[120:123], v[186:189], v[252:255], v[120:123]
	ds_read_b128 v[186:189], v128 offset:37888
	v_mfma_f32_16x16x32_bf16 v[32:35], v[190:193], v[240:243], v[32:35]
	v_mfma_f32_16x16x32_bf16 v[16:19], v[190:193], v[244:247], v[16:19]
	v_mfma_f32_16x16x32_bf16 v[0:3], v[190:193], v[248:251], v[0:3]
	v_mfma_f32_16x16x32_bf16 v[124:127], v[190:193], v[252:255], v[124:127]
	ds_read_b128 v[190:193], v128 offset:39936
	s_waitcnt lgkmcnt(3)
	v_mfma_f32_16x16x32_bf16 v[108:111], v[178:181], v[162:165], v[108:111]
	v_mfma_f32_16x16x32_bf16 v[92:95], v[178:181], v[166:169], v[92:95]
	v_mfma_f32_16x16x32_bf16 v[76:79], v[178:181], v[170:173], v[76:79]
	v_mfma_f32_16x16x32_bf16 v[60:63], v[178:181], v[174:177], v[60:63]
	ds_read_b128 v[240:243], v197 offset:1024
	ds_read_b128 v[244:247], v198 offset:1024
	s_waitcnt lgkmcnt(4)
	v_mfma_f32_16x16x32_bf16 v[104:107], v[182:185], v[162:165], v[104:107]
	v_mfma_f32_16x16x32_bf16 v[88:91], v[182:185], v[166:169], v[88:91]
	v_mfma_f32_16x16x32_bf16 v[72:75], v[182:185], v[170:173], v[72:75]
	v_mfma_f32_16x16x32_bf16 v[56:59], v[182:185], v[174:177], v[56:59]
	ds_read_b128 v[248:251], v199 offset:1024
	ds_read_b128 v[252:255], v200 offset:1024
	s_waitcnt lgkmcnt(5)
	v_mfma_f32_16x16x32_bf16 v[100:103], v[186:189], v[162:165], v[100:103]
	v_mfma_f32_16x16x32_bf16 v[84:87], v[186:189], v[166:169], v[84:87]
	v_mfma_f32_16x16x32_bf16 v[68:71], v[186:189], v[170:173], v[68:71]
	v_mfma_f32_16x16x32_bf16 v[52:55], v[186:189], v[174:177], v[52:55]
	s_waitcnt lgkmcnt(4)
	v_mfma_f32_16x16x32_bf16 v[96:99], v[190:193], v[162:165], v[96:99]
	v_mfma_f32_16x16x32_bf16 v[80:83], v[190:193], v[166:169], v[80:83]
	v_mfma_f32_16x16x32_bf16 v[64:67], v[190:193], v[170:173], v[64:67]
	v_mfma_f32_16x16x32_bf16 v[48:51], v[190:193], v[174:177], v[48:51]
	s_waitcnt vmcnt(0) lgkmcnt(0)
	s_barrier
	s_add_i32 s101, s100, s17
	v_mfma_f32_16x16x32_bf16 v[44:47], v[178:181], v[240:243], v[44:47]
	v_mfma_f32_16x16x32_bf16 v[28:31], v[178:181], v[244:247], v[28:31]
	v_mfma_f32_16x16x32_bf16 v[12:15], v[178:181], v[248:251], v[12:15]
	v_mfma_f32_16x16x32_bf16 v[112:115], v[178:181], v[252:255], v[112:115]
	v_add3_u32 v128, s43, v150, v151
	ds_read_b128 v[178:181], v128 offset:32768
	v_add3_u32 v161, s43, v150, v152
	v_add3_u32 v194, s43, v154, v153
	v_add3_u32 v195, s43, v154, v155
	v_add3_u32 v196, s43, v154, v156
	ds_read_b128 v[162:165], v161
	ds_read_b128 v[166:169], v194
	ds_read_b128 v[170:173], v195
	ds_read_b128 v[174:177], v196
	s_cmpk_eq_i32 s18, 0x700
	s_cbranch_scc1 .Lpk_1040_0
	s_mov_b32 m0, s101
	v_lshl_add_u64 v[146:147], v[146:147], 0, s[98:99]
	global_load_lds_dwordx4 v[146:147], off

.Lpk_1040_1:
	v_mfma_f32_16x16x32_bf16 v[40:43], v[182:185], v[240:243], v[40:43]
	v_mfma_f32_16x16x32_bf16 v[24:27], v[182:185], v[244:247], v[24:27]
	v_mfma_f32_16x16x32_bf16 v[8:11], v[182:185], v[248:251], v[8:11]
	v_mfma_f32_16x16x32_bf16 v[116:119], v[182:185], v[252:255], v[116:119]
	ds_read_b128 v[182:185], v128 offset:34816
	v_add3_u32 v197, s43, v154, v157
	v_add3_u32 v198, s43, v154, v158
	v_add3_u32 v199, s43, v154, v159
	v_add3_u32 v200, s43, v154, v160
	s_cmpk_eq_i32 s18, 0x700
	s_cbranch_scc1 .Lpk_1040_2
	s_add_i32 m0, s101, 0x2000
	v_lshl_add_u64 v[144:145], v[144:145], 0, s[98:99]
	global_load_lds_dwordx4 v[144:145], off

.Lpk_1040_7:
	s_add_i32 s15, s15, 0x10000
	s_add_u32 s18, s18, 0x80
	s_addc_u32 s19, s19, 0
	s_cmpk_lg_i32 s18, 0x780
	s_cbranch_scc1 .LBB0_1040
	s_waitcnt lgkmcnt(0)
	v_add3_u32 v128, s24, v154, v160
	v_add3_u32 v130, s24, v154, v159
	v_add3_u32 v131, s24, v154, v158
	v_add3_u32 v146, s24, v154, v157
	v_add3_u32 v147, s24, v154, v156
	v_add3_u32 v149, s24, v154, v155
	v_add3_u32 v186, s24, v154, v153
	v_add3_u32 v187, s24, v150, v152
	v_add3_u32 v188, s25, v150, v151
	ds_read_b128 v[134:137], v128
	ds_read_b128 v[138:141], v130
	ds_read_b128 v[142:145], v131
	ds_read_b128 v[158:161], v146
	ds_read_b128 v[162:165], v147
	ds_read_b128 v[166:169], v149
	ds_read_b128 v[154:157], v186
	ds_read_b128 v[170:173], v187
	ds_read_b128 v[178:181], v188 offset:4096
	s_waitcnt lgkmcnt(0)
	v_mfma_f32_16x16x32_bf16 v[4:7], v[178:181], v[138:141], v[4:7]
	ds_read_b128 v[174:177], v188 offset:2048
	s_waitcnt lgkmcnt(0)
	v_mfma_f32_16x16x32_bf16 v[8:11], v[174:177], v[138:141], v[8:11]
	ds_read_b128 v[150:153], v188
	s_waitcnt lgkmcnt(0)
	v_mfma_f32_16x16x32_bf16 v[12:15], v[150:153], v[138:141], v[12:15]
	v_mfma_f32_16x16x32_bf16 v[112:115], v[150:153], v[134:137], v[112:115]
	v_mfma_f32_16x16x32_bf16 v[108:111], v[150:153], v[170:173], v[108:111]
	v_mfma_f32_16x16x32_bf16 v[92:95], v[150:153], v[154:157], v[92:95]
	v_mfma_f32_16x16x32_bf16 v[76:79], v[150:153], v[166:169], v[76:79]
	v_mfma_f32_16x16x32_bf16 v[116:119], v[174:177], v[134:137], v[116:119]
	v_mfma_f32_16x16x32_bf16 v[104:107], v[174:177], v[170:173], v[104:107]
	v_mfma_f32_16x16x32_bf16 v[88:91], v[174:177], v[154:157], v[88:91]
	v_mfma_f32_16x16x32_bf16 v[72:75], v[174:177], v[166:169], v[72:75]
	v_mfma_f32_16x16x32_bf16 v[120:123], v[178:181], v[134:137], v[120:123]
	v_mfma_f32_16x16x32_bf16 v[100:103], v[178:181], v[170:173], v[100:103]
	v_mfma_f32_16x16x32_bf16 v[84:87], v[178:181], v[154:157], v[84:87]
	v_mfma_f32_16x16x32_bf16 v[68:71], v[178:181], v[166:169], v[68:71]
	ds_read_b128 v[182:185], v188 offset:6144
	s_waitcnt lgkmcnt(0)
	v_mfma_f32_16x16x32_bf16 v[124:127], v[182:185], v[134:137], v[124:127]
	v_mfma_f32_16x16x32_bf16 v[96:99], v[182:185], v[170:173], v[96:99]
	v_mfma_f32_16x16x32_bf16 v[80:83], v[182:185], v[154:157], v[80:83]
	v_mfma_f32_16x16x32_bf16 v[64:67], v[182:185], v[166:169], v[64:67]
	v_mfma_f32_16x16x32_bf16 v[48:51], v[182:185], v[162:165], v[48:51]
	v_mfma_f32_16x16x32_bf16 v[52:55], v[178:181], v[162:165], v[52:55]
	v_mfma_f32_16x16x32_bf16 v[56:59], v[174:177], v[162:165], v[56:59]
	v_mfma_f32_16x16x32_bf16 v[60:63], v[150:153], v[162:165], v[60:63]
	v_mfma_f32_16x16x32_bf16 v[44:47], v[150:153], v[158:161], v[44:47]
	v_mfma_f32_16x16x32_bf16 v[40:43], v[174:177], v[158:161], v[40:43]
	v_mfma_f32_16x16x32_bf16 v[36:39], v[178:181], v[158:161], v[36:39]
	v_mfma_f32_16x16x32_bf16 v[32:35], v[182:185], v[158:161], v[32:35]
	v_mfma_f32_16x16x32_bf16 v[28:31], v[150:153], v[142:145], v[28:31]
	v_mfma_f32_16x16x32_bf16 v[24:27], v[174:177], v[142:145], v[24:27]
	v_mfma_f32_16x16x32_bf16 v[20:23], v[178:181], v[142:145], v[20:23]
	v_mfma_f32_16x16x32_bf16 v[16:19], v[182:185], v[142:145], v[16:19]
	v_mfma_f32_16x16x32_bf16 v[0:3], v[182:185], v[138:141], v[0:3]
	ds_read_b128 v[134:137], v188 offset:1024
	ds_read_b128 v[138:141], v188 offset:3072
	ds_read_b128 v[142:145], v188 offset:5120
	ds_read_b128 v[154:157], v188 offset:7168
	ds_read_b128 v[150:153], v187 offset:1024
	ds_read_b128 v[158:161], v186 offset:1024
	ds_read_b128 v[162:165], v149 offset:1024
	ds_read_b128 v[166:169], v147 offset:1024
	s_waitcnt lgkmcnt(3)
	v_mfma_f32_16x16x32_bf16 v[108:111], v[134:137], v[150:153], v[108:111]
	v_mfma_f32_16x16x32_bf16 v[104:107], v[138:141], v[150:153], v[104:107]
	v_mfma_f32_16x16x32_bf16 v[100:103], v[142:145], v[150:153], v[100:103]
	v_mfma_f32_16x16x32_bf16 v[96:99], v[154:157], v[150:153], v[96:99]
	ds_read_b128 v[150:153], v146 offset:1024
	s_waitcnt lgkmcnt(3)
	v_mfma_f32_16x16x32_bf16 v[92:95], v[134:137], v[158:161], v[92:95]
	v_mfma_f32_16x16x32_bf16 v[88:91], v[138:141], v[158:161], v[88:91]
	v_mfma_f32_16x16x32_bf16 v[84:87], v[142:145], v[158:161], v[84:87]
	v_mfma_f32_16x16x32_bf16 v[80:83], v[154:157], v[158:161], v[80:83]
	ds_read_b128 v[158:161], v131 offset:1024
	s_waitcnt lgkmcnt(3)
	v_mfma_f32_16x16x32_bf16 v[76:79], v[134:137], v[162:165], v[76:79]
	v_mfma_f32_16x16x32_bf16 v[72:75], v[138:141], v[162:165], v[72:75]
	v_mfma_f32_16x16x32_bf16 v[68:71], v[142:145], v[162:165], v[68:71]
	v_mfma_f32_16x16x32_bf16 v[64:67], v[154:157], v[162:165], v[64:67]
	ds_read_b128 v[162:165], v130 offset:1024
	s_waitcnt lgkmcnt(3)
	v_mfma_f32_16x16x32_bf16 v[60:63], v[134:137], v[166:169], v[60:63]
	v_mfma_f32_16x16x32_bf16 v[56:59], v[138:141], v[166:169], v[56:59]
	v_mfma_f32_16x16x32_bf16 v[52:55], v[142:145], v[166:169], v[52:55]
	v_mfma_f32_16x16x32_bf16 v[48:51], v[154:157], v[166:169], v[48:51]
	ds_read_b128 v[166:169], v128 offset:1024
	s_waitcnt lgkmcnt(3)
	v_mfma_f32_16x16x32_bf16 v[44:47], v[134:137], v[150:153], v[44:47]
	v_mfma_f32_16x16x32_bf16 v[40:43], v[138:141], v[150:153], v[40:43]
	v_mfma_f32_16x16x32_bf16 v[36:39], v[142:145], v[150:153], v[36:39]
	v_mfma_f32_16x16x32_bf16 v[32:35], v[154:157], v[150:153], v[32:35]
	s_waitcnt lgkmcnt(2)
	v_mfma_f32_16x16x32_bf16 v[28:31], v[134:137], v[158:161], v[28:31]
	v_mfma_f32_16x16x32_bf16 v[24:27], v[138:141], v[158:161], v[24:27]
	v_mfma_f32_16x16x32_bf16 v[20:23], v[142:145], v[158:161], v[20:23]
	v_mfma_f32_16x16x32_bf16 v[16:19], v[154:157], v[158:161], v[16:19]
	s_waitcnt lgkmcnt(1)
	v_mfma_f32_16x16x32_bf16 v[12:15], v[134:137], v[162:165], v[12:15]
	v_mfma_f32_16x16x32_bf16 v[8:11], v[138:141], v[162:165], v[8:11]
	v_mfma_f32_16x16x32_bf16 v[4:7], v[142:145], v[162:165], v[4:7]
	v_mfma_f32_16x16x32_bf16 v[0:3], v[154:157], v[162:165], v[0:3]
	s_waitcnt lgkmcnt(0)
	v_mfma_f32_16x16x32_bf16 v[112:115], v[134:137], v[166:169], v[112:115]
	v_mfma_f32_16x16x32_bf16 v[116:119], v[138:141], v[166:169], v[116:119]
	v_mfma_f32_16x16x32_bf16 v[120:123], v[142:145], v[166:169], v[120:123]
	v_mfma_f32_16x16x32_bf16 v[124:127], v[154:157], v[166:169], v[124:127]
	v_mov_b32_e32 v128, s20
	s_waitcnt vmcnt(0)
	s_barrier
	ds_read_b64 v[130:131], v128
	v_ashrrev_i32_e32 v128, 1, v148
	v_and_b32_e32 v128, 0xffffff80, v128
	v_add_u32_e32 v128, s16, v128
	s_ashr_i32 s15, s14, 31
	s_waitcnt lgkmcnt(0)
	v_mad_i64_i32 v[130:131], s[16:17], v128, s26, v[130:131]
	v_and_b32_e32 v128, 0xc0, v148
	v_lshrrev_b32_e32 v135, 6, v148
	v_lshl_add_u64 v[130:131], s[14:15], 1, v[130:131]
	v_lshlrev_b32_e32 v128, 1, v128
	v_lshl_add_u64 v[130:131], v[130:131], 0, v[128:129]
	v_mul_lo_u32 v128, v135, s27
	v_add_u32_e32 v135, s24, v128
	v_lshrrev_b32_e32 v128, 1, v148
	v_and_b32_e32 v136, 24, v128
	v_lshlrev_b32_e32 v128, 4, v148
	v_bfe_u32 v137, v148, 3, 3
	v_and_b32_e32 v134, 15, v148
	v_and_b32_e32 v128, 0x70, v128
	v_mul_u32_u24_e32 v138, 0x90, v137
	v_lshl_add_u64 v[130:131], v[130:131], 0, v[128:129]
	v_add3_u32 v138, v135, v128, v138
	v_mul_u32_u24_e32 v128, 0x90, v134
	v_add3_u32 v134, v135, v136, v128
	v_cvt_pk_bf16_f32 v108, v108, v109
	v_cvt_pk_bf16_f32 v109, v110, v111
	v_cvt_pk_bf16_f32 v104, v104, v105
	v_cvt_pk_bf16_f32 v105, v106, v107
	v_cvt_pk_bf16_f32 v100, v100, v101
	v_cvt_pk_bf16_f32 v101, v102, v103
	v_cvt_pk_bf16_f32 v96, v96, v97
	v_cvt_pk_bf16_f32 v97, v98, v99
	v_cvt_pk_bf16_f32 v92, v92, v93
	v_cvt_pk_bf16_f32 v93, v94, v95
	v_cvt_pk_bf16_f32 v88, v88, v89
	v_cvt_pk_bf16_f32 v89, v90, v91
	v_cvt_pk_bf16_f32 v84, v84, v85
	v_cvt_pk_bf16_f32 v85, v86, v87
	v_cvt_pk_bf16_f32 v80, v80, v81
	v_cvt_pk_bf16_f32 v81, v82, v83
	v_cvt_pk_bf16_f32 v76, v76, v77
	v_cvt_pk_bf16_f32 v77, v78, v79
	v_cvt_pk_bf16_f32 v72, v72, v73
	v_cvt_pk_bf16_f32 v73, v74, v75
	v_cvt_pk_bf16_f32 v68, v68, v69
	v_cvt_pk_bf16_f32 v69, v70, v71
	v_cvt_pk_bf16_f32 v64, v64, v65
	v_cvt_pk_bf16_f32 v65, v66, v67
	v_cvt_pk_bf16_f32 v60, v60, v61
	v_cvt_pk_bf16_f32 v61, v62, v63
	v_cvt_pk_bf16_f32 v56, v56, v57
	v_cvt_pk_bf16_f32 v57, v58, v59
	v_cvt_pk_bf16_f32 v52, v52, v53
	v_cvt_pk_bf16_f32 v53, v54, v55
	v_cvt_pk_bf16_f32 v48, v48, v49
	v_cvt_pk_bf16_f32 v49, v50, v51
	ds_write_b64 v134, v[108:109]
	ds_write_b64 v134, v[104:105] offset:32
	ds_write_b64 v134, v[100:101] offset:64
	ds_write_b64 v134, v[96:97] offset:96
	ds_write_b64 v134, v[92:93] offset:2304
	ds_write_b64 v134, v[88:89] offset:2336
	ds_write_b64 v134, v[84:85] offset:2368
	ds_write_b64 v134, v[80:81] offset:2400
	ds_write_b64 v134, v[76:77] offset:4608
	ds_write_b64 v134, v[72:73] offset:4640
	ds_write_b64 v134, v[68:69] offset:4672
	ds_write_b64 v134, v[64:65] offset:4704
	ds_write_b64 v134, v[60:61] offset:6912
	ds_write_b64 v134, v[56:57] offset:6944
	ds_write_b64 v134, v[52:53] offset:6976
	ds_write_b64 v134, v[48:49] offset:7008
	ds_read_b128 v[48:51], v138
	v_mul_u32_u24_e32 v54, 0xa00, v137
	v_lshl_add_u64 v[52:53], v[130:131], 0, s[12:13]
	v_lshlrev_b32_e32 v128, 1, v54
	v_lshl_add_u64 v[54:55], v[52:53], 0, v[128:129]
	s_waitcnt lgkmcnt(0)
	flat_store_dwordx4 v[54:55], v[48:51] nt
	ds_read_b128 v[48:51], v138 offset:1152
	v_add_co_u32_e32 v56, vcc, s22, v54
	v_cvt_pk_bf16_f32 v0, v0, v1
	s_nop 0
	v_addc_co_u32_e32 v57, vcc, 0, v55, vcc
	s_waitcnt lgkmcnt(0)
	flat_store_dwordx4 v[56:57], v[48:51] nt
	ds_read_b128 v[48:51], v138 offset:2304
	v_add_co_u32_e32 v56, vcc, s28, v54
	v_cvt_pk_bf16_f32 v1, v2, v3
	s_nop 0
	v_addc_co_u32_e32 v57, vcc, 0, v55, vcc
	s_waitcnt lgkmcnt(0)
	flat_store_dwordx4 v[56:57], v[48:51] nt
	ds_read_b128 v[48:51], v138 offset:3456
	v_add_co_u32_e32 v56, vcc, s29, v54
	v_cvt_pk_bf16_f32 v44, v44, v45
	s_nop 0
	v_addc_co_u32_e32 v57, vcc, 0, v55, vcc
	s_waitcnt lgkmcnt(0)
	flat_store_dwordx4 v[56:57], v[48:51] nt
	ds_read_b128 v[48:51], v138 offset:4608
	v_add_u32_e32 v56, 0x28000, v128
	v_mov_b32_e32 v57, v129
	v_lshl_add_u64 v[56:57], v[52:53], 0, v[56:57]
	v_cvt_pk_bf16_f32 v45, v46, v47
	s_waitcnt lgkmcnt(0)
	flat_store_dwordx4 v[56:57], v[48:51] nt
	ds_read_b128 v[48:51], v138 offset:5760
	v_add_u32_e32 v56, 0x32000, v128
	v_mov_b32_e32 v57, v129
	v_lshl_add_u64 v[56:57], v[52:53], 0, v[56:57]
	v_cvt_pk_bf16_f32 v40, v40, v41
	s_waitcnt lgkmcnt(0)
	flat_store_dwordx4 v[56:57], v[48:51] nt
	ds_read_b128 v[48:51], v138 offset:6912
	v_add_u32_e32 v56, 0x3c000, v128
	v_mov_b32_e32 v57, v129
	v_lshl_add_u64 v[56:57], v[52:53], 0, v[56:57]
	v_add_u32_e32 v128, 0x46000, v128
	s_waitcnt lgkmcnt(0)
	flat_store_dwordx4 v[56:57], v[48:51] nt
	ds_read_b128 v[48:51], v138 offset:8064
	v_lshl_add_u64 v[52:53], v[52:53], 0, v[128:129]
	v_cvt_pk_bf16_f32 v41, v42, v43
	v_cvt_pk_bf16_f32 v36, v36, v37
	v_cvt_pk_bf16_f32 v37, v38, v39
	s_waitcnt lgkmcnt(0)
	flat_store_dwordx4 v[52:53], v[48:51] nt
	ds_write_b64 v134, v[0:1] offset:4704
	v_cvt_pk_bf16_f32 v0, v112, v113
	v_cvt_pk_bf16_f32 v1, v114, v115
	ds_write_b64 v134, v[0:1] offset:6912
	v_cvt_pk_bf16_f32 v0, v116, v117
	v_cvt_pk_bf16_f32 v1, v118, v119
	ds_write_b64 v134, v[0:1] offset:6944
	v_cvt_pk_bf16_f32 v0, v120, v121
	v_cvt_pk_bf16_f32 v1, v122, v123
	v_cvt_pk_bf16_f32 v32, v32, v33
	v_cvt_pk_bf16_f32 v33, v34, v35
	v_cvt_pk_bf16_f32 v28, v28, v29
	v_cvt_pk_bf16_f32 v29, v30, v31
	v_cvt_pk_bf16_f32 v24, v24, v25
	v_cvt_pk_bf16_f32 v25, v26, v27
	v_cvt_pk_bf16_f32 v20, v20, v21
	v_cvt_pk_bf16_f32 v21, v22, v23
	v_cvt_pk_bf16_f32 v16, v16, v17
	v_cvt_pk_bf16_f32 v17, v18, v19
	v_cvt_pk_bf16_f32 v12, v12, v13
	v_cvt_pk_bf16_f32 v13, v14, v15
	v_cvt_pk_bf16_f32 v8, v8, v9
	v_cvt_pk_bf16_f32 v9, v10, v11
	v_cvt_pk_bf16_f32 v4, v4, v5
	v_cvt_pk_bf16_f32 v5, v6, v7
	ds_write_b64 v134, v[0:1] offset:6976
	v_cvt_pk_bf16_f32 v0, v124, v125
	v_cvt_pk_bf16_f32 v1, v126, v127
	ds_write_b64 v134, v[44:45]
	ds_write_b64 v134, v[40:41] offset:32
	ds_write_b64 v134, v[36:37] offset:64
	ds_write_b64 v134, v[32:33] offset:96
	ds_write_b64 v134, v[28:29] offset:2304
	ds_write_b64 v134, v[24:25] offset:2336
	ds_write_b64 v134, v[20:21] offset:2368
	ds_write_b64 v134, v[16:17] offset:2400
	ds_write_b64 v134, v[12:13] offset:4608
	ds_write_b64 v134, v[8:9] offset:4640
	ds_write_b64 v134, v[4:5] offset:4672
	ds_write_b64 v134, v[0:1] offset:7008
	ds_read_b128 v[0:3], v138
	v_add_co_u32_e32 v4, vcc, s30, v54
	s_add_i32 s42, s42, s40
	s_nop 0
	v_addc_co_u32_e32 v5, vcc, 0, v55, vcc
	s_waitcnt lgkmcnt(0)
	flat_store_dwordx4 v[4:5], v[0:3] nt
	ds_read_b128 v[0:3], v138 offset:1152
	v_add_co_u32_e32 v4, vcc, s31, v54
	s_cmpk_gt_i32 s42, 0x4ff
	s_nop 0
	v_addc_co_u32_e32 v5, vcc, 0, v55, vcc
	s_waitcnt lgkmcnt(0)
	flat_store_dwordx4 v[4:5], v[0:3] nt
	ds_read_b128 v[0:3], v138 offset:2304
	v_add_co_u32_e32 v4, vcc, s34, v54
	s_nop 1
	v_addc_co_u32_e32 v5, vcc, 0, v55, vcc
	s_waitcnt lgkmcnt(0)
	flat_store_dwordx4 v[4:5], v[0:3] nt
	ds_read_b128 v[0:3], v138 offset:3456
	v_add_co_u32_e32 v4, vcc, s35, v54
	s_nop 1
	v_addc_co_u32_e32 v5, vcc, 0, v55, vcc
	s_waitcnt lgkmcnt(0)
	flat_store_dwordx4 v[4:5], v[0:3] nt
	ds_read_b128 v[0:3], v138 offset:4608
	v_add_co_u32_e32 v4, vcc, s38, v54
	s_nop 1
	v_addc_co_u32_e32 v5, vcc, 0, v55, vcc
	s_waitcnt lgkmcnt(0)
	flat_store_dwordx4 v[4:5], v[0:3] nt
	ds_read_b128 v[0:3], v138 offset:5760
	v_add_co_u32_e32 v4, vcc, s39, v54
	s_nop 1
	v_addc_co_u32_e32 v5, vcc, 0, v55, vcc
	s_waitcnt lgkmcnt(0)
	flat_store_dwordx4 v[4:5], v[0:3] nt
	ds_read_b128 v[0:3], v138 offset:6912
	v_add_co_u32_e32 v4, vcc, 0x8c000, v54
	s_nop 1
	v_addc_co_u32_e32 v5, vcc, 0, v55, vcc
	s_waitcnt lgkmcnt(0)
	flat_store_dwordx4 v[4:5], v[0:3] nt
	ds_read_b128 v[0:3], v138 offset:8064
	v_add_co_u32_e32 v4, vcc, 0x96000, v54
	s_nop 1
	v_addc_co_u32_e32 v5, vcc, 0, v55, vcc
	s_waitcnt lgkmcnt(0)
	flat_store_dwordx4 v[4:5], v[0:3] nt
	s_cbranch_scc0 .LBB0_1039

.LBB0_1137:
	s_ashr_i32 s10, s23, 31
	s_lshr_b32 s10, s10, 26
	s_add_i32 s10, s23, s10
	s_ashr_i32 s11, s10, 6
	s_and_b32 s10, s10, 0xffc0
	s_sub_i32 s10, s23, s10
	s_bfe_i32 s12, s10, 0x80000
	s_bfe_u32 s12, s12, 0x4000b
	v_mov_b32_e32 v148, v132
	v_mov_b32_e32 v18, v132
	s_add_i32 s12, s10, s12
	ds_read_b64 v[0:1], v133
	s_lshl_b32 s25, s11, 4
	v_lshlrev_b32_e32 v9, 4, v18
	v_and_b32_e32 v8, 32, v18
	s_and_b32 s11, s12, 0xf0
	v_bfe_u32 v19, v18, 2, 4
	v_lshrrev_b32_e32 v10, 1, v18
	v_bitop3_b32 v8, v9, v8, 48 bitop3:0x6c
	v_ashrrev_i32_e32 v22, 3, v18
	s_sub_i32 s10, s10, s11
	v_and_b32_e32 v20, 32, v10
	v_lshrrev_b32_e32 v21, 1, v8
	v_and_or_b32 v8, v22, s14, v19
	s_bfe_i32 s13, s12, 0x80000
	s_sext_i32_i8 s10, s10
	v_or_b32_e32 v12, v21, v20
	v_mul_u32_u24_e32 v8, 0xb00, v8
	s_sext_i32_i16 s13, s13
	s_add_i32 s25, s25, s10
	v_and_b32_e32 v11, 0xfffffc00, v9
	v_or_b32_e32 v128, v12, v8
	v_add_u32_e32 v8, 0x2000, v9
	v_add_u32_e32 v10, 0x4000, v9
	v_add_u32_e32 v9, 0x6000, v9
	s_ashr_i32 s26, s13, 4
	s_lshl_b32 s24, s25, 8
	v_ashrrev_i32_e32 v23, 7, v8
	v_ashrrev_i32_e32 v24, 7, v10
	v_ashrrev_i32_e32 v25, 7, v9
	s_lshl_b32 s10, s26, 8
	s_mul_i32 s12, s25, 0x160000
	s_mul_hi_i32 s13, s24, 0x1600
	v_and_or_b32 v8, v23, s14, v19
	v_and_or_b32 v10, v24, s14, v19
	v_and_or_b32 v9, v25, s14, v19
	s_waitcnt lgkmcnt(0)
	v_lshl_add_u64 v[2:3], v[0:1], 0, s[12:13]
	s_mul_i32 s12, s26, 0x160000
	s_mul_hi_i32 s13, s10, 0x1600
	v_mul_u32_u24_e32 v8, 0xb00, v8
	v_mul_u32_u24_e32 v10, 0xb00, v10
	v_mul_u32_u24_e32 v9, 0xb00, v9
	v_add_u32_e32 v149, 0, v11
	v_lshl_add_u64 v[4:5], v[2:3], 0, s[0:1]
	v_lshl_add_u64 v[0:1], v[0:1], 0, s[12:13]
	v_or_b32_e32 v8, v8, v12
	v_or_b32_e32 v10, v10, v12
	v_or_b32_e32 v12, v9, v12
	v_add_u32_e32 v9, 0x8000, v149
	v_lshlrev_b64 v[14:15], 1, v[128:129]
	v_readfirstlane_b32 s12, v149
	v_lshl_add_u64 v[6:7], v[0:1], 0, s[4:5]
	v_lshl_add_u64 v[16:17], v[4:5], 0, v[14:15]
	s_mov_b32 m0, s12
	v_readfirstlane_b32 s12, v9
	v_mov_b32_e32 v9, v129
	v_add_u32_e32 v11, 0x2000, v149
	global_load_lds_dwordx4 v[16:17], off
	v_lshl_add_u64 v[14:15], v[6:7], 0, v[14:15]
	s_mov_b32 m0, s12
	v_lshlrev_b64 v[8:9], 1, v[8:9]
	v_readfirstlane_b32 s12, v11
	v_add_u32_e32 v11, 0xa000, v149
	global_load_lds_dwordx4 v[14:15], off
	v_lshl_add_u64 v[14:15], v[4:5], 0, v[8:9]
	s_mov_b32 m0, s12
	v_readfirstlane_b32 s12, v11
	global_load_lds_dwordx4 v[14:15], off
	v_lshl_add_u64 v[8:9], v[6:7], 0, v[8:9]
	s_mov_b32 m0, s12
	v_mov_b32_e32 v11, v129
	v_add_u32_e32 v13, 0x4000, v149
	global_load_lds_dwordx4 v[8:9], off
	v_lshlrev_b64 v[8:9], 1, v[10:11]
	v_readfirstlane_b32 s12, v13
	v_lshl_add_u64 v[10:11], v[4:5], 0, v[8:9]
	s_mov_b32 m0, s12
	v_lshl_add_u64 v[8:9], v[6:7], 0, v[8:9]
	global_load_lds_dwordx4 v[10:11], off
	v_add_u32_e32 v10, 0xc000, v149
	v_mov_b32_e32 v13, v129
	v_readfirstlane_b32 s12, v10
	s_mov_b32 m0, s12
	v_add_u32_e32 v10, 0x6000, v149
	global_load_lds_dwordx4 v[8:9], off
	v_lshlrev_b64 v[8:9], 1, v[12:13]
	v_readfirstlane_b32 s12, v10
	v_lshl_add_u64 v[4:5], v[4:5], 0, v[8:9]
	s_mov_b32 m0, s12
	v_and_b32_e32 v26, 15, v18
	global_load_lds_dwordx4 v[4:5], off
	v_lshl_add_u64 v[4:5], v[6:7], 0, v[8:9]
	v_add_u32_e32 v6, 0xe000, v149
	v_lshrrev_b32_e32 v8, 4, v23
	v_readfirstlane_b32 s12, v6
	s_mov_b32 m0, s12
	v_lshlrev_b32_e32 v6, 2, v18
	global_load_lds_dwordx4 v[4:5], off
	v_and_b32_e32 v4, 48, v18
	v_lshlrev_b32_e32 v5, 6, v26
	v_and_b32_e32 v6, 32, v6
	v_bitop3_b32 v150, v5, v6, v4 bitop3:0x36
	v_lshlrev_b32_e32 v5, 7, v18
	v_and_b32_e32 v151, 0x6000, v5
	v_lshlrev_b32_e32 v5, 6, v18
	v_and_b32_e32 v152, 0xffffc000, v5
	v_and_b32_e32 v5, 0x3c0, v5
	v_bitop3_b32 v154, v5, v6, v4 bitop3:0x36
	v_lshrrev_b32_e32 v4, 4, v25
	v_mul_lo_u32 v4, v4, s16
	v_lshrrev_b32_e32 v6, 4, v24
	v_or_b32_e32 v4, v21, v4
	v_mul_lo_u32 v6, v6, s16
	v_mad_u32_u24 v4, v19, s15, v4
	v_or_b32_e32 v6, v21, v6
	v_mul_lo_u32 v8, v8, s16
	v_lshrrev_b32_e32 v10, 4, v22
	v_or_b32_e32 v128, v4, v20
	v_mad_u32_u24 v6, v19, s15, v6
	v_or_b32_e32 v8, v21, v8
	v_mul_lo_u32 v10, v10, s16
	v_lshlrev_b64 v[4:5], 1, v[128:129]
	v_or_b32_e32 v128, v6, v20
	v_mad_u32_u24 v8, v19, s15, v8
	v_or_b32_e32 v10, v21, v10
	v_lshlrev_b64 v[6:7], 1, v[128:129]
	v_or_b32_e32 v128, v8, v20
	v_mad_u32_u24 v10, v19, s15, v10
	v_lshlrev_b64 v[8:9], 1, v[128:129]
	v_or_b32_e32 v128, v10, v20
	s_waitcnt vmcnt(0)
	v_lshl_add_u64 v[0:1], v[0:1], 0, s[6:7]
	v_lshlrev_b64 v[10:11], 1, v[128:129]
	v_lshl_add_u64 v[130:131], v[0:1], 0, v[4:5]
	v_lshl_add_u64 v[134:135], v[0:1], 0, v[6:7]
	v_lshl_add_u64 v[136:137], v[0:1], 0, v[8:9]
	v_lshl_add_u64 v[138:139], v[0:1], 0, v[10:11]
	v_lshl_add_u64 v[0:1], v[2:3], 0, s[8:9]
	s_ashr_i32 s11, s10, 31
	v_or_b32_e32 v153, 0x800, v152
	v_or_b32_e32 v155, 0x1000, v152
	v_or_b32_e32 v156, 0x1800, v152
	v_or_b32_e32 v157, 0x2000, v152
	v_or_b32_e32 v158, 0x2800, v152
	v_or_b32_e32 v159, 0x3000, v152
	v_or_b32_e32 v160, 0x3800, v152
	v_lshl_add_u64 v[140:141], v[0:1], 0, v[4:5]
	v_lshl_add_u64 v[142:143], v[0:1], 0, v[6:7]
	v_lshl_add_u64 v[144:145], v[0:1], 0, v[8:9]
	v_lshl_add_u64 v[146:147], v[0:1], 0, v[10:11]
	s_mov_b64 s[12:13], 0
	s_mov_b32 s26, 0
	v_mov_b32_e32 v12, 0
	v_mov_b32_e32 v14, v129
	v_mov_b32_e32 v15, v129
	v_mov_b32_e32 v20, 0
	v_mov_b32_e32 v21, v129
	v_mov_b32_e32 v22, v129
	v_mov_b32_e32 v23, v129
	v_mov_b32_e32 v28, 0
	v_mov_b32_e32 v29, v129
	v_mov_b32_e32 v30, v129
	v_mov_b32_e32 v31, v129
	v_mov_b32_e32 v36, 0
	v_mov_b32_e32 v37, v129
	v_mov_b32_e32 v38, v129
	v_mov_b32_e32 v39, v129
	v_mov_b32_e32 v0, 0
	v_mov_b32_e32 v1, v129
	v_mov_b32_e32 v2, v129
	v_mov_b32_e32 v3, v129
	v_mov_b32_e32 v4, 0
	v_mov_b32_e32 v5, v129
	v_mov_b32_e32 v6, v129
	v_mov_b32_e32 v7, v129
	v_mov_b32_e32 v8, 0
	v_mov_b32_e32 v9, v129
	v_mov_b32_e32 v10, v129
	v_mov_b32_e32 v11, v129
	v_mov_b32_e32 v16, 0
	v_mov_b32_e32 v17, v129
	v_mov_b32_e32 v18, v129
	v_mov_b32_e32 v19, v129
	v_mov_b32_e32 v24, 0
	v_mov_b32_e32 v25, v129
	v_mov_b32_e32 v26, v129
	v_mov_b32_e32 v27, v129
	v_mov_b32_e32 v32, 0
	v_mov_b32_e32 v33, v129
	v_mov_b32_e32 v34, v129
	v_mov_b32_e32 v35, v129
	v_mov_b32_e32 v40, 0
	v_mov_b32_e32 v41, v129
	v_mov_b32_e32 v42, v129
	v_mov_b32_e32 v43, v129
	v_mov_b32_e32 v44, 0
	v_mov_b32_e32 v45, v129
	v_mov_b32_e32 v46, v129
	v_mov_b32_e32 v47, v129
	v_mov_b32_e32 v48, 0
	v_mov_b32_e32 v49, v129
	v_mov_b32_e32 v50, v129
	v_mov_b32_e32 v51, v129
	v_mov_b32_e32 v52, 0
	v_mov_b32_e32 v53, v129
	v_mov_b32_e32 v54, v129
	v_mov_b32_e32 v55, v129
	v_mov_b32_e32 v56, 0
	v_mov_b32_e32 v57, v129
	v_mov_b32_e32 v58, v129
	v_mov_b32_e32 v59, v129
	v_mov_b32_e32 v60, 0
	v_mov_b32_e32 v61, v129
	v_mov_b32_e32 v62, v129
	v_mov_b32_e32 v63, v129
	v_mov_b32_e32 v64, 0
	v_mov_b32_e32 v65, v129
	v_mov_b32_e32 v66, v129
	v_mov_b32_e32 v67, v129
	v_mov_b32_e32 v68, 0
	v_mov_b32_e32 v69, v129
	v_mov_b32_e32 v70, v129
	v_mov_b32_e32 v71, v129
	v_mov_b32_e32 v72, 0
	v_mov_b32_e32 v73, v129
	v_mov_b32_e32 v74, v129
	v_mov_b32_e32 v75, v129
	v_mov_b32_e32 v76, 0
	v_mov_b32_e32 v77, v129
	v_mov_b32_e32 v78, v129
	v_mov_b32_e32 v79, v129
	v_mov_b32_e32 v80, 0
	v_mov_b32_e32 v81, v129
	v_mov_b32_e32 v82, v129
	v_mov_b32_e32 v83, v129
	v_mov_b32_e32 v84, 0
	v_mov_b32_e32 v85, v129
	v_mov_b32_e32 v86, v129
	v_mov_b32_e32 v87, v129
	v_mov_b32_e32 v88, 0
	v_mov_b32_e32 v89, v129
	v_mov_b32_e32 v90, v129
	v_mov_b32_e32 v91, v129
	v_mov_b32_e32 v92, 0
	v_mov_b32_e32 v93, v129
	v_mov_b32_e32 v94, v129
	v_mov_b32_e32 v95, v129
	v_mov_b32_e32 v96, 0
	v_mov_b32_e32 v97, v129
	v_mov_b32_e32 v98, v129
	v_mov_b32_e32 v99, v129
	v_mov_b32_e32 v100, 0
	v_mov_b32_e32 v101, v129
	v_mov_b32_e32 v102, v129
	v_mov_b32_e32 v103, v129
	v_mov_b32_e32 v104, 0
	v_mov_b32_e32 v105, v129
	v_mov_b32_e32 v106, v129
	v_mov_b32_e32 v107, v129
	v_mov_b32_e32 v108, 0
	v_mov_b32_e32 v109, v129
	v_mov_b32_e32 v110, v129
	v_mov_b32_e32 v111, v129
	v_mov_b32_e32 v112, 0
	v_mov_b32_e32 v113, v129
	v_mov_b32_e32 v114, v129
	v_mov_b32_e32 v115, v129
	v_mov_b32_e32 v116, 0
	v_mov_b32_e32 v117, v129
	v_mov_b32_e32 v118, v129
	v_mov_b32_e32 v119, v129
	v_mov_b32_e32 v120, 0
	v_mov_b32_e32 v121, v129
	v_mov_b32_e32 v122, v129
	v_mov_b32_e32 v123, v129
	v_mov_b32_e32 v124, 0
	v_mov_b32_e32 v125, v129
	v_mov_b32_e32 v126, v129
	v_mov_b32_e32 v127, v129
	s_waitcnt vmcnt(0) lgkmcnt(0)
	s_barrier
	v_readfirstlane_b32 s100, v149
	s_mov_b64 s[98:99], 0x80
	s_and_b32 s27, s26, 0x10000
	s_xor_b32 s28, s27, 0x10000
	s_add_i32 s27, s27, 0
	v_add3_u32 v128, s27, v150, v151
	v_add3_u32 v161, s27, v150, v152
	v_add3_u32 v194, s27, v154, v153
	v_add3_u32 v195, s27, v154, v155
	v_add3_u32 v196, s27, v154, v156
	v_add3_u32 v197, s27, v154, v157
	v_add3_u32 v198, s27, v154, v158
	v_add3_u32 v199, s27, v154, v159
	v_add3_u32 v200, s27, v154, v160
	ds_read_b128 v[178:181], v128 offset:32768
	ds_read_b128 v[162:165], v161
	ds_read_b128 v[166:169], v194
	ds_read_b128 v[170:173], v195
	ds_read_b128 v[174:177], v196
	ds_read_b128 v[182:185], v128 offset:34816
	ds_read_b128 v[186:189], v128 offset:36864
	ds_read_b128 v[190:193], v128 offset:38912
	s_add_i32 s101, s100, s28
	s_mov_b32 m0, s101
	s_nop 0
	global_load_lds_dwordx4 v[146:147], off
	s_add_i32 m0, s101, 0x8000
	s_nop 0
	global_load_lds_dwordx4 v[138:139], off
	s_add_i32 m0, s101, 0x2000
	s_nop 0
	global_load_lds_dwordx4 v[144:145], off
	s_add_i32 m0, s101, 0xa000
	s_nop 0
	global_load_lds_dwordx4 v[136:137], off
	s_add_i32 m0, s101, 0x4000
	s_nop 0
	global_load_lds_dwordx4 v[142:143], off
	s_add_i32 m0, s101, 0xc000
	s_nop 0
	global_load_lds_dwordx4 v[134:135], off
	s_add_i32 m0, s101, 0x6000
	s_nop 0
	global_load_lds_dwordx4 v[140:141], off
	s_add_i32 m0, s101, 0xe000
	s_nop 0
	global_load_lds_dwordx4 v[130:131], off
.LBB0_1138:
	s_and_b32 s27, s26, 0x10000
	s_xor_b32 s28, s27, 0x10000
	s_add_i32 s27, s27, 0
	s_waitcnt lgkmcnt(3)
	v_mfma_f32_16x16x32_bf16 v[124:127], v[178:181], v[162:165], v[124:127]
	v_mfma_f32_16x16x32_bf16 v[108:111], v[178:181], v[166:169], v[108:111]
	v_mfma_f32_16x16x32_bf16 v[92:95], v[178:181], v[170:173], v[92:95]
	v_mfma_f32_16x16x32_bf16 v[76:79], v[178:181], v[174:177], v[76:79]
	ds_read_b128 v[240:243], v197
	ds_read_b128 v[244:247], v198
	s_waitcnt lgkmcnt(4)
	v_mfma_f32_16x16x32_bf16 v[120:123], v[182:185], v[162:165], v[120:123]
	v_mfma_f32_16x16x32_bf16 v[104:107], v[182:185], v[166:169], v[104:107]
	v_mfma_f32_16x16x32_bf16 v[88:91], v[182:185], v[170:173], v[88:91]
	v_mfma_f32_16x16x32_bf16 v[72:75], v[182:185], v[174:177], v[72:75]
	ds_read_b128 v[248:251], v199
	ds_read_b128 v[252:255], v200
	s_waitcnt lgkmcnt(5)
	v_mfma_f32_16x16x32_bf16 v[116:119], v[186:189], v[162:165], v[116:119]
	v_mfma_f32_16x16x32_bf16 v[100:103], v[186:189], v[166:169], v[100:103]
	v_mfma_f32_16x16x32_bf16 v[84:87], v[186:189], v[170:173], v[84:87]
	v_mfma_f32_16x16x32_bf16 v[68:71], v[186:189], v[174:177], v[68:71]
	s_waitcnt lgkmcnt(4)
	v_mfma_f32_16x16x32_bf16 v[112:115], v[190:193], v[162:165], v[112:115]
	v_mfma_f32_16x16x32_bf16 v[96:99], v[190:193], v[166:169], v[96:99]
	v_mfma_f32_16x16x32_bf16 v[80:83], v[190:193], v[170:173], v[80:83]
	v_mfma_f32_16x16x32_bf16 v[64:67], v[190:193], v[174:177], v[64:67]
	ds_read_b128 v[162:165], v161 offset:1024
	ds_read_b128 v[166:169], v194 offset:1024
	ds_read_b128 v[170:173], v195 offset:1024
	ds_read_b128 v[174:177], v196 offset:1024
	s_waitcnt lgkmcnt(4)
	v_mfma_f32_16x16x32_bf16 v[60:63], v[178:181], v[240:243], v[60:63]
	v_mfma_f32_16x16x32_bf16 v[44:47], v[178:181], v[244:247], v[44:47]
	v_mfma_f32_16x16x32_bf16 v[16:19], v[178:181], v[248:251], v[16:19]
	v_mfma_f32_16x16x32_bf16 v[36:39], v[178:181], v[252:255], v[36:39]
	ds_read_b128 v[178:181], v128 offset:33792
	v_mfma_f32_16x16x32_bf16 v[56:59], v[182:185], v[240:243], v[56:59]
	v_mfma_f32_16x16x32_bf16 v[40:43], v[182:185], v[244:247], v[40:43]
	v_mfma_f32_16x16x32_bf16 v[8:11], v[182:185], v[248:251], v[8:11]
	v_mfma_f32_16x16x32_bf16 v[28:31], v[182:185], v[252:255], v[28:31]
	ds_read_b128 v[182:185], v128 offset:35840
	v_mfma_f32_16x16x32_bf16 v[52:55], v[186:189], v[240:243], v[52:55]
	v_mfma_f32_16x16x32_bf16 v[32:35], v[186:189], v[244:247], v[32:35]
	v_mfma_f32_16x16x32_bf16 v[4:7], v[186:189], v[248:251], v[4:7]
	v_mfma_f32_16x16x32_bf16 v[20:23], v[186:189], v[252:255], v[20:23]
	ds_read_b128 v[186:189], v128 offset:37888
	v_mfma_f32_16x16x32_bf16 v[48:51], v[190:193], v[240:243], v[48:51]
	v_mfma_f32_16x16x32_bf16 v[24:27], v[190:193], v[244:247], v[24:27]
	v_mfma_f32_16x16x32_bf16 v[0:3], v[190:193], v[248:251], v[0:3]
	v_mfma_f32_16x16x32_bf16 v[12:15], v[190:193], v[252:255], v[12:15]
	ds_read_b128 v[190:193], v128 offset:39936
	s_waitcnt lgkmcnt(3)
	v_mfma_f32_16x16x32_bf16 v[124:127], v[178:181], v[162:165], v[124:127]
	v_mfma_f32_16x16x32_bf16 v[108:111], v[178:181], v[166:169], v[108:111]
	v_mfma_f32_16x16x32_bf16 v[92:95], v[178:181], v[170:173], v[92:95]
	v_mfma_f32_16x16x32_bf16 v[76:79], v[178:181], v[174:177], v[76:79]
	ds_read_b128 v[240:243], v197 offset:1024
	ds_read_b128 v[244:247], v198 offset:1024
	s_waitcnt lgkmcnt(4)
	v_mfma_f32_16x16x32_bf16 v[120:123], v[182:185], v[162:165], v[120:123]
	v_mfma_f32_16x16x32_bf16 v[104:107], v[182:185], v[166:169], v[104:107]
	v_mfma_f32_16x16x32_bf16 v[88:91], v[182:185], v[170:173], v[88:91]
	v_mfma_f32_16x16x32_bf16 v[72:75], v[182:185], v[174:177], v[72:75]
	ds_read_b128 v[248:251], v199 offset:1024
	ds_read_b128 v[252:255], v200 offset:1024
	s_waitcnt lgkmcnt(5)
	v_mfma_f32_16x16x32_bf16 v[116:119], v[186:189], v[162:165], v[116:119]
	v_mfma_f32_16x16x32_bf16 v[100:103], v[186:189], v[166:169], v[100:103]
	v_mfma_f32_16x16x32_bf16 v[84:87], v[186:189], v[170:173], v[84:87]
	v_mfma_f32_16x16x32_bf16 v[68:71], v[186:189], v[174:177], v[68:71]
	s_waitcnt lgkmcnt(4)
	v_mfma_f32_16x16x32_bf16 v[112:115], v[190:193], v[162:165], v[112:115]
	v_mfma_f32_16x16x32_bf16 v[96:99], v[190:193], v[166:169], v[96:99]
	v_mfma_f32_16x16x32_bf16 v[80:83], v[190:193], v[170:173], v[80:83]
	v_mfma_f32_16x16x32_bf16 v[64:67], v[190:193], v[174:177], v[64:67]
	s_waitcnt vmcnt(0) lgkmcnt(0)
	s_barrier
	s_add_i32 s101, s100, s27
	v_mfma_f32_16x16x32_bf16 v[60:63], v[178:181], v[240:243], v[60:63]
	v_mfma_f32_16x16x32_bf16 v[44:47], v[178:181], v[244:247], v[44:47]
	v_mfma_f32_16x16x32_bf16 v[16:19], v[178:181], v[248:251], v[16:19]
	v_mfma_f32_16x16x32_bf16 v[36:39], v[178:181], v[252:255], v[36:39]
	v_add3_u32 v128, s28, v150, v151
	ds_read_b128 v[178:181], v128 offset:32768
	v_add3_u32 v161, s28, v150, v152
	v_add3_u32 v194, s28, v154, v153
	v_add3_u32 v195, s28, v154, v155
	v_add3_u32 v196, s28, v154, v156
	ds_read_b128 v[162:165], v161
	ds_read_b128 v[166:169], v194
	ds_read_b128 v[170:173], v195
	ds_read_b128 v[174:177], v196
	s_cmpk_eq_i32 s12, 0x1500
	s_cbranch_scc1 .Lpk_1138_0
	s_mov_b32 m0, s101
	v_lshl_add_u64 v[146:147], v[146:147], 0, s[98:99]
	global_load_lds_dwordx4 v[146:147], off
.Lpk_1138_0:
	s_cmpk_eq_i32 s12, 0x1500
	s_cbranch_scc1 .Lpk_1138_1
	s_add_i32 m0, s101, 0x8000
	v_lshl_add_u64 v[138:139], v[138:139], 0, s[98:99]
	global_load_lds_dwordx4 v[138:139], off
.Lpk_1138_1:
	v_mfma_f32_16x16x32_bf16 v[56:59], v[182:185], v[240:243], v[56:59]
	v_mfma_f32_16x16x32_bf16 v[40:43], v[182:185], v[244:247], v[40:43]
	v_mfma_f32_16x16x32_bf16 v[8:11], v[182:185], v[248:251], v[8:11]
	v_mfma_f32_16x16x32_bf16 v[28:31], v[182:185], v[252:255], v[28:31]
	ds_read_b128 v[182:185], v128 offset:34816
	v_add3_u32 v197, s28, v154, v157
	v_add3_u32 v198, s28, v154, v158
	v_add3_u32 v199, s28, v154, v159
	v_add3_u32 v200, s28, v154, v160
	s_cmpk_eq_i32 s12, 0x1500
	s_cbranch_scc1 .Lpk_1138_2
	s_add_i32 m0, s101, 0x2000
	v_lshl_add_u64 v[144:145], v[144:145], 0, s[98:99]
	global_load_lds_dwordx4 v[144:145], off
.Lpk_1138_2:
	s_cmpk_eq_i32 s12, 0x1500
	s_cbranch_scc1 .Lpk_1138_3
	s_add_i32 m0, s101, 0xa000
	v_lshl_add_u64 v[136:137], v[136:137], 0, s[98:99]
	global_load_lds_dwordx4 v[136:137], off
.Lpk_1138_3:
	v_mfma_f32_16x16x32_bf16 v[52:55], v[186:189], v[240:243], v[52:55]
	v_mfma_f32_16x16x32_bf16 v[32:35], v[186:189], v[244:247], v[32:35]
	v_mfma_f32_16x16x32_bf16 v[4:7], v[186:189], v[248:251], v[4:7]
	v_mfma_f32_16x16x32_bf16 v[20:23], v[186:189], v[252:255], v[20:23]
	ds_read_b128 v[186:189], v128 offset:36864
	s_cmpk_eq_i32 s12, 0x1500
	s_cbranch_scc1 .Lpk_1138_4
	s_add_i32 m0, s101, 0x4000
	v_lshl_add_u64 v[142:143], v[142:143], 0, s[98:99]
	global_load_lds_dwordx4 v[142:143], off
.Lpk_1138_4:
	s_cmpk_eq_i32 s12, 0x1500
	s_cbranch_scc1 .Lpk_1138_5
	s_add_i32 m0, s101, 0xc000
	v_lshl_add_u64 v[134:135], v[134:135], 0, s[98:99]
	global_load_lds_dwordx4 v[134:135], off
.Lpk_1138_5:
	v_mfma_f32_16x16x32_bf16 v[48:51], v[190:193], v[240:243], v[48:51]
	v_mfma_f32_16x16x32_bf16 v[24:27], v[190:193], v[244:247], v[24:27]
	v_mfma_f32_16x16x32_bf16 v[0:3], v[190:193], v[248:251], v[0:3]
	v_mfma_f32_16x16x32_bf16 v[12:15], v[190:193], v[252:255], v[12:15]
	ds_read_b128 v[190:193], v128 offset:38912
	s_cmpk_eq_i32 s12, 0x1500
	s_cbranch_scc1 .Lpk_1138_6
	s_add_i32 m0, s101, 0x6000
	v_lshl_add_u64 v[140:141], v[140:141], 0, s[98:99]
	global_load_lds_dwordx4 v[140:141], off
.Lpk_1138_6:
	s_cmpk_eq_i32 s12, 0x1500
	s_cbranch_scc1 .Lpk_1138_7
	s_add_i32 m0, s101, 0xe000
	v_lshl_add_u64 v[130:131], v[130:131], 0, s[98:99]
	global_load_lds_dwordx4 v[130:131], off
.Lpk_1138_7:
	s_add_i32 s26, s26, 0x10000
	s_add_u32 s12, s12, 0x80
	s_addc_u32 s13, s13, 0
	s_cmpk_lg_i32 s12, 0x1580
	s_cbranch_scc1 .LBB0_1138
	s_waitcnt lgkmcnt(0)
	v_add3_u32 v128, s17, v154, v160
	v_add3_u32 v130, s17, v154, v159
	v_add3_u32 v131, s17, v154, v158
	v_add3_u32 v146, s17, v154, v157
	v_add3_u32 v147, s17, v154, v156
	v_add3_u32 v149, s17, v154, v155
	v_add3_u32 v186, s17, v154, v153
	v_add3_u32 v187, s17, v150, v152
	v_add3_u32 v188, s18, v150, v151
	ds_read_b128 v[134:137], v128
	ds_read_b128 v[138:141], v130
	ds_read_b128 v[142:145], v131
	ds_read_b128 v[158:161], v146
	ds_read_b128 v[162:165], v147
	ds_read_b128 v[166:169], v149
	ds_read_b128 v[154:157], v186
	ds_read_b128 v[170:173], v187
	ds_read_b128 v[150:153], v188
	s_waitcnt lgkmcnt(0)
	v_mfma_f32_16x16x32_bf16 v[16:19], v[150:153], v[138:141], v[16:19]
	v_mfma_f32_16x16x32_bf16 v[174:177], v[150:153], v[134:137], v[36:39]
	s_nop 2
	ds_read_b128 v[36:39], v188 offset:2048
	s_waitcnt lgkmcnt(0)
	v_mfma_f32_16x16x32_bf16 v[8:11], v[36:39], v[138:141], v[8:11]
	v_mfma_f32_16x16x32_bf16 v[108:111], v[150:153], v[154:157], v[108:111]
	v_mfma_f32_16x16x32_bf16 v[60:63], v[150:153], v[158:161], v[60:63]
	v_mfma_f32_16x16x32_bf16 v[28:31], v[36:39], v[134:137], v[28:31]
	v_mfma_f32_16x16x32_bf16 v[104:107], v[36:39], v[154:157], v[104:107]
	v_mfma_f32_16x16x32_bf16 v[56:59], v[36:39], v[158:161], v[56:59]
	ds_read_b128 v[178:181], v188 offset:4096
	s_waitcnt lgkmcnt(0)
	v_mfma_f32_16x16x32_bf16 v[182:185], v[178:181], v[134:137], v[20:23]
	v_mfma_f32_16x16x32_bf16 v[100:103], v[178:181], v[154:157], v[100:103]
	v_mfma_f32_16x16x32_bf16 v[52:55], v[178:181], v[158:161], v[52:55]
	s_nop 0
	ds_read_b128 v[20:23], v188 offset:6144
	s_waitcnt lgkmcnt(0)
	v_mfma_f32_16x16x32_bf16 v[134:137], v[20:23], v[134:137], v[12:15]
	v_mfma_f32_16x16x32_bf16 v[12:15], v[20:23], v[170:173], v[112:115]
	v_mfma_f32_16x16x32_bf16 v[96:99], v[20:23], v[154:157], v[96:99]
	v_mfma_f32_16x16x32_bf16 v[112:115], v[20:23], v[162:165], v[64:67]
	v_mfma_f32_16x16x32_bf16 v[64:67], v[178:181], v[170:173], v[116:119]
	v_mfma_f32_16x16x32_bf16 v[116:119], v[178:181], v[162:165], v[68:71]
	v_mfma_f32_16x16x32_bf16 v[68:71], v[36:39], v[170:173], v[120:123]
	v_mfma_f32_16x16x32_bf16 v[120:123], v[36:39], v[162:165], v[72:75]
	v_mfma_f32_16x16x32_bf16 v[72:75], v[150:153], v[170:173], v[124:127]
	v_mfma_f32_16x16x32_bf16 v[124:127], v[150:153], v[162:165], v[76:79]
	v_mfma_f32_16x16x32_bf16 v[48:51], v[20:23], v[158:161], v[48:51]
	v_mfma_f32_16x16x32_bf16 v[154:157], v[150:153], v[142:145], v[44:47]
	v_mfma_f32_16x16x32_bf16 v[158:161], v[36:39], v[142:145], v[40:43]
	v_mfma_f32_16x16x32_bf16 v[162:165], v[178:181], v[142:145], v[32:35]
	v_mfma_f32_16x16x32_bf16 v[24:27], v[20:23], v[142:145], v[24:27]
	v_mfma_f32_16x16x32_bf16 v[142:145], v[178:181], v[138:141], v[4:7]
	v_mfma_f32_16x16x32_bf16 v[92:95], v[150:153], v[166:169], v[92:95]
	v_mfma_f32_16x16x32_bf16 v[88:91], v[36:39], v[166:169], v[88:91]
	v_mfma_f32_16x16x32_bf16 v[84:87], v[178:181], v[166:169], v[84:87]
	v_mfma_f32_16x16x32_bf16 v[80:83], v[20:23], v[166:169], v[80:83]
	v_mfma_f32_16x16x32_bf16 v[20:23], v[20:23], v[138:141], v[0:3]
	ds_read_b128 v[138:141], v188 offset:1024
	ds_read_b128 v[150:153], v188 offset:3072
	ds_read_b128 v[166:169], v188 offset:5120
	ds_read_b128 v[170:173], v188 offset:7168
	ds_read_b128 v[0:3], v187 offset:1024
	ds_read_b128 v[4:7], v186 offset:1024
	ds_read_b128 v[32:35], v149 offset:1024
	ds_read_b128 v[36:39], v147 offset:1024
	s_waitcnt lgkmcnt(3)
	v_mfma_f32_16x16x32_bf16 v[178:181], v[138:141], v[0:3], v[72:75]
	v_mfma_f32_16x16x32_bf16 v[186:189], v[150:153], v[0:3], v[68:71]
	v_mfma_f32_16x16x32_bf16 v[190:193], v[166:169], v[0:3], v[64:67]
	v_mfma_f32_16x16x32_bf16 v[194:197], v[170:173], v[0:3], v[12:15]
	ds_read_b128 v[0:3], v146 offset:1024
	s_waitcnt lgkmcnt(3)
	v_mfma_f32_16x16x32_bf16 v[108:111], v[138:141], v[4:7], v[108:111]
	v_mfma_f32_16x16x32_bf16 v[104:107], v[150:153], v[4:7], v[104:107]
	v_mfma_f32_16x16x32_bf16 v[198:201], v[166:169], v[4:7], v[100:103]
	v_mfma_f32_16x16x32_bf16 v[96:99], v[170:173], v[4:7], v[96:99]
	ds_read_b128 v[4:7], v131 offset:1024
	s_waitcnt lgkmcnt(3)
	v_mfma_f32_16x16x32_bf16 v[64:67], v[138:141], v[32:35], v[92:95]
	v_mfma_f32_16x16x32_bf16 v[68:71], v[150:153], v[32:35], v[88:91]
	v_mfma_f32_16x16x32_bf16 v[72:75], v[166:169], v[32:35], v[84:87]
	v_mfma_f32_16x16x32_bf16 v[76:79], v[170:173], v[32:35], v[80:83]
	ds_read_b128 v[12:15], v130 offset:1024
	s_waitcnt lgkmcnt(3)
	v_mfma_f32_16x16x32_bf16 v[80:83], v[138:141], v[36:39], v[124:127]
	v_mfma_f32_16x16x32_bf16 v[84:87], v[150:153], v[36:39], v[120:123]
	v_mfma_f32_16x16x32_bf16 v[88:91], v[166:169], v[36:39], v[116:119]
	v_mfma_f32_16x16x32_bf16 v[92:95], v[170:173], v[36:39], v[112:115]
	ds_read_b128 v[100:103], v128 offset:1024
	s_waitcnt lgkmcnt(3)
	v_mfma_f32_16x16x32_bf16 v[32:35], v[138:141], v[0:3], v[60:63]
	v_mfma_f32_16x16x32_bf16 v[36:39], v[150:153], v[0:3], v[56:59]
	v_mfma_f32_16x16x32_bf16 v[40:43], v[166:169], v[0:3], v[52:55]
	v_mfma_f32_16x16x32_bf16 v[44:47], v[170:173], v[0:3], v[48:51]
	s_waitcnt lgkmcnt(2)
	v_mfma_f32_16x16x32_bf16 v[48:51], v[138:141], v[4:7], v[154:157]
	v_mfma_f32_16x16x32_bf16 v[52:55], v[150:153], v[4:7], v[158:161]
	v_mfma_f32_16x16x32_bf16 v[56:59], v[166:169], v[4:7], v[162:165]
	v_mfma_f32_16x16x32_bf16 v[60:63], v[170:173], v[4:7], v[24:27]
	s_waitcnt lgkmcnt(1)
	v_mfma_f32_16x16x32_bf16 v[0:3], v[138:141], v[12:15], v[16:19]
	v_mfma_f32_16x16x32_bf16 v[4:7], v[150:153], v[12:15], v[8:11]
	v_mfma_f32_16x16x32_bf16 v[8:11], v[166:169], v[12:15], v[142:145]
	v_mfma_f32_16x16x32_bf16 v[12:15], v[170:173], v[12:15], v[20:23]
	s_waitcnt lgkmcnt(0)
	v_mfma_f32_16x16x32_bf16 v[16:19], v[138:141], v[100:103], v[174:177]
	v_mfma_f32_16x16x32_bf16 v[20:23], v[150:153], v[100:103], v[28:31]
	v_mfma_f32_16x16x32_bf16 v[24:27], v[166:169], v[100:103], v[182:185]
	v_mfma_f32_16x16x32_bf16 v[28:31], v[170:173], v[100:103], v[134:137]
	v_mov_b32_e32 v102, s3
	s_waitcnt vmcnt(0)
	s_barrier
	v_and_b32_e32 v100, 63, v132
	v_lshrrev_b32_e32 v101, 6, v132
	v_and_b32_e32 v102, 15, v100
	v_lshrrev_b32_e32 v103, 4, v100
	v_mul_u32_u24_e32 v112, 0x2400, v101
	v_add_u32_e32 v112, 0x10000, v112
	v_mul_u32_u24_e32 v124, 0x110, v102
	v_lshl_add_u32 v124, v103, 4, v124
	v_add_u32_e32 v124, v124, v112
	v_mul_u32_u24_e32 v128, 0x110, v103
	v_lshl_add_u32 v128, v102, 4, v128
	v_add_u32_e32 v128, v128, v112
	v_lshrrev_b32_e32 v113, 2, v101
	v_lshl_add_u32 v113, v113, 7, v103
	v_add_u32_e32 v113, s24, v113
	v_and_b32_e32 v114, 3, v101
	v_lshlrev_b32_e32 v114, 6, v114
	v_lshl_add_u32 v114, v102, 2, v114
	v_add_u32_e32 v114, s10, v114
	v_mov_b32_e32 v252, 0x240a0
	ds_read_b64 v[248:249], v252
	v_mov_b32_e32 v252, 0x240a0
	ds_read_b64 v[250:251], v252
	v_mov_b32_e32 v252, 0x240a8
	ds_read_b64 v[240:241], v252
	s_lshr_b32 s100, s24, 12
	s_mul_i32 s100, s100, 0x6000
	s_add_i32 s100, s100, 0x2285000
	s_mov_b64 s[98:99], 0x4000
	v_lshlrev_b32_e32 v252, 12, v113
	v_lshl_add_u32 v252, v114, 2, v252
	v_mov_b32_e32 v253, 0
	s_waitcnt lgkmcnt(0)
	v_lshl_add_u64 v[248:249], v[248:249], 0, v[252:253]
	v_lshl_add_u64 v[250:251], v[250:251], 0, v[252:253]
	v_lshl_add_u32 v252, v114, 2, s100
	v_lshl_add_u64 v[240:241], v[240:241], 0, v[252:253]
	global_load_dwordx4 v[240:243], v[240:241], off
	ds_write_b128 v124, v[178:181]
	ds_write_b128 v124, v[186:189] offset:64
	ds_write_b128 v124, v[190:193] offset:128
	ds_write_b128 v124, v[194:197] offset:192
	ds_write_b128 v124, v[108:111] offset:4352
	ds_write_b128 v124, v[104:107] offset:4416
	ds_write_b128 v124, v[198:201] offset:4480
	ds_write_b128 v124, v[96:99] offset:4544
	s_waitcnt lgkmcnt(0)
	global_load_dwordx4 v[100:103], v[248:249], off nt
	v_lshl_add_u64 v[248:249], v[248:249], 0, s[98:99]
	global_load_dwordx4 v[112:115], v[248:249], off nt
	v_lshl_add_u64 v[248:249], v[248:249], 0, s[98:99]
	global_load_dwordx4 v[116:119], v[248:249], off nt
	v_lshl_add_u64 v[248:249], v[248:249], 0, s[98:99]
	global_load_dwordx4 v[120:123], v[248:249], off nt
	v_lshl_add_u64 v[248:249], v[248:249], 0, s[98:99]
	global_load_dwordx4 v[178:181], v[248:249], off nt
	v_lshl_add_u64 v[248:249], v[248:249], 0, s[98:99]
	global_load_dwordx4 v[186:189], v[248:249], off nt
	v_lshl_add_u64 v[248:249], v[248:249], 0, s[98:99]
	global_load_dwordx4 v[190:193], v[248:249], off nt
	v_lshl_add_u64 v[248:249], v[248:249], 0, s[98:99]
	global_load_dwordx4 v[194:197], v[248:249], off nt
	v_lshl_add_u64 v[248:249], v[248:249], 0, s[98:99]
	ds_read_b128 v[244:247], v128
	s_waitcnt vmcnt(7) lgkmcnt(0)
	v_pk_fma_f32 v[102:103], v[246:247], v[242:243], v[102:103]
	v_pk_fma_f32 v[100:101], v[244:245], v[240:241], v[100:101]
	global_store_dwordx4 v[250:251], v[100:103], off nt
	v_lshl_add_u64 v[250:251], v[250:251], 0, s[98:99]
	ds_read_b128 v[244:247], v128 offset:1088
	s_waitcnt vmcnt(7) lgkmcnt(0)
	v_pk_fma_f32 v[114:115], v[246:247], v[242:243], v[114:115]
	v_pk_fma_f32 v[112:113], v[244:245], v[240:241], v[112:113]
	global_store_dwordx4 v[250:251], v[112:115], off nt
	v_lshl_add_u64 v[250:251], v[250:251], 0, s[98:99]
	ds_read_b128 v[244:247], v128 offset:2176
	s_waitcnt vmcnt(7) lgkmcnt(0)
	v_pk_fma_f32 v[118:119], v[246:247], v[242:243], v[118:119]
	v_pk_fma_f32 v[116:117], v[244:245], v[240:241], v[116:117]
	global_store_dwordx4 v[250:251], v[116:119], off nt
	v_lshl_add_u64 v[250:251], v[250:251], 0, s[98:99]
	ds_read_b128 v[244:247], v128 offset:3264
	s_waitcnt vmcnt(7) lgkmcnt(0)
	v_pk_fma_f32 v[122:123], v[246:247], v[242:243], v[122:123]
	v_pk_fma_f32 v[120:121], v[244:245], v[240:241], v[120:121]
	global_store_dwordx4 v[250:251], v[120:123], off nt
	v_lshl_add_u64 v[250:251], v[250:251], 0, s[98:99]
	global_load_dwordx4 v[100:103], v[248:249], off nt
	v_lshl_add_u64 v[248:249], v[248:249], 0, s[98:99]
	global_load_dwordx4 v[112:115], v[248:249], off nt
	v_lshl_add_u64 v[248:249], v[248:249], 0, s[98:99]
	global_load_dwordx4 v[116:119], v[248:249], off nt
	v_lshl_add_u64 v[248:249], v[248:249], 0, s[98:99]
	global_load_dwordx4 v[120:123], v[248:249], off nt
	v_lshl_add_u64 v[248:249], v[248:249], 0, s[98:99]
	ds_read_b128 v[244:247], v128 offset:4352
	s_waitcnt vmcnt(11) lgkmcnt(0)
	v_pk_fma_f32 v[180:181], v[246:247], v[242:243], v[180:181]
	v_pk_fma_f32 v[178:179], v[244:245], v[240:241], v[178:179]
	global_store_dwordx4 v[250:251], v[178:181], off nt
	v_lshl_add_u64 v[250:251], v[250:251], 0, s[98:99]
	ds_read_b128 v[244:247], v128 offset:5440
	s_waitcnt vmcnt(11) lgkmcnt(0)
	v_pk_fma_f32 v[188:189], v[246:247], v[242:243], v[188:189]
	v_pk_fma_f32 v[186:187], v[244:245], v[240:241], v[186:187]
	global_store_dwordx4 v[250:251], v[186:189], off nt
	v_lshl_add_u64 v[250:251], v[250:251], 0, s[98:99]
	ds_read_b128 v[244:247], v128 offset:6528
	s_waitcnt vmcnt(11) lgkmcnt(0)
	v_pk_fma_f32 v[192:193], v[246:247], v[242:243], v[192:193]
	v_pk_fma_f32 v[190:191], v[244:245], v[240:241], v[190:191]
	global_store_dwordx4 v[250:251], v[190:193], off nt
	v_lshl_add_u64 v[250:251], v[250:251], 0, s[98:99]
	ds_read_b128 v[244:247], v128 offset:7616
	s_waitcnt vmcnt(11) lgkmcnt(0)
	v_pk_fma_f32 v[196:197], v[246:247], v[242:243], v[196:197]
	v_pk_fma_f32 v[194:195], v[244:245], v[240:241], v[194:195]
	global_store_dwordx4 v[250:251], v[194:197], off nt
	v_lshl_add_u64 v[250:251], v[250:251], 0, s[98:99]
	ds_write_b128 v124, v[64:67]
	ds_write_b128 v124, v[68:71] offset:64
	ds_write_b128 v124, v[72:75] offset:128
	ds_write_b128 v124, v[76:79] offset:192
	ds_write_b128 v124, v[80:83] offset:4352
	ds_write_b128 v124, v[84:87] offset:4416
	ds_write_b128 v124, v[88:91] offset:4480
	ds_write_b128 v124, v[92:95] offset:4544
	global_load_dwordx4 v[178:181], v[248:249], off nt
	v_lshl_add_u64 v[248:249], v[248:249], 0, s[98:99]
	global_load_dwordx4 v[186:189], v[248:249], off nt
	v_lshl_add_u64 v[248:249], v[248:249], 0, s[98:99]
	global_load_dwordx4 v[190:193], v[248:249], off nt
	v_lshl_add_u64 v[248:249], v[248:249], 0, s[98:99]
	global_load_dwordx4 v[194:197], v[248:249], off nt
	v_lshl_add_u64 v[248:249], v[248:249], 0, s[98:99]
	ds_read_b128 v[244:247], v128
	s_waitcnt vmcnt(11) lgkmcnt(0)
	v_pk_fma_f32 v[102:103], v[246:247], v[242:243], v[102:103]
	v_pk_fma_f32 v[100:101], v[244:245], v[240:241], v[100:101]
	global_store_dwordx4 v[250:251], v[100:103], off nt
	v_lshl_add_u64 v[250:251], v[250:251], 0, s[98:99]
	ds_read_b128 v[244:247], v128 offset:1088
	s_waitcnt vmcnt(11) lgkmcnt(0)
	v_pk_fma_f32 v[114:115], v[246:247], v[242:243], v[114:115]
	v_pk_fma_f32 v[112:113], v[244:245], v[240:241], v[112:113]
	global_store_dwordx4 v[250:251], v[112:115], off nt
	v_lshl_add_u64 v[250:251], v[250:251], 0, s[98:99]
	ds_read_b128 v[244:247], v128 offset:2176
	s_waitcnt vmcnt(11) lgkmcnt(0)
	v_pk_fma_f32 v[118:119], v[246:247], v[242:243], v[118:119]
	v_pk_fma_f32 v[116:117], v[244:245], v[240:241], v[116:117]
	global_store_dwordx4 v[250:251], v[116:119], off nt
	v_lshl_add_u64 v[250:251], v[250:251], 0, s[98:99]
	ds_read_b128 v[244:247], v128 offset:3264
	s_waitcnt vmcnt(11) lgkmcnt(0)
	v_pk_fma_f32 v[122:123], v[246:247], v[242:243], v[122:123]
	v_pk_fma_f32 v[120:121], v[244:245], v[240:241], v[120:121]
	global_store_dwordx4 v[250:251], v[120:123], off nt
	v_lshl_add_u64 v[250:251], v[250:251], 0, s[98:99]
	global_load_dwordx4 v[100:103], v[248:249], off nt
	v_lshl_add_u64 v[248:249], v[248:249], 0, s[98:99]
	global_load_dwordx4 v[112:115], v[248:249], off nt
	v_lshl_add_u64 v[248:249], v[248:249], 0, s[98:99]
	global_load_dwordx4 v[116:119], v[248:249], off nt
	v_lshl_add_u64 v[248:249], v[248:249], 0, s[98:99]
	global_load_dwordx4 v[120:123], v[248:249], off nt
	v_lshl_add_u64 v[248:249], v[248:249], 0, s[98:99]
	ds_read_b128 v[244:247], v128 offset:4352
	s_waitcnt vmcnt(11) lgkmcnt(0)
	v_pk_fma_f32 v[180:181], v[246:247], v[242:243], v[180:181]
	v_pk_fma_f32 v[178:179], v[244:245], v[240:241], v[178:179]
	global_store_dwordx4 v[250:251], v[178:181], off nt
	v_lshl_add_u64 v[250:251], v[250:251], 0, s[98:99]
	ds_read_b128 v[244:247], v128 offset:5440
	s_waitcnt vmcnt(11) lgkmcnt(0)
	v_pk_fma_f32 v[188:189], v[246:247], v[242:243], v[188:189]
	v_pk_fma_f32 v[186:187], v[244:245], v[240:241], v[186:187]
	global_store_dwordx4 v[250:251], v[186:189], off nt
	v_lshl_add_u64 v[250:251], v[250:251], 0, s[98:99]
	ds_read_b128 v[244:247], v128 offset:6528
	s_waitcnt vmcnt(11) lgkmcnt(0)
	v_pk_fma_f32 v[192:193], v[246:247], v[242:243], v[192:193]
	v_pk_fma_f32 v[190:191], v[244:245], v[240:241], v[190:191]
	global_store_dwordx4 v[250:251], v[190:193], off nt
	v_lshl_add_u64 v[250:251], v[250:251], 0, s[98:99]
	ds_read_b128 v[244:247], v128 offset:7616
	s_waitcnt vmcnt(11) lgkmcnt(0)
	v_pk_fma_f32 v[196:197], v[246:247], v[242:243], v[196:197]
	v_pk_fma_f32 v[194:195], v[244:245], v[240:241], v[194:195]
	global_store_dwordx4 v[250:251], v[194:197], off nt
	v_lshl_add_u64 v[250:251], v[250:251], 0, s[98:99]
	ds_write_b128 v124, v[32:35]
	ds_write_b128 v124, v[36:39] offset:64
	ds_write_b128 v124, v[40:43] offset:128
	ds_write_b128 v124, v[44:47] offset:192
	ds_write_b128 v124, v[48:51] offset:4352
	ds_write_b128 v124, v[52:55] offset:4416
	ds_write_b128 v124, v[56:59] offset:4480
	ds_write_b128 v124, v[60:63] offset:4544
	global_load_dwordx4 v[178:181], v[248:249], off nt
	v_lshl_add_u64 v[248:249], v[248:249], 0, s[98:99]
	global_load_dwordx4 v[186:189], v[248:249], off nt
	v_lshl_add_u64 v[248:249], v[248:249], 0, s[98:99]
	global_load_dwordx4 v[190:193], v[248:249], off nt
	v_lshl_add_u64 v[248:249], v[248:249], 0, s[98:99]
	global_load_dwordx4 v[194:197], v[248:249], off nt
	v_lshl_add_u64 v[248:249], v[248:249], 0, s[98:99]
	ds_read_b128 v[244:247], v128
	s_waitcnt vmcnt(11) lgkmcnt(0)
	v_pk_fma_f32 v[102:103], v[246:247], v[242:243], v[102:103]
	v_pk_fma_f32 v[100:101], v[244:245], v[240:241], v[100:101]
	global_store_dwordx4 v[250:251], v[100:103], off nt
	v_lshl_add_u64 v[250:251], v[250:251], 0, s[98:99]
	ds_read_b128 v[244:247], v128 offset:1088
	s_waitcnt vmcnt(11) lgkmcnt(0)
	v_pk_fma_f32 v[114:115], v[246:247], v[242:243], v[114:115]
	v_pk_fma_f32 v[112:113], v[244:245], v[240:241], v[112:113]
	global_store_dwordx4 v[250:251], v[112:115], off nt
	v_lshl_add_u64 v[250:251], v[250:251], 0, s[98:99]
	ds_read_b128 v[244:247], v128 offset:2176
	s_waitcnt vmcnt(11) lgkmcnt(0)
	v_pk_fma_f32 v[118:119], v[246:247], v[242:243], v[118:119]
	v_pk_fma_f32 v[116:117], v[244:245], v[240:241], v[116:117]
	global_store_dwordx4 v[250:251], v[116:119], off nt
	v_lshl_add_u64 v[250:251], v[250:251], 0, s[98:99]
	ds_read_b128 v[244:247], v128 offset:3264
	s_waitcnt vmcnt(11) lgkmcnt(0)
	v_pk_fma_f32 v[122:123], v[246:247], v[242:243], v[122:123]
	v_pk_fma_f32 v[120:121], v[244:245], v[240:241], v[120:121]
	global_store_dwordx4 v[250:251], v[120:123], off nt
	v_lshl_add_u64 v[250:251], v[250:251], 0, s[98:99]
	global_load_dwordx4 v[100:103], v[248:249], off nt
	v_lshl_add_u64 v[248:249], v[248:249], 0, s[98:99]
	global_load_dwordx4 v[112:115], v[248:249], off nt
	v_lshl_add_u64 v[248:249], v[248:249], 0, s[98:99]
	global_load_dwordx4 v[116:119], v[248:249], off nt
	v_lshl_add_u64 v[248:249], v[248:249], 0, s[98:99]
	global_load_dwordx4 v[120:123], v[248:249], off nt
	v_lshl_add_u64 v[248:249], v[248:249], 0, s[98:99]
	ds_read_b128 v[244:247], v128 offset:4352
	s_waitcnt vmcnt(11) lgkmcnt(0)
	v_pk_fma_f32 v[180:181], v[246:247], v[242:243], v[180:181]
	v_pk_fma_f32 v[178:179], v[244:245], v[240:241], v[178:179]
	global_store_dwordx4 v[250:251], v[178:181], off nt
	v_lshl_add_u64 v[250:251], v[250:251], 0, s[98:99]
	ds_read_b128 v[244:247], v128 offset:5440
	s_waitcnt vmcnt(11) lgkmcnt(0)
	v_pk_fma_f32 v[188:189], v[246:247], v[242:243], v[188:189]
	v_pk_fma_f32 v[186:187], v[244:245], v[240:241], v[186:187]
	global_store_dwordx4 v[250:251], v[186:189], off nt
	v_lshl_add_u64 v[250:251], v[250:251], 0, s[98:99]
	ds_read_b128 v[244:247], v128 offset:6528
	s_waitcnt vmcnt(11) lgkmcnt(0)
	v_pk_fma_f32 v[192:193], v[246:247], v[242:243], v[192:193]
	v_pk_fma_f32 v[190:191], v[244:245], v[240:241], v[190:191]
	global_store_dwordx4 v[250:251], v[190:193], off nt
	v_lshl_add_u64 v[250:251], v[250:251], 0, s[98:99]
	ds_read_b128 v[244:247], v128 offset:7616
	s_waitcnt vmcnt(11) lgkmcnt(0)
	v_pk_fma_f32 v[196:197], v[246:247], v[242:243], v[196:197]
	v_pk_fma_f32 v[194:195], v[244:245], v[240:241], v[194:195]
	global_store_dwordx4 v[250:251], v[194:197], off nt
	v_lshl_add_u64 v[250:251], v[250:251], 0, s[98:99]
	ds_write_b128 v124, v[0:3]
	ds_write_b128 v124, v[4:7] offset:64
	ds_write_b128 v124, v[8:11] offset:128
	ds_write_b128 v124, v[12:15] offset:192
	ds_write_b128 v124, v[16:19] offset:4352
	ds_write_b128 v124, v[20:23] offset:4416
	ds_write_b128 v124, v[24:27] offset:4480
	ds_write_b128 v124, v[28:31] offset:4544
	global_load_dwordx4 v[178:181], v[248:249], off nt
	v_lshl_add_u64 v[248:249], v[248:249], 0, s[98:99]
	global_load_dwordx4 v[186:189], v[248:249], off nt
	v_lshl_add_u64 v[248:249], v[248:249], 0, s[98:99]
	global_load_dwordx4 v[190:193], v[248:249], off nt
	v_lshl_add_u64 v[248:249], v[248:249], 0, s[98:99]
	global_load_dwordx4 v[194:197], v[248:249], off nt
	v_lshl_add_u64 v[248:249], v[248:249], 0, s[98:99]
	ds_read_b128 v[244:247], v128
	s_waitcnt vmcnt(11) lgkmcnt(0)
	v_pk_fma_f32 v[102:103], v[246:247], v[242:243], v[102:103]
	v_pk_fma_f32 v[100:101], v[244:245], v[240:241], v[100:101]
	global_store_dwordx4 v[250:251], v[100:103], off nt
	v_lshl_add_u64 v[250:251], v[250:251], 0, s[98:99]
	ds_read_b128 v[244:247], v128 offset:1088
	s_waitcnt vmcnt(11) lgkmcnt(0)
	v_pk_fma_f32 v[114:115], v[246:247], v[242:243], v[114:115]
	v_pk_fma_f32 v[112:113], v[244:245], v[240:241], v[112:113]
	global_store_dwordx4 v[250:251], v[112:115], off nt
	v_lshl_add_u64 v[250:251], v[250:251], 0, s[98:99]
	ds_read_b128 v[244:247], v128 offset:2176
	s_waitcnt vmcnt(11) lgkmcnt(0)
	v_pk_fma_f32 v[118:119], v[246:247], v[242:243], v[118:119]
	v_pk_fma_f32 v[116:117], v[244:245], v[240:241], v[116:117]
	global_store_dwordx4 v[250:251], v[116:119], off nt
	v_lshl_add_u64 v[250:251], v[250:251], 0, s[98:99]
	ds_read_b128 v[244:247], v128 offset:3264
	s_waitcnt vmcnt(11) lgkmcnt(0)
	v_pk_fma_f32 v[122:123], v[246:247], v[242:243], v[122:123]
	v_pk_fma_f32 v[120:121], v[244:245], v[240:241], v[120:121]
	global_store_dwordx4 v[250:251], v[120:123], off nt
	v_lshl_add_u64 v[250:251], v[250:251], 0, s[98:99]
	ds_read_b128 v[244:247], v128 offset:4352
	s_waitcnt vmcnt(7) lgkmcnt(0)
	v_pk_fma_f32 v[180:181], v[246:247], v[242:243], v[180:181]
	v_pk_fma_f32 v[178:179], v[244:245], v[240:241], v[178:179]
	global_store_dwordx4 v[250:251], v[178:181], off nt
	v_lshl_add_u64 v[250:251], v[250:251], 0, s[98:99]
	ds_read_b128 v[244:247], v128 offset:5440
	s_waitcnt vmcnt(7) lgkmcnt(0)
	v_pk_fma_f32 v[188:189], v[246:247], v[242:243], v[188:189]
	v_pk_fma_f32 v[186:187], v[244:245], v[240:241], v[186:187]
	global_store_dwordx4 v[250:251], v[186:189], off nt
	v_lshl_add_u64 v[250:251], v[250:251], 0, s[98:99]
	ds_read_b128 v[244:247], v128 offset:6528
	s_waitcnt vmcnt(7) lgkmcnt(0)
	v_pk_fma_f32 v[192:193], v[246:247], v[242:243], v[192:193]
	v_pk_fma_f32 v[190:191], v[244:245], v[240:241], v[190:191]
	global_store_dwordx4 v[250:251], v[190:193], off nt
	v_lshl_add_u64 v[250:251], v[250:251], 0, s[98:99]
	ds_read_b128 v[244:247], v128 offset:7616
	s_waitcnt vmcnt(7) lgkmcnt(0)
	v_pk_fma_f32 v[196:197], v[246:247], v[242:243], v[196:197]
	v_pk_fma_f32 v[194:195], v[244:245], v[240:241], v[194:195]
	global_store_dwordx4 v[250:251], v[194:197], off nt
	v_lshl_add_u64 v[250:251], v[250:251], 0, s[98:99]
	s_add_i32 s23, s23, s40
	s_cmpk_gt_i32 s23, 0x1ff
	s_cbranch_scc0 .LBB0_1137

	.amdhsa_kernel _Z4mega6Params
		.amdhsa_group_segment_fixed_size 0
		.amdhsa_private_segment_fixed_size 0
		.amdhsa_kernarg_size 432
		.amdhsa_user_sgpr_count 2
		.amdhsa_user_sgpr_dispatch_ptr 0
		.amdhsa_user_sgpr_queue_ptr 0
		.amdhsa_user_sgpr_kernarg_segment_ptr 1
		.amdhsa_user_sgpr_dispatch_id 0
		.amdhsa_user_sgpr_kernarg_preload_length 0
		.amdhsa_user_sgpr_kernarg_preload_offset 0
		.amdhsa_user_sgpr_private_segment_size 0
		.amdhsa_uses_dynamic_stack 0
		.amdhsa_enable_private_segment 0
		.amdhsa_system_sgpr_workgroup_id_x 1
		.amdhsa_system_sgpr_workgroup_id_y 0
		.amdhsa_system_sgpr_workgroup_id_z 0
		.amdhsa_system_sgpr_workgroup_info 0
		.amdhsa_system_vgpr_workitem_id 2
		.amdhsa_next_free_vgpr 256
		.amdhsa_next_free_sgpr 102
		.amdhsa_accum_offset 256
		.amdhsa_reserve_vcc 1
		.amdhsa_float_round_mode_32 0
		.amdhsa_float_round_mode_16_64 0
		.amdhsa_float_denorm_mode_32 3
		.amdhsa_float_denorm_mode_16_64 3
		.amdhsa_dx10_clamp 1
		.amdhsa_ieee_mode 1
		.amdhsa_fp16_overflow 0
		.amdhsa_tg_split 0
		.amdhsa_exception_fp_ieee_invalid_op 0
		.amdhsa_exception_fp_denorm_src 0
		.amdhsa_exception_fp_ieee_div_zero 0
		.amdhsa_exception_fp_ieee_overflow 0
		.amdhsa_exception_fp_ieee_underflow 0
		.amdhsa_exception_fp_ieee_inexact 0
		.amdhsa_exception_int_div_zero 0
	.end_amdhsa_kernel

amdhsa.kernels:
  - .agpr_count:     0
    .args:
      - .offset:         0
        .size:           176
        .value_kind:     by_value
      - .offset:         176
        .size:           4
        .value_kind:     hidden_block_count_x
      - .offset:         180
        .size:           4
        .value_kind:     hidden_block_count_y
      - .offset:         184
        .size:           4
        .value_kind:     hidden_block_count_z
      - .offset:         188
        .size:           2
        .value_kind:     hidden_group_size_x
      - .offset:         190
        .size:           2
        .value_kind:     hidden_group_size_y
      - .offset:         192
        .size:           2
        .value_kind:     hidden_group_size_z
      - .offset:         194
        .size:           2
        .value_kind:     hidden_remainder_x
      - .offset:         196
        .size:           2
        .value_kind:     hidden_remainder_y
      - .offset:         198
        .size:           2
        .value_kind:     hidden_remainder_z
      - .offset:         216
        .size:           8
        .value_kind:     hidden_global_offset_x
      - .offset:         224
        .size:           8
        .value_kind:     hidden_global_offset_y
      - .offset:         232
        .size:           8
        .value_kind:     hidden_global_offset_z
      - .offset:         240
        .size:           2
        .value_kind:     hidden_grid_dims
      - .offset:         264
        .size:           8
        .value_kind:     hidden_multigrid_sync_arg
      - .offset:         296
        .size:           4
        .value_kind:     hidden_dynamic_lds_size
    .group_segment_fixed_size: 0
    .kernarg_segment_align: 8
    .kernarg_segment_size: 432
    .language:       OpenCL C
    .language_version:
      - 2
      - 0
    .max_flat_workgroup_size: 512
    .name:           _Z4mega6Params
    .private_segment_fixed_size: 0
    .sgpr_count:     108
    .sgpr_spill_count: 42
    .symbol:         _Z4mega6Params.kd
    .uniform_work_group_size: 1
    .uses_dynamic_stack: false
    .vgpr_count:     256
    .vgpr_spill_count: 0
    .wavefront_size: 64
